# all 871 flat_load/flat_store of workspace pointers rewritten as global_load/global_store (same addresses), on top of counted lgkmcnt GEMM waits
# speedup vs baseline: 1.0160x; 1.0153x over previous
; DI void convert_phase(const Params& p, LAS unsigned char* lds) {
;     ...
;     { u32x4* z = (u32x4*)(ws + OFF_WDOWN + (size_t)1088 * 2048 * 2); const int n16 = 192 * 2048 * 2 / 16;
;       for (int i = gtid; i < n16; i += gsz) z[i] = (u32x4){0u, 0u, 0u, 0u}; }
.LBB1_24:
	v_add_u32_e32 v12, s16, v12
	v_cmp_lt_i32_e32 vcc, s17, v12
	global_store_dwordx4 v[10:11], v[2:5], off
	s_or_b64 s[18:19], vcc, s[18:19]
	v_lshl_add_u64 v[10:11], v[10:11], 0, s[6:7]
	s_andn2_b64 exec, exec, s[18:19]
	s_cbranch_execnz .LBB1_24

;     DI const char* a(const Unit& u) const { return (const char*)(A + (size_t)u.pm * BM * lda); }
;     DI const char* a(const Unit& u) const { return (const char*)(A + (size_t)u.pm * BM * 2048 + (u.pn >> 1) * 512); }
;     DI const char* a(const Unit& u) const { return (const char*)((u.pn < 12 ? A1 : A2) + (size_t)u.pm * BM * 512); }
; DI void convert_phase(const Params& p, LAS unsigned char* lds) {
;     ...
;     { float* ct = (float*)(ws + OFF_ROPE); float* st = ct + S * 32;
;       for (int i = gtid; i < S * 32; i += gsz) { const int s = i >> 5, f = i & 31;
;           const double inv = pow(10000.0, -(double)f / 32.0); const double a = (double)p.positions[s] * inv;
;           ct[i] = (float)cos(a); st[i] = (float)sin(a); } }
.LBB1_27:
	s_or_b64 exec, exec, s[6:7]
	v_mul_f64 v[32:33], v[40:41], v[40:41]
	v_mov_b64_e32 v[48:49], v[16:17]
	v_mul_f64 v[34:35], v[32:33], 0.5
	v_fmac_f64_e32 v[48:49], s[52:53], v[32:33]
	v_mov_b64_e32 v[50:51], v[18:19]
	v_add_f64 v[36:37], -v[34:35], 1.0
	v_fmac_f64_e32 v[50:51], v[32:33], v[48:49]
	v_mov_b64_e32 v[48:49], v[20:21]
	v_add_f64 v[38:39], -v[36:37], 1.0
	v_fmac_f64_e32 v[48:49], v[32:33], v[50:51]
	v_mov_b64_e32 v[50:51], v[22:23]
	v_add_f64 v[34:35], v[38:39], -v[34:35]
	v_fmac_f64_e32 v[50:51], v[32:33], v[48:49]
	v_mov_b64_e32 v[48:49], v[10:11]
	v_mul_f64 v[38:39], v[32:33], v[32:33]
	v_fmac_f64_e32 v[48:49], v[32:33], v[50:51]
	v_fma_f64 v[34:35], v[40:41], -v[42:43], v[34:35]
	v_fmac_f64_e32 v[34:35], v[38:39], v[48:49]
	v_add_f64 v[34:35], v[36:37], v[34:35]
	v_mov_b64_e32 v[36:37], v[24:25]
	v_fmac_f64_e32 v[36:37], s[54:55], v[32:33]
	v_mov_b64_e32 v[38:39], v[26:27]
	v_fmac_f64_e32 v[38:39], v[32:33], v[36:37]
	v_mov_b64_e32 v[36:37], v[28:29]
	v_fmac_f64_e32 v[36:37], v[32:33], v[38:39]
	v_mov_b64_e32 v[38:39], v[4:5]
	v_fmac_f64_e32 v[38:39], v[32:33], v[36:37]
	v_mul_f64 v[36:37], v[40:41], -v[32:33]
	v_mul_f64 v[48:49], v[42:43], 0.5
	v_fmac_f64_e32 v[48:49], v[36:37], v[38:39]
	v_fma_f64 v[32:33], v[32:33], v[48:49], -v[42:43]
	v_fmac_f64_e32 v[32:33], s[22:23], v[36:37]
	v_and_b32_e32 v3, 1, v46
	v_add_f64 v[32:33], v[40:41], -v[32:33]
	v_cmp_eq_u32_e32 vcc, 0, v3
	v_add_u32_e32 v8, s16, v8
	s_nop 0
	v_cndmask_b32_e32 v3, v34, v32, vcc
	v_lshlrev_b32_e32 v32, 30, v46
	v_cndmask_b32_e32 v30, v35, v33, vcc
	v_xor_b32_e32 v31, v32, v31
	v_bitop3_b32 v31, v30, v31, s48 bitop3:0x78
	v_cndmask_b32_e64 v30, 0, v3, s[4:5]
	v_cndmask_b32_e64 v31, v44, v31, s[4:5]
	v_cvt_f32_f64_e32 v3, v[30:31]
	v_cmp_lt_i32_e32 vcc, s56, v8
	global_store_dword v[14:15], v3, off
	s_or_b64 s[20:21], vcc, s[20:21]
	v_lshl_add_u64 v[14:15], v[14:15], 0, s[24:25]
	s_andn2_b64 exec, exec, s[20:21]
	s_cbranch_execz .LBB1_36

;     DI const char* a(const Unit& u) const { return (const char*)(A + (size_t)u.pm * BM * lda); }
;     DI const char* a(const Unit& u) const { return (const char*)(A + (size_t)u.pm * BM * 2048 + (u.pn >> 1) * 512); }
;     DI const char* a(const Unit& u) const { return (const char*)((u.pn < 12 ? A1 : A2) + (size_t)u.pm * BM * 512); }
; DI void convert_phase(const Params& p, LAS unsigned char* lds) {
;     ...
;     { float* ct = (float*)(ws + OFF_ROPE); float* st = ct + S * 32;
;       for (int i = gtid; i < S * 32; i += gsz) { const int s = i >> 5, f = i & 31;
;           const double inv = pow(10000.0, -(double)f / 32.0); const double a = (double)p.positions[s] * inv;
;           ct[i] = (float)cos(a); st[i] = (float)sin(a); } }
.LBB1_32:
	s_or_b64 exec, exec, s[4:5]
	v_mul_f64 v[48:49], v[40:41], v[40:41]
	v_mov_b64_e32 v[56:57], v[16:17]
	v_mul_f64 v[50:51], v[48:49], 0.5
	v_fmac_f64_e32 v[56:57], s[52:53], v[48:49]
	v_mov_b64_e32 v[58:59], v[18:19]
	v_add_f64 v[52:53], -v[50:51], 1.0
	v_fmac_f64_e32 v[58:59], v[48:49], v[56:57]
	v_mov_b64_e32 v[56:57], v[20:21]
	v_add_f64 v[54:55], -v[52:53], 1.0
	v_fmac_f64_e32 v[56:57], v[48:49], v[58:59]
	v_mov_b64_e32 v[58:59], v[22:23]
	v_add_f64 v[50:51], v[54:55], -v[50:51]
	v_fmac_f64_e32 v[58:59], v[48:49], v[56:57]
	v_mov_b64_e32 v[56:57], v[10:11]
	v_mul_f64 v[54:55], v[48:49], v[48:49]
	v_fmac_f64_e32 v[56:57], v[48:49], v[58:59]
	v_fma_f64 v[50:51], v[40:41], -v[42:43], v[50:51]
	v_fmac_f64_e32 v[50:51], v[54:55], v[56:57]
	v_add_f64 v[50:51], v[52:53], v[50:51]
	v_mov_b64_e32 v[52:53], v[24:25]
	v_fmac_f64_e32 v[52:53], s[54:55], v[48:49]
	v_mov_b64_e32 v[54:55], v[26:27]
	v_fmac_f64_e32 v[54:55], v[48:49], v[52:53]
	v_mov_b64_e32 v[52:53], v[28:29]
	v_fmac_f64_e32 v[52:53], v[48:49], v[54:55]
	v_mov_b64_e32 v[54:55], v[4:5]
	v_fmac_f64_e32 v[54:55], v[48:49], v[52:53]
	v_mul_f64 v[52:53], v[40:41], -v[48:49]
	v_mul_f64 v[56:57], v[42:43], 0.5
	v_fmac_f64_e32 v[56:57], v[52:53], v[54:55]
	v_fma_f64 v[42:43], v[48:49], v[56:57], -v[42:43]
	v_fmac_f64_e32 v[42:43], s[22:23], v[52:53]
	v_add_f64 v[40:41], v[40:41], -v[42:43]
	v_xor_b32_e32 v3, 0x80000000, v41
	v_and_b32_e32 v41, 1, v46
	v_cmp_eq_u32_e32 vcc, 0, v41
	v_lshlrev_b32_e32 v41, 30, v46
	v_cmp_class_f64_e64 s[4:5], v[30:31], s49
	v_cndmask_b32_e32 v3, v3, v51, vcc
	v_cndmask_b32_e32 v40, v40, v50, vcc
	v_bitop3_b32 v3, v3, v41, s48 bitop3:0x78
	v_cndmask_b32_e64 v40, 0, v40, s[4:5]
	v_cndmask_b32_e64 v41, v44, v3, s[4:5]
	v_cvt_f32_f64_e32 v3, v[40:41]
	v_add_co_u32_e32 v40, vcc, 0xfff80000, v14
	s_nop 1
	v_addc_co_u32_e32 v41, vcc, -1, v15, vcc
	global_store_dword v[40:41], v3, off
	s_and_saveexec_b64 s[58:59], s[6:7]
	s_xor_b64 s[58:59], exec, s[58:59]
	v_readlane_b32 s61, v246, 49
	s_cbranch_execz .LBB1_34
	v_cmp_ge_f64_e64 vcc, |v[30:31]|, s[30:31]
	s_mov_b32 s34, s36
	s_mov_b32 s41, s39
	v_cndmask_b32_e32 v39, v45, v39, vcc
	v_cndmask_b32_e32 v38, v30, v38, vcc
	v_mul_f64 v[42:43], v[36:37], v[38:39]
	v_mul_f64 v[40:41], v[34:35], v[38:39]
	v_fma_f64 v[36:37], v[36:37], v[38:39], -v[42:43]
	v_add_f64 v[46:47], v[40:41], v[36:37]
	v_add_f64 v[54:55], v[46:47], -v[40:41]
	v_add_f64 v[36:37], v[36:37], -v[54:55]
	v_add_f64 v[54:55], v[46:47], -v[54:55]
	v_add_f64 v[54:55], v[40:41], -v[54:55]
	v_fma_f64 v[34:35], v[34:35], v[38:39], -v[40:41]
	v_mul_f64 v[40:41], v[32:33], v[38:39]
	v_add_f64 v[36:37], v[36:37], v[54:55]
	v_add_f64 v[54:55], v[40:41], v[34:35]
	v_add_f64 v[48:49], v[42:43], v[46:47]
	v_add_f64 v[56:57], v[54:55], v[36:37]
	v_ldexp_f64 v[50:51], v[48:49], -2
	v_add_f64 v[42:43], v[48:49], -v[42:43]
	v_add_f64 v[48:49], v[56:57], -v[54:55]
	v_add_f64 v[36:37], v[36:37], -v[48:49]
	v_add_f64 v[48:49], v[56:57], -v[48:49]
	v_add_f64 v[48:49], v[54:55], -v[48:49]
	v_add_f64 v[36:37], v[36:37], v[48:49]
	v_add_f64 v[48:49], v[54:55], -v[40:41]
	v_add_f64 v[34:35], v[34:35], -v[48:49]
	v_add_f64 v[48:49], v[54:55], -v[48:49]
	v_add_f64 v[48:49], v[40:41], -v[48:49]
	v_add_f64 v[34:35], v[34:35], v[48:49]
	v_fract_f64_e32 v[52:53], v[50:51]
	v_add_f64 v[34:35], v[34:35], v[36:37]
	v_fma_f64 v[32:33], v[32:33], v[38:39], -v[40:41]
	v_add_f64 v[42:43], v[46:47], -v[42:43]
	v_add_f64 v[32:33], v[32:33], v[34:35]
	v_ldexp_f64 v[34:35], v[52:53], 2
	v_cmp_neq_f64_e64 vcc, |v[50:51]|, s[26:27]
	v_add_f64 v[46:47], v[42:43], v[56:57]
	v_add_f64 v[42:43], v[46:47], -v[42:43]
	v_cndmask_b32_e32 v35, 0, v35, vcc
	v_cndmask_b32_e32 v34, 0, v34, vcc
	v_add_f64 v[36:37], v[46:47], v[34:35]
	v_cmp_gt_f64_e32 vcc, 0, v[36:37]
	v_add_f64 v[42:43], v[56:57], -v[42:43]
	v_add_f64 v[32:33], v[42:43], v[32:33]
	v_cndmask_b32_e32 v3, 0, v9, vcc
	v_add_f64 v[34:35], v[34:35], v[2:3]
	v_add_f64 v[36:37], v[46:47], v[34:35]
	v_cvt_i32_f64_e32 v3, v[36:37]
	v_cvt_f64_i32_e32 v[36:37], v3
	v_add_f64 v[34:35], v[34:35], -v[36:37]
	v_add_f64 v[36:37], v[46:47], v[34:35]
	v_add_f64 v[34:35], v[36:37], -v[34:35]
	v_cmp_le_f64_e32 vcc, 0.5, v[36:37]
	v_add_f64 v[34:35], v[46:47], -v[34:35]
	v_add_f64 v[32:33], v[32:33], v[34:35]
	v_addc_co_u32_e64 v46, s[6:7], 0, v3, vcc
	v_cndmask_b32_e32 v3, 0, v1, vcc
	v_add_f64 v[34:35], v[36:37], -v[2:3]
	v_add_f64 v[36:37], v[34:35], v[32:33]
	v_add_f64 v[34:35], v[36:37], -v[34:35]
	v_add_f64 v[32:33], v[32:33], -v[34:35]
	v_mul_f64 v[34:35], v[36:37], s[34:35]
	v_fma_f64 v[38:39], v[36:37], s[34:35], -v[34:35]
	v_fmac_f64_e32 v[38:39], s[40:41], v[36:37]
	v_fmac_f64_e32 v[38:39], s[34:35], v[32:33]
	v_add_f64 v[40:41], v[34:35], v[38:39]
	v_add_f64 v[32:33], v[40:41], -v[34:35]
	v_add_f64 v[42:43], v[38:39], -v[32:33]

; DI float wave_sum(float v) { for (int o = 32; o; o >>= 1) v += __shfl_xor(v, o); return v; }
; template <bool BF> DI void rstd_phase(const Params& p, const void* x) {
;     ...
;     for (int t = bid * 8 + wid; t < T; t += 2 * step) {
;         const int t2 = (t + step < T) ? t + step : t;
;         f32x4 v[2][8];
; #pragma unroll
;         for (int q = 0; q < 2; ++q)
; #pragma unroll
;             for (int i = 0; i < 8; ++i) v[q][i] = ldx4<BF>(x, (size_t)(q ? t2 : t) * D + (i * 64 + lane) * 4);
;         float ss[2] = {0.f, 0.f};
; #pragma unroll
;         for (int q = 0; q < 2; ++q)
; #pragma unroll
;             for (int i = 0; i < 8; ++i) ss[q] += v[q][i][0] * v[q][i][0] + v[q][i][1] * v[q][i][1] + v[q][i][2] * v[q][i][2] + v[q][i][3] * v[q][i][3];
;         ss[0] = wave_sum(ss[0]); ss[1] = wave_sum(ss[1]);
;         if (lane == 0) { rstd[t] = rsqrtf(ss[0] * (1.0f / D) + EPS); rstd[t2] = rsqrtf(ss[1] * (1.0f / D) + EPS); }
.LBB1_39:
	v_add_u32_e32 v26, s24, v2
	v_ashrrev_i32_e32 v3, 31, v2
	v_cmp_gt_i32_e64 s[4:5], s21, v26
	v_lshlrev_b64 v[18:19], 13, v[2:3]
	v_lshl_add_u64 v[80:81], s[8:9], 0, v[18:19]
	v_cndmask_b32_e64 v16, v2, v26, s[4:5]
	v_lshl_add_u64 v[40:41], v[80:81], 0, v[4:5]
	v_lshl_add_u64 v[48:49], v[80:81], 0, v[6:7]
	v_ashrrev_i32_e32 v17, 31, v16
	s_waitcnt lgkmcnt(0)
	global_load_dwordx4 v[18:21], v[40:41], off
	global_load_dwordx4 v[28:31], v[40:41], off offset:1024
	global_load_dwordx4 v[32:35], v[40:41], off offset:2048
	global_load_dwordx4 v[36:39], v[40:41], off offset:3072
	v_lshl_add_u64 v[50:51], v[80:81], 0, v[8:9]
	global_load_dwordx4 v[40:43], v[48:49], off
	global_load_dwordx4 v[44:47], v[50:51], off
	v_lshlrev_b64 v[48:49], 13, v[16:17]
	v_lshl_add_u64 v[82:83], s[8:9], 0, v[48:49]
	v_lshl_add_u64 v[64:65], v[82:83], 0, v[4:5]
	global_load_dwordx4 v[48:51], v[64:65], off
	global_load_dwordx4 v[52:55], v[64:65], off offset:1024
	global_load_dwordx4 v[56:59], v[64:65], off offset:2048
	global_load_dwordx4 v[60:63], v[64:65], off offset:3072
	v_lshl_add_u64 v[64:65], v[82:83], 0, v[6:7]
	global_load_dwordx4 v[64:67], v[64:65], off
	v_lshl_add_u64 v[68:69], v[82:83], 0, v[8:9]
	v_lshl_add_u64 v[86:87], v[82:83], 0, v[10:11]
	global_load_dwordx4 v[68:71], v[68:69], off
	v_lshl_add_u64 v[84:85], v[80:81], 0, v[10:11]
	global_load_dwordx4 v[72:75], v[86:87], off
	global_load_dwordx4 v[76:79], v[84:85], off
	v_lshl_add_u64 v[90:91], v[82:83], 0, v[12:13]
	v_lshl_add_u64 v[88:89], v[80:81], 0, v[12:13]
	global_load_dwordx4 v[80:83], v[90:91], off
	global_load_dwordx4 v[84:87], v[88:89], off
	s_waitcnt vmcnt(0)
	v_mov_b32_e32 v89, v18
	v_mov_b32_e32 v93, v28
	v_mov_b32_e32 v97, v32
	v_mov_b32_e32 v91, v20
	v_mov_b32_e32 v95, v30
	v_mov_b32_e32 v101, v36
	v_mov_b32_e32 v18, v49
	v_mov_b32_e32 v28, v53
	v_mov_b32_e32 v88, v48
	v_mov_b32_e32 v92, v52
	v_mov_b32_e32 v32, v57
	v_pk_mul_f32 v[18:19], v[18:19], v[18:19]
	v_pk_mul_f32 v[28:29], v[28:29], v[28:29]
	v_mov_b32_e32 v90, v50
	v_mov_b32_e32 v94, v54
	v_mov_b32_e32 v96, v56
	v_mov_b32_e32 v36, v61
	v_pk_mul_f32 v[32:33], v[32:33], v[32:33]
	v_pk_fma_f32 v[18:19], v[88:89], v[88:89], v[18:19]
	v_pk_fma_f32 v[28:29], v[92:93], v[92:93], v[28:29]
	v_mov_b32_e32 v99, v34
	v_mov_b32_e32 v20, v51
	v_mov_b32_e32 v30, v55
	v_mov_b32_e32 v98, v58
	v_mov_b32_e32 v100, v60
	v_pk_mul_f32 v[36:37], v[36:37], v[36:37]
	v_pk_fma_f32 v[32:33], v[96:97], v[96:97], v[32:33]
	v_pk_fma_f32 v[18:19], v[90:91], v[90:91], v[18:19]
	v_pk_fma_f32 v[28:29], v[94:95], v[94:95], v[28:29]
	v_mov_b32_e32 v103, v38
	v_mov_b32_e32 v34, v59
	v_mov_b32_e32 v102, v62
	v_pk_fma_f32 v[36:37], v[100:101], v[100:101], v[36:37]
	v_pk_fma_f32 v[32:33], v[98:99], v[98:99], v[32:33]
	v_pk_fma_f32 v[18:19], v[20:21], v[20:21], v[18:19]
	v_pk_fma_f32 v[20:21], v[30:31], v[30:31], v[28:29]
	v_mov_b32_e32 v105, v40
	v_mov_b32_e32 v38, v63
	v_mov_b32_e32 v40, v65
	v_pk_fma_f32 v[36:37], v[102:103], v[102:103], v[36:37]
	v_pk_fma_f32 v[28:29], v[34:35], v[34:35], v[32:33]
	v_pk_add_f32 v[18:19], v[18:19], v[20:21]
	v_mov_b32_e32 v109, v44
	v_mov_b32_e32 v104, v64
	v_mov_b32_e32 v44, v69
	v_pk_mul_f32 v[40:41], v[40:41], v[40:41]
	v_pk_fma_f32 v[30:31], v[38:39], v[38:39], v[36:37]
	v_pk_add_f32 v[18:19], v[18:19], v[28:29]
	v_mov_b32_e32 v29, v76
	v_mov_b32_e32 v76, v73
	v_mov_b32_e32 v107, v42
	v_mov_b32_e32 v106, v66
	v_mov_b32_e32 v108, v68
	v_pk_mul_f32 v[44:45], v[44:45], v[44:45]
	v_pk_fma_f32 v[40:41], v[104:105], v[104:105], v[40:41]
	v_pk_add_f32 v[18:19], v[18:19], v[30:31]
	v_mov_b32_e32 v28, v72
	v_pk_mul_f32 v[30:31], v[76:77], v[76:77]
	v_mov_b32_e32 v42, v67
	v_mov_b32_e32 v48, v70
	v_pk_fma_f32 v[44:45], v[108:109], v[108:109], v[44:45]
	v_pk_fma_f32 v[40:41], v[106:107], v[106:107], v[40:41]
	v_mov_b32_e32 v49, v46
	v_pk_fma_f32 v[28:29], v[28:29], v[28:29], v[30:31]
	v_mov_b32_e32 v30, v74
	v_mov_b32_e32 v31, v78
	v_pk_fma_f32 v[32:33], v[42:43], v[42:43], v[40:41]
	v_pk_fma_f32 v[20:21], v[48:49], v[48:49], v[44:45]
	v_mov_b32_e32 v46, v71
	v_pk_fma_f32 v[28:29], v[30:31], v[30:31], v[28:29]
	v_mov_b32_e32 v31, v84
	v_mov_b32_e32 v84, v81
	v_pk_add_f32 v[18:19], v[18:19], v[32:33]
	v_pk_fma_f32 v[20:21], v[46:47], v[46:47], v[20:21]
	v_mov_b32_e32 v78, v75
	v_mov_b32_e32 v30, v80
	v_pk_mul_f32 v[32:33], v[84:85], v[84:85]
	v_pk_add_f32 v[18:19], v[18:19], v[20:21]
	v_pk_fma_f32 v[30:31], v[30:31], v[30:31], v[32:33]
	v_mov_b32_e32 v32, v82
	v_mov_b32_e32 v33, v86
	v_pk_fma_f32 v[20:21], v[78:79], v[78:79], v[28:29]
	v_mov_b32_e32 v86, v83
	v_pk_add_f32 v[18:19], v[18:19], v[20:21]
	v_pk_fma_f32 v[20:21], v[32:33], v[32:33], v[30:31]
	s_nop 0
	v_pk_fma_f32 v[20:21], v[86:87], v[86:87], v[20:21]
	s_nop 0
	v_pk_add_f32 v[18:19], v[18:19], v[20:21]
	ds_bpermute_b32 v21, v1, v19
	ds_bpermute_b32 v20, v1, v18
	s_waitcnt lgkmcnt(0)
	v_pk_add_f32 v[18:19], v[18:19], v[20:21]
	ds_bpermute_b32 v21, v15, v19
	ds_bpermute_b32 v20, v15, v18
	s_waitcnt lgkmcnt(0)
	v_pk_add_f32 v[18:19], v[18:19], v[20:21]
	ds_bpermute_b32 v21, v22, v19
	ds_bpermute_b32 v20, v22, v18
	s_waitcnt lgkmcnt(0)
	v_pk_add_f32 v[18:19], v[18:19], v[20:21]
	ds_bpermute_b32 v21, v23, v19
	ds_bpermute_b32 v20, v23, v18
	s_waitcnt lgkmcnt(0)
	v_pk_add_f32 v[18:19], v[18:19], v[20:21]
	ds_bpermute_b32 v21, v24, v19
	ds_bpermute_b32 v20, v24, v18
	s_waitcnt lgkmcnt(0)
	v_pk_add_f32 v[18:19], v[18:19], v[20:21]
	ds_bpermute_b32 v21, v25, v19
	ds_bpermute_b32 v20, v25, v18
	s_and_saveexec_b64 s[22:23], vcc
	s_cbranch_execz .LBB1_38
	s_waitcnt lgkmcnt(0)
	v_pk_add_f32 v[18:19], v[18:19], v[20:21]
	v_lshl_add_u64 v[2:3], v[2:3], 2, s[16:17]
	v_pk_fma_f32 v[18:19], v[18:19], s[20:21], v[14:15] op_sel_hi:[1,0,0]
	s_nop 0
	v_mul_f32_e32 v20, 0x4b800000, v19
	v_cmp_gt_f32_e64 s[4:5], s25, v19
	v_cmp_gt_f32_e64 s[6:7], s25, v18
	s_nop 0
	v_cndmask_b32_e64 v19, v19, v20, s[4:5]
	v_rsq_f32_e32 v19, v19
	v_mul_f32_e32 v20, 0x4b800000, v18
	v_cndmask_b32_e64 v18, v18, v20, s[6:7]
	v_rsq_f32_e32 v18, v18
	v_mul_f32_e32 v20, 0x45800000, v19
	v_cndmask_b32_e64 v19, v19, v20, s[4:5]
	global_store_dword v[2:3], v19, off
	v_mul_f32_e32 v2, 0x45800000, v18
	v_cndmask_b32_e64 v18, v18, v2, s[6:7]
	v_lshl_add_u64 v[2:3], v[16:17], 2, s[16:17]
	global_store_dword v[2:3], v18, off
	s_branch .LBB1_38

; DI unsigned pack2(float a, float b) { f32x2 v = {a, b}; hwbf16x2 r = __builtin_convertvector(v, hwbf16x2); return __builtin_bit_cast(unsigned, r); }
; template <bool BF> DI void pool_phase(const Params& p, const void* x, const float* gain) {
;     ...
;     for (int t = t0; t < t1; ++t) {
;         const int b = t / S, s = t - b * S;
;         const int lo = max(s - left, 0), hi = min(s + right + 1, S);
;         if (t == t0 || s == 0) {
;             sum = (f32x4){0.f, 0.f, 0.f, 0.f};
;             for (int u = lo; u < hi; ++u) { const int tu = b * S + u; const float r = rstd[tu]; const f32x4 v = ldx4<BF>(x, (size_t)tu * D + tid * 4); sum += v * r; }
;         } else {
;             if (hi > phi) { const int tu = b * S + hi - 1; sum += ldx4<BF>(x, (size_t)tu * D + tid * 4) * rstd[tu]; }
;             if (lo > plo) { const int tu = b * S + plo;    sum -= ldx4<BF>(x, (size_t)tu * D + tid * 4) * rstd[tu]; }
;         }
;         plo = lo; phi = hi;
;         const float rc = 1.0f / (float)(hi - lo);
;         const f32x4 me = ldx4<BF>(x, (size_t)t * D + tid * 4) * rstd[t];
;         const f32x4 o = (sum * rc - me) * gn;
;         u32x2 w; w[0] = pack2(o[0], o[1]); w[1] = pack2(o[2], o[3]);
;         *(u32x2*)(H + (size_t)t * D + tid * 4) = w;
.LBB1_109:
	s_lshl_b64 s[14:15], s[10:11], 13
	v_lshl_add_u64 v[14:15], v[6:7], 0, s[14:15]
	s_lshl_b64 s[14:15], s[10:11], 2
	s_add_u32 s14, s8, s14
	s_addc_u32 s15, s9, s15
	v_mov_b64_e32 v[20:21], s[14:15]
	global_load_dwordx4 v[14:17], v[14:15], off
	s_lshl_b64 s[14:15], s[10:11], 12
	global_load_dword v20, v[20:21], off
	v_sub_u32_e32 v21, v18, v19
	v_cvt_f32_i32_e32 v21, v21
	v_lshl_add_u64 v[22:23], v[8:9], 0, s[14:15]
	s_add_i32 s10, s10, 1
	v_add_u32_e32 v5, 1, v5
	v_div_scale_f32 v24, s[14:15], v21, v21, 1.0
	v_rcp_f32_e32 v25, v24
	v_div_scale_f32 v26, vcc, 1.0, v21, 1.0
	s_cmp_lt_i32 s10, s4
	v_fma_f32 v27, -v24, v25, 1.0
	v_fmac_f32_e32 v25, v27, v25
	v_mul_f32_e32 v27, v26, v25
	v_fma_f32 v28, -v24, v27, v26
	v_fmac_f32_e32 v27, v28, v25
	v_fma_f32 v24, -v24, v27, v26
	v_div_fmas_f32 v24, v24, v25, v27
	v_div_fixup_f32 v24, v24, v21, 1.0
	s_waitcnt vmcnt(0) lgkmcnt(0)
	v_pk_mul_f32 v[16:17], v[16:17], v[20:21] op_sel_hi:[1,0]
	v_pk_mul_f32 v[14:15], v[14:15], v[20:21] op_sel_hi:[1,0]
	v_pk_fma_f32 v[16:17], v[24:25], v[12:13], v[16:17] op_sel_hi:[0,1,1] neg_lo:[0,0,1] neg_hi:[0,0,1]
	v_pk_fma_f32 v[14:15], v[24:25], v[10:11], v[14:15] op_sel_hi:[0,1,1] neg_lo:[0,0,1] neg_hi:[0,0,1]
	v_pk_mul_f32 v[16:17], v[2:3], v[16:17]
	v_pk_mul_f32 v[14:15], v[0:1], v[14:15]
	s_nop 0
	v_cvt_pk_bf16_f32 v14, v14, v15
	v_cvt_pk_bf16_f32 v15, v16, v17
	global_store_dwordx2 v[22:23], v[14:15], off
	v_mov_b32_e32 v15, v18
	s_cbranch_scc0 .LBB1_121
.LBB1_110:
	s_ashr_i32 s11, s10, 31
	s_lshr_b32 s5, s11, 20
	s_add_i32 s5, s10, s5
	s_and_b32 s5, s5, 0xfffff000
	s_sub_i32 s14, s10, s5
	s_cmp_lg_u32 s10, s3
	v_sub_u32_e32 v14, s14, v37
	v_add_u32_e32 v16, s14, v37
	s_cselect_b64 s[14:15], -1, 0
	s_cmp_lg_u32 s10, s5
	s_cselect_b64 s[16:17], -1, 0
	s_and_b64 s[16:17], s[14:15], s[16:17]
	v_min_i32_e32 v18, 0x1000, v16
	s_mov_b64 s[14:15], -1
	s_and_b64 vcc, exec, s[16:17]
	s_cbranch_vccz .LBB1_116
	v_cmp_gt_i32_e32 vcc, v18, v15
	s_and_saveexec_b64 s[14:15], vcc
	s_cbranch_execz .LBB1_113
	v_add3_u32 v16, s5, -1, v18
	v_ashrrev_i32_e32 v17, 31, v16
	v_lshlrev_b64 v[20:21], 13, v[16:17]
	v_lshl_add_u64 v[20:21], v[6:7], 0, v[20:21]
	v_lshl_add_u64 v[16:17], v[16:17], 2, s[8:9]
	global_load_dword v16, v[16:17], off
	s_nop 0
	global_load_dwordx4 v[20:23], v[20:21], off
	s_waitcnt vmcnt(0) lgkmcnt(0)
	v_pk_fma_f32 v[12:13], v[22:23], v[16:17], v[12:13] op_sel_hi:[1,0,1]
	v_pk_fma_f32 v[10:11], v[20:21], v[16:17], v[10:11] op_sel_hi:[1,0,1]
.LBB1_113:
	s_or_b64 exec, exec, s[14:15]
	v_cmp_gt_i32_e32 vcc, v14, v19
	s_and_saveexec_b64 s[14:15], vcc
	s_cbranch_execz .LBB1_115
	v_add_u32_e32 v16, s5, v19
	v_ashrrev_i32_e32 v17, 31, v16
	v_lshlrev_b64 v[20:21], 13, v[16:17]
	v_lshl_add_u64 v[20:21], v[6:7], 0, v[20:21]
	global_load_dwordx4 v[20:23], v[20:21], off
	v_lshl_add_u64 v[16:17], v[16:17], 2, s[8:9]
	global_load_dword v16, v[16:17], off
	s_waitcnt vmcnt(0)
	v_xor_b32_e32 v23, 0x80000000, v23
	v_xor_b32_e32 v22, 0x80000000, v22
	s_waitcnt lgkmcnt(0)
	v_pk_fma_f32 v[12:13], v[22:23], v[16:17], v[12:13] op_sel_hi:[1,0,1]
	v_pk_fma_f32 v[10:11], v[20:21], v[16:17], v[10:11] op_sel_hi:[1,0,1] neg_lo:[1,0,0] neg_hi:[1,0,0]

; template <bool BF> DI void pool_phase(const Params& p, const void* x, const float* gain) {
;     ...
;             for (int u = lo; u < hi; ++u) { const int tu = b * S + u; const float r = rstd[tu]; const f32x4 v = ldx4<BF>(x, (size_t)tu * D + tid * 4); sum += v * r; }
.LBB1_119:
	global_load_dword v26, v[16:17], off
	global_load_dwordx4 v[22:25], v[14:15], off
	v_add_u32_e32 v20, 1, v20
	v_cmp_ge_i32_e32 vcc, v20, v18
	v_lshl_add_u64 v[14:15], v[14:15], 0, s[18:19]
	v_lshl_add_u64 v[16:17], v[16:17], 0, 4
	s_or_b64 s[16:17], vcc, s[16:17]
	s_waitcnt vmcnt(0) lgkmcnt(0)
	v_pk_fma_f32 v[12:13], v[24:25], v[26:27], v[12:13] op_sel_hi:[1,0,1]
	v_pk_fma_f32 v[10:11], v[22:23], v[26:27], v[10:11] op_sel_hi:[1,0,1]
	s_andn2_b64 exec, exec, s[16:17]
	s_cbranch_execnz .LBB1_119
	s_or_b64 exec, exec, s[16:17]
	s_branch .LBB1_108

; template <bool BF> DI void pool_phase(const Params& p, const void* x, const float* gain) {
;     ...
;             for (int u = lo; u < hi; ++u) { const int tu = b * S + u; sm[c] += ldx4<BF>(x, (size_t)tu * D + tid * 4) * rstd[tu]; }
.LBB1_125:
	v_add_u32_e32 v6, s2, v4
	v_ashrrev_i32_e32 v7, 31, v6
	v_lshlrev_b64 v[8:9], 13, v[6:7]
	v_lshl_add_u64 v[6:7], v[6:7], 2, s[8:9]
	v_lshl_add_u64 v[8:9], v[52:53], 0, v[8:9]
	global_load_dword v10, v[6:7], off
	s_nop 0
	global_load_dwordx4 v[6:9], v[8:9], off
	v_add_u32_e32 v4, 1, v4
	v_cmp_ge_i32_e32 vcc, v4, v75
	s_or_b64 s[16:17], vcc, s[16:17]
	s_waitcnt vmcnt(0) lgkmcnt(0)
	v_pk_fma_f32 v[20:21], v[8:9], v[10:11], v[20:21] op_sel_hi:[1,0,1]
	v_pk_fma_f32 v[18:19], v[6:7], v[10:11], v[18:19] op_sel_hi:[1,0,1]
	s_andn2_b64 exec, exec, s[16:17]
	s_cbranch_execnz .LBB1_125
	s_or_b64 exec, exec, s[16:17]

; template <bool BF> DI void pool_phase(const Params& p, const void* x, const float* gain) {
;     ...
;             for (int u = lo; u < hi; ++u) { const int tu = b * S + u; sm[c] += ldx4<BF>(x, (size_t)tu * D + tid * 4) * rstd[tu]; }
.LBB1_129:
	v_add_u32_e32 v6, s4, v4
	v_ashrrev_i32_e32 v7, 31, v6
	v_lshlrev_b64 v[8:9], 13, v[6:7]
	v_lshl_add_u64 v[6:7], v[6:7], 2, s[8:9]
	v_lshl_add_u64 v[8:9], v[52:53], 0, v[8:9]
	global_load_dword v10, v[6:7], off
	s_nop 0
	global_load_dwordx4 v[6:9], v[8:9], off
	v_add_u32_e32 v4, 1, v4
	v_cmp_ge_i32_e32 vcc, v4, v40
	s_or_b64 s[18:19], vcc, s[18:19]
	s_waitcnt vmcnt(0) lgkmcnt(0)
	v_pk_fma_f32 v[24:25], v[8:9], v[10:11], v[24:25] op_sel_hi:[1,0,1]
	v_pk_fma_f32 v[22:23], v[6:7], v[10:11], v[22:23] op_sel_hi:[1,0,1]
	s_andn2_b64 exec, exec, s[18:19]
	s_cbranch_execnz .LBB1_129
	s_or_b64 exec, exec, s[18:19]
	s_mov_b32 s3, 0
	v_mov_b32_e32 v26, s3
	v_mov_b32_e32 v27, s3
	v_mov_b32_e32 v28, s3
	v_mov_b32_e32 v29, s3
	v_mov_b32_e32 v30, s3
	v_mov_b32_e32 v31, s3
	v_mov_b32_e32 v32, s3
	v_mov_b32_e32 v33, s3

; template <bool BF> DI void pool_phase(const Params& p, const void* x, const float* gain) {
;     ...
;             for (int u = lo; u < hi; ++u) { const int tu = b * S + u; sm[c] += ldx4<BF>(x, (size_t)tu * D + tid * 4) * rstd[tu]; }
.LBB1_133:
	v_add_u32_e32 v6, s3, v4
	v_ashrrev_i32_e32 v7, 31, v6
	v_lshlrev_b64 v[8:9], 13, v[6:7]
	v_lshl_add_u64 v[6:7], v[6:7], 2, s[8:9]
	v_lshl_add_u64 v[8:9], v[52:53], 0, v[8:9]
	global_load_dword v10, v[6:7], off
	s_nop 0
	global_load_dwordx4 v[6:9], v[8:9], off
	v_add_u32_e32 v4, 1, v4
	v_cmp_ge_i32_e32 vcc, v4, v45
	s_or_b64 s[20:21], vcc, s[20:21]
	s_waitcnt vmcnt(0) lgkmcnt(0)
	v_pk_fma_f32 v[28:29], v[8:9], v[10:11], v[28:29] op_sel_hi:[1,0,1]
	v_pk_fma_f32 v[26:27], v[6:7], v[10:11], v[26:27] op_sel_hi:[1,0,1]
	s_andn2_b64 exec, exec, s[20:21]
	s_cbranch_execnz .LBB1_133
	s_or_b64 exec, exec, s[20:21]
	s_mov_b32 s17, 0
	v_mov_b32_e32 v30, s17
	v_mov_b32_e32 v31, s17
	v_mov_b32_e32 v32, s17
	v_mov_b32_e32 v33, s17

; DI unsigned pack2(float a, float b) { f32x2 v = {a, b}; hwbf16x2 r = __builtin_convertvector(v, hwbf16x2); return __builtin_bit_cast(unsigned, r); }
; template <bool BF> DI void pool_phase(const Params& p, const void* x, const float* gain) {
;     ...
;             for (int u = lo; u < hi; ++u) { const int tu = b * S + u; sm[c] += ldx4<BF>(x, (size_t)tu * D + tid * 4) * rstd[tu]; }
;     ...
;         for (int i = 0; i < 16; ++i) {
;             f32x4 va[4], vs[4], vm[4]; float ra[4], rs[4], rm[4], rc[4];
; #pragma unroll
;             for (int c = 0; c < 4; ++c) {
;                 const int t = tb + 16 * c + i, b = t / S, s = t - b * S;
;                 const int lo = max(s - left, 0), hi = min(s + right + 1, S);
;                 const int ta = b * S + hi - 1, ts = b * S + pl[c];
;                 va[c] = ldx4<BF>(x, (size_t)ta * D + tid * 4); vs[c] = ldx4<BF>(x, (size_t)ts * D + tid * 4); vm[c] = ldx4<BF>(x, (size_t)t * D + tid * 4);
;                 ra[c] = (i > 0 && hi > ph[c]) ? rstd[ta] : 0.f; rs[c] = (i > 0 && lo > pl[c]) ? rstd[ts] : 0.f; rm[c] = rstd[t];
;                 rc[c] = 1.0f / (float)(hi - lo); pl[c] = lo; ph[c] = hi;
;             }
; #pragma unroll
;             for (int c = 0; c < 4; ++c) {
;                 const int t = tb + 16 * c + i;
;                 sm[c] += va[c] * ra[c] - vs[c] * rs[c];
;                 const f32x4 o = (sm[c] * rc[c] - vm[c] * rm[c]) * gn;
;                 u32x2 w; w[0] = pack2(o[0], o[1]); w[1] = pack2(o[2], o[3]);
;                 *(u32x2*)(H + (size_t)t * D + tid * 4) = w;
;             }
.LBB1_137:
	v_add_u32_e32 v6, s5, v4
	v_ashrrev_i32_e32 v7, 31, v6
	v_lshlrev_b64 v[8:9], 13, v[6:7]
	v_lshl_add_u64 v[6:7], v[6:7], 2, s[8:9]
	v_lshl_add_u64 v[8:9], v[52:53], 0, v[8:9]
	global_load_dword v10, v[6:7], off
	s_nop 0
	global_load_dwordx4 v[6:9], v[8:9], off
	v_add_u32_e32 v4, 1, v4
	v_cmp_ge_i32_e32 vcc, v4, v77
	s_or_b64 s[22:23], vcc, s[22:23]
	s_waitcnt vmcnt(0) lgkmcnt(0)
	v_pk_fma_f32 v[32:33], v[8:9], v[10:11], v[32:33] op_sel_hi:[1,0,1]
	v_pk_fma_f32 v[30:31], v[6:7], v[10:11], v[30:31] op_sel_hi:[1,0,1]
	s_andn2_b64 exec, exec, s[22:23]
	s_cbranch_execnz .LBB1_137
	s_or_b64 exec, exec, s[22:23]
.LBB1_139:
	s_or_b64 exec, exec, s[14:15]
	v_add_u32_e32 v8, s2, v38
	s_lshl_b64 s[22:23], s[10:11], 13
	s_lshl_b64 s[14:15], s[10:11], 2
	s_add_u32 s24, s8, s14
	v_ashrrev_i32_e32 v9, 31, v8
	v_add3_u32 v12, s2, -1, v75
	s_addc_u32 s25, s9, s15
	v_lshlrev_b64 v[8:9], 13, v[8:9]
	v_ashrrev_i32_e32 v13, 31, v12
	v_lshl_add_u64 v[4:5], v[52:53], 0, s[22:23]
	v_mov_b64_e32 v[10:11], s[24:25]
	v_lshl_add_u64 v[8:9], v[52:53], 0, v[8:9]
	v_lshlrev_b64 v[12:13], 13, v[12:13]
	global_load_dwordx4 v[4:7], v[4:5], off
	v_lshl_add_u64 v[12:13], v[52:53], 0, v[12:13]
	global_load_dword v36, v[10:11], off
	v_add_u32_e32 v46, s4, v39
	global_load_dwordx4 v[8:11], v[8:9], off
	v_add3_u32 v42, s4, -1, v40
	global_load_dwordx4 v[12:15], v[12:13], off
	v_ashrrev_i32_e32 v47, 31, v46
	v_ashrrev_i32_e32 v43, 31, v42
	v_lshlrev_b64 v[46:47], 13, v[46:47]
	v_lshlrev_b64 v[42:43], 13, v[42:43]
	v_lshl_add_u64 v[46:47], v[52:53], 0, v[46:47]
	v_lshl_add_u64 v[42:43], v[52:53], 0, v[42:43]
	global_load_dwordx4 v[46:49], v[46:47], off
	s_ashr_i32 s17, s16, 31
	global_load_dwordx4 v[58:61], v[42:43], off
	s_lshl_b64 s[24:25], s[16:17], 13
	s_lshl_b64 s[26:27], s[16:17], 2
	v_lshl_add_u64 v[42:43], v[52:53], 0, s[24:25]
	s_add_u32 s24, s8, s26
	s_addc_u32 s25, s9, s27
	global_load_dwordx4 v[62:65], v[42:43], off
	v_mov_b64_e32 v[42:43], s[24:25]
	global_load_dword v42, v[42:43], off
	v_sub_u32_e32 v41, v75, v38
	v_cvt_f32_i32_e32 v41, v41
	v_add3_u32 v50, s3, -1, v45
	v_add_u32_e32 v54, s3, v44
	v_ashrrev_i32_e32 v51, 31, v50
	v_ashrrev_i32_e32 v55, 31, v54
	v_add_u32_e32 v66, s5, v79
	v_lshlrev_b64 v[50:51], 13, v[50:51]
	v_lshlrev_b64 v[54:55], 13, v[54:55]
	v_ashrrev_i32_e32 v67, 31, v66
	v_lshl_add_u64 v[50:51], v[52:53], 0, v[50:51]
	v_lshl_add_u64 v[54:55], v[52:53], 0, v[54:55]
	v_div_scale_f32 v43, s[2:3], v41, v41, 1.0
	v_lshlrev_b64 v[80:81], 13, v[66:67]
	global_load_dwordx4 v[66:69], v[50:51], off
	global_load_dwordx4 v[70:73], v[54:55], off
	v_rcp_f32_e32 v55, v43
	v_add3_u32 v56, s5, -1, v77
	s_ashr_i32 s19, s18, 31
	v_ashrrev_i32_e32 v57, 31, v56
	s_lshl_b64 s[2:3], s[18:19], 13
	s_lshl_b64 s[4:5], s[18:19], 2
	v_lshlrev_b64 v[56:57], 13, v[56:57]
	s_add_u32 s4, s8, s4
	v_lshl_add_u64 v[82:83], v[52:53], 0, v[56:57]
	s_addc_u32 s5, s9, s5
	v_fma_f32 v56, -v43, v55, 1.0
	v_div_scale_f32 v54, vcc, 1.0, v41, 1.0
	v_mov_b64_e32 v[50:51], s[4:5]
	v_fmac_f32_e32 v55, v56, v55
	global_load_dword v50, v[50:51], off
	v_mul_f32_e32 v51, v54, v55
	v_fma_f32 v56, -v43, v51, v54
	v_fmac_f32_e32 v51, v56, v55
	v_fma_f32 v43, -v43, v51, v54
	v_div_fmas_f32 v43, v43, v55, v51
	s_ashr_i32 s21, s20, 31
	v_div_fixup_f32 v74, v43, v41, 1.0
	s_lshl_b64 s[4:5], s[20:21], 13
	s_lshl_b64 s[24:25], s[20:21], 2
	s_add_u32 s24, s8, s24
	s_addc_u32 s25, s9, s25
	v_sub_u32_e32 v41, v40, v39
	v_cvt_f32_i32_e32 v41, v41
	v_lshlrev_b64 v[34:35], 1, v[16:17]
	v_lshl_add_u64 v[84:85], s[12:13], 0, v[34:35]
	s_waitcnt vmcnt(0) lgkmcnt(0)
	v_pk_mul_f32 v[4:5], v[4:5], v[36:37] op_sel_hi:[1,0]
	v_pk_mul_f32 v[6:7], v[6:7], v[36:37] op_sel_hi:[1,0]
	v_pk_mul_f32 v[8:9], v[8:9], 0 op_sel_hi:[1,0]
	v_pk_mul_f32 v[10:11], v[10:11], 0 op_sel_hi:[1,0]
	v_pk_fma_f32 v[8:9], v[12:13], 0, v[8:9] op_sel_hi:[1,0,1] neg_lo:[0,0,1] neg_hi:[0,0,1]
	v_pk_fma_f32 v[10:11], v[14:15], 0, v[10:11] op_sel_hi:[1,0,1] neg_lo:[0,0,1] neg_hi:[0,0,1]
	v_pk_add_f32 v[56:57], v[18:19], v[8:9]
	v_pk_add_f32 v[54:55], v[20:21], v[10:11]
	v_pk_fma_f32 v[4:5], v[74:75], v[56:57], v[4:5] op_sel_hi:[0,1,1] neg_lo:[0,0,1] neg_hi:[0,0,1]
	v_pk_mul_f32 v[4:5], v[0:1], v[4:5]
	v_pk_fma_f32 v[6:7], v[74:75], v[54:55], v[6:7] op_sel_hi:[0,1,1] neg_lo:[0,0,1] neg_hi:[0,0,1]
	v_lshl_add_u64 v[12:13], v[52:53], 0, v[80:81]
	v_cvt_pk_bf16_f32 v80, v4, v5
	v_mov_b64_e32 v[4:5], s[24:25]
	v_pk_mul_f32 v[6:7], v[2:3], v[6:7]
	global_load_dword v36, v[4:5], off
	v_lshl_add_u64 v[4:5], v[52:53], 0, s[2:3]
	v_cvt_pk_bf16_f32 v81, v6, v7
	global_load_dwordx4 v[4:7], v[4:5], off
	s_nop 0
	global_load_dwordx4 v[8:11], v[82:83], off
	s_nop 0
	global_load_dwordx4 v[12:15], v[12:13], off
	v_lshl_add_u64 v[18:19], v[52:53], 0, s[4:5]
	global_load_dwordx4 v[18:21], v[18:19], off
	v_pk_mul_f32 v[48:49], v[48:49], 0 op_sel_hi:[1,0]
	v_div_scale_f32 v51, s[2:3], v41, v41, 1.0
	v_pk_fma_f32 v[48:49], v[60:61], 0, v[48:49] op_sel_hi:[1,0,1] neg_lo:[0,0,1] neg_hi:[0,0,1]
	v_rcp_f32_e32 v60, v51
	v_pk_mul_f32 v[46:47], v[46:47], 0 op_sel_hi:[1,0]
	v_pk_mul_f32 v[64:65], v[64:65], v[42:43] op_sel_hi:[1,0]
	v_pk_fma_f32 v[46:47], v[58:59], 0, v[46:47] op_sel_hi:[1,0,1] neg_lo:[0,0,1] neg_hi:[0,0,1]
	v_fma_f32 v58, -v51, v60, 1.0
	v_fmac_f32_e32 v60, v58, v60
	v_div_scale_f32 v58, vcc, 1.0, v41, 1.0
	v_mul_f32_e32 v59, v58, v60
	v_fma_f32 v61, -v51, v59, v58
	v_fmac_f32_e32 v59, v61, v60
	v_fma_f32 v51, -v51, v59, v58
	v_div_fmas_f32 v51, v51, v60, v59
	v_pk_mul_f32 v[42:43], v[62:63], v[42:43] op_sel_hi:[1,0]
	v_pk_add_f32 v[58:59], v[24:25], v[48:49]
	v_pk_add_f32 v[60:61], v[22:23], v[46:47]
	v_div_fixup_f32 v22, v51, v41, 1.0
; DI unsigned pack2(float a, float b) { f32x2 v = {a, b}; hwbf16x2 r = __builtin_convertvector(v, hwbf16x2); return __builtin_bit_cast(unsigned, r); }
; template <bool BF> DI void pool_phase(const Params& p, const void* x, const float* gain) {
;     ...
;         for (int i = 0; i < 16; ++i) {
;             f32x4 va[4], vs[4], vm[4]; float ra[4], rs[4], rm[4], rc[4];
; #pragma unroll
;             for (int c = 0; c < 4; ++c) {
;                 const int t = tb + 16 * c + i, b = t / S, s = t - b * S;
;                 const int lo = max(s - left, 0), hi = min(s + right + 1, S);
;                 const int ta = b * S + hi - 1, ts = b * S + pl[c];
;                 va[c] = ldx4<BF>(x, (size_t)ta * D + tid * 4); vs[c] = ldx4<BF>(x, (size_t)ts * D + tid * 4); vm[c] = ldx4<BF>(x, (size_t)t * D + tid * 4);
;                 ra[c] = (i > 0 && hi > ph[c]) ? rstd[ta] : 0.f; rs[c] = (i > 0 && lo > pl[c]) ? rstd[ts] : 0.f; rm[c] = rstd[t];
;                 rc[c] = 1.0f / (float)(hi - lo); pl[c] = lo; ph[c] = hi;
;             }
; #pragma unroll
;             for (int c = 0; c < 4; ++c) {
;                 const int t = tb + 16 * c + i;
;                 sm[c] += va[c] * ra[c] - vs[c] * rs[c];
;                 const f32x4 o = (sm[c] * rc[c] - vm[c] * rm[c]) * gn;
;                 u32x2 w; w[0] = pack2(o[0], o[1]); w[1] = pack2(o[2], o[3]);
;                 *(u32x2*)(H + (size_t)t * D + tid * 4) = w;
;             }
	v_pk_fma_f32 v[24:25], v[22:23], v[60:61], v[42:43] op_sel_hi:[0,1,1] neg_lo:[0,0,1] neg_hi:[0,0,1]
	v_pk_fma_f32 v[22:23], v[22:23], v[58:59], v[64:65] op_sel_hi:[0,1,1] neg_lo:[0,0,1] neg_hi:[0,0,1]
	v_pk_mul_f32 v[22:23], v[2:3], v[22:23]
	v_pk_mul_f32 v[24:25], v[0:1], v[24:25]
	s_lshl_b64 s[2:3], s[16:17], 12
	v_cvt_pk_bf16_f32 v24, v24, v25
	v_cvt_pk_bf16_f32 v25, v22, v23
	v_sub_u32_e32 v22, v45, v44
	v_cvt_f32_i32_e32 v41, v22
	v_lshl_add_u64 v[22:23], v[84:85], 0, s[2:3]
	v_sub_u32_e32 v48, v77, v79
	v_cvt_f32_i32_e32 v48, v48
	v_div_scale_f32 v42, s[2:3], v41, v41, 1.0
	v_rcp_f32_e32 v43, v42
	global_store_dwordx2 v[22:23], v[24:25], off
	v_pk_mul_f32 v[22:23], v[72:73], 0 op_sel_hi:[1,0]
	v_pk_mul_f32 v[24:25], v[70:71], 0 op_sel_hi:[1,0]
	v_fma_f32 v46, -v42, v43, 1.0
	v_fmac_f32_e32 v43, v46, v43
	v_div_scale_f32 v46, vcc, 1.0, v41, 1.0
	v_mul_f32_e32 v47, v46, v43
	v_fma_f32 v49, -v42, v47, v46
	v_fmac_f32_e32 v47, v49, v43
	v_div_scale_f32 v49, s[2:3], v48, v48, 1.0
	v_rcp_f32_e32 v51, v49
	v_fma_f32 v42, -v42, v47, v46
	v_div_fmas_f32 v42, v42, v43, v47
	v_pk_fma_f32 v[22:23], v[68:69], 0, v[22:23] op_sel_hi:[1,0,1] neg_lo:[0,0,1] neg_hi:[0,0,1]
	v_fma_f32 v43, -v49, v51, 1.0
	v_pk_fma_f32 v[24:25], v[66:67], 0, v[24:25] op_sel_hi:[1,0,1] neg_lo:[0,0,1] neg_hi:[0,0,1]
	v_fmac_f32_e32 v51, v43, v51
	v_div_scale_f32 v43, vcc, 1.0, v48, 1.0
	v_div_fixup_f32 v42, v42, v41, 1.0
	v_pk_add_f32 v[62:63], v[28:29], v[22:23]
	v_pk_add_f32 v[64:65], v[26:27], v[24:25]
	v_mul_f32_e32 v46, v43, v51
	v_fma_f32 v47, -v49, v46, v43
	s_lshl_b64 s[2:3], s[18:19], 12
	v_fmac_f32_e32 v46, v47, v51
	v_fma_f32 v41, -v49, v46, v43
	v_div_fmas_f32 v41, v41, v51, v46
	v_div_fixup_f32 v46, v41, v48, 1.0
	s_lshl_b64 s[24:25], s[10:11], 12
	v_lshl_add_u64 v[82:83], v[84:85], 0, s[24:25]
	global_store_dwordx2 v[82:83], v[80:81], off
	v_lshl_add_u64 v[70:71], s[24:25], 0, v[34:35]
	v_add_u32_e32 v81, s10, v37
	v_sub_u32_e32 v83, s10, v37
	s_waitcnt vmcnt(0)
	v_pk_mul_f32 v[6:7], v[6:7], v[50:51] op_sel_hi:[1,0]
	v_pk_mul_f32 v[4:5], v[4:5], v[50:51] op_sel_hi:[1,0]
	v_pk_fma_f32 v[6:7], v[42:43], v[62:63], v[6:7] op_sel_hi:[0,1,1] neg_lo:[0,0,1] neg_hi:[0,0,1]
	v_pk_fma_f32 v[4:5], v[42:43], v[64:65], v[4:5] op_sel_hi:[0,1,1] neg_lo:[0,0,1] neg_hi:[0,0,1]
	v_pk_mul_f32 v[6:7], v[2:3], v[6:7]
	v_pk_mul_f32 v[4:5], v[0:1], v[4:5]
	s_nop 0
	v_cvt_pk_bf16_f32 v4, v4, v5
	v_cvt_pk_bf16_f32 v5, v6, v7
	v_lshl_add_u64 v[6:7], v[84:85], 0, s[2:3]
	global_store_dwordx2 v[6:7], v[4:5], off
	v_pk_mul_f32 v[4:5], v[14:15], 0 op_sel_hi:[1,0]
	v_pk_mul_f32 v[6:7], v[12:13], 0 op_sel_hi:[1,0]
	v_pk_fma_f32 v[4:5], v[10:11], 0, v[4:5] op_sel_hi:[1,0,1] neg_lo:[0,0,1] neg_hi:[0,0,1]
	v_pk_fma_f32 v[6:7], v[8:9], 0, v[6:7] op_sel_hi:[1,0,1] neg_lo:[0,0,1] neg_hi:[0,0,1]
	v_pk_add_f32 v[66:67], v[32:33], v[4:5]
	v_pk_add_f32 v[68:69], v[30:31], v[6:7]
	s_waitcnt lgkmcnt(0)
	v_pk_mul_f32 v[4:5], v[20:21], v[36:37] op_sel_hi:[1,0]
	v_pk_mul_f32 v[6:7], v[18:19], v[36:37] op_sel_hi:[1,0]
	v_pk_fma_f32 v[4:5], v[46:47], v[66:67], v[4:5] op_sel_hi:[0,1,1] neg_lo:[0,0,1] neg_hi:[0,0,1]
	v_pk_fma_f32 v[6:7], v[46:47], v[68:69], v[6:7] op_sel_hi:[0,1,1] neg_lo:[0,0,1] neg_hi:[0,0,1]
	v_pk_mul_f32 v[4:5], v[2:3], v[4:5]
	v_pk_mul_f32 v[6:7], v[0:1], v[6:7]
	s_lshl_b64 s[2:3], s[20:21], 12
	v_cvt_pk_bf16_f32 v6, v6, v7
	v_cvt_pk_bf16_f32 v7, v4, v5
	v_lshl_add_u64 v[4:5], v[84:85], 0, s[2:3]
	s_add_u32 s2, s44, s22
	s_addc_u32 s3, s45, s23
	global_store_dwordx2 v[4:5], v[6:7], off
	v_lshl_add_u64 v[4:5], v[16:17], 2, s[2:3]
	s_mov_b64 s[2:3], 0x62000
	v_lshl_add_u64 v[72:73], v[4:5], 0, s[2:3]
	s_mov_b32 s2, 0
	s_branch .LBB1_141
.LBB1_140:
	s_or_b64 exec, exec, s[12:13]
	v_sub_u32_e32 v77, v91, v93
	v_cvt_f32_i32_e32 v77, v77
	v_sub_u32_e32 v79, v87, v89
	v_cvt_f32_i32_e32 v79, v79
	v_sub_u32_e32 v102, v75, v85
	v_div_scale_f32 v96, s[12:13], v77, v77, 1.0
	v_rcp_f32_e32 v97, v96
	v_div_scale_f32 v99, vcc, 1.0, v77, 1.0
	v_cvt_f32_i32_e32 v104, v102
	v_fma_f32 v100, -v96, v97, 1.0
	v_fmac_f32_e32 v97, v100, v97
	v_mul_f32_e32 v100, v99, v97
	v_fma_f32 v101, -v96, v100, v99
	v_fmac_f32_e32 v100, v101, v97
	v_fma_f32 v96, -v96, v100, v99
	v_div_scale_f32 v99, s[12:13], v79, v79, 1.0
	v_rcp_f32_e32 v101, v99
	v_div_fmas_f32 v96, v96, v97, v100
	v_div_fixup_f32 v96, v96, v77, 1.0
	s_add_u32 s14, s14, 4
	v_fma_f32 v77, -v99, v101, 1.0
	v_fmac_f32_e32 v101, v77, v101
	v_div_scale_f32 v77, vcc, 1.0, v79, 1.0
	v_mul_f32_e32 v97, v77, v101
	v_fma_f32 v100, -v99, v97, v77
	v_fmac_f32_e32 v97, v100, v101
	v_fma_f32 v77, -v99, v97, v77
	v_div_scale_f32 v99, s[12:13], v104, v104, 1.0
	v_rcp_f32_e32 v105, v99
	v_div_fmas_f32 v77, v77, v101, v97
	v_div_fixup_f32 v100, v77, v79, 1.0
	v_sub_u32_e32 v101, v95, v98
	v_fma_f32 v77, -v99, v105, 1.0
	v_fmac_f32_e32 v105, v77, v105
	v_div_scale_f32 v77, vcc, 1.0, v104, 1.0
	v_mul_f32_e32 v79, v77, v105
	v_fma_f32 v97, -v99, v79, v77
	v_fmac_f32_e32 v79, v97, v105
	v_fma_f32 v77, -v99, v79, v77
	v_mov_b32_e32 v97, s4
	v_mov_b32_e32 v99, s3
	s_mov_b32 s3, 0x13300000
	v_add_co_u32_e64 v102, s[40:41], s3, v97
	v_cvt_f32_i32_e32 v101, v101
	s_nop 0
	v_addc_co_u32_e64 v103, s[40:41], 0, v99, s[40:41]
	global_load_dword v102, v[102:103], off offset:196
	v_div_scale_f32 v97, s[4:5], v101, v101, 1.0
	v_rcp_f32_e32 v99, v97
	v_div_fmas_f32 v77, v77, v105, v79
	v_div_fixup_f32 v104, v77, v104, 1.0
	s_mov_b32 s3, 0x13311000
	v_fma_f32 v77, -v97, v99, 1.0
	v_fmac_f32_e32 v99, v77, v99
	v_div_scale_f32 v77, vcc, 1.0, v101, 1.0
	v_mul_f32_e32 v79, v77, v99
	v_fma_f32 v103, -v97, v79, v77
	v_fmac_f32_e32 v79, v103, v99
	v_fma_f32 v77, -v97, v79, v77
	v_div_fmas_f32 v77, v77, v99, v79
	s_waitcnt vmcnt(0) lgkmcnt(0)
; DI unsigned pack2(float a, float b) { f32x2 v = {a, b}; hwbf16x2 r = __builtin_convertvector(v, hwbf16x2); return __builtin_bit_cast(unsigned, r); }
; template <bool BF> DI void pool_phase(const Params& p, const void* x, const float* gain) {
;     ...
;         for (int i = 0; i < 16; ++i) {
;             f32x4 va[4], vs[4], vm[4]; float ra[4], rs[4], rm[4], rc[4];
; #pragma unroll
;             for (int c = 0; c < 4; ++c) {
;                 const int t = tb + 16 * c + i, b = t / S, s = t - b * S;
;                 const int lo = max(s - left, 0), hi = min(s + right + 1, S);
;                 const int ta = b * S + hi - 1, ts = b * S + pl[c];
;                 va[c] = ldx4<BF>(x, (size_t)ta * D + tid * 4); vs[c] = ldx4<BF>(x, (size_t)ts * D + tid * 4); vm[c] = ldx4<BF>(x, (size_t)t * D + tid * 4);
;                 ra[c] = (i > 0 && hi > ph[c]) ? rstd[ta] : 0.f; rs[c] = (i > 0 && lo > pl[c]) ? rstd[ts] : 0.f; rm[c] = rstd[t];
;                 rc[c] = 1.0f / (float)(hi - lo); pl[c] = lo; ph[c] = hi;
;             }
; #pragma unroll
;             for (int c = 0; c < 4; ++c) {
;                 const int t = tb + 16 * c + i;
;                 sm[c] += va[c] * ra[c] - vs[c] * rs[c];
;                 const f32x4 o = (sm[c] * rc[c] - vm[c] * rm[c]) * gn;
;                 u32x2 w; w[0] = pack2(o[0], o[1]); w[1] = pack2(o[2], o[3]);
;                 *(u32x2*)(H + (size_t)t * D + tid * 4) = w;
;             }
	v_pk_mul_f32 v[14:15], v[14:15], v[76:77] op_sel_hi:[1,0]
	v_pk_mul_f32 v[12:13], v[12:13], v[76:77] op_sel_hi:[1,0]
	v_pk_fma_f32 v[6:7], v[6:7], v[74:75], v[14:15] op_sel_hi:[1,0,1] neg_lo:[0,0,1] neg_hi:[0,0,1]
	v_pk_fma_f32 v[4:5], v[4:5], v[74:75], v[12:13] op_sel_hi:[1,0,1] neg_lo:[0,0,1] neg_hi:[0,0,1]
	v_pk_add_f32 v[54:55], v[54:55], v[6:7]
	v_pk_add_f32 v[56:57], v[56:57], v[4:5]
	v_pk_mul_f32 v[4:5], v[10:11], v[78:79] op_sel_hi:[1,0]
	v_pk_mul_f32 v[6:7], v[8:9], v[78:79] op_sel_hi:[1,0]
	v_pk_fma_f32 v[4:5], v[104:105], v[54:55], v[4:5] op_sel_hi:[0,1,1] neg_lo:[0,0,1] neg_hi:[0,0,1]
	v_pk_fma_f32 v[6:7], v[104:105], v[56:57], v[6:7] op_sel_hi:[0,1,1] neg_lo:[0,0,1] neg_hi:[0,0,1]
	v_pk_mul_f32 v[4:5], v[2:3], v[4:5]
	v_pk_mul_f32 v[6:7], v[0:1], v[6:7]
	v_div_fixup_f32 v106, v77, v101, 1.0
	v_cvt_pk_bf16_f32 v6, v6, v7
	v_cvt_pk_bf16_f32 v7, v4, v5
	v_lshl_add_u64 v[4:5], s[6:7], 0, v[70:71]
	v_add_co_u32_e32 v8, vcc, s3, v4
	s_mov_b32 s3, 0x13321000
	s_nop 0
	v_addc_co_u32_e32 v9, vcc, 0, v5, vcc
	global_store_dwordx2 v[8:9], v[6:7], off
	v_pk_mul_f32 v[6:7], v[26:27], v[82:83] op_sel_hi:[1,0]
	v_pk_mul_f32 v[8:9], v[24:25], v[82:83] op_sel_hi:[1,0]
	v_pk_fma_f32 v[6:7], v[18:19], v[80:81], v[6:7] op_sel_hi:[1,0,1] neg_lo:[0,0,1] neg_hi:[0,0,1]
	v_pk_fma_f32 v[8:9], v[16:17], v[80:81], v[8:9] op_sel_hi:[1,0,1] neg_lo:[0,0,1] neg_hi:[0,0,1]
	v_pk_add_f32 v[58:59], v[58:59], v[6:7]
	v_pk_add_f32 v[60:61], v[60:61], v[8:9]
	v_pk_mul_f32 v[6:7], v[22:23], v[84:85] op_sel_hi:[1,0]
	v_pk_mul_f32 v[8:9], v[20:21], v[84:85] op_sel_hi:[1,0]
	v_pk_fma_f32 v[6:7], v[100:101], v[58:59], v[6:7] op_sel_hi:[0,1,1] neg_lo:[0,0,1] neg_hi:[0,0,1]
	v_pk_fma_f32 v[8:9], v[100:101], v[60:61], v[8:9] op_sel_hi:[0,1,1] neg_lo:[0,0,1] neg_hi:[0,0,1]
	v_pk_mul_f32 v[6:7], v[2:3], v[6:7]
	v_pk_mul_f32 v[8:9], v[0:1], v[8:9]
	s_mov_b64 s[4:5], 0x1000
	v_cvt_pk_bf16_f32 v8, v8, v9
	v_cvt_pk_bf16_f32 v9, v6, v7
	v_add_co_u32_e32 v6, vcc, s3, v4
	s_mov_b32 s3, 0x13331000
	s_nop 0
	v_addc_co_u32_e32 v7, vcc, 0, v5, vcc
	global_store_dwordx2 v[6:7], v[8:9], off
	v_pk_mul_f32 v[6:7], v[38:39], v[88:89] op_sel_hi:[1,0]
	v_pk_mul_f32 v[8:9], v[36:37], v[88:89] op_sel_hi:[1,0]
	v_pk_fma_f32 v[6:7], v[30:31], v[86:87], v[6:7] op_sel_hi:[1,0,1] neg_lo:[0,0,1] neg_hi:[0,0,1]
	v_pk_fma_f32 v[8:9], v[28:29], v[86:87], v[8:9] op_sel_hi:[1,0,1] neg_lo:[0,0,1] neg_hi:[0,0,1]
	v_pk_add_f32 v[62:63], v[62:63], v[6:7]
	v_pk_add_f32 v[64:65], v[64:65], v[8:9]
	v_pk_mul_f32 v[6:7], v[34:35], v[90:91] op_sel_hi:[1,0]
	v_pk_mul_f32 v[8:9], v[32:33], v[90:91] op_sel_hi:[1,0]
	v_pk_fma_f32 v[6:7], v[96:97], v[62:63], v[6:7] op_sel_hi:[0,1,1] neg_lo:[0,0,1] neg_hi:[0,0,1]
	v_pk_fma_f32 v[8:9], v[96:97], v[64:65], v[8:9] op_sel_hi:[0,1,1] neg_lo:[0,0,1] neg_hi:[0,0,1]
	v_pk_mul_f32 v[6:7], v[2:3], v[6:7]
	v_pk_mul_f32 v[8:9], v[0:1], v[8:9]
	s_addc_u32 s15, s15, 0
	v_cvt_pk_bf16_f32 v8, v8, v9
	v_cvt_pk_bf16_f32 v9, v6, v7
	v_add_co_u32_e32 v6, vcc, s3, v4
	s_mov_b32 s3, 0x13341000
	s_nop 0
	v_addc_co_u32_e32 v7, vcc, 0, v5, vcc
	global_store_dwordx2 v[6:7], v[8:9], off
	v_pk_mul_f32 v[6:7], v[50:51], v[94:95] op_sel_hi:[1,0]
	v_pk_mul_f32 v[8:9], v[48:49], v[94:95] op_sel_hi:[1,0]
	v_pk_fma_f32 v[6:7], v[46:47], v[92:93], v[6:7] op_sel_hi:[1,0,1] neg_lo:[0,0,1] neg_hi:[0,0,1]
	v_pk_fma_f32 v[8:9], v[44:45], v[92:93], v[8:9] op_sel_hi:[1,0,1] neg_lo:[0,0,1] neg_hi:[0,0,1]
	v_pk_add_f32 v[66:67], v[66:67], v[6:7]
	v_pk_add_f32 v[68:69], v[68:69], v[8:9]
	v_pk_mul_f32 v[6:7], v[42:43], v[102:103] op_sel_hi:[1,0]
	v_pk_mul_f32 v[8:9], v[40:41], v[102:103] op_sel_hi:[1,0]
	v_pk_fma_f32 v[6:7], v[106:107], v[66:67], v[6:7] op_sel_hi:[0,1,1] neg_lo:[0,0,1] neg_hi:[0,0,1]
	v_pk_fma_f32 v[8:9], v[106:107], v[68:69], v[8:9] op_sel_hi:[0,1,1] neg_lo:[0,0,1] neg_hi:[0,0,1]
	v_pk_mul_f32 v[6:7], v[2:3], v[6:7]
	v_pk_mul_f32 v[8:9], v[0:1], v[8:9]
	v_add_co_u32_e32 v4, vcc, s3, v4
	s_add_i32 s2, s2, 1
	v_lshl_add_u64 v[70:71], v[70:71], 0, s[4:5]
	s_mov_b64 s[4:5], 0x2000
	v_cvt_pk_bf16_f32 v8, v8, v9
	v_cvt_pk_bf16_f32 v9, v6, v7
	v_addc_co_u32_e32 v5, vcc, 0, v5, vcc
	v_lshl_add_u64 v[72:73], v[72:73], 0, s[4:5]
	s_cmp_eq_u32 s2, 15
	v_mov_b32_e32 v77, v95
	v_mov_b32_e32 v45, v91
	v_mov_b32_e32 v40, v87
	v_mov_b32_e32 v38, v85
	v_mov_b32_e32 v39, v89
	v_mov_b32_e32 v44, v93
	v_mov_b32_e32 v79, v98
	global_store_dwordx2 v[4:5], v[8:9], off
	s_cbranch_scc1 .LBB1_157
.LBB1_141:
	s_add_i32 s5, s10, s2
	s_add_i32 s3, s5, 1
	s_ashr_i32 s4, s3, 31
	s_lshr_b32 s4, s4, 20
	s_add_i32 s3, s3, s4
	s_and_b32 s3, s3, 0xfffff000
	v_add_u32_e32 v46, s2, v81
	v_subrev_u32_e32 v4, s3, v46
	v_add_u32_e32 v4, 1, v4
	v_mov_b32_e32 v20, v75
	v_min_i32_e32 v75, 0x1000, v4
	v_add3_u32 v18, s3, -1, v75
	v_add_u32_e32 v16, s3, v38
	v_ashrrev_i32_e32 v19, 31, v18
	v_ashrrev_i32_e32 v17, 31, v16
	v_lshlrev_b64 v[4:5], 13, v[18:19]
	v_lshlrev_b64 v[6:7], 13, v[16:17]
	v_lshl_add_u64 v[4:5], v[52:53], 0, v[4:5]
	v_lshl_add_u64 v[8:9], v[52:53], 0, v[6:7]
	global_load_dwordx4 v[4:7], v[4:5], off
	s_nop 0
	global_load_dwordx4 v[12:15], v[8:9], off
	v_add_co_u32_e32 v8, vcc, 0xfffa0000, v72
	v_mov_b32_e32 v76, 0
	s_nop 0
	v_addc_co_u32_e32 v9, vcc, -1, v73, vcc
	global_load_dwordx4 v[8:11], v[8:9], off
	v_cmp_gt_i32_e32 vcc, v75, v20
	v_mov_b32_e32 v74, 0
	s_and_saveexec_b64 s[12:13], vcc
	s_cbranch_execz .LBB1_143
	v_lshl_add_u64 v[18:19], v[18:19], 2, s[8:9]
	global_load_dword v74, v[18:19], off
; template <bool BF> DI void pool_phase(const Params& p, const void* x, const float* gain) {
;     ...
;                 const int t = tb + 16 * c + i, b = t / S, s = t - b * S;
;                 const int lo = max(s - left, 0), hi = min(s + right + 1, S);
;                 const int ta = b * S + hi - 1, ts = b * S + pl[c];
;                 va[c] = ldx4<BF>(x, (size_t)ta * D + tid * 4); vs[c] = ldx4<BF>(x, (size_t)ts * D + tid * 4); vm[c] = ldx4<BF>(x, (size_t)t * D + tid * 4);
;                 ra[c] = (i > 0 && hi > ph[c]) ? rstd[ta] : 0.f; rs[c] = (i > 0 && lo > pl[c]) ? rstd[ts] : 0.f; rm[c] = rstd[t];
;                 rc[c] = 1.0f / (float)(hi - lo); pl[c] = lo; ph[c] = hi;
.LBB1_143:
	s_or_b64 exec, exec, s[12:13]
	s_sub_i32 s3, 0, s3
	v_add_u32_e32 v100, s2, v83
	v_add3_u32 v18, v100, s3, 1
	v_max_i32_e32 v85, 0, v18
	v_cmp_gt_i32_e32 vcc, v85, v38
	s_and_saveexec_b64 s[12:13], vcc
	s_cbranch_execz .LBB1_145
	v_lshl_add_u64 v[16:17], v[16:17], 2, s[8:9]
	global_load_dword v76, v[16:17], off
.LBB1_145:
	s_or_b64 exec, exec, s[12:13]
	s_add_u32 s4, s6, s14
	s_addc_u32 s3, s7, s15
	s_add_i32 s11, s5, 17
	s_ashr_i32 s12, s11, 31
	v_mov_b32_e32 v16, s4
	s_lshr_b32 s12, s12, 20
	v_add_co_u32_e32 v16, vcc, 0x13300000, v16
	v_mov_b32_e32 v17, s3
	s_add_i32 s11, s11, s12
	v_addc_co_u32_e32 v17, vcc, 0, v17, vcc
	s_and_b32 s11, s11, 0xfffff000
	global_load_dword v78, v[16:17], off offset:4
	v_subrev_u32_e32 v16, s11, v46
	v_add_u32_e32 v16, 17, v16
	v_min_i32_e32 v87, 0x1000, v16
	v_add3_u32 v30, s11, -1, v87
	v_add_u32_e32 v28, s11, v39
	v_ashrrev_i32_e32 v31, 31, v30
	v_ashrrev_i32_e32 v29, 31, v28
	v_lshlrev_b64 v[16:17], 13, v[30:31]
	v_lshlrev_b64 v[18:19], 13, v[28:29]
	v_lshl_add_u64 v[16:17], v[52:53], 0, v[16:17]
	v_lshl_add_u64 v[20:21], v[52:53], 0, v[18:19]
	global_load_dwordx4 v[16:19], v[16:17], off
	s_nop 0
	global_load_dwordx4 v[24:27], v[20:21], off
	v_add_co_u32_e32 v20, vcc, 0xfffc0000, v72
	v_mov_b32_e32 v82, 0
	s_nop 0
	v_addc_co_u32_e32 v21, vcc, -1, v73, vcc
	global_load_dwordx4 v[20:23], v[20:21], off
	v_cmp_gt_i32_e32 vcc, v87, v40
	v_mov_b32_e32 v80, 0
	s_and_saveexec_b64 s[12:13], vcc
	s_cbranch_execz .LBB1_147
	v_lshl_add_u64 v[30:31], v[30:31], 2, s[8:9]
	global_load_dword v80, v[30:31], off
.LBB1_147:
	s_or_b64 exec, exec, s[12:13]
	s_sub_i32 s11, 0, s11
	v_add3_u32 v30, v100, s11, 17
	v_max_i32_e32 v89, 0, v30
	v_cmp_gt_i32_e32 vcc, v89, v39
	s_and_saveexec_b64 s[12:13], vcc
	s_cbranch_execz .LBB1_149
	v_lshl_add_u64 v[28:29], v[28:29], 2, s[8:9]
	global_load_dword v82, v[28:29], off
.LBB1_149:
	s_or_b64 exec, exec, s[12:13]
	s_add_i32 s11, s5, 33
	s_ashr_i32 s12, s11, 31
	v_mov_b32_e32 v28, s4
	s_lshr_b32 s12, s12, 20
	v_add_co_u32_e32 v28, vcc, 0x13300000, v28
	v_mov_b32_e32 v29, s3
	s_add_i32 s11, s11, s12
	v_addc_co_u32_e32 v29, vcc, 0, v29, vcc
	s_and_b32 s11, s11, 0xfffff000
	global_load_dword v84, v[28:29], off offset:68
	v_subrev_u32_e32 v28, s11, v46
	v_add_u32_e32 v28, 33, v28
	v_min_i32_e32 v91, 0x1000, v28
	v_add3_u32 v42, s11, -1, v91
	v_add_u32_e32 v40, s11, v44
	v_ashrrev_i32_e32 v43, 31, v42
	v_ashrrev_i32_e32 v41, 31, v40
	v_lshlrev_b64 v[28:29], 13, v[42:43]
	v_lshlrev_b64 v[30:31], 13, v[40:41]
	v_lshl_add_u64 v[28:29], v[52:53], 0, v[28:29]
	v_lshl_add_u64 v[32:33], v[52:53], 0, v[30:31]
	global_load_dwordx4 v[28:31], v[28:29], off
	s_nop 0
	global_load_dwordx4 v[36:39], v[32:33], off
	v_add_co_u32_e32 v32, vcc, 0xfffe0000, v72
	v_mov_b32_e32 v88, 0
	s_nop 0
	v_addc_co_u32_e32 v33, vcc, -1, v73, vcc
	global_load_dwordx4 v[32:35], v[32:33], off
	v_cmp_gt_i32_e32 vcc, v91, v45
	v_mov_b32_e32 v86, 0
	s_and_saveexec_b64 s[12:13], vcc
	s_cbranch_execz .LBB1_151
	v_lshl_add_u64 v[42:43], v[42:43], 2, s[8:9]
	global_load_dword v86, v[42:43], off
.LBB1_151:
	s_or_b64 exec, exec, s[12:13]
	s_sub_i32 s11, 0, s11
	v_add3_u32 v42, v100, s11, 33
	v_max_i32_e32 v93, 0, v42
	v_cmp_gt_i32_e32 vcc, v93, v44
	s_and_saveexec_b64 s[12:13], vcc
	s_cbranch_execz .LBB1_153
	v_lshl_add_u64 v[40:41], v[40:41], 2, s[8:9]
	global_load_dword v88, v[40:41], off
.LBB1_153:
	s_or_b64 exec, exec, s[12:13]
	s_add_i32 s5, s5, 49
	s_ashr_i32 s11, s5, 31
	v_mov_b32_e32 v40, s4
	s_lshr_b32 s11, s11, 20
	v_add_co_u32_e32 v40, vcc, 0x13300000, v40
	v_mov_b32_e32 v41, s3
	s_add_i32 s5, s5, s11
	v_addc_co_u32_e32 v41, vcc, 0, v41, vcc
	s_and_b32 s5, s5, 0xfffff000
	global_load_dword v90, v[40:41], off offset:132
	v_subrev_u32_e32 v40, s5, v46
	v_add_u32_e32 v40, 49, v40
	v_min_i32_e32 v95, 0x1000, v40
	v_add3_u32 v98, s5, -1, v95
	v_add_u32_e32 v96, s5, v79
	v_ashrrev_i32_e32 v99, 31, v98
	v_ashrrev_i32_e32 v97, 31, v96
	v_lshlrev_b64 v[40:41], 13, v[98:99]
	v_lshlrev_b64 v[42:43], 13, v[96:97]
	v_lshl_add_u64 v[40:41], v[52:53], 0, v[40:41]
	v_lshl_add_u64 v[42:43], v[52:53], 0, v[42:43]
	global_load_dwordx4 v[44:47], v[40:41], off
	global_load_dwordx4 v[48:51], v[42:43], off
	s_nop 0
	global_load_dwordx4 v[40:43], v[72:73], off
	v_cmp_gt_i32_e32 vcc, v95, v77
	v_mov_b32_e32 v94, 0
	v_mov_b32_e32 v92, 0
	s_and_saveexec_b64 s[12:13], vcc
	s_cbranch_execz .LBB1_155
	v_lshl_add_u64 v[98:99], v[98:99], 2, s[8:9]
	global_load_dword v92, v[98:99], off
.LBB1_155:
	s_or_b64 exec, exec, s[12:13]
	s_sub_i32 s5, 0, s5
	v_add3_u32 v77, v100, s5, 49
	v_max_i32_e32 v98, 0, v77
	v_cmp_gt_i32_e32 vcc, v98, v79
	s_and_saveexec_b64 s[12:13], vcc
	s_cbranch_execz .LBB1_140
	v_lshl_add_u64 v[96:97], v[96:97], 2, s[8:9]
	global_load_dword v94, v[96:97], off
	s_branch .LBB1_140

; DI unsigned pack2(float a, float b) { f32x2 v = {a, b}; hwbf16x2 r = __builtin_convertvector(v, hwbf16x2); return __builtin_bit_cast(unsigned, r); }
; DI float bflo(unsigned w) { return __uint_as_float(w << 16); }
; DI float bfhi(unsigned w) { return __uint_as_float(w & 0xffff0000u); }
;     DI void operator()(const f32x4 (&acc)[2][2][4][2], const Unit& u, int wr, int wc, int fr, int fq) const {
;     ...
;             for (int n = 0; n < 2; ++n) sc[bj][n] = scale ? *(const f32x4*)(scale + col0 + bj * HALF + 4 * n) : (f32x4){1.f, 1.f, 1.f, 1.f};
; #pragma unroll
;         for (int ai = 0; ai < 2; ++ai)
; #pragma unroll
;             for (int m = 0; m < 4; ++m) { const size_t ro = (size_t)(row0 + ai * HALF + m * 16) * D + col0;
; #pragma unroll
;                 for (int bj = 0; bj < 2; ++bj) {
;                     f32x4 x0, x1;
;                     if constexpr (IB) { const u32x4 w = *(const u32x4*)((const bf16_t*)Xin + ro + bj * HALF);
;                         x0 = (f32x4){bflo(w[0]), bfhi(w[0]), bflo(w[1]), bfhi(w[1])}; x1 = (f32x4){bflo(w[2]), bfhi(w[2]), bflo(w[3]), bfhi(w[3])}; }
;                     else { x0 = *(const f32x4*)((const float*)Xin + ro + bj * HALF); x1 = *(const f32x4*)((const float*)Xin + ro + bj * HALF + 4); }
;                     x0 += acc[ai][bj][m][0] * sc[bj][0]; x1 += acc[ai][bj][m][1] * sc[bj][1];
;                     if constexpr (OB) { u32x4 o; o[0] = pack2(x0[0], x0[1]); o[1] = pack2(x0[2], x0[3]); o[2] = pack2(x1[0], x1[1]); o[3] = pack2(x1[2], x1[3]);
;                         *(u32x4*)((bf16_t*)Xout + ro + bj * HALF) = o; }
;                     else { *(f32x4*)((float*)Xout + ro + bj * HALF) = x0; *(f32x4*)((float*)Xout + ro + bj * HALF + 4) = x1; } } }
.LBB1_225:
	s_lshl_b32 s17, s22, 8
	s_add_i32 s17, s17, s37
	v_add_u32_e32 v162, s17, v170
	v_ashrrev_i32_e32 v163, 31, v162
	v_lshlrev_b64 v[162:163], 11, v[162:163]
	v_lshl_add_u64 v[160:161], v[162:163], 0, v[160:161]
	v_lshl_add_u64 v[162:163], v[160:161], 2, s[44:45]
	global_load_dwordx4 v[170:173], v[162:163], off offset:16
	global_load_dwordx4 v[174:177], v[162:163], off
	s_mov_b64 s[24:25], 0x8000
	s_and_b64 vcc, exec, s[40:41]
	s_mov_b32 s42, s52
	s_mov_b32 s22, s16
	s_mov_b64 s[26:27], s[18:19]
	s_waitcnt vmcnt(0)
	v_pk_fma_f32 v[172:173], v[138:139], v[82:83], v[172:173]
	v_pk_fma_f32 v[142:143], v[142:143], v[86:87], v[176:177]
	v_pk_fma_f32 v[140:141], v[140:141], v[84:85], v[174:175]
	v_pk_fma_f32 v[138:139], v[136:137], v[80:81], v[170:171]
	v_cvt_pk_bf16_f32 v136, v140, v141
	v_cvt_pk_bf16_f32 v137, v142, v143
	v_cvt_pk_bf16_f32 v138, v138, v139
	v_cvt_pk_bf16_f32 v139, v172, v173
	v_lshl_add_u64 v[170:171], v[160:161], 1, s[10:11]
	global_store_dwordx4 v[170:171], v[136:139], off
	global_load_dwordx4 v[136:139], v[162:163], off offset:528
	s_nop 0
	global_load_dwordx4 v[140:143], v[162:163], off offset:512
	s_waitcnt vmcnt(0)
	v_pk_fma_f32 v[138:139], v[130:131], v[74:75], v[138:139]
	v_pk_fma_f32 v[134:135], v[134:135], v[78:79], v[142:143]
	v_pk_fma_f32 v[132:133], v[132:133], v[76:77], v[140:141]
	v_pk_fma_f32 v[130:131], v[128:129], v[72:73], v[136:137]
	v_cvt_pk_bf16_f32 v128, v132, v133
	v_cvt_pk_bf16_f32 v129, v134, v135
	v_cvt_pk_bf16_f32 v130, v130, v131
	v_cvt_pk_bf16_f32 v131, v138, v139
	v_lshl_add_u64 v[136:137], v[160:161], 0, s[24:25]
	global_store_dwordx4 v[170:171], v[128:131], off offset:256
	v_lshl_add_u64 v[138:139], v[136:137], 2, s[44:45]
	global_load_dwordx4 v[128:131], v[138:139], off offset:16
	global_load_dwordx4 v[132:135], v[138:139], off
	s_mov_b64 s[24:25], 0x10000
	s_waitcnt vmcnt(0)
	v_pk_fma_f32 v[130:131], v[122:123], v[82:83], v[130:131]
	v_pk_fma_f32 v[126:127], v[126:127], v[86:87], v[134:135]
	v_pk_fma_f32 v[124:125], v[124:125], v[84:85], v[132:133]
	v_pk_fma_f32 v[122:123], v[120:121], v[80:81], v[128:129]
	v_cvt_pk_bf16_f32 v120, v124, v125
	v_cvt_pk_bf16_f32 v121, v126, v127
	v_cvt_pk_bf16_f32 v122, v122, v123
	v_cvt_pk_bf16_f32 v123, v130, v131
	v_lshl_add_u64 v[128:129], v[136:137], 1, s[10:11]
	global_store_dwordx4 v[128:129], v[120:123], off
	global_load_dwordx4 v[120:123], v[138:139], off offset:528
	s_nop 0
	global_load_dwordx4 v[124:127], v[138:139], off offset:512
	s_waitcnt vmcnt(0)
	v_pk_fma_f32 v[122:123], v[114:115], v[74:75], v[122:123]
	v_pk_fma_f32 v[118:119], v[118:119], v[78:79], v[126:127]
	v_pk_fma_f32 v[116:117], v[116:117], v[76:77], v[124:125]
	v_pk_fma_f32 v[114:115], v[112:113], v[72:73], v[120:121]
	v_cvt_pk_bf16_f32 v112, v116, v117
	v_cvt_pk_bf16_f32 v113, v118, v119
	v_cvt_pk_bf16_f32 v114, v114, v115
	v_cvt_pk_bf16_f32 v115, v122, v123
	v_lshl_add_u64 v[120:121], v[160:161], 0, s[24:25]
	global_store_dwordx4 v[128:129], v[112:115], off offset:256
	v_lshl_add_u64 v[122:123], v[120:121], 2, s[44:45]
	global_load_dwordx4 v[112:115], v[122:123], off offset:16
	global_load_dwordx4 v[116:119], v[122:123], off
	s_mov_b64 s[24:25], 0x18000
	s_waitcnt vmcnt(0)
	v_pk_fma_f32 v[114:115], v[106:107], v[82:83], v[114:115]
	v_pk_fma_f32 v[110:111], v[110:111], v[86:87], v[118:119]
	v_pk_fma_f32 v[108:109], v[108:109], v[84:85], v[116:117]
	v_pk_fma_f32 v[106:107], v[104:105], v[80:81], v[112:113]
	v_cvt_pk_bf16_f32 v104, v108, v109
	v_cvt_pk_bf16_f32 v105, v110, v111
	v_cvt_pk_bf16_f32 v106, v106, v107
	v_cvt_pk_bf16_f32 v107, v114, v115
	v_lshl_add_u64 v[112:113], v[120:121], 1, s[10:11]
	global_store_dwordx4 v[112:113], v[104:107], off
	global_load_dwordx4 v[104:107], v[122:123], off offset:528
	s_nop 0
	global_load_dwordx4 v[108:111], v[122:123], off offset:512
	s_waitcnt vmcnt(0)
	v_pk_fma_f32 v[106:107], v[98:99], v[74:75], v[106:107]
	v_pk_fma_f32 v[102:103], v[102:103], v[78:79], v[110:111]
	v_pk_fma_f32 v[100:101], v[100:101], v[76:77], v[108:109]
	v_pk_fma_f32 v[98:99], v[96:97], v[72:73], v[104:105]
	v_cvt_pk_bf16_f32 v96, v100, v101
	v_cvt_pk_bf16_f32 v97, v102, v103
	v_cvt_pk_bf16_f32 v98, v98, v99
	v_cvt_pk_bf16_f32 v99, v106, v107
	v_lshl_add_u64 v[104:105], v[160:161], 0, s[24:25]
	global_store_dwordx4 v[112:113], v[96:99], off offset:256
	v_lshl_add_u64 v[106:107], v[104:105], 2, s[44:45]
	global_load_dwordx4 v[96:99], v[106:107], off offset:16
	global_load_dwordx4 v[100:103], v[106:107], off
	s_mov_b64 s[24:25], 0x40000
	s_waitcnt vmcnt(0)
	v_pk_fma_f32 v[98:99], v[90:91], v[82:83], v[98:99]
	v_pk_fma_f32 v[94:95], v[94:95], v[86:87], v[102:103]
	v_pk_fma_f32 v[92:93], v[92:93], v[84:85], v[100:101]
	v_pk_fma_f32 v[90:91], v[88:89], v[80:81], v[96:97]
	v_cvt_pk_bf16_f32 v88, v92, v93
	v_cvt_pk_bf16_f32 v89, v94, v95
	v_cvt_pk_bf16_f32 v90, v90, v91
	v_cvt_pk_bf16_f32 v91, v98, v99
	v_lshl_add_u64 v[96:97], v[104:105], 1, s[10:11]
	global_store_dwordx4 v[96:97], v[88:91], off
	global_load_dwordx4 v[88:91], v[106:107], off offset:528
	s_nop 0
	global_load_dwordx4 v[92:95], v[106:107], off offset:512
	s_waitcnt vmcnt(0)
; DI unsigned pack2(float a, float b) { f32x2 v = {a, b}; hwbf16x2 r = __builtin_convertvector(v, hwbf16x2); return __builtin_bit_cast(unsigned, r); }
; DI float bflo(unsigned w) { return __uint_as_float(w << 16); }
; DI float bfhi(unsigned w) { return __uint_as_float(w & 0xffff0000u); }
;     DI void operator()(const f32x4 (&acc)[2][2][4][2], const Unit& u, int wr, int wc, int fr, int fq) const {
;     ...
;             for (int m = 0; m < 4; ++m) { const size_t ro = (size_t)(row0 + ai * HALF + m * 16) * D + col0;
; #pragma unroll
;                 for (int bj = 0; bj < 2; ++bj) {
;                     f32x4 x0, x1;
;                     if constexpr (IB) { const u32x4 w = *(const u32x4*)((const bf16_t*)Xin + ro + bj * HALF);
;                         x0 = (f32x4){bflo(w[0]), bfhi(w[0]), bflo(w[1]), bfhi(w[1])}; x1 = (f32x4){bflo(w[2]), bfhi(w[2]), bflo(w[3]), bfhi(w[3])}; }
;                     else { x0 = *(const f32x4*)((const float*)Xin + ro + bj * HALF); x1 = *(const f32x4*)((const float*)Xin + ro + bj * HALF + 4); }
;                     x0 += acc[ai][bj][m][0] * sc[bj][0]; x1 += acc[ai][bj][m][1] * sc[bj][1];
;                     if constexpr (OB) { u32x4 o; o[0] = pack2(x0[0], x0[1]); o[1] = pack2(x0[2], x0[3]); o[2] = pack2(x1[0], x1[1]); o[3] = pack2(x1[2], x1[3]);
;                         *(u32x4*)((bf16_t*)Xout + ro + bj * HALF) = o; }
;                     else { *(f32x4*)((float*)Xout + ro + bj * HALF) = x0; *(f32x4*)((float*)Xout + ro + bj * HALF + 4) = x1; } } }
	v_pk_fma_f32 v[90:91], v[66:67], v[74:75], v[90:91]
	v_pk_fma_f32 v[70:71], v[70:71], v[78:79], v[94:95]
	v_pk_fma_f32 v[68:69], v[68:69], v[76:77], v[92:93]
	v_pk_fma_f32 v[66:67], v[64:65], v[72:73], v[88:89]
	v_cvt_pk_bf16_f32 v64, v68, v69
	v_cvt_pk_bf16_f32 v65, v70, v71
	v_cvt_pk_bf16_f32 v66, v66, v67
	v_cvt_pk_bf16_f32 v67, v90, v91
	v_lshl_add_u64 v[88:89], v[160:161], 0, s[24:25]
	global_store_dwordx4 v[96:97], v[64:67], off offset:256
	v_lshl_add_u64 v[90:91], v[88:89], 2, s[44:45]
	global_load_dwordx4 v[64:67], v[90:91], off offset:16
	global_load_dwordx4 v[68:71], v[90:91], off
	s_mov_b64 s[24:25], 0x48000
	s_waitcnt vmcnt(0)
	v_pk_fma_f32 v[66:67], v[58:59], v[82:83], v[66:67]
	v_pk_fma_f32 v[62:63], v[62:63], v[86:87], v[70:71]
	v_pk_fma_f32 v[60:61], v[60:61], v[84:85], v[68:69]
	v_pk_fma_f32 v[58:59], v[56:57], v[80:81], v[64:65]
	v_cvt_pk_bf16_f32 v56, v60, v61
	v_cvt_pk_bf16_f32 v57, v62, v63
	v_cvt_pk_bf16_f32 v58, v58, v59
	v_cvt_pk_bf16_f32 v59, v66, v67
	v_lshl_add_u64 v[64:65], v[88:89], 1, s[10:11]
	global_store_dwordx4 v[64:65], v[56:59], off
	global_load_dwordx4 v[56:59], v[90:91], off offset:528
	s_nop 0
	global_load_dwordx4 v[60:63], v[90:91], off offset:512
	s_waitcnt vmcnt(0)
	v_pk_fma_f32 v[58:59], v[50:51], v[74:75], v[58:59]
	v_pk_fma_f32 v[54:55], v[54:55], v[78:79], v[62:63]
	v_pk_fma_f32 v[52:53], v[52:53], v[76:77], v[60:61]
	v_pk_fma_f32 v[50:51], v[48:49], v[72:73], v[56:57]
	v_cvt_pk_bf16_f32 v48, v52, v53
	v_cvt_pk_bf16_f32 v49, v54, v55
	v_cvt_pk_bf16_f32 v50, v50, v51
	v_cvt_pk_bf16_f32 v51, v58, v59
	v_lshl_add_u64 v[56:57], v[160:161], 0, s[24:25]
	global_store_dwordx4 v[64:65], v[48:51], off offset:256
	v_lshl_add_u64 v[58:59], v[56:57], 2, s[44:45]
	global_load_dwordx4 v[48:51], v[58:59], off offset:16
	global_load_dwordx4 v[52:55], v[58:59], off
	s_mov_b64 s[24:25], 0x50000
	s_waitcnt vmcnt(0)
	v_pk_fma_f32 v[50:51], v[42:43], v[82:83], v[50:51]
	v_pk_fma_f32 v[46:47], v[46:47], v[86:87], v[54:55]
	v_pk_fma_f32 v[44:45], v[44:45], v[84:85], v[52:53]
	v_pk_fma_f32 v[42:43], v[40:41], v[80:81], v[48:49]
	v_cvt_pk_bf16_f32 v40, v44, v45
	v_cvt_pk_bf16_f32 v41, v46, v47
	v_cvt_pk_bf16_f32 v42, v42, v43
	v_cvt_pk_bf16_f32 v43, v50, v51
	v_lshl_add_u64 v[48:49], v[56:57], 1, s[10:11]
	global_store_dwordx4 v[48:49], v[40:43], off
	global_load_dwordx4 v[40:43], v[58:59], off offset:528
	s_nop 0
	global_load_dwordx4 v[44:47], v[58:59], off offset:512
	s_waitcnt vmcnt(0)
	v_pk_fma_f32 v[42:43], v[34:35], v[74:75], v[42:43]
	v_pk_fma_f32 v[38:39], v[38:39], v[78:79], v[46:47]
	v_pk_fma_f32 v[36:37], v[36:37], v[76:77], v[44:45]
	v_pk_fma_f32 v[34:35], v[32:33], v[72:73], v[40:41]
	v_cvt_pk_bf16_f32 v32, v36, v37
	v_cvt_pk_bf16_f32 v33, v38, v39
	v_cvt_pk_bf16_f32 v34, v34, v35
	v_cvt_pk_bf16_f32 v35, v42, v43
	v_lshl_add_u64 v[40:41], v[160:161], 0, s[24:25]
	global_store_dwordx4 v[48:49], v[32:35], off offset:256
	v_lshl_add_u64 v[42:43], v[40:41], 2, s[44:45]
	global_load_dwordx4 v[32:35], v[42:43], off offset:16
	global_load_dwordx4 v[36:39], v[42:43], off
	s_mov_b64 s[24:25], 0x58000
	s_waitcnt vmcnt(0)
	v_pk_fma_f32 v[34:35], v[26:27], v[82:83], v[34:35]
	v_pk_fma_f32 v[30:31], v[30:31], v[86:87], v[38:39]
	v_pk_fma_f32 v[28:29], v[28:29], v[84:85], v[36:37]
	v_pk_fma_f32 v[26:27], v[24:25], v[80:81], v[32:33]
	v_cvt_pk_bf16_f32 v24, v28, v29
	v_cvt_pk_bf16_f32 v25, v30, v31
	v_cvt_pk_bf16_f32 v26, v26, v27
	v_cvt_pk_bf16_f32 v27, v34, v35
	v_lshl_add_u64 v[32:33], v[40:41], 1, s[10:11]
	global_store_dwordx4 v[32:33], v[24:27], off
	global_load_dwordx4 v[24:27], v[42:43], off offset:528
	s_nop 0
	global_load_dwordx4 v[28:31], v[42:43], off offset:512
	s_waitcnt vmcnt(0)
	v_pk_fma_f32 v[26:27], v[18:19], v[74:75], v[26:27]
	v_pk_fma_f32 v[22:23], v[22:23], v[78:79], v[30:31]
	v_pk_fma_f32 v[20:21], v[20:21], v[76:77], v[28:29]
	v_pk_fma_f32 v[18:19], v[16:17], v[72:73], v[24:25]
	v_cvt_pk_bf16_f32 v16, v20, v21
	v_cvt_pk_bf16_f32 v17, v22, v23
	v_cvt_pk_bf16_f32 v18, v18, v19
	v_cvt_pk_bf16_f32 v19, v26, v27
	v_lshl_add_u64 v[24:25], v[160:161], 0, s[24:25]
	global_store_dwordx4 v[32:33], v[16:19], off offset:256
	v_lshl_add_u64 v[26:27], v[24:25], 2, s[44:45]
	global_load_dwordx4 v[16:19], v[26:27], off offset:16
	global_load_dwordx4 v[20:23], v[26:27], off
	s_mov_b64 s[24:25], s[20:21]
	s_waitcnt vmcnt(0)
	v_pk_fma_f32 v[18:19], v[10:11], v[82:83], v[18:19]
	v_pk_fma_f32 v[14:15], v[14:15], v[86:87], v[22:23]
	v_pk_fma_f32 v[12:13], v[12:13], v[84:85], v[20:21]
	v_pk_fma_f32 v[10:11], v[8:9], v[80:81], v[16:17]
	v_cvt_pk_bf16_f32 v8, v12, v13
	v_cvt_pk_bf16_f32 v9, v14, v15
	v_cvt_pk_bf16_f32 v10, v10, v11
	v_cvt_pk_bf16_f32 v11, v18, v19
	v_lshl_add_u64 v[16:17], v[24:25], 1, s[10:11]
	global_store_dwordx4 v[16:17], v[8:11], off
	global_load_dwordx4 v[8:11], v[26:27], off offset:528
	s_nop 0
	global_load_dwordx4 v[12:15], v[26:27], off offset:512
	s_waitcnt vmcnt(0)
	v_pk_fma_f32 v[10:11], v[2:3], v[74:75], v[10:11]
	v_pk_fma_f32 v[6:7], v[6:7], v[78:79], v[14:15]
	v_pk_fma_f32 v[4:5], v[4:5], v[76:77], v[12:13]
	v_pk_fma_f32 v[2:3], v[0:1], v[72:73], v[8:9]
	v_cvt_pk_bf16_f32 v0, v4, v5
	v_cvt_pk_bf16_f32 v1, v6, v7
	v_cvt_pk_bf16_f32 v2, v2, v3
	v_cvt_pk_bf16_f32 v3, v10, v11
	global_store_dwordx4 v[16:17], v[0:3], off offset:256
	s_cbranch_vccnz .LBB1_238

; DI float bflo(unsigned w) { return __uint_as_float(w << 16); }
; DI float bfhi(unsigned w) { return __uint_as_float(w & 0xffff0000u); }
; DI float wave_sum(float v) { for (int o = 32; o; o >>= 1) v += __shfl_xor(v, o); return v; }
; template <bool BF> DI void norm_phase(const Params& p, const void* x, const float* gain) {
;     ...
;     for (int t = bid * 8 + wid; t < T; t += 2 * step) {
;         const int t2 = (t + step < T) ? t + step : t;
;         f32x4 v[2][8];
; #pragma unroll
;         for (int q = 0; q < 2; ++q) {
;             const int tt = q ? t2 : t;
; #pragma unroll
;             for (int i = 0; i < 4; ++i) {
;                 const size_t e = (size_t)tt * D + (i * 64 + lane) * 8;
;                 if constexpr (BF) { const u32x4 w = *(const u32x4*)((const bf16_t*)x + e);
;                     v[q][2 * i] = (f32x4){bflo(w[0]), bfhi(w[0]), bflo(w[1]), bfhi(w[1])}; v[q][2 * i + 1] = (f32x4){bflo(w[2]), bfhi(w[2]), bflo(w[3]), bfhi(w[3])}; }
;                 else { v[q][2 * i] = *(const f32x4*)((const float*)x + e); v[q][2 * i + 1] = *(const f32x4*)((const float*)x + e + 4); }
;             }
;         }
;         float ss[2] = {0.f, 0.f};
; #pragma unroll
;         for (int q = 0; q < 2; ++q)
; #pragma unroll
;             for (int i = 0; i < 8; ++i) ss[q] += v[q][i][0] * v[q][i][0] + v[q][i][1] * v[q][i][1] + v[q][i][2] * v[q][i][2] + v[q][i][3] * v[q][i][3];
;         ss[0] = wave_sum(ss[0]); ss[1] = wave_sum(ss[1]);
.LBB1_307:
	v_add_u32_e32 v85, s33, v12
	v_cmp_gt_i32_e32 vcc, s2, v85
	v_ashrrev_i32_e32 v13, 31, v12
	global_load_dwordx4 v[86:89], v[0:1], off offset:16
	global_load_dwordx4 v[90:93], v[0:1], off
	v_cndmask_b32_e32 v28, v12, v85, vcc
	v_ashrrev_i32_e32 v29, 31, v28
	v_lshlrev_b64 v[12:13], 12, v[12:13]
	v_lshlrev_b64 v[34:35], 12, v[28:29]
	v_lshl_add_u64 v[24:25], v[6:7], 0, v[12:13]
	v_lshl_add_u64 v[28:29], v[6:7], 0, v[34:35]
	v_lshl_add_u64 v[58:59], v[8:9], 0, v[12:13]
	global_load_dwordx4 v[12:15], v[24:25], off offset:2048
	global_load_dwordx4 v[16:19], v[24:25], off offset:3072
	global_load_dwordx4 v[20:23], v[24:25], off
	s_nop 0
	global_load_dwordx4 v[24:27], v[24:25], off offset:1024
	s_nop 0
	global_load_dwordx4 v[94:97], v[28:29], off offset:2048
	global_load_dwordx4 v[98:101], v[28:29], off
	global_load_dwordx4 v[102:105], v[28:29], off offset:1024
	global_load_dwordx4 v[106:109], v[28:29], off offset:3072
	v_lshl_add_u64 v[34:35], v[8:9], 0, v[34:35]
	s_waitcnt vmcnt(0) lgkmcnt(0)
	v_and_b32_e32 v77, 0xffff0000, v12
	v_and_b32_e32 v76, 0xffff0000, v14
	v_and_b32_e32 v69, 0xffff0000, v16
	v_and_b32_e32 v68, 0xffff0000, v18
	v_and_b32_e32 v47, 0xffff0000, v20
	v_and_b32_e32 v51, 0xffff0000, v22
	v_and_b32_e32 v46, 0xffff0000, v98
	v_and_b32_e32 v50, 0xffff0000, v100
	v_lshlrev_b32_e32 v73, 16, v12
	v_lshlrev_b32_e32 v72, 16, v14
	v_lshlrev_b32_e32 v75, 16, v13
	v_and_b32_e32 v79, 0xffff0000, v13
	v_lshlrev_b32_e32 v65, 16, v16
	v_lshlrev_b32_e32 v64, 16, v18
	v_lshlrev_b32_e32 v66, 16, v19
	v_and_b32_e32 v70, 0xffff0000, v19
	v_lshlrev_b32_e32 v39, 16, v20
	v_lshlrev_b32_e32 v43, 16, v22
	v_lshlrev_b32_e32 v45, 16, v23
	v_and_b32_e32 v53, 0xffff0000, v23
	v_lshlrev_b32_e32 v13, 16, v24
	v_and_b32_e32 v37, 0xffff0000, v24
	v_pk_mul_f32 v[18:19], v[76:77], v[76:77]
	v_pk_mul_f32 v[22:23], v[68:69], v[68:69]
	v_and_b32_e32 v61, 0xffff0000, v94
	v_and_b32_e32 v60, 0xffff0000, v96
	v_lshlrev_b32_e32 v38, 16, v98
	v_lshlrev_b32_e32 v42, 16, v100
	v_lshlrev_b32_e32 v44, 16, v101
	v_and_b32_e32 v52, 0xffff0000, v101
	v_lshlrev_b32_e32 v12, 16, v102
	v_and_b32_e32 v36, 0xffff0000, v102
	v_lshlrev_b32_e32 v14, 16, v103
	v_and_b32_e32 v24, 0xffff0000, v103
	v_and_b32_e32 v29, 0xffff0000, v106
	v_and_b32_e32 v28, 0xffff0000, v108
	v_pk_mul_f32 v[100:101], v[46:47], v[46:47]
	v_pk_mul_f32 v[102:103], v[50:51], v[50:51]
	v_lshlrev_b32_e32 v67, 16, v17
	v_and_b32_e32 v71, 0xffff0000, v17
	v_lshlrev_b32_e32 v41, 16, v21
	v_lshlrev_b32_e32 v17, 16, v26
	v_and_b32_e32 v31, 0xffff0000, v26
	v_pk_fma_f32 v[118:119], v[72:73], v[72:73], v[18:19]
	v_pk_fma_f32 v[120:121], v[64:65], v[64:65], v[22:23]
	v_lshlrev_b32_e32 v55, 16, v94
	v_lshlrev_b32_e32 v54, 16, v96
	v_lshlrev_b32_e32 v40, 16, v99
	v_and_b32_e32 v48, 0xffff0000, v99
	v_lshlrev_b32_e32 v16, 16, v104
	v_and_b32_e32 v30, 0xffff0000, v104
	v_lshlrev_b32_e32 v20, 16, v105
	v_and_b32_e32 v26, 0xffff0000, v105
	v_lshlrev_b32_e32 v19, 16, v106
	v_lshlrev_b32_e32 v18, 16, v108
	v_lshlrev_b32_e32 v22, 16, v109
	v_and_b32_e32 v32, 0xffff0000, v109
	v_pk_mul_f32 v[98:99], v[60:61], v[60:61]
	v_pk_mul_f32 v[104:105], v[36:37], v[36:37]
	v_pk_mul_f32 v[108:109], v[28:29], v[28:29]
	v_pk_fma_f32 v[100:101], v[38:39], v[38:39], v[100:101]
	v_pk_fma_f32 v[102:103], v[42:43], v[42:43], v[102:103]
	v_lshlrev_b32_e32 v74, 16, v15
	v_and_b32_e32 v78, 0xffff0000, v15
	v_and_b32_e32 v49, 0xffff0000, v21
	v_lshlrev_b32_e32 v15, 16, v25
	v_lshlrev_b32_e32 v57, 16, v95
	v_lshlrev_b32_e32 v56, 16, v97
	v_lshlrev_b32_e32 v23, 16, v107
	v_and_b32_e32 v33, 0xffff0000, v107
	v_pk_mul_f32 v[106:107], v[30:31], v[30:31]
	v_pk_fma_f32 v[98:99], v[54:55], v[54:55], v[98:99]
	v_pk_fma_f32 v[104:105], v[12:13], v[12:13], v[104:105]
	v_pk_fma_f32 v[108:109], v[18:19], v[18:19], v[108:109]
	v_pk_fma_f32 v[100:101], v[40:41], v[40:41], v[100:101]
	v_pk_fma_f32 v[102:103], v[44:45], v[44:45], v[102:103]
	v_and_b32_e32 v25, 0xffff0000, v25
	v_lshlrev_b32_e32 v21, 16, v27
	v_and_b32_e32 v63, 0xffff0000, v95
	v_and_b32_e32 v62, 0xffff0000, v97
	v_pk_fma_f32 v[94:95], v[74:75], v[74:75], v[118:119]
	v_pk_fma_f32 v[96:97], v[66:67], v[66:67], v[120:121]
	v_pk_fma_f32 v[106:107], v[16:17], v[16:17], v[106:107]
	v_pk_fma_f32 v[98:99], v[56:57], v[56:57], v[98:99]
	v_pk_fma_f32 v[104:105], v[14:15], v[14:15], v[104:105]
	v_pk_fma_f32 v[108:109], v[22:23], v[22:23], v[108:109]
	v_pk_fma_f32 v[100:101], v[48:49], v[48:49], v[100:101]
	v_pk_fma_f32 v[102:103], v[52:53], v[52:53], v[102:103]
	v_and_b32_e32 v27, 0xffff0000, v27
	v_pk_fma_f32 v[94:95], v[78:79], v[78:79], v[94:95]
	v_pk_fma_f32 v[96:97], v[70:71], v[70:71], v[96:97]
	v_pk_fma_f32 v[106:107], v[20:21], v[20:21], v[106:107]
	v_pk_fma_f32 v[98:99], v[62:63], v[62:63], v[98:99]
	v_pk_fma_f32 v[104:105], v[24:25], v[24:25], v[104:105]
	v_pk_fma_f32 v[108:109], v[32:33], v[32:33], v[108:109]
	v_pk_add_f32 v[100:101], v[100:101], v[102:103]
	v_mov_b32_e32 v119, v95
	v_mov_b32_e32 v95, v97
	v_pk_fma_f32 v[106:107], v[26:27], v[26:27], v[106:107]
	v_mov_b32_e32 v118, v99
	v_mov_b32_e32 v99, v94
	v_mov_b32_e32 v94, v109
	v_mov_b32_e32 v109, v96
	v_pk_add_f32 v[96:97], v[100:101], v[104:105]
	v_mov_b32_e32 v110, v39
	v_pk_add_f32 v[96:97], v[106:107], v[96:97]
	v_mov_b32_e32 v112, v41
	v_pk_add_f32 v[96:97], v[118:119], v[96:97]
	v_mov_b32_e32 v111, v47
	v_pk_add_f32 v[96:97], v[98:99], v[96:97]
	v_mov_b32_e32 v113, v49
	v_pk_add_f32 v[94:95], v[94:95], v[96:97]
	v_mov_b32_e32 v114, v43
	v_pk_add_f32 v[94:95], v[108:109], v[94:95]
	ds_bpermute_b32 v97, v11, v95
	ds_bpermute_b32 v96, v11, v94
	v_mov_b32_e32 v115, v51
	v_mov_b32_e32 v116, v45
	v_mov_b32_e32 v117, v53
	v_mov_b32_e32 v43, v50
	s_waitcnt lgkmcnt(0)
; DI unsigned pack2(float a, float b) { f32x2 v = {a, b}; hwbf16x2 r = __builtin_convertvector(v, hwbf16x2); return __builtin_bit_cast(unsigned, r); }
; DI float wave_sum(float v) { for (int o = 32; o; o >>= 1) v += __shfl_xor(v, o); return v; }
;     DI const char* a(const Unit& u) const { return (const char*)(A + (size_t)u.pm * BM * lda); }
;     DI const char* a(const Unit& u) const { return (const char*)(A + (size_t)u.pm * BM * 2048 + (u.pn >> 1) * 512); }
;     DI const char* a(const Unit& u) const { return (const char*)((u.pn < 12 ? A1 : A2) + (size_t)u.pm * BM * 512); }
; template <bool BF> DI void norm_phase(const Params& p, const void* x, const float* gain) {
;     ...
;         ss[0] = wave_sum(ss[0]); ss[1] = wave_sum(ss[1]);
; #pragma unroll
;         for (int q = 0; q < 2; ++q) {
;             const int tt = q ? t2 : t;
;             const float rs = rsqrtf(ss[q] * (1.0f / D) + EPS);
; #pragma unroll
;             for (int i = 0; i < 4; ++i) { const int c = (i * 64 + lane) * 8;
;                 const f32x4 g0 = *(const f32x4*)(gain + c), g1 = *(const f32x4*)(gain + c + 4);
;                 const f32x4 a = v[q][2 * i] * rs * g0, d = v[q][2 * i + 1] * rs * g1;
;                 u32x4 o; o[0] = pack2(a[0], a[1]); o[1] = pack2(a[2], a[3]); o[2] = pack2(d[0], d[1]); o[3] = pack2(d[2], d[3]);
;                 *(u32x4*)(H + (size_t)tt * D + c) = o; }
	v_pk_add_f32 v[94:95], v[94:95], v[96:97]
	ds_bpermute_b32 v97, v80, v95
	ds_bpermute_b32 v96, v80, v94
	v_mov_b32_e32 v45, v52
	s_waitcnt lgkmcnt(0)
	v_pk_add_f32 v[94:95], v[94:95], v[96:97]
	ds_bpermute_b32 v97, v81, v95
	ds_bpermute_b32 v96, v81, v94
	s_waitcnt lgkmcnt(0)
	v_pk_add_f32 v[94:95], v[94:95], v[96:97]
	ds_bpermute_b32 v97, v82, v95
	ds_bpermute_b32 v96, v82, v94
	s_waitcnt lgkmcnt(0)
	v_pk_add_f32 v[94:95], v[94:95], v[96:97]
	ds_bpermute_b32 v97, v83, v95
	ds_bpermute_b32 v96, v83, v94
	s_waitcnt lgkmcnt(0)
	v_pk_add_f32 v[94:95], v[94:95], v[96:97]
	ds_bpermute_b32 v97, v84, v95
	ds_bpermute_b32 v96, v84, v94
	s_waitcnt lgkmcnt(0)
	v_pk_add_f32 v[94:95], v[94:95], v[96:97]
	s_nop 0
	v_pk_fma_f32 v[94:95], v[94:95], s[10:11], v[10:11] op_sel_hi:[1,0,0]
	s_nop 0
	v_mul_f32_e32 v39, 0x4b800000, v95
	v_cmp_gt_f32_e32 vcc, s3, v95
	s_nop 1
	v_cndmask_b32_e32 v39, v95, v39, vcc
	v_rsq_f32_e32 v39, v39
	s_nop 0
	v_mul_f32_e32 v41, 0x45800000, v39
	v_cndmask_b32_e32 v96, v39, v41, vcc
	v_pk_mul_f32 v[98:99], v[96:97], v[110:111] op_sel_hi:[0,1]
	v_pk_mul_f32 v[100:101], v[96:97], v[112:113] op_sel_hi:[0,1]
	v_pk_mul_f32 v[102:103], v[96:97], v[114:115] op_sel_hi:[0,1]
	v_pk_mul_f32 v[104:105], v[96:97], v[116:117] op_sel_hi:[0,1]
	v_pk_mul_f32 v[92:93], v[92:93], v[100:101]
	v_pk_mul_f32 v[90:91], v[90:91], v[98:99]
	v_pk_mul_f32 v[98:99], v[88:89], v[104:105]
	v_pk_mul_f32 v[88:89], v[86:87], v[102:103]
	v_cvt_pk_bf16_f32 v86, v90, v91
	v_cvt_pk_bf16_f32 v87, v92, v93
	v_cvt_pk_bf16_f32 v88, v88, v89
	v_cvt_pk_bf16_f32 v89, v98, v99
	global_store_dwordx4 v[58:59], v[86:89], off
	global_load_dwordx4 v[86:89], v[0:1], off offset:2048
	s_nop 0
	global_load_dwordx4 v[90:93], v[0:1], off offset:2064
	v_mov_b32_e32 v98, v13
	v_mov_b32_e32 v99, v37
	v_mov_b32_e32 v100, v15
	v_mov_b32_e32 v101, v25
	v_mov_b32_e32 v102, v17
	v_mov_b32_e32 v103, v31
	v_mov_b32_e32 v104, v21
	v_mov_b32_e32 v105, v27
	v_pk_mul_f32 v[98:99], v[96:97], v[98:99] op_sel_hi:[0,1]
	v_pk_mul_f32 v[100:101], v[96:97], v[100:101] op_sel_hi:[0,1]
	v_pk_mul_f32 v[102:103], v[96:97], v[102:103] op_sel_hi:[0,1]
	v_pk_mul_f32 v[104:105], v[96:97], v[104:105] op_sel_hi:[0,1]
	v_mul_f32_e32 v13, 0x4b800000, v94
	v_cmp_gt_f32_e32 vcc, s3, v94
	v_mov_b32_e32 v39, v46
	v_mov_b32_e32 v41, v48
	v_cndmask_b32_e32 v13, v94, v13, vcc
	v_rsq_f32_e32 v13, v13
	v_mov_b32_e32 v17, v30
	v_mov_b32_e32 v21, v26
	v_mul_f32_e32 v15, 0x45800000, v13
	v_cndmask_b32_e32 v46, v13, v15, vcc
	v_pk_mul_f32 v[38:39], v[46:47], v[38:39] op_sel_hi:[0,1]
	v_pk_mul_f32 v[40:41], v[46:47], v[40:41] op_sel_hi:[0,1]
	v_pk_mul_f32 v[42:43], v[46:47], v[42:43] op_sel_hi:[0,1]
	v_pk_mul_f32 v[44:45], v[46:47], v[44:45] op_sel_hi:[0,1]
	v_mov_b32_e32 v13, v36
	v_mov_b32_e32 v15, v24
	v_pk_mul_f32 v[12:13], v[46:47], v[12:13] op_sel_hi:[0,1]
	v_pk_mul_f32 v[14:15], v[46:47], v[14:15] op_sel_hi:[0,1]
	v_pk_mul_f32 v[16:17], v[46:47], v[16:17] op_sel_hi:[0,1]
	v_pk_mul_f32 v[20:21], v[46:47], v[20:21] op_sel_hi:[0,1]
	s_waitcnt vmcnt(0)
	v_pk_mul_f32 v[88:89], v[88:89], v[100:101]
	v_pk_mul_f32 v[86:87], v[86:87], v[98:99]
	v_pk_mul_f32 v[92:93], v[92:93], v[104:105]
	v_pk_mul_f32 v[90:91], v[90:91], v[102:103]
	v_cvt_pk_bf16_f32 v86, v86, v87
	v_cvt_pk_bf16_f32 v87, v88, v89
	v_cvt_pk_bf16_f32 v88, v90, v91
	v_cvt_pk_bf16_f32 v89, v92, v93
	global_store_dwordx4 v[58:59], v[86:89], off offset:1024
	global_load_dwordx4 v[86:89], v[2:3], off
	s_nop 0
	global_load_dwordx4 v[90:93], v[2:3], off offset:16
	v_mov_b32_e32 v98, v73
	v_mov_b32_e32 v99, v77
	v_mov_b32_e32 v100, v75
	v_mov_b32_e32 v101, v79
	v_mov_b32_e32 v73, v76
	v_mov_b32_e32 v75, v78
	v_pk_mul_f32 v[76:77], v[96:97], v[98:99] op_sel_hi:[0,1]
	v_pk_mul_f32 v[78:79], v[96:97], v[100:101] op_sel_hi:[0,1]
	v_pk_mul_f32 v[72:73], v[96:97], v[72:73] op_sel_hi:[0,1]
	v_pk_mul_f32 v[74:75], v[96:97], v[74:75] op_sel_hi:[0,1]
	s_waitcnt vmcnt(0)
; DI unsigned pack2(float a, float b) { f32x2 v = {a, b}; hwbf16x2 r = __builtin_convertvector(v, hwbf16x2); return __builtin_bit_cast(unsigned, r); }
;     DI const char* a(const Unit& u) const { return (const char*)(A + (size_t)u.pm * BM * lda); }
;     DI const char* a(const Unit& u) const { return (const char*)(A + (size_t)u.pm * BM * 2048 + (u.pn >> 1) * 512); }
;     DI const char* a(const Unit& u) const { return (const char*)((u.pn < 12 ? A1 : A2) + (size_t)u.pm * BM * 512); }
; template <bool BF> DI void norm_phase(const Params& p, const void* x, const float* gain) {
;     ...
;         for (int q = 0; q < 2; ++q) {
;             const int tt = q ? t2 : t;
;             const float rs = rsqrtf(ss[q] * (1.0f / D) + EPS);
; #pragma unroll
;             for (int i = 0; i < 4; ++i) { const int c = (i * 64 + lane) * 8;
;                 const f32x4 g0 = *(const f32x4*)(gain + c), g1 = *(const f32x4*)(gain + c + 4);
;                 const f32x4 a = v[q][2 * i] * rs * g0, d = v[q][2 * i + 1] * rs * g1;
;                 u32x4 o; o[0] = pack2(a[0], a[1]); o[1] = pack2(a[2], a[3]); o[2] = pack2(d[0], d[1]); o[3] = pack2(d[2], d[3]);
;                 *(u32x4*)(H + (size_t)tt * D + c) = o; }
	v_pk_mul_f32 v[78:79], v[88:89], v[78:79]
	v_pk_mul_f32 v[76:77], v[86:87], v[76:77]
	v_pk_mul_f32 v[86:87], v[92:93], v[74:75]
	v_pk_mul_f32 v[74:75], v[90:91], v[72:73]
	v_cvt_pk_bf16_f32 v72, v76, v77
	v_cvt_pk_bf16_f32 v73, v78, v79
	v_cvt_pk_bf16_f32 v74, v74, v75
	v_cvt_pk_bf16_f32 v75, v86, v87
	global_store_dwordx4 v[58:59], v[72:75], off offset:2048
	global_load_dwordx4 v[72:75], v[4:5], off
	s_nop 0
	global_load_dwordx4 v[76:79], v[4:5], off offset:16
	v_mov_b32_e32 v86, v65
	v_mov_b32_e32 v87, v69
	v_mov_b32_e32 v88, v67
	v_mov_b32_e32 v89, v71
	v_mov_b32_e32 v65, v68
	v_mov_b32_e32 v67, v70
	v_pk_mul_f32 v[68:69], v[96:97], v[86:87] op_sel_hi:[0,1]
	v_pk_mul_f32 v[70:71], v[96:97], v[88:89] op_sel_hi:[0,1]
	v_pk_mul_f32 v[64:65], v[96:97], v[64:65] op_sel_hi:[0,1]
	v_pk_mul_f32 v[66:67], v[96:97], v[66:67] op_sel_hi:[0,1]
	s_waitcnt vmcnt(0)
	v_pk_mul_f32 v[70:71], v[74:75], v[70:71]
	v_pk_mul_f32 v[68:69], v[72:73], v[68:69]
	v_pk_mul_f32 v[72:73], v[78:79], v[66:67]
	v_pk_mul_f32 v[66:67], v[76:77], v[64:65]
	v_cvt_pk_bf16_f32 v64, v68, v69
	v_cvt_pk_bf16_f32 v65, v70, v71
	v_cvt_pk_bf16_f32 v66, v66, v67
	v_cvt_pk_bf16_f32 v67, v72, v73
	global_store_dwordx4 v[58:59], v[64:67], off offset:3072
	global_load_dwordx4 v[64:67], v[0:1], off
	s_nop 0
	global_load_dwordx4 v[68:71], v[0:1], off offset:16
	s_waitcnt vmcnt(0)
	v_pk_mul_f32 v[40:41], v[66:67], v[40:41]
	v_pk_mul_f32 v[38:39], v[64:65], v[38:39]
	v_pk_mul_f32 v[44:45], v[70:71], v[44:45]
	v_pk_mul_f32 v[42:43], v[68:69], v[42:43]
	v_cvt_pk_bf16_f32 v38, v38, v39
	v_cvt_pk_bf16_f32 v39, v40, v41
	v_cvt_pk_bf16_f32 v40, v42, v43
	v_cvt_pk_bf16_f32 v41, v44, v45
	global_store_dwordx4 v[34:35], v[38:41], off
	global_load_dwordx4 v[38:41], v[0:1], off offset:2048
	s_nop 0
	global_load_dwordx4 v[42:45], v[0:1], off offset:2064
	s_waitcnt vmcnt(0)
	v_pk_mul_f32 v[14:15], v[14:15], v[40:41]
	v_pk_mul_f32 v[12:13], v[12:13], v[38:39]
	v_pk_mul_f32 v[20:21], v[20:21], v[44:45]
	v_pk_mul_f32 v[16:17], v[16:17], v[42:43]
	v_cvt_pk_bf16_f32 v12, v12, v13
	v_cvt_pk_bf16_f32 v13, v14, v15
	v_cvt_pk_bf16_f32 v14, v16, v17
	v_cvt_pk_bf16_f32 v15, v20, v21
	global_store_dwordx4 v[34:35], v[12:15], off offset:1024
	global_load_dwordx4 v[12:15], v[2:3], off
	s_nop 0
	global_load_dwordx4 v[24:27], v[2:3], off offset:16
	v_mov_b32_e32 v16, v55
	v_mov_b32_e32 v17, v61
	v_mov_b32_e32 v20, v57
	v_mov_b32_e32 v21, v63
	v_mov_b32_e32 v55, v60
	v_mov_b32_e32 v57, v62
	v_pk_mul_f32 v[16:17], v[46:47], v[16:17] op_sel_hi:[0,1]
	v_pk_mul_f32 v[20:21], v[46:47], v[20:21] op_sel_hi:[0,1]
	v_pk_mul_f32 v[30:31], v[46:47], v[54:55] op_sel_hi:[0,1]
	v_pk_mul_f32 v[36:37], v[46:47], v[56:57] op_sel_hi:[0,1]
	s_waitcnt vmcnt(0)
	v_pk_mul_f32 v[14:15], v[20:21], v[14:15]
	v_pk_mul_f32 v[12:13], v[16:17], v[12:13]
	v_pk_mul_f32 v[16:17], v[36:37], v[26:27]
	v_pk_mul_f32 v[20:21], v[30:31], v[24:25]
	v_cvt_pk_bf16_f32 v12, v12, v13
	v_cvt_pk_bf16_f32 v13, v14, v15
	v_cvt_pk_bf16_f32 v14, v20, v21
	v_cvt_pk_bf16_f32 v15, v16, v17
	global_store_dwordx4 v[34:35], v[12:15], off offset:2048
	global_load_dwordx4 v[14:17], v[4:5], off
	s_nop 0
	global_load_dwordx4 v[24:27], v[4:5], off offset:16
	v_mov_b32_e32 v20, v19
	v_mov_b32_e32 v21, v29
	v_mov_b32_e32 v30, v23
	v_mov_b32_e32 v31, v33
	v_mov_b32_e32 v19, v28
	v_mov_b32_e32 v23, v32
	v_add_u32_e32 v12, s33, v85
	v_pk_mul_f32 v[20:21], v[46:47], v[20:21] op_sel_hi:[0,1]
	v_pk_mul_f32 v[28:29], v[46:47], v[30:31] op_sel_hi:[0,1]
	v_pk_mul_f32 v[18:19], v[46:47], v[18:19] op_sel_hi:[0,1]
	v_pk_mul_f32 v[22:23], v[46:47], v[22:23] op_sel_hi:[0,1]
	v_cmp_lt_i32_e32 vcc, s4, v12
	s_or_b64 s[8:9], vcc, s[8:9]
	s_waitcnt vmcnt(0)
	v_pk_mul_f32 v[16:17], v[28:29], v[16:17]
	v_pk_mul_f32 v[14:15], v[20:21], v[14:15]
	v_pk_mul_f32 v[20:21], v[22:23], v[26:27]
	v_pk_mul_f32 v[18:19], v[18:19], v[24:25]
	v_cvt_pk_bf16_f32 v14, v14, v15
	v_cvt_pk_bf16_f32 v15, v16, v17
	v_cvt_pk_bf16_f32 v16, v18, v19
	v_cvt_pk_bf16_f32 v17, v20, v21
	global_store_dwordx4 v[34:35], v[14:17], off offset:3072
	s_andn2_b64 exec, exec, s[8:9]
	s_cbranch_execnz .LBB1_307

; #define PG8_STAGE(bufoff, gbase, voff) do { _Pragma("unroll") for (int _i = 0; _i < 2; ++_i) \
;         __builtin_amdgcn_global_load_lds((const unsigned*)((const char*)(gbase) + (voff)[_i]), (LAS unsigned*)(lds + (bufoff) + ldsw + _i * 8192), 16, 0, 0); } while (0)
; #define PG8_LDA(dst, b, h) do { _Pragma("unroll") for (int m = 0; m < 4; ++m) _Pragma("unroll") for (int k = 0; k < 2; ++k) dst[m][k] = *(const LAS bf16x8*)(lds + PG8_SA(b, h) + aoff + m * 2048 + k * 1024); } while (0)
; #define PG8_LDB(dst, b, h) do { _Pragma("unroll") for (int n = 0; n < 2; ++n) _Pragma("unroll") for (int k = 0; k < 2; ++k) dst[n][k] = *(const LAS bf16x8*)(lds + PG8_SB(b, h) + boff + n * 2048 + k * 1024); } while (0)
; #define PG8_MMA(ai, bj, At, Bt) do { __builtin_amdgcn_s_setprio(1); _Pragma("unroll") for (int m = 0; m < 4; ++m) _Pragma("unroll") for (int n = 0; n < 2; ++n) _Pragma("unroll") for (int k = 0; k < 2; ++k) \
;         acc[ai][bj][m][n] = __builtin_amdgcn_mfma_f32_16x16x32_bf16(Bt[n][k], At[m][k], acc[ai][bj][m][n], 0, 0, 0); __builtin_amdgcn_s_setprio(0); } while (0)
; #define PG8_WAIT_V(n) asm volatile("s_waitcnt vmcnt(" #n ")" ::: "memory")
; #define PG8_WAIT_L(n) asm volatile("s_waitcnt lgkmcnt(" #n ")" ::: "memory")
; #define PG8_BAR __builtin_amdgcn_s_barrier()
; #define PG8_SCHED __builtin_amdgcn_sched_barrier(0)
; template <class Map, class Epi>
; DI void gemm_phase(LAS unsigned char* lds, const Map& MP, const Epi& E, const int nM, const int nN, const int K, const int lda, const int ldb) {
;     ...
;             PG8_LDB(B0, 0, 0); PG8_SCHED; PG8_LDA(At, 0, 0); PG8_STAGE(PG8_SA(1, 1), a1 + hstepA, voffA);
;             PG8_WAIT_L(8); PG8_BAR; PG8_WAIT_L(0); PG8_MMA(0, 0, At, B0); PG8_BAR; PG8_SCHED;
;             PG8_LDB(B1, 0, 1); PG8_STAGE(PG8_SB(0, 0), b2, voffB);
;             PG8_BAR; PG8_WAIT_L(0); PG8_MMA(0, 1, At, B1); PG8_BAR;
;             PG8_LDA(At, 0, 1); PG8_STAGE(PG8_SA(0, 0), a2, voffA);
;             PG8_BAR; PG8_WAIT_L(0); PG8_MMA(1, 0, At, B0); PG8_BAR; PG8_SCHED;
;             PG8_STAGE(PG8_SB(0, 1), b2 + hstepB, voffB);
;             PG8_WAIT_V(6); PG8_BAR; PG8_MMA(1, 1, At, B1); PG8_BAR;
;             PG8_LDB(B0, 1, 0); PG8_SCHED; PG8_LDA(At, 1, 0); PG8_STAGE(PG8_SA(0, 1), a2 + hstepA, voffA);
;             PG8_WAIT_L(8); PG8_BAR; PG8_WAIT_L(0); PG8_MMA(0, 0, At, B0); PG8_BAR; PG8_SCHED;
.LBB1_380:
	ds_read_b128 v[80:83], v189
	ds_read_b128 v[84:87], v189 offset:1024
	ds_read_b128 v[88:91], v189 offset:2048
	ds_read_b128 v[92:95], v189 offset:3072
	s_add_u32 s28, s44, 0xfff80080
	s_addc_u32 s29, s45, -1
	s_cmp_eq_u32 vcc_hi, 28
	s_cselect_b32 s47, s23, s29
	s_cselect_b32 s46, s61, s28
	s_cselect_b32 s29, s21, vcc_lo
	s_cselect_b32 s28, s58, s59
	v_lshl_add_u64 v[184:185], s[44:45], 0, v[178:179]
	s_add_i32 m0, s38, 0xc000
	ds_read_b128 v[96:99], v190
	ds_read_b128 v[100:103], v190 offset:1024
	ds_read_b128 v[108:111], v190 offset:2048
	ds_read_b128 v[112:115], v190 offset:3072
	ds_read_b128 v[160:163], v190 offset:4096
	ds_read_b128 v[164:167], v190 offset:5120
	ds_read_b128 v[198:201], v190 offset:6144
	ds_read_b128 v[202:205], v190 offset:7168
	global_load_lds_dwordx4 v[184:185], off
	v_lshl_add_u64 v[184:185], s[44:45], 0, v[176:177]
	s_add_i32 m0, s38, 0xe000
	s_nop 0
	global_load_lds_dwordx4 v[184:185], off
	s_waitcnt lgkmcnt(8)
	s_barrier
	s_setprio 1
	s_waitcnt lgkmcnt(7)
	v_mfma_f32_16x16x32_bf16 v[148:151], v[80:83], v[96:99], v[148:151]
	v_mfma_f32_16x16x32_bf16 v[144:147], v[88:91], v[96:99], v[144:147]
	s_waitcnt lgkmcnt(5)
	v_mfma_f32_16x16x32_bf16 v[136:139], v[80:83], v[108:111], v[136:139]
	v_mfma_f32_16x16x32_bf16 v[128:131], v[88:91], v[108:111], v[128:131]
	s_waitcnt lgkmcnt(3)
	v_mfma_f32_16x16x32_bf16 v[120:123], v[80:83], v[160:163], v[120:123]
	v_mfma_f32_16x16x32_bf16 v[104:107], v[88:91], v[160:163], v[104:107]
	s_waitcnt lgkmcnt(1)
	v_mfma_f32_16x16x32_bf16 v[76:79], v[80:83], v[198:201], v[76:79]
	v_mfma_f32_16x16x32_bf16 v[72:75], v[88:91], v[198:201], v[72:75]
	v_mfma_f32_16x16x32_bf16 v[148:151], v[84:87], v[100:103], v[148:151]
	v_mfma_f32_16x16x32_bf16 v[144:147], v[92:95], v[100:103], v[144:147]
	v_mfma_f32_16x16x32_bf16 v[136:139], v[84:87], v[112:115], v[136:139]
	v_mfma_f32_16x16x32_bf16 v[128:131], v[92:95], v[112:115], v[128:131]
	v_mfma_f32_16x16x32_bf16 v[120:123], v[84:87], v[164:167], v[120:123]
	v_mfma_f32_16x16x32_bf16 v[104:107], v[92:95], v[164:167], v[104:107]
	s_waitcnt lgkmcnt(0)
	v_mfma_f32_16x16x32_bf16 v[76:79], v[84:87], v[202:205], v[76:79]
	v_mfma_f32_16x16x32_bf16 v[72:75], v[92:95], v[202:205], v[72:75]
	s_setprio 0
	s_barrier
	s_add_i32 s68, s5, s37
	v_lshl_add_u64 v[184:185], s[28:29], 0, v[172:173]
	s_mov_b32 m0, s68
	ds_read_b128 v[206:209], v191
	ds_read_b128 v[210:213], v191 offset:1024
	ds_read_b128 v[214:217], v191 offset:2048
	ds_read_b128 v[218:221], v191 offset:3072
	global_load_lds_dwordx4 v[184:185], off
	v_lshl_add_u64 v[194:195], s[28:29], 0, v[168:169]
	s_add_i32 m0, s68, 0x2000
	s_nop 0
	global_load_lds_dwordx4 v[194:195], off
	s_barrier
	s_setprio 1
	s_waitcnt lgkmcnt(3)
	v_mfma_f32_16x16x32_bf16 v[156:159], v[206:209], v[96:99], v[156:159]
	s_waitcnt lgkmcnt(1)
	v_mfma_f32_16x16x32_bf16 v[96:99], v[214:217], v[96:99], v[152:155]
	v_mfma_f32_16x16x32_bf16 v[156:159], v[210:213], v[100:103], v[156:159]
	s_waitcnt lgkmcnt(0)
	v_mfma_f32_16x16x32_bf16 v[96:99], v[218:221], v[100:103], v[96:99]
	v_mfma_f32_16x16x32_bf16 v[100:103], v[206:209], v[108:111], v[140:143]
	v_mfma_f32_16x16x32_bf16 v[108:111], v[214:217], v[108:111], v[132:135]
	v_mfma_f32_16x16x32_bf16 v[116:119], v[214:217], v[160:163], v[116:119]
	v_mfma_f32_16x16x32_bf16 v[68:71], v[206:209], v[198:201], v[68:71]
	v_mfma_f32_16x16x32_bf16 v[64:67], v[214:217], v[198:201], v[64:67]
	v_mfma_f32_16x16x32_bf16 v[100:103], v[210:213], v[112:115], v[100:103]
	v_mfma_f32_16x16x32_bf16 v[108:111], v[218:221], v[112:115], v[108:111]
	v_mfma_f32_16x16x32_bf16 v[112:115], v[206:209], v[160:163], v[124:127]
	v_mfma_f32_16x16x32_bf16 v[116:119], v[218:221], v[164:167], v[116:119]
	v_mfma_f32_16x16x32_bf16 v[68:71], v[210:213], v[202:205], v[68:71]
	v_mfma_f32_16x16x32_bf16 v[64:67], v[218:221], v[202:205], v[64:67]
	v_mfma_f32_16x16x32_bf16 v[112:115], v[210:213], v[164:167], v[112:115]
	s_setprio 0
	s_mov_b32 m0, s38
	v_lshl_add_u64 v[226:227], s[46:47], 0, v[174:175]
	s_barrier
	ds_read_b128 v[124:127], v190 offset:16384
	ds_read_b128 v[132:135], v190 offset:17408
	ds_read_b128 v[140:143], v190 offset:18432
	ds_read_b128 v[152:155], v190 offset:19456
	ds_read_b128 v[160:163], v190 offset:20480
	ds_read_b128 v[164:167], v190 offset:21504
	ds_read_b128 v[198:201], v190 offset:22528
	ds_read_b128 v[202:205], v190 offset:23552
	global_load_lds_dwordx4 v[226:227], off
	v_lshl_add_u64 v[234:235], s[46:47], 0, v[170:171]
	s_mov_b32 m0, s39
	s_nop 0
	global_load_lds_dwordx4 v[234:235], off
	s_barrier
	s_setprio 1
	s_waitcnt lgkmcnt(7)
	v_mfma_f32_16x16x32_bf16 v[60:63], v[80:83], v[124:127], v[60:63]
	v_mfma_f32_16x16x32_bf16 v[48:51], v[88:91], v[124:127], v[48:51]
	s_waitcnt lgkmcnt(5)
	v_mfma_f32_16x16x32_bf16 v[40:43], v[80:83], v[140:143], v[40:43]
	v_mfma_f32_16x16x32_bf16 v[32:35], v[88:91], v[140:143], v[32:35]
	s_waitcnt lgkmcnt(3)
	v_mfma_f32_16x16x32_bf16 v[24:27], v[80:83], v[160:163], v[24:27]
	v_mfma_f32_16x16x32_bf16 v[16:19], v[88:91], v[160:163], v[16:19]
	s_waitcnt lgkmcnt(1)
	v_mfma_f32_16x16x32_bf16 v[12:15], v[80:83], v[198:201], v[12:15]
	v_mfma_f32_16x16x32_bf16 v[8:11], v[88:91], v[198:201], v[8:11]
	v_mfma_f32_16x16x32_bf16 v[60:63], v[84:87], v[132:135], v[60:63]
	v_mfma_f32_16x16x32_bf16 v[48:51], v[92:95], v[132:135], v[48:51]
	v_mfma_f32_16x16x32_bf16 v[40:43], v[84:87], v[152:155], v[40:43]
	v_mfma_f32_16x16x32_bf16 v[32:35], v[92:95], v[152:155], v[32:35]
	v_mfma_f32_16x16x32_bf16 v[24:27], v[84:87], v[164:167], v[24:27]
	v_mfma_f32_16x16x32_bf16 v[16:19], v[92:95], v[164:167], v[16:19]
	s_waitcnt lgkmcnt(0)
	v_mfma_f32_16x16x32_bf16 v[12:15], v[84:87], v[202:205], v[12:15]
	v_mfma_f32_16x16x32_bf16 v[8:11], v[92:95], v[202:205], v[8:11]
	s_setprio 0
	s_barrier
; #define PG8_STAGE(bufoff, gbase, voff) do { _Pragma("unroll") for (int _i = 0; _i < 2; ++_i) \
;         __builtin_amdgcn_global_load_lds((const unsigned*)((const char*)(gbase) + (voff)[_i]), (LAS unsigned*)(lds + (bufoff) + ldsw + _i * 8192), 16, 0, 0); } while (0)
; #define PG8_LDA(dst, b, h) do { _Pragma("unroll") for (int m = 0; m < 4; ++m) _Pragma("unroll") for (int k = 0; k < 2; ++k) dst[m][k] = *(const LAS bf16x8*)(lds + PG8_SA(b, h) + aoff + m * 2048 + k * 1024); } while (0)
; #define PG8_LDB(dst, b, h) do { _Pragma("unroll") for (int n = 0; n < 2; ++n) _Pragma("unroll") for (int k = 0; k < 2; ++k) dst[n][k] = *(const LAS bf16x8*)(lds + PG8_SB(b, h) + boff + n * 2048 + k * 1024); } while (0)
; #define PG8_MMA(ai, bj, At, Bt) do { __builtin_amdgcn_s_setprio(1); _Pragma("unroll") for (int m = 0; m < 4; ++m) _Pragma("unroll") for (int n = 0; n < 2; ++n) _Pragma("unroll") for (int k = 0; k < 2; ++k) \
;         acc[ai][bj][m][n] = __builtin_amdgcn_mfma_f32_16x16x32_bf16(Bt[n][k], At[m][k], acc[ai][bj][m][n], 0, 0, 0); __builtin_amdgcn_s_setprio(0); } while (0)
; #define PG8_WAIT_V(n) asm volatile("s_waitcnt vmcnt(" #n ")" ::: "memory")
; #define PG8_WAIT_L(n) asm volatile("s_waitcnt lgkmcnt(" #n ")" ::: "memory")
; #define PG8_BAR __builtin_amdgcn_s_barrier()
; #define PG8_SCHED __builtin_amdgcn_sched_barrier(0)
; template <class Map, class Epi>
; DI void gemm_phase(LAS unsigned char* lds, const Map& MP, const Epi& E, const int nM, const int nN, const int K, const int lda, const int ldb) {
;     ...
;             PG8_BAR; PG8_WAIT_L(0); PG8_MMA(1, 0, At, B0); PG8_BAR; PG8_SCHED;
;             PG8_STAGE(PG8_SB(0, 1), b2 + hstepB, voffB);
;             PG8_WAIT_V(6); PG8_BAR; PG8_MMA(1, 1, At, B1); PG8_BAR;
;             PG8_LDB(B0, 1, 0); PG8_SCHED; PG8_LDA(At, 1, 0); PG8_STAGE(PG8_SA(0, 1), a2 + hstepA, voffA);
;             PG8_WAIT_L(8); PG8_BAR; PG8_WAIT_L(0); PG8_MMA(0, 0, At, B0); PG8_BAR; PG8_SCHED;
;             PG8_LDB(B1, 1, 1); PG8_STAGE(PG8_SB(1, 0), b3, voffB);
;             PG8_BAR; PG8_WAIT_L(0); PG8_MMA(0, 1, At, B1); PG8_BAR;
;             PG8_LDA(At, 1, 1); PG8_STAGE(PG8_SA(1, 0), a3, voffA);
;             PG8_BAR; PG8_WAIT_L(0); PG8_MMA(1, 0, At, B0); PG8_BAR; PG8_SCHED;
	s_add_u32 s68, s28, 0x80000
	s_addc_u32 s69, s29, 0
	s_add_i32 s70, s2, s37
	v_lshl_add_u64 v[80:81], s[68:69], 0, v[172:173]
	s_mov_b32 m0, s70
	s_nop 0
	global_load_lds_dwordx4 v[80:81], off
	v_lshl_add_u64 v[80:81], s[68:69], 0, v[168:169]
	s_add_i32 m0, s70, 0x2000
	s_nop 0
	global_load_lds_dwordx4 v[80:81], off
	s_waitcnt vmcnt(6)
	s_barrier
	s_setprio 1
	v_mfma_f32_16x16x32_bf16 v[56:59], v[206:209], v[124:127], v[56:59]
	v_mfma_f32_16x16x32_bf16 v[52:55], v[214:217], v[124:127], v[52:55]
	v_mfma_f32_16x16x32_bf16 v[44:47], v[206:209], v[140:143], v[44:47]
	v_mfma_f32_16x16x32_bf16 v[36:39], v[214:217], v[140:143], v[36:39]
	v_mfma_f32_16x16x32_bf16 v[28:31], v[206:209], v[160:163], v[28:31]
	v_mfma_f32_16x16x32_bf16 v[20:23], v[214:217], v[160:163], v[20:23]
	v_mfma_f32_16x16x32_bf16 v[4:7], v[206:209], v[198:201], v[4:7]
	v_mfma_f32_16x16x32_bf16 v[0:3], v[214:217], v[198:201], v[0:3]
	v_mfma_f32_16x16x32_bf16 v[56:59], v[210:213], v[132:135], v[56:59]
	v_mfma_f32_16x16x32_bf16 v[52:55], v[218:221], v[132:135], v[52:55]
	v_mfma_f32_16x16x32_bf16 v[44:47], v[210:213], v[152:155], v[44:47]
	v_mfma_f32_16x16x32_bf16 v[36:39], v[218:221], v[152:155], v[36:39]
	v_mfma_f32_16x16x32_bf16 v[28:31], v[210:213], v[164:167], v[28:31]
	v_mfma_f32_16x16x32_bf16 v[20:23], v[218:221], v[164:167], v[20:23]
	v_mfma_f32_16x16x32_bf16 v[4:7], v[210:213], v[202:205], v[4:7]
	v_mfma_f32_16x16x32_bf16 v[0:3], v[218:221], v[202:205], v[0:3]
	s_setprio 0
	s_add_i32 s68, 0, 0x18000
	v_add_u32_e32 v92, s68, v188
	s_barrier
	ds_read_b128 v[80:83], v92
	ds_read_b128 v[84:87], v92 offset:1024
	ds_read_b128 v[88:91], v92 offset:2048
	ds_read_b128 v[92:95], v92 offset:3072
	s_add_u32 s46, s46, 0x80000
	s_addc_u32 s47, s47, 0
	s_mov_b32 m0, s56
	v_lshl_add_u64 v[140:141], s[46:47], 0, v[174:175]
	ds_read_b128 v[124:127], v190 offset:32768
	ds_read_b128 v[132:135], v190 offset:33792
	ds_read_b128 v[160:163], v190 offset:34816
	ds_read_b128 v[164:167], v190 offset:35840
	ds_read_b128 v[198:201], v190 offset:36864
	ds_read_b128 v[202:205], v190 offset:37888
	ds_read_b128 v[206:209], v190 offset:38912
	ds_read_b128 v[210:213], v190 offset:39936
	global_load_lds_dwordx4 v[140:141], off
	v_lshl_add_u64 v[140:141], s[46:47], 0, v[170:171]
	s_mov_b32 m0, s57
	s_nop 0
	global_load_lds_dwordx4 v[140:141], off
	s_waitcnt lgkmcnt(8)
	s_barrier
	s_setprio 1
	s_waitcnt lgkmcnt(7)
	v_mfma_f32_16x16x32_bf16 v[140:143], v[80:83], v[124:127], v[148:151]
	s_waitcnt lgkmcnt(6)
	v_mfma_f32_16x16x32_bf16 v[148:151], v[84:87], v[132:135], v[140:143]
	v_mfma_f32_16x16x32_bf16 v[140:143], v[88:91], v[124:127], v[144:147]
	s_waitcnt lgkmcnt(5)
	v_mfma_f32_16x16x32_bf16 v[136:139], v[80:83], v[160:163], v[136:139]
	v_mfma_f32_16x16x32_bf16 v[128:131], v[88:91], v[160:163], v[128:131]
	s_waitcnt lgkmcnt(3)
	v_mfma_f32_16x16x32_bf16 v[120:123], v[80:83], v[198:201], v[120:123]
	v_mfma_f32_16x16x32_bf16 v[104:107], v[88:91], v[198:201], v[104:107]
	s_waitcnt lgkmcnt(1)
	v_mfma_f32_16x16x32_bf16 v[76:79], v[80:83], v[206:209], v[76:79]
	v_mfma_f32_16x16x32_bf16 v[72:75], v[88:91], v[206:209], v[72:75]
	v_mfma_f32_16x16x32_bf16 v[144:147], v[92:95], v[132:135], v[140:143]
	v_mfma_f32_16x16x32_bf16 v[136:139], v[84:87], v[164:167], v[136:139]
	v_mfma_f32_16x16x32_bf16 v[128:131], v[92:95], v[164:167], v[128:131]
	v_mfma_f32_16x16x32_bf16 v[120:123], v[84:87], v[202:205], v[120:123]
	v_mfma_f32_16x16x32_bf16 v[104:107], v[92:95], v[202:205], v[104:107]
	s_waitcnt lgkmcnt(0)
	v_mfma_f32_16x16x32_bf16 v[76:79], v[84:87], v[210:213], v[76:79]
	v_mfma_f32_16x16x32_bf16 v[72:75], v[92:95], v[210:213], v[72:75]
	s_setprio 0
	s_barrier
	s_add_i32 s46, 0, 0x1c000
	v_add_u32_e32 v140, s46, v188
	s_add_i32 s47, s68, s37
	ds_read_b128 v[214:217], v140
	ds_read_b128 v[218:221], v140 offset:1024
	ds_read_b128 v[222:225], v140 offset:2048
	ds_read_b128 v[230:233], v140 offset:3072
	v_lshl_add_u64 v[140:141], v[184:185], 0, s[14:15]
	s_mov_b32 m0, s47
	s_nop 0
	global_load_lds_dwordx4 v[140:141], off
	v_lshl_add_u64 v[140:141], v[194:195], 0, s[14:15]
	s_add_i32 m0, s47, 0x2000
	s_nop 0
	global_load_lds_dwordx4 v[140:141], off
	s_barrier
	s_setprio 1
	s_waitcnt lgkmcnt(1)
	v_mfma_f32_16x16x32_bf16 v[96:99], v[222:225], v[124:127], v[96:99]
	v_mfma_f32_16x16x32_bf16 v[140:143], v[214:217], v[124:127], v[156:159]
	s_waitcnt lgkmcnt(0)
	v_mfma_f32_16x16x32_bf16 v[152:155], v[230:233], v[132:135], v[96:99]
	v_mfma_f32_16x16x32_bf16 v[96:99], v[214:217], v[160:163], v[100:103]
	v_mfma_f32_16x16x32_bf16 v[156:159], v[218:221], v[132:135], v[140:143]
	v_mfma_f32_16x16x32_bf16 v[140:143], v[218:221], v[164:167], v[96:99]
	v_mfma_f32_16x16x32_bf16 v[96:99], v[222:225], v[160:163], v[108:111]
	v_mfma_f32_16x16x32_bf16 v[132:135], v[230:233], v[164:167], v[96:99]
	v_mfma_f32_16x16x32_bf16 v[96:99], v[214:217], v[198:201], v[112:115]
	v_mfma_f32_16x16x32_bf16 v[124:127], v[218:221], v[202:205], v[96:99]
	v_mfma_f32_16x16x32_bf16 v[96:99], v[222:225], v[198:201], v[116:119]
	v_mfma_f32_16x16x32_bf16 v[68:71], v[214:217], v[206:209], v[68:71]
	v_mfma_f32_16x16x32_bf16 v[64:67], v[222:225], v[206:209], v[64:67]
	v_mfma_f32_16x16x32_bf16 v[116:119], v[230:233], v[202:205], v[96:99]
	v_mfma_f32_16x16x32_bf16 v[68:71], v[218:221], v[210:213], v[68:71]
	v_mfma_f32_16x16x32_bf16 v[64:67], v[230:233], v[210:213], v[64:67]
	s_setprio 0
	s_mov_b32 m0, s62
	v_lshl_add_u64 v[184:185], v[226:227], 0, s[14:15]
	s_barrier
; DI float dpp_ror1(float v)  { return __builtin_bit_cast(float, __builtin_amdgcn_update_dpp(0, __builtin_bit_cast(int, v), 0x121, 0xf, 0xf, false)); }
; #define PG8_WAIT_V(n) asm volatile("s_waitcnt vmcnt(" #n ")" ::: "memory")
;     DI void operator()(const f32x4 (&acc)[2][2][4][2], const Unit& u, int wr, int wc, int fr, int fq) const {
;         const int row0 = u.pm * BM + wr * 64 + fr, ch0 = u.pn * 128 + wc * 32 + 8 * fq;
;         f32x4 w0[2], w1[2], w2[2], bb[2];
; #pragma unroll
;         for (int n = 0; n < 2; ++n) { w0[n] = *(const f32x4*)(cw + ch0 + 4 * n); w1[n] = *(const f32x4*)(cw + DFF + ch0 + 4 * n); w2[n] = *(const f32x4*)(cw + 2 * DFF + ch0 + 4 * n); bb[n] = *(const f32x4*)(cb + ch0 + 4 * n); }
; #pragma unroll
;         for (int ai = 0; ai < 2; ++ai)
; #pragma unroll
;             for (int m = 0; m < 4; ++m) {
;                 const bool efirst = (m == 0) && (fr == 0), elast = (m == 3) && (fr == 15);
;                 const int row = row0 + ai * HALF + m * 16;
;                 f32x4 gc[2];
; #pragma unroll
;                 for (int n = 0; n < 2; ++n) {
;                     const f32x4 g = acc[ai][0][m][n];
;                     const f32x4 gprev = acc[ai][0][m > 0 ? m - 1 : 0][n], gnext = acc[ai][0][m < 3 ? m + 1 : 3][n];
;                     f32x4 up, dn;
; #pragma unroll
;                     for (int e = 0; e < 4; ++e) {
;                         const float pu = (m > 0 && fr == 15) ? gprev[e] : g[e];
;                         const float pd = (m < 3 && fr == 0) ? gnext[e] : g[e];
;                         up[e] = dpp_ror1(pu); dn[e] = dpp_ror15(pd);
;                     }
;                     if (efirst) up = (f32x4){0.f, 0.f, 0.f, 0.f};
;                     if (elast) dn = (f32x4){0.f, 0.f, 0.f, 0.f};
;                     gc[n] = w0[n] * up + w1[n] * g + w2[n] * dn + bb[n];
; template <class Map, class Epi>
; DI void gemm_phase(LAS unsigned char* lds, const Map& MP, const Epi& E, const int nM, const int nN, const int K, const int lda, const int ldb) {
;     ...
;             PG8_BAR; PG8_WAIT_L(0); PG8_MMA(0, 1, At, B1); PG8_BAR;
;             PG8_LDA(At, 1, 1); PG8_STAGE(PG8_SA(1, 0), a3, voffA);
;             PG8_BAR; PG8_WAIT_L(0); PG8_MMA(1, 0, At, B0); PG8_BAR; PG8_SCHED;
;             PG8_STAGE(PG8_SB(1, 1), b3 + hstepB, voffB);
;             PG8_WAIT_V(6); PG8_BAR; PG8_MMA(1, 1, At, B1); PG8_BAR;
	ds_read_b128 v[96:99], v190 offset:49152
	ds_read_b128 v[100:103], v190 offset:50176
	ds_read_b128 v[108:111], v190 offset:51200
	ds_read_b128 v[112:115], v190 offset:52224
	ds_read_b128 v[160:163], v190 offset:53248
	ds_read_b128 v[164:167], v190 offset:54272
	ds_read_b128 v[198:201], v190 offset:55296
	ds_read_b128 v[202:205], v190 offset:56320
	global_load_lds_dwordx4 v[184:185], off
	v_lshl_add_u64 v[184:185], v[234:235], 0, s[14:15]
	s_mov_b32 m0, s63
	s_nop 0
	global_load_lds_dwordx4 v[184:185], off
	s_barrier
	s_setprio 1
	s_waitcnt lgkmcnt(7)
	v_mfma_f32_16x16x32_bf16 v[60:63], v[80:83], v[96:99], v[60:63]
	v_mfma_f32_16x16x32_bf16 v[48:51], v[88:91], v[96:99], v[48:51]
	s_waitcnt lgkmcnt(5)
	v_mfma_f32_16x16x32_bf16 v[40:43], v[80:83], v[108:111], v[40:43]
	v_mfma_f32_16x16x32_bf16 v[32:35], v[88:91], v[108:111], v[32:35]
	s_waitcnt lgkmcnt(3)
	v_mfma_f32_16x16x32_bf16 v[24:27], v[80:83], v[160:163], v[24:27]
	v_mfma_f32_16x16x32_bf16 v[16:19], v[88:91], v[160:163], v[16:19]
	s_waitcnt lgkmcnt(1)
	v_mfma_f32_16x16x32_bf16 v[12:15], v[80:83], v[198:201], v[12:15]
	v_mfma_f32_16x16x32_bf16 v[8:11], v[88:91], v[198:201], v[8:11]
	v_mfma_f32_16x16x32_bf16 v[60:63], v[84:87], v[100:103], v[60:63]
	v_mfma_f32_16x16x32_bf16 v[48:51], v[92:95], v[100:103], v[48:51]
	v_mfma_f32_16x16x32_bf16 v[40:43], v[84:87], v[112:115], v[40:43]
	v_mfma_f32_16x16x32_bf16 v[32:35], v[92:95], v[112:115], v[32:35]
	v_mfma_f32_16x16x32_bf16 v[24:27], v[84:87], v[164:167], v[24:27]
	v_mfma_f32_16x16x32_bf16 v[16:19], v[92:95], v[164:167], v[16:19]
	s_waitcnt lgkmcnt(0)
	v_mfma_f32_16x16x32_bf16 v[12:15], v[84:87], v[202:205], v[12:15]
	v_mfma_f32_16x16x32_bf16 v[8:11], v[92:95], v[202:205], v[8:11]
	s_setprio 0
	s_barrier
	s_add_u32 s28, s28, 0x80080
	s_addc_u32 s29, s29, 0
	s_add_i32 s46, s46, s37
	v_lshl_add_u64 v[80:81], s[28:29], 0, v[172:173]
	s_mov_b32 m0, s46
	s_nop 0
	global_load_lds_dwordx4 v[80:81], off
	v_lshl_add_u64 v[80:81], s[28:29], 0, v[168:169]
	s_add_i32 m0, s46, 0x2000
	s_nop 0
	global_load_lds_dwordx4 v[80:81], off
	s_waitcnt vmcnt(6)
	s_barrier
	s_setprio 1
	v_mfma_f32_16x16x32_bf16 v[56:59], v[214:217], v[96:99], v[56:59]
	v_mfma_f32_16x16x32_bf16 v[52:55], v[222:225], v[96:99], v[52:55]
	v_mfma_f32_16x16x32_bf16 v[44:47], v[214:217], v[108:111], v[44:47]
	v_mfma_f32_16x16x32_bf16 v[36:39], v[222:225], v[108:111], v[36:39]
	v_mfma_f32_16x16x32_bf16 v[28:31], v[214:217], v[160:163], v[28:31]
	v_mfma_f32_16x16x32_bf16 v[20:23], v[222:225], v[160:163], v[20:23]
	v_mfma_f32_16x16x32_bf16 v[4:7], v[214:217], v[198:201], v[4:7]
	v_mfma_f32_16x16x32_bf16 v[0:3], v[222:225], v[198:201], v[0:3]
	v_mfma_f32_16x16x32_bf16 v[56:59], v[218:221], v[100:103], v[56:59]
	v_mfma_f32_16x16x32_bf16 v[52:55], v[230:233], v[100:103], v[52:55]
	v_mfma_f32_16x16x32_bf16 v[44:47], v[218:221], v[112:115], v[44:47]
	v_mfma_f32_16x16x32_bf16 v[36:39], v[230:233], v[112:115], v[36:39]
	v_mfma_f32_16x16x32_bf16 v[28:31], v[218:221], v[164:167], v[28:31]
	v_mfma_f32_16x16x32_bf16 v[20:23], v[230:233], v[164:167], v[20:23]
	v_mfma_f32_16x16x32_bf16 v[4:7], v[218:221], v[202:205], v[4:7]
	v_mfma_f32_16x16x32_bf16 v[0:3], v[230:233], v[202:205], v[0:3]
	s_setprio 0
	s_add_i32 vcc_hi, vcc_hi, 2
	s_add_u32 s59, s59, 0x100
	s_addc_u32 vcc_lo, vcc_lo, 0
	s_add_u32 s44, s44, 0x100
	s_addc_u32 s45, s45, 0
	s_cmp_gt_u32 vcc_hi, 29
	s_barrier
	s_cbranch_scc0 .LBB1_380
	s_lshl_b32 s23, s43, 7
	v_mov_b32_e32 v194, v186
	v_mov_b32_e32 v80, v187
	s_or_b32 s23, s23, s67
	v_mov_b32_e32 v160, 0
	v_lshl_add_u32 v184, v80, 3, s23
	v_ashrrev_i32_e32 v185, 31, v184
	v_lshlrev_b64 v[80:81], 2, v[184:185]
	v_lshl_add_u64 v[84:85], s[52:53], 0, v[80:81]
	v_lshl_add_u64 v[88:89], s[16:17], 0, v[80:81]
	v_lshl_add_u64 v[92:93], s[18:19], 0, v[80:81]
	v_lshl_add_u64 v[112:113], s[54:55], 0, v[80:81]
	global_load_dwordx4 v[80:83], v[84:85], off offset:16
	global_load_dwordx4 v[96:99], v[84:85], off
	s_nop 0
	global_load_dwordx4 v[84:87], v[88:89], off offset:16
	global_load_dwordx4 v[100:103], v[88:89], off
	s_nop 0
	global_load_dwordx4 v[88:91], v[92:93], off offset:16
	global_load_dwordx4 v[108:111], v[92:93], off
	s_nop 0
	global_load_dwordx4 v[92:95], v[112:113], off offset:16
	s_nop 0
	global_load_dwordx4 v[112:115], v[112:113], off
	v_cmp_eq_u32_e32 vcc, 0, v194
	v_mov_b32_e32 v164, 0
	v_mov_b32_e32 v195, 0
	v_cndmask_b32_e32 v161, v148, v136, vcc
	v_cndmask_b32_e32 v162, v149, v137, vcc
	v_cndmask_b32_e32 v163, v150, v138, vcc
	v_mov_b32_dpp v160, v161 row_ror:15 row_mask:0xf bank_mask:0xf
	v_mov_b32_e32 v161, 0
	v_mov_b32_e32 v166, 0
	v_mov_b32_e32 v167, 0
	v_mov_b32_dpp v161, v162 row_ror:15 row_mask:0xf bank_mask:0xf
	v_mov_b32_e32 v162, 0
	v_mov_b32_dpp v164, v150 row_ror:1 row_mask:0xf bank_mask:0xf
	v_cndmask_b32_e32 v165, v151, v139, vcc
	v_mov_b32_dpp v162, v163 row_ror:15 row_mask:0xf bank_mask:0xf
	v_mov_b32_dpp v195, v151 row_ror:1 row_mask:0xf bank_mask:0xf
	v_mov_b32_e32 v163, 0
	v_mov_b32_dpp v166, v148 row_ror:1 row_mask:0xf bank_mask:0xf
	v_mov_b32_dpp v167, v149 row_ror:1 row_mask:0xf bank_mask:0xf
	v_mov_b32_dpp v163, v165 row_ror:15 row_mask:0xf bank_mask:0xf
	v_cndmask_b32_e64 v165, v195, 0, vcc
	v_cndmask_b32_e64 v164, v164, 0, vcc
	v_cndmask_b32_e64 v167, v167, 0, vcc
	v_cndmask_b32_e64 v166, v166, 0, vcc
	v_mov_b32_e32 v195, 0
	v_mov_b32_e32 v196, 0
	v_mov_b32_e32 v198, 0
	v_mov_b32_e32 v200, 0
	v_mov_b32_dpp v195, v144 row_ror:1 row_mask:0xf bank_mask:0xf
	v_mov_b32_dpp v196, v145 row_ror:1 row_mask:0xf bank_mask:0xf
	v_mov_b32_dpp v198, v146 row_ror:1 row_mask:0xf bank_mask:0xf
	v_cndmask_b32_e32 v199, v147, v131, vcc
	v_mov_b32_dpp v200, v147 row_ror:1 row_mask:0xf bank_mask:0xf
	v_cndmask_b32_e64 v198, v198, 0, vcc
	v_cndmask_b32_e64 v201, v196, 0, vcc
	s_lshl_b32 s21, s42, 8
	s_add_i32 s21, s21, s49
	v_add_u32_e32 v193, s21, v194
	v_cmp_ne_u32_e64 s[46:47], 0, v194
	s_waitcnt vmcnt(0)
; DI unsigned pack2(float a, float b) { f32x2 v = {a, b}; hwbf16x2 r = __builtin_convertvector(v, hwbf16x2); return __builtin_bit_cast(unsigned, r); }
; DI float dpp_ror1(float v)  { return __builtin_bit_cast(float, __builtin_amdgcn_update_dpp(0, __builtin_bit_cast(int, v), 0x121, 0xf, 0xf, false)); }
; DI float dpp_ror15(float v) { return __builtin_bit_cast(float, __builtin_amdgcn_update_dpp(0, __builtin_bit_cast(int, v), 0x12F, 0xf, 0xf, false)); }
; DI float silu_mul(float g, float v) { return g * v * __builtin_amdgcn_rcpf(1.0f + __builtin_amdgcn_exp2f(-LOG2E * g)); }
;     DI void operator()(const f32x4 (&acc)[2][2][4][2], const Unit& u, int wr, int wc, int fr, int fq) const {
;     ...
;                 for (int n = 0; n < 2; ++n) {
;                     const f32x4 g = acc[ai][0][m][n];
;                     const f32x4 gprev = acc[ai][0][m > 0 ? m - 1 : 0][n], gnext = acc[ai][0][m < 3 ? m + 1 : 3][n];
;                     f32x4 up, dn;
; #pragma unroll
;                     for (int e = 0; e < 4; ++e) {
;                         const float pu = (m > 0 && fr == 15) ? gprev[e] : g[e];
;                         const float pd = (m < 3 && fr == 0) ? gnext[e] : g[e];
;                         up[e] = dpp_ror1(pu); dn[e] = dpp_ror15(pd);
;                     }
;                     if (efirst) up = (f32x4){0.f, 0.f, 0.f, 0.f};
;                     if (elast) dn = (f32x4){0.f, 0.f, 0.f, 0.f};
;                     gc[n] = w0[n] * up + w1[n] * g + w2[n] * dn + bb[n];
;                 }
;                 if (efirst || elast) {
;                     const size_t eo = (size_t)((row >> 6) * 2 + (elast ? 1 : 0)) * DFF + ch0;
; #pragma unroll
;                     for (int n = 0; n < 2; ++n) { *(f32x4*)(EP + eo + 4 * n) = gc[n]; *(f32x4*)(ER + eo + 4 * n) = acc[ai][0][m][n]; *(f32x4*)(EV + eo + 4 * n) = acc[ai][1][m][n]; }
;                 } else {
;                     const f32x4 v0 = acc[ai][1][m][0], v1 = acc[ai][1][m][1];
;                     u32x4 o;
;                     o[0] = pack2(silu_mul(gc[0][0], v0[0]), silu_mul(gc[0][1], v0[1])); o[1] = pack2(silu_mul(gc[0][2], v0[2]), silu_mul(gc[0][3], v0[3]));
;                     o[2] = pack2(silu_mul(gc[1][0], v1[0]), silu_mul(gc[1][1], v1[1])); o[3] = pack2(silu_mul(gc[1][2], v1[2]), silu_mul(gc[1][3], v1[3]));
;                     *(u32x4*)(ACT + (size_t)row * DFF + ch0) = o;
;                 }
	v_pk_mul_f32 v[164:165], v[98:99], v[164:165]
	v_pk_mul_f32 v[166:167], v[96:97], v[166:167]
	v_pk_fma_f32 v[164:165], v[150:151], v[102:103], v[164:165]
	v_pk_fma_f32 v[166:167], v[148:149], v[100:101], v[166:167]
	v_pk_fma_f32 v[162:163], v[110:111], v[162:163], v[164:165]
	v_cndmask_b32_e32 v165, v144, v128, vcc
	v_mov_b32_e32 v164, 0
	v_pk_fma_f32 v[160:161], v[108:109], v[160:161], v[166:167]
	v_cndmask_b32_e32 v166, v145, v129, vcc
	v_mov_b32_dpp v164, v165 row_ror:15 row_mask:0xf bank_mask:0xf
	v_mov_b32_e32 v165, 0
	v_cndmask_b32_e32 v167, v146, v130, vcc
	v_pk_add_f32 v[162:163], v[114:115], v[162:163]
	v_mov_b32_dpp v165, v166 row_ror:15 row_mask:0xf bank_mask:0xf
	v_mov_b32_e32 v166, 0
	v_pk_add_f32 v[160:161], v[112:113], v[160:161]
	s_nop 0
	v_mov_b32_dpp v166, v167 row_ror:15 row_mask:0xf bank_mask:0xf
	v_mov_b32_e32 v167, 0
	s_nop 1
	v_mov_b32_dpp v167, v199 row_ror:15 row_mask:0xf bank_mask:0xf
	v_cndmask_b32_e64 v199, v200, 0, vcc
	v_cndmask_b32_e64 v200, v195, 0, vcc
	v_pk_mul_f32 v[200:201], v[80:81], v[200:201]
	v_pk_mul_f32 v[198:199], v[82:83], v[198:199]
	v_pk_fma_f32 v[200:201], v[144:145], v[84:85], v[200:201]
	v_pk_fma_f32 v[198:199], v[146:147], v[86:87], v[198:199]
	v_pk_fma_f32 v[164:165], v[88:89], v[164:165], v[200:201]
	v_pk_fma_f32 v[166:167], v[90:91], v[166:167], v[198:199]
	v_pk_add_f32 v[164:165], v[92:93], v[164:165]
	v_pk_add_f32 v[166:167], v[94:95], v[166:167]
	s_and_saveexec_b64 s[28:29], s[46:47]
	s_xor_b64 s[28:29], exec, s[28:29]
	s_cbranch_execz .LBB1_383
	v_mul_f32_e32 v195, 0xbfb8aa3b, v160
	v_exp_f32_e32 v195, v195
	v_mul_f32_e32 v196, 0xbfb8aa3b, v161
	v_exp_f32_e32 v196, v196
	v_pk_mul_f32 v[160:161], v[156:157], v[160:161]
	v_add_f32_e32 v195, 1.0, v195
	v_rcp_f32_e32 v198, v195
	v_add_f32_e32 v196, 1.0, v196
	v_mul_f32_e32 v195, 0xbfb8aa3b, v162
	v_rcp_f32_e32 v199, v196
	v_exp_f32_e32 v195, v195
	v_mul_f32_e32 v196, 0xbfb8aa3b, v163
	v_exp_f32_e32 v196, v196
	v_pk_mul_f32 v[160:161], v[160:161], v[198:199]
	v_add_f32_e32 v195, 1.0, v195
	v_rcp_f32_e32 v200, v195
	v_add_f32_e32 v195, 1.0, v196
	v_rcp_f32_e32 v201, v195
	v_cvt_pk_bf16_f32 v160, v160, v161
	v_mul_f32_e32 v161, 0xbfb8aa3b, v164
	v_exp_f32_e32 v195, v161
	v_mul_f32_e32 v161, 0xbfb8aa3b, v165
	v_exp_f32_e32 v196, v161
	v_pk_mul_f32 v[162:163], v[158:159], v[162:163]
	v_pk_mul_f32 v[164:165], v[152:153], v[164:165]
	v_pk_mul_f32 v[162:163], v[162:163], v[200:201]
	s_nop 0
	v_cvt_pk_bf16_f32 v161, v162, v163
	v_add_f32_e32 v162, 1.0, v195
	v_mul_f32_e32 v195, 0xbfb8aa3b, v166
	v_add_f32_e32 v163, 1.0, v196
	v_exp_f32_e32 v195, v195
	v_mul_f32_e32 v196, 0xbfb8aa3b, v167
	v_exp_f32_e32 v196, v196
	v_rcp_f32_e32 v162, v162
	v_add_f32_e32 v195, 1.0, v195
	v_rcp_f32_e32 v198, v195
	v_add_f32_e32 v195, 1.0, v196
	v_rcp_f32_e32 v163, v163
	v_rcp_f32_e32 v199, v195
	v_pk_mul_f32 v[166:167], v[154:155], v[166:167]
	v_pk_mul_f32 v[162:163], v[164:165], v[162:163]
	v_pk_mul_f32 v[164:165], v[166:167], v[198:199]
	v_cvt_pk_bf16_f32 v162, v162, v163
	v_cvt_pk_bf16_f32 v163, v164, v165
	v_mov_b64_e32 v[164:165], s[6:7]
	v_mad_i64_i32 v[164:165], s[42:43], v193, s30, v[164:165]
	v_lshl_add_u64 v[164:165], v[184:185], 1, v[164:165]
	global_store_dwordx4 v[164:165], v[160:163], off
.LBB1_383:
	s_or_saveexec_b64 s[28:29], s[28:29]
	v_readlane_b32 s61, v246, 49
	s_xor_b64 exec, exec, s[28:29]
	s_cbranch_execz .LBB1_385
	s_ashr_i32 s21, s21, 5
	v_mad_i64_i32 v[198:199], s[42:43], s21, v192, v[184:185]
	v_lshlrev_b64 v[198:199], 2, v[198:199]
	v_lshl_add_u64 v[200:201], s[8:9], 0, v[198:199]
	global_store_dwordx4 v[200:201], v[160:163], off
	s_nop 1
	v_lshl_add_u64 v[160:161], s[10:11], 0, v[198:199]
	v_lshl_add_u64 v[162:163], s[12:13], 0, v[198:199]
	global_store_dwordx4 v[160:161], v[148:151], off
	global_store_dwordx4 v[162:163], v[156:159], off
	global_store_dwordx4 v[200:201], v[164:167], off offset:16
	global_store_dwordx4 v[160:161], v[144:147], off offset:16
	global_store_dwordx4 v[162:163], v[152:155], off offset:16
.LBB1_385:
	s_or_b64 exec, exec, s[28:29]
	v_cmp_eq_u32_e64 s[44:45], 15, v194
	v_cndmask_b32_e32 v153, v136, v120, vcc
	v_cndmask_b32_e32 v154, v137, v121, vcc
	v_cndmask_b32_e64 v152, v136, v148, s[44:45]
	v_mov_b32_e32 v148, 0
	v_cndmask_b32_e32 v155, v138, v122, vcc
	v_cndmask_b32_e32 v156, v139, v123, vcc
	v_mov_b32_dpp v148, v152 row_ror:1 row_mask:0xf bank_mask:0xf
	v_mov_b32_e32 v152, 0
	v_cndmask_b32_e32 v157, v128, v104, vcc
	v_cndmask_b32_e32 v158, v129, v105, vcc
	v_mov_b32_dpp v152, v153 row_ror:15 row_mask:0xf bank_mask:0xf
	v_cndmask_b32_e64 v153, v137, v149, s[44:45]
	v_mov_b32_e32 v149, 0
	v_cndmask_b32_e32 v159, v130, v106, vcc
	v_cndmask_b32_e32 v160, v131, v107, vcc
	v_mov_b32_dpp v149, v153 row_ror:1 row_mask:0xf bank_mask:0xf
	v_mov_b32_e32 v153, 0
	v_pk_mul_f32 v[148:149], v[96:97], v[148:149]
	v_cmp_ne_u32_e64 s[42:43], 15, v194
	v_mov_b32_dpp v153, v154 row_ror:15 row_mask:0xf bank_mask:0xf
	v_pk_fma_f32 v[148:149], v[136:137], v[100:101], v[148:149]
	v_cndmask_b32_e64 v154, v138, v150, s[44:45]
	v_mov_b32_e32 v150, 0
	v_pk_fma_f32 v[148:149], v[108:109], v[152:153], v[148:149]
	s_nop 0
	v_mov_b32_dpp v150, v154 row_ror:1 row_mask:0xf bank_mask:0xf
	v_mov_b32_e32 v154, 0
	v_pk_add_f32 v[148:149], v[112:113], v[148:149]
	s_nop 0
	v_mov_b32_dpp v154, v155 row_ror:15 row_mask:0xf bank_mask:0xf
	v_cndmask_b32_e64 v155, v139, v151, s[44:45]
	v_mov_b32_e32 v151, 0
	v_mul_f32_e32 v152, 0xbfb8aa3b, v148
	v_mul_f32_e32 v153, 0xbfb8aa3b, v149
	v_mov_b32_dpp v151, v155 row_ror:1 row_mask:0xf bank_mask:0xf
	v_exp_f32_e32 v152, v152
	v_exp_f32_e32 v153, v153
	v_mov_b32_e32 v155, 0
	v_pk_mul_f32 v[150:151], v[98:99], v[150:151]
; DI unsigned pack2(float a, float b) { f32x2 v = {a, b}; hwbf16x2 r = __builtin_convertvector(v, hwbf16x2); return __builtin_bit_cast(unsigned, r); }
; DI float dpp_ror1(float v)  { return __builtin_bit_cast(float, __builtin_amdgcn_update_dpp(0, __builtin_bit_cast(int, v), 0x121, 0xf, 0xf, false)); }
; DI float dpp_ror15(float v) { return __builtin_bit_cast(float, __builtin_amdgcn_update_dpp(0, __builtin_bit_cast(int, v), 0x12F, 0xf, 0xf, false)); }
; DI float silu_mul(float g, float v) { return g * v * __builtin_amdgcn_rcpf(1.0f + __builtin_amdgcn_exp2f(-LOG2E * g)); }
;     DI void operator()(const f32x4 (&acc)[2][2][4][2], const Unit& u, int wr, int wc, int fr, int fq) const {
;     ...
;                 for (int n = 0; n < 2; ++n) {
;                     const f32x4 g = acc[ai][0][m][n];
;                     const f32x4 gprev = acc[ai][0][m > 0 ? m - 1 : 0][n], gnext = acc[ai][0][m < 3 ? m + 1 : 3][n];
;                     f32x4 up, dn;
; #pragma unroll
;                     for (int e = 0; e < 4; ++e) {
;                         const float pu = (m > 0 && fr == 15) ? gprev[e] : g[e];
;                         const float pd = (m < 3 && fr == 0) ? gnext[e] : g[e];
;                         up[e] = dpp_ror1(pu); dn[e] = dpp_ror15(pd);
;                     }
;                     if (efirst) up = (f32x4){0.f, 0.f, 0.f, 0.f};
;                     if (elast) dn = (f32x4){0.f, 0.f, 0.f, 0.f};
;                     gc[n] = w0[n] * up + w1[n] * g + w2[n] * dn + bb[n];
;                 }
;                 if (efirst || elast) {
;                     const size_t eo = (size_t)((row >> 6) * 2 + (elast ? 1 : 0)) * DFF + ch0;
; #pragma unroll
;                     for (int n = 0; n < 2; ++n) { *(f32x4*)(EP + eo + 4 * n) = gc[n]; *(f32x4*)(ER + eo + 4 * n) = acc[ai][0][m][n]; *(f32x4*)(EV + eo + 4 * n) = acc[ai][1][m][n]; }
;                 } else {
;                     const f32x4 v0 = acc[ai][1][m][0], v1 = acc[ai][1][m][1];
;                     u32x4 o;
;                     o[0] = pack2(silu_mul(gc[0][0], v0[0]), silu_mul(gc[0][1], v0[1])); o[1] = pack2(silu_mul(gc[0][2], v0[2]), silu_mul(gc[0][3], v0[3]));
;                     o[2] = pack2(silu_mul(gc[1][0], v1[0]), silu_mul(gc[1][1], v1[1])); o[3] = pack2(silu_mul(gc[1][2], v1[2]), silu_mul(gc[1][3], v1[3]));
;                     *(u32x4*)(ACT + (size_t)row * DFF + ch0) = o;
;                 }
	v_add_f32_e32 v152, 1.0, v152
	v_mov_b32_dpp v155, v156 row_ror:15 row_mask:0xf bank_mask:0xf
	v_cndmask_b32_e64 v156, v128, v144, s[44:45]
	v_mov_b32_e32 v144, 0
	v_pk_fma_f32 v[150:151], v[138:139], v[102:103], v[150:151]
	v_add_f32_e32 v153, 1.0, v153
	v_mov_b32_dpp v144, v156 row_ror:1 row_mask:0xf bank_mask:0xf
	v_mov_b32_e32 v156, 0
	v_pk_fma_f32 v[150:151], v[110:111], v[154:155], v[150:151]
	v_rcp_f32_e32 v152, v152
	v_mov_b32_dpp v156, v157 row_ror:15 row_mask:0xf bank_mask:0xf
	v_cndmask_b32_e64 v157, v129, v145, s[44:45]
	v_mov_b32_e32 v145, 0
	v_pk_add_f32 v[150:151], v[114:115], v[150:151]
	v_rcp_f32_e32 v153, v153
	v_mov_b32_dpp v145, v157 row_ror:1 row_mask:0xf bank_mask:0xf
	v_mul_f32_e32 v154, 0xbfb8aa3b, v150
	v_mul_f32_e32 v155, 0xbfb8aa3b, v151
	v_mov_b32_e32 v157, 0
	v_pk_mul_f32 v[144:145], v[80:81], v[144:145]
	v_exp_f32_e32 v154, v154
	v_exp_f32_e32 v155, v155
	v_mov_b32_dpp v157, v158 row_ror:15 row_mask:0xf bank_mask:0xf
	v_pk_fma_f32 v[144:145], v[128:129], v[84:85], v[144:145]
	v_cndmask_b32_e64 v158, v130, v146, s[44:45]
	v_mov_b32_e32 v146, 0
	v_pk_fma_f32 v[144:145], v[88:89], v[156:157], v[144:145]
	v_pk_mul_f32 v[140:141], v[140:141], v[148:149]
	v_mov_b32_dpp v146, v158 row_ror:1 row_mask:0xf bank_mask:0xf
	v_mov_b32_e32 v158, 0
	v_pk_add_f32 v[144:145], v[92:93], v[144:145]
	v_pk_mul_f32 v[140:141], v[140:141], v[152:153]
	v_mov_b32_dpp v158, v159 row_ror:15 row_mask:0xf bank_mask:0xf
	v_cndmask_b32_e64 v159, v131, v147, s[44:45]
	v_mov_b32_e32 v147, 0
	v_pk_mul_f32 v[142:143], v[142:143], v[150:151]
	v_add_f32_e32 v150, 1.0, v154
	v_add_f32_e32 v151, 1.0, v155
	v_cvt_pk_bf16_f32 v140, v140, v141
	v_mul_f32_e32 v141, 0xbfb8aa3b, v144
	v_mov_b32_dpp v147, v159 row_ror:1 row_mask:0xf bank_mask:0xf
	v_rcp_f32_e32 v150, v150
	v_rcp_f32_e32 v151, v151
	v_exp_f32_e32 v148, v141
	v_mul_f32_e32 v141, 0xbfb8aa3b, v145
	v_mov_b32_e32 v159, 0
	v_pk_mul_f32 v[146:147], v[82:83], v[146:147]
	v_exp_f32_e32 v149, v141
	v_mov_b32_dpp v159, v160 row_ror:15 row_mask:0xf bank_mask:0xf
	v_pk_fma_f32 v[146:147], v[130:131], v[86:87], v[146:147]
	v_pk_mul_f32 v[142:143], v[142:143], v[150:151]
	v_pk_fma_f32 v[146:147], v[90:91], v[158:159], v[146:147]
	v_cvt_pk_bf16_f32 v141, v142, v143
	v_pk_add_f32 v[146:147], v[94:95], v[146:147]
	v_add_f32_e32 v142, 1.0, v148
	v_add_f32_e32 v143, 1.0, v149
	v_mul_f32_e32 v148, 0xbfb8aa3b, v146
	v_mul_f32_e32 v149, 0xbfb8aa3b, v147
	v_exp_f32_e32 v148, v148
	v_exp_f32_e32 v149, v149
	v_rcp_f32_e32 v142, v142
	v_rcp_f32_e32 v143, v143
	v_pk_mul_f32 v[134:135], v[134:135], v[146:147]
	v_add_f32_e32 v146, 1.0, v148
	v_add_f32_e32 v147, 1.0, v149
	v_rcp_f32_e32 v146, v146
	v_rcp_f32_e32 v147, v147
	v_pk_mul_f32 v[132:133], v[132:133], v[144:145]
	v_add_u32_e32 v160, 16, v193
	v_pk_mul_f32 v[132:133], v[132:133], v[142:143]
	v_cndmask_b32_e32 v148, v107, v75, vcc
	v_cvt_pk_bf16_f32 v142, v132, v133
	v_pk_mul_f32 v[132:133], v[134:135], v[146:147]
	v_mov_b64_e32 v[134:135], s[6:7]
	v_cvt_pk_bf16_f32 v143, v132, v133
	v_mad_i64_i32 v[144:145], s[28:29], v160, s30, v[134:135]
	v_lshlrev_b64 v[132:133], 1, v[184:185]
	v_lshl_add_u64 v[144:145], v[144:145], 0, v[132:133]
	global_store_dwordx4 v[144:145], v[140:143], off
	v_cndmask_b32_e32 v144, v123, v79, vcc
	v_cndmask_b32_e32 v145, v104, v72, vcc
	v_cndmask_b32_e64 v140, v120, v136, s[44:45]
	v_mov_b32_e32 v136, 0
	v_cndmask_b32_e32 v141, v120, v76, vcc
	v_cndmask_b32_e32 v142, v121, v77, vcc
	v_mov_b32_dpp v136, v140 row_ror:1 row_mask:0xf bank_mask:0xf
	v_mov_b32_e32 v140, 0
	v_cndmask_b32_e32 v143, v122, v78, vcc
	v_cndmask_b32_e32 v146, v105, v73, vcc
	v_mov_b32_dpp v140, v141 row_ror:15 row_mask:0xf bank_mask:0xf
	v_cndmask_b32_e64 v141, v121, v137, s[44:45]
	v_mov_b32_e32 v137, 0
	v_cndmask_b32_e32 v147, v106, v74, vcc
	s_nop 0
	v_mov_b32_dpp v137, v141 row_ror:1 row_mask:0xf bank_mask:0xf
	v_mov_b32_e32 v141, 0
	v_pk_mul_f32 v[136:137], v[96:97], v[136:137]
	s_nop 0
	v_mov_b32_dpp v141, v142 row_ror:15 row_mask:0xf bank_mask:0xf
	v_pk_fma_f32 v[136:137], v[120:121], v[100:101], v[136:137]
	v_cndmask_b32_e64 v142, v122, v138, s[44:45]
	v_mov_b32_e32 v138, 0
	v_pk_fma_f32 v[136:137], v[108:109], v[140:141], v[136:137]
	s_nop 0
	v_mov_b32_dpp v138, v142 row_ror:1 row_mask:0xf bank_mask:0xf
	v_mov_b32_e32 v142, 0
	v_pk_add_f32 v[136:137], v[112:113], v[136:137]
	s_nop 0
	v_mov_b32_dpp v142, v143 row_ror:15 row_mask:0xf bank_mask:0xf
	v_cndmask_b32_e64 v143, v123, v139, s[44:45]
	v_mov_b32_e32 v139, 0
	v_mul_f32_e32 v140, 0xbfb8aa3b, v136
	v_mul_f32_e32 v141, 0xbfb8aa3b, v137
	v_mov_b32_dpp v139, v143 row_ror:1 row_mask:0xf bank_mask:0xf
	v_exp_f32_e32 v140, v140
	v_exp_f32_e32 v141, v141
	v_mov_b32_e32 v143, 0
	v_pk_mul_f32 v[138:139], v[98:99], v[138:139]
	v_add_f32_e32 v140, 1.0, v140
	v_mov_b32_dpp v143, v144 row_ror:15 row_mask:0xf bank_mask:0xf
	v_cndmask_b32_e64 v144, v104, v128, s[44:45]
	v_mov_b32_e32 v128, 0
	v_pk_fma_f32 v[138:139], v[122:123], v[102:103], v[138:139]
	v_add_f32_e32 v141, 1.0, v141
	v_mov_b32_dpp v128, v144 row_ror:1 row_mask:0xf bank_mask:0xf
	v_mov_b32_e32 v144, 0
	v_pk_fma_f32 v[138:139], v[110:111], v[142:143], v[138:139]
	v_rcp_f32_e32 v140, v140
	v_mov_b32_dpp v144, v145 row_ror:15 row_mask:0xf bank_mask:0xf
	v_cndmask_b32_e64 v145, v105, v129, s[44:45]
	v_mov_b32_e32 v129, 0
	v_pk_add_f32 v[138:139], v[114:115], v[138:139]
	v_rcp_f32_e32 v141, v141
	v_mov_b32_dpp v129, v145 row_ror:1 row_mask:0xf bank_mask:0xf
	v_mul_f32_e32 v142, 0xbfb8aa3b, v138
	v_mul_f32_e32 v143, 0xbfb8aa3b, v139
	v_mov_b32_e32 v145, 0
	v_pk_mul_f32 v[128:129], v[80:81], v[128:129]
	v_exp_f32_e32 v142, v142
	v_exp_f32_e32 v143, v143
; DI unsigned pack2(float a, float b) { f32x2 v = {a, b}; hwbf16x2 r = __builtin_convertvector(v, hwbf16x2); return __builtin_bit_cast(unsigned, r); }
; DI float dpp_ror1(float v)  { return __builtin_bit_cast(float, __builtin_amdgcn_update_dpp(0, __builtin_bit_cast(int, v), 0x121, 0xf, 0xf, false)); }
; DI float dpp_ror15(float v) { return __builtin_bit_cast(float, __builtin_amdgcn_update_dpp(0, __builtin_bit_cast(int, v), 0x12F, 0xf, 0xf, false)); }
; DI float silu_mul(float g, float v) { return g * v * __builtin_amdgcn_rcpf(1.0f + __builtin_amdgcn_exp2f(-LOG2E * g)); }
;     DI void operator()(const f32x4 (&acc)[2][2][4][2], const Unit& u, int wr, int wc, int fr, int fq) const {
;     ...
;                 for (int n = 0; n < 2; ++n) {
;                     const f32x4 g = acc[ai][0][m][n];
;                     const f32x4 gprev = acc[ai][0][m > 0 ? m - 1 : 0][n], gnext = acc[ai][0][m < 3 ? m + 1 : 3][n];
;                     f32x4 up, dn;
; #pragma unroll
;                     for (int e = 0; e < 4; ++e) {
;                         const float pu = (m > 0 && fr == 15) ? gprev[e] : g[e];
;                         const float pd = (m < 3 && fr == 0) ? gnext[e] : g[e];
;                         up[e] = dpp_ror1(pu); dn[e] = dpp_ror15(pd);
;                     }
;                     if (efirst) up = (f32x4){0.f, 0.f, 0.f, 0.f};
;                     if (elast) dn = (f32x4){0.f, 0.f, 0.f, 0.f};
;                     gc[n] = w0[n] * up + w1[n] * g + w2[n] * dn + bb[n];
;                 }
;                 if (efirst || elast) {
;                     const size_t eo = (size_t)((row >> 6) * 2 + (elast ? 1 : 0)) * DFF + ch0;
; #pragma unroll
;                     for (int n = 0; n < 2; ++n) { *(f32x4*)(EP + eo + 4 * n) = gc[n]; *(f32x4*)(ER + eo + 4 * n) = acc[ai][0][m][n]; *(f32x4*)(EV + eo + 4 * n) = acc[ai][1][m][n]; }
;                 } else {
;                     const f32x4 v0 = acc[ai][1][m][0], v1 = acc[ai][1][m][1];
;                     u32x4 o;
;                     o[0] = pack2(silu_mul(gc[0][0], v0[0]), silu_mul(gc[0][1], v0[1])); o[1] = pack2(silu_mul(gc[0][2], v0[2]), silu_mul(gc[0][3], v0[3]));
;                     o[2] = pack2(silu_mul(gc[1][0], v1[0]), silu_mul(gc[1][1], v1[1])); o[3] = pack2(silu_mul(gc[1][2], v1[2]), silu_mul(gc[1][3], v1[3]));
;                     *(u32x4*)(ACT + (size_t)row * DFF + ch0) = o;
;                 }
	v_mov_b32_dpp v145, v146 row_ror:15 row_mask:0xf bank_mask:0xf
	v_pk_fma_f32 v[128:129], v[104:105], v[84:85], v[128:129]
	v_cndmask_b32_e64 v146, v106, v130, s[44:45]
	v_mov_b32_e32 v130, 0
	v_pk_fma_f32 v[128:129], v[88:89], v[144:145], v[128:129]
	v_pk_mul_f32 v[124:125], v[124:125], v[136:137]
	v_mov_b32_dpp v130, v146 row_ror:1 row_mask:0xf bank_mask:0xf
	v_mov_b32_e32 v146, 0
	v_pk_add_f32 v[128:129], v[92:93], v[128:129]
	v_pk_mul_f32 v[124:125], v[124:125], v[140:141]
	v_mov_b32_dpp v146, v147 row_ror:15 row_mask:0xf bank_mask:0xf
	v_cndmask_b32_e64 v147, v107, v131, s[44:45]
	v_mov_b32_e32 v131, 0
	v_pk_mul_f32 v[126:127], v[126:127], v[138:139]
	v_add_f32_e32 v138, 1.0, v142
	v_add_f32_e32 v139, 1.0, v143
	v_cvt_pk_bf16_f32 v124, v124, v125
	v_mul_f32_e32 v125, 0xbfb8aa3b, v128
	v_mov_b32_dpp v131, v147 row_ror:1 row_mask:0xf bank_mask:0xf
	v_rcp_f32_e32 v138, v138
	v_rcp_f32_e32 v139, v139
	v_exp_f32_e32 v136, v125
	v_mul_f32_e32 v125, 0xbfb8aa3b, v129
	v_mov_b32_e32 v147, 0
	v_pk_mul_f32 v[130:131], v[82:83], v[130:131]
	v_exp_f32_e32 v137, v125
	v_mov_b32_dpp v147, v148 row_ror:15 row_mask:0xf bank_mask:0xf
	v_pk_fma_f32 v[130:131], v[106:107], v[86:87], v[130:131]
	v_pk_mul_f32 v[126:127], v[126:127], v[138:139]
	v_pk_fma_f32 v[130:131], v[90:91], v[146:147], v[130:131]
	v_cvt_pk_bf16_f32 v125, v126, v127
	v_pk_add_f32 v[130:131], v[94:95], v[130:131]
	v_add_f32_e32 v126, 1.0, v136
	v_add_f32_e32 v127, 1.0, v137
	v_mul_f32_e32 v136, 0xbfb8aa3b, v130
	v_mul_f32_e32 v137, 0xbfb8aa3b, v131
	v_exp_f32_e32 v136, v136
	v_exp_f32_e32 v137, v137
	v_rcp_f32_e32 v126, v126
	v_rcp_f32_e32 v127, v127
	v_pk_mul_f32 v[118:119], v[118:119], v[130:131]
	v_add_f32_e32 v130, 1.0, v136
	v_add_f32_e32 v131, 1.0, v137
	v_rcp_f32_e32 v130, v130
	v_rcp_f32_e32 v131, v131
	v_pk_mul_f32 v[116:117], v[116:117], v[128:129]
	v_add_u32_e32 v148, 32, v193
	v_pk_mul_f32 v[116:117], v[116:117], v[126:127]
	s_nop 0
	v_cvt_pk_bf16_f32 v126, v116, v117
	v_pk_mul_f32 v[116:117], v[118:119], v[130:131]
	v_cndmask_b32_e64 v118, v77, v121, s[44:45]
	v_cvt_pk_bf16_f32 v127, v116, v117
	v_mad_i64_i32 v[116:117], s[28:29], v148, s30, v[134:135]
	v_lshl_add_u64 v[116:117], v[116:117], 0, v[132:133]
	global_store_dwordx4 v[116:117], v[124:127], off
	v_cndmask_b32_e64 v117, v76, v120, s[44:45]
	v_mov_b32_e32 v116, 0
	v_cndmask_b32_e64 v119, v78, v122, s[44:45]
	v_cndmask_b32_e64 v121, v79, v123, s[44:45]
	v_mov_b32_dpp v116, v117 row_ror:1 row_mask:0xf bank_mask:0xf
	v_mov_b32_e32 v117, 0
	v_mov_b32_e32 v120, 0
	v_mov_b32_e32 v124, 0
	v_mov_b32_dpp v117, v118 row_ror:1 row_mask:0xf bank_mask:0xf
	v_mov_b32_e32 v118, 0
	v_mov_b32_dpp v120, v78 row_ror:15 row_mask:0xf bank_mask:0xf
	v_cndmask_b32_e64 v120, v120, 0, s[44:45]
	v_mov_b32_dpp v118, v119 row_ror:1 row_mask:0xf bank_mask:0xf
	v_mov_b32_e32 v119, 0
	v_mov_b32_e32 v125, 0
	v_mov_b32_dpp v124, v76 row_ror:15 row_mask:0xf bank_mask:0xf
	v_mov_b32_dpp v119, v121 row_ror:1 row_mask:0xf bank_mask:0xf
	v_mov_b32_e32 v121, 0
	v_pk_mul_f32 v[118:119], v[98:99], v[118:119]
	v_mov_b32_dpp v125, v77 row_ror:15 row_mask:0xf bank_mask:0xf
	v_mov_b32_dpp v121, v79 row_ror:15 row_mask:0xf bank_mask:0xf
	v_cndmask_b32_e64 v121, v121, 0, s[44:45]
	v_pk_fma_f32 v[118:119], v[78:79], v[102:103], v[118:119]
	v_pk_mul_f32 v[116:117], v[96:97], v[116:117]
	v_pk_fma_f32 v[118:119], v[110:111], v[120:121], v[118:119]
	v_cndmask_b32_e64 v120, v72, v104, s[44:45]
	v_mov_b32_e32 v104, 0
	v_cndmask_b32_e64 v123, v125, 0, s[44:45]
	v_cndmask_b32_e64 v122, v124, 0, s[44:45]
	v_mov_b32_dpp v104, v120 row_ror:1 row_mask:0xf bank_mask:0xf
	v_cndmask_b32_e64 v120, v73, v105, s[44:45]
	v_mov_b32_e32 v105, 0
	v_pk_fma_f32 v[116:117], v[76:77], v[100:101], v[116:117]
	v_cndmask_b32_e64 v121, v75, v107, s[44:45]
	v_mov_b32_dpp v105, v120 row_ror:1 row_mask:0xf bank_mask:0xf
	v_cndmask_b32_e64 v120, v74, v106, s[44:45]
	v_mov_b32_e32 v106, 0
	v_mov_b32_e32 v107, 0
	v_pk_fma_f32 v[116:117], v[108:109], v[122:123], v[116:117]
	v_mov_b32_e32 v122, 0
	v_mov_b32_e32 v123, 0
	v_mov_b32_dpp v106, v120 row_ror:1 row_mask:0xf bank_mask:0xf
	v_mov_b32_e32 v120, 0
	v_mov_b32_dpp v107, v121 row_ror:1 row_mask:0xf bank_mask:0xf
	v_mov_b32_e32 v121, 0
	v_mov_b32_dpp v122, v72 row_ror:15 row_mask:0xf bank_mask:0xf
	v_mov_b32_dpp v123, v73 row_ror:15 row_mask:0xf bank_mask:0xf
	v_mov_b32_dpp v120, v74 row_ror:15 row_mask:0xf bank_mask:0xf
	v_mov_b32_dpp v121, v75 row_ror:15 row_mask:0xf bank_mask:0xf
	v_pk_mul_f32 v[104:105], v[80:81], v[104:105]
	v_pk_mul_f32 v[106:107], v[82:83], v[106:107]
	v_cndmask_b32_e64 v121, v121, 0, s[44:45]
	v_cndmask_b32_e64 v120, v120, 0, s[44:45]
	v_cndmask_b32_e64 v123, v123, 0, s[44:45]
	v_cndmask_b32_e64 v122, v122, 0, s[44:45]
	v_pk_fma_f32 v[106:107], v[74:75], v[86:87], v[106:107]
	v_pk_fma_f32 v[104:105], v[72:73], v[84:85], v[104:105]
	v_pk_fma_f32 v[106:107], v[90:91], v[120:121], v[106:107]
	v_pk_fma_f32 v[104:105], v[88:89], v[122:123], v[104:105]
	v_pk_add_f32 v[118:119], v[114:115], v[118:119]
	v_pk_add_f32 v[116:117], v[112:113], v[116:117]
	v_pk_add_f32 v[106:107], v[94:95], v[106:107]
	v_pk_add_f32 v[104:105], v[92:93], v[104:105]
	v_add_u32_e32 v120, 48, v193
	s_and_saveexec_b64 s[28:29], s[42:43]
	s_xor_b64 s[28:29], exec, s[28:29]
	s_cbranch_execz .LBB1_387
	v_mul_f32_e32 v121, 0xbfb8aa3b, v116
	v_exp_f32_e32 v121, v121
	v_mul_f32_e32 v122, 0xbfb8aa3b, v117
	v_exp_f32_e32 v122, v122
	v_mul_f32_e32 v124, 0xbfb8aa3b, v119
	v_add_f32_e32 v121, 1.0, v121
	v_exp_f32_e32 v125, v124
	v_add_f32_e32 v123, 1.0, v122
	v_rcp_f32_e32 v122, v121
	v_mul_f32_e32 v121, 0xbfb8aa3b, v118
	v_exp_f32_e32 v121, v121
	v_rcp_f32_e32 v123, v123
	v_pk_mul_f32 v[116:117], v[68:69], v[116:117]
	v_pk_mul_f32 v[118:119], v[70:71], v[118:119]
	v_add_f32_e32 v121, 1.0, v121
	v_rcp_f32_e32 v124, v121
	v_add_f32_e32 v121, 1.0, v125
	v_pk_mul_f32 v[116:117], v[116:117], v[122:123]
	v_rcp_f32_e32 v125, v121
	v_cvt_pk_bf16_f32 v116, v116, v117
	v_mul_f32_e32 v117, 0xbfb8aa3b, v104
	v_exp_f32_e32 v121, v117
	v_mul_f32_e32 v117, 0xbfb8aa3b, v105
	v_exp_f32_e32 v122, v117
	v_pk_mul_f32 v[118:119], v[118:119], v[124:125]
	v_pk_mul_f32 v[104:105], v[64:65], v[104:105]
	v_cvt_pk_bf16_f32 v117, v118, v119
	v_add_f32_e32 v118, 1.0, v121
	v_mul_f32_e32 v121, 0xbfb8aa3b, v106
	v_add_f32_e32 v119, 1.0, v122
	v_exp_f32_e32 v121, v121
	v_mul_f32_e32 v122, 0xbfb8aa3b, v107
	v_exp_f32_e32 v123, v122
	v_rcp_f32_e32 v118, v118
	v_add_f32_e32 v121, 1.0, v121
	v_rcp_f32_e32 v119, v119
	v_rcp_f32_e32 v122, v121
	v_add_f32_e32 v121, 1.0, v123
	v_rcp_f32_e32 v123, v121
	v_pk_mul_f32 v[106:107], v[66:67], v[106:107]
	v_pk_mul_f32 v[104:105], v[104:105], v[118:119]
	s_nop 0
	v_cvt_pk_bf16_f32 v118, v104, v105
	v_pk_mul_f32 v[104:105], v[106:107], v[122:123]
	s_nop 0
	v_cvt_pk_bf16_f32 v119, v104, v105
	v_mov_b64_e32 v[104:105], s[6:7]
	v_mad_i64_i32 v[104:105], s[58:59], v120, s30, v[104:105]
	v_lshl_add_u64 v[104:105], v[184:185], 1, v[104:105]
	global_store_dwordx4 v[104:105], v[116:119], off
; DI unsigned pack2(float a, float b) { f32x2 v = {a, b}; hwbf16x2 r = __builtin_convertvector(v, hwbf16x2); return __builtin_bit_cast(unsigned, r); }
; DI float dpp_ror1(float v)  { return __builtin_bit_cast(float, __builtin_amdgcn_update_dpp(0, __builtin_bit_cast(int, v), 0x121, 0xf, 0xf, false)); }
; DI float dpp_ror15(float v) { return __builtin_bit_cast(float, __builtin_amdgcn_update_dpp(0, __builtin_bit_cast(int, v), 0x12F, 0xf, 0xf, false)); }
; DI float silu_mul(float g, float v) { return g * v * __builtin_amdgcn_rcpf(1.0f + __builtin_amdgcn_exp2f(-LOG2E * g)); }
;     DI void operator()(const f32x4 (&acc)[2][2][4][2], const Unit& u, int wr, int wc, int fr, int fq) const {
;     ...
;                 for (int n = 0; n < 2; ++n) {
;                     const f32x4 g = acc[ai][0][m][n];
;                     const f32x4 gprev = acc[ai][0][m > 0 ? m - 1 : 0][n], gnext = acc[ai][0][m < 3 ? m + 1 : 3][n];
;                     f32x4 up, dn;
; #pragma unroll
;                     for (int e = 0; e < 4; ++e) {
;                         const float pu = (m > 0 && fr == 15) ? gprev[e] : g[e];
;                         const float pd = (m < 3 && fr == 0) ? gnext[e] : g[e];
;                         up[e] = dpp_ror1(pu); dn[e] = dpp_ror15(pd);
;                     }
;                     if (efirst) up = (f32x4){0.f, 0.f, 0.f, 0.f};
;                     if (elast) dn = (f32x4){0.f, 0.f, 0.f, 0.f};
;                     gc[n] = w0[n] * up + w1[n] * g + w2[n] * dn + bb[n];
;     ...
;                 if (efirst || elast) {
;                     const size_t eo = (size_t)((row >> 6) * 2 + (elast ? 1 : 0)) * DFF + ch0;
; #pragma unroll
;                     for (int n = 0; n < 2; ++n) { *(f32x4*)(EP + eo + 4 * n) = gc[n]; *(f32x4*)(ER + eo + 4 * n) = acc[ai][0][m][n]; *(f32x4*)(EV + eo + 4 * n) = acc[ai][1][m][n]; }
;                 } else {
;                     const f32x4 v0 = acc[ai][1][m][0], v1 = acc[ai][1][m][1];
;                     u32x4 o;
;                     o[0] = pack2(silu_mul(gc[0][0], v0[0]), silu_mul(gc[0][1], v0[1])); o[1] = pack2(silu_mul(gc[0][2], v0[2]), silu_mul(gc[0][3], v0[3]));
;                     o[2] = pack2(silu_mul(gc[1][0], v1[0]), silu_mul(gc[1][1], v1[1])); o[3] = pack2(silu_mul(gc[1][2], v1[2]), silu_mul(gc[1][3], v1[3]));
;                     *(u32x4*)(ACT + (size_t)row * DFF + ch0) = o;
;                 }
.LBB1_387:
	s_or_saveexec_b64 s[28:29], s[28:29]
	s_mov_b64 s[68:69], s[72:73]
	s_xor_b64 exec, exec, s[28:29]
	s_cbranch_execz .LBB1_389
	v_ashrrev_i32_e32 v120, 5, v120
	v_mad_i64_i32 v[120:121], s[58:59], v120, s60, v[184:185]
	v_lshlrev_b64 v[120:121], 2, v[120:121]
	v_lshl_add_u64 v[122:123], s[8:9], 0, v[120:121]
	global_store_dwordx4 v[122:123], v[116:119], off
	s_nop 1
	v_lshl_add_u64 v[116:117], s[10:11], 0, v[120:121]
	global_store_dwordx4 v[116:117], v[76:79], off
	s_nop 1
	v_lshl_add_u64 v[76:77], s[12:13], 0, v[120:121]
	global_store_dwordx4 v[76:77], v[68:71], off
	global_store_dwordx4 v[122:123], v[104:107], off offset:16
	global_store_dwordx4 v[116:117], v[72:75], off offset:16
	global_store_dwordx4 v[76:77], v[64:67], off offset:16
.LBB1_389:
	s_or_b64 exec, exec, s[28:29]
	s_nop 0
	v_cndmask_b32_e32 v65, v60, v40, vcc
	v_mov_b32_e32 v64, 0
	v_cndmask_b32_e32 v66, v61, v41, vcc
	v_cndmask_b32_e32 v67, v62, v42, vcc
	v_mov_b32_dpp v64, v65 row_ror:15 row_mask:0xf bank_mask:0xf
	v_mov_b32_e32 v65, 0
	v_mov_b32_e32 v68, 0
	v_mov_b32_e32 v73, 0
	v_mov_b32_dpp v65, v66 row_ror:15 row_mask:0xf bank_mask:0xf
	v_mov_b32_e32 v66, 0
	v_mov_b32_e32 v70, 0
	v_mov_b32_e32 v71, 0
	v_mov_b32_dpp v68, v62 row_ror:1 row_mask:0xf bank_mask:0xf
	v_mov_b32_dpp v66, v67 row_ror:15 row_mask:0xf bank_mask:0xf
	v_cndmask_b32_e32 v69, v63, v43, vcc
	v_mov_b32_dpp v73, v63 row_ror:1 row_mask:0xf bank_mask:0xf
	v_mov_b32_e32 v67, 0
	v_mov_b32_dpp v70, v60 row_ror:1 row_mask:0xf bank_mask:0xf
	v_mov_b32_dpp v71, v61 row_ror:1 row_mask:0xf bank_mask:0xf
	v_mov_b32_dpp v67, v69 row_ror:15 row_mask:0xf bank_mask:0xf
	v_cndmask_b32_e64 v69, v73, 0, vcc
	v_cndmask_b32_e64 v68, v68, 0, vcc
	v_cndmask_b32_e64 v71, v71, 0, vcc
	v_cndmask_b32_e64 v70, v70, 0, vcc
	v_pk_mul_f32 v[68:69], v[98:99], v[68:69]
	v_pk_mul_f32 v[70:71], v[96:97], v[70:71]
	v_pk_fma_f32 v[68:69], v[62:63], v[102:103], v[68:69]
	v_pk_fma_f32 v[70:71], v[60:61], v[100:101], v[70:71]
	v_pk_fma_f32 v[66:67], v[110:111], v[66:67], v[68:69]
	v_cndmask_b32_e32 v69, v48, v32, vcc
	v_mov_b32_e32 v68, 0
	v_pk_fma_f32 v[64:65], v[108:109], v[64:65], v[70:71]
	v_cndmask_b32_e32 v70, v49, v33, vcc
	v_mov_b32_dpp v68, v69 row_ror:15 row_mask:0xf bank_mask:0xf
	v_mov_b32_e32 v69, 0
	v_mov_b32_e32 v73, 0
	v_mov_b32_e32 v76, 0
	v_mov_b32_dpp v69, v70 row_ror:15 row_mask:0xf bank_mask:0xf
	v_cndmask_b32_e32 v71, v50, v34, vcc
	v_mov_b32_e32 v74, 0
	v_mov_b32_e32 v70, 0
	v_mov_b32_e32 v77, 0
	v_mov_b32_dpp v73, v48 row_ror:1 row_mask:0xf bank_mask:0xf
	v_mov_b32_dpp v76, v49 row_ror:1 row_mask:0xf bank_mask:0xf
	v_mov_b32_dpp v74, v50 row_ror:1 row_mask:0xf bank_mask:0xf
	v_mov_b32_dpp v70, v71 row_ror:15 row_mask:0xf bank_mask:0xf
	v_cndmask_b32_e32 v75, v51, v35, vcc
	v_mov_b32_dpp v77, v51 row_ror:1 row_mask:0xf bank_mask:0xf
	v_mov_b32_e32 v71, 0
	v_cndmask_b32_e64 v74, v74, 0, vcc
	v_add_u32_e32 v72, 0x80, v193
	v_mov_b32_dpp v71, v75 row_ror:15 row_mask:0xf bank_mask:0xf
	v_cndmask_b32_e64 v75, v77, 0, vcc
	v_cndmask_b32_e64 v77, v76, 0, vcc
	v_cndmask_b32_e64 v76, v73, 0, vcc
	v_pk_mul_f32 v[76:77], v[80:81], v[76:77]
	v_pk_mul_f32 v[74:75], v[82:83], v[74:75]
	v_pk_fma_f32 v[76:77], v[48:49], v[84:85], v[76:77]
	v_pk_fma_f32 v[74:75], v[50:51], v[86:87], v[74:75]
	v_pk_fma_f32 v[68:69], v[88:89], v[68:69], v[76:77]
	v_pk_fma_f32 v[70:71], v[90:91], v[70:71], v[74:75]
	v_pk_add_f32 v[66:67], v[114:115], v[66:67]
	v_pk_add_f32 v[64:65], v[112:113], v[64:65]
	v_pk_add_f32 v[70:71], v[94:95], v[70:71]
	v_pk_add_f32 v[68:69], v[92:93], v[68:69]
	s_and_saveexec_b64 s[28:29], s[46:47]
	s_xor_b64 s[28:29], exec, s[28:29]
	s_cbranch_execz .LBB1_391
	v_mul_f32_e32 v73, 0xbfb8aa3b, v64
	v_exp_f32_e32 v73, v73
	v_mul_f32_e32 v74, 0xbfb8aa3b, v65
	v_exp_f32_e32 v74, v74
	v_mul_f32_e32 v76, 0xbfb8aa3b, v67
	v_add_f32_e32 v73, 1.0, v73
	v_exp_f32_e32 v77, v76
	v_add_f32_e32 v75, 1.0, v74
	v_rcp_f32_e32 v74, v73
	v_mul_f32_e32 v73, 0xbfb8aa3b, v66
	v_exp_f32_e32 v73, v73
	v_rcp_f32_e32 v75, v75
	v_pk_mul_f32 v[64:65], v[56:57], v[64:65]
	v_pk_mul_f32 v[66:67], v[58:59], v[66:67]
	v_add_f32_e32 v73, 1.0, v73
	v_rcp_f32_e32 v76, v73
	v_add_f32_e32 v73, 1.0, v77
	v_pk_mul_f32 v[64:65], v[64:65], v[74:75]
	v_rcp_f32_e32 v77, v73
	v_cvt_pk_bf16_f32 v64, v64, v65
	v_mul_f32_e32 v65, 0xbfb8aa3b, v68
	v_exp_f32_e32 v73, v65
	v_mul_f32_e32 v65, 0xbfb8aa3b, v69
	v_exp_f32_e32 v74, v65
	v_pk_mul_f32 v[66:67], v[66:67], v[76:77]
	v_pk_mul_f32 v[68:69], v[52:53], v[68:69]
	v_cvt_pk_bf16_f32 v65, v66, v67
	v_add_f32_e32 v66, 1.0, v73
	v_mul_f32_e32 v73, 0xbfb8aa3b, v70
	v_add_f32_e32 v67, 1.0, v74
	v_exp_f32_e32 v73, v73
	v_mul_f32_e32 v74, 0xbfb8aa3b, v71
	v_exp_f32_e32 v75, v74
	v_rcp_f32_e32 v66, v66
	v_add_f32_e32 v73, 1.0, v73
	v_rcp_f32_e32 v74, v73
	v_add_f32_e32 v73, 1.0, v75
	v_rcp_f32_e32 v67, v67
	v_rcp_f32_e32 v75, v73
	v_pk_mul_f32 v[70:71], v[54:55], v[70:71]
	v_pk_mul_f32 v[66:67], v[68:69], v[66:67]
	v_pk_mul_f32 v[68:69], v[70:71], v[74:75]
	v_cvt_pk_bf16_f32 v66, v66, v67
	v_cvt_pk_bf16_f32 v67, v68, v69
	v_mov_b64_e32 v[68:69], s[6:7]
	v_mad_i64_i32 v[68:69], s[46:47], v72, s30, v[68:69]
	v_lshl_add_u64 v[68:69], v[184:185], 1, v[68:69]
	global_store_dwordx4 v[68:69], v[64:67], off
.LBB1_391:
	s_andn2_saveexec_b64 s[28:29], s[28:29]
	s_cbranch_execz .LBB1_393
	v_ashrrev_i32_e32 v72, 5, v72
	v_mad_i64_i32 v[72:73], s[46:47], v72, s60, v[184:185]
	v_lshlrev_b64 v[72:73], 2, v[72:73]
	v_lshl_add_u64 v[74:75], s[8:9], 0, v[72:73]
	global_store_dwordx4 v[74:75], v[64:67], off
	s_nop 1
	v_lshl_add_u64 v[64:65], s[10:11], 0, v[72:73]
	v_lshl_add_u64 v[66:67], s[12:13], 0, v[72:73]
	global_store_dwordx4 v[64:65], v[60:63], off
	global_store_dwordx4 v[66:67], v[56:59], off
	global_store_dwordx4 v[74:75], v[68:71], off offset:16
	global_store_dwordx4 v[64:65], v[48:51], off offset:16
	global_store_dwordx4 v[66:67], v[52:55], off offset:16
; DI unsigned pack2(float a, float b) { f32x2 v = {a, b}; hwbf16x2 r = __builtin_convertvector(v, hwbf16x2); return __builtin_bit_cast(unsigned, r); }
; DI float dpp_ror1(float v)  { return __builtin_bit_cast(float, __builtin_amdgcn_update_dpp(0, __builtin_bit_cast(int, v), 0x121, 0xf, 0xf, false)); }
; DI float dpp_ror15(float v) { return __builtin_bit_cast(float, __builtin_amdgcn_update_dpp(0, __builtin_bit_cast(int, v), 0x12F, 0xf, 0xf, false)); }
; DI float silu_mul(float g, float v) { return g * v * __builtin_amdgcn_rcpf(1.0f + __builtin_amdgcn_exp2f(-LOG2E * g)); }
;     DI void operator()(const f32x4 (&acc)[2][2][4][2], const Unit& u, int wr, int wc, int fr, int fq) const {
;     ...
;                 for (int n = 0; n < 2; ++n) {
;                     const f32x4 g = acc[ai][0][m][n];
;                     const f32x4 gprev = acc[ai][0][m > 0 ? m - 1 : 0][n], gnext = acc[ai][0][m < 3 ? m + 1 : 3][n];
;                     f32x4 up, dn;
; #pragma unroll
;                     for (int e = 0; e < 4; ++e) {
;                         const float pu = (m > 0 && fr == 15) ? gprev[e] : g[e];
;                         const float pd = (m < 3 && fr == 0) ? gnext[e] : g[e];
;                         up[e] = dpp_ror1(pu); dn[e] = dpp_ror15(pd);
;                     }
;                     if (efirst) up = (f32x4){0.f, 0.f, 0.f, 0.f};
;                     if (elast) dn = (f32x4){0.f, 0.f, 0.f, 0.f};
;                     gc[n] = w0[n] * up + w1[n] * g + w2[n] * dn + bb[n];
;                 }
;                 if (efirst || elast) {
;                     const size_t eo = (size_t)((row >> 6) * 2 + (elast ? 1 : 0)) * DFF + ch0;
; #pragma unroll
;                     for (int n = 0; n < 2; ++n) { *(f32x4*)(EP + eo + 4 * n) = gc[n]; *(f32x4*)(ER + eo + 4 * n) = acc[ai][0][m][n]; *(f32x4*)(EV + eo + 4 * n) = acc[ai][1][m][n]; }
;                 } else {
;                     const f32x4 v0 = acc[ai][1][m][0], v1 = acc[ai][1][m][1];
;                     u32x4 o;
;                     o[0] = pack2(silu_mul(gc[0][0], v0[0]), silu_mul(gc[0][1], v0[1])); o[1] = pack2(silu_mul(gc[0][2], v0[2]), silu_mul(gc[0][3], v0[3]));
;                     o[2] = pack2(silu_mul(gc[1][0], v1[0]), silu_mul(gc[1][1], v1[1])); o[3] = pack2(silu_mul(gc[1][2], v1[2]), silu_mul(gc[1][3], v1[3]));
;                     *(u32x4*)(ACT + (size_t)row * DFF + ch0) = o;
;                 }
.LBB1_393:
	s_or_b64 exec, exec, s[28:29]
	s_nop 0
	v_cndmask_b32_e64 v53, v40, v60, s[44:45]
	v_cndmask_b32_e32 v55, v40, v24, vcc
	v_mov_b32_e32 v52, 0
	v_mov_b32_e32 v54, 0
	v_cndmask_b32_e32 v56, v41, v25, vcc
	v_mov_b32_dpp v52, v53 row_ror:1 row_mask:0xf bank_mask:0xf
	v_mov_b32_dpp v54, v55 row_ror:15 row_mask:0xf bank_mask:0xf
	v_cndmask_b32_e64 v55, v41, v61, s[44:45]
	v_mov_b32_e32 v53, 0
	v_cndmask_b32_e64 v57, v42, v62, s[44:45]
	v_cndmask_b32_e32 v59, v42, v26, vcc
	v_mov_b32_dpp v53, v55 row_ror:1 row_mask:0xf bank_mask:0xf
	v_mov_b32_e32 v55, 0
	v_mov_b32_e32 v58, 0
	v_pk_mul_f32 v[52:53], v[96:97], v[52:53]
	v_mov_b32_dpp v55, v56 row_ror:15 row_mask:0xf bank_mask:0xf
	v_mov_b32_e32 v56, 0
	v_mov_b32_dpp v58, v59 row_ror:15 row_mask:0xf bank_mask:0xf
	v_cndmask_b32_e64 v59, v43, v63, s[44:45]
	v_mov_b32_dpp v56, v57 row_ror:1 row_mask:0xf bank_mask:0xf
	v_mov_b32_e32 v57, 0
	v_pk_fma_f32 v[52:53], v[40:41], v[100:101], v[52:53]
	v_cndmask_b32_e32 v60, v43, v27, vcc
	v_mov_b32_dpp v57, v59 row_ror:1 row_mask:0xf bank_mask:0xf
	v_pk_fma_f32 v[52:53], v[108:109], v[54:55], v[52:53]
	v_mov_b32_e32 v59, 0
	v_pk_mul_f32 v[56:57], v[98:99], v[56:57]
	v_pk_add_f32 v[52:53], v[112:113], v[52:53]
	v_mov_b32_dpp v59, v60 row_ror:15 row_mask:0xf bank_mask:0xf
	v_pk_fma_f32 v[56:57], v[42:43], v[102:103], v[56:57]
	v_mul_f32_e32 v54, 0xbfb8aa3b, v52
	v_pk_fma_f32 v[56:57], v[110:111], v[58:59], v[56:57]
	v_exp_f32_e32 v58, v54
	v_mul_f32_e32 v54, 0xbfb8aa3b, v53
	v_exp_f32_e32 v59, v54
	v_cndmask_b32_e64 v60, v32, v48, s[44:45]
	v_mov_b32_e32 v48, 0
	v_cndmask_b32_e32 v61, v32, v16, vcc
	v_pk_add_f32 v[54:55], v[114:115], v[56:57]
	v_mov_b32_dpp v48, v60 row_ror:1 row_mask:0xf bank_mask:0xf
	v_mov_b32_e32 v60, 0
	v_add_f32_e32 v56, 1.0, v58
	v_add_f32_e32 v57, 1.0, v59
	v_mov_b32_dpp v60, v61 row_ror:15 row_mask:0xf bank_mask:0xf
	v_cndmask_b32_e64 v61, v33, v49, s[44:45]
	v_mov_b32_e32 v49, 0
	v_rcp_f32_e32 v56, v56
	v_rcp_f32_e32 v57, v57
	v_mov_b32_dpp v49, v61 row_ror:1 row_mask:0xf bank_mask:0xf
	v_mul_f32_e32 v58, 0xbfb8aa3b, v54
	v_mul_f32_e32 v59, 0xbfb8aa3b, v55
	v_cndmask_b32_e32 v62, v33, v17, vcc
	v_mov_b32_e32 v61, 0
	v_pk_mul_f32 v[48:49], v[80:81], v[48:49]
	v_exp_f32_e32 v58, v58
	v_exp_f32_e32 v59, v59
	v_mov_b32_dpp v61, v62 row_ror:15 row_mask:0xf bank_mask:0xf
	v_pk_fma_f32 v[48:49], v[32:33], v[84:85], v[48:49]
	v_cndmask_b32_e64 v62, v34, v50, s[44:45]
	v_mov_b32_e32 v50, 0
	v_pk_fma_f32 v[48:49], v[88:89], v[60:61], v[48:49]
	v_pk_mul_f32 v[44:45], v[44:45], v[52:53]
	v_cndmask_b32_e32 v63, v34, v18, vcc
	v_mov_b32_dpp v50, v62 row_ror:1 row_mask:0xf bank_mask:0xf
	v_mov_b32_e32 v62, 0
	v_pk_add_f32 v[48:49], v[92:93], v[48:49]
	v_pk_mul_f32 v[44:45], v[44:45], v[56:57]
	v_mov_b32_dpp v62, v63 row_ror:15 row_mask:0xf bank_mask:0xf
	v_cndmask_b32_e64 v63, v35, v51, s[44:45]
	v_mov_b32_e32 v51, 0
	v_pk_mul_f32 v[46:47], v[46:47], v[54:55]
	v_add_f32_e32 v54, 1.0, v58
	v_add_f32_e32 v55, 1.0, v59
	v_cvt_pk_bf16_f32 v44, v44, v45
	v_mul_f32_e32 v45, 0xbfb8aa3b, v48
	v_mov_b32_dpp v51, v63 row_ror:1 row_mask:0xf bank_mask:0xf
	v_rcp_f32_e32 v54, v54
	v_rcp_f32_e32 v55, v55
	v_exp_f32_e32 v52, v45
	v_mul_f32_e32 v45, 0xbfb8aa3b, v49
	v_cndmask_b32_e32 v64, v35, v19, vcc
	v_mov_b32_e32 v63, 0
	v_pk_mul_f32 v[50:51], v[82:83], v[50:51]
	v_exp_f32_e32 v53, v45
	v_mov_b32_dpp v63, v64 row_ror:15 row_mask:0xf bank_mask:0xf
	v_pk_fma_f32 v[50:51], v[34:35], v[86:87], v[50:51]
	v_pk_mul_f32 v[46:47], v[46:47], v[54:55]
	v_pk_fma_f32 v[50:51], v[90:91], v[62:63], v[50:51]
	v_cvt_pk_bf16_f32 v45, v46, v47
	v_pk_add_f32 v[50:51], v[94:95], v[50:51]
	v_add_f32_e32 v46, 1.0, v52
	v_add_f32_e32 v47, 1.0, v53
	v_mul_f32_e32 v52, 0xbfb8aa3b, v50
	v_mul_f32_e32 v53, 0xbfb8aa3b, v51
	v_exp_f32_e32 v52, v52
	v_exp_f32_e32 v53, v53
	v_rcp_f32_e32 v46, v46
	v_rcp_f32_e32 v47, v47
	v_pk_mul_f32 v[38:39], v[38:39], v[50:51]
	v_add_f32_e32 v50, 1.0, v52
	v_add_f32_e32 v51, 1.0, v53
	v_rcp_f32_e32 v50, v50
	v_rcp_f32_e32 v51, v51
	v_pk_mul_f32 v[36:37], v[36:37], v[48:49]
	v_add_u32_e32 v64, 0x90, v193
	v_pk_mul_f32 v[36:37], v[36:37], v[46:47]
	v_cndmask_b32_e64 v41, v25, v41, s[44:45]
	v_cvt_pk_bf16_f32 v46, v36, v37
	v_pk_mul_f32 v[36:37], v[38:39], v[50:51]
	v_cndmask_b32_e32 v48, v17, v9, vcc
	v_cvt_pk_bf16_f32 v47, v36, v37
	v_mov_b64_e32 v[36:37], s[6:7]
	v_mad_i64_i32 v[38:39], s[28:29], v64, s30, v[36:37]
	v_lshl_add_u64 v[38:39], v[38:39], 0, v[132:133]
	global_store_dwordx4 v[38:39], v[44:47], off
	v_cndmask_b32_e64 v39, v24, v40, s[44:45]
	v_mov_b32_e32 v38, 0
	v_cndmask_b32_e32 v44, v24, v12, vcc
	v_mov_b32_e32 v40, 0
	v_mov_b32_dpp v38, v39 row_ror:1 row_mask:0xf bank_mask:0xf
	v_mov_b32_e32 v39, 0
	v_mov_b32_dpp v40, v44 row_ror:15 row_mask:0xf bank_mask:0xf
	v_cndmask_b32_e32 v44, v25, v13, vcc
	v_mov_b32_dpp v39, v41 row_ror:1 row_mask:0xf bank_mask:0xf
	v_mov_b32_e32 v41, 0
	v_cndmask_b32_e32 v45, v26, v14, vcc
	v_pk_mul_f32 v[38:39], v[96:97], v[38:39]
	v_mov_b32_dpp v41, v44 row_ror:15 row_mask:0xf bank_mask:0xf
	v_cndmask_b32_e64 v44, v26, v42, s[44:45]
	v_mov_b32_e32 v42, 0
	v_pk_fma_f32 v[38:39], v[24:25], v[100:101], v[38:39]
	v_cndmask_b32_e32 v46, v27, v15, vcc
	v_mov_b32_dpp v42, v44 row_ror:1 row_mask:0xf bank_mask:0xf
	v_mov_b32_e32 v44, 0
	v_pk_fma_f32 v[38:39], v[108:109], v[40:41], v[38:39]
	v_cndmask_b32_e32 v47, v16, v8, vcc
	v_mov_b32_dpp v44, v45 row_ror:15 row_mask:0xf bank_mask:0xf
	v_cndmask_b32_e64 v45, v27, v43, s[44:45]
	v_mov_b32_e32 v43, 0
	v_pk_add_f32 v[38:39], v[112:113], v[38:39]
	v_cndmask_b32_e32 v49, v18, v10, vcc
	v_mov_b32_dpp v43, v45 row_ror:1 row_mask:0xf bank_mask:0xf
	v_mov_b32_e32 v45, 0
; DI unsigned pack2(float a, float b) { f32x2 v = {a, b}; hwbf16x2 r = __builtin_convertvector(v, hwbf16x2); return __builtin_bit_cast(unsigned, r); }
; DI float dpp_ror1(float v)  { return __builtin_bit_cast(float, __builtin_amdgcn_update_dpp(0, __builtin_bit_cast(int, v), 0x121, 0xf, 0xf, false)); }
; DI float dpp_ror15(float v) { return __builtin_bit_cast(float, __builtin_amdgcn_update_dpp(0, __builtin_bit_cast(int, v), 0x12F, 0xf, 0xf, false)); }
; DI float silu_mul(float g, float v) { return g * v * __builtin_amdgcn_rcpf(1.0f + __builtin_amdgcn_exp2f(-LOG2E * g)); }
;     DI void operator()(const f32x4 (&acc)[2][2][4][2], const Unit& u, int wr, int wc, int fr, int fq) const {
;     ...
;                 for (int n = 0; n < 2; ++n) {
;                     const f32x4 g = acc[ai][0][m][n];
;                     const f32x4 gprev = acc[ai][0][m > 0 ? m - 1 : 0][n], gnext = acc[ai][0][m < 3 ? m + 1 : 3][n];
;                     f32x4 up, dn;
; #pragma unroll
;                     for (int e = 0; e < 4; ++e) {
;                         const float pu = (m > 0 && fr == 15) ? gprev[e] : g[e];
;                         const float pd = (m < 3 && fr == 0) ? gnext[e] : g[e];
;                         up[e] = dpp_ror1(pu); dn[e] = dpp_ror15(pd);
;                     }
;                     if (efirst) up = (f32x4){0.f, 0.f, 0.f, 0.f};
;                     if (elast) dn = (f32x4){0.f, 0.f, 0.f, 0.f};
;                     gc[n] = w0[n] * up + w1[n] * g + w2[n] * dn + bb[n];
;                 }
;                 if (efirst || elast) {
;                     const size_t eo = (size_t)((row >> 6) * 2 + (elast ? 1 : 0)) * DFF + ch0;
; #pragma unroll
;                     for (int n = 0; n < 2; ++n) { *(f32x4*)(EP + eo + 4 * n) = gc[n]; *(f32x4*)(ER + eo + 4 * n) = acc[ai][0][m][n]; *(f32x4*)(EV + eo + 4 * n) = acc[ai][1][m][n]; }
;                 } else {
;                     const f32x4 v0 = acc[ai][1][m][0], v1 = acc[ai][1][m][1];
;                     u32x4 o;
;                     o[0] = pack2(silu_mul(gc[0][0], v0[0]), silu_mul(gc[0][1], v0[1])); o[1] = pack2(silu_mul(gc[0][2], v0[2]), silu_mul(gc[0][3], v0[3]));
;                     o[2] = pack2(silu_mul(gc[1][0], v1[0]), silu_mul(gc[1][1], v1[1])); o[3] = pack2(silu_mul(gc[1][2], v1[2]), silu_mul(gc[1][3], v1[3]));
;                     *(u32x4*)(ACT + (size_t)row * DFF + ch0) = o;
;                 }
	v_pk_mul_f32 v[42:43], v[98:99], v[42:43]
	v_mul_f32_e32 v40, 0xbfb8aa3b, v38
	v_mov_b32_dpp v45, v46 row_ror:15 row_mask:0xf bank_mask:0xf
	v_pk_fma_f32 v[42:43], v[26:27], v[102:103], v[42:43]
	v_cndmask_b32_e64 v46, v16, v32, s[44:45]
	v_pk_fma_f32 v[42:43], v[110:111], v[44:45], v[42:43]
	v_exp_f32_e32 v44, v40
	v_mul_f32_e32 v40, 0xbfb8aa3b, v39
	v_exp_f32_e32 v45, v40
	v_mov_b32_e32 v32, 0
	v_pk_add_f32 v[40:41], v[114:115], v[42:43]
	v_add_f32_e32 v42, 1.0, v44
	v_mov_b32_dpp v32, v46 row_ror:1 row_mask:0xf bank_mask:0xf
	v_mov_b32_e32 v46, 0
	v_add_f32_e32 v43, 1.0, v45
	v_rcp_f32_e32 v42, v42
	v_mov_b32_dpp v46, v47 row_ror:15 row_mask:0xf bank_mask:0xf
	v_cndmask_b32_e64 v47, v17, v33, s[44:45]
	v_mov_b32_e32 v33, 0
	v_rcp_f32_e32 v43, v43
	v_mul_f32_e32 v44, 0xbfb8aa3b, v40
	v_mov_b32_dpp v33, v47 row_ror:1 row_mask:0xf bank_mask:0xf
	v_mul_f32_e32 v45, 0xbfb8aa3b, v41
	v_mov_b32_e32 v47, 0
	v_pk_mul_f32 v[32:33], v[80:81], v[32:33]
	v_exp_f32_e32 v44, v44
	v_exp_f32_e32 v45, v45
	v_mov_b32_dpp v47, v48 row_ror:15 row_mask:0xf bank_mask:0xf
	v_pk_fma_f32 v[32:33], v[16:17], v[84:85], v[32:33]
	v_cndmask_b32_e64 v48, v18, v34, s[44:45]
	v_mov_b32_e32 v34, 0
	v_pk_fma_f32 v[32:33], v[88:89], v[46:47], v[32:33]
	v_pk_mul_f32 v[28:29], v[28:29], v[38:39]
	v_mov_b32_dpp v34, v48 row_ror:1 row_mask:0xf bank_mask:0xf
	v_mov_b32_e32 v48, 0
	v_pk_add_f32 v[32:33], v[92:93], v[32:33]
	v_pk_mul_f32 v[28:29], v[28:29], v[42:43]
	v_mov_b32_dpp v48, v49 row_ror:15 row_mask:0xf bank_mask:0xf
	v_cndmask_b32_e64 v49, v19, v35, s[44:45]
	v_mov_b32_e32 v35, 0
	v_pk_mul_f32 v[30:31], v[30:31], v[40:41]
	v_add_f32_e32 v40, 1.0, v44
	v_add_f32_e32 v41, 1.0, v45
	v_cvt_pk_bf16_f32 v28, v28, v29
	v_mul_f32_e32 v29, 0xbfb8aa3b, v32
	v_mov_b32_dpp v35, v49 row_ror:1 row_mask:0xf bank_mask:0xf
	v_rcp_f32_e32 v40, v40
	v_rcp_f32_e32 v41, v41
	v_exp_f32_e32 v38, v29
	v_mul_f32_e32 v29, 0xbfb8aa3b, v33
	v_cndmask_b32_e32 v50, v19, v11, vcc
	v_mov_b32_e32 v49, 0
	v_pk_mul_f32 v[34:35], v[82:83], v[34:35]
	v_exp_f32_e32 v39, v29
	v_mov_b32_dpp v49, v50 row_ror:15 row_mask:0xf bank_mask:0xf
	v_pk_fma_f32 v[34:35], v[18:19], v[86:87], v[34:35]
	v_pk_mul_f32 v[30:31], v[30:31], v[40:41]
	v_pk_fma_f32 v[34:35], v[90:91], v[48:49], v[34:35]
	v_cvt_pk_bf16_f32 v29, v30, v31
	v_pk_add_f32 v[34:35], v[94:95], v[34:35]
	v_add_f32_e32 v30, 1.0, v38
	v_add_f32_e32 v31, 1.0, v39
	v_mul_f32_e32 v38, 0xbfb8aa3b, v34
	v_mul_f32_e32 v39, 0xbfb8aa3b, v35
	v_exp_f32_e32 v38, v38
	v_exp_f32_e32 v39, v39
	v_rcp_f32_e32 v30, v30
	v_rcp_f32_e32 v31, v31
	v_pk_mul_f32 v[22:23], v[22:23], v[34:35]
	v_add_f32_e32 v34, 1.0, v38
	v_add_f32_e32 v35, 1.0, v39
	v_rcp_f32_e32 v34, v34
	v_rcp_f32_e32 v35, v35
	v_pk_mul_f32 v[20:21], v[20:21], v[32:33]
	v_add_u32_e32 v50, 0xa0, v193
	v_pk_mul_f32 v[20:21], v[20:21], v[30:31]
	s_nop 0
	v_cvt_pk_bf16_f32 v30, v20, v21
	v_pk_mul_f32 v[20:21], v[22:23], v[34:35]
	v_cndmask_b32_e64 v22, v13, v25, s[44:45]
	v_cvt_pk_bf16_f32 v31, v20, v21
	v_mad_i64_i32 v[20:21], s[28:29], v50, s30, v[36:37]
	v_lshl_add_u64 v[20:21], v[20:21], 0, v[132:133]
	global_store_dwordx4 v[20:21], v[28:31], off
	v_cndmask_b32_e64 v21, v12, v24, s[44:45]
	v_mov_b32_e32 v20, 0
	v_cndmask_b32_e64 v23, v14, v26, s[44:45]
	v_cndmask_b32_e64 v25, v15, v27, s[44:45]
	v_mov_b32_dpp v20, v21 row_ror:1 row_mask:0xf bank_mask:0xf
	v_mov_b32_e32 v21, 0
	v_mov_b32_e32 v24, 0
	v_mov_b32_e32 v28, 0
	v_mov_b32_dpp v21, v22 row_ror:1 row_mask:0xf bank_mask:0xf
	v_mov_b32_e32 v22, 0
	v_mov_b32_dpp v24, v14 row_ror:15 row_mask:0xf bank_mask:0xf
	v_cndmask_b32_e64 v24, v24, 0, s[44:45]
	v_mov_b32_dpp v22, v23 row_ror:1 row_mask:0xf bank_mask:0xf
	v_mov_b32_e32 v23, 0
	v_mov_b32_e32 v29, 0
	v_mov_b32_dpp v28, v12 row_ror:15 row_mask:0xf bank_mask:0xf
	v_mov_b32_dpp v23, v25 row_ror:1 row_mask:0xf bank_mask:0xf
	v_mov_b32_e32 v25, 0
	v_pk_mul_f32 v[22:23], v[98:99], v[22:23]
	v_mov_b32_dpp v29, v13 row_ror:15 row_mask:0xf bank_mask:0xf
	v_mov_b32_dpp v25, v15 row_ror:15 row_mask:0xf bank_mask:0xf
	v_cndmask_b32_e64 v25, v25, 0, s[44:45]
	v_pk_fma_f32 v[22:23], v[14:15], v[102:103], v[22:23]
	v_pk_mul_f32 v[20:21], v[96:97], v[20:21]
	v_pk_fma_f32 v[22:23], v[110:111], v[24:25], v[22:23]
	v_cndmask_b32_e64 v24, v8, v16, s[44:45]
	v_mov_b32_e32 v16, 0
	v_cndmask_b32_e64 v27, v29, 0, s[44:45]
	v_cndmask_b32_e64 v26, v28, 0, s[44:45]
	v_mov_b32_dpp v16, v24 row_ror:1 row_mask:0xf bank_mask:0xf
	v_cndmask_b32_e64 v24, v9, v17, s[44:45]
	v_mov_b32_e32 v17, 0
	v_pk_fma_f32 v[20:21], v[12:13], v[100:101], v[20:21]
	v_cndmask_b32_e64 v25, v11, v19, s[44:45]
	v_mov_b32_dpp v17, v24 row_ror:1 row_mask:0xf bank_mask:0xf
	v_cndmask_b32_e64 v24, v10, v18, s[44:45]
	v_mov_b32_e32 v18, 0
	v_mov_b32_e32 v19, 0
	v_pk_fma_f32 v[20:21], v[108:109], v[26:27], v[20:21]
	v_mov_b32_e32 v26, 0
	v_mov_b32_e32 v27, 0
	v_mov_b32_dpp v18, v24 row_ror:1 row_mask:0xf bank_mask:0xf
	v_mov_b32_e32 v24, 0
	v_mov_b32_dpp v19, v25 row_ror:1 row_mask:0xf bank_mask:0xf
	v_mov_b32_e32 v25, 0
	v_mov_b32_dpp v26, v8 row_ror:15 row_mask:0xf bank_mask:0xf
	v_mov_b32_dpp v27, v9 row_ror:15 row_mask:0xf bank_mask:0xf
	v_mov_b32_dpp v24, v10 row_ror:15 row_mask:0xf bank_mask:0xf
	v_mov_b32_dpp v25, v11 row_ror:15 row_mask:0xf bank_mask:0xf
	v_pk_mul_f32 v[16:17], v[80:81], v[16:17]
	v_pk_mul_f32 v[18:19], v[82:83], v[18:19]
	v_cndmask_b32_e64 v25, v25, 0, s[44:45]
	v_cndmask_b32_e64 v24, v24, 0, s[44:45]
	v_cndmask_b32_e64 v27, v27, 0, s[44:45]
	v_cndmask_b32_e64 v26, v26, 0, s[44:45]
	v_pk_fma_f32 v[18:19], v[10:11], v[86:87], v[18:19]
	v_pk_fma_f32 v[16:17], v[8:9], v[84:85], v[16:17]
	v_pk_fma_f32 v[18:19], v[90:91], v[24:25], v[18:19]
	v_pk_fma_f32 v[16:17], v[88:89], v[26:27], v[16:17]
	v_pk_add_f32 v[22:23], v[114:115], v[22:23]
	v_pk_add_f32 v[20:21], v[112:113], v[20:21]
	v_pk_add_f32 v[18:19], v[94:95], v[18:19]
	v_pk_add_f32 v[16:17], v[92:93], v[16:17]
	v_add_u32_e32 v24, 0xb0, v193
	s_and_saveexec_b64 s[28:29], s[42:43]
	s_xor_b64 s[28:29], exec, s[28:29]
	s_cbranch_execz .LBB1_395
; DI unsigned pack2(float a, float b) { f32x2 v = {a, b}; hwbf16x2 r = __builtin_convertvector(v, hwbf16x2); return __builtin_bit_cast(unsigned, r); }
; DI float silu_mul(float g, float v) { return g * v * __builtin_amdgcn_rcpf(1.0f + __builtin_amdgcn_exp2f(-LOG2E * g)); }
;     DI void operator()(const f32x4 (&acc)[2][2][4][2], const Unit& u, int wr, int wc, int fr, int fq) const {
;     ...
;                 if (efirst || elast) {
;                     const size_t eo = (size_t)((row >> 6) * 2 + (elast ? 1 : 0)) * DFF + ch0;
; #pragma unroll
;                     for (int n = 0; n < 2; ++n) { *(f32x4*)(EP + eo + 4 * n) = gc[n]; *(f32x4*)(ER + eo + 4 * n) = acc[ai][0][m][n]; *(f32x4*)(EV + eo + 4 * n) = acc[ai][1][m][n]; }
;                 } else {
;                     const f32x4 v0 = acc[ai][1][m][0], v1 = acc[ai][1][m][1];
;                     u32x4 o;
;                     o[0] = pack2(silu_mul(gc[0][0], v0[0]), silu_mul(gc[0][1], v0[1])); o[1] = pack2(silu_mul(gc[0][2], v0[2]), silu_mul(gc[0][3], v0[3]));
;                     o[2] = pack2(silu_mul(gc[1][0], v1[0]), silu_mul(gc[1][1], v1[1])); o[3] = pack2(silu_mul(gc[1][2], v1[2]), silu_mul(gc[1][3], v1[3]));
;                     *(u32x4*)(ACT + (size_t)row * DFF + ch0) = o;
;                 }
	v_mul_f32_e32 v25, 0xbfb8aa3b, v20
	v_exp_f32_e32 v25, v25
	v_mul_f32_e32 v26, 0xbfb8aa3b, v21
	v_exp_f32_e32 v26, v26
	v_mul_f32_e32 v28, 0xbfb8aa3b, v23
	v_add_f32_e32 v25, 1.0, v25
	v_exp_f32_e32 v29, v28
	v_add_f32_e32 v27, 1.0, v26
	v_rcp_f32_e32 v26, v25
	v_mul_f32_e32 v25, 0xbfb8aa3b, v22
	v_exp_f32_e32 v25, v25
	v_rcp_f32_e32 v27, v27
	v_pk_mul_f32 v[20:21], v[4:5], v[20:21]
	v_pk_mul_f32 v[22:23], v[6:7], v[22:23]
	v_add_f32_e32 v25, 1.0, v25
	v_rcp_f32_e32 v28, v25
	v_add_f32_e32 v25, 1.0, v29
	v_pk_mul_f32 v[20:21], v[20:21], v[26:27]
	v_rcp_f32_e32 v29, v25
	v_cvt_pk_bf16_f32 v20, v20, v21
	v_mul_f32_e32 v21, 0xbfb8aa3b, v16
	v_exp_f32_e32 v25, v21
	v_mul_f32_e32 v21, 0xbfb8aa3b, v17
	v_exp_f32_e32 v26, v21
	v_pk_mul_f32 v[22:23], v[22:23], v[28:29]
	v_pk_mul_f32 v[16:17], v[0:1], v[16:17]
	v_cvt_pk_bf16_f32 v21, v22, v23
	v_add_f32_e32 v22, 1.0, v25
	v_mul_f32_e32 v25, 0xbfb8aa3b, v18
	v_add_f32_e32 v23, 1.0, v26
	v_exp_f32_e32 v25, v25
	v_mul_f32_e32 v26, 0xbfb8aa3b, v19
	v_exp_f32_e32 v27, v26
	v_rcp_f32_e32 v22, v22
	v_add_f32_e32 v25, 1.0, v25
	v_rcp_f32_e32 v23, v23
	v_rcp_f32_e32 v26, v25
	v_add_f32_e32 v25, 1.0, v27
	v_rcp_f32_e32 v27, v25
	v_pk_mul_f32 v[18:19], v[2:3], v[18:19]
	v_pk_mul_f32 v[16:17], v[16:17], v[22:23]
	s_nop 0
	v_cvt_pk_bf16_f32 v22, v16, v17
	v_pk_mul_f32 v[16:17], v[18:19], v[26:27]
	s_nop 0
	v_cvt_pk_bf16_f32 v23, v16, v17
	v_mov_b64_e32 v[16:17], s[6:7]
	v_mad_i64_i32 v[16:17], s[42:43], v24, s30, v[16:17]
	v_lshl_add_u64 v[16:17], v[184:185], 1, v[16:17]
	global_store_dwordx4 v[16:17], v[20:23], off
.LBB1_395:
	s_andn2_saveexec_b64 s[28:29], s[28:29]
	s_cbranch_execz .LBB1_376
	v_ashrrev_i32_e32 v24, 5, v24
	v_mad_i64_i32 v[24:25], s[42:43], v24, s60, v[184:185]
	v_lshlrev_b64 v[24:25], 2, v[24:25]
	v_lshl_add_u64 v[26:27], s[8:9], 0, v[24:25]
	global_store_dwordx4 v[26:27], v[20:23], off
	s_nop 1
	v_lshl_add_u64 v[20:21], s[10:11], 0, v[24:25]
	global_store_dwordx4 v[20:21], v[12:15], off
	s_nop 1
	v_lshl_add_u64 v[12:13], s[12:13], 0, v[24:25]
	global_store_dwordx4 v[12:13], v[4:7], off
	global_store_dwordx4 v[26:27], v[16:19], off offset:16
	global_store_dwordx4 v[20:21], v[8:11], off offset:16
	global_store_dwordx4 v[12:13], v[0:3], off offset:16
	s_branch .LBB1_376

; DI void glu_fix_phase(const Params& p, int layer) {
;     ...
;     for (int task0 = bid * 512 + tid; task0 < NTASK; task0 += 3 * tstride) {
;         f32x4 gc[3], vv[3], nb[3], wv[3]; int rowc[3], cc[3];
; #pragma unroll
;         for (int u = 0; u < 3; ++u) {
;             const int task = task0 + u * tstride;
;             if (task < NTASK) {
;                 const int e = task / NC4, c = (task - e * NC4) * 4, b64 = e >> 1, last = e & 1, row = b64 * 64 + (last ? 63 : 0), sq = row & (S - 1);
;                 const bool valid = last ? (sq != S - 1) : (sq != 0);
;                 const int en = valid ? (last ? e + 1 : e - 1) : e;
;                 gc[u] = *(const f32x4*)(EP + (size_t)e * DFF + c); vv[u] = *(const f32x4*)(EV + (size_t)e * DFF + c);
;                 nb[u] = *(const f32x4*)(ER + (size_t)en * DFF + c);
;                 wv[u] = *(const f32x4*)(cw + (last ? 2 * DFF : 0) + c);
;                 if (!valid) wv[u] = (f32x4){0.f, 0.f, 0.f, 0.f};
;                 rowc[u] = row; cc[u] = c;
;             }
.LBB1_467:
	v_mul_hi_i32 v32, v51, s4
	v_lshrrev_b32_e32 v33, 31, v32
	v_ashrrev_i32_e32 v32, 8, v32
	v_add_u32_e32 v32, v32, v33
	v_mul_i32_i24_e32 v33, 0xfffffa80, v32
	v_bfe_i32 v59, v32, 0, 1
	v_lshlrev_b32_e32 v60, 5, v32
	v_add_lshl_u32 v54, v33, v51, 2
	v_and_b32_e32 v33, 1, v32
	v_and_b32_e32 v34, 0xffffffc0, v60
	v_and_b32_e32 v35, 63, v59
	v_bitop3_b32 v34, v35, s22, v34 bitop3:0xc8
	v_and_b32_e32 v35, 0xfff, v59
	v_cmp_eq_u32_e32 vcc, 0, v33
	v_cmp_eq_u32_e64 s[40:41], v34, v35
	v_ashrrev_i32_e32 v55, 31, v54
	v_cndmask_b32_e64 v33, 1, -1, vcc
	v_cndmask_b32_e64 v33, v33, 0, s[40:41]
	v_add_u32_e32 v40, v33, v32
	v_mul_hi_i32_i24_e32 v33, 0x1600, v32
	v_mul_i32_i24_e32 v32, 0x1600, v32
	v_lshlrev_b64 v[32:33], 2, v[32:33]
	v_mul_hi_i32_i24_e32 v41, 0x5800, v40
	v_mul_i32_i24_e32 v40, 0x5800, v40
	v_and_b32_e32 v48, 0xb000, v59
	v_lshl_add_u64 v[34:35], s[10:11], 0, v[32:33]
	v_lshlrev_b64 v[44:45], 2, v[54:55]
	v_lshl_add_u64 v[32:33], s[14:15], 0, v[32:33]
	v_lshl_add_u64 v[40:41], s[12:13], 0, v[40:41]
	s_waitcnt lgkmcnt(0)
	v_lshl_add_u64 v[46:47], s[16:17], 0, v[48:49]
	v_lshl_add_u64 v[34:35], v[34:35], 0, v[44:45]
	v_lshl_add_u64 v[32:33], v[32:33], 0, v[44:45]
	v_lshl_add_u64 v[40:41], v[40:41], 0, v[44:45]
	v_lshl_add_u64 v[44:45], v[46:47], 0, v[44:45]
	global_load_dwordx4 v[36:39], v[34:35], off
	s_nop 0
	global_load_dwordx4 v[32:35], v[32:33], off
	v_add_u32_e32 v58, s60, v51
	global_load_dwordx4 v[40:43], v[40:41], off
	v_cmp_gt_i32_e32 vcc, s2, v58
	global_load_dwordx4 v[44:47], v[44:45], off
	s_and_saveexec_b64 s[20:21], vcc
	s_cbranch_execz .LBB1_469
	v_mul_hi_i32 v0, v58, s4
	v_lshrrev_b32_e32 v1, 31, v0
	v_ashrrev_i32_e32 v0, 8, v0
	v_add_u32_e32 v0, v0, v1
	v_mov_b32_e32 v1, s60
	v_mad_i32_i24 v1, v0, s5, v1
	v_bfe_i32 v57, v0, 0, 1
	v_lshlrev_b32_e32 v61, 5, v0
	v_add_lshl_u32 v52, v1, v51, 2
	v_and_b32_e32 v1, 1, v0
	v_and_b32_e32 v2, 0xffffffc0, v61
	v_and_b32_e32 v3, 63, v57
	v_bitop3_b32 v2, v3, s22, v2 bitop3:0xc8
	v_and_b32_e32 v3, 0xfff, v57
	v_cmp_eq_u32_e64 s[42:43], 0, v1
	v_ashrrev_i32_e32 v53, 31, v52
	v_and_b32_e32 v48, 0xb000, v57
	v_cndmask_b32_e64 v1, 1, -1, s[42:43]
	v_cmp_eq_u32_e64 s[42:43], v2, v3
	v_lshlrev_b64 v[16:17], 2, v[52:53]
	v_lshl_add_u64 v[28:29], s[16:17], 0, v[48:49]
	v_cndmask_b32_e64 v1, v1, 0, s[42:43]
	v_add_u32_e32 v18, v1, v0
	v_mul_hi_i32_i24_e32 v1, 0x1600, v0
	v_mul_i32_i24_e32 v0, 0x1600, v0
	v_lshlrev_b64 v[0:1], 2, v[0:1]
	v_lshl_add_u64 v[2:3], s[10:11], 0, v[0:1]
	v_lshl_add_u64 v[0:1], s[14:15], 0, v[0:1]
	v_mul_hi_i32_i24_e32 v19, 0x5800, v18
	v_mul_i32_i24_e32 v18, 0x5800, v18
	v_lshl_add_u64 v[2:3], v[2:3], 0, v[16:17]
	v_lshl_add_u64 v[12:13], v[0:1], 0, v[16:17]
	v_lshl_add_u64 v[28:29], v[28:29], 0, v[16:17]
	v_lshl_add_u64 v[18:19], s[12:13], 0, v[18:19]
	global_load_dwordx4 v[0:3], v[2:3], off
	s_nop 0
	global_load_dwordx4 v[12:15], v[12:13], off
	v_lshl_add_u64 v[16:17], v[18:19], 0, v[16:17]
	global_load_dwordx4 v[28:31], v[28:29], off
	v_bfi_b32 v57, 63, v57, v61
	global_load_dwordx4 v[16:19], v[16:17], off
	s_waitcnt vmcnt(0)
	v_cndmask_b32_e64 v31, v31, 0, s[42:43]
	v_cndmask_b32_e64 v30, v30, 0, s[42:43]
	v_cndmask_b32_e64 v29, v29, 0, s[42:43]
	v_cndmask_b32_e64 v28, v28, 0, s[42:43]
.LBB1_469:
	s_or_b64 exec, exec, s[20:21]
	v_add_u32_e32 v48, s3, v51
	v_cmp_gt_i32_e64 s[42:43], s2, v48
	s_and_saveexec_b64 s[20:21], s[42:43]
	s_cbranch_execz .LBB1_471
	v_mul_hi_i32 v4, v48, s4
	v_lshrrev_b32_e32 v5, 31, v4
	v_ashrrev_i32_e32 v4, 8, v4
	v_add_u32_e32 v4, v4, v5
	v_mov_b32_e32 v5, s3
	v_mad_i32_i24 v5, v4, s5, v5
	v_bfe_i32 v53, v4, 0, 1
	v_lshlrev_b32_e32 v56, 5, v4
	v_add_lshl_u32 v50, v5, v51, 2
	v_and_b32_e32 v5, 1, v4
	v_and_b32_e32 v6, 0xffffffc0, v56
	v_and_b32_e32 v7, 63, v53
	v_bitop3_b32 v6, v7, s22, v6 bitop3:0xc8
	v_and_b32_e32 v7, 0xfff, v53
	v_cmp_eq_u32_e64 s[44:45], 0, v5
	v_ashrrev_i32_e32 v51, 31, v50
	v_lshlrev_b64 v[8:9], 2, v[50:51]
	v_cndmask_b32_e64 v5, 1, -1, s[44:45]
	v_cmp_eq_u32_e64 s[44:45], v6, v7
	v_and_b32_e32 v48, 0xb000, v53
	v_lshl_add_u64 v[20:21], s[16:17], 0, v[48:49]
	v_cndmask_b32_e64 v5, v5, 0, s[44:45]
	v_add_u32_e32 v61, v5, v4
	v_mul_hi_i32_i24_e32 v5, 0x1600, v4
	v_mul_i32_i24_e32 v4, 0x1600, v4
	v_lshlrev_b64 v[4:5], 2, v[4:5]
	v_lshl_add_u64 v[6:7], s[10:11], 0, v[4:5]
	v_lshl_add_u64 v[4:5], s[14:15], 0, v[4:5]
	v_lshl_add_u64 v[6:7], v[6:7], 0, v[8:9]
	v_lshl_add_u64 v[10:11], v[4:5], 0, v[8:9]
	global_load_dwordx4 v[4:7], v[6:7], off
	s_nop 0
	global_load_dwordx4 v[24:27], v[10:11], off
	v_mul_hi_i32_i24_e32 v11, 0x5800, v61
	v_mul_i32_i24_e32 v10, 0x5800, v61
	v_lshl_add_u64 v[20:21], v[20:21], 0, v[8:9]
	v_lshl_add_u64 v[10:11], s[12:13], 0, v[10:11]
	global_load_dwordx4 v[20:23], v[20:21], off
	v_lshl_add_u64 v[8:9], v[10:11], 0, v[8:9]
	global_load_dwordx4 v[8:11], v[8:9], off
	v_bfi_b32 v56, 63, v53, v56
	s_waitcnt vmcnt(0)
	v_cndmask_b32_e64 v23, v23, 0, s[44:45]
	v_cndmask_b32_e64 v22, v22, 0, s[44:45]
	v_cndmask_b32_e64 v21, v21, 0, s[44:45]
	v_cndmask_b32_e64 v20, v20, 0, s[44:45]
; DI unsigned pack2(float a, float b) { f32x2 v = {a, b}; hwbf16x2 r = __builtin_convertvector(v, hwbf16x2); return __builtin_bit_cast(unsigned, r); }
; DI float silu_mul(float g, float v) { return g * v * __builtin_amdgcn_rcpf(1.0f + __builtin_amdgcn_exp2f(-LOG2E * g)); }
; DI void glu_fix_phase(const Params& p, int layer) {
;     ...
; #pragma unroll
;         for (int u = 0; u < 3; ++u) {
;             const int task = task0 + u * tstride;
;             if (task < NTASK) {
;                 const f32x4 g = gc[u] + wv[u] * nb[u], v = vv[u];
;                 u32x2 o;
;                 o[0] = pack2(silu_mul(g[0], v[0]), silu_mul(g[1], v[1]));
;                 o[1] = pack2(silu_mul(g[2], v[2]), silu_mul(g[3], v[3]));
;                 *(u32x2*)(ACT + (size_t)rowc[u] * DFF + cc[u]) = o;
;             }
;         }
.LBB1_471:
	s_or_b64 exec, exec, s[20:21]
	s_waitcnt vmcnt(0)
	v_cndmask_b32_e64 v45, v45, 0, s[40:41]
	v_cndmask_b32_e64 v44, v44, 0, s[40:41]
	v_cndmask_b32_e64 v47, v47, 0, s[40:41]
	v_cndmask_b32_e64 v46, v46, 0, s[40:41]
	s_waitcnt lgkmcnt(0)
	v_pk_fma_f32 v[36:37], v[40:41], v[44:45], v[36:37]
	v_pk_fma_f32 v[38:39], v[42:43], v[46:47], v[38:39]
	v_mul_f32_e32 v40, 0xbfb8aa3b, v36
	v_mul_f32_e32 v41, 0xbfb8aa3b, v37
	v_mul_f32_e32 v42, 0xbfb8aa3b, v38
	v_mul_f32_e32 v43, 0xbfb8aa3b, v39
	v_exp_f32_e32 v40, v40
	v_exp_f32_e32 v41, v41
	v_exp_f32_e32 v42, v42
	v_exp_f32_e32 v43, v43
	v_add_f32_e32 v40, 1.0, v40
	v_add_f32_e32 v41, 1.0, v41
	v_pk_mul_f32 v[32:33], v[32:33], v[36:37]
	v_add_f32_e32 v36, 1.0, v42
	v_add_f32_e32 v37, 1.0, v43
	v_rcp_f32_e32 v40, v40
	v_rcp_f32_e32 v41, v41
	v_rcp_f32_e32 v36, v36
	v_rcp_f32_e32 v37, v37
	v_pk_mul_f32 v[34:35], v[34:35], v[38:39]
	v_pk_mul_f32 v[32:33], v[32:33], v[40:41]
	v_bfi_b32 v48, 63, v59, v60
	v_pk_mul_f32 v[34:35], v[34:35], v[36:37]
	v_cvt_pk_bf16_f32 v32, v32, v33
	v_cvt_pk_bf16_f32 v33, v34, v35
	v_mov_b64_e32 v[34:35], s[8:9]
	v_mad_i64_i32 v[34:35], s[20:21], v48, s23, v[34:35]
	v_lshl_add_u64 v[34:35], v[54:55], 1, v[34:35]
	global_store_dwordx2 v[34:35], v[32:33], off
	s_and_saveexec_b64 s[20:21], vcc
	s_cbranch_execz .LBB1_473
	v_pk_fma_f32 v[34:35], v[16:17], v[28:29], v[0:1]
	v_pk_fma_f32 v[32:33], v[18:19], v[30:31], v[2:3]
	v_mul_f32_e32 v36, 0xbfb8aa3b, v34
	v_mul_f32_e32 v37, 0xbfb8aa3b, v35
	v_exp_f32_e32 v36, v36
	v_exp_f32_e32 v37, v37
	v_pk_mul_f32 v[34:35], v[12:13], v[34:35]
	v_ashrrev_i32_e32 v53, 31, v52
	v_add_f32_e32 v36, 1.0, v36
	v_add_f32_e32 v37, 1.0, v37
	v_rcp_f32_e32 v36, v36
	v_rcp_f32_e32 v37, v37
	s_nop 0
	v_pk_mul_f32 v[34:35], v[34:35], v[36:37]
	s_nop 0
	v_cvt_pk_bf16_f32 v34, v34, v35
	v_mul_f32_e32 v35, 0xbfb8aa3b, v32
	v_exp_f32_e32 v35, v35
	s_nop 0
	v_add_f32_e32 v35, 1.0, v35
	v_rcp_f32_e32 v36, v35
	v_mul_f32_e32 v35, 0xbfb8aa3b, v33
	v_exp_f32_e32 v35, v35
	v_pk_mul_f32 v[32:33], v[14:15], v[32:33]
	v_add_f32_e32 v35, 1.0, v35
	v_rcp_f32_e32 v37, v35
	s_nop 0
	v_pk_mul_f32 v[32:33], v[32:33], v[36:37]
	s_nop 0
	v_cvt_pk_bf16_f32 v35, v32, v33
	v_mov_b64_e32 v[32:33], s[8:9]
	v_mad_i64_i32 v[32:33], s[26:27], v57, s23, v[32:33]
	v_lshl_add_u64 v[32:33], v[52:53], 1, v[32:33]
	global_store_dwordx2 v[32:33], v[34:35], off
.LBB1_473:
	s_or_b64 exec, exec, s[20:21]
	s_and_saveexec_b64 s[20:21], s[42:43]
	s_cbranch_execz .LBB1_466
	v_pk_fma_f32 v[34:35], v[8:9], v[20:21], v[4:5]
	v_pk_fma_f32 v[32:33], v[10:11], v[22:23], v[6:7]
	v_mul_f32_e32 v36, 0xbfb8aa3b, v34
	v_mul_f32_e32 v37, 0xbfb8aa3b, v35
	v_exp_f32_e32 v36, v36
	v_exp_f32_e32 v37, v37
	v_pk_mul_f32 v[34:35], v[24:25], v[34:35]
	v_ashrrev_i32_e32 v51, 31, v50
	v_add_f32_e32 v36, 1.0, v36
	v_add_f32_e32 v37, 1.0, v37
	v_rcp_f32_e32 v36, v36
	v_rcp_f32_e32 v37, v37
	s_nop 0
	v_pk_mul_f32 v[34:35], v[34:35], v[36:37]
	s_nop 0
	v_cvt_pk_bf16_f32 v34, v34, v35
	v_mul_f32_e32 v35, 0xbfb8aa3b, v32
	v_exp_f32_e32 v35, v35
	s_nop 0
	v_add_f32_e32 v35, 1.0, v35
	v_rcp_f32_e32 v36, v35
	v_mul_f32_e32 v35, 0xbfb8aa3b, v33
	v_exp_f32_e32 v35, v35
	v_pk_mul_f32 v[32:33], v[26:27], v[32:33]
	v_add_f32_e32 v35, 1.0, v35
	v_rcp_f32_e32 v37, v35
	s_nop 0
	v_pk_mul_f32 v[32:33], v[32:33], v[36:37]
	s_nop 0
	v_cvt_pk_bf16_f32 v35, v32, v33
	v_mov_b64_e32 v[32:33], s[8:9]
	v_mad_i64_i32 v[32:33], s[26:27], v56, s23, v[32:33]
	v_lshl_add_u64 v[32:33], v[50:51], 1, v[32:33]
	global_store_dwordx2 v[32:33], v[34:35], off
	s_branch .LBB1_466

; #define PG8_STAGE(bufoff, gbase, voff) do { _Pragma("unroll") for (int _i = 0; _i < 2; ++_i) \
;         __builtin_amdgcn_global_load_lds((const unsigned*)((const char*)(gbase) + (voff)[_i]), (LAS unsigned*)(lds + (bufoff) + ldsw + _i * 8192), 16, 0, 0); } while (0)
; #define PG8_LDA(dst, b, h) do { _Pragma("unroll") for (int m = 0; m < 4; ++m) _Pragma("unroll") for (int k = 0; k < 2; ++k) dst[m][k] = *(const LAS bf16x8*)(lds + PG8_SA(b, h) + aoff + m * 2048 + k * 1024); } while (0)
; #define PG8_LDB(dst, b, h) do { _Pragma("unroll") for (int n = 0; n < 2; ++n) _Pragma("unroll") for (int k = 0; k < 2; ++k) dst[n][k] = *(const LAS bf16x8*)(lds + PG8_SB(b, h) + boff + n * 2048 + k * 1024); } while (0)
; #define PG8_MMA(ai, bj, At, Bt) do { __builtin_amdgcn_s_setprio(1); _Pragma("unroll") for (int m = 0; m < 4; ++m) _Pragma("unroll") for (int n = 0; n < 2; ++n) _Pragma("unroll") for (int k = 0; k < 2; ++k) \
;         acc[ai][bj][m][n] = __builtin_amdgcn_mfma_f32_16x16x32_bf16(Bt[n][k], At[m][k], acc[ai][bj][m][n], 0, 0, 0); __builtin_amdgcn_s_setprio(0); } while (0)
; #define PG8_WAIT_V(n) asm volatile("s_waitcnt vmcnt(" #n ")" ::: "memory")
; #define PG8_WAIT_L(n) asm volatile("s_waitcnt lgkmcnt(" #n ")" ::: "memory")
; #define PG8_BAR __builtin_amdgcn_s_barrier()
; #define PG8_SCHED __builtin_amdgcn_sched_barrier(0)
; template <class Map, class Epi>
; DI void gemm_phase(LAS unsigned char* lds, const Map& MP, const Epi& E, const int nM, const int nN, const int K, const int lda, const int ldb) {
;     ...
;             PG8_LDB(B0, 0, 0); PG8_SCHED; PG8_LDA(At, 0, 0); PG8_STAGE(PG8_SA(1, 1), a1 + hstepA, voffA);
;             PG8_WAIT_L(8); PG8_BAR; PG8_WAIT_L(0); PG8_MMA(0, 0, At, B0); PG8_BAR; PG8_SCHED;
;             PG8_LDB(B1, 0, 1); PG8_STAGE(PG8_SB(0, 0), b2, voffB);
;             PG8_BAR; PG8_WAIT_L(0); PG8_MMA(0, 1, At, B1); PG8_BAR;
;             PG8_LDA(At, 0, 1); PG8_STAGE(PG8_SA(0, 0), a2, voffA);
;             PG8_BAR; PG8_WAIT_L(0); PG8_MMA(1, 0, At, B0); PG8_BAR; PG8_SCHED;
;             PG8_STAGE(PG8_SB(0, 1), b2 + hstepB, voffB);
;             PG8_WAIT_V(6); PG8_BAR; PG8_MMA(1, 1, At, B1); PG8_BAR;
.LBB1_550:
	ds_read_b128 v[152:155], v149
	ds_read_b128 v[156:159], v149 offset:1024
	ds_read_b128 v[160:163], v149 offset:2048
	ds_read_b128 v[164:167], v149 offset:3072
	s_add_u32 s10, s8, 0x100
	s_addc_u32 s11, s9, 0
	s_cmpk_eq_i32 s3, 0x54
	s_cselect_b32 s15, s43, s11
	s_cselect_b32 s14, s42, s10
	s_cselect_b32 s13, s7, s38
	s_cselect_b32 s12, s6, s5
	v_lshl_add_u64 v[144:145], s[8:9], 0, v[138:139]
	s_add_i32 m0, s24, 0xc000
	ds_read_b128 v[168:171], v150
	ds_read_b128 v[172:175], v150 offset:1024
	ds_read_b128 v[176:179], v150 offset:2048
	ds_read_b128 v[180:183], v150 offset:3072
	ds_read_b128 v[184:187], v150 offset:4096
	ds_read_b128 v[188:191], v150 offset:5120
	ds_read_b128 v[192:195], v150 offset:6144
	ds_read_b128 v[198:201], v150 offset:7168
	global_load_lds_dwordx4 v[144:145], off
	v_lshl_add_u64 v[144:145], s[8:9], 0, v[136:137]
	s_add_i32 m0, s24, 0xe000
	s_nop 0
	global_load_lds_dwordx4 v[144:145], off
	s_waitcnt lgkmcnt(8)
	s_barrier
	s_setprio 1
	s_waitcnt lgkmcnt(7)
	v_mfma_f32_16x16x32_bf16 v[124:127], v[152:155], v[168:171], v[124:127]
	v_mfma_f32_16x16x32_bf16 v[120:123], v[160:163], v[168:171], v[120:123]
	s_waitcnt lgkmcnt(5)
	v_mfma_f32_16x16x32_bf16 v[108:111], v[152:155], v[176:179], v[108:111]
	v_mfma_f32_16x16x32_bf16 v[104:107], v[160:163], v[176:179], v[104:107]
	s_waitcnt lgkmcnt(3)
	v_mfma_f32_16x16x32_bf16 v[92:95], v[152:155], v[184:187], v[92:95]
	v_mfma_f32_16x16x32_bf16 v[88:91], v[160:163], v[184:187], v[88:91]
	s_waitcnt lgkmcnt(1)
	v_mfma_f32_16x16x32_bf16 v[76:79], v[152:155], v[192:195], v[76:79]
	v_mfma_f32_16x16x32_bf16 v[72:75], v[160:163], v[192:195], v[72:75]
	v_mfma_f32_16x16x32_bf16 v[124:127], v[156:159], v[172:175], v[124:127]
	v_mfma_f32_16x16x32_bf16 v[120:123], v[164:167], v[172:175], v[120:123]
	v_mfma_f32_16x16x32_bf16 v[108:111], v[156:159], v[180:183], v[108:111]
	v_mfma_f32_16x16x32_bf16 v[104:107], v[164:167], v[180:183], v[104:107]
	v_mfma_f32_16x16x32_bf16 v[92:95], v[156:159], v[188:191], v[92:95]
	v_mfma_f32_16x16x32_bf16 v[88:91], v[164:167], v[188:191], v[88:91]
	s_waitcnt lgkmcnt(0)
	v_mfma_f32_16x16x32_bf16 v[76:79], v[156:159], v[198:201], v[76:79]
	v_mfma_f32_16x16x32_bf16 v[72:75], v[164:167], v[198:201], v[72:75]
	s_setprio 0
	s_barrier
	s_add_i32 s8, s35, s22
	v_lshl_add_u64 v[144:145], s[12:13], 0, v[132:133]
	s_mov_b32 m0, s8
	ds_read_b128 v[202:205], v151
	ds_read_b128 v[206:209], v151 offset:1024
	ds_read_b128 v[210:213], v151 offset:2048
	ds_read_b128 v[214:217], v151 offset:3072
	global_load_lds_dwordx4 v[144:145], off
	v_lshl_add_u64 v[218:219], s[12:13], 0, v[128:129]
	s_add_i32 m0, s8, 0x2000
	s_nop 0
	global_load_lds_dwordx4 v[218:219], off
	s_barrier
	s_setprio 1
	s_waitcnt lgkmcnt(3)
	v_mfma_f32_16x16x32_bf16 v[116:119], v[202:205], v[168:171], v[116:119]
	s_waitcnt lgkmcnt(1)
	v_mfma_f32_16x16x32_bf16 v[112:115], v[210:213], v[168:171], v[112:115]
	v_mfma_f32_16x16x32_bf16 v[100:103], v[202:205], v[176:179], v[100:103]
	v_mfma_f32_16x16x32_bf16 v[96:99], v[210:213], v[176:179], v[96:99]
	v_mfma_f32_16x16x32_bf16 v[84:87], v[202:205], v[184:187], v[84:87]
	v_mfma_f32_16x16x32_bf16 v[80:83], v[210:213], v[184:187], v[80:83]
	v_mfma_f32_16x16x32_bf16 v[68:71], v[202:205], v[192:195], v[68:71]
	v_mfma_f32_16x16x32_bf16 v[64:67], v[210:213], v[192:195], v[64:67]
	v_mfma_f32_16x16x32_bf16 v[116:119], v[206:209], v[172:175], v[116:119]
	s_waitcnt lgkmcnt(0)
	v_mfma_f32_16x16x32_bf16 v[112:115], v[214:217], v[172:175], v[112:115]
	v_mfma_f32_16x16x32_bf16 v[100:103], v[206:209], v[180:183], v[100:103]
	v_mfma_f32_16x16x32_bf16 v[96:99], v[214:217], v[180:183], v[96:99]
	v_mfma_f32_16x16x32_bf16 v[84:87], v[206:209], v[188:191], v[84:87]
	v_mfma_f32_16x16x32_bf16 v[80:83], v[214:217], v[188:191], v[80:83]
	v_mfma_f32_16x16x32_bf16 v[68:71], v[206:209], v[198:201], v[68:71]
	v_mfma_f32_16x16x32_bf16 v[64:67], v[214:217], v[198:201], v[64:67]
	s_setprio 0
	s_mov_b32 m0, s24
	v_lshl_add_u64 v[220:221], s[14:15], 0, v[134:135]
	s_barrier
	ds_read_b128 v[168:171], v150 offset:16384
	ds_read_b128 v[172:175], v150 offset:17408
	ds_read_b128 v[176:179], v150 offset:18432
	ds_read_b128 v[180:183], v150 offset:19456
	ds_read_b128 v[184:187], v150 offset:20480
	ds_read_b128 v[188:191], v150 offset:21504
	ds_read_b128 v[192:195], v150 offset:22528
	ds_read_b128 v[198:201], v150 offset:23552
	global_load_lds_dwordx4 v[220:221], off
	v_lshl_add_u64 v[222:223], s[14:15], 0, v[130:131]
	s_mov_b32 m0, s25
	s_nop 0
	global_load_lds_dwordx4 v[222:223], off
	s_barrier
	s_setprio 1
	s_waitcnt lgkmcnt(7)
	v_mfma_f32_16x16x32_bf16 v[60:63], v[152:155], v[168:171], v[60:63]
	v_mfma_f32_16x16x32_bf16 v[56:59], v[160:163], v[168:171], v[56:59]
	s_waitcnt lgkmcnt(5)
	v_mfma_f32_16x16x32_bf16 v[44:47], v[152:155], v[176:179], v[44:47]
	v_mfma_f32_16x16x32_bf16 v[40:43], v[160:163], v[176:179], v[40:43]
	s_waitcnt lgkmcnt(3)
	v_mfma_f32_16x16x32_bf16 v[28:31], v[152:155], v[184:187], v[28:31]
	v_mfma_f32_16x16x32_bf16 v[24:27], v[160:163], v[184:187], v[24:27]
	s_waitcnt lgkmcnt(1)
	v_mfma_f32_16x16x32_bf16 v[12:15], v[152:155], v[192:195], v[12:15]
	v_mfma_f32_16x16x32_bf16 v[8:11], v[160:163], v[192:195], v[8:11]
	v_mfma_f32_16x16x32_bf16 v[60:63], v[156:159], v[172:175], v[60:63]
	v_mfma_f32_16x16x32_bf16 v[56:59], v[164:167], v[172:175], v[56:59]
	v_mfma_f32_16x16x32_bf16 v[44:47], v[156:159], v[180:183], v[44:47]
	v_mfma_f32_16x16x32_bf16 v[40:43], v[164:167], v[180:183], v[40:43]
	v_mfma_f32_16x16x32_bf16 v[28:31], v[156:159], v[188:191], v[28:31]
	v_mfma_f32_16x16x32_bf16 v[24:27], v[164:167], v[188:191], v[24:27]
	s_waitcnt lgkmcnt(0)
	v_mfma_f32_16x16x32_bf16 v[12:15], v[156:159], v[198:201], v[12:15]
	v_mfma_f32_16x16x32_bf16 v[8:11], v[164:167], v[198:201], v[8:11]
	s_setprio 0
	s_barrier
; #define PG8_STAGE(bufoff, gbase, voff) do { _Pragma("unroll") for (int _i = 0; _i < 2; ++_i) \
;         __builtin_amdgcn_global_load_lds((const unsigned*)((const char*)(gbase) + (voff)[_i]), (LAS unsigned*)(lds + (bufoff) + ldsw + _i * 8192), 16, 0, 0); } while (0)
; #define PG8_LDA(dst, b, h) do { _Pragma("unroll") for (int m = 0; m < 4; ++m) _Pragma("unroll") for (int k = 0; k < 2; ++k) dst[m][k] = *(const LAS bf16x8*)(lds + PG8_SA(b, h) + aoff + m * 2048 + k * 1024); } while (0)
; #define PG8_LDB(dst, b, h) do { _Pragma("unroll") for (int n = 0; n < 2; ++n) _Pragma("unroll") for (int k = 0; k < 2; ++k) dst[n][k] = *(const LAS bf16x8*)(lds + PG8_SB(b, h) + boff + n * 2048 + k * 1024); } while (0)
; #define PG8_MMA(ai, bj, At, Bt) do { __builtin_amdgcn_s_setprio(1); _Pragma("unroll") for (int m = 0; m < 4; ++m) _Pragma("unroll") for (int n = 0; n < 2; ++n) _Pragma("unroll") for (int k = 0; k < 2; ++k) \
;         acc[ai][bj][m][n] = __builtin_amdgcn_mfma_f32_16x16x32_bf16(Bt[n][k], At[m][k], acc[ai][bj][m][n], 0, 0, 0); __builtin_amdgcn_s_setprio(0); } while (0)
; #define PG8_WAIT_V(n) asm volatile("s_waitcnt vmcnt(" #n ")" ::: "memory")
; #define PG8_WAIT_L(n) asm volatile("s_waitcnt lgkmcnt(" #n ")" ::: "memory")
; #define PG8_BAR __builtin_amdgcn_s_barrier()
; #define PG8_SCHED __builtin_amdgcn_sched_barrier(0)
; template <class Map, class Epi>
; DI void gemm_phase(LAS unsigned char* lds, const Map& MP, const Epi& E, const int nM, const int nN, const int K, const int lda, const int ldb) {
;     ...
;             PG8_WAIT_V(6); PG8_BAR; PG8_MMA(1, 1, At, B1); PG8_BAR;
;             PG8_LDB(B0, 1, 0); PG8_SCHED; PG8_LDA(At, 1, 0); PG8_STAGE(PG8_SA(0, 1), a2 + hstepA, voffA);
;             PG8_WAIT_L(8); PG8_BAR; PG8_WAIT_L(0); PG8_MMA(0, 0, At, B0); PG8_BAR; PG8_SCHED;
;             PG8_LDB(B1, 1, 1); PG8_STAGE(PG8_SB(1, 0), b3, voffB);
;             PG8_BAR; PG8_WAIT_L(0); PG8_MMA(0, 1, At, B1); PG8_BAR;
;             PG8_LDA(At, 1, 1); PG8_STAGE(PG8_SA(1, 0), a3, voffA);
;             PG8_BAR; PG8_WAIT_L(0); PG8_MMA(1, 0, At, B0); PG8_BAR; PG8_SCHED;
	s_add_u32 s8, s12, 0x160000
	s_addc_u32 s9, s13, 0
	s_add_i32 s39, s36, s22
	v_lshl_add_u64 v[152:153], s[8:9], 0, v[132:133]
	s_mov_b32 m0, s39
	s_nop 0
	global_load_lds_dwordx4 v[152:153], off
	v_lshl_add_u64 v[152:153], s[8:9], 0, v[128:129]
	s_add_i32 m0, s39, 0x2000
	s_nop 0
	global_load_lds_dwordx4 v[152:153], off
	s_waitcnt vmcnt(6)
	s_barrier
	s_setprio 1
	v_mfma_f32_16x16x32_bf16 v[52:55], v[202:205], v[168:171], v[52:55]
	v_mfma_f32_16x16x32_bf16 v[48:51], v[210:213], v[168:171], v[48:51]
	v_mfma_f32_16x16x32_bf16 v[36:39], v[202:205], v[176:179], v[36:39]
	v_mfma_f32_16x16x32_bf16 v[32:35], v[210:213], v[176:179], v[32:35]
	v_mfma_f32_16x16x32_bf16 v[20:23], v[202:205], v[184:187], v[20:23]
	v_mfma_f32_16x16x32_bf16 v[16:19], v[210:213], v[184:187], v[16:19]
	v_mfma_f32_16x16x32_bf16 v[4:7], v[202:205], v[192:195], v[4:7]
	v_mfma_f32_16x16x32_bf16 v[0:3], v[210:213], v[192:195], v[0:3]
	v_mfma_f32_16x16x32_bf16 v[52:55], v[206:209], v[172:175], v[52:55]
	v_mfma_f32_16x16x32_bf16 v[48:51], v[214:217], v[172:175], v[48:51]
	v_mfma_f32_16x16x32_bf16 v[36:39], v[206:209], v[180:183], v[36:39]
	v_mfma_f32_16x16x32_bf16 v[32:35], v[214:217], v[180:183], v[32:35]
	v_mfma_f32_16x16x32_bf16 v[20:23], v[206:209], v[188:191], v[20:23]
	v_mfma_f32_16x16x32_bf16 v[16:19], v[214:217], v[188:191], v[16:19]
	v_mfma_f32_16x16x32_bf16 v[4:7], v[206:209], v[198:201], v[4:7]
	v_mfma_f32_16x16x32_bf16 v[0:3], v[214:217], v[198:201], v[0:3]
	s_setprio 0
	s_add_i32 s39, 0, 0x18000
	v_add_u32_e32 v164, s39, v148
	s_barrier
	ds_read_b128 v[152:155], v164
	ds_read_b128 v[156:159], v164 offset:1024
	ds_read_b128 v[160:163], v164 offset:2048
	ds_read_b128 v[164:167], v164 offset:3072
	s_add_u32 s8, s14, 0x160000
	s_addc_u32 s9, s15, 0
	s_mov_b32 m0, s26
	v_lshl_add_u64 v[202:203], s[8:9], 0, v[134:135]
	ds_read_b128 v[168:171], v150 offset:32768
	ds_read_b128 v[172:175], v150 offset:33792
	ds_read_b128 v[176:179], v150 offset:34816
	ds_read_b128 v[180:183], v150 offset:35840
	ds_read_b128 v[184:187], v150 offset:36864
	ds_read_b128 v[188:191], v150 offset:37888
	ds_read_b128 v[192:195], v150 offset:38912
	ds_read_b128 v[198:201], v150 offset:39936
	global_load_lds_dwordx4 v[202:203], off
	v_lshl_add_u64 v[202:203], s[8:9], 0, v[130:131]
	s_mov_b32 m0, s27
	s_nop 0
	global_load_lds_dwordx4 v[202:203], off
	s_waitcnt lgkmcnt(8)
	s_barrier
	s_setprio 1
	s_waitcnt lgkmcnt(7)
	v_mfma_f32_16x16x32_bf16 v[124:127], v[152:155], v[168:171], v[124:127]
	v_mfma_f32_16x16x32_bf16 v[120:123], v[160:163], v[168:171], v[120:123]
	s_waitcnt lgkmcnt(5)
	v_mfma_f32_16x16x32_bf16 v[108:111], v[152:155], v[176:179], v[108:111]
	v_mfma_f32_16x16x32_bf16 v[104:107], v[160:163], v[176:179], v[104:107]
	s_waitcnt lgkmcnt(3)
	v_mfma_f32_16x16x32_bf16 v[92:95], v[152:155], v[184:187], v[92:95]
	v_mfma_f32_16x16x32_bf16 v[88:91], v[160:163], v[184:187], v[88:91]
	s_waitcnt lgkmcnt(1)
	v_mfma_f32_16x16x32_bf16 v[76:79], v[152:155], v[192:195], v[76:79]
	v_mfma_f32_16x16x32_bf16 v[72:75], v[160:163], v[192:195], v[72:75]
	v_mfma_f32_16x16x32_bf16 v[124:127], v[156:159], v[172:175], v[124:127]
	v_mfma_f32_16x16x32_bf16 v[120:123], v[164:167], v[172:175], v[120:123]
	v_mfma_f32_16x16x32_bf16 v[108:111], v[156:159], v[180:183], v[108:111]
	v_mfma_f32_16x16x32_bf16 v[104:107], v[164:167], v[180:183], v[104:107]
	v_mfma_f32_16x16x32_bf16 v[92:95], v[156:159], v[188:191], v[92:95]
	v_mfma_f32_16x16x32_bf16 v[88:91], v[164:167], v[188:191], v[88:91]
	s_waitcnt lgkmcnt(0)
	v_mfma_f32_16x16x32_bf16 v[76:79], v[156:159], v[198:201], v[76:79]
	v_mfma_f32_16x16x32_bf16 v[72:75], v[164:167], v[198:201], v[72:75]
	s_setprio 0
	s_barrier
	s_add_i32 s14, 0, 0x1c000
	s_add_i32 s8, s39, s22
	v_add_u32_e32 v196, s14, v148
	v_lshl_add_u64 v[144:145], v[144:145], 0, s[52:53]
	s_mov_b32 m0, s8
	ds_read_b128 v[202:205], v196
	ds_read_b128 v[206:209], v196 offset:1024
	ds_read_b128 v[210:213], v196 offset:2048
	ds_read_b128 v[214:217], v196 offset:3072
	global_load_lds_dwordx4 v[144:145], off
	v_lshl_add_u64 v[144:145], v[218:219], 0, s[52:53]
	s_add_i32 m0, s8, 0x2000
	s_nop 0
	global_load_lds_dwordx4 v[144:145], off
	s_barrier
	s_setprio 1
	s_waitcnt lgkmcnt(3)
	v_mfma_f32_16x16x32_bf16 v[116:119], v[202:205], v[168:171], v[116:119]
	s_waitcnt lgkmcnt(1)
	v_mfma_f32_16x16x32_bf16 v[112:115], v[210:213], v[168:171], v[112:115]
	v_mfma_f32_16x16x32_bf16 v[100:103], v[202:205], v[176:179], v[100:103]
	v_mfma_f32_16x16x32_bf16 v[96:99], v[210:213], v[176:179], v[96:99]
	v_mfma_f32_16x16x32_bf16 v[84:87], v[202:205], v[184:187], v[84:87]
	v_mfma_f32_16x16x32_bf16 v[80:83], v[210:213], v[184:187], v[80:83]
	v_mfma_f32_16x16x32_bf16 v[68:71], v[202:205], v[192:195], v[68:71]
	v_mfma_f32_16x16x32_bf16 v[64:67], v[210:213], v[192:195], v[64:67]
	v_mfma_f32_16x16x32_bf16 v[116:119], v[206:209], v[172:175], v[116:119]
	s_waitcnt lgkmcnt(0)
	v_mfma_f32_16x16x32_bf16 v[112:115], v[214:217], v[172:175], v[112:115]
	v_mfma_f32_16x16x32_bf16 v[100:103], v[206:209], v[180:183], v[100:103]
	v_mfma_f32_16x16x32_bf16 v[96:99], v[214:217], v[180:183], v[96:99]
	v_mfma_f32_16x16x32_bf16 v[84:87], v[206:209], v[188:191], v[84:87]
	v_mfma_f32_16x16x32_bf16 v[80:83], v[214:217], v[188:191], v[80:83]
	v_mfma_f32_16x16x32_bf16 v[68:71], v[206:209], v[198:201], v[68:71]
	v_mfma_f32_16x16x32_bf16 v[64:67], v[214:217], v[198:201], v[64:67]
	s_setprio 0
	s_mov_b32 m0, s30
	v_lshl_add_u64 v[144:145], v[220:221], 0, s[52:53]
	s_barrier
; DI unsigned pack2(float a, float b) { f32x2 v = {a, b}; hwbf16x2 r = __builtin_convertvector(v, hwbf16x2); return __builtin_bit_cast(unsigned, r); }
; DI float bflo(unsigned w) { return __uint_as_float(w << 16); }
; DI float bfhi(unsigned w) { return __uint_as_float(w & 0xffff0000u); }
; #define PG8_STAGE(bufoff, gbase, voff) do { _Pragma("unroll") for (int _i = 0; _i < 2; ++_i) \
;         __builtin_amdgcn_global_load_lds((const unsigned*)((const char*)(gbase) + (voff)[_i]), (LAS unsigned*)(lds + (bufoff) + ldsw + _i * 8192), 16, 0, 0); } while (0)
; #define PG8_WAIT_V(n) asm volatile("s_waitcnt vmcnt(" #n ")" ::: "memory")
; #define PG8_WAIT_L(n) asm volatile("s_waitcnt lgkmcnt(" #n ")" ::: "memory")
;     DI void operator()(const f32x4 (&acc)[2][2][4][2], const Unit& u, int wr, int wc, int fr, int fq) const {
;     ...
;         for (int ai = 0; ai < 2; ++ai)
; #pragma unroll
;             for (int m = 0; m < 4; ++m) { const size_t ro = (size_t)(row0 + ai * HALF + m * 16) * D + col0;
; #pragma unroll
;                 for (int bj = 0; bj < 2; ++bj) {
;                     f32x4 x0, x1;
;                     if constexpr (IB) { const u32x4 w = *(const u32x4*)((const bf16_t*)Xin + ro + bj * HALF);
;                         x0 = (f32x4){bflo(w[0]), bfhi(w[0]), bflo(w[1]), bfhi(w[1])}; x1 = (f32x4){bflo(w[2]), bfhi(w[2]), bflo(w[3]), bfhi(w[3])}; }
;                     else { x0 = *(const f32x4*)((const float*)Xin + ro + bj * HALF); x1 = *(const f32x4*)((const float*)Xin + ro + bj * HALF + 4); }
;                     x0 += acc[ai][bj][m][0] * sc[bj][0]; x1 += acc[ai][bj][m][1] * sc[bj][1];
;                     if constexpr (OB) { u32x4 o; o[0] = pack2(x0[0], x0[1]); o[1] = pack2(x0[2], x0[3]); o[2] = pack2(x1[0], x1[1]); o[3] = pack2(x1[2], x1[3]);
;                         *(u32x4*)((bf16_t*)Xout + ro + bj * HALF) = o; }
;                     else { *(f32x4*)((float*)Xout + ro + bj * HALF) = x0; *(f32x4*)((float*)Xout + ro + bj * HALF + 4) = x1; } } }
; template <class Map, class Epi>
; DI void gemm_phase(LAS unsigned char* lds, const Map& MP, const Epi& E, const int nM, const int nN, const int K, const int lda, const int ldb) {
;     ...
;             PG8_BAR; PG8_WAIT_L(0); PG8_MMA(1, 0, At, B0); PG8_BAR; PG8_SCHED;
;             PG8_STAGE(PG8_SB(1, 1), b3 + hstepB, voffB);
;             PG8_WAIT_V(6); PG8_BAR; PG8_MMA(1, 1, At, B1); PG8_BAR;
	ds_read_b128 v[168:171], v150 offset:49152
	ds_read_b128 v[172:175], v150 offset:50176
	ds_read_b128 v[176:179], v150 offset:51200
	ds_read_b128 v[180:183], v150 offset:52224
	ds_read_b128 v[184:187], v150 offset:53248
	ds_read_b128 v[188:191], v150 offset:54272
	ds_read_b128 v[192:195], v150 offset:55296
	ds_read_b128 v[198:201], v150 offset:56320
	global_load_lds_dwordx4 v[144:145], off
	v_lshl_add_u64 v[144:145], v[222:223], 0, s[52:53]
	s_mov_b32 m0, s31
	s_nop 0
	global_load_lds_dwordx4 v[144:145], off
	s_barrier
	s_setprio 1
	s_waitcnt lgkmcnt(7)
	v_mfma_f32_16x16x32_bf16 v[60:63], v[152:155], v[168:171], v[60:63]
	v_mfma_f32_16x16x32_bf16 v[56:59], v[160:163], v[168:171], v[56:59]
	s_waitcnt lgkmcnt(5)
	v_mfma_f32_16x16x32_bf16 v[44:47], v[152:155], v[176:179], v[44:47]
	v_mfma_f32_16x16x32_bf16 v[40:43], v[160:163], v[176:179], v[40:43]
	s_waitcnt lgkmcnt(3)
	v_mfma_f32_16x16x32_bf16 v[28:31], v[152:155], v[184:187], v[28:31]
	v_mfma_f32_16x16x32_bf16 v[24:27], v[160:163], v[184:187], v[24:27]
	s_waitcnt lgkmcnt(1)
	v_mfma_f32_16x16x32_bf16 v[12:15], v[152:155], v[192:195], v[12:15]
	v_mfma_f32_16x16x32_bf16 v[8:11], v[160:163], v[192:195], v[8:11]
	v_mfma_f32_16x16x32_bf16 v[60:63], v[156:159], v[172:175], v[60:63]
	v_mfma_f32_16x16x32_bf16 v[56:59], v[164:167], v[172:175], v[56:59]
	v_mfma_f32_16x16x32_bf16 v[44:47], v[156:159], v[180:183], v[44:47]
	v_mfma_f32_16x16x32_bf16 v[40:43], v[164:167], v[180:183], v[40:43]
	v_mfma_f32_16x16x32_bf16 v[28:31], v[156:159], v[188:191], v[28:31]
	v_mfma_f32_16x16x32_bf16 v[24:27], v[164:167], v[188:191], v[24:27]
	s_waitcnt lgkmcnt(0)
	v_mfma_f32_16x16x32_bf16 v[12:15], v[156:159], v[198:201], v[12:15]
	v_mfma_f32_16x16x32_bf16 v[8:11], v[164:167], v[198:201], v[8:11]
	s_setprio 0
	s_barrier
	s_add_u32 s8, s12, 0x160080
	s_addc_u32 s9, s13, 0
	s_add_i32 s12, s14, s22
	v_lshl_add_u64 v[144:145], s[8:9], 0, v[132:133]
	s_mov_b32 m0, s12
	s_nop 0
	global_load_lds_dwordx4 v[144:145], off
	v_lshl_add_u64 v[144:145], s[8:9], 0, v[128:129]
	s_add_i32 m0, s12, 0x2000
	s_nop 0
	global_load_lds_dwordx4 v[144:145], off
	s_waitcnt vmcnt(6)
	s_barrier
	s_setprio 1
	v_mfma_f32_16x16x32_bf16 v[52:55], v[202:205], v[168:171], v[52:55]
	v_mfma_f32_16x16x32_bf16 v[48:51], v[210:213], v[168:171], v[48:51]
	v_mfma_f32_16x16x32_bf16 v[36:39], v[202:205], v[176:179], v[36:39]
	v_mfma_f32_16x16x32_bf16 v[32:35], v[210:213], v[176:179], v[32:35]
	v_mfma_f32_16x16x32_bf16 v[20:23], v[202:205], v[184:187], v[20:23]
	v_mfma_f32_16x16x32_bf16 v[16:19], v[210:213], v[184:187], v[16:19]
	v_mfma_f32_16x16x32_bf16 v[4:7], v[202:205], v[192:195], v[4:7]
	v_mfma_f32_16x16x32_bf16 v[0:3], v[210:213], v[192:195], v[0:3]
	v_mfma_f32_16x16x32_bf16 v[52:55], v[206:209], v[172:175], v[52:55]
	v_mfma_f32_16x16x32_bf16 v[48:51], v[214:217], v[172:175], v[48:51]
	v_mfma_f32_16x16x32_bf16 v[36:39], v[206:209], v[180:183], v[36:39]
	v_mfma_f32_16x16x32_bf16 v[32:35], v[214:217], v[180:183], v[32:35]
	v_mfma_f32_16x16x32_bf16 v[20:23], v[206:209], v[188:191], v[20:23]
	v_mfma_f32_16x16x32_bf16 v[16:19], v[214:217], v[188:191], v[16:19]
	v_mfma_f32_16x16x32_bf16 v[4:7], v[206:209], v[198:201], v[4:7]
	v_mfma_f32_16x16x32_bf16 v[0:3], v[214:217], v[198:201], v[0:3]
	s_setprio 0
	s_add_i32 s3, s3, 2
	s_add_u32 s5, s5, 0x100
	s_addc_u32 s38, s38, 0
	s_cmpk_gt_u32 s3, 0x55
	s_mov_b64 s[8:9], s[10:11]
	s_barrier
	s_cbranch_scc0 .LBB1_550
	v_mov_b32_e32 v144, v146
	v_mov_b32_e32 v152, v147
	s_lshl_b32 s2, s2, 8
	s_add_i32 s2, s2, s29
	s_lshl_b32 s3, s4, 8
	v_add_u32_e32 v152, s2, v152
	s_or_b32 s3, s3, s54
	v_ashrrev_i32_e32 v153, 31, v152
	v_lshl_add_u32 v144, v144, 3, s3
	v_lshlrev_b64 v[152:153], 12, v[152:153]
	v_ashrrev_i32_e32 v145, 31, v144
	v_lshl_add_u64 v[152:153], s[46:47], 0, v[152:153]
	v_lshl_add_u64 v[144:145], v[144:145], 1, v[152:153]
	global_load_dwordx4 v[152:155], v[144:145], off
	s_mov_b64 s[2:3], 0x10000
	s_mov_b32 s4, s37
	s_mov_b64 s[10:11], s[6:7]
	s_mov_b64 s[8:9], s[42:43]
	s_waitcnt vmcnt(0) lgkmcnt(0)
	v_lshlrev_b32_e32 v156, 16, v152
	v_and_b32_e32 v157, 0xffff0000, v152
	v_lshlrev_b32_e32 v152, 16, v153
	v_and_b32_e32 v153, 0xffff0000, v153
	v_lshlrev_b32_e32 v158, 16, v154
	v_and_b32_e32 v159, 0xffff0000, v154
	v_lshlrev_b32_e32 v154, 16, v155
	v_and_b32_e32 v155, 0xffff0000, v155
	v_pk_add_f32 v[126:127], v[126:127], v[152:153]
	v_pk_add_f32 v[124:125], v[124:125], v[156:157]
	v_pk_add_f32 v[152:153], v[122:123], v[154:155]
	v_pk_add_f32 v[122:123], v[120:121], v[158:159]
	v_cvt_pk_bf16_f32 v120, v124, v125
	v_cvt_pk_bf16_f32 v121, v126, v127
	v_cvt_pk_bf16_f32 v122, v122, v123
	v_cvt_pk_bf16_f32 v123, v152, v153
	global_store_dwordx4 v[144:145], v[120:123], off
	global_load_dwordx4 v[120:123], v[144:145], off offset:256
	s_waitcnt vmcnt(0) lgkmcnt(0)
	v_lshlrev_b32_e32 v124, 16, v120
	v_and_b32_e32 v125, 0xffff0000, v120
	v_lshlrev_b32_e32 v120, 16, v121
	v_and_b32_e32 v121, 0xffff0000, v121
	v_lshlrev_b32_e32 v126, 16, v122
	v_and_b32_e32 v127, 0xffff0000, v122
	v_lshlrev_b32_e32 v122, 16, v123
	v_and_b32_e32 v123, 0xffff0000, v123
	v_pk_add_f32 v[116:117], v[116:117], v[124:125]
	v_pk_add_f32 v[118:119], v[118:119], v[120:121]
	v_pk_add_f32 v[120:121], v[114:115], v[122:123]
	v_pk_add_f32 v[114:115], v[112:113], v[126:127]
	v_cvt_pk_bf16_f32 v112, v116, v117
	v_lshl_add_u64 v[116:117], v[144:145], 0, s[2:3]
	s_mov_b32 s2, 0x10000
	v_cvt_pk_bf16_f32 v113, v118, v119
	v_add_co_u32_e32 v118, vcc, s2, v144
	v_cvt_pk_bf16_f32 v114, v114, v115
	v_cvt_pk_bf16_f32 v115, v120, v121
	v_addc_co_u32_e32 v119, vcc, 0, v145, vcc
	global_store_dwordx4 v[144:145], v[112:115], off offset:256
	global_load_dwordx4 v[112:115], v[118:119], off
	s_mov_b64 s[2:3], 0x20000
	s_waitcnt vmcnt(0) lgkmcnt(0)
; DI unsigned pack2(float a, float b) { f32x2 v = {a, b}; hwbf16x2 r = __builtin_convertvector(v, hwbf16x2); return __builtin_bit_cast(unsigned, r); }
; DI float bflo(unsigned w) { return __uint_as_float(w << 16); }
; DI float bfhi(unsigned w) { return __uint_as_float(w & 0xffff0000u); }
;     DI void operator()(const f32x4 (&acc)[2][2][4][2], const Unit& u, int wr, int wc, int fr, int fq) const {
;     ...
;         for (int ai = 0; ai < 2; ++ai)
; #pragma unroll
;             for (int m = 0; m < 4; ++m) { const size_t ro = (size_t)(row0 + ai * HALF + m * 16) * D + col0;
; #pragma unroll
;                 for (int bj = 0; bj < 2; ++bj) {
;                     f32x4 x0, x1;
;                     if constexpr (IB) { const u32x4 w = *(const u32x4*)((const bf16_t*)Xin + ro + bj * HALF);
;                         x0 = (f32x4){bflo(w[0]), bfhi(w[0]), bflo(w[1]), bfhi(w[1])}; x1 = (f32x4){bflo(w[2]), bfhi(w[2]), bflo(w[3]), bfhi(w[3])}; }
;                     else { x0 = *(const f32x4*)((const float*)Xin + ro + bj * HALF); x1 = *(const f32x4*)((const float*)Xin + ro + bj * HALF + 4); }
;                     x0 += acc[ai][bj][m][0] * sc[bj][0]; x1 += acc[ai][bj][m][1] * sc[bj][1];
;                     if constexpr (OB) { u32x4 o; o[0] = pack2(x0[0], x0[1]); o[1] = pack2(x0[2], x0[3]); o[2] = pack2(x1[0], x1[1]); o[3] = pack2(x1[2], x1[3]);
;                         *(u32x4*)((bf16_t*)Xout + ro + bj * HALF) = o; }
;                     else { *(f32x4*)((float*)Xout + ro + bj * HALF) = x0; *(f32x4*)((float*)Xout + ro + bj * HALF + 4) = x1; } } }
	v_lshlrev_b32_e32 v120, 16, v112
	v_and_b32_e32 v121, 0xffff0000, v112
	v_lshlrev_b32_e32 v112, 16, v113
	v_and_b32_e32 v113, 0xffff0000, v113
	v_lshlrev_b32_e32 v122, 16, v114
	v_and_b32_e32 v123, 0xffff0000, v114
	v_lshlrev_b32_e32 v114, 16, v115
	v_and_b32_e32 v115, 0xffff0000, v115
	v_pk_add_f32 v[110:111], v[110:111], v[112:113]
	v_pk_add_f32 v[108:109], v[108:109], v[120:121]
	v_pk_add_f32 v[112:113], v[106:107], v[114:115]
	v_pk_add_f32 v[106:107], v[104:105], v[122:123]
	v_cvt_pk_bf16_f32 v104, v108, v109
	v_cvt_pk_bf16_f32 v105, v110, v111
	v_cvt_pk_bf16_f32 v106, v106, v107
	v_cvt_pk_bf16_f32 v107, v112, v113
	global_store_dwordx4 v[118:119], v[104:107], off
	global_load_dwordx4 v[104:107], v[116:117], off offset:256
	s_waitcnt vmcnt(0) lgkmcnt(0)
	v_lshlrev_b32_e32 v108, 16, v104
	v_and_b32_e32 v109, 0xffff0000, v104
	v_lshlrev_b32_e32 v104, 16, v105
	v_and_b32_e32 v105, 0xffff0000, v105
	v_lshlrev_b32_e32 v110, 16, v106
	v_and_b32_e32 v111, 0xffff0000, v106
	v_lshlrev_b32_e32 v106, 16, v107
	v_and_b32_e32 v107, 0xffff0000, v107
	v_pk_add_f32 v[100:101], v[100:101], v[108:109]
	v_pk_add_f32 v[102:103], v[102:103], v[104:105]
	v_pk_add_f32 v[104:105], v[98:99], v[106:107]
	v_pk_add_f32 v[98:99], v[96:97], v[110:111]
	v_cvt_pk_bf16_f32 v96, v100, v101
	v_lshl_add_u64 v[100:101], v[144:145], 0, s[2:3]
	s_mov_b32 s2, 0x20000
	v_cvt_pk_bf16_f32 v97, v102, v103
	v_add_co_u32_e32 v102, vcc, s2, v144
	v_cvt_pk_bf16_f32 v98, v98, v99
	v_cvt_pk_bf16_f32 v99, v104, v105
	v_addc_co_u32_e32 v103, vcc, 0, v145, vcc
	global_store_dwordx4 v[116:117], v[96:99], off offset:256
	global_load_dwordx4 v[96:99], v[102:103], off
	s_mov_b64 s[2:3], 0x30000
	s_waitcnt vmcnt(0) lgkmcnt(0)
	v_lshlrev_b32_e32 v104, 16, v96
	v_and_b32_e32 v105, 0xffff0000, v96
	v_lshlrev_b32_e32 v96, 16, v97
	v_and_b32_e32 v97, 0xffff0000, v97
	v_lshlrev_b32_e32 v106, 16, v98
	v_and_b32_e32 v107, 0xffff0000, v98
	v_lshlrev_b32_e32 v98, 16, v99
	v_and_b32_e32 v99, 0xffff0000, v99
	v_pk_add_f32 v[94:95], v[94:95], v[96:97]
	v_pk_add_f32 v[92:93], v[92:93], v[104:105]
	v_pk_add_f32 v[96:97], v[90:91], v[98:99]
	v_pk_add_f32 v[90:91], v[88:89], v[106:107]
	v_cvt_pk_bf16_f32 v88, v92, v93
	v_cvt_pk_bf16_f32 v89, v94, v95
	v_cvt_pk_bf16_f32 v90, v90, v91
	v_cvt_pk_bf16_f32 v91, v96, v97
	global_store_dwordx4 v[102:103], v[88:91], off
	global_load_dwordx4 v[88:91], v[100:101], off offset:256
	s_waitcnt vmcnt(0) lgkmcnt(0)
	v_lshlrev_b32_e32 v92, 16, v88
	v_and_b32_e32 v93, 0xffff0000, v88
	v_lshlrev_b32_e32 v88, 16, v89
	v_and_b32_e32 v89, 0xffff0000, v89
	v_lshlrev_b32_e32 v94, 16, v90
	v_and_b32_e32 v95, 0xffff0000, v90
	v_lshlrev_b32_e32 v90, 16, v91
	v_and_b32_e32 v91, 0xffff0000, v91
	v_pk_add_f32 v[86:87], v[86:87], v[88:89]
	v_pk_add_f32 v[84:85], v[84:85], v[92:93]
	v_pk_add_f32 v[88:89], v[82:83], v[90:91]
	v_pk_add_f32 v[82:83], v[80:81], v[94:95]
	v_cvt_pk_bf16_f32 v80, v84, v85
	v_cvt_pk_bf16_f32 v81, v86, v87
	v_cvt_pk_bf16_f32 v82, v82, v83
	v_cvt_pk_bf16_f32 v83, v88, v89
	global_store_dwordx4 v[100:101], v[80:83], off offset:256
	s_nop 1
	v_lshl_add_u64 v[80:81], v[144:145], 0, s[2:3]
	s_mov_b32 s2, 0x30000
	v_add_co_u32_e32 v86, vcc, s2, v144
	s_mov_b64 s[2:3], 0x80000
	s_nop 0
	v_addc_co_u32_e32 v87, vcc, 0, v145, vcc
	global_load_dwordx4 v[82:85], v[86:87], off
	s_waitcnt vmcnt(0) lgkmcnt(0)
	v_lshlrev_b32_e32 v88, 16, v82
	v_and_b32_e32 v89, 0xffff0000, v82
	v_lshlrev_b32_e32 v82, 16, v83
	v_and_b32_e32 v83, 0xffff0000, v83
	v_lshlrev_b32_e32 v90, 16, v84
	v_and_b32_e32 v91, 0xffff0000, v84
	v_lshlrev_b32_e32 v84, 16, v85
	v_and_b32_e32 v85, 0xffff0000, v85
	v_pk_add_f32 v[78:79], v[78:79], v[82:83]
	v_pk_add_f32 v[76:77], v[76:77], v[88:89]
	v_pk_add_f32 v[82:83], v[74:75], v[84:85]
	v_pk_add_f32 v[74:75], v[72:73], v[90:91]
	v_cvt_pk_bf16_f32 v72, v76, v77
	v_cvt_pk_bf16_f32 v73, v78, v79
	v_cvt_pk_bf16_f32 v74, v74, v75
	v_cvt_pk_bf16_f32 v75, v82, v83
	global_store_dwordx4 v[86:87], v[72:75], off
	global_load_dwordx4 v[72:75], v[80:81], off offset:256
	s_waitcnt vmcnt(0) lgkmcnt(0)
	v_lshlrev_b32_e32 v76, 16, v72
	v_and_b32_e32 v77, 0xffff0000, v72
	v_lshlrev_b32_e32 v72, 16, v73
	v_and_b32_e32 v73, 0xffff0000, v73
	v_lshlrev_b32_e32 v78, 16, v74
	v_and_b32_e32 v79, 0xffff0000, v74
	v_lshlrev_b32_e32 v74, 16, v75
	v_and_b32_e32 v75, 0xffff0000, v75
	v_pk_add_f32 v[70:71], v[70:71], v[72:73]
	v_pk_add_f32 v[68:69], v[68:69], v[76:77]
	v_pk_add_f32 v[72:73], v[66:67], v[74:75]
	v_pk_add_f32 v[66:67], v[64:65], v[78:79]
	v_cvt_pk_bf16_f32 v64, v68, v69
	v_cvt_pk_bf16_f32 v65, v70, v71
	v_cvt_pk_bf16_f32 v66, v66, v67
	v_cvt_pk_bf16_f32 v67, v72, v73
	global_store_dwordx4 v[80:81], v[64:67], off offset:256
	s_nop 1
	v_lshl_add_u64 v[64:65], v[144:145], 0, s[2:3]
	s_mov_b32 s2, 0x80000
	v_add_co_u32_e32 v70, vcc, s2, v144
	s_mov_b64 s[2:3], 0x90000
	s_nop 0
	v_addc_co_u32_e32 v71, vcc, 0, v145, vcc
	global_load_dwordx4 v[66:69], v[70:71], off
	s_waitcnt vmcnt(0) lgkmcnt(0)
	v_lshlrev_b32_e32 v72, 16, v66
	v_and_b32_e32 v73, 0xffff0000, v66
	v_lshlrev_b32_e32 v66, 16, v67
	v_and_b32_e32 v67, 0xffff0000, v67
	v_lshlrev_b32_e32 v74, 16, v68
	v_and_b32_e32 v75, 0xffff0000, v68
	v_lshlrev_b32_e32 v68, 16, v69
	v_and_b32_e32 v69, 0xffff0000, v69
	v_pk_add_f32 v[62:63], v[62:63], v[66:67]
	v_pk_add_f32 v[60:61], v[60:61], v[72:73]
	v_pk_add_f32 v[66:67], v[58:59], v[68:69]
	v_pk_add_f32 v[58:59], v[56:57], v[74:75]
	v_cvt_pk_bf16_f32 v56, v60, v61
	v_cvt_pk_bf16_f32 v57, v62, v63
	v_cvt_pk_bf16_f32 v58, v58, v59
	v_cvt_pk_bf16_f32 v59, v66, v67
	global_store_dwordx4 v[70:71], v[56:59], off
	global_load_dwordx4 v[56:59], v[64:65], off offset:256
	s_waitcnt vmcnt(0) lgkmcnt(0)
; DI unsigned pack2(float a, float b) { f32x2 v = {a, b}; hwbf16x2 r = __builtin_convertvector(v, hwbf16x2); return __builtin_bit_cast(unsigned, r); }
; DI float bflo(unsigned w) { return __uint_as_float(w << 16); }
; DI float bfhi(unsigned w) { return __uint_as_float(w & 0xffff0000u); }
;     DI void operator()(const f32x4 (&acc)[2][2][4][2], const Unit& u, int wr, int wc, int fr, int fq) const {
;     ...
;         for (int ai = 0; ai < 2; ++ai)
; #pragma unroll
;             for (int m = 0; m < 4; ++m) { const size_t ro = (size_t)(row0 + ai * HALF + m * 16) * D + col0;
; #pragma unroll
;                 for (int bj = 0; bj < 2; ++bj) {
;                     f32x4 x0, x1;
;                     if constexpr (IB) { const u32x4 w = *(const u32x4*)((const bf16_t*)Xin + ro + bj * HALF);
;                         x0 = (f32x4){bflo(w[0]), bfhi(w[0]), bflo(w[1]), bfhi(w[1])}; x1 = (f32x4){bflo(w[2]), bfhi(w[2]), bflo(w[3]), bfhi(w[3])}; }
;                     else { x0 = *(const f32x4*)((const float*)Xin + ro + bj * HALF); x1 = *(const f32x4*)((const float*)Xin + ro + bj * HALF + 4); }
;                     x0 += acc[ai][bj][m][0] * sc[bj][0]; x1 += acc[ai][bj][m][1] * sc[bj][1];
;                     if constexpr (OB) { u32x4 o; o[0] = pack2(x0[0], x0[1]); o[1] = pack2(x0[2], x0[3]); o[2] = pack2(x1[0], x1[1]); o[3] = pack2(x1[2], x1[3]);
;                         *(u32x4*)((bf16_t*)Xout + ro + bj * HALF) = o; }
;                     else { *(f32x4*)((float*)Xout + ro + bj * HALF) = x0; *(f32x4*)((float*)Xout + ro + bj * HALF + 4) = x1; } } }
	v_lshlrev_b32_e32 v60, 16, v56
	v_and_b32_e32 v61, 0xffff0000, v56
	v_lshlrev_b32_e32 v56, 16, v57
	v_and_b32_e32 v57, 0xffff0000, v57
	v_lshlrev_b32_e32 v62, 16, v58
	v_and_b32_e32 v63, 0xffff0000, v58
	v_lshlrev_b32_e32 v58, 16, v59
	v_and_b32_e32 v59, 0xffff0000, v59
	v_pk_add_f32 v[54:55], v[54:55], v[56:57]
	v_pk_add_f32 v[52:53], v[52:53], v[60:61]
	v_pk_add_f32 v[56:57], v[50:51], v[58:59]
	v_pk_add_f32 v[50:51], v[48:49], v[62:63]
	v_cvt_pk_bf16_f32 v48, v52, v53
	v_cvt_pk_bf16_f32 v49, v54, v55
	v_cvt_pk_bf16_f32 v50, v50, v51
	v_cvt_pk_bf16_f32 v51, v56, v57
	global_store_dwordx4 v[64:65], v[48:51], off offset:256
	s_nop 1
	v_lshl_add_u64 v[48:49], v[144:145], 0, s[2:3]
	s_mov_b32 s2, 0x90000
	v_add_co_u32_e32 v54, vcc, s2, v144
	s_mov_b64 s[2:3], 0xa0000
	s_nop 0
	v_addc_co_u32_e32 v55, vcc, 0, v145, vcc
	global_load_dwordx4 v[50:53], v[54:55], off
	s_waitcnt vmcnt(0) lgkmcnt(0)
	v_lshlrev_b32_e32 v56, 16, v50
	v_and_b32_e32 v57, 0xffff0000, v50
	v_lshlrev_b32_e32 v50, 16, v51
	v_and_b32_e32 v51, 0xffff0000, v51
	v_lshlrev_b32_e32 v58, 16, v52
	v_and_b32_e32 v59, 0xffff0000, v52
	v_lshlrev_b32_e32 v52, 16, v53
	v_and_b32_e32 v53, 0xffff0000, v53
	v_pk_add_f32 v[46:47], v[46:47], v[50:51]
	v_pk_add_f32 v[44:45], v[44:45], v[56:57]
	v_pk_add_f32 v[50:51], v[42:43], v[52:53]
	v_pk_add_f32 v[42:43], v[40:41], v[58:59]
	v_cvt_pk_bf16_f32 v40, v44, v45
	v_cvt_pk_bf16_f32 v41, v46, v47
	v_cvt_pk_bf16_f32 v42, v42, v43
	v_cvt_pk_bf16_f32 v43, v50, v51
	global_store_dwordx4 v[54:55], v[40:43], off
	global_load_dwordx4 v[40:43], v[48:49], off offset:256
	s_waitcnt vmcnt(0) lgkmcnt(0)
	v_lshlrev_b32_e32 v44, 16, v40
	v_and_b32_e32 v45, 0xffff0000, v40
	v_lshlrev_b32_e32 v40, 16, v41
	v_and_b32_e32 v41, 0xffff0000, v41
	v_lshlrev_b32_e32 v46, 16, v42
	v_and_b32_e32 v47, 0xffff0000, v42
	v_lshlrev_b32_e32 v42, 16, v43
	v_and_b32_e32 v43, 0xffff0000, v43
	v_pk_add_f32 v[38:39], v[38:39], v[40:41]
	v_pk_add_f32 v[36:37], v[36:37], v[44:45]
	v_pk_add_f32 v[40:41], v[34:35], v[42:43]
	v_pk_add_f32 v[34:35], v[32:33], v[46:47]
	v_cvt_pk_bf16_f32 v32, v36, v37
	v_cvt_pk_bf16_f32 v33, v38, v39
	v_cvt_pk_bf16_f32 v34, v34, v35
	v_cvt_pk_bf16_f32 v35, v40, v41
	global_store_dwordx4 v[48:49], v[32:35], off offset:256
	s_nop 1
	v_lshl_add_u64 v[32:33], v[144:145], 0, s[2:3]
	s_mov_b32 s2, 0xa0000
	v_add_co_u32_e32 v38, vcc, s2, v144
	s_mov_b64 s[2:3], 0xb0000
	s_nop 0
	v_addc_co_u32_e32 v39, vcc, 0, v145, vcc
	global_load_dwordx4 v[34:37], v[38:39], off
	s_waitcnt vmcnt(0) lgkmcnt(0)
	v_lshlrev_b32_e32 v40, 16, v34
	v_and_b32_e32 v41, 0xffff0000, v34
	v_lshlrev_b32_e32 v34, 16, v35
	v_and_b32_e32 v35, 0xffff0000, v35
	v_lshlrev_b32_e32 v42, 16, v36
	v_and_b32_e32 v43, 0xffff0000, v36
	v_lshlrev_b32_e32 v36, 16, v37
	v_and_b32_e32 v37, 0xffff0000, v37
	v_pk_add_f32 v[30:31], v[30:31], v[34:35]
	v_pk_add_f32 v[28:29], v[28:29], v[40:41]
	v_pk_add_f32 v[34:35], v[26:27], v[36:37]
	v_pk_add_f32 v[26:27], v[24:25], v[42:43]
	v_cvt_pk_bf16_f32 v24, v28, v29
	v_cvt_pk_bf16_f32 v25, v30, v31
	v_cvt_pk_bf16_f32 v26, v26, v27
	v_cvt_pk_bf16_f32 v27, v34, v35
	global_store_dwordx4 v[38:39], v[24:27], off
	global_load_dwordx4 v[24:27], v[32:33], off offset:256
	s_waitcnt vmcnt(0) lgkmcnt(0)
	v_lshlrev_b32_e32 v28, 16, v24
	v_and_b32_e32 v29, 0xffff0000, v24
	v_lshlrev_b32_e32 v24, 16, v25
	v_and_b32_e32 v25, 0xffff0000, v25
	v_lshlrev_b32_e32 v30, 16, v26
	v_and_b32_e32 v31, 0xffff0000, v26
	v_lshlrev_b32_e32 v26, 16, v27
	v_and_b32_e32 v27, 0xffff0000, v27
	v_pk_add_f32 v[22:23], v[22:23], v[24:25]
	v_pk_add_f32 v[20:21], v[20:21], v[28:29]
	v_pk_add_f32 v[24:25], v[18:19], v[26:27]
	v_pk_add_f32 v[18:19], v[16:17], v[30:31]
	v_cvt_pk_bf16_f32 v16, v20, v21
	v_cvt_pk_bf16_f32 v17, v22, v23
	v_cvt_pk_bf16_f32 v18, v18, v19
	v_cvt_pk_bf16_f32 v19, v24, v25
	global_store_dwordx4 v[32:33], v[16:19], off offset:256
	s_nop 1
	v_lshl_add_u64 v[16:17], v[144:145], 0, s[2:3]
	s_mov_b32 s2, 0xb0000
	v_add_co_u32_e32 v22, vcc, s2, v144
	s_mov_b32 s2, s55
	s_nop 0
	v_addc_co_u32_e32 v23, vcc, 0, v145, vcc
	global_load_dwordx4 v[18:21], v[22:23], off
	s_and_b64 vcc, exec, s[40:41]
	s_waitcnt vmcnt(0) lgkmcnt(0)
	v_lshlrev_b32_e32 v24, 16, v18
	v_and_b32_e32 v25, 0xffff0000, v18
	v_lshlrev_b32_e32 v18, 16, v19
	v_and_b32_e32 v19, 0xffff0000, v19
	v_lshlrev_b32_e32 v26, 16, v20
	v_and_b32_e32 v27, 0xffff0000, v20
	v_lshlrev_b32_e32 v20, 16, v21
	v_and_b32_e32 v21, 0xffff0000, v21
	v_pk_add_f32 v[14:15], v[14:15], v[18:19]
	v_pk_add_f32 v[12:13], v[12:13], v[24:25]
	v_pk_add_f32 v[18:19], v[10:11], v[20:21]
	v_pk_add_f32 v[10:11], v[8:9], v[26:27]
	v_cvt_pk_bf16_f32 v8, v12, v13
	v_cvt_pk_bf16_f32 v9, v14, v15
	v_cvt_pk_bf16_f32 v10, v10, v11
	v_cvt_pk_bf16_f32 v11, v18, v19
	global_store_dwordx4 v[22:23], v[8:11], off
	global_load_dwordx4 v[8:11], v[16:17], off offset:256
	s_waitcnt vmcnt(0) lgkmcnt(0)
	v_lshlrev_b32_e32 v12, 16, v8
	v_and_b32_e32 v13, 0xffff0000, v8
	v_lshlrev_b32_e32 v8, 16, v9
	v_and_b32_e32 v9, 0xffff0000, v9
	v_lshlrev_b32_e32 v14, 16, v10
	v_and_b32_e32 v15, 0xffff0000, v10
	v_lshlrev_b32_e32 v10, 16, v11
	v_and_b32_e32 v11, 0xffff0000, v11
	v_pk_add_f32 v[6:7], v[6:7], v[8:9]
	v_pk_add_f32 v[4:5], v[4:5], v[12:13]
	v_pk_add_f32 v[8:9], v[2:3], v[10:11]
	v_pk_add_f32 v[2:3], v[0:1], v[14:15]
	v_cvt_pk_bf16_f32 v0, v4, v5
	v_cvt_pk_bf16_f32 v1, v6, v7
	v_cvt_pk_bf16_f32 v2, v2, v3
	v_cvt_pk_bf16_f32 v3, v8, v9
	global_store_dwordx4 v[16:17], v[0:3], off offset:256
	s_cbranch_vccz .LBB1_543
	s_waitcnt vmcnt(0)
	s_cmpk_gt_u32 s17, 0xff
	s_cbranch_scc1 .LBB1_554
	s_barrier

; DI float bflo(unsigned w) { return __uint_as_float(w << 16); }
; DI float bfhi(unsigned w) { return __uint_as_float(w & 0xffff0000u); }
; DI float wave_sum(float v) { for (int o = 32; o; o >>= 1) v += __shfl_xor(v, o); return v; }
; template <bool BF> DI void norm_phase(const Params& p, const void* x, const float* gain) {
;     ...
;     for (int t = bid * 8 + wid; t < T; t += 2 * step) {
;         const int t2 = (t + step < T) ? t + step : t;
;         f32x4 v[2][8];
; #pragma unroll
;         for (int q = 0; q < 2; ++q) {
;             const int tt = q ? t2 : t;
; #pragma unroll
;             for (int i = 0; i < 4; ++i) {
;                 const size_t e = (size_t)tt * D + (i * 64 + lane) * 8;
;                 if constexpr (BF) { const u32x4 w = *(const u32x4*)((const bf16_t*)x + e);
;                     v[q][2 * i] = (f32x4){bflo(w[0]), bfhi(w[0]), bflo(w[1]), bfhi(w[1])}; v[q][2 * i + 1] = (f32x4){bflo(w[2]), bfhi(w[2]), bflo(w[3]), bfhi(w[3])}; }
;                 else { v[q][2 * i] = *(const f32x4*)((const float*)x + e); v[q][2 * i + 1] = *(const f32x4*)((const float*)x + e + 4); }
;             }
;         }
;         float ss[2] = {0.f, 0.f};
; #pragma unroll
;         for (int q = 0; q < 2; ++q)
; #pragma unroll
;             for (int i = 0; i < 8; ++i) ss[q] += v[q][i][0] * v[q][i][0] + v[q][i][1] * v[q][i][1] + v[q][i][2] * v[q][i][2] + v[q][i][3] * v[q][i][3];
;         ss[0] = wave_sum(ss[0]); ss[1] = wave_sum(ss[1]);
.LBB1_621:
	v_add_u32_e32 v79, s33, v22
	v_cmp_gt_i32_e32 vcc, s2, v79
	v_ashrrev_i32_e32 v23, 31, v22
	global_load_dwordx4 v[0:3], v[8:9], off offset:16
	global_load_dwordx4 v[4:7], v[8:9], off
	v_cndmask_b32_e32 v38, v22, v79, vcc
	v_ashrrev_i32_e32 v39, 31, v38
	v_lshlrev_b64 v[22:23], 12, v[22:23]
	v_lshlrev_b64 v[52:53], 12, v[38:39]
	v_lshl_add_u64 v[34:35], v[16:17], 0, v[22:23]
	v_lshl_add_u64 v[38:39], v[16:17], 0, v[52:53]
	v_lshl_add_u64 v[72:73], v[18:19], 0, v[22:23]
	global_load_dwordx4 v[22:25], v[34:35], off offset:2048
	global_load_dwordx4 v[26:29], v[34:35], off offset:3072
	global_load_dwordx4 v[30:33], v[34:35], off
	s_nop 0
	global_load_dwordx4 v[34:37], v[34:35], off offset:1024
	s_nop 0
	global_load_dwordx4 v[80:83], v[38:39], off offset:2048
	global_load_dwordx4 v[84:87], v[38:39], off
	global_load_dwordx4 v[88:91], v[38:39], off offset:1024
	global_load_dwordx4 v[92:95], v[38:39], off offset:3072
	v_lshl_add_u64 v[52:53], v[18:19], 0, v[52:53]
	s_waitcnt vmcnt(0) lgkmcnt(0)
	v_and_b32_e32 v99, 0xffff0000, v22
	v_and_b32_e32 v98, 0xffff0000, v24
	v_and_b32_e32 v107, 0xffff0000, v26
	v_and_b32_e32 v106, 0xffff0000, v28
	v_and_b32_e32 v65, 0xffff0000, v30
	v_and_b32_e32 v69, 0xffff0000, v32
	v_and_b32_e32 v64, 0xffff0000, v84
	v_and_b32_e32 v68, 0xffff0000, v86
	v_lshlrev_b32_e32 v97, 16, v22
	v_lshlrev_b32_e32 v96, 16, v24
	v_lshlrev_b32_e32 v101, 16, v23
	v_lshlrev_b32_e32 v100, 16, v25
	v_and_b32_e32 v103, 0xffff0000, v23
	v_and_b32_e32 v102, 0xffff0000, v25
	v_lshlrev_b32_e32 v105, 16, v26
	v_lshlrev_b32_e32 v104, 16, v28
	v_lshlrev_b32_e32 v108, 16, v29
	v_and_b32_e32 v110, 0xffff0000, v29
	v_lshlrev_b32_e32 v57, 16, v30
	v_lshlrev_b32_e32 v61, 16, v32
	v_lshlrev_b32_e32 v39, 16, v34
	v_and_b32_e32 v55, 0xffff0000, v34
	v_lshlrev_b32_e32 v41, 16, v35
	v_and_b32_e32 v47, 0xffff0000, v35
	v_pk_mul_f32 v[22:23], v[98:99], v[98:99]
	v_pk_mul_f32 v[24:25], v[106:107], v[106:107]
	v_and_b32_e32 v35, 0xffff0000, v80
	v_and_b32_e32 v34, 0xffff0000, v82
	v_lshlrev_b32_e32 v56, 16, v84
	v_lshlrev_b32_e32 v60, 16, v86
	v_lshlrev_b32_e32 v62, 16, v87
	v_and_b32_e32 v70, 0xffff0000, v87
	v_lshlrev_b32_e32 v38, 16, v88
	v_and_b32_e32 v54, 0xffff0000, v88
	v_lshlrev_b32_e32 v40, 16, v89
	v_and_b32_e32 v46, 0xffff0000, v89
	v_and_b32_e32 v29, 0xffff0000, v92
	v_and_b32_e32 v28, 0xffff0000, v94
	v_pk_mul_f32 v[86:87], v[64:65], v[64:65]
	v_pk_mul_f32 v[88:89], v[68:69], v[68:69]
	v_lshlrev_b32_e32 v59, 16, v31
	v_lshlrev_b32_e32 v63, 16, v33
	v_and_b32_e32 v51, 0xffff0000, v36
	v_pk_fma_f32 v[120:121], v[96:97], v[96:97], v[22:23]
	v_pk_fma_f32 v[122:123], v[104:105], v[104:105], v[24:25]
	v_lshlrev_b32_e32 v23, 16, v80
	v_lshlrev_b32_e32 v22, 16, v82
	v_lshlrev_b32_e32 v58, 16, v85
	v_and_b32_e32 v66, 0xffff0000, v85
	v_lshlrev_b32_e32 v42, 16, v90
	v_and_b32_e32 v50, 0xffff0000, v90
	v_lshlrev_b32_e32 v44, 16, v91
	v_and_b32_e32 v48, 0xffff0000, v91
	v_lshlrev_b32_e32 v25, 16, v92
	v_lshlrev_b32_e32 v24, 16, v94
	v_lshlrev_b32_e32 v26, 16, v95
	v_and_b32_e32 v30, 0xffff0000, v95
	v_pk_mul_f32 v[84:85], v[34:35], v[34:35]
	v_pk_mul_f32 v[90:91], v[54:55], v[54:55]
	v_pk_mul_f32 v[94:95], v[28:29], v[28:29]
	v_pk_fma_f32 v[86:87], v[56:57], v[56:57], v[86:87]
	v_pk_fma_f32 v[88:89], v[60:61], v[60:61], v[88:89]
	v_lshlrev_b32_e32 v109, 16, v27
	v_and_b32_e32 v111, 0xffff0000, v27
	v_and_b32_e32 v67, 0xffff0000, v31
	v_and_b32_e32 v71, 0xffff0000, v33
	v_lshlrev_b32_e32 v43, 16, v36
	v_lshlrev_b32_e32 v33, 16, v81
	v_lshlrev_b32_e32 v32, 16, v83
	v_lshlrev_b32_e32 v27, 16, v93
	v_and_b32_e32 v31, 0xffff0000, v93
	v_pk_mul_f32 v[92:93], v[50:51], v[50:51]
	v_pk_fma_f32 v[84:85], v[22:23], v[22:23], v[84:85]
	v_pk_fma_f32 v[90:91], v[38:39], v[38:39], v[90:91]
	v_pk_fma_f32 v[94:95], v[24:25], v[24:25], v[94:95]
	v_pk_fma_f32 v[86:87], v[58:59], v[58:59], v[86:87]
	v_pk_fma_f32 v[88:89], v[62:63], v[62:63], v[88:89]
	v_lshlrev_b32_e32 v45, 16, v37
	v_and_b32_e32 v49, 0xffff0000, v37
	v_and_b32_e32 v37, 0xffff0000, v81
	v_and_b32_e32 v36, 0xffff0000, v83
	v_pk_fma_f32 v[80:81], v[100:101], v[100:101], v[120:121]
	v_pk_fma_f32 v[82:83], v[108:109], v[108:109], v[122:123]
	v_pk_fma_f32 v[92:93], v[42:43], v[42:43], v[92:93]
	v_pk_fma_f32 v[84:85], v[32:33], v[32:33], v[84:85]
	v_pk_fma_f32 v[90:91], v[40:41], v[40:41], v[90:91]
	v_pk_fma_f32 v[94:95], v[26:27], v[26:27], v[94:95]
	v_pk_fma_f32 v[86:87], v[66:67], v[66:67], v[86:87]
	v_pk_fma_f32 v[88:89], v[70:71], v[70:71], v[88:89]
	v_pk_fma_f32 v[80:81], v[102:103], v[102:103], v[80:81]
	v_pk_fma_f32 v[82:83], v[110:111], v[110:111], v[82:83]
	v_pk_fma_f32 v[92:93], v[44:45], v[44:45], v[92:93]
	v_pk_fma_f32 v[84:85], v[36:37], v[36:37], v[84:85]
	v_pk_fma_f32 v[90:91], v[46:47], v[46:47], v[90:91]
	v_pk_fma_f32 v[94:95], v[30:31], v[30:31], v[94:95]
	v_pk_add_f32 v[86:87], v[86:87], v[88:89]
	v_mov_b32_e32 v121, v81
	v_mov_b32_e32 v81, v83
	v_pk_fma_f32 v[92:93], v[48:49], v[48:49], v[92:93]
	v_mov_b32_e32 v120, v85
	v_mov_b32_e32 v85, v80
	v_mov_b32_e32 v80, v95
	v_mov_b32_e32 v95, v82
	v_pk_add_f32 v[82:83], v[86:87], v[90:91]
	v_mov_b32_e32 v112, v57
	v_pk_add_f32 v[82:83], v[92:93], v[82:83]
	v_mov_b32_e32 v114, v59
	v_pk_add_f32 v[82:83], v[120:121], v[82:83]
	v_mov_b32_e32 v113, v65
	v_pk_add_f32 v[82:83], v[84:85], v[82:83]
	v_mov_b32_e32 v115, v67
	v_pk_add_f32 v[80:81], v[80:81], v[82:83]
	v_mov_b32_e32 v116, v61
	v_pk_add_f32 v[80:81], v[94:95], v[80:81]
	ds_bpermute_b32 v83, v21, v81
	ds_bpermute_b32 v82, v21, v80
	v_mov_b32_e32 v117, v69
	v_mov_b32_e32 v118, v63
	v_mov_b32_e32 v119, v71
	v_mov_b32_e32 v61, v68
	s_waitcnt lgkmcnt(0)
; DI unsigned pack2(float a, float b) { f32x2 v = {a, b}; hwbf16x2 r = __builtin_convertvector(v, hwbf16x2); return __builtin_bit_cast(unsigned, r); }
; DI float wave_sum(float v) { for (int o = 32; o; o >>= 1) v += __shfl_xor(v, o); return v; }
;     DI const char* a(const Unit& u) const { return (const char*)(A + (size_t)u.pm * BM * lda); }
;     DI const char* a(const Unit& u) const { return (const char*)(A + (size_t)u.pm * BM * 2048 + (u.pn >> 1) * 512); }
;     DI const char* a(const Unit& u) const { return (const char*)((u.pn < 12 ? A1 : A2) + (size_t)u.pm * BM * 512); }
; template <bool BF> DI void norm_phase(const Params& p, const void* x, const float* gain) {
;     ...
;         ss[0] = wave_sum(ss[0]); ss[1] = wave_sum(ss[1]);
; #pragma unroll
;         for (int q = 0; q < 2; ++q) {
;             const int tt = q ? t2 : t;
;             const float rs = rsqrtf(ss[q] * (1.0f / D) + EPS);
; #pragma unroll
;             for (int i = 0; i < 4; ++i) { const int c = (i * 64 + lane) * 8;
;                 const f32x4 g0 = *(const f32x4*)(gain + c), g1 = *(const f32x4*)(gain + c + 4);
;                 const f32x4 a = v[q][2 * i] * rs * g0, d = v[q][2 * i + 1] * rs * g1;
;                 u32x4 o; o[0] = pack2(a[0], a[1]); o[1] = pack2(a[2], a[3]); o[2] = pack2(d[0], d[1]); o[3] = pack2(d[2], d[3]);
;                 *(u32x4*)(H + (size_t)tt * D + c) = o; }
	v_pk_add_f32 v[80:81], v[80:81], v[82:83]
	ds_bpermute_b32 v83, v74, v81
	ds_bpermute_b32 v82, v74, v80
	v_mov_b32_e32 v63, v70
	s_waitcnt lgkmcnt(0)
	v_pk_add_f32 v[80:81], v[80:81], v[82:83]
	ds_bpermute_b32 v83, v75, v81
	ds_bpermute_b32 v82, v75, v80
	s_waitcnt lgkmcnt(0)
	v_pk_add_f32 v[80:81], v[80:81], v[82:83]
	ds_bpermute_b32 v83, v76, v81
	ds_bpermute_b32 v82, v76, v80
	s_waitcnt lgkmcnt(0)
	v_pk_add_f32 v[80:81], v[80:81], v[82:83]
	ds_bpermute_b32 v83, v77, v81
	ds_bpermute_b32 v82, v77, v80
	s_waitcnt lgkmcnt(0)
	v_pk_add_f32 v[80:81], v[80:81], v[82:83]
	ds_bpermute_b32 v83, v78, v81
	ds_bpermute_b32 v82, v78, v80
	s_waitcnt lgkmcnt(0)
	v_pk_add_f32 v[80:81], v[80:81], v[82:83]
	s_nop 0
	v_pk_fma_f32 v[80:81], v[80:81], s[10:11], v[20:21] op_sel_hi:[1,0,0]
	s_nop 0
	v_mul_f32_e32 v57, 0x4b800000, v81
	v_cmp_gt_f32_e32 vcc, s3, v81
	s_nop 1
	v_cndmask_b32_e32 v57, v81, v57, vcc
	v_rsq_f32_e32 v57, v57
	s_nop 0
	v_mul_f32_e32 v59, 0x45800000, v57
	v_cndmask_b32_e32 v82, v57, v59, vcc
	v_pk_mul_f32 v[84:85], v[82:83], v[112:113] op_sel_hi:[0,1]
	v_pk_mul_f32 v[86:87], v[82:83], v[114:115] op_sel_hi:[0,1]
	v_pk_mul_f32 v[88:89], v[82:83], v[116:117] op_sel_hi:[0,1]
	v_pk_mul_f32 v[90:91], v[82:83], v[118:119] op_sel_hi:[0,1]
	v_pk_mul_f32 v[6:7], v[6:7], v[86:87]
	v_pk_mul_f32 v[4:5], v[4:5], v[84:85]
	v_pk_mul_f32 v[84:85], v[2:3], v[90:91]
	v_pk_mul_f32 v[2:3], v[0:1], v[88:89]
	v_cvt_pk_bf16_f32 v0, v4, v5
	v_cvt_pk_bf16_f32 v1, v6, v7
	v_cvt_pk_bf16_f32 v2, v2, v3
	v_cvt_pk_bf16_f32 v3, v84, v85
	global_store_dwordx4 v[72:73], v[0:3], off
	global_load_dwordx4 v[0:3], v[10:11], off
	s_nop 0
	global_load_dwordx4 v[4:7], v[10:11], off offset:16
	v_mov_b32_e32 v84, v39
	v_mov_b32_e32 v85, v55
	v_mov_b32_e32 v86, v41
	v_mov_b32_e32 v87, v47
	v_mov_b32_e32 v88, v43
	v_mov_b32_e32 v89, v51
	v_mov_b32_e32 v90, v45
	v_mov_b32_e32 v91, v49
	v_pk_mul_f32 v[84:85], v[82:83], v[84:85] op_sel_hi:[0,1]
	v_pk_mul_f32 v[86:87], v[82:83], v[86:87] op_sel_hi:[0,1]
	v_pk_mul_f32 v[88:89], v[82:83], v[88:89] op_sel_hi:[0,1]
	v_pk_mul_f32 v[90:91], v[82:83], v[90:91] op_sel_hi:[0,1]
	v_mul_f32_e32 v39, 0x4b800000, v80
	v_cmp_gt_f32_e32 vcc, s3, v80
	v_mov_b32_e32 v57, v64
	v_mov_b32_e32 v59, v66
	v_cndmask_b32_e32 v39, v80, v39, vcc
	v_rsq_f32_e32 v39, v39
	v_mov_b32_e32 v43, v50
	v_mov_b32_e32 v45, v48
	v_mul_f32_e32 v41, 0x45800000, v39
	v_cndmask_b32_e32 v64, v39, v41, vcc
	v_pk_mul_f32 v[56:57], v[64:65], v[56:57] op_sel_hi:[0,1]
	v_pk_mul_f32 v[58:59], v[64:65], v[58:59] op_sel_hi:[0,1]
	v_pk_mul_f32 v[60:61], v[64:65], v[60:61] op_sel_hi:[0,1]
	v_pk_mul_f32 v[62:63], v[64:65], v[62:63] op_sel_hi:[0,1]
	v_mov_b32_e32 v39, v54
	v_mov_b32_e32 v41, v46
	v_pk_mul_f32 v[38:39], v[64:65], v[38:39] op_sel_hi:[0,1]
	v_pk_mul_f32 v[40:41], v[64:65], v[40:41] op_sel_hi:[0,1]
	v_pk_mul_f32 v[42:43], v[64:65], v[42:43] op_sel_hi:[0,1]
	v_pk_mul_f32 v[44:45], v[64:65], v[44:45] op_sel_hi:[0,1]
	s_waitcnt vmcnt(0)
	v_pk_mul_f32 v[2:3], v[2:3], v[86:87]
	v_pk_mul_f32 v[0:1], v[0:1], v[84:85]
	v_pk_mul_f32 v[6:7], v[6:7], v[90:91]
	v_pk_mul_f32 v[4:5], v[4:5], v[88:89]
	v_cvt_pk_bf16_f32 v0, v0, v1
	v_cvt_pk_bf16_f32 v1, v2, v3
	v_cvt_pk_bf16_f32 v2, v4, v5
	v_cvt_pk_bf16_f32 v3, v6, v7
	global_store_dwordx4 v[72:73], v[0:3], off offset:1024
	global_load_dwordx4 v[0:3], v[12:13], off
	s_nop 0
	global_load_dwordx4 v[4:7], v[12:13], off offset:16
	v_mov_b32_e32 v84, v97
	v_mov_b32_e32 v85, v99
	v_mov_b32_e32 v86, v101
	v_mov_b32_e32 v87, v103
	v_mov_b32_e32 v97, v98
	v_mov_b32_e32 v101, v102
	v_pk_mul_f32 v[84:85], v[82:83], v[84:85] op_sel_hi:[0,1]
	v_pk_mul_f32 v[86:87], v[82:83], v[86:87] op_sel_hi:[0,1]
	v_pk_mul_f32 v[88:89], v[82:83], v[96:97] op_sel_hi:[0,1]
	v_pk_mul_f32 v[90:91], v[82:83], v[100:101] op_sel_hi:[0,1]
	s_waitcnt vmcnt(0)
; DI unsigned pack2(float a, float b) { f32x2 v = {a, b}; hwbf16x2 r = __builtin_convertvector(v, hwbf16x2); return __builtin_bit_cast(unsigned, r); }
;     DI const char* a(const Unit& u) const { return (const char*)(A + (size_t)u.pm * BM * lda); }
;     DI const char* a(const Unit& u) const { return (const char*)(A + (size_t)u.pm * BM * 2048 + (u.pn >> 1) * 512); }
;     DI const char* a(const Unit& u) const { return (const char*)((u.pn < 12 ? A1 : A2) + (size_t)u.pm * BM * 512); }
; template <bool BF> DI void norm_phase(const Params& p, const void* x, const float* gain) {
;     ...
;         for (int q = 0; q < 2; ++q) {
;             const int tt = q ? t2 : t;
;             const float rs = rsqrtf(ss[q] * (1.0f / D) + EPS);
; #pragma unroll
;             for (int i = 0; i < 4; ++i) { const int c = (i * 64 + lane) * 8;
;                 const f32x4 g0 = *(const f32x4*)(gain + c), g1 = *(const f32x4*)(gain + c + 4);
;                 const f32x4 a = v[q][2 * i] * rs * g0, d = v[q][2 * i + 1] * rs * g1;
;                 u32x4 o; o[0] = pack2(a[0], a[1]); o[1] = pack2(a[2], a[3]); o[2] = pack2(d[0], d[1]); o[3] = pack2(d[2], d[3]);
;                 *(u32x4*)(H + (size_t)tt * D + c) = o; }
;         }
	v_pk_mul_f32 v[2:3], v[2:3], v[86:87]
	v_pk_mul_f32 v[0:1], v[0:1], v[84:85]
	v_pk_mul_f32 v[6:7], v[6:7], v[90:91]
	v_pk_mul_f32 v[4:5], v[4:5], v[88:89]
	v_cvt_pk_bf16_f32 v0, v0, v1
	v_cvt_pk_bf16_f32 v1, v2, v3
	v_cvt_pk_bf16_f32 v2, v4, v5
	v_cvt_pk_bf16_f32 v3, v6, v7
	global_store_dwordx4 v[72:73], v[0:3], off offset:2048
	global_load_dwordx4 v[0:3], v[14:15], off
	s_nop 0
	global_load_dwordx4 v[4:7], v[14:15], off offset:16
	v_mov_b32_e32 v84, v105
	v_mov_b32_e32 v85, v107
	v_mov_b32_e32 v86, v109
	v_mov_b32_e32 v87, v111
	v_mov_b32_e32 v105, v106
	v_mov_b32_e32 v109, v110
	v_pk_mul_f32 v[84:85], v[82:83], v[84:85] op_sel_hi:[0,1]
	v_pk_mul_f32 v[86:87], v[82:83], v[86:87] op_sel_hi:[0,1]
	v_pk_mul_f32 v[88:89], v[82:83], v[104:105] op_sel_hi:[0,1]
	v_pk_mul_f32 v[82:83], v[82:83], v[108:109] op_sel_hi:[0,1]
	s_waitcnt vmcnt(0)
	v_pk_mul_f32 v[2:3], v[2:3], v[86:87]
	v_pk_mul_f32 v[0:1], v[0:1], v[84:85]
	v_pk_mul_f32 v[6:7], v[6:7], v[82:83]
	v_pk_mul_f32 v[4:5], v[4:5], v[88:89]
	v_cvt_pk_bf16_f32 v0, v0, v1
	v_cvt_pk_bf16_f32 v1, v2, v3
	v_cvt_pk_bf16_f32 v2, v4, v5
	v_cvt_pk_bf16_f32 v3, v6, v7
	global_store_dwordx4 v[72:73], v[0:3], off offset:3072
	global_load_dwordx4 v[0:3], v[8:9], off
	s_nop 0
	global_load_dwordx4 v[4:7], v[8:9], off offset:16
	s_waitcnt vmcnt(0)
	v_pk_mul_f32 v[2:3], v[2:3], v[58:59]
	v_pk_mul_f32 v[0:1], v[0:1], v[56:57]
	v_pk_mul_f32 v[6:7], v[6:7], v[62:63]
	v_pk_mul_f32 v[4:5], v[4:5], v[60:61]
	v_cvt_pk_bf16_f32 v0, v0, v1
	v_cvt_pk_bf16_f32 v1, v2, v3
	v_cvt_pk_bf16_f32 v2, v4, v5
	v_cvt_pk_bf16_f32 v3, v6, v7
	global_store_dwordx4 v[52:53], v[0:3], off
	global_load_dwordx4 v[0:3], v[10:11], off
	s_nop 0
	global_load_dwordx4 v[4:7], v[10:11], off offset:16
	s_waitcnt vmcnt(0)
	v_pk_mul_f32 v[2:3], v[40:41], v[2:3]
	v_pk_mul_f32 v[0:1], v[38:39], v[0:1]
	v_pk_mul_f32 v[6:7], v[44:45], v[6:7]
	v_pk_mul_f32 v[4:5], v[42:43], v[4:5]
	v_cvt_pk_bf16_f32 v0, v0, v1
	v_cvt_pk_bf16_f32 v1, v2, v3
	v_cvt_pk_bf16_f32 v2, v4, v5
	v_cvt_pk_bf16_f32 v3, v6, v7
	global_store_dwordx4 v[52:53], v[0:3], off offset:1024
	global_load_dwordx4 v[0:3], v[12:13], off
	s_nop 0
	global_load_dwordx4 v[4:7], v[12:13], off offset:16
	v_mov_b32_e32 v38, v23
	v_mov_b32_e32 v39, v35
	v_mov_b32_e32 v40, v33
	v_mov_b32_e32 v41, v37
	v_mov_b32_e32 v23, v34
	v_mov_b32_e32 v33, v36
	v_pk_mul_f32 v[34:35], v[64:65], v[38:39] op_sel_hi:[0,1]
	v_pk_mul_f32 v[36:37], v[64:65], v[40:41] op_sel_hi:[0,1]
	v_pk_mul_f32 v[22:23], v[64:65], v[22:23] op_sel_hi:[0,1]
	v_pk_mul_f32 v[32:33], v[64:65], v[32:33] op_sel_hi:[0,1]
	s_waitcnt vmcnt(0)
	v_pk_mul_f32 v[2:3], v[36:37], v[2:3]
	v_pk_mul_f32 v[0:1], v[34:35], v[0:1]
	v_pk_mul_f32 v[6:7], v[32:33], v[6:7]
	v_pk_mul_f32 v[4:5], v[22:23], v[4:5]
	v_cvt_pk_bf16_f32 v0, v0, v1
	v_cvt_pk_bf16_f32 v1, v2, v3
	v_cvt_pk_bf16_f32 v2, v4, v5
	v_cvt_pk_bf16_f32 v3, v6, v7
	global_store_dwordx4 v[52:53], v[0:3], off offset:2048
	global_load_dwordx4 v[0:3], v[14:15], off
	s_nop 0
	global_load_dwordx4 v[4:7], v[14:15], off offset:16
	v_mov_b32_e32 v32, v25
	v_mov_b32_e32 v33, v29
	v_mov_b32_e32 v34, v27
	v_mov_b32_e32 v35, v31
	v_mov_b32_e32 v25, v28
	v_mov_b32_e32 v27, v30
	v_add_u32_e32 v22, s33, v79
	v_pk_mul_f32 v[28:29], v[64:65], v[32:33] op_sel_hi:[0,1]
	v_pk_mul_f32 v[30:31], v[64:65], v[34:35] op_sel_hi:[0,1]
	v_pk_mul_f32 v[24:25], v[64:65], v[24:25] op_sel_hi:[0,1]
	v_pk_mul_f32 v[26:27], v[64:65], v[26:27] op_sel_hi:[0,1]
	v_cmp_lt_i32_e32 vcc, s4, v22
	s_or_b64 s[8:9], vcc, s[8:9]
	s_waitcnt vmcnt(0)
	v_pk_mul_f32 v[2:3], v[30:31], v[2:3]
	v_pk_mul_f32 v[0:1], v[28:29], v[0:1]
	v_pk_mul_f32 v[6:7], v[26:27], v[6:7]
	v_pk_mul_f32 v[4:5], v[24:25], v[4:5]
	v_cvt_pk_bf16_f32 v0, v0, v1
	v_cvt_pk_bf16_f32 v1, v2, v3
	v_cvt_pk_bf16_f32 v2, v4, v5
	v_cvt_pk_bf16_f32 v3, v6, v7
	global_store_dwordx4 v[52:53], v[0:3], off offset:3072
	s_andn2_b64 exec, exec, s[8:9]
	s_cbranch_execnz .LBB1_621

; #define PG8_STAGE(bufoff, gbase, voff) do { _Pragma("unroll") for (int _i = 0; _i < 2; ++_i) \
;         __builtin_amdgcn_global_load_lds((const unsigned*)((const char*)(gbase) + (voff)[_i]), (LAS unsigned*)(lds + (bufoff) + ldsw + _i * 8192), 16, 0, 0); } while (0)
; #define PG8_LDA(dst, b, h) do { _Pragma("unroll") for (int m = 0; m < 4; ++m) _Pragma("unroll") for (int k = 0; k < 2; ++k) dst[m][k] = *(const LAS bf16x8*)(lds + PG8_SA(b, h) + aoff + m * 2048 + k * 1024); } while (0)
; #define PG8_LDB(dst, b, h) do { _Pragma("unroll") for (int n = 0; n < 2; ++n) _Pragma("unroll") for (int k = 0; k < 2; ++k) dst[n][k] = *(const LAS bf16x8*)(lds + PG8_SB(b, h) + boff + n * 2048 + k * 1024); } while (0)
; #define PG8_MMA(ai, bj, At, Bt) do { __builtin_amdgcn_s_setprio(1); _Pragma("unroll") for (int m = 0; m < 4; ++m) _Pragma("unroll") for (int n = 0; n < 2; ++n) _Pragma("unroll") for (int k = 0; k < 2; ++k) \
;         acc[ai][bj][m][n] = __builtin_amdgcn_mfma_f32_16x16x32_bf16(Bt[n][k], At[m][k], acc[ai][bj][m][n], 0, 0, 0); __builtin_amdgcn_s_setprio(0); } while (0)
; #define PG8_WAIT_V(n) asm volatile("s_waitcnt vmcnt(" #n ")" ::: "memory")
; #define PG8_WAIT_L(n) asm volatile("s_waitcnt lgkmcnt(" #n ")" ::: "memory")
; #define PG8_BAR __builtin_amdgcn_s_barrier()
; #define PG8_SCHED __builtin_amdgcn_sched_barrier(0)
; template <class Map, class Epi>
; DI void gemm_phase(LAS unsigned char* lds, const Map& MP, const Epi& E, const int nM, const int nN, const int K, const int lda, const int ldb) {
;     ...
;             PG8_LDB(B0, 0, 0); PG8_SCHED; PG8_LDA(At, 0, 0); PG8_STAGE(PG8_SA(1, 1), a1 + hstepA, voffA);
;             PG8_WAIT_L(8); PG8_BAR; PG8_WAIT_L(0); PG8_MMA(0, 0, At, B0); PG8_BAR; PG8_SCHED;
;             PG8_LDB(B1, 0, 1); PG8_STAGE(PG8_SB(0, 0), b2, voffB);
;             PG8_BAR; PG8_WAIT_L(0); PG8_MMA(0, 1, At, B1); PG8_BAR;
;             PG8_LDA(At, 0, 1); PG8_STAGE(PG8_SA(0, 0), a2, voffA);
;             PG8_BAR; PG8_WAIT_L(0); PG8_MMA(1, 0, At, B0); PG8_BAR; PG8_SCHED;
;             PG8_STAGE(PG8_SB(0, 1), b2 + hstepB, voffB);
;             PG8_WAIT_V(6); PG8_BAR; PG8_MMA(1, 1, At, B1); PG8_BAR;
.LBB1_693:
	ds_read_b128 v[150:153], v147
	ds_read_b128 v[154:157], v147 offset:1024
	ds_read_b128 v[158:161], v147 offset:2048
	ds_read_b128 v[162:165], v147 offset:3072
	s_add_u32 s3, s20, 0xfff80080
	s_addc_u32 s22, s21, -1
	s_cmp_eq_u32 s54, 28
	s_cselect_b32 s25, s15, s22
	s_cselect_b32 s24, s48, s3
	s_cselect_b32 s23, s13, s53
	s_cselect_b32 s22, s49, s52
	v_lshl_add_u64 v[194:195], s[20:21], 0, v[138:139]
	s_add_i32 m0, s31, 0xc000
	ds_read_b128 v[166:169], v148
	ds_read_b128 v[170:173], v148 offset:1024
	ds_read_b128 v[174:177], v148 offset:2048
	ds_read_b128 v[178:181], v148 offset:3072
	ds_read_b128 v[182:185], v148 offset:4096
	ds_read_b128 v[186:189], v148 offset:5120
	ds_read_b128 v[190:193], v148 offset:6144
	ds_read_b128 v[198:201], v148 offset:7168
	global_load_lds_dwordx4 v[194:195], off
	v_lshl_add_u64 v[194:195], s[20:21], 0, v[136:137]
	s_add_i32 m0, s31, 0xe000
	s_nop 0
	global_load_lds_dwordx4 v[194:195], off
	s_waitcnt lgkmcnt(8)
	s_barrier
	s_setprio 1
	s_waitcnt lgkmcnt(7)
	v_mfma_f32_16x16x32_bf16 v[124:127], v[150:153], v[166:169], v[124:127]
	v_mfma_f32_16x16x32_bf16 v[120:123], v[158:161], v[166:169], v[120:123]
	s_waitcnt lgkmcnt(5)
	v_mfma_f32_16x16x32_bf16 v[116:119], v[150:153], v[174:177], v[116:119]
	v_mfma_f32_16x16x32_bf16 v[112:115], v[158:161], v[174:177], v[112:115]
	s_waitcnt lgkmcnt(3)
	v_mfma_f32_16x16x32_bf16 v[100:103], v[150:153], v[182:185], v[100:103]
	v_mfma_f32_16x16x32_bf16 v[96:99], v[158:161], v[182:185], v[96:99]
	s_waitcnt lgkmcnt(1)
	v_mfma_f32_16x16x32_bf16 v[84:87], v[150:153], v[190:193], v[84:87]
	v_mfma_f32_16x16x32_bf16 v[80:83], v[158:161], v[190:193], v[80:83]
	v_mfma_f32_16x16x32_bf16 v[124:127], v[154:157], v[170:173], v[124:127]
	v_mfma_f32_16x16x32_bf16 v[120:123], v[162:165], v[170:173], v[120:123]
	v_mfma_f32_16x16x32_bf16 v[116:119], v[154:157], v[178:181], v[116:119]
	v_mfma_f32_16x16x32_bf16 v[112:115], v[162:165], v[178:181], v[112:115]
	v_mfma_f32_16x16x32_bf16 v[100:103], v[154:157], v[186:189], v[100:103]
	v_mfma_f32_16x16x32_bf16 v[96:99], v[162:165], v[186:189], v[96:99]
	s_waitcnt lgkmcnt(0)
	v_mfma_f32_16x16x32_bf16 v[84:87], v[154:157], v[198:201], v[84:87]
	v_mfma_f32_16x16x32_bf16 v[80:83], v[162:165], v[198:201], v[80:83]
	s_setprio 0
	s_barrier
	s_add_i32 s3, s44, s29
	v_lshl_add_u64 v[194:195], s[22:23], 0, v[132:133]
	s_mov_b32 m0, s3
	ds_read_b128 v[202:205], v149
	ds_read_b128 v[206:209], v149 offset:1024
	ds_read_b128 v[210:213], v149 offset:2048
	ds_read_b128 v[214:217], v149 offset:3072
	global_load_lds_dwordx4 v[194:195], off
	v_lshl_add_u64 v[218:219], s[22:23], 0, v[128:129]
	s_add_i32 m0, s3, 0x2000
	s_nop 0
	global_load_lds_dwordx4 v[218:219], off
	s_barrier
	s_setprio 1
	s_waitcnt lgkmcnt(3)
	v_mfma_f32_16x16x32_bf16 v[108:111], v[202:205], v[166:169], v[108:111]
	s_waitcnt lgkmcnt(1)
	v_mfma_f32_16x16x32_bf16 v[104:107], v[210:213], v[166:169], v[104:107]
	v_mfma_f32_16x16x32_bf16 v[92:95], v[202:205], v[174:177], v[92:95]
	v_mfma_f32_16x16x32_bf16 v[88:91], v[210:213], v[174:177], v[88:91]
	v_mfma_f32_16x16x32_bf16 v[76:79], v[202:205], v[182:185], v[76:79]
	v_mfma_f32_16x16x32_bf16 v[72:75], v[210:213], v[182:185], v[72:75]
	v_mfma_f32_16x16x32_bf16 v[68:71], v[202:205], v[190:193], v[68:71]
	v_mfma_f32_16x16x32_bf16 v[64:67], v[210:213], v[190:193], v[64:67]
	v_mfma_f32_16x16x32_bf16 v[108:111], v[206:209], v[170:173], v[108:111]
	s_waitcnt lgkmcnt(0)
	v_mfma_f32_16x16x32_bf16 v[104:107], v[214:217], v[170:173], v[104:107]
	v_mfma_f32_16x16x32_bf16 v[92:95], v[206:209], v[178:181], v[92:95]
	v_mfma_f32_16x16x32_bf16 v[88:91], v[214:217], v[178:181], v[88:91]
	v_mfma_f32_16x16x32_bf16 v[76:79], v[206:209], v[186:189], v[76:79]
	v_mfma_f32_16x16x32_bf16 v[72:75], v[214:217], v[186:189], v[72:75]
	v_mfma_f32_16x16x32_bf16 v[68:71], v[206:209], v[198:201], v[68:71]
	v_mfma_f32_16x16x32_bf16 v[64:67], v[214:217], v[198:201], v[64:67]
	s_setprio 0
	s_mov_b32 m0, s31
	v_lshl_add_u64 v[220:221], s[24:25], 0, v[134:135]
	s_barrier
	ds_read_b128 v[166:169], v148 offset:16384
	ds_read_b128 v[170:173], v148 offset:17408
	ds_read_b128 v[174:177], v148 offset:18432
	ds_read_b128 v[178:181], v148 offset:19456
	ds_read_b128 v[182:185], v148 offset:20480
	ds_read_b128 v[186:189], v148 offset:21504
	ds_read_b128 v[190:193], v148 offset:22528
	ds_read_b128 v[198:201], v148 offset:23552
	global_load_lds_dwordx4 v[220:221], off
	v_lshl_add_u64 v[222:223], s[24:25], 0, v[130:131]
	s_mov_b32 m0, s11
	s_nop 0
	global_load_lds_dwordx4 v[222:223], off
	s_barrier
	s_setprio 1
	s_waitcnt lgkmcnt(7)
	v_mfma_f32_16x16x32_bf16 v[60:63], v[150:153], v[166:169], v[60:63]
	v_mfma_f32_16x16x32_bf16 v[56:59], v[158:161], v[166:169], v[56:59]
	s_waitcnt lgkmcnt(5)
	v_mfma_f32_16x16x32_bf16 v[52:55], v[150:153], v[174:177], v[52:55]
	v_mfma_f32_16x16x32_bf16 v[48:51], v[158:161], v[174:177], v[48:51]
	s_waitcnt lgkmcnt(3)
	v_mfma_f32_16x16x32_bf16 v[36:39], v[150:153], v[182:185], v[36:39]
	v_mfma_f32_16x16x32_bf16 v[32:35], v[158:161], v[182:185], v[32:35]
	s_waitcnt lgkmcnt(1)
	v_mfma_f32_16x16x32_bf16 v[20:23], v[150:153], v[190:193], v[20:23]
	v_mfma_f32_16x16x32_bf16 v[16:19], v[158:161], v[190:193], v[16:19]
	v_mfma_f32_16x16x32_bf16 v[60:63], v[154:157], v[170:173], v[60:63]
	v_mfma_f32_16x16x32_bf16 v[56:59], v[162:165], v[170:173], v[56:59]
	v_mfma_f32_16x16x32_bf16 v[52:55], v[154:157], v[178:181], v[52:55]
	v_mfma_f32_16x16x32_bf16 v[48:51], v[162:165], v[178:181], v[48:51]
	v_mfma_f32_16x16x32_bf16 v[36:39], v[154:157], v[186:189], v[36:39]
	v_mfma_f32_16x16x32_bf16 v[32:35], v[162:165], v[186:189], v[32:35]
	s_waitcnt lgkmcnt(0)
	v_mfma_f32_16x16x32_bf16 v[20:23], v[154:157], v[198:201], v[20:23]
	v_mfma_f32_16x16x32_bf16 v[16:19], v[162:165], v[198:201], v[16:19]
	s_setprio 0
	s_barrier
; #define PG8_STAGE(bufoff, gbase, voff) do { _Pragma("unroll") for (int _i = 0; _i < 2; ++_i) \
;         __builtin_amdgcn_global_load_lds((const unsigned*)((const char*)(gbase) + (voff)[_i]), (LAS unsigned*)(lds + (bufoff) + ldsw + _i * 8192), 16, 0, 0); } while (0)
; #define PG8_LDA(dst, b, h) do { _Pragma("unroll") for (int m = 0; m < 4; ++m) _Pragma("unroll") for (int k = 0; k < 2; ++k) dst[m][k] = *(const LAS bf16x8*)(lds + PG8_SA(b, h) + aoff + m * 2048 + k * 1024); } while (0)
; #define PG8_LDB(dst, b, h) do { _Pragma("unroll") for (int n = 0; n < 2; ++n) _Pragma("unroll") for (int k = 0; k < 2; ++k) dst[n][k] = *(const LAS bf16x8*)(lds + PG8_SB(b, h) + boff + n * 2048 + k * 1024); } while (0)
; #define PG8_MMA(ai, bj, At, Bt) do { __builtin_amdgcn_s_setprio(1); _Pragma("unroll") for (int m = 0; m < 4; ++m) _Pragma("unroll") for (int n = 0; n < 2; ++n) _Pragma("unroll") for (int k = 0; k < 2; ++k) \
;         acc[ai][bj][m][n] = __builtin_amdgcn_mfma_f32_16x16x32_bf16(Bt[n][k], At[m][k], acc[ai][bj][m][n], 0, 0, 0); __builtin_amdgcn_s_setprio(0); } while (0)
; #define PG8_WAIT_V(n) asm volatile("s_waitcnt vmcnt(" #n ")" ::: "memory")
; #define PG8_WAIT_L(n) asm volatile("s_waitcnt lgkmcnt(" #n ")" ::: "memory")
; #define PG8_BAR __builtin_amdgcn_s_barrier()
; #define PG8_SCHED __builtin_amdgcn_sched_barrier(0)
; template <class Map, class Epi>
; DI void gemm_phase(LAS unsigned char* lds, const Map& MP, const Epi& E, const int nM, const int nN, const int K, const int lda, const int ldb) {
;     ...
;             PG8_WAIT_V(6); PG8_BAR; PG8_MMA(1, 1, At, B1); PG8_BAR;
;             PG8_LDB(B0, 1, 0); PG8_SCHED; PG8_LDA(At, 1, 0); PG8_STAGE(PG8_SA(0, 1), a2 + hstepA, voffA);
;             PG8_WAIT_L(8); PG8_BAR; PG8_WAIT_L(0); PG8_MMA(0, 0, At, B0); PG8_BAR; PG8_SCHED;
;             PG8_LDB(B1, 1, 1); PG8_STAGE(PG8_SB(1, 0), b3, voffB);
;             PG8_BAR; PG8_WAIT_L(0); PG8_MMA(0, 1, At, B1); PG8_BAR;
;             PG8_LDA(At, 1, 1); PG8_STAGE(PG8_SA(1, 0), a3, voffA);
;             PG8_BAR; PG8_WAIT_L(0); PG8_MMA(1, 0, At, B0); PG8_BAR; PG8_SCHED;
	s_add_u32 s56, s22, 0x80000
	s_addc_u32 s57, s23, 0
	s_add_i32 s3, s45, s29
	v_lshl_add_u64 v[150:151], s[56:57], 0, v[132:133]
	s_mov_b32 m0, s3
	s_nop 0
	global_load_lds_dwordx4 v[150:151], off
	v_lshl_add_u64 v[150:151], s[56:57], 0, v[128:129]
	s_add_i32 m0, s3, 0x2000
	s_nop 0
	global_load_lds_dwordx4 v[150:151], off
	s_waitcnt vmcnt(6)
	s_barrier
	s_setprio 1
	v_mfma_f32_16x16x32_bf16 v[44:47], v[202:205], v[166:169], v[44:47]
	v_mfma_f32_16x16x32_bf16 v[40:43], v[210:213], v[166:169], v[40:43]
	v_mfma_f32_16x16x32_bf16 v[28:31], v[202:205], v[174:177], v[28:31]
	v_mfma_f32_16x16x32_bf16 v[24:27], v[210:213], v[174:177], v[24:27]
	v_mfma_f32_16x16x32_bf16 v[12:15], v[202:205], v[182:185], v[12:15]
	v_mfma_f32_16x16x32_bf16 v[8:11], v[210:213], v[182:185], v[8:11]
	v_mfma_f32_16x16x32_bf16 v[4:7], v[202:205], v[190:193], v[4:7]
	v_mfma_f32_16x16x32_bf16 v[0:3], v[210:213], v[190:193], v[0:3]
	v_mfma_f32_16x16x32_bf16 v[44:47], v[206:209], v[170:173], v[44:47]
	v_mfma_f32_16x16x32_bf16 v[40:43], v[214:217], v[170:173], v[40:43]
	v_mfma_f32_16x16x32_bf16 v[28:31], v[206:209], v[178:181], v[28:31]
	v_mfma_f32_16x16x32_bf16 v[24:27], v[214:217], v[178:181], v[24:27]
	v_mfma_f32_16x16x32_bf16 v[12:15], v[206:209], v[186:189], v[12:15]
	v_mfma_f32_16x16x32_bf16 v[8:11], v[214:217], v[186:189], v[8:11]
	v_mfma_f32_16x16x32_bf16 v[4:7], v[206:209], v[198:201], v[4:7]
	v_mfma_f32_16x16x32_bf16 v[0:3], v[214:217], v[198:201], v[0:3]
	s_setprio 0
	s_add_i32 s3, 0, 0x18000
	v_add_u32_e32 v162, s3, v146
	s_barrier
	ds_read_b128 v[150:153], v162
	ds_read_b128 v[154:157], v162 offset:1024
	ds_read_b128 v[158:161], v162 offset:2048
	ds_read_b128 v[162:165], v162 offset:3072
	s_add_u32 s24, s24, 0x80000
	s_addc_u32 s25, s25, 0
	s_mov_b32 m0, s34
	v_lshl_add_u64 v[202:203], s[24:25], 0, v[134:135]
	ds_read_b128 v[166:169], v148 offset:32768
	ds_read_b128 v[170:173], v148 offset:33792
	ds_read_b128 v[174:177], v148 offset:34816
	ds_read_b128 v[178:181], v148 offset:35840
	ds_read_b128 v[182:185], v148 offset:36864
	ds_read_b128 v[186:189], v148 offset:37888
	ds_read_b128 v[190:193], v148 offset:38912
	ds_read_b128 v[198:201], v148 offset:39936
	global_load_lds_dwordx4 v[202:203], off
	v_lshl_add_u64 v[202:203], s[24:25], 0, v[130:131]
	s_mov_b32 m0, s35
	s_nop 0
	global_load_lds_dwordx4 v[202:203], off
	s_waitcnt lgkmcnt(8)
	s_barrier
	s_setprio 1
	s_waitcnt lgkmcnt(7)
	v_mfma_f32_16x16x32_bf16 v[124:127], v[150:153], v[166:169], v[124:127]
	v_mfma_f32_16x16x32_bf16 v[120:123], v[158:161], v[166:169], v[120:123]
	s_waitcnt lgkmcnt(5)
	v_mfma_f32_16x16x32_bf16 v[116:119], v[150:153], v[174:177], v[116:119]
	v_mfma_f32_16x16x32_bf16 v[112:115], v[158:161], v[174:177], v[112:115]
	s_waitcnt lgkmcnt(3)
	v_mfma_f32_16x16x32_bf16 v[100:103], v[150:153], v[182:185], v[100:103]
	v_mfma_f32_16x16x32_bf16 v[96:99], v[158:161], v[182:185], v[96:99]
	s_waitcnt lgkmcnt(1)
	v_mfma_f32_16x16x32_bf16 v[84:87], v[150:153], v[190:193], v[84:87]
	v_mfma_f32_16x16x32_bf16 v[80:83], v[158:161], v[190:193], v[80:83]
	v_mfma_f32_16x16x32_bf16 v[124:127], v[154:157], v[170:173], v[124:127]
	v_mfma_f32_16x16x32_bf16 v[120:123], v[162:165], v[170:173], v[120:123]
	v_mfma_f32_16x16x32_bf16 v[116:119], v[154:157], v[178:181], v[116:119]
	v_mfma_f32_16x16x32_bf16 v[112:115], v[162:165], v[178:181], v[112:115]
	v_mfma_f32_16x16x32_bf16 v[100:103], v[154:157], v[186:189], v[100:103]
	v_mfma_f32_16x16x32_bf16 v[96:99], v[162:165], v[186:189], v[96:99]
	s_waitcnt lgkmcnt(0)
	v_mfma_f32_16x16x32_bf16 v[84:87], v[154:157], v[198:201], v[84:87]
	v_mfma_f32_16x16x32_bf16 v[80:83], v[162:165], v[198:201], v[80:83]
	s_setprio 0
	s_barrier
	s_add_i32 s24, 0, 0x1c000
	s_add_i32 s3, s3, s29
	v_add_u32_e32 v196, s24, v146
	v_lshl_add_u64 v[194:195], v[194:195], 0, s[8:9]
	s_mov_b32 m0, s3
	ds_read_b128 v[202:205], v196
	ds_read_b128 v[206:209], v196 offset:1024
	ds_read_b128 v[210:213], v196 offset:2048
	ds_read_b128 v[214:217], v196 offset:3072
	global_load_lds_dwordx4 v[194:195], off
	v_lshl_add_u64 v[194:195], v[218:219], 0, s[8:9]
	s_add_i32 m0, s3, 0x2000
	s_nop 0
	global_load_lds_dwordx4 v[194:195], off
	s_barrier
	s_setprio 1
	s_waitcnt lgkmcnt(3)
	v_mfma_f32_16x16x32_bf16 v[108:111], v[202:205], v[166:169], v[108:111]
	s_waitcnt lgkmcnt(1)
	v_mfma_f32_16x16x32_bf16 v[104:107], v[210:213], v[166:169], v[104:107]
	v_mfma_f32_16x16x32_bf16 v[92:95], v[202:205], v[174:177], v[92:95]
	v_mfma_f32_16x16x32_bf16 v[88:91], v[210:213], v[174:177], v[88:91]
	v_mfma_f32_16x16x32_bf16 v[76:79], v[202:205], v[182:185], v[76:79]
	v_mfma_f32_16x16x32_bf16 v[72:75], v[210:213], v[182:185], v[72:75]
	v_mfma_f32_16x16x32_bf16 v[68:71], v[202:205], v[190:193], v[68:71]
	v_mfma_f32_16x16x32_bf16 v[64:67], v[210:213], v[190:193], v[64:67]
	v_mfma_f32_16x16x32_bf16 v[108:111], v[206:209], v[170:173], v[108:111]
	s_waitcnt lgkmcnt(0)
	v_mfma_f32_16x16x32_bf16 v[104:107], v[214:217], v[170:173], v[104:107]
	v_mfma_f32_16x16x32_bf16 v[92:95], v[206:209], v[178:181], v[92:95]
	v_mfma_f32_16x16x32_bf16 v[88:91], v[214:217], v[178:181], v[88:91]
	v_mfma_f32_16x16x32_bf16 v[76:79], v[206:209], v[186:189], v[76:79]
	v_mfma_f32_16x16x32_bf16 v[72:75], v[214:217], v[186:189], v[72:75]
	v_mfma_f32_16x16x32_bf16 v[68:71], v[206:209], v[198:201], v[68:71]
	v_mfma_f32_16x16x32_bf16 v[64:67], v[214:217], v[198:201], v[64:67]
	s_setprio 0
	s_mov_b32 m0, s39
	v_lshl_add_u64 v[194:195], v[220:221], 0, s[8:9]
	s_barrier
; #define PG8_STAGE(bufoff, gbase, voff) do { _Pragma("unroll") for (int _i = 0; _i < 2; ++_i) \
;         __builtin_amdgcn_global_load_lds((const unsigned*)((const char*)(gbase) + (voff)[_i]), (LAS unsigned*)(lds + (bufoff) + ldsw + _i * 8192), 16, 0, 0); } while (0)
; #define PG8_MMA(ai, bj, At, Bt) do { __builtin_amdgcn_s_setprio(1); _Pragma("unroll") for (int m = 0; m < 4; ++m) _Pragma("unroll") for (int n = 0; n < 2; ++n) _Pragma("unroll") for (int k = 0; k < 2; ++k) \
;         acc[ai][bj][m][n] = __builtin_amdgcn_mfma_f32_16x16x32_bf16(Bt[n][k], At[m][k], acc[ai][bj][m][n], 0, 0, 0); __builtin_amdgcn_s_setprio(0); } while (0)
; #define PG8_WAIT_V(n) asm volatile("s_waitcnt vmcnt(" #n ")" ::: "memory")
; #define PG8_WAIT_L(n) asm volatile("s_waitcnt lgkmcnt(" #n ")" ::: "memory")
; #define PG8_BAR __builtin_amdgcn_s_barrier()
; #define PG8_SCHED __builtin_amdgcn_sched_barrier(0)
; template <class Map, class Epi>
; DI void gemm_phase(LAS unsigned char* lds, const Map& MP, const Epi& E, const int nM, const int nN, const int K, const int lda, const int ldb) {
;     ...
;             PG8_BAR; PG8_WAIT_L(0); PG8_MMA(1, 0, At, B0); PG8_BAR; PG8_SCHED;
;             PG8_STAGE(PG8_SB(1, 1), b3 + hstepB, voffB);
;             PG8_WAIT_V(6); PG8_BAR; PG8_MMA(1, 1, At, B1); PG8_BAR;
	ds_read_b128 v[166:169], v148 offset:49152
	ds_read_b128 v[170:173], v148 offset:50176
	ds_read_b128 v[174:177], v148 offset:51200
	ds_read_b128 v[178:181], v148 offset:52224
	ds_read_b128 v[182:185], v148 offset:53248
	ds_read_b128 v[186:189], v148 offset:54272
	ds_read_b128 v[190:193], v148 offset:55296
	ds_read_b128 v[198:201], v148 offset:56320
	global_load_lds_dwordx4 v[194:195], off
	v_lshl_add_u64 v[194:195], v[222:223], 0, s[8:9]
	s_mov_b32 m0, s42
	s_nop 0
	global_load_lds_dwordx4 v[194:195], off
	s_barrier
	s_setprio 1
	s_waitcnt lgkmcnt(7)
	v_mfma_f32_16x16x32_bf16 v[60:63], v[150:153], v[166:169], v[60:63]
	v_mfma_f32_16x16x32_bf16 v[56:59], v[158:161], v[166:169], v[56:59]
	s_waitcnt lgkmcnt(5)
	v_mfma_f32_16x16x32_bf16 v[52:55], v[150:153], v[174:177], v[52:55]
	v_mfma_f32_16x16x32_bf16 v[48:51], v[158:161], v[174:177], v[48:51]
	s_waitcnt lgkmcnt(3)
	v_mfma_f32_16x16x32_bf16 v[36:39], v[150:153], v[182:185], v[36:39]
	v_mfma_f32_16x16x32_bf16 v[32:35], v[158:161], v[182:185], v[32:35]
	s_waitcnt lgkmcnt(1)
	v_mfma_f32_16x16x32_bf16 v[20:23], v[150:153], v[190:193], v[20:23]
	v_mfma_f32_16x16x32_bf16 v[16:19], v[158:161], v[190:193], v[16:19]
	v_mfma_f32_16x16x32_bf16 v[60:63], v[154:157], v[170:173], v[60:63]
	v_mfma_f32_16x16x32_bf16 v[56:59], v[162:165], v[170:173], v[56:59]
	v_mfma_f32_16x16x32_bf16 v[52:55], v[154:157], v[178:181], v[52:55]
	v_mfma_f32_16x16x32_bf16 v[48:51], v[162:165], v[178:181], v[48:51]
	v_mfma_f32_16x16x32_bf16 v[36:39], v[154:157], v[186:189], v[36:39]
	v_mfma_f32_16x16x32_bf16 v[32:35], v[162:165], v[186:189], v[32:35]
	s_waitcnt lgkmcnt(0)
	v_mfma_f32_16x16x32_bf16 v[20:23], v[154:157], v[198:201], v[20:23]
	v_mfma_f32_16x16x32_bf16 v[16:19], v[162:165], v[198:201], v[16:19]
	s_setprio 0
	s_barrier
	s_add_u32 s22, s22, 0x80080
	s_addc_u32 s23, s23, 0
	s_add_i32 s3, s24, s29
	v_lshl_add_u64 v[150:151], s[22:23], 0, v[132:133]
	s_mov_b32 m0, s3
	s_nop 0
	global_load_lds_dwordx4 v[150:151], off
	v_lshl_add_u64 v[150:151], s[22:23], 0, v[128:129]
	s_add_i32 m0, s3, 0x2000
	s_nop 0
	global_load_lds_dwordx4 v[150:151], off
	s_waitcnt vmcnt(6)
	s_barrier
	s_setprio 1
	v_mfma_f32_16x16x32_bf16 v[44:47], v[202:205], v[166:169], v[44:47]
	v_mfma_f32_16x16x32_bf16 v[40:43], v[210:213], v[166:169], v[40:43]
	v_mfma_f32_16x16x32_bf16 v[28:31], v[202:205], v[174:177], v[28:31]
	v_mfma_f32_16x16x32_bf16 v[24:27], v[210:213], v[174:177], v[24:27]
	v_mfma_f32_16x16x32_bf16 v[12:15], v[202:205], v[182:185], v[12:15]
	v_mfma_f32_16x16x32_bf16 v[8:11], v[210:213], v[182:185], v[8:11]
	v_mfma_f32_16x16x32_bf16 v[4:7], v[202:205], v[190:193], v[4:7]
	v_mfma_f32_16x16x32_bf16 v[0:3], v[210:213], v[190:193], v[0:3]
	v_mfma_f32_16x16x32_bf16 v[44:47], v[206:209], v[170:173], v[44:47]
	v_mfma_f32_16x16x32_bf16 v[40:43], v[214:217], v[170:173], v[40:43]
	v_mfma_f32_16x16x32_bf16 v[28:31], v[206:209], v[178:181], v[28:31]
	v_mfma_f32_16x16x32_bf16 v[24:27], v[214:217], v[178:181], v[24:27]
	v_mfma_f32_16x16x32_bf16 v[12:15], v[206:209], v[186:189], v[12:15]
	v_mfma_f32_16x16x32_bf16 v[8:11], v[214:217], v[186:189], v[8:11]
	v_mfma_f32_16x16x32_bf16 v[4:7], v[206:209], v[198:201], v[4:7]
	v_mfma_f32_16x16x32_bf16 v[0:3], v[214:217], v[198:201], v[0:3]
	s_setprio 0
	s_add_i32 s54, s54, 2
	s_add_u32 s52, s52, 0x100
	s_addc_u32 s53, s53, 0
	s_add_u32 s20, s20, 0x100
	s_addc_u32 s21, s21, 0
	s_cmp_gt_u32 s54, 29
	s_barrier
	s_cbranch_scc0 .LBB1_693
; DI unsigned pack2(float a, float b) { f32x2 v = {a, b}; hwbf16x2 r = __builtin_convertvector(v, hwbf16x2); return __builtin_bit_cast(unsigned, r); }
;     DI const char* a(const Unit& u) const { return (const char*)(A + (size_t)u.pm * BM * lda); }
;     DI const char* a(const Unit& u) const { return (const char*)(A + (size_t)u.pm * BM * 2048 + (u.pn >> 1) * 512); }
;     DI const char* a(const Unit& u) const { return (const char*)((u.pn < 12 ? A1 : A2) + (size_t)u.pm * BM * 512); }
; #define PG8_WAIT_V(n) asm volatile("s_waitcnt vmcnt(" #n ")" ::: "memory")
; #define PG8_BAR __builtin_amdgcn_s_barrier()
;     DI void operator()(const f32x4 (&acc)[2][2][4][2], const Unit& u, int wr, int wc, int fr, int fq) const {
;         bf16_t* O = O1; int ldc = ldc1, pn = u.pn; if (pn >= split) { O = O2; ldc = ldc2; pn -= split; }
;         const int row0 = u.pm * BM + wr * 64 + fr, col0 = pn * BM + wc * 32 + 8 * fq;
; #pragma unroll
;         for (int ai = 0; ai < 2; ++ai)
; #pragma unroll
;             for (int m = 0; m < 4; ++m) { bf16_t* rowp = O + (size_t)(row0 + ai * HALF + m * 16) * ldc + col0;
; #pragma unroll
;                 for (int bj = 0; bj < 2; ++bj) { const f32x4 v0 = acc[ai][bj][m][0], v1 = acc[ai][bj][m][1];
;                     u32x4 o; o[0] = pack2(v0[0], v0[1]); o[1] = pack2(v0[2], v0[3]); o[2] = pack2(v1[0], v1[1]); o[3] = pack2(v1[2], v1[3]);
;                     *(u32x4*)(rowp + bj * HALF) = o; } }
;     }
; template <class Map, class Epi>
; DI void gemm_phase(LAS unsigned char* lds, const Map& MP, const Epi& E, const int nM, const int nN, const int K, const int lda, const int ldb) {
;     ...
;         if (!has_next) break;
; #pragma unroll
;         for (int a = 0; a < 2; ++a)
; #pragma unroll
;             for (int b = 0; b < 2; ++b)
; #pragma unroll
;                 for (int m = 0; m < 4; ++m)
; #pragma unroll
;                     for (int n = 0; n < 2; ++n) acc[a][b][m][n] = (f32x4){0.f, 0.f, 0.f, 0.f};
;         cur = nxt; cA = nA; cB = nB; ++ui;
;     }
;     PG8_WAIT_V(0);
;     if (wr == 0) PG8_BAR;
;     PG8_BAR;
	s_lshl_b32 s3, s10, 8
	v_mov_b32_e32 v150, v144
	v_mov_b32_e32 v151, v145
	s_add_i32 s3, s3, s37
	v_cvt_pk_bf16_f32 v68, v68, v69
	v_add_u32_e32 v154, s3, v150
	s_lshl_b32 s3, s47, 8
	s_or_b32 s3, s3, s38
	v_lshl_add_u32 v150, v151, 3, s3
	v_ashrrev_i32_e32 v151, 31, v150
	v_lshl_add_u64 v[150:151], v[150:151], 1, s[6:7]
	v_cvt_pk_bf16_f32 v69, v70, v71
	v_cvt_pk_bf16_f32 v70, v64, v65
	v_add_u32_e32 v64, 0x80, v154
	v_mad_i64_i32 v[152:153], s[20:21], v154, s46, v[150:151]
	v_cvt_pk_bf16_f32 v108, v108, v109
	v_cvt_pk_bf16_f32 v109, v110, v111
	v_cvt_pk_bf16_f32 v110, v104, v105
	v_cvt_pk_bf16_f32 v111, v106, v107
	v_add_u32_e32 v104, 16, v154
	v_mad_i64_i32 v[64:65], s[20:21], v64, s46, v[150:151]
	v_cvt_pk_bf16_f32 v44, v44, v45
	v_cvt_pk_bf16_f32 v45, v46, v47
	v_cvt_pk_bf16_f32 v46, v40, v41
	v_cvt_pk_bf16_f32 v47, v42, v43
	v_add_u32_e32 v40, 0x90, v154
	global_store_dwordx4 v[152:153], v[108:111], off offset:256
	v_cvt_pk_bf16_f32 v92, v92, v93
	v_cvt_pk_bf16_f32 v93, v94, v95
	v_mad_i64_i32 v[108:109], s[20:21], v104, s46, v[150:151]
	v_cvt_pk_bf16_f32 v94, v88, v89
	v_cvt_pk_bf16_f32 v95, v90, v91
	v_add_u32_e32 v88, 32, v154
	global_store_dwordx4 v[64:65], v[44:47], off offset:256
	v_cvt_pk_bf16_f32 v28, v28, v29
	v_cvt_pk_bf16_f32 v29, v30, v31
	v_mad_i64_i32 v[44:45], s[20:21], v40, s46, v[150:151]
	v_cvt_pk_bf16_f32 v30, v24, v25
	v_cvt_pk_bf16_f32 v31, v26, v27
	v_add_u32_e32 v24, 0xa0, v154
	global_store_dwordx4 v[108:109], v[92:95], off offset:256
	v_cvt_pk_bf16_f32 v76, v76, v77
	v_cvt_pk_bf16_f32 v77, v78, v79
	v_mad_i64_i32 v[92:93], s[20:21], v88, s46, v[150:151]
	v_cvt_pk_bf16_f32 v78, v72, v73
	v_cvt_pk_bf16_f32 v79, v74, v75
	v_add_u32_e32 v72, 48, v154
	global_store_dwordx4 v[44:45], v[28:31], off offset:256
	v_cvt_pk_bf16_f32 v12, v12, v13
	v_cvt_pk_bf16_f32 v13, v14, v15
	v_mad_i64_i32 v[28:29], s[20:21], v24, s46, v[150:151]
	v_cvt_pk_bf16_f32 v14, v8, v9
	v_cvt_pk_bf16_f32 v15, v10, v11
	v_add_u32_e32 v8, 0xb0, v154
	global_store_dwordx4 v[92:93], v[76:79], off offset:256
	global_store_dwordx4 v[28:29], v[12:15], off offset:256
	v_cvt_pk_bf16_f32 v124, v124, v125
	v_mad_i64_i32 v[76:77], s[20:21], v72, s46, v[150:151]
	v_mad_i64_i32 v[12:13], s[20:21], v8, s46, v[150:151]
	v_cvt_pk_bf16_f32 v125, v126, v127
	v_cvt_pk_bf16_f32 v126, v120, v121
	v_cvt_pk_bf16_f32 v127, v122, v123
	v_cvt_pk_bf16_f32 v104, v116, v117
	v_cvt_pk_bf16_f32 v105, v118, v119
	v_cvt_pk_bf16_f32 v106, v112, v113
	v_cvt_pk_bf16_f32 v107, v114, v115
	v_cvt_pk_bf16_f32 v88, v100, v101
	v_cvt_pk_bf16_f32 v89, v102, v103
	v_cvt_pk_bf16_f32 v90, v96, v97
	v_cvt_pk_bf16_f32 v91, v98, v99
	v_cvt_pk_bf16_f32 v72, v84, v85
	v_cvt_pk_bf16_f32 v73, v86, v87
	v_cvt_pk_bf16_f32 v74, v80, v81
	v_cvt_pk_bf16_f32 v75, v82, v83
	v_cvt_pk_bf16_f32 v71, v66, v67
	v_cvt_pk_bf16_f32 v60, v60, v61
	v_cvt_pk_bf16_f32 v61, v62, v63
	v_cvt_pk_bf16_f32 v62, v56, v57
	v_cvt_pk_bf16_f32 v63, v58, v59
	v_cvt_pk_bf16_f32 v40, v52, v53
	v_cvt_pk_bf16_f32 v41, v54, v55
	v_cvt_pk_bf16_f32 v42, v48, v49
	v_cvt_pk_bf16_f32 v43, v50, v51
	v_cvt_pk_bf16_f32 v24, v36, v37
	v_cvt_pk_bf16_f32 v25, v38, v39
	v_cvt_pk_bf16_f32 v26, v32, v33
	v_cvt_pk_bf16_f32 v27, v34, v35
	v_cvt_pk_bf16_f32 v8, v20, v21
	v_cvt_pk_bf16_f32 v9, v22, v23
	v_cvt_pk_bf16_f32 v10, v16, v17
	v_cvt_pk_bf16_f32 v11, v18, v19
	v_cvt_pk_bf16_f32 v4, v4, v5
	v_cvt_pk_bf16_f32 v5, v6, v7
	v_cvt_pk_bf16_f32 v6, v0, v1
	v_cvt_pk_bf16_f32 v7, v2, v3
	s_and_b64 vcc, exec, s[40:41]
	s_mov_b32 s47, s12
	s_mov_b32 s10, s14
	s_mov_b64 s[20:21], s[18:19]
	s_mov_b64 s[22:23], s[16:17]
	global_store_dwordx4 v[152:153], v[124:127], off
	global_store_dwordx4 v[108:109], v[104:107], off
	global_store_dwordx4 v[92:93], v[88:91], off
	global_store_dwordx4 v[76:77], v[72:75], off
	global_store_dwordx4 v[76:77], v[68:71], off offset:256
	global_store_dwordx4 v[64:65], v[60:63], off
	global_store_dwordx4 v[44:45], v[40:43], off
	global_store_dwordx4 v[28:29], v[24:27], off
	global_store_dwordx4 v[12:13], v[8:11], off
	global_store_dwordx4 v[12:13], v[4:7], off offset:256
	s_cbranch_vccz .LBB1_690
	s_waitcnt vmcnt(0)
	s_cmpk_gt_u32 s4, 0xff
	s_cbranch_scc1 .LBB1_697
	s_barrier

; DI unsigned pack2(float a, float b) { f32x2 v = {a, b}; hwbf16x2 r = __builtin_convertvector(v, hwbf16x2); return __builtin_bit_cast(unsigned, r); }
; DI float bflo(unsigned w) { return __uint_as_float(w << 16); }
; DI float bfhi(unsigned w) { return __uint_as_float(w & 0xffff0000u); }
; DI float sum16(float v) { v += dppf<0x128>(v); v += dppf<0x124>(v); v += dppf<0x122>(v); v += dppf<0x121>(v); return v; }
; DI void swa_prep_phase(const Params& p) {
;     ...
;         u32x2 wl[2][9];
; #pragma unroll
;         for (int q2 = 0; q2 < 2; ++q2) { const int tq = t0 + q2 * tstep; if (tq < T) {
; #pragma unroll
;             for (int it = 0; it < 9; ++it) wl[q2][it] = *(const u32x2*)(QKV + (size_t)tq * 2560 + it * 256 + lane * 4); } }
; #pragma unroll
;       for (int q2 = 0; q2 < 2; ++q2) { const int t = t0 + q2 * tstep; if (t < T) {
;         const int b = t / S, s = t - b * S;
; #pragma unroll
;         for (int it = 0; it < 9; ++it) {
;             const int col = it * 256 + lane * 4;
;             const u32x2 wv = wl[q2][it]; const f32x4 v = {bflo(wv[0]), bfhi(wv[0]), bflo(wv[1]), bfhi(wv[1])};
;             float ss = v[0] * v[0] + v[1] * v[1] + v[2] * v[2] + v[3] * v[3];
;             ss = sum16(ss);
;             const float rs = rsqrtf(ss * (1.0f / 64.f) + EPS);
;             const int d = col & 63;
;             if (it < 8) { const f32x4 g = *(const f32x4*)(p.swa_q_gain + d); const float f = rs * qsc;
;                 u32x2 o; o[0] = pack2(v[0] * f * g[0], v[1] * f * g[1]); o[1] = pack2(v[2] * f * g[2], v[3] * f * g[3]);
;                 *(u32x2*)(QS + (size_t)t * 2048 + col) = o; }
.LBB1_765:
	v_mad_i64_i32 v[32:33], s[18:19], v0, s5, v[4:5]
	global_load_dwordx2 v[2:3], v[32:33], off
	global_load_dwordx2 v[52:53], v[32:33], off offset:512
	global_load_dwordx2 v[42:43], v[32:33], off offset:1024
	global_load_dwordx2 v[50:51], v[32:33], off offset:1536
	global_load_dwordx2 v[48:49], v[32:33], off offset:2048
	global_load_dwordx2 v[46:47], v[32:33], off offset:2560
	global_load_dwordx2 v[44:45], v[32:33], off offset:3072
	global_load_dwordx2 v[40:41], v[32:33], off offset:3584
	v_add_co_u32_e32 v32, vcc, 0x1000, v32
	s_nop 1
	v_addc_co_u32_e32 v33, vcc, 0, v33, vcc
	global_load_dwordx2 v[38:39], v[32:33], off
	v_add_u32_e32 v32, s33, v0
	v_cmp_gt_i32_e64 s[40:41], s2, v32
	s_and_saveexec_b64 s[18:19], s[40:41]
	s_cbranch_execz .LBB1_767
	v_mad_i64_i32 v[30:31], s[20:21], v32, s5, v[4:5]
	global_load_dwordx2 v[28:29], v[30:31], off
	global_load_dwordx2 v[26:27], v[30:31], off offset:512
	global_load_dwordx2 v[24:25], v[30:31], off offset:1024
	global_load_dwordx2 v[22:23], v[30:31], off offset:1536
	global_load_dwordx2 v[20:21], v[30:31], off offset:2048
	global_load_dwordx2 v[18:19], v[30:31], off offset:2560
	global_load_dwordx2 v[16:17], v[30:31], off offset:3072
	global_load_dwordx2 v[14:15], v[30:31], off offset:3584
	v_add_co_u32_e32 v30, vcc, 0x1000, v30
	s_nop 1
	v_addc_co_u32_e32 v31, vcc, 0, v31, vcc
	global_load_dwordx2 v[30:31], v[30:31], off
.LBB1_767:
	s_or_b64 exec, exec, s[18:19]
	global_load_dwordx4 v[54:57], v[10:11], off
	s_waitcnt vmcnt(0) lgkmcnt(0)
	v_lshlrev_b32_e32 v64, 16, v2
	v_and_b32_e32 v65, 0xffff0000, v2
	v_lshlrev_b32_e32 v36, 16, v3
	v_and_b32_e32 v37, 0xffff0000, v3
	v_pk_mul_f32 v[2:3], v[64:65], v[64:65]
	v_pk_mul_f32 v[58:59], v[36:37], v[36:37]
	v_add_f32_e32 v2, v2, v3
	v_add_f32_e32 v2, v58, v2
	v_add_f32_e32 v2, v59, v2
	v_ashrrev_i32_e32 v33, 31, v0
	v_lshrrev_b32_e32 v33, 20, v33
	v_add_f32_dpp v2, v2, v2 row_ror:8 row_mask:0xf bank_mask:0xf bound_ctrl:1
	v_add_u32_e32 v34, v0, v33
	v_ashrrev_i32_e32 v1, 31, v0
	v_add_f32_dpp v2, v2, v2 row_ror:4 row_mask:0xf bank_mask:0xf bound_ctrl:1
	v_ashrrev_i32_e32 v33, 12, v34
	v_and_b32_e32 v34, 0xfffff000, v34
	v_add_f32_dpp v2, v2, v2 row_ror:2 row_mask:0xf bank_mask:0xf bound_ctrl:1
	v_sub_u32_e32 v34, v0, v34
	v_lshlrev_b64 v[0:1], 12, v[0:1]
	v_add_f32_dpp v2, v2, v2 row_ror:1 row_mask:0xf bank_mask:0xf bound_ctrl:1
	v_fmamk_f32 v2, v2, 0x3c800000, v62
	v_cmp_gt_f32_e32 vcc, s15, v2
	v_mul_f32_e32 v3, 0x4b800000, v2
	v_ashrrev_i32_e32 v35, 31, v34
	v_cndmask_b32_e32 v2, v2, v3, vcc
	v_rsq_f32_e32 v2, v2
	v_lshlrev_b64 v[34:35], 7, v[34:35]
	v_lshl_add_u64 v[34:35], v[6:7], 0, v[34:35]
	v_mul_f32_e32 v3, 0x45800000, v2
	v_cndmask_b32_e32 v2, v2, v3, vcc
	v_mul_f32_e32 v2, 0x3e38aa3b, v2
	v_pk_mul_f32 v[58:59], v[2:3], v[64:65] op_sel_hi:[0,1]
	v_pk_mul_f32 v[2:3], v[2:3], v[36:37] op_sel_hi:[0,1]
	v_lshl_add_u64 v[36:37], v[8:9], 0, v[0:1]
	v_pk_mul_f32 v[54:55], v[54:55], v[58:59]
	v_pk_mul_f32 v[2:3], v[56:57], v[2:3]
	v_cvt_pk_bf16_f32 v54, v54, v55
	v_cvt_pk_bf16_f32 v55, v2, v3
	global_store_dwordx2 v[36:37], v[54:55], off
	global_load_dwordx4 v[0:3], v[10:11], off
	v_lshlrev_b32_e32 v58, 16, v52
	v_and_b32_e32 v59, 0xffff0000, v52
	v_lshlrev_b32_e32 v56, 16, v42
	v_and_b32_e32 v57, 0xffff0000, v42
	v_lshlrev_b32_e32 v54, 16, v53
	v_and_b32_e32 v55, 0xffff0000, v53
	v_pk_mul_f32 v[66:67], v[58:59], v[58:59]
	v_lshlrev_b32_e32 v52, 16, v43
	v_and_b32_e32 v53, 0xffff0000, v43
	v_pk_mul_f32 v[42:43], v[56:57], v[56:57]
	v_pk_mul_f32 v[64:65], v[54:55], v[54:55]
	v_pk_mul_f32 v[68:69], v[52:53], v[52:53]
	v_mov_b32_e32 v70, v42
	v_mov_b32_e32 v71, v66
	v_mov_b32_e32 v66, v43
	v_pk_add_f32 v[42:43], v[70:71], v[66:67]
	v_mov_b32_e32 v66, v68
	v_mov_b32_e32 v67, v64
	v_pk_add_f32 v[42:43], v[66:67], v[42:43]
	v_mov_b32_e32 v64, v69
	v_pk_add_f32 v[42:43], v[64:65], v[42:43]
	v_mov_b32_e32 v65, 0
	v_mov_b32_e32 v64, 0
	s_nop 0
	v_mov_b32_dpp v65, v43 row_ror:8 row_mask:0xf bank_mask:0xf
	v_mov_b32_dpp v64, v42 row_ror:8 row_mask:0xf bank_mask:0xf
	v_pk_add_f32 v[42:43], v[42:43], v[64:65]
	v_mov_b32_e32 v65, 0
	v_mov_b32_e32 v64, 0
	s_nop 0
	v_mov_b32_dpp v65, v43 row_ror:4 row_mask:0xf bank_mask:0xf
	v_mov_b32_dpp v64, v42 row_ror:4 row_mask:0xf bank_mask:0xf
	v_pk_add_f32 v[42:43], v[42:43], v[64:65]
	v_mov_b32_e32 v65, 0
	v_mov_b32_e32 v64, 0
	s_nop 0
	v_mov_b32_dpp v65, v43 row_ror:2 row_mask:0xf bank_mask:0xf
	v_mov_b32_dpp v64, v42 row_ror:2 row_mask:0xf bank_mask:0xf
	v_pk_add_f32 v[42:43], v[42:43], v[64:65]
	v_mov_b32_e32 v65, 0
	v_mov_b32_e32 v64, 0
	s_nop 0
	v_mov_b32_dpp v65, v43 row_ror:1 row_mask:0xf bank_mask:0xf
	v_mov_b32_dpp v64, v42 row_ror:1 row_mask:0xf bank_mask:0xf
	v_pk_add_f32 v[64:65], v[42:43], v[64:65]
	v_mov_b64_e32 v[42:43], s[16:17]
	v_pk_fma_f32 v[64:65], v[64:65], s[14:15], v[42:43] op_sel_hi:[1,0,0]
	s_nop 0
	v_mul_f32_e32 v63, 0x4b800000, v65
	v_cmp_gt_f32_e64 s[42:43], s15, v65
	v_cmp_gt_f32_e32 vcc, s15, v64
	s_nop 0
	v_cndmask_b32_e64 v63, v65, v63, s[42:43]
	v_rsq_f32_e32 v63, v63
	s_nop 0
	v_mul_f32_e32 v65, 0x45800000, v63
	v_cndmask_b32_e64 v63, v63, v65, s[42:43]
	v_mul_f32_e32 v66, 0x3e38aa3b, v63
	v_pk_mul_f32 v[58:59], v[66:67], v[58:59] op_sel_hi:[0,1]
	v_pk_mul_f32 v[54:55], v[66:67], v[54:55] op_sel_hi:[0,1]
	s_waitcnt vmcnt(0)
; DI unsigned pack2(float a, float b) { f32x2 v = {a, b}; hwbf16x2 r = __builtin_convertvector(v, hwbf16x2); return __builtin_bit_cast(unsigned, r); }
; DI float bflo(unsigned w) { return __uint_as_float(w << 16); }
; DI float bfhi(unsigned w) { return __uint_as_float(w & 0xffff0000u); }
; DI float sum16(float v) { v += dppf<0x128>(v); v += dppf<0x124>(v); v += dppf<0x122>(v); v += dppf<0x121>(v); return v; }
; DI void swa_prep_phase(const Params& p) {
;     ...
;         for (int it = 0; it < 9; ++it) {
;             const int col = it * 256 + lane * 4;
;             const u32x2 wv = wl[q2][it]; const f32x4 v = {bflo(wv[0]), bfhi(wv[0]), bflo(wv[1]), bfhi(wv[1])};
;             float ss = v[0] * v[0] + v[1] * v[1] + v[2] * v[2] + v[3] * v[3];
;             ss = sum16(ss);
;             const float rs = rsqrtf(ss * (1.0f / 64.f) + EPS);
;             const int d = col & 63;
;             if (it < 8) { const f32x4 g = *(const f32x4*)(p.swa_q_gain + d); const float f = rs * qsc;
;                 u32x2 o; o[0] = pack2(v[0] * f * g[0], v[1] * f * g[1]); o[1] = pack2(v[2] * f * g[2], v[3] * f * g[3]);
;                 *(u32x2*)(QS + (size_t)t * 2048 + col) = o; }
;             else { const f32x4 g = *(const f32x4*)(p.swa_k_gain + d); const int kvh = (col - 2048) >> 6;
;                 u32x2 o; o[0] = pack2(v[0] * rs * g[0], v[1] * rs * g[1]); o[1] = pack2(v[2] * rs * g[2], v[3] * rs * g[3]);
;                 *(u32x2*)(KS + ((size_t)(b * 4 + kvh) * S + s) * 64 + d) = o; }
;         }
	v_pk_mul_f32 v[0:1], v[0:1], v[58:59]
	v_pk_mul_f32 v[2:3], v[2:3], v[54:55]
	v_cvt_pk_bf16_f32 v0, v0, v1
	v_cvt_pk_bf16_f32 v1, v2, v3
	global_store_dwordx2 v[36:37], v[0:1], off offset:512
	global_load_dwordx4 v[0:3], v[10:11], off
	v_mul_f32_e32 v54, 0x4b800000, v64
	v_cndmask_b32_e32 v54, v64, v54, vcc
	v_rsq_f32_e32 v54, v54
	v_lshlrev_b32_e32 v58, 16, v50
	v_and_b32_e32 v59, 0xffff0000, v50
	v_pk_mul_f32 v[64:65], v[58:59], v[58:59]
	v_mul_f32_e32 v55, 0x45800000, v54
	v_cndmask_b32_e32 v54, v54, v55, vcc
	v_mul_f32_e32 v54, 0x3e38aa3b, v54
	v_pk_mul_f32 v[56:57], v[54:55], v[56:57] op_sel_hi:[0,1]
	v_pk_mul_f32 v[52:53], v[54:55], v[52:53] op_sel_hi:[0,1]
	v_lshlrev_b32_e32 v54, 16, v48
	v_and_b32_e32 v55, 0xffff0000, v48
	v_lshlrev_b32_e32 v50, 16, v49
	v_mov_b32_e32 v69, v64
	s_waitcnt vmcnt(0)
	v_pk_mul_f32 v[0:1], v[0:1], v[56:57]
	v_pk_mul_f32 v[2:3], v[2:3], v[52:53]
	v_cvt_pk_bf16_f32 v0, v0, v1
	v_cvt_pk_bf16_f32 v1, v2, v3
	global_store_dwordx2 v[36:37], v[0:1], off offset:1024
	global_load_dwordx4 v[0:3], v[10:11], off
	v_lshlrev_b32_e32 v52, 16, v51
	v_and_b32_e32 v53, 0xffff0000, v51
	v_and_b32_e32 v51, 0xffff0000, v49
	v_pk_mul_f32 v[48:49], v[54:55], v[54:55]
	v_pk_mul_f32 v[56:57], v[52:53], v[52:53]
	v_pk_mul_f32 v[66:67], v[50:51], v[50:51]
	v_mov_b32_e32 v68, v48
	v_mov_b32_e32 v64, v49
	v_pk_add_f32 v[48:49], v[68:69], v[64:65]
	v_mov_b32_e32 v64, v66
	v_mov_b32_e32 v65, v56
	v_pk_add_f32 v[48:49], v[64:65], v[48:49]
	v_mov_b32_e32 v56, v67
	v_pk_add_f32 v[48:49], v[56:57], v[48:49]
	v_mov_b32_e32 v57, 0
	v_mov_b32_e32 v56, 0
	s_nop 0
	v_mov_b32_dpp v57, v49 row_ror:8 row_mask:0xf bank_mask:0xf
	v_mov_b32_dpp v56, v48 row_ror:8 row_mask:0xf bank_mask:0xf
	v_pk_add_f32 v[48:49], v[48:49], v[56:57]
	v_mov_b32_e32 v57, 0
	v_mov_b32_e32 v56, 0
	s_nop 0
	v_mov_b32_dpp v57, v49 row_ror:4 row_mask:0xf bank_mask:0xf
	v_mov_b32_dpp v56, v48 row_ror:4 row_mask:0xf bank_mask:0xf
	v_pk_add_f32 v[48:49], v[48:49], v[56:57]
	v_mov_b32_e32 v57, 0
	v_mov_b32_e32 v56, 0
	s_nop 0
	v_mov_b32_dpp v57, v49 row_ror:2 row_mask:0xf bank_mask:0xf
	v_mov_b32_dpp v56, v48 row_ror:2 row_mask:0xf bank_mask:0xf
	v_pk_add_f32 v[48:49], v[48:49], v[56:57]
	v_mov_b32_e32 v57, 0
	v_mov_b32_e32 v56, 0
	s_nop 0
	v_mov_b32_dpp v57, v49 row_ror:1 row_mask:0xf bank_mask:0xf
	v_mov_b32_dpp v56, v48 row_ror:1 row_mask:0xf bank_mask:0xf
	v_pk_add_f32 v[48:49], v[48:49], v[56:57]
	s_nop 0
	v_pk_fma_f32 v[48:49], v[48:49], s[14:15], v[42:43] op_sel_hi:[1,0,0]
	s_nop 0
	v_mul_f32_e32 v56, 0x4b800000, v49
	v_cmp_gt_f32_e64 s[42:43], s15, v49
	v_cmp_gt_f32_e32 vcc, s15, v48
	s_nop 0
	v_cndmask_b32_e64 v49, v49, v56, s[42:43]
	v_rsq_f32_e32 v49, v49
	s_nop 0
	v_mul_f32_e32 v56, 0x45800000, v49
	v_cndmask_b32_e64 v49, v49, v56, s[42:43]
	v_mul_f32_e32 v56, 0x3e38aa3b, v49
	v_pk_mul_f32 v[58:59], v[56:57], v[58:59] op_sel_hi:[0,1]
	v_pk_mul_f32 v[52:53], v[56:57], v[52:53] op_sel_hi:[0,1]
	v_mul_f32_e32 v49, 0x4b800000, v48
	v_cndmask_b32_e32 v48, v48, v49, vcc
	v_rsq_f32_e32 v48, v48
	s_waitcnt vmcnt(0)
	v_pk_mul_f32 v[0:1], v[0:1], v[58:59]
	v_pk_mul_f32 v[2:3], v[2:3], v[52:53]
	v_cvt_pk_bf16_f32 v0, v0, v1
	v_cvt_pk_bf16_f32 v1, v2, v3
	global_store_dwordx2 v[36:37], v[0:1], off offset:1536
	global_load_dwordx4 v[0:3], v[10:11], off
	v_mul_f32_e32 v49, 0x45800000, v48
	v_cndmask_b32_e32 v48, v48, v49, vcc
	v_mul_f32_e32 v48, 0x3e38aa3b, v48
	v_pk_mul_f32 v[52:53], v[48:49], v[54:55] op_sel_hi:[0,1]
	v_pk_mul_f32 v[48:49], v[48:49], v[50:51] op_sel_hi:[0,1]
	v_lshlrev_b32_e32 v54, 16, v46
	v_and_b32_e32 v55, 0xffff0000, v46
	v_lshlrev_b32_e32 v50, 16, v44
	v_and_b32_e32 v51, 0xffff0000, v44
	v_pk_mul_f32 v[56:57], v[54:55], v[54:55]
	v_lshlrev_b32_e32 v46, 16, v45
	v_mov_b32_e32 v65, v56
	s_waitcnt vmcnt(0)
	v_pk_mul_f32 v[0:1], v[0:1], v[52:53]
	v_pk_mul_f32 v[2:3], v[2:3], v[48:49]
	v_cvt_pk_bf16_f32 v0, v0, v1
	v_cvt_pk_bf16_f32 v1, v2, v3
	global_store_dwordx2 v[36:37], v[0:1], off offset:2048
	global_load_dwordx4 v[0:3], v[10:11], off
	v_lshlrev_b32_e32 v48, 16, v47
	v_and_b32_e32 v49, 0xffff0000, v47
	v_and_b32_e32 v47, 0xffff0000, v45
	v_pk_mul_f32 v[44:45], v[50:51], v[50:51]
	v_pk_mul_f32 v[52:53], v[48:49], v[48:49]
	v_pk_mul_f32 v[58:59], v[46:47], v[46:47]
	v_mov_b32_e32 v64, v44
	v_mov_b32_e32 v56, v45
	v_pk_add_f32 v[44:45], v[64:65], v[56:57]
	v_mov_b32_e32 v56, v58
	v_mov_b32_e32 v57, v52
	v_pk_add_f32 v[44:45], v[56:57], v[44:45]
	v_mov_b32_e32 v52, v59
	v_pk_add_f32 v[44:45], v[52:53], v[44:45]
	v_mov_b32_e32 v53, 0
	v_mov_b32_e32 v52, 0
	s_nop 0
	v_mov_b32_dpp v53, v45 row_ror:8 row_mask:0xf bank_mask:0xf
	v_mov_b32_dpp v52, v44 row_ror:8 row_mask:0xf bank_mask:0xf
	v_pk_add_f32 v[44:45], v[44:45], v[52:53]
	v_mov_b32_e32 v53, 0
	v_mov_b32_e32 v52, 0
	s_nop 0
	v_mov_b32_dpp v53, v45 row_ror:4 row_mask:0xf bank_mask:0xf
	v_mov_b32_dpp v52, v44 row_ror:4 row_mask:0xf bank_mask:0xf
	v_pk_add_f32 v[44:45], v[44:45], v[52:53]
	v_mov_b32_e32 v53, 0
	v_mov_b32_e32 v52, 0
	s_nop 0
	v_mov_b32_dpp v53, v45 row_ror:2 row_mask:0xf bank_mask:0xf
	v_mov_b32_dpp v52, v44 row_ror:2 row_mask:0xf bank_mask:0xf
	v_pk_add_f32 v[44:45], v[44:45], v[52:53]
	v_mov_b32_e32 v53, 0
	v_mov_b32_e32 v52, 0
	s_nop 0
	v_mov_b32_dpp v53, v45 row_ror:1 row_mask:0xf bank_mask:0xf
	v_mov_b32_dpp v52, v44 row_ror:1 row_mask:0xf bank_mask:0xf
	v_pk_add_f32 v[44:45], v[44:45], v[52:53]
	s_nop 0
	v_pk_fma_f32 v[44:45], v[44:45], s[14:15], v[42:43] op_sel_hi:[1,0,0]
	s_nop 0
	v_mul_f32_e32 v52, 0x4b800000, v45
	v_cmp_gt_f32_e64 s[42:43], s15, v45
	v_cmp_gt_f32_e32 vcc, s15, v44
	s_nop 0
	v_cndmask_b32_e64 v45, v45, v52, s[42:43]
	v_rsq_f32_e32 v45, v45
	s_nop 0
	v_mul_f32_e32 v52, 0x45800000, v45
	v_cndmask_b32_e64 v45, v45, v52, s[42:43]
	v_mul_f32_e32 v52, 0x3e38aa3b, v45
	v_pk_mul_f32 v[54:55], v[52:53], v[54:55] op_sel_hi:[0,1]
	v_pk_mul_f32 v[48:49], v[52:53], v[48:49] op_sel_hi:[0,1]
	v_mul_f32_e32 v45, 0x4b800000, v44
	v_cndmask_b32_e32 v44, v44, v45, vcc
	v_rsq_f32_e32 v44, v44
	s_waitcnt vmcnt(0)
; DI unsigned pack2(float a, float b) { f32x2 v = {a, b}; hwbf16x2 r = __builtin_convertvector(v, hwbf16x2); return __builtin_bit_cast(unsigned, r); }
; DI float bflo(unsigned w) { return __uint_as_float(w << 16); }
; DI float bfhi(unsigned w) { return __uint_as_float(w & 0xffff0000u); }
; DI float sum16(float v) { v += dppf<0x128>(v); v += dppf<0x124>(v); v += dppf<0x122>(v); v += dppf<0x121>(v); return v; }
; DI void swa_prep_phase(const Params& p) {
;     ...
;         for (int it = 0; it < 9; ++it) {
;             const int col = it * 256 + lane * 4;
;             const u32x2 wv = wl[q2][it]; const f32x4 v = {bflo(wv[0]), bfhi(wv[0]), bflo(wv[1]), bfhi(wv[1])};
;             float ss = v[0] * v[0] + v[1] * v[1] + v[2] * v[2] + v[3] * v[3];
;             ss = sum16(ss);
;             const float rs = rsqrtf(ss * (1.0f / 64.f) + EPS);
;             const int d = col & 63;
;             if (it < 8) { const f32x4 g = *(const f32x4*)(p.swa_q_gain + d); const float f = rs * qsc;
;                 u32x2 o; o[0] = pack2(v[0] * f * g[0], v[1] * f * g[1]); o[1] = pack2(v[2] * f * g[2], v[3] * f * g[3]);
;                 *(u32x2*)(QS + (size_t)t * 2048 + col) = o; }
;             else { const f32x4 g = *(const f32x4*)(p.swa_k_gain + d); const int kvh = (col - 2048) >> 6;
;                 u32x2 o; o[0] = pack2(v[0] * rs * g[0], v[1] * rs * g[1]); o[1] = pack2(v[2] * rs * g[2], v[3] * rs * g[3]);
;                 *(u32x2*)(KS + ((size_t)(b * 4 + kvh) * S + s) * 64 + d) = o; }
;         }
	v_pk_mul_f32 v[0:1], v[0:1], v[54:55]
	v_pk_mul_f32 v[2:3], v[2:3], v[48:49]
	v_cvt_pk_bf16_f32 v0, v0, v1
	v_cvt_pk_bf16_f32 v1, v2, v3
	global_store_dwordx2 v[36:37], v[0:1], off offset:2560
	global_load_dwordx4 v[0:3], v[10:11], off
	v_mul_f32_e32 v45, 0x45800000, v44
	v_cndmask_b32_e32 v44, v44, v45, vcc
	v_mul_f32_e32 v44, 0x3e38aa3b, v44
	v_pk_mul_f32 v[48:49], v[44:45], v[50:51] op_sel_hi:[0,1]
	v_pk_mul_f32 v[44:45], v[44:45], v[46:47] op_sel_hi:[0,1]
	v_lshlrev_b32_e32 v50, 16, v40
	v_and_b32_e32 v51, 0xffff0000, v40
	v_lshlrev_b32_e32 v46, 16, v38
	v_and_b32_e32 v47, 0xffff0000, v38
	v_pk_mul_f32 v[52:53], v[50:51], v[50:51]
	v_lshlrev_b32_e32 v40, 16, v39
	v_mov_b32_e32 v57, v52
	s_waitcnt vmcnt(0)
	v_pk_mul_f32 v[0:1], v[0:1], v[48:49]
	v_pk_mul_f32 v[2:3], v[2:3], v[44:45]
	v_cvt_pk_bf16_f32 v0, v0, v1
	v_cvt_pk_bf16_f32 v1, v2, v3
	global_store_dwordx2 v[36:37], v[0:1], off offset:3072
	global_load_dwordx4 v[0:3], v[10:11], off
	v_lshlrev_b32_e32 v44, 16, v41
	v_and_b32_e32 v45, 0xffff0000, v41
	v_and_b32_e32 v41, 0xffff0000, v39
	v_pk_mul_f32 v[38:39], v[46:47], v[46:47]
	v_pk_mul_f32 v[48:49], v[44:45], v[44:45]
	v_pk_mul_f32 v[54:55], v[40:41], v[40:41]
	v_mov_b32_e32 v56, v38
	v_mov_b32_e32 v52, v39
	v_pk_add_f32 v[38:39], v[56:57], v[52:53]
	v_mov_b32_e32 v52, v54
	v_mov_b32_e32 v53, v48
	v_pk_add_f32 v[38:39], v[52:53], v[38:39]
	v_mov_b32_e32 v48, v55
	v_pk_add_f32 v[38:39], v[48:49], v[38:39]
	v_mov_b32_e32 v49, 0
	v_mov_b32_e32 v48, 0
	s_nop 0
	v_mov_b32_dpp v49, v39 row_ror:8 row_mask:0xf bank_mask:0xf
	v_mov_b32_dpp v48, v38 row_ror:8 row_mask:0xf bank_mask:0xf
	v_pk_add_f32 v[38:39], v[38:39], v[48:49]
	v_mov_b32_e32 v49, 0
	v_mov_b32_e32 v48, 0
	s_nop 0
	v_mov_b32_dpp v49, v39 row_ror:4 row_mask:0xf bank_mask:0xf
	v_mov_b32_dpp v48, v38 row_ror:4 row_mask:0xf bank_mask:0xf
	v_pk_add_f32 v[38:39], v[38:39], v[48:49]
	v_mov_b32_e32 v49, 0
	v_mov_b32_e32 v48, 0
	s_nop 0
	v_mov_b32_dpp v49, v39 row_ror:2 row_mask:0xf bank_mask:0xf
	v_mov_b32_dpp v48, v38 row_ror:2 row_mask:0xf bank_mask:0xf
	v_pk_add_f32 v[38:39], v[38:39], v[48:49]
	v_mov_b32_e32 v49, 0
	v_mov_b32_e32 v48, 0
	s_nop 0
	v_mov_b32_dpp v49, v39 row_ror:1 row_mask:0xf bank_mask:0xf
	v_mov_b32_dpp v48, v38 row_ror:1 row_mask:0xf bank_mask:0xf
	v_pk_add_f32 v[38:39], v[38:39], v[48:49]
	s_nop 0
	v_pk_fma_f32 v[38:39], v[38:39], s[14:15], v[42:43] op_sel_hi:[1,0,0]
	s_nop 0
	v_mul_f32_e32 v42, 0x4b800000, v39
	v_cmp_gt_f32_e64 s[42:43], s15, v39
	v_cmp_gt_f32_e32 vcc, s15, v38
	s_nop 0
	v_cndmask_b32_e64 v39, v39, v42, s[42:43]
	v_rsq_f32_e32 v39, v39
	s_nop 0
	v_mul_f32_e32 v42, 0x45800000, v39
	v_cndmask_b32_e64 v39, v39, v42, s[42:43]
	v_mul_f32_e32 v42, 0x3e38aa3b, v39
	v_pk_mul_f32 v[48:49], v[42:43], v[50:51] op_sel_hi:[0,1]
	v_pk_mul_f32 v[42:43], v[42:43], v[44:45] op_sel_hi:[0,1]
	s_waitcnt vmcnt(0)
	v_pk_mul_f32 v[0:1], v[0:1], v[48:49]
	v_pk_mul_f32 v[2:3], v[2:3], v[42:43]
	v_cvt_pk_bf16_f32 v0, v0, v1
	v_cvt_pk_bf16_f32 v1, v2, v3
	global_store_dwordx2 v[36:37], v[0:1], off offset:3584
	global_load_dwordx4 v[0:3], v[12:13], off
	v_mul_f32_e32 v36, 0x4b800000, v38
	v_cndmask_b32_e32 v36, v38, v36, vcc
	v_rsq_f32_e32 v36, v36
	s_nop 0
	v_mul_f32_e32 v37, 0x45800000, v36
	v_cndmask_b32_e32 v36, v36, v37, vcc
	v_pk_mul_f32 v[38:39], v[36:37], v[46:47] op_sel_hi:[0,1]
	v_pk_mul_f32 v[36:37], v[36:37], v[40:41] op_sel_hi:[0,1]
	s_waitcnt vmcnt(0)
	v_pk_mul_f32 v[0:1], v[0:1], v[38:39]
	v_pk_mul_f32 v[2:3], v[2:3], v[36:37]
	v_cvt_pk_bf16_f32 v0, v0, v1
	v_cvt_pk_bf16_f32 v1, v2, v3
	v_lshl_or_b32 v2, v33, 2, v61
	v_ashrrev_i32_e32 v3, 31, v2
	v_lshlrev_b64 v[2:3], 19, v[2:3]
	v_lshl_add_u64 v[2:3], v[34:35], 0, v[2:3]
	global_store_dwordx2 v[2:3], v[0:1], off
	s_and_saveexec_b64 s[18:19], s[40:41]
	s_cbranch_execz .LBB1_764
	global_load_dwordx4 v[34:37], v[10:11], off
	v_lshlrev_b32_e32 v38, 16, v28
	v_and_b32_e32 v39, 0xffff0000, v28
	v_lshlrev_b32_e32 v2, 16, v29
	v_and_b32_e32 v3, 0xffff0000, v29
	v_pk_mul_f32 v[40:41], v[38:39], v[38:39]
	v_pk_mul_f32 v[0:1], v[2:3], v[2:3]
	v_add_f32_e32 v33, v40, v41
	v_add_f32_e32 v0, v0, v33
	v_add_f32_e32 v0, v1, v0
	v_ashrrev_i32_e32 v33, 31, v32
	v_lshlrev_b32_e32 v44, 16, v24
	v_add_f32_dpp v0, v0, v0 row_ror:8 row_mask:0xf bank_mask:0xf bound_ctrl:1
	v_and_b32_e32 v45, 0xffff0000, v24
	v_lshlrev_b32_e32 v42, 16, v25
	v_add_f32_dpp v0, v0, v0 row_ror:4 row_mask:0xf bank_mask:0xf bound_ctrl:1
	v_and_b32_e32 v43, 0xffff0000, v25
	v_pk_mul_f32 v[64:65], v[44:45], v[44:45]
	v_add_f32_dpp v0, v0, v0 row_ror:2 row_mask:0xf bank_mask:0xf bound_ctrl:1
	v_pk_mul_f32 v[58:59], v[42:43], v[42:43]
	v_mov_b32_e32 v66, v64
	v_add_f32_dpp v0, v0, v0 row_ror:1 row_mask:0xf bank_mask:0xf bound_ctrl:1
	v_fmamk_f32 v0, v0, 0x3c800000, v62
	v_mul_f32_e32 v1, 0x4b800000, v0
	v_cmp_gt_f32_e32 vcc, s15, v0
	v_mov_b32_e32 v64, v58
	v_mov_b32_e32 v47, 0
	v_cndmask_b32_e32 v0, v0, v1, vcc
	v_rsq_f32_e32 v40, v0
	v_lshlrev_b64 v[0:1], 12, v[32:33]
	v_lshl_add_u64 v[0:1], v[8:9], 0, v[0:1]
	v_mov_b32_e32 v46, 0
	v_mul_f32_e32 v41, 0x45800000, v40
	v_cndmask_b32_e32 v40, v40, v41, vcc
	v_mul_f32_e32 v40, 0x3e38aa3b, v40
	v_pk_mul_f32 v[38:39], v[40:41], v[38:39] op_sel_hi:[0,1]
	v_pk_mul_f32 v[2:3], v[40:41], v[2:3] op_sel_hi:[0,1]
	v_lshlrev_b32_e32 v40, 16, v26
	v_and_b32_e32 v41, 0xffff0000, v26
	v_pk_mul_f32 v[56:57], v[40:41], v[40:41]
	v_mov_b32_e32 v49, 0
	v_mov_b32_e32 v67, v56
	v_mov_b32_e32 v56, v65
	v_pk_add_f32 v[56:57], v[66:67], v[56:57]
	v_mov_b32_e32 v48, 0
	v_mov_b32_e32 v51, 0
	v_mov_b32_e32 v50, 0
	v_mov_b32_e32 v53, 0
	v_mov_b32_e32 v52, 0
	v_lshrrev_b32_e32 v33, 20, v33
	v_add_u32_e32 v33, v32, v33
	s_waitcnt vmcnt(0)
; DI unsigned pack2(float a, float b) { f32x2 v = {a, b}; hwbf16x2 r = __builtin_convertvector(v, hwbf16x2); return __builtin_bit_cast(unsigned, r); }
; DI float bflo(unsigned w) { return __uint_as_float(w << 16); }
; DI float bfhi(unsigned w) { return __uint_as_float(w & 0xffff0000u); }
; DI float sum16(float v) { v += dppf<0x128>(v); v += dppf<0x124>(v); v += dppf<0x122>(v); v += dppf<0x121>(v); return v; }
; DI void swa_prep_phase(const Params& p) {
;     ...
;         for (int it = 0; it < 9; ++it) {
;             const int col = it * 256 + lane * 4;
;             const u32x2 wv = wl[q2][it]; const f32x4 v = {bflo(wv[0]), bfhi(wv[0]), bflo(wv[1]), bfhi(wv[1])};
;             float ss = v[0] * v[0] + v[1] * v[1] + v[2] * v[2] + v[3] * v[3];
;             ss = sum16(ss);
;             const float rs = rsqrtf(ss * (1.0f / 64.f) + EPS);
;             const int d = col & 63;
;             if (it < 8) { const f32x4 g = *(const f32x4*)(p.swa_q_gain + d); const float f = rs * qsc;
;                 u32x2 o; o[0] = pack2(v[0] * f * g[0], v[1] * f * g[1]); o[1] = pack2(v[2] * f * g[2], v[3] * f * g[3]);
;                 *(u32x2*)(QS + (size_t)t * 2048 + col) = o; }
;             else { const f32x4 g = *(const f32x4*)(p.swa_k_gain + d); const int kvh = (col - 2048) >> 6;
;                 u32x2 o; o[0] = pack2(v[0] * rs * g[0], v[1] * rs * g[1]); o[1] = pack2(v[2] * rs * g[2], v[3] * rs * g[3]);
;                 *(u32x2*)(KS + ((size_t)(b * 4 + kvh) * S + s) * 64 + d) = o; }
;         }
	v_pk_mul_f32 v[34:35], v[34:35], v[38:39]
	v_pk_mul_f32 v[2:3], v[36:37], v[2:3]
	v_cvt_pk_bf16_f32 v34, v34, v35
	v_cvt_pk_bf16_f32 v35, v2, v3
	global_store_dwordx2 v[0:1], v[34:35], off
	global_load_dwordx4 v[34:37], v[10:11], off
	v_lshlrev_b32_e32 v38, 16, v27
	v_and_b32_e32 v39, 0xffff0000, v27
	v_pk_mul_f32 v[54:55], v[38:39], v[38:39]
	v_mov_b64_e32 v[2:3], s[16:17]
	v_mov_b32_e32 v65, v54
	v_mov_b32_e32 v54, v59
	v_pk_add_f32 v[56:57], v[64:65], v[56:57]
	s_nop 0
	v_pk_add_f32 v[54:55], v[54:55], v[56:57]
	s_nop 1
	v_mov_b32_dpp v47, v55 row_ror:8 row_mask:0xf bank_mask:0xf
	v_mov_b32_dpp v46, v54 row_ror:8 row_mask:0xf bank_mask:0xf
	v_pk_add_f32 v[46:47], v[54:55], v[46:47]
	s_nop 1
	v_mov_b32_dpp v49, v47 row_ror:4 row_mask:0xf bank_mask:0xf
	v_mov_b32_dpp v48, v46 row_ror:4 row_mask:0xf bank_mask:0xf
	v_pk_add_f32 v[46:47], v[46:47], v[48:49]
	s_nop 1
	v_mov_b32_dpp v51, v47 row_ror:2 row_mask:0xf bank_mask:0xf
	v_mov_b32_dpp v50, v46 row_ror:2 row_mask:0xf bank_mask:0xf
	v_pk_add_f32 v[46:47], v[46:47], v[50:51]
	v_mov_b32_e32 v51, 0
	v_mov_b32_e32 v50, 0
	v_mov_b32_dpp v53, v47 row_ror:1 row_mask:0xf bank_mask:0xf
	v_mov_b32_dpp v52, v46 row_ror:1 row_mask:0xf bank_mask:0xf
	v_pk_add_f32 v[46:47], v[46:47], v[52:53]
	v_mov_b32_e32 v53, 0
	v_pk_fma_f32 v[46:47], v[46:47], s[14:15], v[2:3] op_sel_hi:[1,0,0]
	v_mov_b32_e32 v52, 0
	v_mul_f32_e32 v48, 0x4b800000, v47
	v_cmp_gt_f32_e32 vcc, s15, v47
	s_nop 1
	v_cndmask_b32_e32 v47, v47, v48, vcc
	v_rsq_f32_e32 v47, v47
	s_nop 0
	v_mul_f32_e32 v48, 0x45800000, v47
	v_cndmask_b32_e32 v47, v47, v48, vcc
	v_mul_f32_e32 v48, 0x3e38aa3b, v47
	v_pk_mul_f32 v[40:41], v[48:49], v[40:41] op_sel_hi:[0,1]
	v_pk_mul_f32 v[38:39], v[48:49], v[38:39] op_sel_hi:[0,1]
	v_cmp_gt_f32_e32 vcc, s15, v46
	v_mov_b32_e32 v47, 0
	v_mov_b32_e32 v49, 0
	v_mov_b32_e32 v48, 0
	s_waitcnt vmcnt(0)
	v_pk_mul_f32 v[34:35], v[34:35], v[40:41]
	v_pk_mul_f32 v[36:37], v[36:37], v[38:39]
	v_cvt_pk_bf16_f32 v34, v34, v35
	v_cvt_pk_bf16_f32 v35, v36, v37
	global_store_dwordx2 v[0:1], v[34:35], off offset:512
	global_load_dwordx4 v[34:37], v[10:11], off
	v_mul_f32_e32 v38, 0x4b800000, v46
	v_cndmask_b32_e32 v38, v46, v38, vcc
	v_rsq_f32_e32 v38, v38
	v_mov_b32_e32 v46, 0
	v_mul_f32_e32 v39, 0x45800000, v38
	v_cndmask_b32_e32 v38, v38, v39, vcc
	v_mul_f32_e32 v38, 0x3e38aa3b, v38
	v_pk_mul_f32 v[40:41], v[38:39], v[44:45] op_sel_hi:[0,1]
	v_pk_mul_f32 v[38:39], v[38:39], v[42:43] op_sel_hi:[0,1]
	v_lshlrev_b32_e32 v44, 16, v20
	v_and_b32_e32 v45, 0xffff0000, v20
	v_lshlrev_b32_e32 v42, 16, v21
	v_and_b32_e32 v43, 0xffff0000, v21
	v_pk_mul_f32 v[64:65], v[44:45], v[44:45]
	v_pk_mul_f32 v[58:59], v[42:43], v[42:43]
	v_mov_b32_e32 v66, v64
	v_mov_b32_e32 v64, v58
	s_waitcnt vmcnt(0)
	v_pk_mul_f32 v[34:35], v[34:35], v[40:41]
	v_pk_mul_f32 v[36:37], v[36:37], v[38:39]
	v_cvt_pk_bf16_f32 v34, v34, v35
	v_cvt_pk_bf16_f32 v35, v36, v37
	global_store_dwordx2 v[0:1], v[34:35], off offset:1024
	global_load_dwordx4 v[34:37], v[10:11], off
	v_lshlrev_b32_e32 v40, 16, v22
	v_and_b32_e32 v41, 0xffff0000, v22
	v_lshlrev_b32_e32 v38, 16, v23
	v_and_b32_e32 v39, 0xffff0000, v23
	v_pk_mul_f32 v[56:57], v[40:41], v[40:41]
	v_pk_mul_f32 v[54:55], v[38:39], v[38:39]
	v_mov_b32_e32 v67, v56
	v_mov_b32_e32 v56, v65
	v_mov_b32_e32 v65, v54
	v_pk_add_f32 v[56:57], v[66:67], v[56:57]
	v_mov_b32_e32 v54, v59
	v_pk_add_f32 v[56:57], v[64:65], v[56:57]
	s_nop 0
	v_pk_add_f32 v[54:55], v[54:55], v[56:57]
	s_nop 1
	v_mov_b32_dpp v47, v55 row_ror:8 row_mask:0xf bank_mask:0xf
	v_mov_b32_dpp v46, v54 row_ror:8 row_mask:0xf bank_mask:0xf
	v_pk_add_f32 v[46:47], v[54:55], v[46:47]
	s_nop 1
	v_mov_b32_dpp v49, v47 row_ror:4 row_mask:0xf bank_mask:0xf
	v_mov_b32_dpp v48, v46 row_ror:4 row_mask:0xf bank_mask:0xf
	v_pk_add_f32 v[46:47], v[46:47], v[48:49]
	s_nop 1
	v_mov_b32_dpp v51, v47 row_ror:2 row_mask:0xf bank_mask:0xf
	v_mov_b32_dpp v50, v46 row_ror:2 row_mask:0xf bank_mask:0xf
	v_pk_add_f32 v[46:47], v[46:47], v[50:51]
	v_mov_b32_e32 v51, 0
	v_mov_b32_e32 v50, 0
	v_mov_b32_dpp v53, v47 row_ror:1 row_mask:0xf bank_mask:0xf
	v_mov_b32_dpp v52, v46 row_ror:1 row_mask:0xf bank_mask:0xf
	v_pk_add_f32 v[46:47], v[46:47], v[52:53]
	v_mov_b32_e32 v53, 0
	v_pk_fma_f32 v[46:47], v[46:47], s[14:15], v[2:3] op_sel_hi:[1,0,0]
	v_mov_b32_e32 v52, 0
	v_mul_f32_e32 v48, 0x4b800000, v47
	v_cmp_gt_f32_e32 vcc, s15, v47
	s_nop 1
	v_cndmask_b32_e32 v47, v47, v48, vcc
	v_rsq_f32_e32 v47, v47
	s_nop 0
	v_mul_f32_e32 v48, 0x45800000, v47
	v_cndmask_b32_e32 v47, v47, v48, vcc
	v_mul_f32_e32 v48, 0x3e38aa3b, v47
	v_pk_mul_f32 v[40:41], v[48:49], v[40:41] op_sel_hi:[0,1]
	v_pk_mul_f32 v[38:39], v[48:49], v[38:39] op_sel_hi:[0,1]
	v_cmp_gt_f32_e32 vcc, s15, v46
	v_mov_b32_e32 v47, 0
	v_mov_b32_e32 v49, 0
	v_mov_b32_e32 v48, 0
	s_waitcnt vmcnt(0)
	v_pk_mul_f32 v[34:35], v[34:35], v[40:41]
	v_pk_mul_f32 v[36:37], v[36:37], v[38:39]
	v_cvt_pk_bf16_f32 v34, v34, v35
	v_cvt_pk_bf16_f32 v35, v36, v37
	global_store_dwordx2 v[0:1], v[34:35], off offset:1536
	global_load_dwordx4 v[34:37], v[10:11], off
	v_mul_f32_e32 v38, 0x4b800000, v46
	v_cndmask_b32_e32 v38, v46, v38, vcc
	v_rsq_f32_e32 v38, v38
	v_mov_b32_e32 v46, 0
	v_mul_f32_e32 v39, 0x45800000, v38
	v_cndmask_b32_e32 v38, v38, v39, vcc
	v_mul_f32_e32 v38, 0x3e38aa3b, v38
	v_pk_mul_f32 v[40:41], v[38:39], v[44:45] op_sel_hi:[0,1]
	v_pk_mul_f32 v[38:39], v[38:39], v[42:43] op_sel_hi:[0,1]
	v_lshlrev_b32_e32 v44, 16, v16
	v_and_b32_e32 v45, 0xffff0000, v16
	v_lshlrev_b32_e32 v42, 16, v17
	v_and_b32_e32 v43, 0xffff0000, v17
	v_pk_mul_f32 v[64:65], v[44:45], v[44:45]
	v_pk_mul_f32 v[58:59], v[42:43], v[42:43]
	v_mov_b32_e32 v66, v64
	v_mov_b32_e32 v64, v58
	s_waitcnt vmcnt(0)
; DI unsigned pack2(float a, float b) { f32x2 v = {a, b}; hwbf16x2 r = __builtin_convertvector(v, hwbf16x2); return __builtin_bit_cast(unsigned, r); }
; DI float bflo(unsigned w) { return __uint_as_float(w << 16); }
; DI float bfhi(unsigned w) { return __uint_as_float(w & 0xffff0000u); }
; DI float sum16(float v) { v += dppf<0x128>(v); v += dppf<0x124>(v); v += dppf<0x122>(v); v += dppf<0x121>(v); return v; }
; DI void swa_prep_phase(const Params& p) {
;     ...
;         for (int it = 0; it < 9; ++it) {
;             const int col = it * 256 + lane * 4;
;             const u32x2 wv = wl[q2][it]; const f32x4 v = {bflo(wv[0]), bfhi(wv[0]), bflo(wv[1]), bfhi(wv[1])};
;             float ss = v[0] * v[0] + v[1] * v[1] + v[2] * v[2] + v[3] * v[3];
;             ss = sum16(ss);
;             const float rs = rsqrtf(ss * (1.0f / 64.f) + EPS);
;             const int d = col & 63;
;             if (it < 8) { const f32x4 g = *(const f32x4*)(p.swa_q_gain + d); const float f = rs * qsc;
;                 u32x2 o; o[0] = pack2(v[0] * f * g[0], v[1] * f * g[1]); o[1] = pack2(v[2] * f * g[2], v[3] * f * g[3]);
;                 *(u32x2*)(QS + (size_t)t * 2048 + col) = o; }
;             else { const f32x4 g = *(const f32x4*)(p.swa_k_gain + d); const int kvh = (col - 2048) >> 6;
;                 u32x2 o; o[0] = pack2(v[0] * rs * g[0], v[1] * rs * g[1]); o[1] = pack2(v[2] * rs * g[2], v[3] * rs * g[3]);
;                 *(u32x2*)(KS + ((size_t)(b * 4 + kvh) * S + s) * 64 + d) = o; }
;         }
	v_pk_mul_f32 v[34:35], v[34:35], v[40:41]
	v_pk_mul_f32 v[36:37], v[36:37], v[38:39]
	v_cvt_pk_bf16_f32 v34, v34, v35
	v_cvt_pk_bf16_f32 v35, v36, v37
	global_store_dwordx2 v[0:1], v[34:35], off offset:2048
	global_load_dwordx4 v[34:37], v[10:11], off
	v_lshlrev_b32_e32 v40, 16, v18
	v_and_b32_e32 v41, 0xffff0000, v18
	v_lshlrev_b32_e32 v38, 16, v19
	v_and_b32_e32 v39, 0xffff0000, v19
	v_pk_mul_f32 v[56:57], v[40:41], v[40:41]
	v_pk_mul_f32 v[54:55], v[38:39], v[38:39]
	v_mov_b32_e32 v67, v56
	v_mov_b32_e32 v56, v65
	v_mov_b32_e32 v65, v54
	v_pk_add_f32 v[56:57], v[66:67], v[56:57]
	v_mov_b32_e32 v54, v59
	v_pk_add_f32 v[56:57], v[64:65], v[56:57]
	s_nop 0
	v_pk_add_f32 v[54:55], v[54:55], v[56:57]
	s_nop 1
	v_mov_b32_dpp v47, v55 row_ror:8 row_mask:0xf bank_mask:0xf
	v_mov_b32_dpp v46, v54 row_ror:8 row_mask:0xf bank_mask:0xf
	v_pk_add_f32 v[46:47], v[54:55], v[46:47]
	s_nop 1
	v_mov_b32_dpp v49, v47 row_ror:4 row_mask:0xf bank_mask:0xf
	v_mov_b32_dpp v48, v46 row_ror:4 row_mask:0xf bank_mask:0xf
	v_pk_add_f32 v[46:47], v[46:47], v[48:49]
	s_nop 1
	v_mov_b32_dpp v51, v47 row_ror:2 row_mask:0xf bank_mask:0xf
	v_mov_b32_dpp v50, v46 row_ror:2 row_mask:0xf bank_mask:0xf
	v_pk_add_f32 v[46:47], v[46:47], v[50:51]
	v_mov_b32_e32 v51, 0
	v_mov_b32_e32 v50, 0
	v_mov_b32_dpp v53, v47 row_ror:1 row_mask:0xf bank_mask:0xf
	v_mov_b32_dpp v52, v46 row_ror:1 row_mask:0xf bank_mask:0xf
	v_pk_add_f32 v[46:47], v[46:47], v[52:53]
	v_mov_b32_e32 v53, 0
	v_pk_fma_f32 v[46:47], v[46:47], s[14:15], v[2:3] op_sel_hi:[1,0,0]
	v_mov_b32_e32 v52, 0
	v_mul_f32_e32 v48, 0x4b800000, v47
	v_cmp_gt_f32_e32 vcc, s15, v47
	s_nop 1
	v_cndmask_b32_e32 v47, v47, v48, vcc
	v_rsq_f32_e32 v47, v47
	s_nop 0
	v_mul_f32_e32 v48, 0x45800000, v47
	v_cndmask_b32_e32 v47, v47, v48, vcc
	v_mul_f32_e32 v48, 0x3e38aa3b, v47
	v_pk_mul_f32 v[40:41], v[48:49], v[40:41] op_sel_hi:[0,1]
	v_pk_mul_f32 v[38:39], v[48:49], v[38:39] op_sel_hi:[0,1]
	v_cmp_gt_f32_e32 vcc, s15, v46
	v_mov_b32_e32 v47, 0
	v_mov_b32_e32 v49, 0
	v_mov_b32_e32 v48, 0
	s_waitcnt vmcnt(0)
	v_pk_mul_f32 v[34:35], v[34:35], v[40:41]
	v_pk_mul_f32 v[36:37], v[36:37], v[38:39]
	v_cvt_pk_bf16_f32 v34, v34, v35
	v_cvt_pk_bf16_f32 v35, v36, v37
	global_store_dwordx2 v[0:1], v[34:35], off offset:2560
	global_load_dwordx4 v[34:37], v[10:11], off
	v_mul_f32_e32 v38, 0x4b800000, v46
	v_cndmask_b32_e32 v38, v46, v38, vcc
	v_rsq_f32_e32 v38, v38
	v_mov_b32_e32 v46, 0
	v_mul_f32_e32 v39, 0x45800000, v38
	v_cndmask_b32_e32 v38, v38, v39, vcc
	v_mul_f32_e32 v38, 0x3e38aa3b, v38
	v_pk_mul_f32 v[40:41], v[38:39], v[44:45] op_sel_hi:[0,1]
	v_pk_mul_f32 v[38:39], v[38:39], v[42:43] op_sel_hi:[0,1]
	v_lshlrev_b32_e32 v44, 16, v30
	v_and_b32_e32 v45, 0xffff0000, v30
	v_lshlrev_b32_e32 v42, 16, v31
	v_and_b32_e32 v43, 0xffff0000, v31
	v_pk_mul_f32 v[64:65], v[44:45], v[44:45]
	v_pk_mul_f32 v[58:59], v[42:43], v[42:43]
	v_mov_b32_e32 v66, v64
	v_mov_b32_e32 v64, v58
	s_waitcnt vmcnt(0)
	v_pk_mul_f32 v[34:35], v[34:35], v[40:41]
	v_pk_mul_f32 v[36:37], v[36:37], v[38:39]
	v_cvt_pk_bf16_f32 v34, v34, v35
	v_cvt_pk_bf16_f32 v35, v36, v37
	global_store_dwordx2 v[0:1], v[34:35], off offset:3072
	global_load_dwordx4 v[34:37], v[10:11], off
	v_lshlrev_b32_e32 v40, 16, v14
	v_and_b32_e32 v41, 0xffff0000, v14
	v_lshlrev_b32_e32 v38, 16, v15
	v_and_b32_e32 v39, 0xffff0000, v15
	v_pk_mul_f32 v[56:57], v[40:41], v[40:41]
	v_pk_mul_f32 v[54:55], v[38:39], v[38:39]
	v_mov_b32_e32 v67, v56
	v_mov_b32_e32 v56, v65
	v_mov_b32_e32 v65, v54
	v_pk_add_f32 v[56:57], v[66:67], v[56:57]
	v_mov_b32_e32 v54, v59
	v_pk_add_f32 v[56:57], v[64:65], v[56:57]
	s_nop 0
	v_pk_add_f32 v[54:55], v[54:55], v[56:57]
	s_nop 1
	v_mov_b32_dpp v47, v55 row_ror:8 row_mask:0xf bank_mask:0xf
	v_mov_b32_dpp v46, v54 row_ror:8 row_mask:0xf bank_mask:0xf
	v_pk_add_f32 v[46:47], v[54:55], v[46:47]
	s_nop 1
	v_mov_b32_dpp v49, v47 row_ror:4 row_mask:0xf bank_mask:0xf
	v_mov_b32_dpp v48, v46 row_ror:4 row_mask:0xf bank_mask:0xf
	v_pk_add_f32 v[46:47], v[46:47], v[48:49]
	s_nop 1
	v_mov_b32_dpp v51, v47 row_ror:2 row_mask:0xf bank_mask:0xf
	v_mov_b32_dpp v50, v46 row_ror:2 row_mask:0xf bank_mask:0xf
	v_pk_add_f32 v[46:47], v[46:47], v[50:51]
	s_nop 1
	v_mov_b32_dpp v53, v47 row_ror:1 row_mask:0xf bank_mask:0xf
	v_mov_b32_dpp v52, v46 row_ror:1 row_mask:0xf bank_mask:0xf
	v_pk_add_f32 v[46:47], v[46:47], v[52:53]
	s_nop 0
	v_pk_fma_f32 v[46:47], v[46:47], s[14:15], v[2:3] op_sel_hi:[1,0,0]
	s_nop 0
	v_mul_f32_e32 v2, 0x4b800000, v47
	v_cmp_gt_f32_e32 vcc, s15, v47
	s_nop 1
	v_cndmask_b32_e32 v2, v47, v2, vcc
	v_rsq_f32_e32 v2, v2
	s_nop 0
	v_mul_f32_e32 v3, 0x45800000, v2
	v_cndmask_b32_e32 v2, v2, v3, vcc
	v_mul_f32_e32 v2, 0x3e38aa3b, v2
	v_pk_mul_f32 v[40:41], v[2:3], v[40:41] op_sel_hi:[0,1]
	v_pk_mul_f32 v[2:3], v[2:3], v[38:39] op_sel_hi:[0,1]
	v_cmp_gt_f32_e32 vcc, s15, v46
	s_waitcnt vmcnt(0)
	v_pk_mul_f32 v[34:35], v[34:35], v[40:41]
	v_pk_mul_f32 v[2:3], v[36:37], v[2:3]
	v_cvt_pk_bf16_f32 v34, v34, v35
	v_cvt_pk_bf16_f32 v35, v2, v3
	global_store_dwordx2 v[0:1], v[34:35], off offset:3584
	global_load_dwordx4 v[0:3], v[12:13], off
	v_ashrrev_i32_e32 v35, 12, v33
	v_and_b32_e32 v33, 0xfffff000, v33
	v_sub_u32_e32 v34, v32, v33
	v_mul_f32_e32 v33, 0x4b800000, v46
	v_cndmask_b32_e32 v33, v46, v33, vcc
	v_rsq_f32_e32 v33, v33
	v_lshl_or_b32 v36, v35, 2, v61
	v_ashrrev_i32_e32 v35, 31, v34
	v_ashrrev_i32_e32 v37, 31, v36
	v_mul_f32_e32 v38, 0x45800000, v33
	v_cndmask_b32_e32 v38, v33, v38, vcc
	v_lshlrev_b64 v[34:35], 7, v[34:35]
	v_pk_mul_f32 v[40:41], v[38:39], v[44:45] op_sel_hi:[0,1]
	v_pk_mul_f32 v[38:39], v[38:39], v[42:43] op_sel_hi:[0,1]
	v_lshlrev_b64 v[36:37], 19, v[36:37]
	v_lshl_add_u64 v[34:35], v[6:7], 0, v[34:35]
	s_waitcnt vmcnt(0)
	v_pk_mul_f32 v[0:1], v[0:1], v[40:41]
	v_pk_mul_f32 v[2:3], v[2:3], v[38:39]
	v_cvt_pk_bf16_f32 v0, v0, v1
	v_cvt_pk_bf16_f32 v1, v2, v3
	v_lshl_add_u64 v[2:3], v[34:35], 0, v[36:37]
	global_store_dwordx2 v[2:3], v[0:1], off
	s_branch .LBB1_764

; DI void swa_prep_phase(const Params& p) {
;     ...
;     for (int ch = bid; ch < T / 64; ch += gridDim.x) {
;         const int c = tid & 255, kvh = c >> 6, d = c & 63, tq = tid >> 8;
; #pragma unroll
;         for (int gi = 0; gi < 4; ++gi) {
;             const int t0 = ch * 64 + (tq + 2 * gi) * 8, b = t0 / S, s0 = t0 - b * S;
;             unsigned v[8];
; #pragma unroll
;             for (int e = 0; e < 8; ++e) v[e] = QKV[(size_t)(t0 + e) * 2560 + 2304 + c];
;             u32x4 o; o[0] = v[0] | (v[1] << 16); o[1] = v[2] | (v[3] << 16); o[2] = v[4] | (v[5] << 16); o[3] = v[6] | (v[7] << 16);
;             *(u32x4*)(VTS + ((size_t)(b * 4 + kvh) * 64 + d) * S + s0) = o;
;         }
.LBB1_771:
	v_subrev_u32_e32 v42, 55, v7
	v_mad_i64_i32 v[8:9], s[6:7], v42, s3, v[4:5]
	v_subrev_u32_e32 v10, 54, v7
	v_lshl_add_u64 v[8:9], v[8:9], 0, v[0:1]
	v_mad_i64_i32 v[10:11], s[6:7], v10, s3, v[4:5]
	v_add_co_u32_e32 v8, vcc, 0x1000, v8
	v_subrev_u32_e32 v12, 53, v7
	v_lshl_add_u64 v[10:11], v[10:11], 0, v[0:1]
	v_addc_co_u32_e32 v9, vcc, 0, v9, vcc
	v_mad_i64_i32 v[12:13], s[6:7], v12, s3, v[4:5]
	v_add_co_u32_e32 v10, vcc, 0x1000, v10
	v_subrev_u32_e32 v14, 52, v7
	v_lshl_add_u64 v[12:13], v[12:13], 0, v[0:1]
	v_addc_co_u32_e32 v11, vcc, 0, v11, vcc
	v_mad_i64_i32 v[14:15], s[6:7], v14, s3, v[4:5]
	v_add_co_u32_e32 v12, vcc, 0x1000, v12
	v_subrev_u32_e32 v16, 51, v7
	v_lshl_add_u64 v[14:15], v[14:15], 0, v[0:1]
	v_addc_co_u32_e32 v13, vcc, 0, v13, vcc
	v_mad_i64_i32 v[16:17], s[6:7], v16, s3, v[4:5]
	global_load_ushort v61, v[8:9], off offset:512
	global_load_ushort v62, v[10:11], off offset:512
	v_add_co_u32_e32 v8, vcc, 0x1000, v14
	v_subrev_u32_e32 v18, 50, v7
	v_lshl_add_u64 v[16:17], v[16:17], 0, v[0:1]
	v_addc_co_u32_e32 v9, vcc, 0, v15, vcc
	v_mad_i64_i32 v[18:19], s[6:7], v18, s3, v[4:5]
	v_add_co_u32_e32 v10, vcc, 0x1000, v16
	v_subrev_u32_e32 v20, 49, v7
	v_lshl_add_u64 v[18:19], v[18:19], 0, v[0:1]
	v_addc_co_u32_e32 v11, vcc, 0, v17, vcc
	v_mad_i64_i32 v[20:21], s[6:7], v20, s3, v[4:5]
	global_load_ushort v63, v[12:13], off offset:512
	global_load_ushort v64, v[8:9], off offset:512
	v_add_co_u32_e32 v8, vcc, 0x1000, v18
	v_subrev_u32_e32 v22, 48, v7
	v_lshl_add_u64 v[20:21], v[20:21], 0, v[0:1]
	v_addc_co_u32_e32 v9, vcc, 0, v19, vcc
	v_mad_i64_i32 v[22:23], s[6:7], v22, s3, v[4:5]
	v_add_co_u32_e32 v12, vcc, 0x1000, v20
	v_lshl_add_u64 v[22:23], v[22:23], 0, v[0:1]
	s_nop 0
	v_addc_co_u32_e32 v13, vcc, 0, v21, vcc
	global_load_ushort v65, v[10:11], off offset:512
	global_load_ushort v66, v[8:9], off offset:512
	v_add_co_u32_e32 v8, vcc, 0x1000, v22
	v_subrev_u32_e32 v43, 39, v7
	s_nop 0
	v_addc_co_u32_e32 v9, vcc, 0, v23, vcc
	global_load_ushort v67, v[12:13], off offset:512
	global_load_ushort v68, v[8:9], off offset:512
	v_subrev_u32_e32 v28, 37, v7
	v_mad_i64_i32 v[24:25], s[6:7], v43, s3, v[4:5]
	v_subrev_u32_e32 v26, 38, v7
	v_mad_i64_i32 v[28:29], s[6:7], v28, s3, v[4:5]
	v_lshl_add_u64 v[8:9], v[24:25], 0, v[0:1]
	v_subrev_u32_e32 v30, 36, v7
	v_mad_i64_i32 v[26:27], s[6:7], v26, s3, v[4:5]
	v_lshl_add_u64 v[16:17], v[28:29], 0, v[0:1]
	v_add_co_u32_e32 v28, vcc, s5, v8
	v_mad_i64_i32 v[30:31], s[6:7], v30, s3, v[4:5]
	v_lshl_add_u64 v[10:11], v[26:27], 0, v[0:1]
	v_addc_co_u32_e32 v29, vcc, 0, v9, vcc
	v_lshl_add_u64 v[18:19], v[30:31], 0, v[0:1]
	v_add_co_u32_e32 v30, vcc, s5, v10
	v_subrev_u32_e32 v32, 35, v7
	s_nop 0
	v_addc_co_u32_e32 v31, vcc, 0, v11, vcc
	v_add_co_u32_e32 v16, vcc, s5, v16
	v_subrev_u32_e32 v45, 22, v7
	v_ashrrev_i32_e32 v59, 31, v42
	v_addc_co_u32_e32 v17, vcc, 0, v17, vcc
	v_mad_i64_i32 v[32:33], s[6:7], v32, s3, v[4:5]
	v_mad_i64_i32 v[12:13], s[6:7], v45, s3, v[4:5]
	v_lshrrev_b32_e32 v45, 20, v59
	v_add_co_u32_e32 v18, vcc, s5, v18
	v_subrev_u32_e32 v34, 34, v7
	v_lshl_add_u64 v[20:21], v[32:33], 0, v[0:1]
	v_add_u32_e32 v32, v42, v45
	v_addc_co_u32_e32 v19, vcc, 0, v19, vcc
	v_mad_i64_i32 v[34:35], s[6:7], v34, s3, v[4:5]
	v_add_co_u32_e32 v20, vcc, s5, v20
	v_ashrrev_i32_e32 v8, 12, v32
	v_and_b32_e32 v9, 0xfffff000, v32
	v_subrev_u32_e32 v36, 33, v7
	v_lshl_add_u64 v[22:23], v[34:35], 0, v[0:1]
	v_addc_co_u32_e32 v21, vcc, 0, v21, vcc
	v_sub_u32_e32 v9, v7, v9
	v_lshl_or_b32 v8, v8, 2, v6
	v_mad_i64_i32 v[36:37], s[6:7], v36, s3, v[4:5]
	v_add_co_u32_e32 v22, vcc, s5, v22
	v_subrev_u32_e32 v10, 55, v9
	v_ashrrev_i32_e32 v9, 31, v8
	v_subrev_u32_e32 v38, 32, v7
	v_lshl_add_u64 v[24:25], v[36:37], 0, v[0:1]
	v_addc_co_u32_e32 v23, vcc, 0, v23, vcc
	v_lshlrev_b64 v[8:9], 19, v[8:9]
	v_mad_i64_i32 v[38:39], s[6:7], v38, s3, v[4:5]
	v_add_co_u32_e32 v24, vcc, s5, v24
	v_ashrrev_i32_e32 v11, 31, v10
	v_lshl_add_u64 v[8:9], v[2:3], 0, v[8:9]
	v_lshl_add_u64 v[26:27], v[38:39], 0, v[0:1]
	v_addc_co_u32_e32 v25, vcc, 0, v25, vcc
	v_lshl_add_u64 v[32:33], v[10:11], 1, v[8:9]
	s_waitcnt vmcnt(0) lgkmcnt(0)
; DI void swa_prep_phase(const Params& p) {
;     ...
;         for (int gi = 0; gi < 4; ++gi) {
;             const int t0 = ch * 64 + (tq + 2 * gi) * 8, b = t0 / S, s0 = t0 - b * S;
;             unsigned v[8];
; #pragma unroll
;             for (int e = 0; e < 8; ++e) v[e] = QKV[(size_t)(t0 + e) * 2560 + 2304 + c];
;             u32x4 o; o[0] = v[0] | (v[1] << 16); o[1] = v[2] | (v[3] << 16); o[2] = v[4] | (v[5] << 16); o[3] = v[6] | (v[7] << 16);
;             *(u32x4*)(VTS + ((size_t)(b * 4 + kvh) * 64 + d) * S + s0) = o;
;         }
	v_lshl_or_b32 v8, v62, 16, v61
	v_lshl_or_b32 v9, v64, 16, v63
	v_lshl_or_b32 v10, v66, 16, v65
	v_add_co_u32_e32 v26, vcc, s5, v26
	v_lshl_or_b32 v11, v68, 16, v67
	global_store_dwordx4 v[32:33], v[8:11], off
	v_addc_co_u32_e32 v27, vcc, 0, v27, vcc
	global_load_ushort v32, v[28:29], off offset:512
	s_nop 0
	global_load_ushort v30, v[30:31], off offset:512
	s_nop 0
	global_load_ushort v31, v[16:17], off offset:512
	global_load_ushort v33, v[18:19], off offset:512
	global_load_ushort v34, v[20:21], off offset:512
	global_load_ushort v35, v[22:23], off offset:512
	global_load_ushort v36, v[24:25], off offset:512
	global_load_ushort v37, v[26:27], off offset:512
	v_subrev_u32_e32 v44, 23, v7
	v_mad_i64_i32 v[40:41], s[6:7], v44, s3, v[4:5]
	v_lshl_add_u64 v[22:23], v[40:41], 0, v[0:1]
	v_add_co_u32_e32 v22, vcc, s5, v22
	v_subrev_u32_e32 v46, 21, v7
	v_lshl_add_u64 v[12:13], v[12:13], 0, v[0:1]
	v_addc_co_u32_e32 v23, vcc, 0, v23, vcc
	v_mad_i64_i32 v[14:15], s[6:7], v46, s3, v[4:5]
	v_add_co_u32_e32 v12, vcc, s5, v12
	v_subrev_u32_e32 v47, 20, v7
	v_lshl_add_u64 v[14:15], v[14:15], 0, v[0:1]
	v_addc_co_u32_e32 v13, vcc, 0, v13, vcc
	v_ashrrev_i32_e32 v60, 31, v43
	v_mad_i64_i32 v[8:9], s[6:7], v47, s3, v[4:5]
	v_add_co_u32_e32 v14, vcc, s5, v14
	v_subrev_u32_e32 v48, 19, v7
	v_lshrrev_b32_e32 v24, 20, v60
	v_lshl_add_u64 v[8:9], v[8:9], 0, v[0:1]
	v_addc_co_u32_e32 v15, vcc, 0, v15, vcc
	v_mad_i64_i32 v[10:11], s[6:7], v48, s3, v[4:5]
	v_add_u32_e32 v28, v43, v24
	v_add_co_u32_e32 v24, vcc, s5, v8
	v_subrev_u32_e32 v49, 18, v7
	v_lshl_add_u64 v[10:11], v[10:11], 0, v[0:1]
	v_addc_co_u32_e32 v25, vcc, 0, v9, vcc
	v_mad_i64_i32 v[16:17], s[6:7], v49, s3, v[4:5]
	v_add_co_u32_e32 v26, vcc, s5, v10
	v_ashrrev_i32_e32 v8, 12, v28
	v_and_b32_e32 v9, 0xfffff000, v28
	v_subrev_u32_e32 v50, 17, v7
	v_lshl_add_u64 v[16:17], v[16:17], 0, v[0:1]
	v_addc_co_u32_e32 v27, vcc, 0, v11, vcc
	v_sub_u32_e32 v9, v7, v9
	v_lshl_or_b32 v8, v8, 2, v6
	v_mad_i64_i32 v[18:19], s[6:7], v50, s3, v[4:5]
	v_add_co_u32_e32 v16, vcc, s5, v16
	v_subrev_u32_e32 v10, 39, v9
	v_ashrrev_i32_e32 v9, 31, v8
	v_add_u32_e32 v51, -16, v7
	v_lshl_add_u64 v[18:19], v[18:19], 0, v[0:1]
	v_addc_co_u32_e32 v17, vcc, 0, v17, vcc
	v_lshlrev_b64 v[8:9], 19, v[8:9]
	v_mad_i64_i32 v[20:21], s[6:7], v51, s3, v[4:5]
	v_add_co_u32_e32 v18, vcc, s5, v18
	v_ashrrev_i32_e32 v11, 31, v10
	v_lshl_add_u64 v[8:9], v[2:3], 0, v[8:9]
	v_lshl_add_u64 v[20:21], v[20:21], 0, v[0:1]
	v_addc_co_u32_e32 v19, vcc, 0, v19, vcc
	v_lshl_add_u64 v[28:29], v[10:11], 1, v[8:9]
	v_add_co_u32_e32 v20, vcc, s5, v20
	v_add_u32_e32 v52, -7, v7
	s_waitcnt vmcnt(0) lgkmcnt(0)
	v_lshl_or_b32 v8, v30, 16, v32
	v_addc_co_u32_e32 v21, vcc, 0, v21, vcc
	v_lshl_or_b32 v9, v33, 16, v31
	v_lshl_or_b32 v10, v35, 16, v34
	v_add_u32_e32 v53, -6, v7
	v_lshl_or_b32 v11, v37, 16, v36
	global_store_dwordx4 v[28:29], v[8:11], off
	global_load_ushort v30, v[22:23], off offset:512
	global_load_ushort v31, v[12:13], off offset:512
	global_load_ushort v32, v[14:15], off offset:512
	global_load_ushort v33, v[24:25], off offset:512
	global_load_ushort v34, v[26:27], off offset:512
	global_load_ushort v35, v[16:17], off offset:512
	global_load_ushort v36, v[18:19], off offset:512
	global_load_ushort v37, v[20:21], off offset:512
	v_mad_i64_i32 v[8:9], s[6:7], v7, s3, v[4:5]
	v_ashrrev_i32_e32 v24, 31, v44
	v_lshl_add_u64 v[8:9], v[8:9], 0, v[0:1]
	v_mad_i64_i32 v[10:11], s[6:7], v52, s3, v[4:5]
	v_lshrrev_b32_e32 v26, 20, v24
	v_add_co_u32_e32 v24, vcc, s5, v8
	v_lshl_add_u64 v[10:11], v[10:11], 0, v[0:1]
	s_nop 0
	v_addc_co_u32_e32 v25, vcc, 0, v9, vcc
	v_mad_i64_i32 v[12:13], s[6:7], v53, s3, v[4:5]
	v_add_u32_e32 v8, v44, v26
	v_add_co_u32_e32 v26, vcc, s5, v10
	v_add_u32_e32 v54, -5, v7
	v_lshl_add_u64 v[12:13], v[12:13], 0, v[0:1]
	v_addc_co_u32_e32 v27, vcc, 0, v11, vcc
	v_mad_i64_i32 v[14:15], s[6:7], v54, s3, v[4:5]
	v_add_co_u32_e32 v12, vcc, s5, v12
	v_add_u32_e32 v55, -4, v7
	v_lshl_add_u64 v[14:15], v[14:15], 0, v[0:1]
	v_addc_co_u32_e32 v13, vcc, 0, v13, vcc
	v_mad_i64_i32 v[16:17], s[6:7], v55, s3, v[4:5]
	v_add_co_u32_e32 v14, vcc, s5, v14
	v_add_u32_e32 v56, -3, v7
	v_lshl_add_u64 v[16:17], v[16:17], 0, v[0:1]
	v_addc_co_u32_e32 v15, vcc, 0, v15, vcc
	v_mad_i64_i32 v[18:19], s[6:7], v56, s3, v[4:5]
	v_add_co_u32_e32 v16, vcc, s5, v16
	v_ashrrev_i32_e32 v9, 12, v8
	v_and_b32_e32 v8, 0xfffff000, v8
	v_add_u32_e32 v57, -2, v7
	v_lshl_add_u64 v[18:19], v[18:19], 0, v[0:1]
	v_addc_co_u32_e32 v17, vcc, 0, v17, vcc
	v_sub_u32_e32 v10, v7, v8
	v_lshl_or_b32 v8, v9, 2, v6
	v_mad_i64_i32 v[20:21], s[6:7], v57, s3, v[4:5]
	v_add_co_u32_e32 v18, vcc, s5, v18
	v_ashrrev_i32_e32 v9, 31, v8
	v_add_u32_e32 v58, -1, v7
	v_lshl_add_u64 v[20:21], v[20:21], 0, v[0:1]
	v_addc_co_u32_e32 v19, vcc, 0, v19, vcc
	v_subrev_u32_e32 v10, 23, v10
	v_lshlrev_b64 v[8:9], 19, v[8:9]
	v_mad_i64_i32 v[22:23], s[6:7], v58, s3, v[4:5]
	v_add_co_u32_e32 v20, vcc, s5, v20
	v_ashrrev_i32_e32 v11, 31, v10
	v_lshl_add_u64 v[8:9], v[2:3], 0, v[8:9]
	v_lshl_add_u64 v[22:23], v[22:23], 0, v[0:1]
	v_addc_co_u32_e32 v21, vcc, 0, v21, vcc
	v_lshl_add_u64 v[28:29], v[10:11], 1, v[8:9]
	v_add_co_u32_e32 v22, vcc, s5, v22
	s_add_i32 s4, s4, s50
	s_waitcnt vmcnt(0) lgkmcnt(0)
	v_lshl_or_b32 v8, v31, 16, v30
	v_addc_co_u32_e32 v23, vcc, 0, v23, vcc
	v_lshl_or_b32 v9, v33, 16, v32
	v_lshl_or_b32 v10, v35, 16, v34
	s_cmpk_lt_i32 s4, 0x100
	v_lshl_or_b32 v11, v37, 16, v36
	global_store_dwordx4 v[28:29], v[8:11], off
	global_load_ushort v26, v[26:27], off offset:512
	s_nop 0
	global_load_ushort v27, v[12:13], off offset:512
	s_nop 0
	global_load_ushort v14, v[14:15], off offset:512
	s_nop 0
	global_load_ushort v15, v[16:17], off offset:512
	s_nop 0
	global_load_ushort v16, v[18:19], off offset:512
	global_load_ushort v17, v[20:21], off offset:512
	s_nop 0
	global_load_ushort v18, v[22:23], off offset:512
	global_load_ushort v19, v[24:25], off offset:512
	v_ashrrev_i32_e32 v8, 31, v52
	v_lshrrev_b32_e32 v8, 20, v8
	v_add_u32_e32 v8, v52, v8
	v_ashrrev_i32_e32 v9, 12, v8
	v_and_b32_e32 v8, 0xfffff000, v8
	v_sub_u32_e32 v10, v7, v8
	v_lshl_or_b32 v8, v9, 2, v6
	v_ashrrev_i32_e32 v9, 31, v8
	v_add_u32_e32 v10, -7, v10
	v_lshlrev_b64 v[8:9], 19, v[8:9]
	v_ashrrev_i32_e32 v11, 31, v10
	v_lshl_add_u64 v[8:9], v[2:3], 0, v[8:9]
	v_add_u32_e32 v7, s2, v7
	v_lshl_add_u64 v[12:13], v[10:11], 1, v[8:9]
	s_waitcnt vmcnt(0) lgkmcnt(0)
	v_lshl_or_b32 v8, v27, 16, v26
	v_lshl_or_b32 v9, v15, 16, v14
	v_lshl_or_b32 v10, v17, 16, v16
	v_lshl_or_b32 v11, v19, 16, v18
	global_store_dwordx4 v[12:13], v[8:11], off
	s_cbranch_scc1 .LBB1_771

; DI unsigned pack2(float a, float b) { f32x2 v = {a, b}; hwbf16x2 r = __builtin_convertvector(v, hwbf16x2); return __builtin_bit_cast(unsigned, r); }
; DI float xsum32(float v) { return v + __shfl_xor(v, 32); }
; DI float fast_exp2(float x) { return __builtin_amdgcn_exp2f(x); }
; DI void swa_attn_phase(const Params& p, LAS unsigned char* lds) {
;     ...
;         const float lt = xsum32(l) + fast_exp2(sink2 - m), inv = 1.0f / lt;
;         bf16_t* Op = O + (size_t)(b * S + qi) * 2048 + hq * 64 + 4 * h;
; #pragma unroll
;         for (int db = 0; db < 2; ++db)
; #pragma unroll
;             for (int g = 0; g < 4; ++g) { u32x2 o; o[0] = pack2(oacc[db][4 * g] * inv, oacc[db][4 * g + 1] * inv); o[1] = pack2(oacc[db][4 * g + 2] * inv, oacc[db][4 * g + 3] * inv);
;                 *(u32x2*)(Op + db * 32 + 8 * g) = o; }
;         __syncthreads();
.LBB1_838:
	ds_bpermute_b32 v32, v83, v75
	v_sub_f32_e32 v33, v95, v97
	v_exp_f32_e32 v33, v33
	s_add_i32 s2, s2, s50
	s_cmpk_gt_i32 s2, 0x7ff
	s_waitcnt lgkmcnt(0)
	v_add_f32_e32 v32, v75, v32
	v_add_f32_e32 v34, v33, v32
	v_div_scale_f32 v35, s[12:13], v34, v34, 1.0
	v_rcp_f32_e32 v36, v35
	v_div_scale_f32 v37, vcc, 1.0, v34, 1.0
	v_lshl_add_u64 v[32:33], s[8:9], 0, v[78:79]
	v_fma_f32 v38, -v35, v36, 1.0
	v_fmac_f32_e32 v36, v38, v36
	v_mul_f32_e32 v38, v37, v36
	v_fma_f32 v39, -v35, v38, v37
	v_fmac_f32_e32 v38, v39, v36
	v_fma_f32 v35, -v35, v38, v37
	v_div_fmas_f32 v35, v35, v36, v38
	v_div_fixup_f32 v34, v35, v34, 1.0
	v_lshl_add_u64 v[32:33], v[76:77], 1, v[32:33]
	v_mov_b32_e32 v75, v65
	v_pk_mul_f32 v[16:17], v[16:17], v[34:35] op_sel_hi:[1,0]
	v_pk_mul_f32 v[18:19], v[18:19], v[34:35] op_sel_hi:[1,0]
	v_pk_mul_f32 v[0:1], v[0:1], v[34:35] op_sel_hi:[1,0]
	v_pk_mul_f32 v[2:3], v[2:3], v[34:35] op_sel_hi:[1,0]
	v_lshl_add_u64 v[32:33], v[32:33], 0, v[74:75]
	v_cvt_pk_bf16_f32 v16, v16, v17
	v_cvt_pk_bf16_f32 v17, v18, v19
	v_cvt_pk_bf16_f32 v0, v0, v1
	v_cvt_pk_bf16_f32 v1, v2, v3
	global_store_dwordx2 v[32:33], v[16:17], off
	v_pk_mul_f32 v[16:17], v[20:21], v[34:35] op_sel_hi:[1,0]
	v_pk_mul_f32 v[18:19], v[22:23], v[34:35] op_sel_hi:[1,0]
	global_store_dwordx2 v[32:33], v[0:1], off offset:64
	v_pk_mul_f32 v[0:1], v[4:5], v[34:35] op_sel_hi:[1,0]
	v_pk_mul_f32 v[2:3], v[6:7], v[34:35] op_sel_hi:[1,0]
	v_cvt_pk_bf16_f32 v16, v16, v17
	v_cvt_pk_bf16_f32 v17, v18, v19
	v_cvt_pk_bf16_f32 v0, v0, v1
	v_cvt_pk_bf16_f32 v1, v2, v3
	global_store_dwordx2 v[32:33], v[16:17], off offset:16
	v_pk_mul_f32 v[16:17], v[24:25], v[34:35] op_sel_hi:[1,0]
	v_pk_mul_f32 v[18:19], v[26:27], v[34:35] op_sel_hi:[1,0]
	global_store_dwordx2 v[32:33], v[0:1], off offset:80
	v_pk_mul_f32 v[0:1], v[8:9], v[34:35] op_sel_hi:[1,0]
	v_pk_mul_f32 v[2:3], v[10:11], v[34:35] op_sel_hi:[1,0]
	v_cvt_pk_bf16_f32 v16, v16, v17
	v_cvt_pk_bf16_f32 v17, v18, v19
	v_cvt_pk_bf16_f32 v0, v0, v1
	v_cvt_pk_bf16_f32 v1, v2, v3
	global_store_dwordx2 v[32:33], v[16:17], off offset:32
	v_pk_mul_f32 v[16:17], v[28:29], v[34:35] op_sel_hi:[1,0]
	v_pk_mul_f32 v[18:19], v[30:31], v[34:35] op_sel_hi:[1,0]
	global_store_dwordx2 v[32:33], v[0:1], off offset:96
	v_pk_mul_f32 v[0:1], v[12:13], v[34:35] op_sel_hi:[1,0]
	v_pk_mul_f32 v[2:3], v[14:15], v[34:35] op_sel_hi:[1,0]
	v_cvt_pk_bf16_f32 v16, v16, v17
	v_cvt_pk_bf16_f32 v17, v18, v19
	v_cvt_pk_bf16_f32 v0, v0, v1
	v_cvt_pk_bf16_f32 v1, v2, v3
	global_store_dwordx2 v[32:33], v[16:17], off offset:48
	global_store_dwordx2 v[32:33], v[0:1], off offset:112
	s_waitcnt lgkmcnt(0)
	s_barrier
	s_cbranch_scc1 .LBB1_854

; #define LAS __attribute__((address_space(3)))
; DI void swa_attn_phase(const Params& p, LAS unsigned char* lds) {
;     ...
;         for (int c = tid; c < 2304; c += 512) { const int row = c >> 3, cc = c & 7, key = kstart + row;
;             if (key >= 0 && key < S) *(LAS u32x4*)(lds + row * KSTR + cc * 16) = *(const u32x4*)(Kg + (size_t)key * 64 + cc * 8); }
.LBB1_842:
	v_ashrrev_i32_e32 v3, 3, v2
	v_add_u32_e32 v4, s23, v3
	v_cmp_gt_u32_e32 vcc, s20, v4
	s_and_saveexec_b64 s[18:19], vcc
	s_cbranch_execz .LBB1_841
	v_lshlrev_b32_e32 v64, 7, v4
	v_lshl_add_u64 v[4:5], v[0:1], 0, v[64:65]
	global_load_dwordx4 v[4:7], v[4:5], off
	s_movk_i32 s26, 0x90
	v_mad_u64_u32 v[8:9], s[26:27], v3, s26, v[70:71]
	s_waitcnt vmcnt(0) lgkmcnt(0)
	ds_write_b128 v8, v[4:7]
	s_branch .LBB1_841

; #define LAS __attribute__((address_space(3)))
; DI void swa_attn_phase(const Params& p, LAS unsigned char* lds) {
;     ...
;         for (int c = tid; c < 2304; c += 512) { const int row = c / 36, cc = c - row * 36, key0 = kstart + cc * 8;
;             if (key0 >= 0 && key0 < S) { const u32x4 v = *(const u32x4*)(Vg + (size_t)row * S + key0);
;                 LAS u32x2* dp = (LAS u32x2*)(lds + VOFF + row * VSTR + (cc >> 1) * 32 + (cc & 1) * 8); dp[0] = (u32x2){v[0], v[1]}; dp[2] = (u32x2){v[2], v[3]}; } }
;         __syncthreads();
;         const int hq = kvh * 8 + wid;
;         const float slope2 = exp2f(-(float)(hq + 1) * 0.25f) * LOG2E, sink2 = p.swa_sinks[hq] * LOG2E;
;         const bf16_t* Qp = QS + (size_t)(b * S + q0 + r) * 2048 + hq * 64 + 8 * h;
;         bf16x8 qf[4];
; #pragma unroll
;         for (int ks = 0; ks < 4; ++ks) qf[ks] = *(const bf16x8*)(Qp + 16 * ks);
;         const int qi = q0 + r, pq = p.positions[qi];
;         float m = sink2, l = 0.f;
;         f32x16 oacc[2];
; #pragma unroll
;         for (int db = 0; db < 2; ++db)
; #pragma unroll
;             for (int i = 0; i < 16; ++i) oacc[db][i] = 0.f;
.LBB1_846:
	s_mov_b32 s18, 0x38e38e39
	v_mul_hi_i32 v2, v4, s18
	v_lshrrev_b32_e32 v3, 31, v2
	v_ashrrev_i32_e32 v2, 3, v2
	v_add_u32_e32 v2, v2, v3
	s_movk_i32 s18, 0xfee0
	v_mul_lo_u32 v3, v2, s18
	v_add3_u32 v64, s23, v1, v3
	v_cmp_gt_u32_e32 vcc, s20, v64
	s_and_saveexec_b64 s[18:19], vcc
	s_cbranch_execz .LBB1_845
	v_ashrrev_i32_e32 v3, 31, v2
	v_lshlrev_b64 v[6:7], 13, v[2:3]
	v_lshl_add_u64 v[6:7], s[14:15], 0, v[6:7]
	v_lshl_add_u64 v[6:7], v[64:65], 1, v[6:7]
	global_load_dwordx4 v[6:9], v[6:7], off
	s_movk_i32 s26, 0x250
	v_mul_lo_u32 v3, v2, s26
	s_movk_i32 s26, 0xfdc0
	v_add_u32_e32 v5, 0, v3
	v_mad_u64_u32 v[2:3], s[26:27], v2, s26, v[0:1]
	v_and_b32_e32 v2, 0xffffffe0, v2
	v_and_b32_e32 v3, 8, v1
	v_add3_u32 v2, v5, v2, v3
	v_add_u32_e32 v2, 0xa000, v2
	s_waitcnt vmcnt(0) lgkmcnt(0)
	ds_write2_b64 v2, v[6:7], v[8:9] offset0:64 offset1:66
	s_branch .LBB1_845
.LBB1_848:
	s_or_b64 exec, exec, s[12:13]
	s_waitcnt lgkmcnt(0)
	s_barrier
	s_load_dwordx2 s[12:13], s[0:1], 0x38
	v_lshl_add_u32 v0, s25, 3, v71
	v_ashrrev_i32_e32 v1, 31, v0
	v_lshlrev_b32_e32 v76, 6, v0
	v_ashrrev_i32_e32 v77, 31, v76
	s_waitcnt lgkmcnt(0)
	v_lshl_add_u64 v[2:3], v[0:1], 2, s[12:13]
	v_or_b32_e32 v1, s24, v82
	global_load_dword v13, v[2:3], off
	v_lshl_or_b32 v2, s3, 12, v1
	v_ashrrev_i32_e32 v3, 31, v2
	v_lshlrev_b64 v[78:79], 12, v[2:3]
	v_lshl_add_u64 v[2:3], s[6:7], 0, v[78:79]
	v_lshl_add_u64 v[2:3], v[76:77], 1, v[2:3]
	v_lshl_add_u64 v[2:3], v[2:3], 0, v[72:73]
	v_lshlrev_b32_e32 v1, 2, v1
	global_load_dwordx4 v[48:51], v[2:3], off
	global_load_dwordx4 v[52:55], v[2:3], off offset:32
	global_load_dword v92, v1, s[10:11]
	global_load_dwordx4 v[56:59], v[2:3], off offset:64
	global_load_dwordx4 v[60:63], v[2:3], off offset:96
	v_add_u32_e32 v8, 1, v0
	v_cvt_f32_i32_e32 v11, v8
	s_mov_b32 s3, 0xc2fc0000
	v_mov_b32_e32 v75, 0
	s_mov_b32 s12, 0
	v_mul_f32_e32 v12, 0xbe800000, v11
	v_cmp_gt_f32_e32 vcc, s3, v12
	v_mov_b32_e32 v93, v87
	v_mov_b32_e32 v94, v86
	v_cndmask_b32_e32 v12, 0, v89, vcc
	v_fmac_f32_e32 v12, 0xbe800000, v11
	v_exp_f32_e32 v14, v12
	v_cndmask_b32_e32 v15, 0, v90, vcc
	v_mov_b32_e32 v16, 0
	v_mov_b32_e32 v17, v75
	v_ldexp_f32 v14, v14, v15
	v_mov_b32_e32 v18, v75
	v_mov_b32_e32 v19, v75
	v_mov_b32_e32 v20, v75
	v_mov_b32_e32 v21, v75
	v_mov_b32_e32 v22, v75
	v_mov_b32_e32 v23, v75
	v_mov_b32_e32 v24, v75
	v_mov_b32_e32 v25, v75
	v_mov_b32_e32 v26, v75
	v_mov_b32_e32 v27, v75
	v_mov_b32_e32 v28, v75
	v_mov_b32_e32 v29, v75
	v_mov_b32_e32 v30, v75
	v_mov_b32_e32 v31, v75
	v_mov_b32_e32 v0, v75
	v_mov_b32_e32 v1, v75
	v_mov_b32_e32 v2, v75
	v_mov_b32_e32 v3, v75
	v_mov_b32_e32 v4, v75
	v_mov_b32_e32 v5, v75
	v_mov_b32_e32 v6, v75
	v_mov_b32_e32 v7, v75
	v_mov_b32_e32 v8, v75
	v_mov_b32_e32 v9, v75
	v_mov_b32_e32 v10, v75
	v_mov_b32_e32 v11, v75
	v_mov_b32_e32 v12, v75
	v_mul_f32_e32 v96, 0x3fb8aa3b, v14
	v_mov_b32_e32 v14, v75
	v_mov_b32_e32 v15, v75
	s_waitcnt vmcnt(0)
	v_mul_f32_e32 v95, 0x3fb8aa3b, v13
	v_mov_b32_e32 v97, v95
	v_mov_b32_e32 v13, v75
	s_branch .LBB1_851

; #define PG8_STAGE(bufoff, gbase, voff) do { _Pragma("unroll") for (int _i = 0; _i < 2; ++_i) \
;         __builtin_amdgcn_global_load_lds((const unsigned*)((const char*)(gbase) + (voff)[_i]), (LAS unsigned*)(lds + (bufoff) + ldsw + _i * 8192), 16, 0, 0); } while (0)
; #define PG8_LDA(dst, b, h) do { _Pragma("unroll") for (int m = 0; m < 4; ++m) _Pragma("unroll") for (int k = 0; k < 2; ++k) dst[m][k] = *(const LAS bf16x8*)(lds + PG8_SA(b, h) + aoff + m * 2048 + k * 1024); } while (0)
; #define PG8_LDB(dst, b, h) do { _Pragma("unroll") for (int n = 0; n < 2; ++n) _Pragma("unroll") for (int k = 0; k < 2; ++k) dst[n][k] = *(const LAS bf16x8*)(lds + PG8_SB(b, h) + boff + n * 2048 + k * 1024); } while (0)
; #define PG8_MMA(ai, bj, At, Bt) do { __builtin_amdgcn_s_setprio(1); _Pragma("unroll") for (int m = 0; m < 4; ++m) _Pragma("unroll") for (int n = 0; n < 2; ++n) _Pragma("unroll") for (int k = 0; k < 2; ++k) \
;         acc[ai][bj][m][n] = __builtin_amdgcn_mfma_f32_16x16x32_bf16(Bt[n][k], At[m][k], acc[ai][bj][m][n], 0, 0, 0); __builtin_amdgcn_s_setprio(0); } while (0)
; #define PG8_WAIT_V(n) asm volatile("s_waitcnt vmcnt(" #n ")" ::: "memory")
; #define PG8_WAIT_L(n) asm volatile("s_waitcnt lgkmcnt(" #n ")" ::: "memory")
; #define PG8_BAR __builtin_amdgcn_s_barrier()
; #define PG8_SCHED __builtin_amdgcn_sched_barrier(0)
; template <class Map, class Epi>
; DI void gemm_phase(LAS unsigned char* lds, const Map& MP, const Epi& E, const int nM, const int nN, const int K, const int lda, const int ldb) {
;     ...
;             PG8_LDB(B0, 0, 0); PG8_SCHED; PG8_LDA(At, 0, 0); PG8_STAGE(PG8_SA(1, 1), a1 + hstepA, voffA);
;             PG8_WAIT_L(8); PG8_BAR; PG8_WAIT_L(0); PG8_MMA(0, 0, At, B0); PG8_BAR; PG8_SCHED;
;             PG8_LDB(B1, 0, 1); PG8_STAGE(PG8_SB(0, 0), b2, voffB);
;             PG8_BAR; PG8_WAIT_L(0); PG8_MMA(0, 1, At, B1); PG8_BAR;
;             PG8_LDA(At, 0, 1); PG8_STAGE(PG8_SA(0, 0), a2, voffA);
;             PG8_BAR; PG8_WAIT_L(0); PG8_MMA(1, 0, At, B0); PG8_BAR; PG8_SCHED;
;             PG8_STAGE(PG8_SB(0, 1), b2 + hstepB, voffB);
;             PG8_WAIT_V(6); PG8_BAR; PG8_MMA(1, 1, At, B1); PG8_BAR;
.LBB1_925:
	ds_read_b128 v[152:155], v149
	ds_read_b128 v[156:159], v149 offset:1024
	ds_read_b128 v[160:163], v149 offset:2048
	ds_read_b128 v[164:167], v149 offset:3072
	s_add_u32 s3, s10, 0xfff80080
	s_addc_u32 s12, s11, -1
	s_cmp_eq_u32 s48, 28
	s_cselect_b32 s15, s4, s12
	s_cselect_b32 s14, s5, s3
	s_cselect_b32 s13, s37, s47
	s_cselect_b32 s12, s38, s39
	v_lshl_add_u64 v[144:145], s[10:11], 0, v[138:139]
	s_add_i32 m0, s24, 0xc000
	ds_read_b128 v[168:171], v150
	ds_read_b128 v[172:175], v150 offset:1024
	ds_read_b128 v[176:179], v150 offset:2048
	ds_read_b128 v[180:183], v150 offset:3072
	ds_read_b128 v[184:187], v150 offset:4096
	ds_read_b128 v[188:191], v150 offset:5120
	ds_read_b128 v[192:195], v150 offset:6144
	ds_read_b128 v[198:201], v150 offset:7168
	global_load_lds_dwordx4 v[144:145], off
	v_lshl_add_u64 v[144:145], s[10:11], 0, v[136:137]
	s_add_i32 m0, s24, 0xe000
	s_nop 0
	global_load_lds_dwordx4 v[144:145], off
	s_waitcnt lgkmcnt(8)
	s_barrier
	s_setprio 1
	s_waitcnt lgkmcnt(7)
	v_mfma_f32_16x16x32_bf16 v[124:127], v[152:155], v[168:171], v[124:127]
	v_mfma_f32_16x16x32_bf16 v[120:123], v[160:163], v[168:171], v[120:123]
	s_waitcnt lgkmcnt(5)
	v_mfma_f32_16x16x32_bf16 v[108:111], v[152:155], v[176:179], v[108:111]
	v_mfma_f32_16x16x32_bf16 v[104:107], v[160:163], v[176:179], v[104:107]
	s_waitcnt lgkmcnt(3)
	v_mfma_f32_16x16x32_bf16 v[92:95], v[152:155], v[184:187], v[92:95]
	v_mfma_f32_16x16x32_bf16 v[88:91], v[160:163], v[184:187], v[88:91]
	s_waitcnt lgkmcnt(1)
	v_mfma_f32_16x16x32_bf16 v[76:79], v[152:155], v[192:195], v[76:79]
	v_mfma_f32_16x16x32_bf16 v[72:75], v[160:163], v[192:195], v[72:75]
	v_mfma_f32_16x16x32_bf16 v[124:127], v[156:159], v[172:175], v[124:127]
	v_mfma_f32_16x16x32_bf16 v[120:123], v[164:167], v[172:175], v[120:123]
	v_mfma_f32_16x16x32_bf16 v[108:111], v[156:159], v[180:183], v[108:111]
	v_mfma_f32_16x16x32_bf16 v[104:107], v[164:167], v[180:183], v[104:107]
	v_mfma_f32_16x16x32_bf16 v[92:95], v[156:159], v[188:191], v[92:95]
	v_mfma_f32_16x16x32_bf16 v[88:91], v[164:167], v[188:191], v[88:91]
	s_waitcnt lgkmcnt(0)
	v_mfma_f32_16x16x32_bf16 v[76:79], v[156:159], v[198:201], v[76:79]
	v_mfma_f32_16x16x32_bf16 v[72:75], v[164:167], v[198:201], v[72:75]
	s_setprio 0
	s_barrier
	s_add_i32 s3, s35, s22
	v_lshl_add_u64 v[144:145], s[12:13], 0, v[132:133]
	s_mov_b32 m0, s3
	ds_read_b128 v[202:205], v151
	ds_read_b128 v[206:209], v151 offset:1024
	ds_read_b128 v[210:213], v151 offset:2048
	ds_read_b128 v[214:217], v151 offset:3072
	global_load_lds_dwordx4 v[144:145], off
	v_lshl_add_u64 v[218:219], s[12:13], 0, v[128:129]
	s_add_i32 m0, s3, 0x2000
	s_nop 0
	global_load_lds_dwordx4 v[218:219], off
	s_barrier
	s_setprio 1
	s_waitcnt lgkmcnt(3)
	v_mfma_f32_16x16x32_bf16 v[116:119], v[202:205], v[168:171], v[116:119]
	s_waitcnt lgkmcnt(1)
	v_mfma_f32_16x16x32_bf16 v[112:115], v[210:213], v[168:171], v[112:115]
	v_mfma_f32_16x16x32_bf16 v[100:103], v[202:205], v[176:179], v[100:103]
	v_mfma_f32_16x16x32_bf16 v[96:99], v[210:213], v[176:179], v[96:99]
	v_mfma_f32_16x16x32_bf16 v[84:87], v[202:205], v[184:187], v[84:87]
	v_mfma_f32_16x16x32_bf16 v[80:83], v[210:213], v[184:187], v[80:83]
	v_mfma_f32_16x16x32_bf16 v[68:71], v[202:205], v[192:195], v[68:71]
	v_mfma_f32_16x16x32_bf16 v[64:67], v[210:213], v[192:195], v[64:67]
	v_mfma_f32_16x16x32_bf16 v[116:119], v[206:209], v[172:175], v[116:119]
	s_waitcnt lgkmcnt(0)
	v_mfma_f32_16x16x32_bf16 v[112:115], v[214:217], v[172:175], v[112:115]
	v_mfma_f32_16x16x32_bf16 v[100:103], v[206:209], v[180:183], v[100:103]
	v_mfma_f32_16x16x32_bf16 v[96:99], v[214:217], v[180:183], v[96:99]
	v_mfma_f32_16x16x32_bf16 v[84:87], v[206:209], v[188:191], v[84:87]
	v_mfma_f32_16x16x32_bf16 v[80:83], v[214:217], v[188:191], v[80:83]
	v_mfma_f32_16x16x32_bf16 v[68:71], v[206:209], v[198:201], v[68:71]
	v_mfma_f32_16x16x32_bf16 v[64:67], v[214:217], v[198:201], v[64:67]
	s_setprio 0
	s_mov_b32 m0, s24
	v_lshl_add_u64 v[220:221], s[14:15], 0, v[134:135]
	s_barrier
	ds_read_b128 v[168:171], v150 offset:16384
	ds_read_b128 v[172:175], v150 offset:17408
	ds_read_b128 v[176:179], v150 offset:18432
	ds_read_b128 v[180:183], v150 offset:19456
	ds_read_b128 v[184:187], v150 offset:20480
	ds_read_b128 v[188:191], v150 offset:21504
	ds_read_b128 v[192:195], v150 offset:22528
	ds_read_b128 v[198:201], v150 offset:23552
	global_load_lds_dwordx4 v[220:221], off
	v_lshl_add_u64 v[222:223], s[14:15], 0, v[130:131]
	s_mov_b32 m0, s9
	s_nop 0
	global_load_lds_dwordx4 v[222:223], off
	s_barrier
	s_setprio 1
	s_waitcnt lgkmcnt(7)
	v_mfma_f32_16x16x32_bf16 v[60:63], v[152:155], v[168:171], v[60:63]
	v_mfma_f32_16x16x32_bf16 v[56:59], v[160:163], v[168:171], v[56:59]
	s_waitcnt lgkmcnt(5)
	v_mfma_f32_16x16x32_bf16 v[44:47], v[152:155], v[176:179], v[44:47]
	v_mfma_f32_16x16x32_bf16 v[40:43], v[160:163], v[176:179], v[40:43]
	s_waitcnt lgkmcnt(3)
	v_mfma_f32_16x16x32_bf16 v[28:31], v[152:155], v[184:187], v[28:31]
	v_mfma_f32_16x16x32_bf16 v[24:27], v[160:163], v[184:187], v[24:27]
	s_waitcnt lgkmcnt(1)
	v_mfma_f32_16x16x32_bf16 v[12:15], v[152:155], v[192:195], v[12:15]
	v_mfma_f32_16x16x32_bf16 v[8:11], v[160:163], v[192:195], v[8:11]
	v_mfma_f32_16x16x32_bf16 v[60:63], v[156:159], v[172:175], v[60:63]
	v_mfma_f32_16x16x32_bf16 v[56:59], v[164:167], v[172:175], v[56:59]
	v_mfma_f32_16x16x32_bf16 v[44:47], v[156:159], v[180:183], v[44:47]
	v_mfma_f32_16x16x32_bf16 v[40:43], v[164:167], v[180:183], v[40:43]
	v_mfma_f32_16x16x32_bf16 v[28:31], v[156:159], v[188:191], v[28:31]
	v_mfma_f32_16x16x32_bf16 v[24:27], v[164:167], v[188:191], v[24:27]
	s_waitcnt lgkmcnt(0)
	v_mfma_f32_16x16x32_bf16 v[12:15], v[156:159], v[198:201], v[12:15]
	v_mfma_f32_16x16x32_bf16 v[8:11], v[164:167], v[198:201], v[8:11]
	s_setprio 0
	s_barrier
; #define PG8_STAGE(bufoff, gbase, voff) do { _Pragma("unroll") for (int _i = 0; _i < 2; ++_i) \
;         __builtin_amdgcn_global_load_lds((const unsigned*)((const char*)(gbase) + (voff)[_i]), (LAS unsigned*)(lds + (bufoff) + ldsw + _i * 8192), 16, 0, 0); } while (0)
; #define PG8_LDA(dst, b, h) do { _Pragma("unroll") for (int m = 0; m < 4; ++m) _Pragma("unroll") for (int k = 0; k < 2; ++k) dst[m][k] = *(const LAS bf16x8*)(lds + PG8_SA(b, h) + aoff + m * 2048 + k * 1024); } while (0)
; #define PG8_LDB(dst, b, h) do { _Pragma("unroll") for (int n = 0; n < 2; ++n) _Pragma("unroll") for (int k = 0; k < 2; ++k) dst[n][k] = *(const LAS bf16x8*)(lds + PG8_SB(b, h) + boff + n * 2048 + k * 1024); } while (0)
; #define PG8_MMA(ai, bj, At, Bt) do { __builtin_amdgcn_s_setprio(1); _Pragma("unroll") for (int m = 0; m < 4; ++m) _Pragma("unroll") for (int n = 0; n < 2; ++n) _Pragma("unroll") for (int k = 0; k < 2; ++k) \
;         acc[ai][bj][m][n] = __builtin_amdgcn_mfma_f32_16x16x32_bf16(Bt[n][k], At[m][k], acc[ai][bj][m][n], 0, 0, 0); __builtin_amdgcn_s_setprio(0); } while (0)
; #define PG8_WAIT_V(n) asm volatile("s_waitcnt vmcnt(" #n ")" ::: "memory")
; #define PG8_WAIT_L(n) asm volatile("s_waitcnt lgkmcnt(" #n ")" ::: "memory")
; #define PG8_BAR __builtin_amdgcn_s_barrier()
; #define PG8_SCHED __builtin_amdgcn_sched_barrier(0)
; template <class Map, class Epi>
; DI void gemm_phase(LAS unsigned char* lds, const Map& MP, const Epi& E, const int nM, const int nN, const int K, const int lda, const int ldb) {
;     ...
;             PG8_STAGE(PG8_SB(0, 1), b2 + hstepB, voffB);
;             PG8_WAIT_V(6); PG8_BAR; PG8_MMA(1, 1, At, B1); PG8_BAR;
;             PG8_LDB(B0, 1, 0); PG8_SCHED; PG8_LDA(At, 1, 0); PG8_STAGE(PG8_SA(0, 1), a2 + hstepA, voffA);
;             PG8_WAIT_L(8); PG8_BAR; PG8_WAIT_L(0); PG8_MMA(0, 0, At, B0); PG8_BAR; PG8_SCHED;
;             PG8_LDB(B1, 1, 1); PG8_STAGE(PG8_SB(1, 0), b3, voffB);
;             PG8_BAR; PG8_WAIT_L(0); PG8_MMA(0, 1, At, B1); PG8_BAR;
	s_add_u32 s56, s12, 0x80000
	s_addc_u32 s57, s13, 0
	s_add_i32 s3, s36, s22
	v_lshl_add_u64 v[152:153], s[56:57], 0, v[132:133]
	s_mov_b32 m0, s3
	s_nop 0
	global_load_lds_dwordx4 v[152:153], off
	v_lshl_add_u64 v[152:153], s[56:57], 0, v[128:129]
	s_add_i32 m0, s3, 0x2000
	s_nop 0
	global_load_lds_dwordx4 v[152:153], off
	s_waitcnt vmcnt(6)
	s_barrier
	s_setprio 1
	v_mfma_f32_16x16x32_bf16 v[52:55], v[202:205], v[168:171], v[52:55]
	v_mfma_f32_16x16x32_bf16 v[48:51], v[210:213], v[168:171], v[48:51]
	v_mfma_f32_16x16x32_bf16 v[36:39], v[202:205], v[176:179], v[36:39]
	v_mfma_f32_16x16x32_bf16 v[32:35], v[210:213], v[176:179], v[32:35]
	v_mfma_f32_16x16x32_bf16 v[20:23], v[202:205], v[184:187], v[20:23]
	v_mfma_f32_16x16x32_bf16 v[16:19], v[210:213], v[184:187], v[16:19]
	v_mfma_f32_16x16x32_bf16 v[4:7], v[202:205], v[192:195], v[4:7]
	v_mfma_f32_16x16x32_bf16 v[0:3], v[210:213], v[192:195], v[0:3]
	v_mfma_f32_16x16x32_bf16 v[52:55], v[206:209], v[172:175], v[52:55]
	v_mfma_f32_16x16x32_bf16 v[48:51], v[214:217], v[172:175], v[48:51]
	v_mfma_f32_16x16x32_bf16 v[36:39], v[206:209], v[180:183], v[36:39]
	v_mfma_f32_16x16x32_bf16 v[32:35], v[214:217], v[180:183], v[32:35]
	v_mfma_f32_16x16x32_bf16 v[20:23], v[206:209], v[188:191], v[20:23]
	v_mfma_f32_16x16x32_bf16 v[16:19], v[214:217], v[188:191], v[16:19]
	v_mfma_f32_16x16x32_bf16 v[4:7], v[206:209], v[198:201], v[4:7]
	v_mfma_f32_16x16x32_bf16 v[0:3], v[214:217], v[198:201], v[0:3]
	s_setprio 0
	s_add_i32 s3, 0, 0x18000
	v_add_u32_e32 v164, s3, v148
	s_barrier
	ds_read_b128 v[152:155], v164
	ds_read_b128 v[156:159], v164 offset:1024
	ds_read_b128 v[160:163], v164 offset:2048
	ds_read_b128 v[164:167], v164 offset:3072
	s_add_u32 s14, s14, 0x80000
	s_addc_u32 s15, s15, 0
	s_mov_b32 m0, s25
	v_lshl_add_u64 v[202:203], s[14:15], 0, v[134:135]
	ds_read_b128 v[168:171], v150 offset:32768
	ds_read_b128 v[172:175], v150 offset:33792
	ds_read_b128 v[176:179], v150 offset:34816
	ds_read_b128 v[180:183], v150 offset:35840
	ds_read_b128 v[184:187], v150 offset:36864
	ds_read_b128 v[188:191], v150 offset:37888
	ds_read_b128 v[192:195], v150 offset:38912
	ds_read_b128 v[198:201], v150 offset:39936
	global_load_lds_dwordx4 v[202:203], off
	v_lshl_add_u64 v[202:203], s[14:15], 0, v[130:131]
	s_mov_b32 m0, s26
	s_nop 0
	global_load_lds_dwordx4 v[202:203], off
	s_waitcnt lgkmcnt(8)
	s_barrier
	s_setprio 1
	s_waitcnt lgkmcnt(7)
	v_mfma_f32_16x16x32_bf16 v[124:127], v[152:155], v[168:171], v[124:127]
	v_mfma_f32_16x16x32_bf16 v[120:123], v[160:163], v[168:171], v[120:123]
	s_waitcnt lgkmcnt(5)
	v_mfma_f32_16x16x32_bf16 v[108:111], v[152:155], v[176:179], v[108:111]
	v_mfma_f32_16x16x32_bf16 v[104:107], v[160:163], v[176:179], v[104:107]
	s_waitcnt lgkmcnt(3)
	v_mfma_f32_16x16x32_bf16 v[92:95], v[152:155], v[184:187], v[92:95]
	v_mfma_f32_16x16x32_bf16 v[88:91], v[160:163], v[184:187], v[88:91]
	s_waitcnt lgkmcnt(1)
	v_mfma_f32_16x16x32_bf16 v[76:79], v[152:155], v[192:195], v[76:79]
	v_mfma_f32_16x16x32_bf16 v[72:75], v[160:163], v[192:195], v[72:75]
	v_mfma_f32_16x16x32_bf16 v[124:127], v[156:159], v[172:175], v[124:127]
	v_mfma_f32_16x16x32_bf16 v[120:123], v[164:167], v[172:175], v[120:123]
	v_mfma_f32_16x16x32_bf16 v[108:111], v[156:159], v[180:183], v[108:111]
	v_mfma_f32_16x16x32_bf16 v[104:107], v[164:167], v[180:183], v[104:107]
	v_mfma_f32_16x16x32_bf16 v[92:95], v[156:159], v[188:191], v[92:95]
	v_mfma_f32_16x16x32_bf16 v[88:91], v[164:167], v[188:191], v[88:91]
	s_waitcnt lgkmcnt(0)
	v_mfma_f32_16x16x32_bf16 v[76:79], v[156:159], v[198:201], v[76:79]
	v_mfma_f32_16x16x32_bf16 v[72:75], v[164:167], v[198:201], v[72:75]
	s_setprio 0
	s_barrier
	s_add_i32 s14, 0, 0x1c000
	s_add_i32 s3, s3, s22
	v_add_u32_e32 v196, s14, v148
	v_lshl_add_u64 v[144:145], v[144:145], 0, s[44:45]
	s_mov_b32 m0, s3
	ds_read_b128 v[202:205], v196
	ds_read_b128 v[206:209], v196 offset:1024
	ds_read_b128 v[210:213], v196 offset:2048
	ds_read_b128 v[214:217], v196 offset:3072
	global_load_lds_dwordx4 v[144:145], off
	v_lshl_add_u64 v[144:145], v[218:219], 0, s[44:45]
	s_add_i32 m0, s3, 0x2000
	s_nop 0
	global_load_lds_dwordx4 v[144:145], off
	s_barrier
	s_setprio 1
	s_waitcnt lgkmcnt(3)
	v_mfma_f32_16x16x32_bf16 v[116:119], v[202:205], v[168:171], v[116:119]
	s_waitcnt lgkmcnt(1)
	v_mfma_f32_16x16x32_bf16 v[112:115], v[210:213], v[168:171], v[112:115]
	v_mfma_f32_16x16x32_bf16 v[100:103], v[202:205], v[176:179], v[100:103]
	v_mfma_f32_16x16x32_bf16 v[96:99], v[210:213], v[176:179], v[96:99]
	v_mfma_f32_16x16x32_bf16 v[84:87], v[202:205], v[184:187], v[84:87]
	v_mfma_f32_16x16x32_bf16 v[80:83], v[210:213], v[184:187], v[80:83]
	v_mfma_f32_16x16x32_bf16 v[68:71], v[202:205], v[192:195], v[68:71]
	v_mfma_f32_16x16x32_bf16 v[64:67], v[210:213], v[192:195], v[64:67]
	v_mfma_f32_16x16x32_bf16 v[116:119], v[206:209], v[172:175], v[116:119]
	s_waitcnt lgkmcnt(0)
	v_mfma_f32_16x16x32_bf16 v[112:115], v[214:217], v[172:175], v[112:115]
	v_mfma_f32_16x16x32_bf16 v[100:103], v[206:209], v[180:183], v[100:103]
	v_mfma_f32_16x16x32_bf16 v[96:99], v[214:217], v[180:183], v[96:99]
	v_mfma_f32_16x16x32_bf16 v[84:87], v[206:209], v[188:191], v[84:87]
	v_mfma_f32_16x16x32_bf16 v[80:83], v[214:217], v[188:191], v[80:83]
	v_mfma_f32_16x16x32_bf16 v[68:71], v[206:209], v[198:201], v[68:71]
	v_mfma_f32_16x16x32_bf16 v[64:67], v[214:217], v[198:201], v[64:67]
	s_setprio 0
	s_mov_b32 m0, s30
	v_lshl_add_u64 v[144:145], v[220:221], 0, s[44:45]
	s_barrier
; DI unsigned pack2(float a, float b) { f32x2 v = {a, b}; hwbf16x2 r = __builtin_convertvector(v, hwbf16x2); return __builtin_bit_cast(unsigned, r); }
; DI float bflo(unsigned w) { return __uint_as_float(w << 16); }
; DI float bfhi(unsigned w) { return __uint_as_float(w & 0xffff0000u); }
; #define PG8_STAGE(bufoff, gbase, voff) do { _Pragma("unroll") for (int _i = 0; _i < 2; ++_i) \
;         __builtin_amdgcn_global_load_lds((const unsigned*)((const char*)(gbase) + (voff)[_i]), (LAS unsigned*)(lds + (bufoff) + ldsw + _i * 8192), 16, 0, 0); } while (0)
; #define PG8_WAIT_V(n) asm volatile("s_waitcnt vmcnt(" #n ")" ::: "memory")
;     DI void operator()(const f32x4 (&acc)[2][2][4][2], const Unit& u, int wr, int wc, int fr, int fq) const {
;     ...
;         for (int ai = 0; ai < 2; ++ai)
; #pragma unroll
;             for (int m = 0; m < 4; ++m) { const size_t ro = (size_t)(row0 + ai * HALF + m * 16) * D + col0;
; #pragma unroll
;                 for (int bj = 0; bj < 2; ++bj) {
;                     f32x4 x0, x1;
;                     if constexpr (IB) { const u32x4 w = *(const u32x4*)((const bf16_t*)Xin + ro + bj * HALF);
;                         x0 = (f32x4){bflo(w[0]), bfhi(w[0]), bflo(w[1]), bfhi(w[1])}; x1 = (f32x4){bflo(w[2]), bfhi(w[2]), bflo(w[3]), bfhi(w[3])}; }
;                     else { x0 = *(const f32x4*)((const float*)Xin + ro + bj * HALF); x1 = *(const f32x4*)((const float*)Xin + ro + bj * HALF + 4); }
;                     x0 += acc[ai][bj][m][0] * sc[bj][0]; x1 += acc[ai][bj][m][1] * sc[bj][1];
;                     if constexpr (OB) { u32x4 o; o[0] = pack2(x0[0], x0[1]); o[1] = pack2(x0[2], x0[3]); o[2] = pack2(x1[0], x1[1]); o[3] = pack2(x1[2], x1[3]);
;                         *(u32x4*)((bf16_t*)Xout + ro + bj * HALF) = o; }
;                     else { *(f32x4*)((float*)Xout + ro + bj * HALF) = x0; *(f32x4*)((float*)Xout + ro + bj * HALF + 4) = x1; } } }
; template <class Map, class Epi>
; DI void gemm_phase(LAS unsigned char* lds, const Map& MP, const Epi& E, const int nM, const int nN, const int K, const int lda, const int ldb) {
;     ...
;             PG8_LDA(At, 1, 1); PG8_STAGE(PG8_SA(1, 0), a3, voffA);
;             PG8_BAR; PG8_WAIT_L(0); PG8_MMA(1, 0, At, B0); PG8_BAR; PG8_SCHED;
;             PG8_STAGE(PG8_SB(1, 1), b3 + hstepB, voffB);
;             PG8_WAIT_V(6); PG8_BAR; PG8_MMA(1, 1, At, B1); PG8_BAR;
	ds_read_b128 v[168:171], v150 offset:49152
	ds_read_b128 v[172:175], v150 offset:50176
	ds_read_b128 v[176:179], v150 offset:51200
	ds_read_b128 v[180:183], v150 offset:52224
	ds_read_b128 v[184:187], v150 offset:53248
	ds_read_b128 v[188:191], v150 offset:54272
	ds_read_b128 v[192:195], v150 offset:55296
	ds_read_b128 v[198:201], v150 offset:56320
	global_load_lds_dwordx4 v[144:145], off
	v_lshl_add_u64 v[144:145], v[222:223], 0, s[44:45]
	s_mov_b32 m0, s31
	s_nop 0
	global_load_lds_dwordx4 v[144:145], off
	s_barrier
	s_setprio 1
	s_waitcnt lgkmcnt(7)
	v_mfma_f32_16x16x32_bf16 v[60:63], v[152:155], v[168:171], v[60:63]
	v_mfma_f32_16x16x32_bf16 v[56:59], v[160:163], v[168:171], v[56:59]
	s_waitcnt lgkmcnt(5)
	v_mfma_f32_16x16x32_bf16 v[44:47], v[152:155], v[176:179], v[44:47]
	v_mfma_f32_16x16x32_bf16 v[40:43], v[160:163], v[176:179], v[40:43]
	s_waitcnt lgkmcnt(3)
	v_mfma_f32_16x16x32_bf16 v[28:31], v[152:155], v[184:187], v[28:31]
	v_mfma_f32_16x16x32_bf16 v[24:27], v[160:163], v[184:187], v[24:27]
	s_waitcnt lgkmcnt(1)
	v_mfma_f32_16x16x32_bf16 v[12:15], v[152:155], v[192:195], v[12:15]
	v_mfma_f32_16x16x32_bf16 v[8:11], v[160:163], v[192:195], v[8:11]
	v_mfma_f32_16x16x32_bf16 v[60:63], v[156:159], v[172:175], v[60:63]
	v_mfma_f32_16x16x32_bf16 v[56:59], v[164:167], v[172:175], v[56:59]
	v_mfma_f32_16x16x32_bf16 v[44:47], v[156:159], v[180:183], v[44:47]
	v_mfma_f32_16x16x32_bf16 v[40:43], v[164:167], v[180:183], v[40:43]
	v_mfma_f32_16x16x32_bf16 v[28:31], v[156:159], v[188:191], v[28:31]
	v_mfma_f32_16x16x32_bf16 v[24:27], v[164:167], v[188:191], v[24:27]
	s_waitcnt lgkmcnt(0)
	v_mfma_f32_16x16x32_bf16 v[12:15], v[156:159], v[198:201], v[12:15]
	v_mfma_f32_16x16x32_bf16 v[8:11], v[164:167], v[198:201], v[8:11]
	s_setprio 0
	s_barrier
	s_add_u32 s12, s12, 0x80080
	s_addc_u32 s13, s13, 0
	s_add_i32 s3, s14, s22
	v_lshl_add_u64 v[144:145], s[12:13], 0, v[132:133]
	s_mov_b32 m0, s3
	s_nop 0
	global_load_lds_dwordx4 v[144:145], off
	v_lshl_add_u64 v[144:145], s[12:13], 0, v[128:129]
	s_add_i32 m0, s3, 0x2000
	s_nop 0
	global_load_lds_dwordx4 v[144:145], off
	s_waitcnt vmcnt(6)
	s_barrier
	s_setprio 1
	v_mfma_f32_16x16x32_bf16 v[52:55], v[202:205], v[168:171], v[52:55]
	v_mfma_f32_16x16x32_bf16 v[48:51], v[210:213], v[168:171], v[48:51]
	v_mfma_f32_16x16x32_bf16 v[36:39], v[202:205], v[176:179], v[36:39]
	v_mfma_f32_16x16x32_bf16 v[32:35], v[210:213], v[176:179], v[32:35]
	v_mfma_f32_16x16x32_bf16 v[20:23], v[202:205], v[184:187], v[20:23]
	v_mfma_f32_16x16x32_bf16 v[16:19], v[210:213], v[184:187], v[16:19]
	v_mfma_f32_16x16x32_bf16 v[4:7], v[202:205], v[192:195], v[4:7]
	v_mfma_f32_16x16x32_bf16 v[0:3], v[210:213], v[192:195], v[0:3]
	v_mfma_f32_16x16x32_bf16 v[52:55], v[206:209], v[172:175], v[52:55]
	v_mfma_f32_16x16x32_bf16 v[48:51], v[214:217], v[172:175], v[48:51]
	v_mfma_f32_16x16x32_bf16 v[36:39], v[206:209], v[180:183], v[36:39]
	v_mfma_f32_16x16x32_bf16 v[32:35], v[214:217], v[180:183], v[32:35]
	v_mfma_f32_16x16x32_bf16 v[20:23], v[206:209], v[188:191], v[20:23]
	v_mfma_f32_16x16x32_bf16 v[16:19], v[214:217], v[188:191], v[16:19]
	v_mfma_f32_16x16x32_bf16 v[4:7], v[206:209], v[198:201], v[4:7]
	v_mfma_f32_16x16x32_bf16 v[0:3], v[214:217], v[198:201], v[0:3]
	s_setprio 0
	s_add_i32 s48, s48, 2
	s_add_u32 s39, s39, 0x100
	s_addc_u32 s47, s47, 0
	s_add_u32 s10, s10, 0x100
	s_addc_u32 s11, s11, 0
	s_cmp_gt_u32 s48, 29
	s_barrier
	s_cbranch_scc0 .LBB1_925
	v_mov_b32_e32 v152, v147
	v_mov_b32_e32 v144, v146
	s_lshl_b32 s2, s2, 8
	s_or_b32 s2, s2, s29
	v_lshl_add_u32 v144, v144, 3, s2
	s_lshl_b32 s2, s8, 8
	s_add_i32 s2, s2, s28
	v_add_u32_e32 v152, s2, v152
	v_ashrrev_i32_e32 v153, 31, v152
	v_lshlrev_b64 v[152:153], 12, v[152:153]
	v_ashrrev_i32_e32 v145, 31, v144
	v_lshl_add_u64 v[152:153], s[42:43], 0, v[152:153]
	v_lshl_add_u64 v[144:145], v[144:145], 1, v[152:153]
	global_load_dwordx4 v[152:155], v[144:145], off
	s_mov_b64 s[2:3], 0x10000
	s_mov_b32 s8, s52
	s_mov_b64 s[10:11], s[6:7]
	s_mov_b64 s[12:13], s[54:55]
	s_waitcnt vmcnt(0) lgkmcnt(0)
	v_lshlrev_b32_e32 v156, 16, v152
	v_and_b32_e32 v157, 0xffff0000, v152
	v_lshlrev_b32_e32 v152, 16, v153
	v_and_b32_e32 v153, 0xffff0000, v153
	v_lshlrev_b32_e32 v158, 16, v154
	v_and_b32_e32 v159, 0xffff0000, v154
	v_lshlrev_b32_e32 v154, 16, v155
	v_and_b32_e32 v155, 0xffff0000, v155
	v_pk_add_f32 v[126:127], v[126:127], v[152:153]
	v_pk_add_f32 v[124:125], v[124:125], v[156:157]
	v_pk_add_f32 v[152:153], v[122:123], v[154:155]
	v_pk_add_f32 v[122:123], v[120:121], v[158:159]
	v_cvt_pk_bf16_f32 v120, v124, v125
	v_cvt_pk_bf16_f32 v121, v126, v127
	v_cvt_pk_bf16_f32 v122, v122, v123
	v_cvt_pk_bf16_f32 v123, v152, v153
	global_store_dwordx4 v[144:145], v[120:123], off
	global_load_dwordx4 v[120:123], v[144:145], off offset:256
	s_waitcnt vmcnt(0) lgkmcnt(0)
	v_lshlrev_b32_e32 v124, 16, v120
	v_and_b32_e32 v125, 0xffff0000, v120
	v_lshlrev_b32_e32 v120, 16, v121
	v_and_b32_e32 v121, 0xffff0000, v121
	v_lshlrev_b32_e32 v126, 16, v122
	v_and_b32_e32 v127, 0xffff0000, v122
	v_lshlrev_b32_e32 v122, 16, v123
	v_and_b32_e32 v123, 0xffff0000, v123
	v_pk_add_f32 v[116:117], v[116:117], v[124:125]
	v_pk_add_f32 v[118:119], v[118:119], v[120:121]
	v_pk_add_f32 v[120:121], v[114:115], v[122:123]
	v_pk_add_f32 v[114:115], v[112:113], v[126:127]
	v_cvt_pk_bf16_f32 v112, v116, v117
	v_lshl_add_u64 v[116:117], v[144:145], 0, s[2:3]
	s_mov_b32 s2, 0x10000
	v_cvt_pk_bf16_f32 v113, v118, v119
	v_add_co_u32_e32 v118, vcc, s2, v144
	v_cvt_pk_bf16_f32 v114, v114, v115
	v_cvt_pk_bf16_f32 v115, v120, v121
	v_addc_co_u32_e32 v119, vcc, 0, v145, vcc
	global_store_dwordx4 v[144:145], v[112:115], off offset:256
	global_load_dwordx4 v[112:115], v[118:119], off
	s_mov_b64 s[2:3], 0x20000
	s_waitcnt vmcnt(0) lgkmcnt(0)
; DI unsigned pack2(float a, float b) { f32x2 v = {a, b}; hwbf16x2 r = __builtin_convertvector(v, hwbf16x2); return __builtin_bit_cast(unsigned, r); }
; DI float bflo(unsigned w) { return __uint_as_float(w << 16); }
; DI float bfhi(unsigned w) { return __uint_as_float(w & 0xffff0000u); }
;     DI void operator()(const f32x4 (&acc)[2][2][4][2], const Unit& u, int wr, int wc, int fr, int fq) const {
;     ...
;         for (int ai = 0; ai < 2; ++ai)
; #pragma unroll
;             for (int m = 0; m < 4; ++m) { const size_t ro = (size_t)(row0 + ai * HALF + m * 16) * D + col0;
; #pragma unroll
;                 for (int bj = 0; bj < 2; ++bj) {
;                     f32x4 x0, x1;
;                     if constexpr (IB) { const u32x4 w = *(const u32x4*)((const bf16_t*)Xin + ro + bj * HALF);
;                         x0 = (f32x4){bflo(w[0]), bfhi(w[0]), bflo(w[1]), bfhi(w[1])}; x1 = (f32x4){bflo(w[2]), bfhi(w[2]), bflo(w[3]), bfhi(w[3])}; }
;                     else { x0 = *(const f32x4*)((const float*)Xin + ro + bj * HALF); x1 = *(const f32x4*)((const float*)Xin + ro + bj * HALF + 4); }
;                     x0 += acc[ai][bj][m][0] * sc[bj][0]; x1 += acc[ai][bj][m][1] * sc[bj][1];
;                     if constexpr (OB) { u32x4 o; o[0] = pack2(x0[0], x0[1]); o[1] = pack2(x0[2], x0[3]); o[2] = pack2(x1[0], x1[1]); o[3] = pack2(x1[2], x1[3]);
;                         *(u32x4*)((bf16_t*)Xout + ro + bj * HALF) = o; }
;                     else { *(f32x4*)((float*)Xout + ro + bj * HALF) = x0; *(f32x4*)((float*)Xout + ro + bj * HALF + 4) = x1; } } }
	v_lshlrev_b32_e32 v120, 16, v112
	v_and_b32_e32 v121, 0xffff0000, v112
	v_lshlrev_b32_e32 v112, 16, v113
	v_and_b32_e32 v113, 0xffff0000, v113
	v_lshlrev_b32_e32 v122, 16, v114
	v_and_b32_e32 v123, 0xffff0000, v114
	v_lshlrev_b32_e32 v114, 16, v115
	v_and_b32_e32 v115, 0xffff0000, v115
	v_pk_add_f32 v[110:111], v[110:111], v[112:113]
	v_pk_add_f32 v[108:109], v[108:109], v[120:121]
	v_pk_add_f32 v[112:113], v[106:107], v[114:115]
	v_pk_add_f32 v[106:107], v[104:105], v[122:123]
	v_cvt_pk_bf16_f32 v104, v108, v109
	v_cvt_pk_bf16_f32 v105, v110, v111
	v_cvt_pk_bf16_f32 v106, v106, v107
	v_cvt_pk_bf16_f32 v107, v112, v113
	global_store_dwordx4 v[118:119], v[104:107], off
	global_load_dwordx4 v[104:107], v[116:117], off offset:256
	s_waitcnt vmcnt(0) lgkmcnt(0)
	v_lshlrev_b32_e32 v108, 16, v104
	v_and_b32_e32 v109, 0xffff0000, v104
	v_lshlrev_b32_e32 v104, 16, v105
	v_and_b32_e32 v105, 0xffff0000, v105
	v_lshlrev_b32_e32 v110, 16, v106
	v_and_b32_e32 v111, 0xffff0000, v106
	v_lshlrev_b32_e32 v106, 16, v107
	v_and_b32_e32 v107, 0xffff0000, v107
	v_pk_add_f32 v[100:101], v[100:101], v[108:109]
	v_pk_add_f32 v[102:103], v[102:103], v[104:105]
	v_pk_add_f32 v[104:105], v[98:99], v[106:107]
	v_pk_add_f32 v[98:99], v[96:97], v[110:111]
	v_cvt_pk_bf16_f32 v96, v100, v101
	v_lshl_add_u64 v[100:101], v[144:145], 0, s[2:3]
	s_mov_b32 s2, 0x20000
	v_cvt_pk_bf16_f32 v97, v102, v103
	v_add_co_u32_e32 v102, vcc, s2, v144
	v_cvt_pk_bf16_f32 v98, v98, v99
	v_cvt_pk_bf16_f32 v99, v104, v105
	v_addc_co_u32_e32 v103, vcc, 0, v145, vcc
	global_store_dwordx4 v[116:117], v[96:99], off offset:256
	global_load_dwordx4 v[96:99], v[102:103], off
	s_mov_b64 s[2:3], 0x30000
	s_waitcnt vmcnt(0) lgkmcnt(0)
	v_lshlrev_b32_e32 v104, 16, v96
	v_and_b32_e32 v105, 0xffff0000, v96
	v_lshlrev_b32_e32 v96, 16, v97
	v_and_b32_e32 v97, 0xffff0000, v97
	v_lshlrev_b32_e32 v106, 16, v98
	v_and_b32_e32 v107, 0xffff0000, v98
	v_lshlrev_b32_e32 v98, 16, v99
	v_and_b32_e32 v99, 0xffff0000, v99
	v_pk_add_f32 v[94:95], v[94:95], v[96:97]
	v_pk_add_f32 v[92:93], v[92:93], v[104:105]
	v_pk_add_f32 v[96:97], v[90:91], v[98:99]
	v_pk_add_f32 v[90:91], v[88:89], v[106:107]
	v_cvt_pk_bf16_f32 v88, v92, v93
	v_cvt_pk_bf16_f32 v89, v94, v95
	v_cvt_pk_bf16_f32 v90, v90, v91
	v_cvt_pk_bf16_f32 v91, v96, v97
	global_store_dwordx4 v[102:103], v[88:91], off
	global_load_dwordx4 v[88:91], v[100:101], off offset:256
	s_waitcnt vmcnt(0) lgkmcnt(0)
	v_lshlrev_b32_e32 v92, 16, v88
	v_and_b32_e32 v93, 0xffff0000, v88
	v_lshlrev_b32_e32 v88, 16, v89
	v_and_b32_e32 v89, 0xffff0000, v89
	v_lshlrev_b32_e32 v94, 16, v90
	v_and_b32_e32 v95, 0xffff0000, v90
	v_lshlrev_b32_e32 v90, 16, v91
	v_and_b32_e32 v91, 0xffff0000, v91
	v_pk_add_f32 v[86:87], v[86:87], v[88:89]
	v_pk_add_f32 v[84:85], v[84:85], v[92:93]
	v_pk_add_f32 v[88:89], v[82:83], v[90:91]
	v_pk_add_f32 v[82:83], v[80:81], v[94:95]
	v_cvt_pk_bf16_f32 v80, v84, v85
	v_cvt_pk_bf16_f32 v81, v86, v87
	v_cvt_pk_bf16_f32 v82, v82, v83
	v_cvt_pk_bf16_f32 v83, v88, v89
	global_store_dwordx4 v[100:101], v[80:83], off offset:256
	s_nop 1
	v_lshl_add_u64 v[80:81], v[144:145], 0, s[2:3]
	s_mov_b32 s2, 0x30000
	v_add_co_u32_e32 v86, vcc, s2, v144
	s_mov_b64 s[2:3], 0x80000
	s_nop 0
	v_addc_co_u32_e32 v87, vcc, 0, v145, vcc
	global_load_dwordx4 v[82:85], v[86:87], off
	s_waitcnt vmcnt(0) lgkmcnt(0)
	v_lshlrev_b32_e32 v88, 16, v82
	v_and_b32_e32 v89, 0xffff0000, v82
	v_lshlrev_b32_e32 v82, 16, v83
	v_and_b32_e32 v83, 0xffff0000, v83
	v_lshlrev_b32_e32 v90, 16, v84
	v_and_b32_e32 v91, 0xffff0000, v84
	v_lshlrev_b32_e32 v84, 16, v85
	v_and_b32_e32 v85, 0xffff0000, v85
	v_pk_add_f32 v[78:79], v[78:79], v[82:83]
	v_pk_add_f32 v[76:77], v[76:77], v[88:89]
	v_pk_add_f32 v[82:83], v[74:75], v[84:85]
	v_pk_add_f32 v[74:75], v[72:73], v[90:91]
	v_cvt_pk_bf16_f32 v72, v76, v77
	v_cvt_pk_bf16_f32 v73, v78, v79
	v_cvt_pk_bf16_f32 v74, v74, v75
	v_cvt_pk_bf16_f32 v75, v82, v83
	global_store_dwordx4 v[86:87], v[72:75], off
	global_load_dwordx4 v[72:75], v[80:81], off offset:256
	s_waitcnt vmcnt(0) lgkmcnt(0)
	v_lshlrev_b32_e32 v76, 16, v72
	v_and_b32_e32 v77, 0xffff0000, v72
	v_lshlrev_b32_e32 v72, 16, v73
	v_and_b32_e32 v73, 0xffff0000, v73
	v_lshlrev_b32_e32 v78, 16, v74
	v_and_b32_e32 v79, 0xffff0000, v74
	v_lshlrev_b32_e32 v74, 16, v75
	v_and_b32_e32 v75, 0xffff0000, v75
	v_pk_add_f32 v[70:71], v[70:71], v[72:73]
	v_pk_add_f32 v[68:69], v[68:69], v[76:77]
	v_pk_add_f32 v[72:73], v[66:67], v[74:75]
	v_pk_add_f32 v[66:67], v[64:65], v[78:79]
	v_cvt_pk_bf16_f32 v64, v68, v69
	v_cvt_pk_bf16_f32 v65, v70, v71
	v_cvt_pk_bf16_f32 v66, v66, v67
	v_cvt_pk_bf16_f32 v67, v72, v73
	global_store_dwordx4 v[80:81], v[64:67], off offset:256
	s_nop 1
	v_lshl_add_u64 v[64:65], v[144:145], 0, s[2:3]
	s_mov_b32 s2, 0x80000
	v_add_co_u32_e32 v70, vcc, s2, v144
	s_mov_b64 s[2:3], 0x90000
	s_nop 0
	v_addc_co_u32_e32 v71, vcc, 0, v145, vcc
	global_load_dwordx4 v[66:69], v[70:71], off
	s_waitcnt vmcnt(0) lgkmcnt(0)
	v_lshlrev_b32_e32 v72, 16, v66
	v_and_b32_e32 v73, 0xffff0000, v66
	v_lshlrev_b32_e32 v66, 16, v67
	v_and_b32_e32 v67, 0xffff0000, v67
	v_lshlrev_b32_e32 v74, 16, v68
	v_and_b32_e32 v75, 0xffff0000, v68
	v_lshlrev_b32_e32 v68, 16, v69
	v_and_b32_e32 v69, 0xffff0000, v69
	v_pk_add_f32 v[62:63], v[62:63], v[66:67]
	v_pk_add_f32 v[60:61], v[60:61], v[72:73]
	v_pk_add_f32 v[66:67], v[58:59], v[68:69]
	v_pk_add_f32 v[58:59], v[56:57], v[74:75]
	v_cvt_pk_bf16_f32 v56, v60, v61
	v_cvt_pk_bf16_f32 v57, v62, v63
	v_cvt_pk_bf16_f32 v58, v58, v59
	v_cvt_pk_bf16_f32 v59, v66, v67
	global_store_dwordx4 v[70:71], v[56:59], off
	global_load_dwordx4 v[56:59], v[64:65], off offset:256
	s_waitcnt vmcnt(0) lgkmcnt(0)
; DI unsigned pack2(float a, float b) { f32x2 v = {a, b}; hwbf16x2 r = __builtin_convertvector(v, hwbf16x2); return __builtin_bit_cast(unsigned, r); }
; DI float bflo(unsigned w) { return __uint_as_float(w << 16); }
; DI float bfhi(unsigned w) { return __uint_as_float(w & 0xffff0000u); }
;     DI const char* a(const Unit& u) const { return (const char*)(A + (size_t)u.pm * BM * lda); }
;     DI const char* a(const Unit& u) const { return (const char*)(A + (size_t)u.pm * BM * 2048 + (u.pn >> 1) * 512); }
;     DI void operator()(const f32x4 (&acc)[2][2][4][2], const Unit& u, int wr, int wc, int fr, int fq) const {
;     ...
;         for (int ai = 0; ai < 2; ++ai)
; #pragma unroll
;             for (int m = 0; m < 4; ++m) { const size_t ro = (size_t)(row0 + ai * HALF + m * 16) * D + col0;
; #pragma unroll
;                 for (int bj = 0; bj < 2; ++bj) {
;                     f32x4 x0, x1;
;                     if constexpr (IB) { const u32x4 w = *(const u32x4*)((const bf16_t*)Xin + ro + bj * HALF);
;                         x0 = (f32x4){bflo(w[0]), bfhi(w[0]), bflo(w[1]), bfhi(w[1])}; x1 = (f32x4){bflo(w[2]), bfhi(w[2]), bflo(w[3]), bfhi(w[3])}; }
;                     else { x0 = *(const f32x4*)((const float*)Xin + ro + bj * HALF); x1 = *(const f32x4*)((const float*)Xin + ro + bj * HALF + 4); }
;                     x0 += acc[ai][bj][m][0] * sc[bj][0]; x1 += acc[ai][bj][m][1] * sc[bj][1];
;                     if constexpr (OB) { u32x4 o; o[0] = pack2(x0[0], x0[1]); o[1] = pack2(x0[2], x0[3]); o[2] = pack2(x1[0], x1[1]); o[3] = pack2(x1[2], x1[3]);
;                         *(u32x4*)((bf16_t*)Xout + ro + bj * HALF) = o; }
;                     else { *(f32x4*)((float*)Xout + ro + bj * HALF) = x0; *(f32x4*)((float*)Xout + ro + bj * HALF + 4) = x1; } } }
; template <class Map, class Epi>
; DI void gemm_phase(LAS unsigned char* lds, const Map& MP, const Epi& E, const int nM, const int nN, const int K, const int lda, const int ldb) {
;     ...
;         if (!has_next) break;
; #pragma unroll
;         for (int a = 0; a < 2; ++a)
; #pragma unroll
;             for (int b = 0; b < 2; ++b)
; #pragma unroll
;                 for (int m = 0; m < 4; ++m)
; #pragma unroll
;                     for (int n = 0; n < 2; ++n) acc[a][b][m][n] = (f32x4){0.f, 0.f, 0.f, 0.f};
;         cur = nxt; cA = nA; cB = nB; ++ui;
;     }
;     PG8_WAIT_V(0);
;     if (wr == 0) PG8_BAR;
;     PG8_BAR;
	v_lshlrev_b32_e32 v60, 16, v56
	v_and_b32_e32 v61, 0xffff0000, v56
	v_lshlrev_b32_e32 v56, 16, v57
	v_and_b32_e32 v57, 0xffff0000, v57
	v_lshlrev_b32_e32 v62, 16, v58
	v_and_b32_e32 v63, 0xffff0000, v58
	v_lshlrev_b32_e32 v58, 16, v59
	v_and_b32_e32 v59, 0xffff0000, v59
	v_pk_add_f32 v[54:55], v[54:55], v[56:57]
	v_pk_add_f32 v[52:53], v[52:53], v[60:61]
	v_pk_add_f32 v[56:57], v[50:51], v[58:59]
	v_pk_add_f32 v[50:51], v[48:49], v[62:63]
	v_cvt_pk_bf16_f32 v48, v52, v53
	v_cvt_pk_bf16_f32 v49, v54, v55
	v_cvt_pk_bf16_f32 v50, v50, v51
	v_cvt_pk_bf16_f32 v51, v56, v57
	global_store_dwordx4 v[64:65], v[48:51], off offset:256
	s_nop 1
	v_lshl_add_u64 v[48:49], v[144:145], 0, s[2:3]
	s_mov_b32 s2, 0x90000
	v_add_co_u32_e32 v54, vcc, s2, v144
	s_mov_b64 s[2:3], 0xa0000
	s_nop 0
	v_addc_co_u32_e32 v55, vcc, 0, v145, vcc
	global_load_dwordx4 v[50:53], v[54:55], off
	s_waitcnt vmcnt(0) lgkmcnt(0)
	v_lshlrev_b32_e32 v56, 16, v50
	v_and_b32_e32 v57, 0xffff0000, v50
	v_lshlrev_b32_e32 v50, 16, v51
	v_and_b32_e32 v51, 0xffff0000, v51
	v_lshlrev_b32_e32 v58, 16, v52
	v_and_b32_e32 v59, 0xffff0000, v52
	v_lshlrev_b32_e32 v52, 16, v53
	v_and_b32_e32 v53, 0xffff0000, v53
	v_pk_add_f32 v[46:47], v[46:47], v[50:51]
	v_pk_add_f32 v[44:45], v[44:45], v[56:57]
	v_pk_add_f32 v[50:51], v[42:43], v[52:53]
	v_pk_add_f32 v[42:43], v[40:41], v[58:59]
	v_cvt_pk_bf16_f32 v40, v44, v45
	v_cvt_pk_bf16_f32 v41, v46, v47
	v_cvt_pk_bf16_f32 v42, v42, v43
	v_cvt_pk_bf16_f32 v43, v50, v51
	global_store_dwordx4 v[54:55], v[40:43], off
	global_load_dwordx4 v[40:43], v[48:49], off offset:256
	s_waitcnt vmcnt(0) lgkmcnt(0)
	v_lshlrev_b32_e32 v44, 16, v40
	v_and_b32_e32 v45, 0xffff0000, v40
	v_lshlrev_b32_e32 v40, 16, v41
	v_and_b32_e32 v41, 0xffff0000, v41
	v_lshlrev_b32_e32 v46, 16, v42
	v_and_b32_e32 v47, 0xffff0000, v42
	v_lshlrev_b32_e32 v42, 16, v43
	v_and_b32_e32 v43, 0xffff0000, v43
	v_pk_add_f32 v[38:39], v[38:39], v[40:41]
	v_pk_add_f32 v[36:37], v[36:37], v[44:45]
	v_pk_add_f32 v[40:41], v[34:35], v[42:43]
	v_pk_add_f32 v[34:35], v[32:33], v[46:47]
	v_cvt_pk_bf16_f32 v32, v36, v37
	v_cvt_pk_bf16_f32 v33, v38, v39
	v_cvt_pk_bf16_f32 v34, v34, v35
	v_cvt_pk_bf16_f32 v35, v40, v41
	global_store_dwordx4 v[48:49], v[32:35], off offset:256
	s_nop 1
	v_lshl_add_u64 v[32:33], v[144:145], 0, s[2:3]
	s_mov_b32 s2, 0xa0000
	v_add_co_u32_e32 v38, vcc, s2, v144
	s_mov_b64 s[2:3], 0xb0000
	s_nop 0
	v_addc_co_u32_e32 v39, vcc, 0, v145, vcc
	global_load_dwordx4 v[34:37], v[38:39], off
	s_waitcnt vmcnt(0) lgkmcnt(0)
	v_lshlrev_b32_e32 v40, 16, v34
	v_and_b32_e32 v41, 0xffff0000, v34
	v_lshlrev_b32_e32 v34, 16, v35
	v_and_b32_e32 v35, 0xffff0000, v35
	v_lshlrev_b32_e32 v42, 16, v36
	v_and_b32_e32 v43, 0xffff0000, v36
	v_lshlrev_b32_e32 v36, 16, v37
	v_and_b32_e32 v37, 0xffff0000, v37
	v_pk_add_f32 v[30:31], v[30:31], v[34:35]
	v_pk_add_f32 v[28:29], v[28:29], v[40:41]
	v_pk_add_f32 v[34:35], v[26:27], v[36:37]
	v_pk_add_f32 v[26:27], v[24:25], v[42:43]
	v_cvt_pk_bf16_f32 v24, v28, v29
	v_cvt_pk_bf16_f32 v25, v30, v31
	v_cvt_pk_bf16_f32 v26, v26, v27
	v_cvt_pk_bf16_f32 v27, v34, v35
	global_store_dwordx4 v[38:39], v[24:27], off
	global_load_dwordx4 v[24:27], v[32:33], off offset:256
	s_waitcnt vmcnt(0) lgkmcnt(0)
	v_lshlrev_b32_e32 v28, 16, v24
	v_and_b32_e32 v29, 0xffff0000, v24
	v_lshlrev_b32_e32 v24, 16, v25
	v_and_b32_e32 v25, 0xffff0000, v25
	v_lshlrev_b32_e32 v30, 16, v26
	v_and_b32_e32 v31, 0xffff0000, v26
	v_lshlrev_b32_e32 v26, 16, v27
	v_and_b32_e32 v27, 0xffff0000, v27
	v_pk_add_f32 v[22:23], v[22:23], v[24:25]
	v_pk_add_f32 v[20:21], v[20:21], v[28:29]
	v_pk_add_f32 v[24:25], v[18:19], v[26:27]
	v_pk_add_f32 v[18:19], v[16:17], v[30:31]
	v_cvt_pk_bf16_f32 v16, v20, v21
	v_cvt_pk_bf16_f32 v17, v22, v23
	v_cvt_pk_bf16_f32 v18, v18, v19
	v_cvt_pk_bf16_f32 v19, v24, v25
	global_store_dwordx4 v[32:33], v[16:19], off offset:256
	s_nop 1
	v_lshl_add_u64 v[16:17], v[144:145], 0, s[2:3]
	s_mov_b32 s2, 0xb0000
	v_add_co_u32_e32 v22, vcc, s2, v144
	s_mov_b32 s2, s46
	s_nop 0
	v_addc_co_u32_e32 v23, vcc, 0, v145, vcc
	global_load_dwordx4 v[18:21], v[22:23], off
	s_and_b64 vcc, exec, s[40:41]
	s_waitcnt vmcnt(0) lgkmcnt(0)
	v_lshlrev_b32_e32 v24, 16, v18
	v_and_b32_e32 v25, 0xffff0000, v18
	v_lshlrev_b32_e32 v18, 16, v19
	v_and_b32_e32 v19, 0xffff0000, v19
	v_lshlrev_b32_e32 v26, 16, v20
	v_and_b32_e32 v27, 0xffff0000, v20
	v_lshlrev_b32_e32 v20, 16, v21
	v_and_b32_e32 v21, 0xffff0000, v21
	v_pk_add_f32 v[14:15], v[14:15], v[18:19]
	v_pk_add_f32 v[12:13], v[12:13], v[24:25]
	v_pk_add_f32 v[18:19], v[10:11], v[20:21]
	v_pk_add_f32 v[10:11], v[8:9], v[26:27]
	v_cvt_pk_bf16_f32 v8, v12, v13
	v_cvt_pk_bf16_f32 v9, v14, v15
	v_cvt_pk_bf16_f32 v10, v10, v11
	v_cvt_pk_bf16_f32 v11, v18, v19
	global_store_dwordx4 v[22:23], v[8:11], off
	global_load_dwordx4 v[8:11], v[16:17], off offset:256
	s_waitcnt vmcnt(0) lgkmcnt(0)
	v_lshlrev_b32_e32 v12, 16, v8
	v_and_b32_e32 v13, 0xffff0000, v8
	v_lshlrev_b32_e32 v8, 16, v9
	v_and_b32_e32 v9, 0xffff0000, v9
	v_lshlrev_b32_e32 v14, 16, v10
	v_and_b32_e32 v15, 0xffff0000, v10
	v_lshlrev_b32_e32 v10, 16, v11
	v_and_b32_e32 v11, 0xffff0000, v11
	v_pk_add_f32 v[6:7], v[6:7], v[8:9]
	v_pk_add_f32 v[4:5], v[4:5], v[12:13]
	v_pk_add_f32 v[8:9], v[2:3], v[10:11]
	v_pk_add_f32 v[2:3], v[0:1], v[14:15]
	v_cvt_pk_bf16_f32 v0, v4, v5
	v_cvt_pk_bf16_f32 v1, v6, v7
	v_cvt_pk_bf16_f32 v2, v2, v3
	v_cvt_pk_bf16_f32 v3, v8, v9
	global_store_dwordx4 v[16:17], v[0:3], off offset:256
	s_cbranch_vccz .LBB1_922
	s_waitcnt vmcnt(0)
	s_cmpk_gt_u32 s17, 0xff
	s_cbranch_scc1 .LBB1_929
	s_barrier

; #define PG8_STAGE(bufoff, gbase, voff) do { _Pragma("unroll") for (int _i = 0; _i < 2; ++_i) \
;         __builtin_amdgcn_global_load_lds((const unsigned*)((const char*)(gbase) + (voff)[_i]), (LAS unsigned*)(lds + (bufoff) + ldsw + _i * 8192), 16, 0, 0); } while (0)
; #define PG8_LDA(dst, b, h) do { _Pragma("unroll") for (int m = 0; m < 4; ++m) _Pragma("unroll") for (int k = 0; k < 2; ++k) dst[m][k] = *(const LAS bf16x8*)(lds + PG8_SA(b, h) + aoff + m * 2048 + k * 1024); } while (0)
; #define PG8_LDB(dst, b, h) do { _Pragma("unroll") for (int n = 0; n < 2; ++n) _Pragma("unroll") for (int k = 0; k < 2; ++k) dst[n][k] = *(const LAS bf16x8*)(lds + PG8_SB(b, h) + boff + n * 2048 + k * 1024); } while (0)
; #define PG8_MMA(ai, bj, At, Bt) do { __builtin_amdgcn_s_setprio(1); _Pragma("unroll") for (int m = 0; m < 4; ++m) _Pragma("unroll") for (int n = 0; n < 2; ++n) _Pragma("unroll") for (int k = 0; k < 2; ++k) \
;         acc[ai][bj][m][n] = __builtin_amdgcn_mfma_f32_16x16x32_bf16(Bt[n][k], At[m][k], acc[ai][bj][m][n], 0, 0, 0); __builtin_amdgcn_s_setprio(0); } while (0)
; #define PG8_WAIT_L(n) asm volatile("s_waitcnt lgkmcnt(" #n ")" ::: "memory")
; #define PG8_BAR __builtin_amdgcn_s_barrier()
; #define PG8_SCHED __builtin_amdgcn_sched_barrier(0)
; template <class Map, class Epi>
; DI void gemm_phase(LAS unsigned char* lds, const Map& MP, const Epi& E, const int nM, const int nN, const int K, const int lda, const int ldb) {
;     ...
;             const bool last = (t == nt - 2);
;             const char* a1 = cA + (size_t)(t + 1) * kstep;
;             const char* a2 = last ? nA : cA + (size_t)(t + 2) * kstep; const char* b2 = last ? nB : cB + (size_t)(t + 2) * kstep;
;             const char* a3 = a2 + kstep; const char* b3 = b2 + kstep;
;             PG8_LDB(B0, 0, 0); PG8_SCHED; PG8_LDA(At, 0, 0); PG8_STAGE(PG8_SA(1, 1), a1 + hstepA, voffA);
;             PG8_WAIT_L(8); PG8_BAR; PG8_WAIT_L(0); PG8_MMA(0, 0, At, B0); PG8_BAR; PG8_SCHED;
;             PG8_LDB(B1, 0, 1); PG8_STAGE(PG8_SB(0, 0), b2, voffB);
;             PG8_BAR; PG8_WAIT_L(0); PG8_MMA(0, 1, At, B1); PG8_BAR;
;             PG8_LDA(At, 0, 1); PG8_STAGE(PG8_SA(0, 0), a2, voffA);
;             PG8_BAR; PG8_WAIT_L(0); PG8_MMA(1, 0, At, B0); PG8_BAR; PG8_SCHED;
.LBB1_1069:
	ds_read_b128 v[80:83], v189
	ds_read_b128 v[84:87], v189 offset:1024
	ds_read_b128 v[88:91], v189 offset:2048
	ds_read_b128 v[92:95], v189 offset:3072
	s_add_u32 s24, s42, 0xfff80080
	s_addc_u32 s25, s43, -1
	s_cmp_eq_u32 s3, 28
	s_cselect_b32 s47, s23, s25
	s_cselect_b32 s46, s58, s24
	s_cselect_b32 s25, s21, vcc_hi
	s_cselect_b32 s24, s59, vcc_lo
	v_lshl_add_u64 v[184:185], s[42:43], 0, v[178:179]
	s_add_i32 m0, s38, 0xc000
	ds_read_b128 v[96:99], v190
	ds_read_b128 v[100:103], v190 offset:1024
	ds_read_b128 v[108:111], v190 offset:2048
	ds_read_b128 v[112:115], v190 offset:3072
	ds_read_b128 v[160:163], v190 offset:4096
	ds_read_b128 v[164:167], v190 offset:5120
	ds_read_b128 v[198:201], v190 offset:6144
	ds_read_b128 v[202:205], v190 offset:7168
	global_load_lds_dwordx4 v[184:185], off
	v_lshl_add_u64 v[184:185], s[42:43], 0, v[176:177]
	s_add_i32 m0, s38, 0xe000
	s_nop 0
	global_load_lds_dwordx4 v[184:185], off
	s_waitcnt lgkmcnt(8)
	s_barrier
	s_setprio 1
	s_waitcnt lgkmcnt(7)
	v_mfma_f32_16x16x32_bf16 v[148:151], v[80:83], v[96:99], v[148:151]
	v_mfma_f32_16x16x32_bf16 v[144:147], v[88:91], v[96:99], v[144:147]
	s_waitcnt lgkmcnt(5)
	v_mfma_f32_16x16x32_bf16 v[136:139], v[80:83], v[108:111], v[136:139]
	v_mfma_f32_16x16x32_bf16 v[128:131], v[88:91], v[108:111], v[128:131]
	s_waitcnt lgkmcnt(3)
	v_mfma_f32_16x16x32_bf16 v[120:123], v[80:83], v[160:163], v[120:123]
	v_mfma_f32_16x16x32_bf16 v[104:107], v[88:91], v[160:163], v[104:107]
	s_waitcnt lgkmcnt(1)
	v_mfma_f32_16x16x32_bf16 v[76:79], v[80:83], v[198:201], v[76:79]
	v_mfma_f32_16x16x32_bf16 v[72:75], v[88:91], v[198:201], v[72:75]
	v_mfma_f32_16x16x32_bf16 v[148:151], v[84:87], v[100:103], v[148:151]
	v_mfma_f32_16x16x32_bf16 v[144:147], v[92:95], v[100:103], v[144:147]
	v_mfma_f32_16x16x32_bf16 v[136:139], v[84:87], v[112:115], v[136:139]
	v_mfma_f32_16x16x32_bf16 v[128:131], v[92:95], v[112:115], v[128:131]
	v_mfma_f32_16x16x32_bf16 v[120:123], v[84:87], v[164:167], v[120:123]
	v_mfma_f32_16x16x32_bf16 v[104:107], v[92:95], v[164:167], v[104:107]
	s_waitcnt lgkmcnt(0)
	v_mfma_f32_16x16x32_bf16 v[76:79], v[84:87], v[202:205], v[76:79]
	v_mfma_f32_16x16x32_bf16 v[72:75], v[92:95], v[202:205], v[72:75]
	s_setprio 0
	s_barrier
	s_add_i32 s68, s31, s66
	v_lshl_add_u64 v[184:185], s[24:25], 0, v[172:173]
	s_mov_b32 m0, s68
	ds_read_b128 v[206:209], v191
	ds_read_b128 v[210:213], v191 offset:1024
	ds_read_b128 v[214:217], v191 offset:2048
	ds_read_b128 v[218:221], v191 offset:3072
	global_load_lds_dwordx4 v[184:185], off
	v_lshl_add_u64 v[194:195], s[24:25], 0, v[168:169]
	s_add_i32 m0, s68, 0x2000
	s_nop 0
	global_load_lds_dwordx4 v[194:195], off
	s_barrier
	s_setprio 1
	s_waitcnt lgkmcnt(3)
	v_mfma_f32_16x16x32_bf16 v[156:159], v[206:209], v[96:99], v[156:159]
	s_waitcnt lgkmcnt(1)
	v_mfma_f32_16x16x32_bf16 v[96:99], v[214:217], v[96:99], v[152:155]
	v_mfma_f32_16x16x32_bf16 v[156:159], v[210:213], v[100:103], v[156:159]
	s_waitcnt lgkmcnt(0)
	v_mfma_f32_16x16x32_bf16 v[96:99], v[218:221], v[100:103], v[96:99]
	v_mfma_f32_16x16x32_bf16 v[100:103], v[206:209], v[108:111], v[140:143]
	v_mfma_f32_16x16x32_bf16 v[108:111], v[214:217], v[108:111], v[132:135]
	v_mfma_f32_16x16x32_bf16 v[116:119], v[214:217], v[160:163], v[116:119]
	v_mfma_f32_16x16x32_bf16 v[68:71], v[206:209], v[198:201], v[68:71]
	v_mfma_f32_16x16x32_bf16 v[64:67], v[214:217], v[198:201], v[64:67]
	v_mfma_f32_16x16x32_bf16 v[100:103], v[210:213], v[112:115], v[100:103]
	v_mfma_f32_16x16x32_bf16 v[108:111], v[218:221], v[112:115], v[108:111]
	v_mfma_f32_16x16x32_bf16 v[112:115], v[206:209], v[160:163], v[124:127]
	v_mfma_f32_16x16x32_bf16 v[116:119], v[218:221], v[164:167], v[116:119]
	v_mfma_f32_16x16x32_bf16 v[68:71], v[210:213], v[202:205], v[68:71]
	v_mfma_f32_16x16x32_bf16 v[64:67], v[218:221], v[202:205], v[64:67]
	v_mfma_f32_16x16x32_bf16 v[112:115], v[210:213], v[164:167], v[112:115]
	s_setprio 0
	s_mov_b32 m0, s38
	v_lshl_add_u64 v[226:227], s[46:47], 0, v[174:175]
	s_barrier
	ds_read_b128 v[124:127], v190 offset:16384
	ds_read_b128 v[132:135], v190 offset:17408
	ds_read_b128 v[140:143], v190 offset:18432
	ds_read_b128 v[152:155], v190 offset:19456
	ds_read_b128 v[160:163], v190 offset:20480
	ds_read_b128 v[164:167], v190 offset:21504
	ds_read_b128 v[198:201], v190 offset:22528
	ds_read_b128 v[202:205], v190 offset:23552
	global_load_lds_dwordx4 v[226:227], off
	v_lshl_add_u64 v[234:235], s[46:47], 0, v[170:171]
	s_mov_b32 m0, s39
	s_nop 0
	global_load_lds_dwordx4 v[234:235], off
	s_barrier
	s_setprio 1
	s_waitcnt lgkmcnt(7)
	v_mfma_f32_16x16x32_bf16 v[60:63], v[80:83], v[124:127], v[60:63]
	v_mfma_f32_16x16x32_bf16 v[48:51], v[88:91], v[124:127], v[48:51]
	s_waitcnt lgkmcnt(5)
	v_mfma_f32_16x16x32_bf16 v[40:43], v[80:83], v[140:143], v[40:43]
	v_mfma_f32_16x16x32_bf16 v[32:35], v[88:91], v[140:143], v[32:35]
	s_waitcnt lgkmcnt(3)
	v_mfma_f32_16x16x32_bf16 v[24:27], v[80:83], v[160:163], v[24:27]
	v_mfma_f32_16x16x32_bf16 v[16:19], v[88:91], v[160:163], v[16:19]
	s_waitcnt lgkmcnt(1)
	v_mfma_f32_16x16x32_bf16 v[12:15], v[80:83], v[198:201], v[12:15]
	v_mfma_f32_16x16x32_bf16 v[8:11], v[88:91], v[198:201], v[8:11]
	v_mfma_f32_16x16x32_bf16 v[60:63], v[84:87], v[132:135], v[60:63]
	v_mfma_f32_16x16x32_bf16 v[48:51], v[92:95], v[132:135], v[48:51]
	v_mfma_f32_16x16x32_bf16 v[40:43], v[84:87], v[152:155], v[40:43]
	v_mfma_f32_16x16x32_bf16 v[32:35], v[92:95], v[152:155], v[32:35]
	v_mfma_f32_16x16x32_bf16 v[24:27], v[84:87], v[164:167], v[24:27]
	v_mfma_f32_16x16x32_bf16 v[16:19], v[92:95], v[164:167], v[16:19]
	s_waitcnt lgkmcnt(0)
	v_mfma_f32_16x16x32_bf16 v[12:15], v[84:87], v[202:205], v[12:15]
	v_mfma_f32_16x16x32_bf16 v[8:11], v[92:95], v[202:205], v[8:11]
	s_setprio 0
	s_barrier
; #define PG8_STAGE(bufoff, gbase, voff) do { _Pragma("unroll") for (int _i = 0; _i < 2; ++_i) \
;         __builtin_amdgcn_global_load_lds((const unsigned*)((const char*)(gbase) + (voff)[_i]), (LAS unsigned*)(lds + (bufoff) + ldsw + _i * 8192), 16, 0, 0); } while (0)
; #define PG8_LDA(dst, b, h) do { _Pragma("unroll") for (int m = 0; m < 4; ++m) _Pragma("unroll") for (int k = 0; k < 2; ++k) dst[m][k] = *(const LAS bf16x8*)(lds + PG8_SA(b, h) + aoff + m * 2048 + k * 1024); } while (0)
; #define PG8_LDB(dst, b, h) do { _Pragma("unroll") for (int n = 0; n < 2; ++n) _Pragma("unroll") for (int k = 0; k < 2; ++k) dst[n][k] = *(const LAS bf16x8*)(lds + PG8_SB(b, h) + boff + n * 2048 + k * 1024); } while (0)
; #define PG8_MMA(ai, bj, At, Bt) do { __builtin_amdgcn_s_setprio(1); _Pragma("unroll") for (int m = 0; m < 4; ++m) _Pragma("unroll") for (int n = 0; n < 2; ++n) _Pragma("unroll") for (int k = 0; k < 2; ++k) \
;         acc[ai][bj][m][n] = __builtin_amdgcn_mfma_f32_16x16x32_bf16(Bt[n][k], At[m][k], acc[ai][bj][m][n], 0, 0, 0); __builtin_amdgcn_s_setprio(0); } while (0)
; #define PG8_WAIT_V(n) asm volatile("s_waitcnt vmcnt(" #n ")" ::: "memory")
; #define PG8_WAIT_L(n) asm volatile("s_waitcnt lgkmcnt(" #n ")" ::: "memory")
; #define PG8_BAR __builtin_amdgcn_s_barrier()
; #define PG8_SCHED __builtin_amdgcn_sched_barrier(0)
; template <class Map, class Epi>
; DI void gemm_phase(LAS unsigned char* lds, const Map& MP, const Epi& E, const int nM, const int nN, const int K, const int lda, const int ldb) {
;     ...
;             PG8_STAGE(PG8_SB(0, 1), b2 + hstepB, voffB);
;             PG8_WAIT_V(6); PG8_BAR; PG8_MMA(1, 1, At, B1); PG8_BAR;
;             PG8_LDB(B0, 1, 0); PG8_SCHED; PG8_LDA(At, 1, 0); PG8_STAGE(PG8_SA(0, 1), a2 + hstepA, voffA);
;             PG8_WAIT_L(8); PG8_BAR; PG8_WAIT_L(0); PG8_MMA(0, 0, At, B0); PG8_BAR; PG8_SCHED;
;             PG8_LDB(B1, 1, 1); PG8_STAGE(PG8_SB(1, 0), b3, voffB);
;             PG8_BAR; PG8_WAIT_L(0); PG8_MMA(0, 1, At, B1); PG8_BAR;
	s_add_u32 s68, s24, 0x80000
	s_addc_u32 s69, s25, 0
	s_add_i32 s70, s2, s66
	v_lshl_add_u64 v[80:81], s[68:69], 0, v[172:173]
	s_mov_b32 m0, s70
	s_nop 0
	global_load_lds_dwordx4 v[80:81], off
	v_lshl_add_u64 v[80:81], s[68:69], 0, v[168:169]
	s_add_i32 m0, s70, 0x2000
	s_nop 0
	global_load_lds_dwordx4 v[80:81], off
	s_waitcnt vmcnt(6)
	s_barrier
	s_setprio 1
	v_mfma_f32_16x16x32_bf16 v[56:59], v[206:209], v[124:127], v[56:59]
	v_mfma_f32_16x16x32_bf16 v[52:55], v[214:217], v[124:127], v[52:55]
	v_mfma_f32_16x16x32_bf16 v[44:47], v[206:209], v[140:143], v[44:47]
	v_mfma_f32_16x16x32_bf16 v[36:39], v[214:217], v[140:143], v[36:39]
	v_mfma_f32_16x16x32_bf16 v[28:31], v[206:209], v[160:163], v[28:31]
	v_mfma_f32_16x16x32_bf16 v[20:23], v[214:217], v[160:163], v[20:23]
	v_mfma_f32_16x16x32_bf16 v[4:7], v[206:209], v[198:201], v[4:7]
	v_mfma_f32_16x16x32_bf16 v[0:3], v[214:217], v[198:201], v[0:3]
	v_mfma_f32_16x16x32_bf16 v[56:59], v[210:213], v[132:135], v[56:59]
	v_mfma_f32_16x16x32_bf16 v[52:55], v[218:221], v[132:135], v[52:55]
	v_mfma_f32_16x16x32_bf16 v[44:47], v[210:213], v[152:155], v[44:47]
	v_mfma_f32_16x16x32_bf16 v[36:39], v[218:221], v[152:155], v[36:39]
	v_mfma_f32_16x16x32_bf16 v[28:31], v[210:213], v[164:167], v[28:31]
	v_mfma_f32_16x16x32_bf16 v[20:23], v[218:221], v[164:167], v[20:23]
	v_mfma_f32_16x16x32_bf16 v[4:7], v[210:213], v[202:205], v[4:7]
	v_mfma_f32_16x16x32_bf16 v[0:3], v[218:221], v[202:205], v[0:3]
	s_setprio 0
	s_add_i32 s68, 0, 0x18000
	v_add_u32_e32 v92, s68, v188
	s_barrier
	ds_read_b128 v[80:83], v92
	ds_read_b128 v[84:87], v92 offset:1024
	ds_read_b128 v[88:91], v92 offset:2048
	ds_read_b128 v[92:95], v92 offset:3072
	s_add_u32 s46, s46, 0x80000
	s_addc_u32 s47, s47, 0
	s_mov_b32 m0, s56
	v_lshl_add_u64 v[140:141], s[46:47], 0, v[174:175]
	ds_read_b128 v[124:127], v190 offset:32768
	ds_read_b128 v[132:135], v190 offset:33792
	ds_read_b128 v[160:163], v190 offset:34816
	ds_read_b128 v[164:167], v190 offset:35840
	ds_read_b128 v[198:201], v190 offset:36864
	ds_read_b128 v[202:205], v190 offset:37888
	ds_read_b128 v[206:209], v190 offset:38912
	ds_read_b128 v[210:213], v190 offset:39936
	global_load_lds_dwordx4 v[140:141], off
	v_lshl_add_u64 v[140:141], s[46:47], 0, v[170:171]
	s_mov_b32 m0, s57
	s_nop 0
	global_load_lds_dwordx4 v[140:141], off
	s_waitcnt lgkmcnt(8)
	s_barrier
	s_setprio 1
	s_waitcnt lgkmcnt(7)
	v_mfma_f32_16x16x32_bf16 v[140:143], v[80:83], v[124:127], v[148:151]
	s_waitcnt lgkmcnt(6)
	v_mfma_f32_16x16x32_bf16 v[148:151], v[84:87], v[132:135], v[140:143]
	v_mfma_f32_16x16x32_bf16 v[140:143], v[88:91], v[124:127], v[144:147]
	s_waitcnt lgkmcnt(5)
	v_mfma_f32_16x16x32_bf16 v[136:139], v[80:83], v[160:163], v[136:139]
	v_mfma_f32_16x16x32_bf16 v[128:131], v[88:91], v[160:163], v[128:131]
	s_waitcnt lgkmcnt(3)
	v_mfma_f32_16x16x32_bf16 v[120:123], v[80:83], v[198:201], v[120:123]
	v_mfma_f32_16x16x32_bf16 v[104:107], v[88:91], v[198:201], v[104:107]
	s_waitcnt lgkmcnt(1)
	v_mfma_f32_16x16x32_bf16 v[76:79], v[80:83], v[206:209], v[76:79]
	v_mfma_f32_16x16x32_bf16 v[72:75], v[88:91], v[206:209], v[72:75]
	v_mfma_f32_16x16x32_bf16 v[144:147], v[92:95], v[132:135], v[140:143]
	v_mfma_f32_16x16x32_bf16 v[136:139], v[84:87], v[164:167], v[136:139]
	v_mfma_f32_16x16x32_bf16 v[128:131], v[92:95], v[164:167], v[128:131]
	v_mfma_f32_16x16x32_bf16 v[120:123], v[84:87], v[202:205], v[120:123]
	v_mfma_f32_16x16x32_bf16 v[104:107], v[92:95], v[202:205], v[104:107]
	s_waitcnt lgkmcnt(0)
	v_mfma_f32_16x16x32_bf16 v[76:79], v[84:87], v[210:213], v[76:79]
	v_mfma_f32_16x16x32_bf16 v[72:75], v[92:95], v[210:213], v[72:75]
	s_setprio 0
	s_barrier
	s_add_i32 s46, 0, 0x1c000
	v_add_u32_e32 v140, s46, v188
	s_add_i32 s47, s68, s66
	ds_read_b128 v[214:217], v140
	ds_read_b128 v[218:221], v140 offset:1024
	ds_read_b128 v[222:225], v140 offset:2048
	ds_read_b128 v[230:233], v140 offset:3072
	v_lshl_add_u64 v[140:141], v[184:185], 0, s[14:15]
	s_mov_b32 m0, s47
	s_nop 0
	global_load_lds_dwordx4 v[140:141], off
	v_lshl_add_u64 v[140:141], v[194:195], 0, s[14:15]
	s_add_i32 m0, s47, 0x2000
	s_nop 0
	global_load_lds_dwordx4 v[140:141], off
	s_barrier
	s_setprio 1
	s_waitcnt lgkmcnt(1)
	v_mfma_f32_16x16x32_bf16 v[96:99], v[222:225], v[124:127], v[96:99]
	v_mfma_f32_16x16x32_bf16 v[140:143], v[214:217], v[124:127], v[156:159]
	s_waitcnt lgkmcnt(0)
	v_mfma_f32_16x16x32_bf16 v[152:155], v[230:233], v[132:135], v[96:99]
	v_mfma_f32_16x16x32_bf16 v[96:99], v[214:217], v[160:163], v[100:103]
	v_mfma_f32_16x16x32_bf16 v[156:159], v[218:221], v[132:135], v[140:143]
	v_mfma_f32_16x16x32_bf16 v[140:143], v[218:221], v[164:167], v[96:99]
	v_mfma_f32_16x16x32_bf16 v[96:99], v[222:225], v[160:163], v[108:111]
	v_mfma_f32_16x16x32_bf16 v[132:135], v[230:233], v[164:167], v[96:99]
	v_mfma_f32_16x16x32_bf16 v[96:99], v[214:217], v[198:201], v[112:115]
	v_mfma_f32_16x16x32_bf16 v[124:127], v[218:221], v[202:205], v[96:99]
	v_mfma_f32_16x16x32_bf16 v[96:99], v[222:225], v[198:201], v[116:119]
	v_mfma_f32_16x16x32_bf16 v[68:71], v[214:217], v[206:209], v[68:71]
	v_mfma_f32_16x16x32_bf16 v[64:67], v[222:225], v[206:209], v[64:67]
	v_mfma_f32_16x16x32_bf16 v[116:119], v[230:233], v[202:205], v[96:99]
	v_mfma_f32_16x16x32_bf16 v[68:71], v[218:221], v[210:213], v[68:71]
	v_mfma_f32_16x16x32_bf16 v[64:67], v[230:233], v[210:213], v[64:67]
	s_setprio 0
	s_mov_b32 m0, s63
	v_lshl_add_u64 v[184:185], v[226:227], 0, s[14:15]
	s_barrier
; DI float dpp_ror1(float v)  { return __builtin_bit_cast(float, __builtin_amdgcn_update_dpp(0, __builtin_bit_cast(int, v), 0x121, 0xf, 0xf, false)); }
; DI float dpp_ror15(float v) { return __builtin_bit_cast(float, __builtin_amdgcn_update_dpp(0, __builtin_bit_cast(int, v), 0x12F, 0xf, 0xf, false)); }
;     DI void operator()(const f32x4 (&acc)[2][2][4][2], const Unit& u, int wr, int wc, int fr, int fq) const {
;         const int row0 = u.pm * BM + wr * 64 + fr, ch0 = u.pn * 128 + wc * 32 + 8 * fq;
;         f32x4 w0[2], w1[2], w2[2], bb[2];
; #pragma unroll
;         for (int n = 0; n < 2; ++n) { w0[n] = *(const f32x4*)(cw + ch0 + 4 * n); w1[n] = *(const f32x4*)(cw + DFF + ch0 + 4 * n); w2[n] = *(const f32x4*)(cw + 2 * DFF + ch0 + 4 * n); bb[n] = *(const f32x4*)(cb + ch0 + 4 * n); }
; #pragma unroll
;         for (int ai = 0; ai < 2; ++ai)
; #pragma unroll
;             for (int m = 0; m < 4; ++m) {
;                 const bool efirst = (m == 0) && (fr == 0), elast = (m == 3) && (fr == 15);
;                 const int row = row0 + ai * HALF + m * 16;
;                 f32x4 gc[2];
; #pragma unroll
;                 for (int n = 0; n < 2; ++n) {
;                     const f32x4 g = acc[ai][0][m][n];
;                     const f32x4 gprev = acc[ai][0][m > 0 ? m - 1 : 0][n], gnext = acc[ai][0][m < 3 ? m + 1 : 3][n];
;                     f32x4 up, dn;
; #pragma unroll
;                     for (int e = 0; e < 4; ++e) {
;                         const float pu = (m > 0 && fr == 15) ? gprev[e] : g[e];
;                         const float pd = (m < 3 && fr == 0) ? gnext[e] : g[e];
;                         up[e] = dpp_ror1(pu); dn[e] = dpp_ror15(pd);
;                     }
;                     if (efirst) up = (f32x4){0.f, 0.f, 0.f, 0.f};
;                     if (elast) dn = (f32x4){0.f, 0.f, 0.f, 0.f};
;                     gc[n] = w0[n] * up + w1[n] * g + w2[n] * dn + bb[n];
;                 }
; template <class Map, class Epi>
; DI void gemm_phase(LAS unsigned char* lds, const Map& MP, const Epi& E, const int nM, const int nN, const int K, const int lda, const int ldb) {
;     ...
;             PG8_LDA(At, 1, 1); PG8_STAGE(PG8_SA(1, 0), a3, voffA);
;             PG8_BAR; PG8_WAIT_L(0); PG8_MMA(1, 0, At, B0); PG8_BAR; PG8_SCHED;
;             PG8_STAGE(PG8_SB(1, 1), b3 + hstepB, voffB);
;             PG8_WAIT_V(6); PG8_BAR; PG8_MMA(1, 1, At, B1); PG8_BAR;
	ds_read_b128 v[96:99], v190 offset:49152
	ds_read_b128 v[100:103], v190 offset:50176
	ds_read_b128 v[108:111], v190 offset:51200
	ds_read_b128 v[112:115], v190 offset:52224
	ds_read_b128 v[160:163], v190 offset:53248
	ds_read_b128 v[164:167], v190 offset:54272
	ds_read_b128 v[198:201], v190 offset:55296
	ds_read_b128 v[202:205], v190 offset:56320
	global_load_lds_dwordx4 v[184:185], off
	v_lshl_add_u64 v[184:185], v[234:235], 0, s[14:15]
	s_mov_b32 m0, s4
	s_nop 0
	global_load_lds_dwordx4 v[184:185], off
	s_barrier
	s_setprio 1
	s_waitcnt lgkmcnt(7)
	v_mfma_f32_16x16x32_bf16 v[60:63], v[80:83], v[96:99], v[60:63]
	v_mfma_f32_16x16x32_bf16 v[48:51], v[88:91], v[96:99], v[48:51]
	s_waitcnt lgkmcnt(5)
	v_mfma_f32_16x16x32_bf16 v[40:43], v[80:83], v[108:111], v[40:43]
	v_mfma_f32_16x16x32_bf16 v[32:35], v[88:91], v[108:111], v[32:35]
	s_waitcnt lgkmcnt(3)
	v_mfma_f32_16x16x32_bf16 v[24:27], v[80:83], v[160:163], v[24:27]
	v_mfma_f32_16x16x32_bf16 v[16:19], v[88:91], v[160:163], v[16:19]
	s_waitcnt lgkmcnt(1)
	v_mfma_f32_16x16x32_bf16 v[12:15], v[80:83], v[198:201], v[12:15]
	v_mfma_f32_16x16x32_bf16 v[8:11], v[88:91], v[198:201], v[8:11]
	v_mfma_f32_16x16x32_bf16 v[60:63], v[84:87], v[100:103], v[60:63]
	v_mfma_f32_16x16x32_bf16 v[48:51], v[92:95], v[100:103], v[48:51]
	v_mfma_f32_16x16x32_bf16 v[40:43], v[84:87], v[112:115], v[40:43]
	v_mfma_f32_16x16x32_bf16 v[32:35], v[92:95], v[112:115], v[32:35]
	v_mfma_f32_16x16x32_bf16 v[24:27], v[84:87], v[164:167], v[24:27]
	v_mfma_f32_16x16x32_bf16 v[16:19], v[92:95], v[164:167], v[16:19]
	s_waitcnt lgkmcnt(0)
	v_mfma_f32_16x16x32_bf16 v[12:15], v[84:87], v[202:205], v[12:15]
	v_mfma_f32_16x16x32_bf16 v[8:11], v[92:95], v[202:205], v[8:11]
	s_setprio 0
	s_barrier
	s_add_u32 s24, s24, 0x80080
	s_addc_u32 s25, s25, 0
	s_add_i32 s46, s46, s66
	v_lshl_add_u64 v[80:81], s[24:25], 0, v[172:173]
	s_mov_b32 m0, s46
	s_nop 0
	global_load_lds_dwordx4 v[80:81], off
	v_lshl_add_u64 v[80:81], s[24:25], 0, v[168:169]
	s_add_i32 m0, s46, 0x2000
	s_nop 0
	global_load_lds_dwordx4 v[80:81], off
	s_waitcnt vmcnt(6)
	s_barrier
	s_setprio 1
	v_mfma_f32_16x16x32_bf16 v[56:59], v[214:217], v[96:99], v[56:59]
	v_mfma_f32_16x16x32_bf16 v[52:55], v[222:225], v[96:99], v[52:55]
	v_mfma_f32_16x16x32_bf16 v[44:47], v[214:217], v[108:111], v[44:47]
	v_mfma_f32_16x16x32_bf16 v[36:39], v[222:225], v[108:111], v[36:39]
	v_mfma_f32_16x16x32_bf16 v[28:31], v[214:217], v[160:163], v[28:31]
	v_mfma_f32_16x16x32_bf16 v[20:23], v[222:225], v[160:163], v[20:23]
	v_mfma_f32_16x16x32_bf16 v[4:7], v[214:217], v[198:201], v[4:7]
	v_mfma_f32_16x16x32_bf16 v[0:3], v[222:225], v[198:201], v[0:3]
	v_mfma_f32_16x16x32_bf16 v[56:59], v[218:221], v[100:103], v[56:59]
	v_mfma_f32_16x16x32_bf16 v[52:55], v[230:233], v[100:103], v[52:55]
	v_mfma_f32_16x16x32_bf16 v[44:47], v[218:221], v[112:115], v[44:47]
	v_mfma_f32_16x16x32_bf16 v[36:39], v[230:233], v[112:115], v[36:39]
	v_mfma_f32_16x16x32_bf16 v[28:31], v[218:221], v[164:167], v[28:31]
	v_mfma_f32_16x16x32_bf16 v[20:23], v[230:233], v[164:167], v[20:23]
	v_mfma_f32_16x16x32_bf16 v[4:7], v[218:221], v[202:205], v[4:7]
	v_mfma_f32_16x16x32_bf16 v[0:3], v[230:233], v[202:205], v[0:3]
	s_setprio 0
	s_add_i32 s3, s3, 2
	s_add_u32 vcc_lo, vcc_lo, 0x100
	s_addc_u32 vcc_hi, vcc_hi, 0
	s_add_u32 s42, s42, 0x100
	s_addc_u32 s43, s43, 0
	s_cmp_gt_u32 s3, 29
	s_barrier
	s_cbranch_scc0 .LBB1_1069
	s_lshl_b32 s21, s45, 7
	v_mov_b32_e32 v194, v186
	v_mov_b32_e32 v80, v187
	s_or_b32 s21, s21, s62
	v_mov_b32_e32 v160, 0
	v_lshl_add_u32 v184, v80, 3, s21
	v_ashrrev_i32_e32 v185, 31, v184
	v_lshlrev_b64 v[80:81], 2, v[184:185]
	v_lshl_add_u64 v[84:85], s[6:7], 0, v[80:81]
	v_lshl_add_u64 v[88:89], s[16:17], 0, v[80:81]
	v_lshl_add_u64 v[92:93], s[18:19], 0, v[80:81]
	v_lshl_add_u64 v[112:113], s[52:53], 0, v[80:81]
	global_load_dwordx4 v[80:83], v[84:85], off offset:16
	global_load_dwordx4 v[96:99], v[84:85], off
	s_nop 0
	global_load_dwordx4 v[84:87], v[88:89], off offset:16
	global_load_dwordx4 v[100:103], v[88:89], off
	s_nop 0
	global_load_dwordx4 v[88:91], v[92:93], off offset:16
	global_load_dwordx4 v[108:111], v[92:93], off
	s_nop 0
	global_load_dwordx4 v[92:95], v[112:113], off offset:16
	s_nop 0
	global_load_dwordx4 v[112:115], v[112:113], off
	v_cmp_eq_u32_e32 vcc, 0, v194
	v_mov_b32_e32 v164, 0
	v_mov_b32_e32 v195, 0
	v_cndmask_b32_e32 v161, v148, v136, vcc
	v_cndmask_b32_e32 v162, v149, v137, vcc
	v_cndmask_b32_e32 v163, v150, v138, vcc
	v_mov_b32_dpp v160, v161 row_ror:15 row_mask:0xf bank_mask:0xf
	v_mov_b32_e32 v161, 0
	v_mov_b32_e32 v166, 0
	v_mov_b32_e32 v167, 0
	v_mov_b32_dpp v161, v162 row_ror:15 row_mask:0xf bank_mask:0xf
	v_mov_b32_e32 v162, 0
	v_mov_b32_dpp v164, v150 row_ror:1 row_mask:0xf bank_mask:0xf
	v_cndmask_b32_e32 v165, v151, v139, vcc
	v_mov_b32_dpp v162, v163 row_ror:15 row_mask:0xf bank_mask:0xf
	v_mov_b32_dpp v195, v151 row_ror:1 row_mask:0xf bank_mask:0xf
	v_mov_b32_e32 v163, 0
	v_mov_b32_dpp v166, v148 row_ror:1 row_mask:0xf bank_mask:0xf
	v_mov_b32_dpp v167, v149 row_ror:1 row_mask:0xf bank_mask:0xf
	v_mov_b32_dpp v163, v165 row_ror:15 row_mask:0xf bank_mask:0xf
	v_cndmask_b32_e64 v165, v195, 0, vcc
	v_cndmask_b32_e64 v164, v164, 0, vcc
	v_cndmask_b32_e64 v167, v167, 0, vcc
	v_cndmask_b32_e64 v166, v166, 0, vcc
	v_mov_b32_e32 v195, 0
	v_mov_b32_e32 v196, 0
	v_mov_b32_e32 v198, 0
	v_mov_b32_e32 v200, 0
	v_mov_b32_dpp v195, v144 row_ror:1 row_mask:0xf bank_mask:0xf
	v_mov_b32_dpp v196, v145 row_ror:1 row_mask:0xf bank_mask:0xf
	v_mov_b32_dpp v198, v146 row_ror:1 row_mask:0xf bank_mask:0xf
	v_cndmask_b32_e32 v199, v147, v131, vcc
	v_mov_b32_dpp v200, v147 row_ror:1 row_mask:0xf bank_mask:0xf
	v_cndmask_b32_e64 v198, v198, 0, vcc
	v_cndmask_b32_e64 v201, v196, 0, vcc
	s_lshl_b32 s3, s44, 8
	s_add_i32 s3, s3, s49
	v_add_u32_e32 v193, s3, v194
	v_cmp_ne_u32_e64 s[46:47], 0, v194
	s_waitcnt vmcnt(0)
; DI unsigned pack2(float a, float b) { f32x2 v = {a, b}; hwbf16x2 r = __builtin_convertvector(v, hwbf16x2); return __builtin_bit_cast(unsigned, r); }
; DI float dpp_ror1(float v)  { return __builtin_bit_cast(float, __builtin_amdgcn_update_dpp(0, __builtin_bit_cast(int, v), 0x121, 0xf, 0xf, false)); }
;     DI void operator()(const f32x4 (&acc)[2][2][4][2], const Unit& u, int wr, int wc, int fr, int fq) const {
;     ...
;                 const bool efirst = (m == 0) && (fr == 0), elast = (m == 3) && (fr == 15);
;                 const int row = row0 + ai * HALF + m * 16;
;                 f32x4 gc[2];
; #pragma unroll
;                 for (int n = 0; n < 2; ++n) {
;                     const f32x4 g = acc[ai][0][m][n];
;                     const f32x4 gprev = acc[ai][0][m > 0 ? m - 1 : 0][n], gnext = acc[ai][0][m < 3 ? m + 1 : 3][n];
;                     f32x4 up, dn;
; #pragma unroll
;                     for (int e = 0; e < 4; ++e) {
;                         const float pu = (m > 0 && fr == 15) ? gprev[e] : g[e];
;                         const float pd = (m < 3 && fr == 0) ? gnext[e] : g[e];
;                         up[e] = dpp_ror1(pu); dn[e] = dpp_ror15(pd);
;                     }
;                     if (efirst) up = (f32x4){0.f, 0.f, 0.f, 0.f};
;                     if (elast) dn = (f32x4){0.f, 0.f, 0.f, 0.f};
;                     gc[n] = w0[n] * up + w1[n] * g + w2[n] * dn + bb[n];
;                 }
;                 if (efirst || elast) {
;                     const size_t eo = (size_t)((row >> 6) * 2 + (elast ? 1 : 0)) * DFF + ch0;
; #pragma unroll
;                     for (int n = 0; n < 2; ++n) { *(f32x4*)(EP + eo + 4 * n) = gc[n]; *(f32x4*)(ER + eo + 4 * n) = acc[ai][0][m][n]; *(f32x4*)(EV + eo + 4 * n) = acc[ai][1][m][n]; }
;                 } else {
;                     const f32x4 v0 = acc[ai][1][m][0], v1 = acc[ai][1][m][1];
;                     u32x4 o;
;                     o[0] = pack2(silu_mul(gc[0][0], v0[0]), silu_mul(gc[0][1], v0[1])); o[1] = pack2(silu_mul(gc[0][2], v0[2]), silu_mul(gc[0][3], v0[3]));
;                     o[2] = pack2(silu_mul(gc[1][0], v1[0]), silu_mul(gc[1][1], v1[1])); o[3] = pack2(silu_mul(gc[1][2], v1[2]), silu_mul(gc[1][3], v1[3]));
;                     *(u32x4*)(ACT + (size_t)row * DFF + ch0) = o;
;                 }
	v_pk_mul_f32 v[164:165], v[98:99], v[164:165]
	v_pk_mul_f32 v[166:167], v[96:97], v[166:167]
	v_pk_fma_f32 v[164:165], v[150:151], v[102:103], v[164:165]
	v_pk_fma_f32 v[166:167], v[148:149], v[100:101], v[166:167]
	v_pk_fma_f32 v[162:163], v[110:111], v[162:163], v[164:165]
	v_cndmask_b32_e32 v165, v144, v128, vcc
	v_mov_b32_e32 v164, 0
	v_pk_fma_f32 v[160:161], v[108:109], v[160:161], v[166:167]
	v_cndmask_b32_e32 v166, v145, v129, vcc
	v_mov_b32_dpp v164, v165 row_ror:15 row_mask:0xf bank_mask:0xf
	v_mov_b32_e32 v165, 0
	v_cndmask_b32_e32 v167, v146, v130, vcc
	v_pk_add_f32 v[162:163], v[114:115], v[162:163]
	v_mov_b32_dpp v165, v166 row_ror:15 row_mask:0xf bank_mask:0xf
	v_mov_b32_e32 v166, 0
	v_pk_add_f32 v[160:161], v[112:113], v[160:161]
	s_nop 0
	v_mov_b32_dpp v166, v167 row_ror:15 row_mask:0xf bank_mask:0xf
	v_mov_b32_e32 v167, 0
	s_nop 1
	v_mov_b32_dpp v167, v199 row_ror:15 row_mask:0xf bank_mask:0xf
	v_cndmask_b32_e64 v199, v200, 0, vcc
	v_cndmask_b32_e64 v200, v195, 0, vcc
	v_pk_mul_f32 v[200:201], v[80:81], v[200:201]
	v_pk_mul_f32 v[198:199], v[82:83], v[198:199]
	v_pk_fma_f32 v[200:201], v[144:145], v[84:85], v[200:201]
	v_pk_fma_f32 v[198:199], v[146:147], v[86:87], v[198:199]
	v_pk_fma_f32 v[164:165], v[88:89], v[164:165], v[200:201]
	v_pk_fma_f32 v[166:167], v[90:91], v[166:167], v[198:199]
	v_pk_add_f32 v[164:165], v[92:93], v[164:165]
	v_pk_add_f32 v[166:167], v[94:95], v[166:167]
	s_and_saveexec_b64 s[24:25], s[46:47]
	s_xor_b64 s[24:25], exec, s[24:25]
	s_cbranch_execz .LBB1_1072
	v_mul_f32_e32 v195, 0xbfb8aa3b, v160
	v_exp_f32_e32 v195, v195
	v_mul_f32_e32 v196, 0xbfb8aa3b, v161
	v_exp_f32_e32 v196, v196
	v_pk_mul_f32 v[160:161], v[156:157], v[160:161]
	v_add_f32_e32 v195, 1.0, v195
	v_rcp_f32_e32 v198, v195
	v_add_f32_e32 v196, 1.0, v196
	v_mul_f32_e32 v195, 0xbfb8aa3b, v162
	v_rcp_f32_e32 v199, v196
	v_exp_f32_e32 v195, v195
	v_mul_f32_e32 v196, 0xbfb8aa3b, v163
	v_exp_f32_e32 v196, v196
	v_pk_mul_f32 v[160:161], v[160:161], v[198:199]
	v_add_f32_e32 v195, 1.0, v195
	v_rcp_f32_e32 v200, v195
	v_add_f32_e32 v195, 1.0, v196
	v_rcp_f32_e32 v201, v195
	v_cvt_pk_bf16_f32 v160, v160, v161
	v_mul_f32_e32 v161, 0xbfb8aa3b, v164
	v_exp_f32_e32 v195, v161
	v_mul_f32_e32 v161, 0xbfb8aa3b, v165
	v_exp_f32_e32 v196, v161
	v_pk_mul_f32 v[162:163], v[158:159], v[162:163]
	v_pk_mul_f32 v[164:165], v[152:153], v[164:165]
	v_pk_mul_f32 v[162:163], v[162:163], v[200:201]
	s_nop 0
	v_cvt_pk_bf16_f32 v161, v162, v163
	v_add_f32_e32 v162, 1.0, v195
	v_mul_f32_e32 v195, 0xbfb8aa3b, v166
	v_add_f32_e32 v163, 1.0, v196
	v_exp_f32_e32 v195, v195
	v_mul_f32_e32 v196, 0xbfb8aa3b, v167
	v_exp_f32_e32 v196, v196
	v_rcp_f32_e32 v162, v162
	v_add_f32_e32 v195, 1.0, v195
	v_rcp_f32_e32 v198, v195
	v_add_f32_e32 v195, 1.0, v196
	v_rcp_f32_e32 v163, v163
	v_rcp_f32_e32 v199, v195
	v_pk_mul_f32 v[166:167], v[154:155], v[166:167]
	v_pk_mul_f32 v[162:163], v[164:165], v[162:163]
	v_pk_mul_f32 v[164:165], v[166:167], v[198:199]
	v_cvt_pk_bf16_f32 v162, v162, v163
	v_cvt_pk_bf16_f32 v163, v164, v165
	v_mov_b64_e32 v[164:165], s[54:55]
	v_mad_i64_i32 v[164:165], s[42:43], v193, s60, v[164:165]
	v_lshl_add_u64 v[164:165], v[184:185], 1, v[164:165]
	global_store_dwordx4 v[164:165], v[160:163], off
.LBB1_1072:
	s_andn2_saveexec_b64 s[24:25], s[24:25]
	s_cbranch_execz .LBB1_1074
	s_ashr_i32 s3, s3, 5
	v_mad_i64_i32 v[198:199], s[42:43], s3, v192, v[184:185]
	v_lshlrev_b64 v[198:199], 2, v[198:199]
	v_lshl_add_u64 v[200:201], s[8:9], 0, v[198:199]
	global_store_dwordx4 v[200:201], v[160:163], off
	s_nop 1
	v_lshl_add_u64 v[160:161], s[10:11], 0, v[198:199]
	v_lshl_add_u64 v[162:163], s[12:13], 0, v[198:199]
	global_store_dwordx4 v[160:161], v[148:151], off
	global_store_dwordx4 v[162:163], v[156:159], off
	global_store_dwordx4 v[200:201], v[164:167], off offset:16
	global_store_dwordx4 v[160:161], v[144:147], off offset:16
	global_store_dwordx4 v[162:163], v[152:155], off offset:16
.LBB1_1074:
	s_or_b64 exec, exec, s[24:25]
	v_cmp_eq_u32_e64 s[44:45], 15, v194
	v_cndmask_b32_e32 v153, v136, v120, vcc
	v_cndmask_b32_e32 v154, v137, v121, vcc
	v_cndmask_b32_e64 v152, v136, v148, s[44:45]
	v_mov_b32_e32 v148, 0
	v_cndmask_b32_e32 v155, v138, v122, vcc
	v_cndmask_b32_e32 v156, v139, v123, vcc
	v_mov_b32_dpp v148, v152 row_ror:1 row_mask:0xf bank_mask:0xf
	v_mov_b32_e32 v152, 0
	v_cndmask_b32_e32 v157, v128, v104, vcc
	v_cndmask_b32_e32 v158, v129, v105, vcc
	v_mov_b32_dpp v152, v153 row_ror:15 row_mask:0xf bank_mask:0xf
	v_cndmask_b32_e64 v153, v137, v149, s[44:45]
	v_mov_b32_e32 v149, 0
	v_cndmask_b32_e32 v159, v130, v106, vcc
	v_cndmask_b32_e32 v160, v131, v107, vcc
	v_mov_b32_dpp v149, v153 row_ror:1 row_mask:0xf bank_mask:0xf
	v_mov_b32_e32 v153, 0
	v_pk_mul_f32 v[148:149], v[96:97], v[148:149]
	v_cmp_ne_u32_e64 s[42:43], 15, v194
	v_mov_b32_dpp v153, v154 row_ror:15 row_mask:0xf bank_mask:0xf
	v_pk_fma_f32 v[148:149], v[136:137], v[100:101], v[148:149]
	v_cndmask_b32_e64 v154, v138, v150, s[44:45]
	v_mov_b32_e32 v150, 0
	v_pk_fma_f32 v[148:149], v[108:109], v[152:153], v[148:149]
	s_nop 0
	v_mov_b32_dpp v150, v154 row_ror:1 row_mask:0xf bank_mask:0xf
	v_mov_b32_e32 v154, 0
	v_pk_add_f32 v[148:149], v[112:113], v[148:149]
	s_nop 0
	v_mov_b32_dpp v154, v155 row_ror:15 row_mask:0xf bank_mask:0xf
	v_cndmask_b32_e64 v155, v139, v151, s[44:45]
	v_mov_b32_e32 v151, 0
	v_mul_f32_e32 v152, 0xbfb8aa3b, v148
	v_mul_f32_e32 v153, 0xbfb8aa3b, v149
	v_mov_b32_dpp v151, v155 row_ror:1 row_mask:0xf bank_mask:0xf
	v_exp_f32_e32 v152, v152
	v_exp_f32_e32 v153, v153
	v_mov_b32_e32 v155, 0
	v_pk_mul_f32 v[150:151], v[98:99], v[150:151]
	v_add_f32_e32 v152, 1.0, v152
; DI unsigned pack2(float a, float b) { f32x2 v = {a, b}; hwbf16x2 r = __builtin_convertvector(v, hwbf16x2); return __builtin_bit_cast(unsigned, r); }
; DI float dpp_ror1(float v)  { return __builtin_bit_cast(float, __builtin_amdgcn_update_dpp(0, __builtin_bit_cast(int, v), 0x121, 0xf, 0xf, false)); }
;     DI void operator()(const f32x4 (&acc)[2][2][4][2], const Unit& u, int wr, int wc, int fr, int fq) const {
;     ...
;                 const bool efirst = (m == 0) && (fr == 0), elast = (m == 3) && (fr == 15);
;                 const int row = row0 + ai * HALF + m * 16;
;                 f32x4 gc[2];
; #pragma unroll
;                 for (int n = 0; n < 2; ++n) {
;                     const f32x4 g = acc[ai][0][m][n];
;                     const f32x4 gprev = acc[ai][0][m > 0 ? m - 1 : 0][n], gnext = acc[ai][0][m < 3 ? m + 1 : 3][n];
;                     f32x4 up, dn;
; #pragma unroll
;                     for (int e = 0; e < 4; ++e) {
;                         const float pu = (m > 0 && fr == 15) ? gprev[e] : g[e];
;                         const float pd = (m < 3 && fr == 0) ? gnext[e] : g[e];
;                         up[e] = dpp_ror1(pu); dn[e] = dpp_ror15(pd);
;                     }
;                     if (efirst) up = (f32x4){0.f, 0.f, 0.f, 0.f};
;                     if (elast) dn = (f32x4){0.f, 0.f, 0.f, 0.f};
;                     gc[n] = w0[n] * up + w1[n] * g + w2[n] * dn + bb[n];
;                 }
;                 if (efirst || elast) {
;                     const size_t eo = (size_t)((row >> 6) * 2 + (elast ? 1 : 0)) * DFF + ch0;
; #pragma unroll
;                     for (int n = 0; n < 2; ++n) { *(f32x4*)(EP + eo + 4 * n) = gc[n]; *(f32x4*)(ER + eo + 4 * n) = acc[ai][0][m][n]; *(f32x4*)(EV + eo + 4 * n) = acc[ai][1][m][n]; }
;                 } else {
;                     const f32x4 v0 = acc[ai][1][m][0], v1 = acc[ai][1][m][1];
;                     u32x4 o;
;                     o[0] = pack2(silu_mul(gc[0][0], v0[0]), silu_mul(gc[0][1], v0[1])); o[1] = pack2(silu_mul(gc[0][2], v0[2]), silu_mul(gc[0][3], v0[3]));
;                     o[2] = pack2(silu_mul(gc[1][0], v1[0]), silu_mul(gc[1][1], v1[1])); o[3] = pack2(silu_mul(gc[1][2], v1[2]), silu_mul(gc[1][3], v1[3]));
;                     *(u32x4*)(ACT + (size_t)row * DFF + ch0) = o;
	v_mov_b32_dpp v155, v156 row_ror:15 row_mask:0xf bank_mask:0xf
	v_cndmask_b32_e64 v156, v128, v144, s[44:45]
	v_mov_b32_e32 v144, 0
	v_pk_fma_f32 v[150:151], v[138:139], v[102:103], v[150:151]
	v_add_f32_e32 v153, 1.0, v153
	v_mov_b32_dpp v144, v156 row_ror:1 row_mask:0xf bank_mask:0xf
	v_mov_b32_e32 v156, 0
	v_pk_fma_f32 v[150:151], v[110:111], v[154:155], v[150:151]
	v_rcp_f32_e32 v152, v152
	v_mov_b32_dpp v156, v157 row_ror:15 row_mask:0xf bank_mask:0xf
	v_cndmask_b32_e64 v157, v129, v145, s[44:45]
	v_mov_b32_e32 v145, 0
	v_pk_add_f32 v[150:151], v[114:115], v[150:151]
	v_rcp_f32_e32 v153, v153
	v_mov_b32_dpp v145, v157 row_ror:1 row_mask:0xf bank_mask:0xf
	v_mul_f32_e32 v154, 0xbfb8aa3b, v150
	v_mul_f32_e32 v155, 0xbfb8aa3b, v151
	v_mov_b32_e32 v157, 0
	v_pk_mul_f32 v[144:145], v[80:81], v[144:145]
	v_exp_f32_e32 v154, v154
	v_exp_f32_e32 v155, v155
	v_mov_b32_dpp v157, v158 row_ror:15 row_mask:0xf bank_mask:0xf
	v_pk_fma_f32 v[144:145], v[128:129], v[84:85], v[144:145]
	v_cndmask_b32_e64 v158, v130, v146, s[44:45]
	v_mov_b32_e32 v146, 0
	v_pk_fma_f32 v[144:145], v[88:89], v[156:157], v[144:145]
	v_pk_mul_f32 v[140:141], v[140:141], v[148:149]
	v_mov_b32_dpp v146, v158 row_ror:1 row_mask:0xf bank_mask:0xf
	v_mov_b32_e32 v158, 0
	v_pk_add_f32 v[144:145], v[92:93], v[144:145]
	v_pk_mul_f32 v[140:141], v[140:141], v[152:153]
	v_mov_b32_dpp v158, v159 row_ror:15 row_mask:0xf bank_mask:0xf
	v_cndmask_b32_e64 v159, v131, v147, s[44:45]
	v_mov_b32_e32 v147, 0
	v_pk_mul_f32 v[142:143], v[142:143], v[150:151]
	v_add_f32_e32 v150, 1.0, v154
	v_add_f32_e32 v151, 1.0, v155
	v_cvt_pk_bf16_f32 v140, v140, v141
	v_mul_f32_e32 v141, 0xbfb8aa3b, v144
	v_mov_b32_dpp v147, v159 row_ror:1 row_mask:0xf bank_mask:0xf
	v_rcp_f32_e32 v150, v150
	v_rcp_f32_e32 v151, v151
	v_exp_f32_e32 v148, v141
	v_mul_f32_e32 v141, 0xbfb8aa3b, v145
	v_mov_b32_e32 v159, 0
	v_pk_mul_f32 v[146:147], v[82:83], v[146:147]
	v_exp_f32_e32 v149, v141
	v_mov_b32_dpp v159, v160 row_ror:15 row_mask:0xf bank_mask:0xf
	v_pk_fma_f32 v[146:147], v[130:131], v[86:87], v[146:147]
	v_pk_mul_f32 v[142:143], v[142:143], v[150:151]
	v_pk_fma_f32 v[146:147], v[90:91], v[158:159], v[146:147]
	v_cvt_pk_bf16_f32 v141, v142, v143
	v_pk_add_f32 v[146:147], v[94:95], v[146:147]
	v_add_f32_e32 v142, 1.0, v148
	v_add_f32_e32 v143, 1.0, v149
	v_mul_f32_e32 v148, 0xbfb8aa3b, v146
	v_mul_f32_e32 v149, 0xbfb8aa3b, v147
	v_exp_f32_e32 v148, v148
	v_exp_f32_e32 v149, v149
	v_rcp_f32_e32 v142, v142
	v_rcp_f32_e32 v143, v143
	v_pk_mul_f32 v[134:135], v[134:135], v[146:147]
	v_add_f32_e32 v146, 1.0, v148
	v_add_f32_e32 v147, 1.0, v149
	v_rcp_f32_e32 v146, v146
	v_rcp_f32_e32 v147, v147
	v_pk_mul_f32 v[132:133], v[132:133], v[144:145]
	v_add_u32_e32 v160, 16, v193
	v_pk_mul_f32 v[132:133], v[132:133], v[142:143]
	v_cndmask_b32_e32 v148, v107, v75, vcc
	v_cvt_pk_bf16_f32 v142, v132, v133
	v_pk_mul_f32 v[132:133], v[134:135], v[146:147]
	v_mov_b64_e32 v[134:135], s[54:55]
	v_cvt_pk_bf16_f32 v143, v132, v133
	v_mad_i64_i32 v[144:145], s[24:25], v160, s60, v[134:135]
	v_lshlrev_b64 v[132:133], 1, v[184:185]
	v_lshl_add_u64 v[144:145], v[144:145], 0, v[132:133]
	global_store_dwordx4 v[144:145], v[140:143], off
	v_cndmask_b32_e32 v144, v123, v79, vcc
	v_cndmask_b32_e32 v145, v104, v72, vcc
	v_cndmask_b32_e64 v140, v120, v136, s[44:45]
	v_mov_b32_e32 v136, 0
	v_cndmask_b32_e32 v141, v120, v76, vcc
	v_cndmask_b32_e32 v142, v121, v77, vcc
	v_mov_b32_dpp v136, v140 row_ror:1 row_mask:0xf bank_mask:0xf
	v_mov_b32_e32 v140, 0
	v_cndmask_b32_e32 v143, v122, v78, vcc
	v_cndmask_b32_e32 v146, v105, v73, vcc
	v_mov_b32_dpp v140, v141 row_ror:15 row_mask:0xf bank_mask:0xf
	v_cndmask_b32_e64 v141, v121, v137, s[44:45]
	v_mov_b32_e32 v137, 0
	v_cndmask_b32_e32 v147, v106, v74, vcc
	s_nop 0
	v_mov_b32_dpp v137, v141 row_ror:1 row_mask:0xf bank_mask:0xf
	v_mov_b32_e32 v141, 0
	v_pk_mul_f32 v[136:137], v[96:97], v[136:137]
	s_nop 0
	v_mov_b32_dpp v141, v142 row_ror:15 row_mask:0xf bank_mask:0xf
	v_pk_fma_f32 v[136:137], v[120:121], v[100:101], v[136:137]
	v_cndmask_b32_e64 v142, v122, v138, s[44:45]
	v_mov_b32_e32 v138, 0
	v_pk_fma_f32 v[136:137], v[108:109], v[140:141], v[136:137]
	s_nop 0
	v_mov_b32_dpp v138, v142 row_ror:1 row_mask:0xf bank_mask:0xf
	v_mov_b32_e32 v142, 0
	v_pk_add_f32 v[136:137], v[112:113], v[136:137]
	s_nop 0
	v_mov_b32_dpp v142, v143 row_ror:15 row_mask:0xf bank_mask:0xf
	v_cndmask_b32_e64 v143, v123, v139, s[44:45]
	v_mov_b32_e32 v139, 0
	v_mul_f32_e32 v140, 0xbfb8aa3b, v136
	v_mul_f32_e32 v141, 0xbfb8aa3b, v137
	v_mov_b32_dpp v139, v143 row_ror:1 row_mask:0xf bank_mask:0xf
	v_exp_f32_e32 v140, v140
	v_exp_f32_e32 v141, v141
	v_mov_b32_e32 v143, 0
	v_pk_mul_f32 v[138:139], v[98:99], v[138:139]
	v_add_f32_e32 v140, 1.0, v140
	v_mov_b32_dpp v143, v144 row_ror:15 row_mask:0xf bank_mask:0xf
	v_cndmask_b32_e64 v144, v104, v128, s[44:45]
	v_mov_b32_e32 v128, 0
	v_pk_fma_f32 v[138:139], v[122:123], v[102:103], v[138:139]
	v_add_f32_e32 v141, 1.0, v141
	v_mov_b32_dpp v128, v144 row_ror:1 row_mask:0xf bank_mask:0xf
	v_mov_b32_e32 v144, 0
	v_pk_fma_f32 v[138:139], v[110:111], v[142:143], v[138:139]
	v_rcp_f32_e32 v140, v140
	v_mov_b32_dpp v144, v145 row_ror:15 row_mask:0xf bank_mask:0xf
	v_cndmask_b32_e64 v145, v105, v129, s[44:45]
	v_mov_b32_e32 v129, 0
	v_pk_add_f32 v[138:139], v[114:115], v[138:139]
	v_rcp_f32_e32 v141, v141
	v_mov_b32_dpp v129, v145 row_ror:1 row_mask:0xf bank_mask:0xf
	v_mul_f32_e32 v142, 0xbfb8aa3b, v138
	v_mul_f32_e32 v143, 0xbfb8aa3b, v139
	v_mov_b32_e32 v145, 0
	v_pk_mul_f32 v[128:129], v[80:81], v[128:129]
	v_exp_f32_e32 v142, v142
	v_exp_f32_e32 v143, v143
; DI unsigned pack2(float a, float b) { f32x2 v = {a, b}; hwbf16x2 r = __builtin_convertvector(v, hwbf16x2); return __builtin_bit_cast(unsigned, r); }
; DI float dpp_ror1(float v)  { return __builtin_bit_cast(float, __builtin_amdgcn_update_dpp(0, __builtin_bit_cast(int, v), 0x121, 0xf, 0xf, false)); }
;     DI void operator()(const f32x4 (&acc)[2][2][4][2], const Unit& u, int wr, int wc, int fr, int fq) const {
;     ...
;                 const bool efirst = (m == 0) && (fr == 0), elast = (m == 3) && (fr == 15);
;                 const int row = row0 + ai * HALF + m * 16;
;                 f32x4 gc[2];
; #pragma unroll
;                 for (int n = 0; n < 2; ++n) {
;                     const f32x4 g = acc[ai][0][m][n];
;                     const f32x4 gprev = acc[ai][0][m > 0 ? m - 1 : 0][n], gnext = acc[ai][0][m < 3 ? m + 1 : 3][n];
;                     f32x4 up, dn;
; #pragma unroll
;                     for (int e = 0; e < 4; ++e) {
;                         const float pu = (m > 0 && fr == 15) ? gprev[e] : g[e];
;                         const float pd = (m < 3 && fr == 0) ? gnext[e] : g[e];
;                         up[e] = dpp_ror1(pu); dn[e] = dpp_ror15(pd);
;                     }
;                     if (efirst) up = (f32x4){0.f, 0.f, 0.f, 0.f};
;                     if (elast) dn = (f32x4){0.f, 0.f, 0.f, 0.f};
;                     gc[n] = w0[n] * up + w1[n] * g + w2[n] * dn + bb[n];
;                 }
;                 if (efirst || elast) {
;                     const size_t eo = (size_t)((row >> 6) * 2 + (elast ? 1 : 0)) * DFF + ch0;
; #pragma unroll
;                     for (int n = 0; n < 2; ++n) { *(f32x4*)(EP + eo + 4 * n) = gc[n]; *(f32x4*)(ER + eo + 4 * n) = acc[ai][0][m][n]; *(f32x4*)(EV + eo + 4 * n) = acc[ai][1][m][n]; }
;                 } else {
;                     const f32x4 v0 = acc[ai][1][m][0], v1 = acc[ai][1][m][1];
;                     u32x4 o;
;                     o[0] = pack2(silu_mul(gc[0][0], v0[0]), silu_mul(gc[0][1], v0[1])); o[1] = pack2(silu_mul(gc[0][2], v0[2]), silu_mul(gc[0][3], v0[3]));
;                     o[2] = pack2(silu_mul(gc[1][0], v1[0]), silu_mul(gc[1][1], v1[1])); o[3] = pack2(silu_mul(gc[1][2], v1[2]), silu_mul(gc[1][3], v1[3]));
;                     *(u32x4*)(ACT + (size_t)row * DFF + ch0) = o;
;                 }
	v_mov_b32_dpp v145, v146 row_ror:15 row_mask:0xf bank_mask:0xf
	v_pk_fma_f32 v[128:129], v[104:105], v[84:85], v[128:129]
	v_cndmask_b32_e64 v146, v106, v130, s[44:45]
	v_mov_b32_e32 v130, 0
	v_pk_fma_f32 v[128:129], v[88:89], v[144:145], v[128:129]
	v_pk_mul_f32 v[124:125], v[124:125], v[136:137]
	v_mov_b32_dpp v130, v146 row_ror:1 row_mask:0xf bank_mask:0xf
	v_mov_b32_e32 v146, 0
	v_pk_add_f32 v[128:129], v[92:93], v[128:129]
	v_pk_mul_f32 v[124:125], v[124:125], v[140:141]
	v_mov_b32_dpp v146, v147 row_ror:15 row_mask:0xf bank_mask:0xf
	v_cndmask_b32_e64 v147, v107, v131, s[44:45]
	v_mov_b32_e32 v131, 0
	v_pk_mul_f32 v[126:127], v[126:127], v[138:139]
	v_add_f32_e32 v138, 1.0, v142
	v_add_f32_e32 v139, 1.0, v143
	v_cvt_pk_bf16_f32 v124, v124, v125
	v_mul_f32_e32 v125, 0xbfb8aa3b, v128
	v_mov_b32_dpp v131, v147 row_ror:1 row_mask:0xf bank_mask:0xf
	v_rcp_f32_e32 v138, v138
	v_rcp_f32_e32 v139, v139
	v_exp_f32_e32 v136, v125
	v_mul_f32_e32 v125, 0xbfb8aa3b, v129
	v_mov_b32_e32 v147, 0
	v_pk_mul_f32 v[130:131], v[82:83], v[130:131]
	v_exp_f32_e32 v137, v125
	v_mov_b32_dpp v147, v148 row_ror:15 row_mask:0xf bank_mask:0xf
	v_pk_fma_f32 v[130:131], v[106:107], v[86:87], v[130:131]
	v_pk_mul_f32 v[126:127], v[126:127], v[138:139]
	v_pk_fma_f32 v[130:131], v[90:91], v[146:147], v[130:131]
	v_cvt_pk_bf16_f32 v125, v126, v127
	v_pk_add_f32 v[130:131], v[94:95], v[130:131]
	v_add_f32_e32 v126, 1.0, v136
	v_add_f32_e32 v127, 1.0, v137
	v_mul_f32_e32 v136, 0xbfb8aa3b, v130
	v_mul_f32_e32 v137, 0xbfb8aa3b, v131
	v_exp_f32_e32 v136, v136
	v_exp_f32_e32 v137, v137
	v_rcp_f32_e32 v126, v126
	v_rcp_f32_e32 v127, v127
	v_pk_mul_f32 v[118:119], v[118:119], v[130:131]
	v_add_f32_e32 v130, 1.0, v136
	v_add_f32_e32 v131, 1.0, v137
	v_rcp_f32_e32 v130, v130
	v_rcp_f32_e32 v131, v131
	v_pk_mul_f32 v[116:117], v[116:117], v[128:129]
	v_add_u32_e32 v148, 32, v193
	v_pk_mul_f32 v[116:117], v[116:117], v[126:127]
	s_nop 0
	v_cvt_pk_bf16_f32 v126, v116, v117
	v_pk_mul_f32 v[116:117], v[118:119], v[130:131]
	v_cndmask_b32_e64 v118, v77, v121, s[44:45]
	v_cvt_pk_bf16_f32 v127, v116, v117
	v_mad_i64_i32 v[116:117], s[24:25], v148, s60, v[134:135]
	v_lshl_add_u64 v[116:117], v[116:117], 0, v[132:133]
	global_store_dwordx4 v[116:117], v[124:127], off
	v_cndmask_b32_e64 v117, v76, v120, s[44:45]
	v_mov_b32_e32 v116, 0
	v_cndmask_b32_e64 v119, v78, v122, s[44:45]
	v_cndmask_b32_e64 v121, v79, v123, s[44:45]
	v_mov_b32_dpp v116, v117 row_ror:1 row_mask:0xf bank_mask:0xf
	v_mov_b32_e32 v117, 0
	v_mov_b32_e32 v120, 0
	v_mov_b32_e32 v124, 0
	v_mov_b32_dpp v117, v118 row_ror:1 row_mask:0xf bank_mask:0xf
	v_mov_b32_e32 v118, 0
	v_mov_b32_dpp v120, v78 row_ror:15 row_mask:0xf bank_mask:0xf
	v_cndmask_b32_e64 v120, v120, 0, s[44:45]
	v_mov_b32_dpp v118, v119 row_ror:1 row_mask:0xf bank_mask:0xf
	v_mov_b32_e32 v119, 0
	v_mov_b32_e32 v125, 0
	v_mov_b32_dpp v124, v76 row_ror:15 row_mask:0xf bank_mask:0xf
	v_mov_b32_dpp v119, v121 row_ror:1 row_mask:0xf bank_mask:0xf
	v_mov_b32_e32 v121, 0
	v_pk_mul_f32 v[118:119], v[98:99], v[118:119]
	v_mov_b32_dpp v125, v77 row_ror:15 row_mask:0xf bank_mask:0xf
	v_mov_b32_dpp v121, v79 row_ror:15 row_mask:0xf bank_mask:0xf
	v_cndmask_b32_e64 v121, v121, 0, s[44:45]
	v_pk_fma_f32 v[118:119], v[78:79], v[102:103], v[118:119]
	v_pk_mul_f32 v[116:117], v[96:97], v[116:117]
	v_pk_fma_f32 v[118:119], v[110:111], v[120:121], v[118:119]
	v_cndmask_b32_e64 v120, v72, v104, s[44:45]
	v_mov_b32_e32 v104, 0
	v_cndmask_b32_e64 v123, v125, 0, s[44:45]
	v_cndmask_b32_e64 v122, v124, 0, s[44:45]
	v_mov_b32_dpp v104, v120 row_ror:1 row_mask:0xf bank_mask:0xf
	v_cndmask_b32_e64 v120, v73, v105, s[44:45]
	v_mov_b32_e32 v105, 0
	v_pk_fma_f32 v[116:117], v[76:77], v[100:101], v[116:117]
	v_cndmask_b32_e64 v121, v75, v107, s[44:45]
	v_mov_b32_dpp v105, v120 row_ror:1 row_mask:0xf bank_mask:0xf
	v_cndmask_b32_e64 v120, v74, v106, s[44:45]
	v_mov_b32_e32 v106, 0
	v_mov_b32_e32 v107, 0
	v_pk_fma_f32 v[116:117], v[108:109], v[122:123], v[116:117]
	v_mov_b32_e32 v122, 0
	v_mov_b32_e32 v123, 0
	v_mov_b32_dpp v106, v120 row_ror:1 row_mask:0xf bank_mask:0xf
	v_mov_b32_e32 v120, 0
	v_mov_b32_dpp v107, v121 row_ror:1 row_mask:0xf bank_mask:0xf
	v_mov_b32_e32 v121, 0
	v_mov_b32_dpp v122, v72 row_ror:15 row_mask:0xf bank_mask:0xf
	v_mov_b32_dpp v123, v73 row_ror:15 row_mask:0xf bank_mask:0xf
	v_mov_b32_dpp v120, v74 row_ror:15 row_mask:0xf bank_mask:0xf
	v_mov_b32_dpp v121, v75 row_ror:15 row_mask:0xf bank_mask:0xf
	v_pk_mul_f32 v[104:105], v[80:81], v[104:105]
	v_pk_mul_f32 v[106:107], v[82:83], v[106:107]
	v_cndmask_b32_e64 v121, v121, 0, s[44:45]
	v_cndmask_b32_e64 v120, v120, 0, s[44:45]
	v_cndmask_b32_e64 v123, v123, 0, s[44:45]
	v_cndmask_b32_e64 v122, v122, 0, s[44:45]
	v_pk_fma_f32 v[106:107], v[74:75], v[86:87], v[106:107]
	v_pk_fma_f32 v[104:105], v[72:73], v[84:85], v[104:105]
	v_pk_fma_f32 v[106:107], v[90:91], v[120:121], v[106:107]
	v_pk_fma_f32 v[104:105], v[88:89], v[122:123], v[104:105]
	v_pk_add_f32 v[118:119], v[114:115], v[118:119]
	v_pk_add_f32 v[116:117], v[112:113], v[116:117]
	v_pk_add_f32 v[106:107], v[94:95], v[106:107]
	v_pk_add_f32 v[104:105], v[92:93], v[104:105]
	v_add_u32_e32 v120, 48, v193
	s_and_saveexec_b64 s[24:25], s[42:43]
	s_xor_b64 s[24:25], exec, s[24:25]
	s_cbranch_execz .LBB1_1076
	v_mul_f32_e32 v121, 0xbfb8aa3b, v116
	v_exp_f32_e32 v121, v121
	v_mul_f32_e32 v122, 0xbfb8aa3b, v117
	v_exp_f32_e32 v122, v122
	v_mul_f32_e32 v124, 0xbfb8aa3b, v119
	v_add_f32_e32 v121, 1.0, v121
	v_exp_f32_e32 v125, v124
	v_add_f32_e32 v123, 1.0, v122
	v_rcp_f32_e32 v122, v121
	v_mul_f32_e32 v121, 0xbfb8aa3b, v118
	v_exp_f32_e32 v121, v121
	v_rcp_f32_e32 v123, v123
	v_pk_mul_f32 v[116:117], v[68:69], v[116:117]
	v_pk_mul_f32 v[118:119], v[70:71], v[118:119]
	v_add_f32_e32 v121, 1.0, v121
	v_rcp_f32_e32 v124, v121
	v_add_f32_e32 v121, 1.0, v125
	v_pk_mul_f32 v[116:117], v[116:117], v[122:123]
	v_rcp_f32_e32 v125, v121
	v_cvt_pk_bf16_f32 v116, v116, v117
	v_mul_f32_e32 v117, 0xbfb8aa3b, v104
	v_exp_f32_e32 v121, v117
	v_mul_f32_e32 v117, 0xbfb8aa3b, v105
	v_exp_f32_e32 v122, v117
	v_pk_mul_f32 v[118:119], v[118:119], v[124:125]
	v_pk_mul_f32 v[104:105], v[64:65], v[104:105]
	v_cvt_pk_bf16_f32 v117, v118, v119
	v_add_f32_e32 v118, 1.0, v121
	v_mul_f32_e32 v121, 0xbfb8aa3b, v106
	v_add_f32_e32 v119, 1.0, v122
	v_exp_f32_e32 v121, v121
	v_mul_f32_e32 v122, 0xbfb8aa3b, v107
	v_exp_f32_e32 v123, v122
	v_rcp_f32_e32 v118, v118
	v_add_f32_e32 v121, 1.0, v121
	v_rcp_f32_e32 v119, v119
	v_rcp_f32_e32 v122, v121
	v_add_f32_e32 v121, 1.0, v123
	v_rcp_f32_e32 v123, v121
	v_pk_mul_f32 v[106:107], v[66:67], v[106:107]
	v_pk_mul_f32 v[104:105], v[104:105], v[118:119]
	s_nop 0
	v_cvt_pk_bf16_f32 v118, v104, v105
	v_pk_mul_f32 v[104:105], v[106:107], v[122:123]
	s_nop 0
	v_cvt_pk_bf16_f32 v119, v104, v105
	v_mov_b64_e32 v[104:105], s[54:55]
	v_mad_i64_i32 v[104:105], s[58:59], v120, s60, v[104:105]
	v_lshl_add_u64 v[104:105], v[184:185], 1, v[104:105]
	global_store_dwordx4 v[104:105], v[116:119], off
; DI unsigned pack2(float a, float b) { f32x2 v = {a, b}; hwbf16x2 r = __builtin_convertvector(v, hwbf16x2); return __builtin_bit_cast(unsigned, r); }
; DI float dpp_ror1(float v)  { return __builtin_bit_cast(float, __builtin_amdgcn_update_dpp(0, __builtin_bit_cast(int, v), 0x121, 0xf, 0xf, false)); }
;     DI void operator()(const f32x4 (&acc)[2][2][4][2], const Unit& u, int wr, int wc, int fr, int fq) const {
;     ...
;                 const bool efirst = (m == 0) && (fr == 0), elast = (m == 3) && (fr == 15);
;                 const int row = row0 + ai * HALF + m * 16;
;                 f32x4 gc[2];
; #pragma unroll
;                 for (int n = 0; n < 2; ++n) {
;                     const f32x4 g = acc[ai][0][m][n];
;                     const f32x4 gprev = acc[ai][0][m > 0 ? m - 1 : 0][n], gnext = acc[ai][0][m < 3 ? m + 1 : 3][n];
;                     f32x4 up, dn;
; #pragma unroll
;                     for (int e = 0; e < 4; ++e) {
;                         const float pu = (m > 0 && fr == 15) ? gprev[e] : g[e];
;                         const float pd = (m < 3 && fr == 0) ? gnext[e] : g[e];
;                         up[e] = dpp_ror1(pu); dn[e] = dpp_ror15(pd);
;                     }
;                     if (efirst) up = (f32x4){0.f, 0.f, 0.f, 0.f};
;                     if (elast) dn = (f32x4){0.f, 0.f, 0.f, 0.f};
;                     gc[n] = w0[n] * up + w1[n] * g + w2[n] * dn + bb[n];
;                 }
;                 if (efirst || elast) {
;                     const size_t eo = (size_t)((row >> 6) * 2 + (elast ? 1 : 0)) * DFF + ch0;
; #pragma unroll
;                     for (int n = 0; n < 2; ++n) { *(f32x4*)(EP + eo + 4 * n) = gc[n]; *(f32x4*)(ER + eo + 4 * n) = acc[ai][0][m][n]; *(f32x4*)(EV + eo + 4 * n) = acc[ai][1][m][n]; }
;                 } else {
;                     const f32x4 v0 = acc[ai][1][m][0], v1 = acc[ai][1][m][1];
;                     u32x4 o;
;                     o[0] = pack2(silu_mul(gc[0][0], v0[0]), silu_mul(gc[0][1], v0[1])); o[1] = pack2(silu_mul(gc[0][2], v0[2]), silu_mul(gc[0][3], v0[3]));
;                     o[2] = pack2(silu_mul(gc[1][0], v1[0]), silu_mul(gc[1][1], v1[1])); o[3] = pack2(silu_mul(gc[1][2], v1[2]), silu_mul(gc[1][3], v1[3]));
;                     *(u32x4*)(ACT + (size_t)row * DFF + ch0) = o;
;                 }
.LBB1_1076:
	s_or_saveexec_b64 s[24:25], s[24:25]
	s_mov_b64 s[68:69], s[72:73]
	s_xor_b64 exec, exec, s[24:25]
	s_cbranch_execz .LBB1_1078
	v_ashrrev_i32_e32 v120, 5, v120
	v_mad_i64_i32 v[120:121], s[58:59], v120, s61, v[184:185]
	v_lshlrev_b64 v[120:121], 2, v[120:121]
	v_lshl_add_u64 v[122:123], s[8:9], 0, v[120:121]
	global_store_dwordx4 v[122:123], v[116:119], off
	s_nop 1
	v_lshl_add_u64 v[116:117], s[10:11], 0, v[120:121]
	global_store_dwordx4 v[116:117], v[76:79], off
	s_nop 1
	v_lshl_add_u64 v[76:77], s[12:13], 0, v[120:121]
	global_store_dwordx4 v[76:77], v[68:71], off
	global_store_dwordx4 v[122:123], v[104:107], off offset:16
	global_store_dwordx4 v[116:117], v[72:75], off offset:16
	global_store_dwordx4 v[76:77], v[64:67], off offset:16
.LBB1_1078:
	s_or_b64 exec, exec, s[24:25]
	s_nop 0
	v_cndmask_b32_e32 v65, v60, v40, vcc
	v_mov_b32_e32 v64, 0
	v_cndmask_b32_e32 v66, v61, v41, vcc
	v_cndmask_b32_e32 v67, v62, v42, vcc
	v_mov_b32_dpp v64, v65 row_ror:15 row_mask:0xf bank_mask:0xf
	v_mov_b32_e32 v65, 0
	v_mov_b32_e32 v68, 0
	v_mov_b32_e32 v73, 0
	v_mov_b32_dpp v65, v66 row_ror:15 row_mask:0xf bank_mask:0xf
	v_mov_b32_e32 v66, 0
	v_mov_b32_e32 v70, 0
	v_mov_b32_e32 v71, 0
	v_mov_b32_dpp v68, v62 row_ror:1 row_mask:0xf bank_mask:0xf
	v_mov_b32_dpp v66, v67 row_ror:15 row_mask:0xf bank_mask:0xf
	v_cndmask_b32_e32 v69, v63, v43, vcc
	v_mov_b32_dpp v73, v63 row_ror:1 row_mask:0xf bank_mask:0xf
	v_mov_b32_e32 v67, 0
	v_mov_b32_dpp v70, v60 row_ror:1 row_mask:0xf bank_mask:0xf
	v_mov_b32_dpp v71, v61 row_ror:1 row_mask:0xf bank_mask:0xf
	v_mov_b32_dpp v67, v69 row_ror:15 row_mask:0xf bank_mask:0xf
	v_cndmask_b32_e64 v69, v73, 0, vcc
	v_cndmask_b32_e64 v68, v68, 0, vcc
	v_cndmask_b32_e64 v71, v71, 0, vcc
	v_cndmask_b32_e64 v70, v70, 0, vcc
	v_pk_mul_f32 v[68:69], v[98:99], v[68:69]
	v_pk_mul_f32 v[70:71], v[96:97], v[70:71]
	v_pk_fma_f32 v[68:69], v[62:63], v[102:103], v[68:69]
	v_pk_fma_f32 v[70:71], v[60:61], v[100:101], v[70:71]
	v_pk_fma_f32 v[66:67], v[110:111], v[66:67], v[68:69]
	v_cndmask_b32_e32 v69, v48, v32, vcc
	v_mov_b32_e32 v68, 0
	v_pk_fma_f32 v[64:65], v[108:109], v[64:65], v[70:71]
	v_cndmask_b32_e32 v70, v49, v33, vcc
	v_mov_b32_dpp v68, v69 row_ror:15 row_mask:0xf bank_mask:0xf
	v_mov_b32_e32 v69, 0
	v_mov_b32_e32 v73, 0
	v_mov_b32_e32 v76, 0
	v_mov_b32_dpp v69, v70 row_ror:15 row_mask:0xf bank_mask:0xf
	v_cndmask_b32_e32 v71, v50, v34, vcc
	v_mov_b32_e32 v74, 0
	v_mov_b32_e32 v70, 0
	v_mov_b32_e32 v77, 0
	v_mov_b32_dpp v73, v48 row_ror:1 row_mask:0xf bank_mask:0xf
	v_mov_b32_dpp v76, v49 row_ror:1 row_mask:0xf bank_mask:0xf
	v_mov_b32_dpp v74, v50 row_ror:1 row_mask:0xf bank_mask:0xf
	v_mov_b32_dpp v70, v71 row_ror:15 row_mask:0xf bank_mask:0xf
	v_cndmask_b32_e32 v75, v51, v35, vcc
	v_mov_b32_dpp v77, v51 row_ror:1 row_mask:0xf bank_mask:0xf
	v_mov_b32_e32 v71, 0
	v_cndmask_b32_e64 v74, v74, 0, vcc
	v_add_u32_e32 v72, 0x80, v193
	v_mov_b32_dpp v71, v75 row_ror:15 row_mask:0xf bank_mask:0xf
	v_cndmask_b32_e64 v75, v77, 0, vcc
	v_cndmask_b32_e64 v77, v76, 0, vcc
	v_cndmask_b32_e64 v76, v73, 0, vcc
	v_pk_mul_f32 v[76:77], v[80:81], v[76:77]
	v_pk_mul_f32 v[74:75], v[82:83], v[74:75]
	v_pk_fma_f32 v[76:77], v[48:49], v[84:85], v[76:77]
	v_pk_fma_f32 v[74:75], v[50:51], v[86:87], v[74:75]
	v_pk_fma_f32 v[68:69], v[88:89], v[68:69], v[76:77]
	v_pk_fma_f32 v[70:71], v[90:91], v[70:71], v[74:75]
	v_pk_add_f32 v[66:67], v[114:115], v[66:67]
	v_pk_add_f32 v[64:65], v[112:113], v[64:65]
	v_pk_add_f32 v[70:71], v[94:95], v[70:71]
	v_pk_add_f32 v[68:69], v[92:93], v[68:69]
	s_and_saveexec_b64 s[24:25], s[46:47]
	s_xor_b64 s[24:25], exec, s[24:25]
	s_cbranch_execz .LBB1_1080
	v_mul_f32_e32 v73, 0xbfb8aa3b, v64
	v_exp_f32_e32 v73, v73
	v_mul_f32_e32 v74, 0xbfb8aa3b, v65
	v_exp_f32_e32 v74, v74
	v_mul_f32_e32 v76, 0xbfb8aa3b, v67
	v_add_f32_e32 v73, 1.0, v73
	v_exp_f32_e32 v77, v76
	v_add_f32_e32 v75, 1.0, v74
	v_rcp_f32_e32 v74, v73
	v_mul_f32_e32 v73, 0xbfb8aa3b, v66
	v_exp_f32_e32 v73, v73
	v_rcp_f32_e32 v75, v75
	v_pk_mul_f32 v[64:65], v[56:57], v[64:65]
	v_pk_mul_f32 v[66:67], v[58:59], v[66:67]
	v_add_f32_e32 v73, 1.0, v73
	v_rcp_f32_e32 v76, v73
	v_add_f32_e32 v73, 1.0, v77
	v_pk_mul_f32 v[64:65], v[64:65], v[74:75]
	v_rcp_f32_e32 v77, v73
	v_cvt_pk_bf16_f32 v64, v64, v65
	v_mul_f32_e32 v65, 0xbfb8aa3b, v68
	v_exp_f32_e32 v73, v65
	v_mul_f32_e32 v65, 0xbfb8aa3b, v69
	v_exp_f32_e32 v74, v65
	v_pk_mul_f32 v[66:67], v[66:67], v[76:77]
	v_pk_mul_f32 v[68:69], v[52:53], v[68:69]
	v_cvt_pk_bf16_f32 v65, v66, v67
	v_add_f32_e32 v66, 1.0, v73
	v_mul_f32_e32 v73, 0xbfb8aa3b, v70
	v_add_f32_e32 v67, 1.0, v74
	v_exp_f32_e32 v73, v73
	v_mul_f32_e32 v74, 0xbfb8aa3b, v71
	v_exp_f32_e32 v75, v74
	v_rcp_f32_e32 v66, v66
	v_add_f32_e32 v73, 1.0, v73
	v_rcp_f32_e32 v74, v73
	v_add_f32_e32 v73, 1.0, v75
	v_rcp_f32_e32 v67, v67
	v_rcp_f32_e32 v75, v73
	v_pk_mul_f32 v[70:71], v[54:55], v[70:71]
	v_pk_mul_f32 v[66:67], v[68:69], v[66:67]
	v_pk_mul_f32 v[68:69], v[70:71], v[74:75]
	v_cvt_pk_bf16_f32 v66, v66, v67
	v_cvt_pk_bf16_f32 v67, v68, v69
	v_mov_b64_e32 v[68:69], s[54:55]
	v_mad_i64_i32 v[68:69], s[46:47], v72, s60, v[68:69]
	v_lshl_add_u64 v[68:69], v[184:185], 1, v[68:69]
	global_store_dwordx4 v[68:69], v[64:67], off
.LBB1_1080:
	s_andn2_saveexec_b64 s[24:25], s[24:25]
	s_cbranch_execz .LBB1_1082
	v_ashrrev_i32_e32 v72, 5, v72
	v_mad_i64_i32 v[72:73], s[46:47], v72, s61, v[184:185]
	v_lshlrev_b64 v[72:73], 2, v[72:73]
	v_lshl_add_u64 v[74:75], s[8:9], 0, v[72:73]
	global_store_dwordx4 v[74:75], v[64:67], off
	s_nop 1
	v_lshl_add_u64 v[64:65], s[10:11], 0, v[72:73]
	v_lshl_add_u64 v[66:67], s[12:13], 0, v[72:73]
	global_store_dwordx4 v[64:65], v[60:63], off
	global_store_dwordx4 v[66:67], v[56:59], off
	global_store_dwordx4 v[74:75], v[68:71], off offset:16
	global_store_dwordx4 v[64:65], v[48:51], off offset:16
	global_store_dwordx4 v[66:67], v[52:55], off offset:16
; DI unsigned pack2(float a, float b) { f32x2 v = {a, b}; hwbf16x2 r = __builtin_convertvector(v, hwbf16x2); return __builtin_bit_cast(unsigned, r); }
; DI float dpp_ror1(float v)  { return __builtin_bit_cast(float, __builtin_amdgcn_update_dpp(0, __builtin_bit_cast(int, v), 0x121, 0xf, 0xf, false)); }
;     DI void operator()(const f32x4 (&acc)[2][2][4][2], const Unit& u, int wr, int wc, int fr, int fq) const {
;     ...
;                 const bool efirst = (m == 0) && (fr == 0), elast = (m == 3) && (fr == 15);
;                 const int row = row0 + ai * HALF + m * 16;
;                 f32x4 gc[2];
; #pragma unroll
;                 for (int n = 0; n < 2; ++n) {
;                     const f32x4 g = acc[ai][0][m][n];
;                     const f32x4 gprev = acc[ai][0][m > 0 ? m - 1 : 0][n], gnext = acc[ai][0][m < 3 ? m + 1 : 3][n];
;                     f32x4 up, dn;
; #pragma unroll
;                     for (int e = 0; e < 4; ++e) {
;                         const float pu = (m > 0 && fr == 15) ? gprev[e] : g[e];
;                         const float pd = (m < 3 && fr == 0) ? gnext[e] : g[e];
;                         up[e] = dpp_ror1(pu); dn[e] = dpp_ror15(pd);
;                     }
;                     if (efirst) up = (f32x4){0.f, 0.f, 0.f, 0.f};
;                     if (elast) dn = (f32x4){0.f, 0.f, 0.f, 0.f};
;                     gc[n] = w0[n] * up + w1[n] * g + w2[n] * dn + bb[n];
;                 }
;                 if (efirst || elast) {
;                     const size_t eo = (size_t)((row >> 6) * 2 + (elast ? 1 : 0)) * DFF + ch0;
; #pragma unroll
;                     for (int n = 0; n < 2; ++n) { *(f32x4*)(EP + eo + 4 * n) = gc[n]; *(f32x4*)(ER + eo + 4 * n) = acc[ai][0][m][n]; *(f32x4*)(EV + eo + 4 * n) = acc[ai][1][m][n]; }
;                 } else {
;                     const f32x4 v0 = acc[ai][1][m][0], v1 = acc[ai][1][m][1];
;                     u32x4 o;
;                     o[0] = pack2(silu_mul(gc[0][0], v0[0]), silu_mul(gc[0][1], v0[1])); o[1] = pack2(silu_mul(gc[0][2], v0[2]), silu_mul(gc[0][3], v0[3]));
;                     o[2] = pack2(silu_mul(gc[1][0], v1[0]), silu_mul(gc[1][1], v1[1])); o[3] = pack2(silu_mul(gc[1][2], v1[2]), silu_mul(gc[1][3], v1[3]));
;                     *(u32x4*)(ACT + (size_t)row * DFF + ch0) = o;
.LBB1_1082:
	s_or_b64 exec, exec, s[24:25]
	s_nop 0
	v_cndmask_b32_e64 v53, v40, v60, s[44:45]
	v_cndmask_b32_e32 v55, v40, v24, vcc
	v_mov_b32_e32 v52, 0
	v_mov_b32_e32 v54, 0
	v_cndmask_b32_e32 v56, v41, v25, vcc
	v_mov_b32_dpp v52, v53 row_ror:1 row_mask:0xf bank_mask:0xf
	v_mov_b32_dpp v54, v55 row_ror:15 row_mask:0xf bank_mask:0xf
	v_cndmask_b32_e64 v55, v41, v61, s[44:45]
	v_mov_b32_e32 v53, 0
	v_cndmask_b32_e64 v57, v42, v62, s[44:45]
	v_cndmask_b32_e32 v59, v42, v26, vcc
	v_mov_b32_dpp v53, v55 row_ror:1 row_mask:0xf bank_mask:0xf
	v_mov_b32_e32 v55, 0
	v_mov_b32_e32 v58, 0
	v_pk_mul_f32 v[52:53], v[96:97], v[52:53]
	v_mov_b32_dpp v55, v56 row_ror:15 row_mask:0xf bank_mask:0xf
	v_mov_b32_e32 v56, 0
	v_mov_b32_dpp v58, v59 row_ror:15 row_mask:0xf bank_mask:0xf
	v_cndmask_b32_e64 v59, v43, v63, s[44:45]
	v_mov_b32_dpp v56, v57 row_ror:1 row_mask:0xf bank_mask:0xf
	v_mov_b32_e32 v57, 0
	v_pk_fma_f32 v[52:53], v[40:41], v[100:101], v[52:53]
	v_cndmask_b32_e32 v60, v43, v27, vcc
	v_mov_b32_dpp v57, v59 row_ror:1 row_mask:0xf bank_mask:0xf
	v_pk_fma_f32 v[52:53], v[108:109], v[54:55], v[52:53]
	v_mov_b32_e32 v59, 0
	v_pk_mul_f32 v[56:57], v[98:99], v[56:57]
	v_pk_add_f32 v[52:53], v[112:113], v[52:53]
	v_mov_b32_dpp v59, v60 row_ror:15 row_mask:0xf bank_mask:0xf
	v_pk_fma_f32 v[56:57], v[42:43], v[102:103], v[56:57]
	v_mul_f32_e32 v54, 0xbfb8aa3b, v52
	v_pk_fma_f32 v[56:57], v[110:111], v[58:59], v[56:57]
	v_exp_f32_e32 v58, v54
	v_mul_f32_e32 v54, 0xbfb8aa3b, v53
	v_exp_f32_e32 v59, v54
	v_cndmask_b32_e64 v60, v32, v48, s[44:45]
	v_mov_b32_e32 v48, 0
	v_cndmask_b32_e32 v61, v32, v16, vcc
	v_pk_add_f32 v[54:55], v[114:115], v[56:57]
	v_mov_b32_dpp v48, v60 row_ror:1 row_mask:0xf bank_mask:0xf
	v_mov_b32_e32 v60, 0
	v_add_f32_e32 v56, 1.0, v58
	v_add_f32_e32 v57, 1.0, v59
	v_mov_b32_dpp v60, v61 row_ror:15 row_mask:0xf bank_mask:0xf
	v_cndmask_b32_e64 v61, v33, v49, s[44:45]
	v_mov_b32_e32 v49, 0
	v_rcp_f32_e32 v56, v56
	v_rcp_f32_e32 v57, v57
	v_mov_b32_dpp v49, v61 row_ror:1 row_mask:0xf bank_mask:0xf
	v_mul_f32_e32 v58, 0xbfb8aa3b, v54
	v_mul_f32_e32 v59, 0xbfb8aa3b, v55
	v_cndmask_b32_e32 v62, v33, v17, vcc
	v_mov_b32_e32 v61, 0
	v_pk_mul_f32 v[48:49], v[80:81], v[48:49]
	v_exp_f32_e32 v58, v58
	v_exp_f32_e32 v59, v59
	v_mov_b32_dpp v61, v62 row_ror:15 row_mask:0xf bank_mask:0xf
	v_pk_fma_f32 v[48:49], v[32:33], v[84:85], v[48:49]
	v_cndmask_b32_e64 v62, v34, v50, s[44:45]
	v_mov_b32_e32 v50, 0
	v_pk_fma_f32 v[48:49], v[88:89], v[60:61], v[48:49]
	v_pk_mul_f32 v[44:45], v[44:45], v[52:53]
	v_cndmask_b32_e32 v63, v34, v18, vcc
	v_mov_b32_dpp v50, v62 row_ror:1 row_mask:0xf bank_mask:0xf
	v_mov_b32_e32 v62, 0
	v_pk_add_f32 v[48:49], v[92:93], v[48:49]
	v_pk_mul_f32 v[44:45], v[44:45], v[56:57]
	v_mov_b32_dpp v62, v63 row_ror:15 row_mask:0xf bank_mask:0xf
	v_cndmask_b32_e64 v63, v35, v51, s[44:45]
	v_mov_b32_e32 v51, 0
	v_pk_mul_f32 v[46:47], v[46:47], v[54:55]
	v_add_f32_e32 v54, 1.0, v58
	v_add_f32_e32 v55, 1.0, v59
	v_cvt_pk_bf16_f32 v44, v44, v45
	v_mul_f32_e32 v45, 0xbfb8aa3b, v48
	v_mov_b32_dpp v51, v63 row_ror:1 row_mask:0xf bank_mask:0xf
	v_rcp_f32_e32 v54, v54
	v_rcp_f32_e32 v55, v55
	v_exp_f32_e32 v52, v45
	v_mul_f32_e32 v45, 0xbfb8aa3b, v49
	v_cndmask_b32_e32 v64, v35, v19, vcc
	v_mov_b32_e32 v63, 0
	v_pk_mul_f32 v[50:51], v[82:83], v[50:51]
	v_exp_f32_e32 v53, v45
	v_mov_b32_dpp v63, v64 row_ror:15 row_mask:0xf bank_mask:0xf
	v_pk_fma_f32 v[50:51], v[34:35], v[86:87], v[50:51]
	v_pk_mul_f32 v[46:47], v[46:47], v[54:55]
	v_pk_fma_f32 v[50:51], v[90:91], v[62:63], v[50:51]
	v_cvt_pk_bf16_f32 v45, v46, v47
	v_pk_add_f32 v[50:51], v[94:95], v[50:51]
	v_add_f32_e32 v46, 1.0, v52
	v_add_f32_e32 v47, 1.0, v53
	v_mul_f32_e32 v52, 0xbfb8aa3b, v50
	v_mul_f32_e32 v53, 0xbfb8aa3b, v51
	v_exp_f32_e32 v52, v52
	v_exp_f32_e32 v53, v53
	v_rcp_f32_e32 v46, v46
	v_rcp_f32_e32 v47, v47
	v_pk_mul_f32 v[38:39], v[38:39], v[50:51]
	v_add_f32_e32 v50, 1.0, v52
	v_add_f32_e32 v51, 1.0, v53
	v_rcp_f32_e32 v50, v50
	v_rcp_f32_e32 v51, v51
	v_pk_mul_f32 v[36:37], v[36:37], v[48:49]
	v_add_u32_e32 v64, 0x90, v193
	v_pk_mul_f32 v[36:37], v[36:37], v[46:47]
	v_cndmask_b32_e64 v41, v25, v41, s[44:45]
	v_cvt_pk_bf16_f32 v46, v36, v37
	v_pk_mul_f32 v[36:37], v[38:39], v[50:51]
	v_cndmask_b32_e32 v48, v17, v9, vcc
	v_cvt_pk_bf16_f32 v47, v36, v37
	v_mov_b64_e32 v[36:37], s[54:55]
	v_mad_i64_i32 v[38:39], s[24:25], v64, s60, v[36:37]
	v_lshl_add_u64 v[38:39], v[38:39], 0, v[132:133]
	global_store_dwordx4 v[38:39], v[44:47], off
	v_cndmask_b32_e64 v39, v24, v40, s[44:45]
	v_mov_b32_e32 v38, 0
	v_cndmask_b32_e32 v44, v24, v12, vcc
	v_mov_b32_e32 v40, 0
	v_mov_b32_dpp v38, v39 row_ror:1 row_mask:0xf bank_mask:0xf
	v_mov_b32_e32 v39, 0
	v_mov_b32_dpp v40, v44 row_ror:15 row_mask:0xf bank_mask:0xf
	v_cndmask_b32_e32 v44, v25, v13, vcc
	v_mov_b32_dpp v39, v41 row_ror:1 row_mask:0xf bank_mask:0xf
	v_mov_b32_e32 v41, 0
	v_cndmask_b32_e32 v45, v26, v14, vcc
	v_pk_mul_f32 v[38:39], v[96:97], v[38:39]
	v_mov_b32_dpp v41, v44 row_ror:15 row_mask:0xf bank_mask:0xf
	v_cndmask_b32_e64 v44, v26, v42, s[44:45]
	v_mov_b32_e32 v42, 0
	v_pk_fma_f32 v[38:39], v[24:25], v[100:101], v[38:39]
	v_cndmask_b32_e32 v46, v27, v15, vcc
	v_mov_b32_dpp v42, v44 row_ror:1 row_mask:0xf bank_mask:0xf
	v_mov_b32_e32 v44, 0
	v_pk_fma_f32 v[38:39], v[108:109], v[40:41], v[38:39]
	v_cndmask_b32_e32 v47, v16, v8, vcc
	v_mov_b32_dpp v44, v45 row_ror:15 row_mask:0xf bank_mask:0xf
	v_cndmask_b32_e64 v45, v27, v43, s[44:45]
	v_mov_b32_e32 v43, 0
	v_pk_add_f32 v[38:39], v[112:113], v[38:39]
	v_cndmask_b32_e32 v49, v18, v10, vcc
	v_mov_b32_dpp v43, v45 row_ror:1 row_mask:0xf bank_mask:0xf
; DI unsigned pack2(float a, float b) { f32x2 v = {a, b}; hwbf16x2 r = __builtin_convertvector(v, hwbf16x2); return __builtin_bit_cast(unsigned, r); }
; DI float dpp_ror1(float v)  { return __builtin_bit_cast(float, __builtin_amdgcn_update_dpp(0, __builtin_bit_cast(int, v), 0x121, 0xf, 0xf, false)); }
;     DI void operator()(const f32x4 (&acc)[2][2][4][2], const Unit& u, int wr, int wc, int fr, int fq) const {
;     ...
;                 const bool efirst = (m == 0) && (fr == 0), elast = (m == 3) && (fr == 15);
;                 const int row = row0 + ai * HALF + m * 16;
;                 f32x4 gc[2];
; #pragma unroll
;                 for (int n = 0; n < 2; ++n) {
;                     const f32x4 g = acc[ai][0][m][n];
;                     const f32x4 gprev = acc[ai][0][m > 0 ? m - 1 : 0][n], gnext = acc[ai][0][m < 3 ? m + 1 : 3][n];
;                     f32x4 up, dn;
; #pragma unroll
;                     for (int e = 0; e < 4; ++e) {
;                         const float pu = (m > 0 && fr == 15) ? gprev[e] : g[e];
;                         const float pd = (m < 3 && fr == 0) ? gnext[e] : g[e];
;                         up[e] = dpp_ror1(pu); dn[e] = dpp_ror15(pd);
;                     }
;                     if (efirst) up = (f32x4){0.f, 0.f, 0.f, 0.f};
;                     if (elast) dn = (f32x4){0.f, 0.f, 0.f, 0.f};
;                     gc[n] = w0[n] * up + w1[n] * g + w2[n] * dn + bb[n];
;                 }
;                 if (efirst || elast) {
;                     const size_t eo = (size_t)((row >> 6) * 2 + (elast ? 1 : 0)) * DFF + ch0;
; #pragma unroll
;                     for (int n = 0; n < 2; ++n) { *(f32x4*)(EP + eo + 4 * n) = gc[n]; *(f32x4*)(ER + eo + 4 * n) = acc[ai][0][m][n]; *(f32x4*)(EV + eo + 4 * n) = acc[ai][1][m][n]; }
;                 } else {
;                     const f32x4 v0 = acc[ai][1][m][0], v1 = acc[ai][1][m][1];
;                     u32x4 o;
;                     o[0] = pack2(silu_mul(gc[0][0], v0[0]), silu_mul(gc[0][1], v0[1])); o[1] = pack2(silu_mul(gc[0][2], v0[2]), silu_mul(gc[0][3], v0[3]));
;                     o[2] = pack2(silu_mul(gc[1][0], v1[0]), silu_mul(gc[1][1], v1[1])); o[3] = pack2(silu_mul(gc[1][2], v1[2]), silu_mul(gc[1][3], v1[3]));
;                     *(u32x4*)(ACT + (size_t)row * DFF + ch0) = o;
;                 }
	v_mov_b32_e32 v45, 0
	v_pk_mul_f32 v[42:43], v[98:99], v[42:43]
	v_mul_f32_e32 v40, 0xbfb8aa3b, v38
	v_mov_b32_dpp v45, v46 row_ror:15 row_mask:0xf bank_mask:0xf
	v_pk_fma_f32 v[42:43], v[26:27], v[102:103], v[42:43]
	v_cndmask_b32_e64 v46, v16, v32, s[44:45]
	v_pk_fma_f32 v[42:43], v[110:111], v[44:45], v[42:43]
	v_exp_f32_e32 v44, v40
	v_mul_f32_e32 v40, 0xbfb8aa3b, v39
	v_exp_f32_e32 v45, v40
	v_mov_b32_e32 v32, 0
	v_pk_add_f32 v[40:41], v[114:115], v[42:43]
	v_add_f32_e32 v42, 1.0, v44
	v_mov_b32_dpp v32, v46 row_ror:1 row_mask:0xf bank_mask:0xf
	v_mov_b32_e32 v46, 0
	v_add_f32_e32 v43, 1.0, v45
	v_rcp_f32_e32 v42, v42
	v_mov_b32_dpp v46, v47 row_ror:15 row_mask:0xf bank_mask:0xf
	v_cndmask_b32_e64 v47, v17, v33, s[44:45]
	v_mov_b32_e32 v33, 0
	v_rcp_f32_e32 v43, v43
	v_mul_f32_e32 v44, 0xbfb8aa3b, v40
	v_mov_b32_dpp v33, v47 row_ror:1 row_mask:0xf bank_mask:0xf
	v_mul_f32_e32 v45, 0xbfb8aa3b, v41
	v_mov_b32_e32 v47, 0
	v_pk_mul_f32 v[32:33], v[80:81], v[32:33]
	v_exp_f32_e32 v44, v44
	v_exp_f32_e32 v45, v45
	v_mov_b32_dpp v47, v48 row_ror:15 row_mask:0xf bank_mask:0xf
	v_pk_fma_f32 v[32:33], v[16:17], v[84:85], v[32:33]
	v_cndmask_b32_e64 v48, v18, v34, s[44:45]
	v_mov_b32_e32 v34, 0
	v_pk_fma_f32 v[32:33], v[88:89], v[46:47], v[32:33]
	v_pk_mul_f32 v[28:29], v[28:29], v[38:39]
	v_mov_b32_dpp v34, v48 row_ror:1 row_mask:0xf bank_mask:0xf
	v_mov_b32_e32 v48, 0
	v_pk_add_f32 v[32:33], v[92:93], v[32:33]
	v_pk_mul_f32 v[28:29], v[28:29], v[42:43]
	v_mov_b32_dpp v48, v49 row_ror:15 row_mask:0xf bank_mask:0xf
	v_cndmask_b32_e64 v49, v19, v35, s[44:45]
	v_mov_b32_e32 v35, 0
	v_pk_mul_f32 v[30:31], v[30:31], v[40:41]
	v_add_f32_e32 v40, 1.0, v44
	v_add_f32_e32 v41, 1.0, v45
	v_cvt_pk_bf16_f32 v28, v28, v29
	v_mul_f32_e32 v29, 0xbfb8aa3b, v32
	v_mov_b32_dpp v35, v49 row_ror:1 row_mask:0xf bank_mask:0xf
	v_rcp_f32_e32 v40, v40
	v_rcp_f32_e32 v41, v41
	v_exp_f32_e32 v38, v29
	v_mul_f32_e32 v29, 0xbfb8aa3b, v33
	v_cndmask_b32_e32 v50, v19, v11, vcc
	v_mov_b32_e32 v49, 0
	v_pk_mul_f32 v[34:35], v[82:83], v[34:35]
	v_exp_f32_e32 v39, v29
	v_mov_b32_dpp v49, v50 row_ror:15 row_mask:0xf bank_mask:0xf
	v_pk_fma_f32 v[34:35], v[18:19], v[86:87], v[34:35]
	v_pk_mul_f32 v[30:31], v[30:31], v[40:41]
	v_pk_fma_f32 v[34:35], v[90:91], v[48:49], v[34:35]
	v_cvt_pk_bf16_f32 v29, v30, v31
	v_pk_add_f32 v[34:35], v[94:95], v[34:35]
	v_add_f32_e32 v30, 1.0, v38
	v_add_f32_e32 v31, 1.0, v39
	v_mul_f32_e32 v38, 0xbfb8aa3b, v34
	v_mul_f32_e32 v39, 0xbfb8aa3b, v35
	v_exp_f32_e32 v38, v38
	v_exp_f32_e32 v39, v39
	v_rcp_f32_e32 v30, v30
	v_rcp_f32_e32 v31, v31
	v_pk_mul_f32 v[22:23], v[22:23], v[34:35]
	v_add_f32_e32 v34, 1.0, v38
	v_add_f32_e32 v35, 1.0, v39
	v_rcp_f32_e32 v34, v34
	v_rcp_f32_e32 v35, v35
	v_pk_mul_f32 v[20:21], v[20:21], v[32:33]
	v_add_u32_e32 v50, 0xa0, v193
	v_pk_mul_f32 v[20:21], v[20:21], v[30:31]
	s_nop 0
	v_cvt_pk_bf16_f32 v30, v20, v21
	v_pk_mul_f32 v[20:21], v[22:23], v[34:35]
	v_cndmask_b32_e64 v22, v13, v25, s[44:45]
	v_cvt_pk_bf16_f32 v31, v20, v21
	v_mad_i64_i32 v[20:21], s[24:25], v50, s60, v[36:37]
	v_lshl_add_u64 v[20:21], v[20:21], 0, v[132:133]
	global_store_dwordx4 v[20:21], v[28:31], off
	v_cndmask_b32_e64 v21, v12, v24, s[44:45]
	v_mov_b32_e32 v20, 0
	v_cndmask_b32_e64 v23, v14, v26, s[44:45]
	v_cndmask_b32_e64 v25, v15, v27, s[44:45]
	v_mov_b32_dpp v20, v21 row_ror:1 row_mask:0xf bank_mask:0xf
	v_mov_b32_e32 v21, 0
	v_mov_b32_e32 v24, 0
	v_mov_b32_e32 v28, 0
	v_mov_b32_dpp v21, v22 row_ror:1 row_mask:0xf bank_mask:0xf
	v_mov_b32_e32 v22, 0
	v_mov_b32_dpp v24, v14 row_ror:15 row_mask:0xf bank_mask:0xf
	v_cndmask_b32_e64 v24, v24, 0, s[44:45]
	v_mov_b32_dpp v22, v23 row_ror:1 row_mask:0xf bank_mask:0xf
	v_mov_b32_e32 v23, 0
	v_mov_b32_e32 v29, 0
	v_mov_b32_dpp v28, v12 row_ror:15 row_mask:0xf bank_mask:0xf
	v_mov_b32_dpp v23, v25 row_ror:1 row_mask:0xf bank_mask:0xf
	v_mov_b32_e32 v25, 0
	v_pk_mul_f32 v[22:23], v[98:99], v[22:23]
	v_mov_b32_dpp v29, v13 row_ror:15 row_mask:0xf bank_mask:0xf
	v_mov_b32_dpp v25, v15 row_ror:15 row_mask:0xf bank_mask:0xf
	v_cndmask_b32_e64 v25, v25, 0, s[44:45]
	v_pk_fma_f32 v[22:23], v[14:15], v[102:103], v[22:23]
	v_pk_mul_f32 v[20:21], v[96:97], v[20:21]
	v_pk_fma_f32 v[22:23], v[110:111], v[24:25], v[22:23]
	v_cndmask_b32_e64 v24, v8, v16, s[44:45]
	v_mov_b32_e32 v16, 0
	v_cndmask_b32_e64 v27, v29, 0, s[44:45]
	v_cndmask_b32_e64 v26, v28, 0, s[44:45]
	v_mov_b32_dpp v16, v24 row_ror:1 row_mask:0xf bank_mask:0xf
	v_cndmask_b32_e64 v24, v9, v17, s[44:45]
	v_mov_b32_e32 v17, 0
	v_pk_fma_f32 v[20:21], v[12:13], v[100:101], v[20:21]
	v_cndmask_b32_e64 v25, v11, v19, s[44:45]
	v_mov_b32_dpp v17, v24 row_ror:1 row_mask:0xf bank_mask:0xf
	v_cndmask_b32_e64 v24, v10, v18, s[44:45]
	v_mov_b32_e32 v18, 0
	v_mov_b32_e32 v19, 0
	v_pk_fma_f32 v[20:21], v[108:109], v[26:27], v[20:21]
	v_mov_b32_e32 v26, 0
	v_mov_b32_e32 v27, 0
	v_mov_b32_dpp v18, v24 row_ror:1 row_mask:0xf bank_mask:0xf
	v_mov_b32_e32 v24, 0
	v_mov_b32_dpp v19, v25 row_ror:1 row_mask:0xf bank_mask:0xf
	v_mov_b32_e32 v25, 0
	v_mov_b32_dpp v26, v8 row_ror:15 row_mask:0xf bank_mask:0xf
	v_mov_b32_dpp v27, v9 row_ror:15 row_mask:0xf bank_mask:0xf
	v_mov_b32_dpp v24, v10 row_ror:15 row_mask:0xf bank_mask:0xf
	v_mov_b32_dpp v25, v11 row_ror:15 row_mask:0xf bank_mask:0xf
	v_pk_mul_f32 v[16:17], v[80:81], v[16:17]
	v_pk_mul_f32 v[18:19], v[82:83], v[18:19]
	v_cndmask_b32_e64 v25, v25, 0, s[44:45]
	v_cndmask_b32_e64 v24, v24, 0, s[44:45]
	v_cndmask_b32_e64 v27, v27, 0, s[44:45]
	v_cndmask_b32_e64 v26, v26, 0, s[44:45]
	v_pk_fma_f32 v[18:19], v[10:11], v[86:87], v[18:19]
	v_pk_fma_f32 v[16:17], v[8:9], v[84:85], v[16:17]
	v_pk_fma_f32 v[18:19], v[90:91], v[24:25], v[18:19]
	v_pk_fma_f32 v[16:17], v[88:89], v[26:27], v[16:17]
	v_pk_add_f32 v[22:23], v[114:115], v[22:23]
	v_pk_add_f32 v[20:21], v[112:113], v[20:21]
	v_pk_add_f32 v[18:19], v[94:95], v[18:19]
	v_pk_add_f32 v[16:17], v[92:93], v[16:17]
	v_add_u32_e32 v24, 0xb0, v193
	s_and_saveexec_b64 s[24:25], s[42:43]
	s_xor_b64 s[24:25], exec, s[24:25]
	s_cbranch_execz .LBB1_1084
; DI unsigned pack2(float a, float b) { f32x2 v = {a, b}; hwbf16x2 r = __builtin_convertvector(v, hwbf16x2); return __builtin_bit_cast(unsigned, r); }
; DI float silu_mul(float g, float v) { return g * v * __builtin_amdgcn_rcpf(1.0f + __builtin_amdgcn_exp2f(-LOG2E * g)); }
;     DI void operator()(const f32x4 (&acc)[2][2][4][2], const Unit& u, int wr, int wc, int fr, int fq) const {
;     ...
;                 if (efirst || elast) {
;                     const size_t eo = (size_t)((row >> 6) * 2 + (elast ? 1 : 0)) * DFF + ch0;
; #pragma unroll
;                     for (int n = 0; n < 2; ++n) { *(f32x4*)(EP + eo + 4 * n) = gc[n]; *(f32x4*)(ER + eo + 4 * n) = acc[ai][0][m][n]; *(f32x4*)(EV + eo + 4 * n) = acc[ai][1][m][n]; }
;                 } else {
;                     const f32x4 v0 = acc[ai][1][m][0], v1 = acc[ai][1][m][1];
;                     u32x4 o;
;                     o[0] = pack2(silu_mul(gc[0][0], v0[0]), silu_mul(gc[0][1], v0[1])); o[1] = pack2(silu_mul(gc[0][2], v0[2]), silu_mul(gc[0][3], v0[3]));
;                     o[2] = pack2(silu_mul(gc[1][0], v1[0]), silu_mul(gc[1][1], v1[1])); o[3] = pack2(silu_mul(gc[1][2], v1[2]), silu_mul(gc[1][3], v1[3]));
;                     *(u32x4*)(ACT + (size_t)row * DFF + ch0) = o;
;                 }
	v_mul_f32_e32 v25, 0xbfb8aa3b, v20
	v_exp_f32_e32 v25, v25
	v_mul_f32_e32 v26, 0xbfb8aa3b, v21
	v_exp_f32_e32 v26, v26
	v_mul_f32_e32 v28, 0xbfb8aa3b, v23
	v_add_f32_e32 v25, 1.0, v25
	v_exp_f32_e32 v29, v28
	v_add_f32_e32 v27, 1.0, v26
	v_rcp_f32_e32 v26, v25
	v_mul_f32_e32 v25, 0xbfb8aa3b, v22
	v_exp_f32_e32 v25, v25
	v_rcp_f32_e32 v27, v27
	v_pk_mul_f32 v[20:21], v[4:5], v[20:21]
	v_pk_mul_f32 v[22:23], v[6:7], v[22:23]
	v_add_f32_e32 v25, 1.0, v25
	v_rcp_f32_e32 v28, v25
	v_add_f32_e32 v25, 1.0, v29
	v_pk_mul_f32 v[20:21], v[20:21], v[26:27]
	v_rcp_f32_e32 v29, v25
	v_cvt_pk_bf16_f32 v20, v20, v21
	v_mul_f32_e32 v21, 0xbfb8aa3b, v16
	v_exp_f32_e32 v25, v21
	v_mul_f32_e32 v21, 0xbfb8aa3b, v17
	v_exp_f32_e32 v26, v21
	v_pk_mul_f32 v[22:23], v[22:23], v[28:29]
	v_pk_mul_f32 v[16:17], v[0:1], v[16:17]
	v_cvt_pk_bf16_f32 v21, v22, v23
	v_add_f32_e32 v22, 1.0, v25
	v_mul_f32_e32 v25, 0xbfb8aa3b, v18
	v_add_f32_e32 v23, 1.0, v26
	v_exp_f32_e32 v25, v25
	v_mul_f32_e32 v26, 0xbfb8aa3b, v19
	v_exp_f32_e32 v27, v26
	v_rcp_f32_e32 v22, v22
	v_add_f32_e32 v25, 1.0, v25
	v_rcp_f32_e32 v23, v23
	v_rcp_f32_e32 v26, v25
	v_add_f32_e32 v25, 1.0, v27
	v_rcp_f32_e32 v27, v25
	v_pk_mul_f32 v[18:19], v[2:3], v[18:19]
	v_pk_mul_f32 v[16:17], v[16:17], v[22:23]
	s_nop 0
	v_cvt_pk_bf16_f32 v22, v16, v17
	v_pk_mul_f32 v[16:17], v[18:19], v[26:27]
	s_nop 0
	v_cvt_pk_bf16_f32 v23, v16, v17
	v_mov_b64_e32 v[16:17], s[54:55]
	v_mad_i64_i32 v[16:17], s[42:43], v24, s60, v[16:17]
	v_lshl_add_u64 v[16:17], v[184:185], 1, v[16:17]
	global_store_dwordx4 v[16:17], v[20:23], off
.LBB1_1084:
	s_andn2_saveexec_b64 s[24:25], s[24:25]
	s_cbranch_execz .LBB1_1065
	v_ashrrev_i32_e32 v24, 5, v24
	v_mad_i64_i32 v[24:25], s[42:43], v24, s61, v[184:185]
	v_lshlrev_b64 v[24:25], 2, v[24:25]
	v_lshl_add_u64 v[26:27], s[8:9], 0, v[24:25]
	global_store_dwordx4 v[26:27], v[20:23], off
	s_nop 1
	v_lshl_add_u64 v[20:21], s[10:11], 0, v[24:25]
	global_store_dwordx4 v[20:21], v[12:15], off
	s_nop 1
	v_lshl_add_u64 v[12:13], s[12:13], 0, v[24:25]
	global_store_dwordx4 v[12:13], v[4:7], off
	global_store_dwordx4 v[26:27], v[16:19], off offset:16
	global_store_dwordx4 v[20:21], v[8:11], off offset:16
	global_store_dwordx4 v[12:13], v[0:3], off offset:16
	s_branch .LBB1_1065

; DI void glu_fix_phase(const Params& p, int layer) {
;     ...
;     for (int task0 = bid * 512 + tid; task0 < NTASK; task0 += 3 * tstride) {
;         f32x4 gc[3], vv[3], nb[3], wv[3]; int rowc[3], cc[3];
; #pragma unroll
;         for (int u = 0; u < 3; ++u) {
;             const int task = task0 + u * tstride;
;             if (task < NTASK) {
;                 const int e = task / NC4, c = (task - e * NC4) * 4, b64 = e >> 1, last = e & 1, row = b64 * 64 + (last ? 63 : 0), sq = row & (S - 1);
;                 const bool valid = last ? (sq != S - 1) : (sq != 0);
;                 const int en = valid ? (last ? e + 1 : e - 1) : e;
;                 gc[u] = *(const f32x4*)(EP + (size_t)e * DFF + c); vv[u] = *(const f32x4*)(EV + (size_t)e * DFF + c);
;                 nb[u] = *(const f32x4*)(ER + (size_t)en * DFF + c);
;                 wv[u] = *(const f32x4*)(cw + (last ? 2 * DFF : 0) + c);
;                 if (!valid) wv[u] = (f32x4){0.f, 0.f, 0.f, 0.f};
;                 rowc[u] = row; cc[u] = c;
;             }
.LBB1_1156:
	v_mul_hi_i32 v32, v51, s4
	v_lshrrev_b32_e32 v33, 31, v32
	v_ashrrev_i32_e32 v32, 8, v32
	v_add_u32_e32 v32, v32, v33
	v_mul_i32_i24_e32 v33, 0xfffffa80, v32
	v_bfe_i32 v59, v32, 0, 1
	v_lshlrev_b32_e32 v60, 5, v32
	v_add_lshl_u32 v54, v33, v51, 2
	v_and_b32_e32 v33, 1, v32
	v_and_b32_e32 v34, 0xffffffc0, v60
	v_and_b32_e32 v35, 63, v59
	v_bitop3_b32 v34, v35, s22, v34 bitop3:0xc8
	v_and_b32_e32 v35, 0xfff, v59
	v_cmp_eq_u32_e32 vcc, 0, v33
	v_cmp_eq_u32_e64 s[40:41], v34, v35
	v_ashrrev_i32_e32 v55, 31, v54
	v_cndmask_b32_e64 v33, 1, -1, vcc
	v_cndmask_b32_e64 v33, v33, 0, s[40:41]
	v_add_u32_e32 v40, v33, v32
	v_mul_hi_i32_i24_e32 v33, 0x1600, v32
	v_mul_i32_i24_e32 v32, 0x1600, v32
	v_lshlrev_b64 v[32:33], 2, v[32:33]
	v_mul_hi_i32_i24_e32 v41, 0x5800, v40
	v_mul_i32_i24_e32 v40, 0x5800, v40
	v_and_b32_e32 v48, 0xb000, v59
	v_lshl_add_u64 v[34:35], s[10:11], 0, v[32:33]
	v_lshlrev_b64 v[44:45], 2, v[54:55]
	v_lshl_add_u64 v[32:33], s[14:15], 0, v[32:33]
	v_lshl_add_u64 v[40:41], s[12:13], 0, v[40:41]
	v_lshl_add_u64 v[46:47], s[16:17], 0, v[48:49]
	v_lshl_add_u64 v[34:35], v[34:35], 0, v[44:45]
	v_lshl_add_u64 v[32:33], v[32:33], 0, v[44:45]
	v_lshl_add_u64 v[40:41], v[40:41], 0, v[44:45]
	v_lshl_add_u64 v[44:45], v[46:47], 0, v[44:45]
	global_load_dwordx4 v[36:39], v[34:35], off
	s_nop 0
	global_load_dwordx4 v[32:35], v[32:33], off
	v_add_u32_e32 v58, s60, v51
	global_load_dwordx4 v[40:43], v[40:41], off
	v_cmp_gt_i32_e32 vcc, s2, v58
	global_load_dwordx4 v[44:47], v[44:45], off
	s_and_saveexec_b64 s[20:21], vcc
	s_cbranch_execz .LBB1_1158
	v_mul_hi_i32 v0, v58, s4
	v_lshrrev_b32_e32 v1, 31, v0
	v_ashrrev_i32_e32 v0, 8, v0
	v_add_u32_e32 v0, v0, v1
	v_mov_b32_e32 v1, s60
	v_mad_i32_i24 v1, v0, s5, v1
	v_bfe_i32 v57, v0, 0, 1
	v_lshlrev_b32_e32 v61, 5, v0
	v_add_lshl_u32 v52, v1, v51, 2
	v_and_b32_e32 v1, 1, v0
	v_and_b32_e32 v2, 0xffffffc0, v61
	v_and_b32_e32 v3, 63, v57
	v_bitop3_b32 v2, v3, s22, v2 bitop3:0xc8
	v_and_b32_e32 v3, 0xfff, v57
	v_cmp_eq_u32_e64 s[42:43], 0, v1
	v_ashrrev_i32_e32 v53, 31, v52
	v_and_b32_e32 v48, 0xb000, v57
	v_cndmask_b32_e64 v1, 1, -1, s[42:43]
	v_cmp_eq_u32_e64 s[42:43], v2, v3
	v_lshlrev_b64 v[16:17], 2, v[52:53]
	v_lshl_add_u64 v[28:29], s[16:17], 0, v[48:49]
	v_cndmask_b32_e64 v1, v1, 0, s[42:43]
	v_add_u32_e32 v18, v1, v0
	v_mul_hi_i32_i24_e32 v1, 0x1600, v0
	v_mul_i32_i24_e32 v0, 0x1600, v0
	v_lshlrev_b64 v[0:1], 2, v[0:1]
	v_lshl_add_u64 v[2:3], s[10:11], 0, v[0:1]
	v_lshl_add_u64 v[0:1], s[14:15], 0, v[0:1]
	v_mul_hi_i32_i24_e32 v19, 0x5800, v18
	v_mul_i32_i24_e32 v18, 0x5800, v18
	v_lshl_add_u64 v[2:3], v[2:3], 0, v[16:17]
	v_lshl_add_u64 v[12:13], v[0:1], 0, v[16:17]
	v_lshl_add_u64 v[28:29], v[28:29], 0, v[16:17]
	v_lshl_add_u64 v[18:19], s[12:13], 0, v[18:19]
	global_load_dwordx4 v[0:3], v[2:3], off
	s_nop 0
	global_load_dwordx4 v[12:15], v[12:13], off
	v_lshl_add_u64 v[16:17], v[18:19], 0, v[16:17]
	global_load_dwordx4 v[28:31], v[28:29], off
	v_bfi_b32 v57, 63, v57, v61
	global_load_dwordx4 v[16:19], v[16:17], off
	s_waitcnt vmcnt(0)
	v_cndmask_b32_e64 v31, v31, 0, s[42:43]
	v_cndmask_b32_e64 v30, v30, 0, s[42:43]
	v_cndmask_b32_e64 v29, v29, 0, s[42:43]
	v_cndmask_b32_e64 v28, v28, 0, s[42:43]

; #define PG8_STAGE(bufoff, gbase, voff) do { _Pragma("unroll") for (int _i = 0; _i < 2; ++_i) \
;         __builtin_amdgcn_global_load_lds((const unsigned*)((const char*)(gbase) + (voff)[_i]), (LAS unsigned*)(lds + (bufoff) + ldsw + _i * 8192), 16, 0, 0); } while (0)
; #define PG8_LDA(dst, b, h) do { _Pragma("unroll") for (int m = 0; m < 4; ++m) _Pragma("unroll") for (int k = 0; k < 2; ++k) dst[m][k] = *(const LAS bf16x8*)(lds + PG8_SA(b, h) + aoff + m * 2048 + k * 1024); } while (0)
; #define PG8_LDB(dst, b, h) do { _Pragma("unroll") for (int n = 0; n < 2; ++n) _Pragma("unroll") for (int k = 0; k < 2; ++k) dst[n][k] = *(const LAS bf16x8*)(lds + PG8_SB(b, h) + boff + n * 2048 + k * 1024); } while (0)
; #define PG8_MMA(ai, bj, At, Bt) do { __builtin_amdgcn_s_setprio(1); _Pragma("unroll") for (int m = 0; m < 4; ++m) _Pragma("unroll") for (int n = 0; n < 2; ++n) _Pragma("unroll") for (int k = 0; k < 2; ++k) \
;         acc[ai][bj][m][n] = __builtin_amdgcn_mfma_f32_16x16x32_bf16(Bt[n][k], At[m][k], acc[ai][bj][m][n], 0, 0, 0); __builtin_amdgcn_s_setprio(0); } while (0)
; #define PG8_WAIT_L(n) asm volatile("s_waitcnt lgkmcnt(" #n ")" ::: "memory")
; #define PG8_BAR __builtin_amdgcn_s_barrier()
; #define PG8_SCHED __builtin_amdgcn_sched_barrier(0)
; template <class Map, class Epi>
; DI void gemm_phase(LAS unsigned char* lds, const Map& MP, const Epi& E, const int nM, const int nN, const int K, const int lda, const int ldb) {
;     ...
;             const bool last = (t == nt - 2);
;             const char* a1 = cA + (size_t)(t + 1) * kstep;
;             const char* a2 = last ? nA : cA + (size_t)(t + 2) * kstep; const char* b2 = last ? nB : cB + (size_t)(t + 2) * kstep;
;             const char* a3 = a2 + kstep; const char* b3 = b2 + kstep;
;             PG8_LDB(B0, 0, 0); PG8_SCHED; PG8_LDA(At, 0, 0); PG8_STAGE(PG8_SA(1, 1), a1 + hstepA, voffA);
;             PG8_WAIT_L(8); PG8_BAR; PG8_WAIT_L(0); PG8_MMA(0, 0, At, B0); PG8_BAR; PG8_SCHED;
;             PG8_LDB(B1, 0, 1); PG8_STAGE(PG8_SB(0, 0), b2, voffB);
;             PG8_BAR; PG8_WAIT_L(0); PG8_MMA(0, 1, At, B1); PG8_BAR;
;             PG8_LDA(At, 0, 1); PG8_STAGE(PG8_SA(0, 0), a2, voffA);
;             PG8_BAR; PG8_WAIT_L(0); PG8_MMA(1, 0, At, B0); PG8_BAR; PG8_SCHED;
.LBB1_1239:
	ds_read_b128 v[152:155], v149
	ds_read_b128 v[156:159], v149 offset:1024
	ds_read_b128 v[160:163], v149 offset:2048
	ds_read_b128 v[164:167], v149 offset:3072
	s_add_u32 s10, s8, 0x100
	s_addc_u32 s11, s9, 0
	s_cmpk_eq_i32 s3, 0x54
	s_cselect_b32 s15, s43, s11
	s_cselect_b32 s14, s42, s10
	s_cselect_b32 s13, s7, s38
	s_cselect_b32 s12, s6, s5
	v_lshl_add_u64 v[144:145], s[8:9], 0, v[138:139]
	s_add_i32 m0, s24, 0xc000
	ds_read_b128 v[168:171], v150
	ds_read_b128 v[172:175], v150 offset:1024
	ds_read_b128 v[176:179], v150 offset:2048
	ds_read_b128 v[180:183], v150 offset:3072
	ds_read_b128 v[184:187], v150 offset:4096
	ds_read_b128 v[188:191], v150 offset:5120
	ds_read_b128 v[192:195], v150 offset:6144
	ds_read_b128 v[198:201], v150 offset:7168
	global_load_lds_dwordx4 v[144:145], off
	v_lshl_add_u64 v[144:145], s[8:9], 0, v[136:137]
	s_add_i32 m0, s24, 0xe000
	s_nop 0
	global_load_lds_dwordx4 v[144:145], off
	s_waitcnt lgkmcnt(8)
	s_barrier
	s_setprio 1
	s_waitcnt lgkmcnt(7)
	v_mfma_f32_16x16x32_bf16 v[124:127], v[152:155], v[168:171], v[124:127]
	v_mfma_f32_16x16x32_bf16 v[120:123], v[160:163], v[168:171], v[120:123]
	s_waitcnt lgkmcnt(5)
	v_mfma_f32_16x16x32_bf16 v[108:111], v[152:155], v[176:179], v[108:111]
	v_mfma_f32_16x16x32_bf16 v[104:107], v[160:163], v[176:179], v[104:107]
	s_waitcnt lgkmcnt(3)
	v_mfma_f32_16x16x32_bf16 v[92:95], v[152:155], v[184:187], v[92:95]
	v_mfma_f32_16x16x32_bf16 v[88:91], v[160:163], v[184:187], v[88:91]
	s_waitcnt lgkmcnt(1)
	v_mfma_f32_16x16x32_bf16 v[76:79], v[152:155], v[192:195], v[76:79]
	v_mfma_f32_16x16x32_bf16 v[72:75], v[160:163], v[192:195], v[72:75]
	v_mfma_f32_16x16x32_bf16 v[124:127], v[156:159], v[172:175], v[124:127]
	v_mfma_f32_16x16x32_bf16 v[120:123], v[164:167], v[172:175], v[120:123]
	v_mfma_f32_16x16x32_bf16 v[108:111], v[156:159], v[180:183], v[108:111]
	v_mfma_f32_16x16x32_bf16 v[104:107], v[164:167], v[180:183], v[104:107]
	v_mfma_f32_16x16x32_bf16 v[92:95], v[156:159], v[188:191], v[92:95]
	v_mfma_f32_16x16x32_bf16 v[88:91], v[164:167], v[188:191], v[88:91]
	s_waitcnt lgkmcnt(0)
	v_mfma_f32_16x16x32_bf16 v[76:79], v[156:159], v[198:201], v[76:79]
	v_mfma_f32_16x16x32_bf16 v[72:75], v[164:167], v[198:201], v[72:75]
	s_setprio 0
	s_barrier
	s_add_i32 s8, s35, s22
	v_lshl_add_u64 v[144:145], s[12:13], 0, v[132:133]
	s_mov_b32 m0, s8
	ds_read_b128 v[202:205], v151
	ds_read_b128 v[206:209], v151 offset:1024
	ds_read_b128 v[210:213], v151 offset:2048
	ds_read_b128 v[214:217], v151 offset:3072
	global_load_lds_dwordx4 v[144:145], off
	v_lshl_add_u64 v[218:219], s[12:13], 0, v[128:129]
	s_add_i32 m0, s8, 0x2000
	s_nop 0
	global_load_lds_dwordx4 v[218:219], off
	s_barrier
	s_setprio 1
	s_waitcnt lgkmcnt(3)
	v_mfma_f32_16x16x32_bf16 v[116:119], v[202:205], v[168:171], v[116:119]
	s_waitcnt lgkmcnt(1)
	v_mfma_f32_16x16x32_bf16 v[112:115], v[210:213], v[168:171], v[112:115]
	v_mfma_f32_16x16x32_bf16 v[100:103], v[202:205], v[176:179], v[100:103]
	v_mfma_f32_16x16x32_bf16 v[96:99], v[210:213], v[176:179], v[96:99]
	v_mfma_f32_16x16x32_bf16 v[84:87], v[202:205], v[184:187], v[84:87]
	v_mfma_f32_16x16x32_bf16 v[80:83], v[210:213], v[184:187], v[80:83]
	v_mfma_f32_16x16x32_bf16 v[68:71], v[202:205], v[192:195], v[68:71]
	v_mfma_f32_16x16x32_bf16 v[64:67], v[210:213], v[192:195], v[64:67]
	v_mfma_f32_16x16x32_bf16 v[116:119], v[206:209], v[172:175], v[116:119]
	s_waitcnt lgkmcnt(0)
	v_mfma_f32_16x16x32_bf16 v[112:115], v[214:217], v[172:175], v[112:115]
	v_mfma_f32_16x16x32_bf16 v[100:103], v[206:209], v[180:183], v[100:103]
	v_mfma_f32_16x16x32_bf16 v[96:99], v[214:217], v[180:183], v[96:99]
	v_mfma_f32_16x16x32_bf16 v[84:87], v[206:209], v[188:191], v[84:87]
	v_mfma_f32_16x16x32_bf16 v[80:83], v[214:217], v[188:191], v[80:83]
	v_mfma_f32_16x16x32_bf16 v[68:71], v[206:209], v[198:201], v[68:71]
	v_mfma_f32_16x16x32_bf16 v[64:67], v[214:217], v[198:201], v[64:67]
	s_setprio 0
	s_mov_b32 m0, s24
	v_lshl_add_u64 v[220:221], s[14:15], 0, v[134:135]
	s_barrier
	ds_read_b128 v[168:171], v150 offset:16384
	ds_read_b128 v[172:175], v150 offset:17408
	ds_read_b128 v[176:179], v150 offset:18432
	ds_read_b128 v[180:183], v150 offset:19456
	ds_read_b128 v[184:187], v150 offset:20480
	ds_read_b128 v[188:191], v150 offset:21504
	ds_read_b128 v[192:195], v150 offset:22528
	ds_read_b128 v[198:201], v150 offset:23552
	global_load_lds_dwordx4 v[220:221], off
	v_lshl_add_u64 v[222:223], s[14:15], 0, v[130:131]
	s_mov_b32 m0, s25
	s_nop 0
	global_load_lds_dwordx4 v[222:223], off
	s_barrier
	s_setprio 1
	s_waitcnt lgkmcnt(7)
	v_mfma_f32_16x16x32_bf16 v[60:63], v[152:155], v[168:171], v[60:63]
	v_mfma_f32_16x16x32_bf16 v[56:59], v[160:163], v[168:171], v[56:59]
	s_waitcnt lgkmcnt(5)
	v_mfma_f32_16x16x32_bf16 v[44:47], v[152:155], v[176:179], v[44:47]
	v_mfma_f32_16x16x32_bf16 v[40:43], v[160:163], v[176:179], v[40:43]
	s_waitcnt lgkmcnt(3)
	v_mfma_f32_16x16x32_bf16 v[28:31], v[152:155], v[184:187], v[28:31]
	v_mfma_f32_16x16x32_bf16 v[24:27], v[160:163], v[184:187], v[24:27]
	s_waitcnt lgkmcnt(1)
	v_mfma_f32_16x16x32_bf16 v[12:15], v[152:155], v[192:195], v[12:15]
	v_mfma_f32_16x16x32_bf16 v[8:11], v[160:163], v[192:195], v[8:11]
	v_mfma_f32_16x16x32_bf16 v[60:63], v[156:159], v[172:175], v[60:63]
	v_mfma_f32_16x16x32_bf16 v[56:59], v[164:167], v[172:175], v[56:59]
	v_mfma_f32_16x16x32_bf16 v[44:47], v[156:159], v[180:183], v[44:47]
	v_mfma_f32_16x16x32_bf16 v[40:43], v[164:167], v[180:183], v[40:43]
	v_mfma_f32_16x16x32_bf16 v[28:31], v[156:159], v[188:191], v[28:31]
	v_mfma_f32_16x16x32_bf16 v[24:27], v[164:167], v[188:191], v[24:27]
	s_waitcnt lgkmcnt(0)
	v_mfma_f32_16x16x32_bf16 v[12:15], v[156:159], v[198:201], v[12:15]
	v_mfma_f32_16x16x32_bf16 v[8:11], v[164:167], v[198:201], v[8:11]
	s_setprio 0
	s_barrier
; #define PG8_STAGE(bufoff, gbase, voff) do { _Pragma("unroll") for (int _i = 0; _i < 2; ++_i) \
;         __builtin_amdgcn_global_load_lds((const unsigned*)((const char*)(gbase) + (voff)[_i]), (LAS unsigned*)(lds + (bufoff) + ldsw + _i * 8192), 16, 0, 0); } while (0)
; #define PG8_LDA(dst, b, h) do { _Pragma("unroll") for (int m = 0; m < 4; ++m) _Pragma("unroll") for (int k = 0; k < 2; ++k) dst[m][k] = *(const LAS bf16x8*)(lds + PG8_SA(b, h) + aoff + m * 2048 + k * 1024); } while (0)
; #define PG8_LDB(dst, b, h) do { _Pragma("unroll") for (int n = 0; n < 2; ++n) _Pragma("unroll") for (int k = 0; k < 2; ++k) dst[n][k] = *(const LAS bf16x8*)(lds + PG8_SB(b, h) + boff + n * 2048 + k * 1024); } while (0)
; #define PG8_MMA(ai, bj, At, Bt) do { __builtin_amdgcn_s_setprio(1); _Pragma("unroll") for (int m = 0; m < 4; ++m) _Pragma("unroll") for (int n = 0; n < 2; ++n) _Pragma("unroll") for (int k = 0; k < 2; ++k) \
;         acc[ai][bj][m][n] = __builtin_amdgcn_mfma_f32_16x16x32_bf16(Bt[n][k], At[m][k], acc[ai][bj][m][n], 0, 0, 0); __builtin_amdgcn_s_setprio(0); } while (0)
; #define PG8_WAIT_V(n) asm volatile("s_waitcnt vmcnt(" #n ")" ::: "memory")
; #define PG8_WAIT_L(n) asm volatile("s_waitcnt lgkmcnt(" #n ")" ::: "memory")
; #define PG8_BAR __builtin_amdgcn_s_barrier()
; #define PG8_SCHED __builtin_amdgcn_sched_barrier(0)
; template <class Map, class Epi>
; DI void gemm_phase(LAS unsigned char* lds, const Map& MP, const Epi& E, const int nM, const int nN, const int K, const int lda, const int ldb) {
;     ...
;             PG8_STAGE(PG8_SB(0, 1), b2 + hstepB, voffB);
;             PG8_WAIT_V(6); PG8_BAR; PG8_MMA(1, 1, At, B1); PG8_BAR;
;             PG8_LDB(B0, 1, 0); PG8_SCHED; PG8_LDA(At, 1, 0); PG8_STAGE(PG8_SA(0, 1), a2 + hstepA, voffA);
;             PG8_WAIT_L(8); PG8_BAR; PG8_WAIT_L(0); PG8_MMA(0, 0, At, B0); PG8_BAR; PG8_SCHED;
;             PG8_LDB(B1, 1, 1); PG8_STAGE(PG8_SB(1, 0), b3, voffB);
;             PG8_BAR; PG8_WAIT_L(0); PG8_MMA(0, 1, At, B1); PG8_BAR;
	s_add_u32 s8, s12, 0x160000
	s_addc_u32 s9, s13, 0
	s_add_i32 s39, s36, s22
	v_lshl_add_u64 v[152:153], s[8:9], 0, v[132:133]
	s_mov_b32 m0, s39
	s_nop 0
	global_load_lds_dwordx4 v[152:153], off
	v_lshl_add_u64 v[152:153], s[8:9], 0, v[128:129]
	s_add_i32 m0, s39, 0x2000
	s_nop 0
	global_load_lds_dwordx4 v[152:153], off
	s_waitcnt vmcnt(6)
	s_barrier
	s_setprio 1
	v_mfma_f32_16x16x32_bf16 v[52:55], v[202:205], v[168:171], v[52:55]
	v_mfma_f32_16x16x32_bf16 v[48:51], v[210:213], v[168:171], v[48:51]
	v_mfma_f32_16x16x32_bf16 v[36:39], v[202:205], v[176:179], v[36:39]
	v_mfma_f32_16x16x32_bf16 v[32:35], v[210:213], v[176:179], v[32:35]
	v_mfma_f32_16x16x32_bf16 v[20:23], v[202:205], v[184:187], v[20:23]
	v_mfma_f32_16x16x32_bf16 v[16:19], v[210:213], v[184:187], v[16:19]
	v_mfma_f32_16x16x32_bf16 v[4:7], v[202:205], v[192:195], v[4:7]
	v_mfma_f32_16x16x32_bf16 v[0:3], v[210:213], v[192:195], v[0:3]
	v_mfma_f32_16x16x32_bf16 v[52:55], v[206:209], v[172:175], v[52:55]
	v_mfma_f32_16x16x32_bf16 v[48:51], v[214:217], v[172:175], v[48:51]
	v_mfma_f32_16x16x32_bf16 v[36:39], v[206:209], v[180:183], v[36:39]
	v_mfma_f32_16x16x32_bf16 v[32:35], v[214:217], v[180:183], v[32:35]
	v_mfma_f32_16x16x32_bf16 v[20:23], v[206:209], v[188:191], v[20:23]
	v_mfma_f32_16x16x32_bf16 v[16:19], v[214:217], v[188:191], v[16:19]
	v_mfma_f32_16x16x32_bf16 v[4:7], v[206:209], v[198:201], v[4:7]
	v_mfma_f32_16x16x32_bf16 v[0:3], v[214:217], v[198:201], v[0:3]
	s_setprio 0
	s_add_i32 s39, 0, 0x18000
	v_add_u32_e32 v164, s39, v148
	s_barrier
	ds_read_b128 v[152:155], v164
	ds_read_b128 v[156:159], v164 offset:1024
	ds_read_b128 v[160:163], v164 offset:2048
	ds_read_b128 v[164:167], v164 offset:3072
	s_add_u32 s8, s14, 0x160000
	s_addc_u32 s9, s15, 0
	s_mov_b32 m0, s26
	v_lshl_add_u64 v[202:203], s[8:9], 0, v[134:135]
	ds_read_b128 v[168:171], v150 offset:32768
	ds_read_b128 v[172:175], v150 offset:33792
	ds_read_b128 v[176:179], v150 offset:34816
	ds_read_b128 v[180:183], v150 offset:35840
	ds_read_b128 v[184:187], v150 offset:36864
	ds_read_b128 v[188:191], v150 offset:37888
	ds_read_b128 v[192:195], v150 offset:38912
	ds_read_b128 v[198:201], v150 offset:39936
	global_load_lds_dwordx4 v[202:203], off
	v_lshl_add_u64 v[202:203], s[8:9], 0, v[130:131]
	s_mov_b32 m0, s27
	s_nop 0
	global_load_lds_dwordx4 v[202:203], off
	s_waitcnt lgkmcnt(8)
	s_barrier
	s_setprio 1
	s_waitcnt lgkmcnt(7)
	v_mfma_f32_16x16x32_bf16 v[124:127], v[152:155], v[168:171], v[124:127]
	v_mfma_f32_16x16x32_bf16 v[120:123], v[160:163], v[168:171], v[120:123]
	s_waitcnt lgkmcnt(5)
	v_mfma_f32_16x16x32_bf16 v[108:111], v[152:155], v[176:179], v[108:111]
	v_mfma_f32_16x16x32_bf16 v[104:107], v[160:163], v[176:179], v[104:107]
	s_waitcnt lgkmcnt(3)
	v_mfma_f32_16x16x32_bf16 v[92:95], v[152:155], v[184:187], v[92:95]
	v_mfma_f32_16x16x32_bf16 v[88:91], v[160:163], v[184:187], v[88:91]
	s_waitcnt lgkmcnt(1)
	v_mfma_f32_16x16x32_bf16 v[76:79], v[152:155], v[192:195], v[76:79]
	v_mfma_f32_16x16x32_bf16 v[72:75], v[160:163], v[192:195], v[72:75]
	v_mfma_f32_16x16x32_bf16 v[124:127], v[156:159], v[172:175], v[124:127]
	v_mfma_f32_16x16x32_bf16 v[120:123], v[164:167], v[172:175], v[120:123]
	v_mfma_f32_16x16x32_bf16 v[108:111], v[156:159], v[180:183], v[108:111]
	v_mfma_f32_16x16x32_bf16 v[104:107], v[164:167], v[180:183], v[104:107]
	v_mfma_f32_16x16x32_bf16 v[92:95], v[156:159], v[188:191], v[92:95]
	v_mfma_f32_16x16x32_bf16 v[88:91], v[164:167], v[188:191], v[88:91]
	s_waitcnt lgkmcnt(0)
	v_mfma_f32_16x16x32_bf16 v[76:79], v[156:159], v[198:201], v[76:79]
	v_mfma_f32_16x16x32_bf16 v[72:75], v[164:167], v[198:201], v[72:75]
	s_setprio 0
	s_barrier
	s_add_i32 s14, 0, 0x1c000
	s_add_i32 s8, s39, s22
	v_add_u32_e32 v196, s14, v148
	v_lshl_add_u64 v[144:145], v[144:145], 0, s[52:53]
	s_mov_b32 m0, s8
	ds_read_b128 v[202:205], v196
	ds_read_b128 v[206:209], v196 offset:1024
	ds_read_b128 v[210:213], v196 offset:2048
	ds_read_b128 v[214:217], v196 offset:3072
	global_load_lds_dwordx4 v[144:145], off
	v_lshl_add_u64 v[144:145], v[218:219], 0, s[52:53]
	s_add_i32 m0, s8, 0x2000
	s_nop 0
	global_load_lds_dwordx4 v[144:145], off
	s_barrier
	s_setprio 1
	s_waitcnt lgkmcnt(3)
	v_mfma_f32_16x16x32_bf16 v[116:119], v[202:205], v[168:171], v[116:119]
	s_waitcnt lgkmcnt(1)
	v_mfma_f32_16x16x32_bf16 v[112:115], v[210:213], v[168:171], v[112:115]
	v_mfma_f32_16x16x32_bf16 v[100:103], v[202:205], v[176:179], v[100:103]
	v_mfma_f32_16x16x32_bf16 v[96:99], v[210:213], v[176:179], v[96:99]
	v_mfma_f32_16x16x32_bf16 v[84:87], v[202:205], v[184:187], v[84:87]
	v_mfma_f32_16x16x32_bf16 v[80:83], v[210:213], v[184:187], v[80:83]
	v_mfma_f32_16x16x32_bf16 v[68:71], v[202:205], v[192:195], v[68:71]
	v_mfma_f32_16x16x32_bf16 v[64:67], v[210:213], v[192:195], v[64:67]
	v_mfma_f32_16x16x32_bf16 v[116:119], v[206:209], v[172:175], v[116:119]
	s_waitcnt lgkmcnt(0)
	v_mfma_f32_16x16x32_bf16 v[112:115], v[214:217], v[172:175], v[112:115]
	v_mfma_f32_16x16x32_bf16 v[100:103], v[206:209], v[180:183], v[100:103]
	v_mfma_f32_16x16x32_bf16 v[96:99], v[214:217], v[180:183], v[96:99]
	v_mfma_f32_16x16x32_bf16 v[84:87], v[206:209], v[188:191], v[84:87]
	v_mfma_f32_16x16x32_bf16 v[80:83], v[214:217], v[188:191], v[80:83]
	v_mfma_f32_16x16x32_bf16 v[68:71], v[206:209], v[198:201], v[68:71]
	v_mfma_f32_16x16x32_bf16 v[64:67], v[214:217], v[198:201], v[64:67]
	s_setprio 0
	s_mov_b32 m0, s30
	v_lshl_add_u64 v[144:145], v[220:221], 0, s[52:53]
	s_barrier
; DI unsigned pack2(float a, float b) { f32x2 v = {a, b}; hwbf16x2 r = __builtin_convertvector(v, hwbf16x2); return __builtin_bit_cast(unsigned, r); }
; DI float bflo(unsigned w) { return __uint_as_float(w << 16); }
; DI float bfhi(unsigned w) { return __uint_as_float(w & 0xffff0000u); }
; #define PG8_STAGE(bufoff, gbase, voff) do { _Pragma("unroll") for (int _i = 0; _i < 2; ++_i) \
;         __builtin_amdgcn_global_load_lds((const unsigned*)((const char*)(gbase) + (voff)[_i]), (LAS unsigned*)(lds + (bufoff) + ldsw + _i * 8192), 16, 0, 0); } while (0)
; #define PG8_WAIT_V(n) asm volatile("s_waitcnt vmcnt(" #n ")" ::: "memory")
;     DI void operator()(const f32x4 (&acc)[2][2][4][2], const Unit& u, int wr, int wc, int fr, int fq) const {
;     ...
;         for (int ai = 0; ai < 2; ++ai)
; #pragma unroll
;             for (int m = 0; m < 4; ++m) { const size_t ro = (size_t)(row0 + ai * HALF + m * 16) * D + col0;
; #pragma unroll
;                 for (int bj = 0; bj < 2; ++bj) {
;                     f32x4 x0, x1;
;                     if constexpr (IB) { const u32x4 w = *(const u32x4*)((const bf16_t*)Xin + ro + bj * HALF);
;                         x0 = (f32x4){bflo(w[0]), bfhi(w[0]), bflo(w[1]), bfhi(w[1])}; x1 = (f32x4){bflo(w[2]), bfhi(w[2]), bflo(w[3]), bfhi(w[3])}; }
;                     else { x0 = *(const f32x4*)((const float*)Xin + ro + bj * HALF); x1 = *(const f32x4*)((const float*)Xin + ro + bj * HALF + 4); }
;                     x0 += acc[ai][bj][m][0] * sc[bj][0]; x1 += acc[ai][bj][m][1] * sc[bj][1];
;                     if constexpr (OB) { u32x4 o; o[0] = pack2(x0[0], x0[1]); o[1] = pack2(x0[2], x0[3]); o[2] = pack2(x1[0], x1[1]); o[3] = pack2(x1[2], x1[3]);
;                         *(u32x4*)((bf16_t*)Xout + ro + bj * HALF) = o; }
;                     else { *(f32x4*)((float*)Xout + ro + bj * HALF) = x0; *(f32x4*)((float*)Xout + ro + bj * HALF + 4) = x1; } } }
; template <class Map, class Epi>
; DI void gemm_phase(LAS unsigned char* lds, const Map& MP, const Epi& E, const int nM, const int nN, const int K, const int lda, const int ldb) {
;     ...
;             PG8_LDA(At, 1, 1); PG8_STAGE(PG8_SA(1, 0), a3, voffA);
;             PG8_BAR; PG8_WAIT_L(0); PG8_MMA(1, 0, At, B0); PG8_BAR; PG8_SCHED;
;             PG8_STAGE(PG8_SB(1, 1), b3 + hstepB, voffB);
;             PG8_WAIT_V(6); PG8_BAR; PG8_MMA(1, 1, At, B1); PG8_BAR;
	ds_read_b128 v[168:171], v150 offset:49152
	ds_read_b128 v[172:175], v150 offset:50176
	ds_read_b128 v[176:179], v150 offset:51200
	ds_read_b128 v[180:183], v150 offset:52224
	ds_read_b128 v[184:187], v150 offset:53248
	ds_read_b128 v[188:191], v150 offset:54272
	ds_read_b128 v[192:195], v150 offset:55296
	ds_read_b128 v[198:201], v150 offset:56320
	global_load_lds_dwordx4 v[144:145], off
	v_lshl_add_u64 v[144:145], v[222:223], 0, s[52:53]
	s_mov_b32 m0, s31
	s_nop 0
	global_load_lds_dwordx4 v[144:145], off
	s_barrier
	s_setprio 1
	s_waitcnt lgkmcnt(7)
	v_mfma_f32_16x16x32_bf16 v[60:63], v[152:155], v[168:171], v[60:63]
	v_mfma_f32_16x16x32_bf16 v[56:59], v[160:163], v[168:171], v[56:59]
	s_waitcnt lgkmcnt(5)
	v_mfma_f32_16x16x32_bf16 v[44:47], v[152:155], v[176:179], v[44:47]
	v_mfma_f32_16x16x32_bf16 v[40:43], v[160:163], v[176:179], v[40:43]
	s_waitcnt lgkmcnt(3)
	v_mfma_f32_16x16x32_bf16 v[28:31], v[152:155], v[184:187], v[28:31]
	v_mfma_f32_16x16x32_bf16 v[24:27], v[160:163], v[184:187], v[24:27]
	s_waitcnt lgkmcnt(1)
	v_mfma_f32_16x16x32_bf16 v[12:15], v[152:155], v[192:195], v[12:15]
	v_mfma_f32_16x16x32_bf16 v[8:11], v[160:163], v[192:195], v[8:11]
	v_mfma_f32_16x16x32_bf16 v[60:63], v[156:159], v[172:175], v[60:63]
	v_mfma_f32_16x16x32_bf16 v[56:59], v[164:167], v[172:175], v[56:59]
	v_mfma_f32_16x16x32_bf16 v[44:47], v[156:159], v[180:183], v[44:47]
	v_mfma_f32_16x16x32_bf16 v[40:43], v[164:167], v[180:183], v[40:43]
	v_mfma_f32_16x16x32_bf16 v[28:31], v[156:159], v[188:191], v[28:31]
	v_mfma_f32_16x16x32_bf16 v[24:27], v[164:167], v[188:191], v[24:27]
	s_waitcnt lgkmcnt(0)
	v_mfma_f32_16x16x32_bf16 v[12:15], v[156:159], v[198:201], v[12:15]
	v_mfma_f32_16x16x32_bf16 v[8:11], v[164:167], v[198:201], v[8:11]
	s_setprio 0
	s_barrier
	s_add_u32 s8, s12, 0x160080
	s_addc_u32 s9, s13, 0
	s_add_i32 s12, s14, s22
	v_lshl_add_u64 v[144:145], s[8:9], 0, v[132:133]
	s_mov_b32 m0, s12
	s_nop 0
	global_load_lds_dwordx4 v[144:145], off
	v_lshl_add_u64 v[144:145], s[8:9], 0, v[128:129]
	s_add_i32 m0, s12, 0x2000
	s_nop 0
	global_load_lds_dwordx4 v[144:145], off
	s_waitcnt vmcnt(6)
	s_barrier
	s_setprio 1
	v_mfma_f32_16x16x32_bf16 v[52:55], v[202:205], v[168:171], v[52:55]
	v_mfma_f32_16x16x32_bf16 v[48:51], v[210:213], v[168:171], v[48:51]
	v_mfma_f32_16x16x32_bf16 v[36:39], v[202:205], v[176:179], v[36:39]
	v_mfma_f32_16x16x32_bf16 v[32:35], v[210:213], v[176:179], v[32:35]
	v_mfma_f32_16x16x32_bf16 v[20:23], v[202:205], v[184:187], v[20:23]
	v_mfma_f32_16x16x32_bf16 v[16:19], v[210:213], v[184:187], v[16:19]
	v_mfma_f32_16x16x32_bf16 v[4:7], v[202:205], v[192:195], v[4:7]
	v_mfma_f32_16x16x32_bf16 v[0:3], v[210:213], v[192:195], v[0:3]
	v_mfma_f32_16x16x32_bf16 v[52:55], v[206:209], v[172:175], v[52:55]
	v_mfma_f32_16x16x32_bf16 v[48:51], v[214:217], v[172:175], v[48:51]
	v_mfma_f32_16x16x32_bf16 v[36:39], v[206:209], v[180:183], v[36:39]
	v_mfma_f32_16x16x32_bf16 v[32:35], v[214:217], v[180:183], v[32:35]
	v_mfma_f32_16x16x32_bf16 v[20:23], v[206:209], v[188:191], v[20:23]
	v_mfma_f32_16x16x32_bf16 v[16:19], v[214:217], v[188:191], v[16:19]
	v_mfma_f32_16x16x32_bf16 v[4:7], v[206:209], v[198:201], v[4:7]
	v_mfma_f32_16x16x32_bf16 v[0:3], v[214:217], v[198:201], v[0:3]
	s_setprio 0
	s_add_i32 s3, s3, 2
	s_add_u32 s5, s5, 0x100
	s_addc_u32 s38, s38, 0
	s_cmpk_gt_u32 s3, 0x55
	s_mov_b64 s[8:9], s[10:11]
	s_barrier
	s_cbranch_scc0 .LBB1_1239
	v_mov_b32_e32 v152, v147
	v_mov_b32_e32 v144, v146
	s_lshl_b32 s2, s2, 8
	s_add_i32 s2, s2, s29
	s_lshl_b32 s3, s4, 8
	v_add_u32_e32 v152, s2, v152
	s_or_b32 s3, s3, s54
	v_ashrrev_i32_e32 v153, 31, v152
	v_lshl_add_u32 v144, v144, 3, s3
	v_lshlrev_b64 v[152:153], 12, v[152:153]
	v_ashrrev_i32_e32 v145, 31, v144
	v_lshl_add_u64 v[152:153], s[46:47], 0, v[152:153]
	v_lshl_add_u64 v[144:145], v[144:145], 1, v[152:153]
	global_load_dwordx4 v[152:155], v[144:145], off
	s_mov_b64 s[2:3], 0x10000
	s_mov_b32 s4, s37
	s_mov_b64 s[10:11], s[6:7]
	s_mov_b64 s[8:9], s[42:43]
	s_waitcnt vmcnt(0) lgkmcnt(0)
	v_lshlrev_b32_e32 v156, 16, v152
	v_and_b32_e32 v157, 0xffff0000, v152
	v_lshlrev_b32_e32 v152, 16, v153
	v_and_b32_e32 v153, 0xffff0000, v153
	v_lshlrev_b32_e32 v158, 16, v154
	v_and_b32_e32 v159, 0xffff0000, v154
	v_lshlrev_b32_e32 v154, 16, v155
	v_and_b32_e32 v155, 0xffff0000, v155
	v_pk_add_f32 v[126:127], v[126:127], v[152:153]
	v_pk_add_f32 v[124:125], v[124:125], v[156:157]
	v_pk_add_f32 v[152:153], v[122:123], v[154:155]
	v_pk_add_f32 v[122:123], v[120:121], v[158:159]
	v_cvt_pk_bf16_f32 v120, v124, v125
	v_cvt_pk_bf16_f32 v121, v126, v127
	v_cvt_pk_bf16_f32 v122, v122, v123
	v_cvt_pk_bf16_f32 v123, v152, v153
	global_store_dwordx4 v[144:145], v[120:123], off
	global_load_dwordx4 v[120:123], v[144:145], off offset:256
	s_waitcnt vmcnt(0) lgkmcnt(0)
	v_lshlrev_b32_e32 v124, 16, v120
	v_and_b32_e32 v125, 0xffff0000, v120
	v_lshlrev_b32_e32 v120, 16, v121
	v_and_b32_e32 v121, 0xffff0000, v121
	v_lshlrev_b32_e32 v126, 16, v122
	v_and_b32_e32 v127, 0xffff0000, v122
	v_lshlrev_b32_e32 v122, 16, v123
	v_and_b32_e32 v123, 0xffff0000, v123
	v_pk_add_f32 v[116:117], v[116:117], v[124:125]
	v_pk_add_f32 v[118:119], v[118:119], v[120:121]
	v_pk_add_f32 v[120:121], v[114:115], v[122:123]
	v_pk_add_f32 v[114:115], v[112:113], v[126:127]
	v_cvt_pk_bf16_f32 v112, v116, v117
	v_lshl_add_u64 v[116:117], v[144:145], 0, s[2:3]
	s_mov_b32 s2, 0x10000
	v_cvt_pk_bf16_f32 v113, v118, v119
	v_add_co_u32_e32 v118, vcc, s2, v144
	v_cvt_pk_bf16_f32 v114, v114, v115
	v_cvt_pk_bf16_f32 v115, v120, v121
	v_addc_co_u32_e32 v119, vcc, 0, v145, vcc
	global_store_dwordx4 v[144:145], v[112:115], off offset:256
	global_load_dwordx4 v[112:115], v[118:119], off
	s_mov_b64 s[2:3], 0x20000
	s_waitcnt vmcnt(0) lgkmcnt(0)
; DI unsigned pack2(float a, float b) { f32x2 v = {a, b}; hwbf16x2 r = __builtin_convertvector(v, hwbf16x2); return __builtin_bit_cast(unsigned, r); }
; DI float bflo(unsigned w) { return __uint_as_float(w << 16); }
; DI float bfhi(unsigned w) { return __uint_as_float(w & 0xffff0000u); }
;     DI void operator()(const f32x4 (&acc)[2][2][4][2], const Unit& u, int wr, int wc, int fr, int fq) const {
;     ...
;         for (int ai = 0; ai < 2; ++ai)
; #pragma unroll
;             for (int m = 0; m < 4; ++m) { const size_t ro = (size_t)(row0 + ai * HALF + m * 16) * D + col0;
; #pragma unroll
;                 for (int bj = 0; bj < 2; ++bj) {
;                     f32x4 x0, x1;
;                     if constexpr (IB) { const u32x4 w = *(const u32x4*)((const bf16_t*)Xin + ro + bj * HALF);
;                         x0 = (f32x4){bflo(w[0]), bfhi(w[0]), bflo(w[1]), bfhi(w[1])}; x1 = (f32x4){bflo(w[2]), bfhi(w[2]), bflo(w[3]), bfhi(w[3])}; }
;                     else { x0 = *(const f32x4*)((const float*)Xin + ro + bj * HALF); x1 = *(const f32x4*)((const float*)Xin + ro + bj * HALF + 4); }
;                     x0 += acc[ai][bj][m][0] * sc[bj][0]; x1 += acc[ai][bj][m][1] * sc[bj][1];
;                     if constexpr (OB) { u32x4 o; o[0] = pack2(x0[0], x0[1]); o[1] = pack2(x0[2], x0[3]); o[2] = pack2(x1[0], x1[1]); o[3] = pack2(x1[2], x1[3]);
;                         *(u32x4*)((bf16_t*)Xout + ro + bj * HALF) = o; }
;                     else { *(f32x4*)((float*)Xout + ro + bj * HALF) = x0; *(f32x4*)((float*)Xout + ro + bj * HALF + 4) = x1; } } }
	v_lshlrev_b32_e32 v120, 16, v112
	v_and_b32_e32 v121, 0xffff0000, v112
	v_lshlrev_b32_e32 v112, 16, v113
	v_and_b32_e32 v113, 0xffff0000, v113
	v_lshlrev_b32_e32 v122, 16, v114
	v_and_b32_e32 v123, 0xffff0000, v114
	v_lshlrev_b32_e32 v114, 16, v115
	v_and_b32_e32 v115, 0xffff0000, v115
	v_pk_add_f32 v[110:111], v[110:111], v[112:113]
	v_pk_add_f32 v[108:109], v[108:109], v[120:121]
	v_pk_add_f32 v[112:113], v[106:107], v[114:115]
	v_pk_add_f32 v[106:107], v[104:105], v[122:123]
	v_cvt_pk_bf16_f32 v104, v108, v109
	v_cvt_pk_bf16_f32 v105, v110, v111
	v_cvt_pk_bf16_f32 v106, v106, v107
	v_cvt_pk_bf16_f32 v107, v112, v113
	global_store_dwordx4 v[118:119], v[104:107], off
	global_load_dwordx4 v[104:107], v[116:117], off offset:256
	s_waitcnt vmcnt(0) lgkmcnt(0)
	v_lshlrev_b32_e32 v108, 16, v104
	v_and_b32_e32 v109, 0xffff0000, v104
	v_lshlrev_b32_e32 v104, 16, v105
	v_and_b32_e32 v105, 0xffff0000, v105
	v_lshlrev_b32_e32 v110, 16, v106
	v_and_b32_e32 v111, 0xffff0000, v106
	v_lshlrev_b32_e32 v106, 16, v107
	v_and_b32_e32 v107, 0xffff0000, v107
	v_pk_add_f32 v[100:101], v[100:101], v[108:109]
	v_pk_add_f32 v[102:103], v[102:103], v[104:105]
	v_pk_add_f32 v[104:105], v[98:99], v[106:107]
	v_pk_add_f32 v[98:99], v[96:97], v[110:111]
	v_cvt_pk_bf16_f32 v96, v100, v101
	v_lshl_add_u64 v[100:101], v[144:145], 0, s[2:3]
	s_mov_b32 s2, 0x20000
	v_cvt_pk_bf16_f32 v97, v102, v103
	v_add_co_u32_e32 v102, vcc, s2, v144
	v_cvt_pk_bf16_f32 v98, v98, v99
	v_cvt_pk_bf16_f32 v99, v104, v105
	v_addc_co_u32_e32 v103, vcc, 0, v145, vcc
	global_store_dwordx4 v[116:117], v[96:99], off offset:256
	global_load_dwordx4 v[96:99], v[102:103], off
	s_mov_b64 s[2:3], 0x30000
	s_waitcnt vmcnt(0) lgkmcnt(0)
	v_lshlrev_b32_e32 v104, 16, v96
	v_and_b32_e32 v105, 0xffff0000, v96
	v_lshlrev_b32_e32 v96, 16, v97
	v_and_b32_e32 v97, 0xffff0000, v97
	v_lshlrev_b32_e32 v106, 16, v98
	v_and_b32_e32 v107, 0xffff0000, v98
	v_lshlrev_b32_e32 v98, 16, v99
	v_and_b32_e32 v99, 0xffff0000, v99
	v_pk_add_f32 v[94:95], v[94:95], v[96:97]
	v_pk_add_f32 v[92:93], v[92:93], v[104:105]
	v_pk_add_f32 v[96:97], v[90:91], v[98:99]
	v_pk_add_f32 v[90:91], v[88:89], v[106:107]
	v_cvt_pk_bf16_f32 v88, v92, v93
	v_cvt_pk_bf16_f32 v89, v94, v95
	v_cvt_pk_bf16_f32 v90, v90, v91
	v_cvt_pk_bf16_f32 v91, v96, v97
	global_store_dwordx4 v[102:103], v[88:91], off
	global_load_dwordx4 v[88:91], v[100:101], off offset:256
	s_waitcnt vmcnt(0) lgkmcnt(0)
	v_lshlrev_b32_e32 v92, 16, v88
	v_and_b32_e32 v93, 0xffff0000, v88
	v_lshlrev_b32_e32 v88, 16, v89
	v_and_b32_e32 v89, 0xffff0000, v89
	v_lshlrev_b32_e32 v94, 16, v90
	v_and_b32_e32 v95, 0xffff0000, v90
	v_lshlrev_b32_e32 v90, 16, v91
	v_and_b32_e32 v91, 0xffff0000, v91
	v_pk_add_f32 v[86:87], v[86:87], v[88:89]
	v_pk_add_f32 v[84:85], v[84:85], v[92:93]
	v_pk_add_f32 v[88:89], v[82:83], v[90:91]
	v_pk_add_f32 v[82:83], v[80:81], v[94:95]
	v_cvt_pk_bf16_f32 v80, v84, v85
	v_cvt_pk_bf16_f32 v81, v86, v87
	v_cvt_pk_bf16_f32 v82, v82, v83
	v_cvt_pk_bf16_f32 v83, v88, v89
	global_store_dwordx4 v[100:101], v[80:83], off offset:256
	s_nop 1
	v_lshl_add_u64 v[80:81], v[144:145], 0, s[2:3]
	s_mov_b32 s2, 0x30000
	v_add_co_u32_e32 v86, vcc, s2, v144
	s_mov_b64 s[2:3], 0x80000
	s_nop 0
	v_addc_co_u32_e32 v87, vcc, 0, v145, vcc
	global_load_dwordx4 v[82:85], v[86:87], off
	s_waitcnt vmcnt(0) lgkmcnt(0)
	v_lshlrev_b32_e32 v88, 16, v82
	v_and_b32_e32 v89, 0xffff0000, v82
	v_lshlrev_b32_e32 v82, 16, v83
	v_and_b32_e32 v83, 0xffff0000, v83
	v_lshlrev_b32_e32 v90, 16, v84
	v_and_b32_e32 v91, 0xffff0000, v84
	v_lshlrev_b32_e32 v84, 16, v85
	v_and_b32_e32 v85, 0xffff0000, v85
	v_pk_add_f32 v[78:79], v[78:79], v[82:83]
	v_pk_add_f32 v[76:77], v[76:77], v[88:89]
	v_pk_add_f32 v[82:83], v[74:75], v[84:85]
	v_pk_add_f32 v[74:75], v[72:73], v[90:91]
	v_cvt_pk_bf16_f32 v72, v76, v77
	v_cvt_pk_bf16_f32 v73, v78, v79
	v_cvt_pk_bf16_f32 v74, v74, v75
	v_cvt_pk_bf16_f32 v75, v82, v83
	global_store_dwordx4 v[86:87], v[72:75], off
	global_load_dwordx4 v[72:75], v[80:81], off offset:256
	s_waitcnt vmcnt(0) lgkmcnt(0)
	v_lshlrev_b32_e32 v76, 16, v72
	v_and_b32_e32 v77, 0xffff0000, v72
	v_lshlrev_b32_e32 v72, 16, v73
	v_and_b32_e32 v73, 0xffff0000, v73
	v_lshlrev_b32_e32 v78, 16, v74
	v_and_b32_e32 v79, 0xffff0000, v74
	v_lshlrev_b32_e32 v74, 16, v75
	v_and_b32_e32 v75, 0xffff0000, v75
	v_pk_add_f32 v[70:71], v[70:71], v[72:73]
	v_pk_add_f32 v[68:69], v[68:69], v[76:77]
	v_pk_add_f32 v[72:73], v[66:67], v[74:75]
	v_pk_add_f32 v[66:67], v[64:65], v[78:79]
	v_cvt_pk_bf16_f32 v64, v68, v69
	v_cvt_pk_bf16_f32 v65, v70, v71
	v_cvt_pk_bf16_f32 v66, v66, v67
	v_cvt_pk_bf16_f32 v67, v72, v73
	global_store_dwordx4 v[80:81], v[64:67], off offset:256
	s_nop 1
	v_lshl_add_u64 v[64:65], v[144:145], 0, s[2:3]
	s_mov_b32 s2, 0x80000
	v_add_co_u32_e32 v70, vcc, s2, v144
	s_mov_b64 s[2:3], 0x90000
	s_nop 0
	v_addc_co_u32_e32 v71, vcc, 0, v145, vcc
	global_load_dwordx4 v[66:69], v[70:71], off
	s_waitcnt vmcnt(0) lgkmcnt(0)
	v_lshlrev_b32_e32 v72, 16, v66
	v_and_b32_e32 v73, 0xffff0000, v66
	v_lshlrev_b32_e32 v66, 16, v67
	v_and_b32_e32 v67, 0xffff0000, v67
	v_lshlrev_b32_e32 v74, 16, v68
	v_and_b32_e32 v75, 0xffff0000, v68
	v_lshlrev_b32_e32 v68, 16, v69
	v_and_b32_e32 v69, 0xffff0000, v69
	v_pk_add_f32 v[62:63], v[62:63], v[66:67]
	v_pk_add_f32 v[60:61], v[60:61], v[72:73]
	v_pk_add_f32 v[66:67], v[58:59], v[68:69]
	v_pk_add_f32 v[58:59], v[56:57], v[74:75]
	v_cvt_pk_bf16_f32 v56, v60, v61
	v_cvt_pk_bf16_f32 v57, v62, v63
	v_cvt_pk_bf16_f32 v58, v58, v59
	v_cvt_pk_bf16_f32 v59, v66, v67
	global_store_dwordx4 v[70:71], v[56:59], off
	global_load_dwordx4 v[56:59], v[64:65], off offset:256
	s_waitcnt vmcnt(0) lgkmcnt(0)
; DI unsigned pack2(float a, float b) { f32x2 v = {a, b}; hwbf16x2 r = __builtin_convertvector(v, hwbf16x2); return __builtin_bit_cast(unsigned, r); }
; DI float bflo(unsigned w) { return __uint_as_float(w << 16); }
; DI float bfhi(unsigned w) { return __uint_as_float(w & 0xffff0000u); }
;     DI const char* a(const Unit& u) const { return (const char*)(A + (size_t)u.pm * BM * lda); }
;     DI const char* a(const Unit& u) const { return (const char*)(A + (size_t)u.pm * BM * 2048 + (u.pn >> 1) * 512); }
;     DI void operator()(const f32x4 (&acc)[2][2][4][2], const Unit& u, int wr, int wc, int fr, int fq) const {
;     ...
;         for (int ai = 0; ai < 2; ++ai)
; #pragma unroll
;             for (int m = 0; m < 4; ++m) { const size_t ro = (size_t)(row0 + ai * HALF + m * 16) * D + col0;
; #pragma unroll
;                 for (int bj = 0; bj < 2; ++bj) {
;                     f32x4 x0, x1;
;                     if constexpr (IB) { const u32x4 w = *(const u32x4*)((const bf16_t*)Xin + ro + bj * HALF);
;                         x0 = (f32x4){bflo(w[0]), bfhi(w[0]), bflo(w[1]), bfhi(w[1])}; x1 = (f32x4){bflo(w[2]), bfhi(w[2]), bflo(w[3]), bfhi(w[3])}; }
;                     else { x0 = *(const f32x4*)((const float*)Xin + ro + bj * HALF); x1 = *(const f32x4*)((const float*)Xin + ro + bj * HALF + 4); }
;                     x0 += acc[ai][bj][m][0] * sc[bj][0]; x1 += acc[ai][bj][m][1] * sc[bj][1];
;                     if constexpr (OB) { u32x4 o; o[0] = pack2(x0[0], x0[1]); o[1] = pack2(x0[2], x0[3]); o[2] = pack2(x1[0], x1[1]); o[3] = pack2(x1[2], x1[3]);
;                         *(u32x4*)((bf16_t*)Xout + ro + bj * HALF) = o; }
;                     else { *(f32x4*)((float*)Xout + ro + bj * HALF) = x0; *(f32x4*)((float*)Xout + ro + bj * HALF + 4) = x1; } } }
; template <class Map, class Epi>
; DI void gemm_phase(LAS unsigned char* lds, const Map& MP, const Epi& E, const int nM, const int nN, const int K, const int lda, const int ldb) {
;     ...
;         if (!has_next) break;
; #pragma unroll
;         for (int a = 0; a < 2; ++a)
; #pragma unroll
;             for (int b = 0; b < 2; ++b)
; #pragma unroll
;                 for (int m = 0; m < 4; ++m)
; #pragma unroll
;                     for (int n = 0; n < 2; ++n) acc[a][b][m][n] = (f32x4){0.f, 0.f, 0.f, 0.f};
;         cur = nxt; cA = nA; cB = nB; ++ui;
;     }
;     PG8_WAIT_V(0);
;     if (wr == 0) PG8_BAR;
;     PG8_BAR;
	v_lshlrev_b32_e32 v60, 16, v56
	v_and_b32_e32 v61, 0xffff0000, v56
	v_lshlrev_b32_e32 v56, 16, v57
	v_and_b32_e32 v57, 0xffff0000, v57
	v_lshlrev_b32_e32 v62, 16, v58
	v_and_b32_e32 v63, 0xffff0000, v58
	v_lshlrev_b32_e32 v58, 16, v59
	v_and_b32_e32 v59, 0xffff0000, v59
	v_pk_add_f32 v[54:55], v[54:55], v[56:57]
	v_pk_add_f32 v[52:53], v[52:53], v[60:61]
	v_pk_add_f32 v[56:57], v[50:51], v[58:59]
	v_pk_add_f32 v[50:51], v[48:49], v[62:63]
	v_cvt_pk_bf16_f32 v48, v52, v53
	v_cvt_pk_bf16_f32 v49, v54, v55
	v_cvt_pk_bf16_f32 v50, v50, v51
	v_cvt_pk_bf16_f32 v51, v56, v57
	global_store_dwordx4 v[64:65], v[48:51], off offset:256
	s_nop 1
	v_lshl_add_u64 v[48:49], v[144:145], 0, s[2:3]
	s_mov_b32 s2, 0x90000
	v_add_co_u32_e32 v54, vcc, s2, v144
	s_mov_b64 s[2:3], 0xa0000
	s_nop 0
	v_addc_co_u32_e32 v55, vcc, 0, v145, vcc
	global_load_dwordx4 v[50:53], v[54:55], off
	s_waitcnt vmcnt(0) lgkmcnt(0)
	v_lshlrev_b32_e32 v56, 16, v50
	v_and_b32_e32 v57, 0xffff0000, v50
	v_lshlrev_b32_e32 v50, 16, v51
	v_and_b32_e32 v51, 0xffff0000, v51
	v_lshlrev_b32_e32 v58, 16, v52
	v_and_b32_e32 v59, 0xffff0000, v52
	v_lshlrev_b32_e32 v52, 16, v53
	v_and_b32_e32 v53, 0xffff0000, v53
	v_pk_add_f32 v[46:47], v[46:47], v[50:51]
	v_pk_add_f32 v[44:45], v[44:45], v[56:57]
	v_pk_add_f32 v[50:51], v[42:43], v[52:53]
	v_pk_add_f32 v[42:43], v[40:41], v[58:59]
	v_cvt_pk_bf16_f32 v40, v44, v45
	v_cvt_pk_bf16_f32 v41, v46, v47
	v_cvt_pk_bf16_f32 v42, v42, v43
	v_cvt_pk_bf16_f32 v43, v50, v51
	global_store_dwordx4 v[54:55], v[40:43], off
	global_load_dwordx4 v[40:43], v[48:49], off offset:256
	s_waitcnt vmcnt(0) lgkmcnt(0)
	v_lshlrev_b32_e32 v44, 16, v40
	v_and_b32_e32 v45, 0xffff0000, v40
	v_lshlrev_b32_e32 v40, 16, v41
	v_and_b32_e32 v41, 0xffff0000, v41
	v_lshlrev_b32_e32 v46, 16, v42
	v_and_b32_e32 v47, 0xffff0000, v42
	v_lshlrev_b32_e32 v42, 16, v43
	v_and_b32_e32 v43, 0xffff0000, v43
	v_pk_add_f32 v[38:39], v[38:39], v[40:41]
	v_pk_add_f32 v[36:37], v[36:37], v[44:45]
	v_pk_add_f32 v[40:41], v[34:35], v[42:43]
	v_pk_add_f32 v[34:35], v[32:33], v[46:47]
	v_cvt_pk_bf16_f32 v32, v36, v37
	v_cvt_pk_bf16_f32 v33, v38, v39
	v_cvt_pk_bf16_f32 v34, v34, v35
	v_cvt_pk_bf16_f32 v35, v40, v41
	global_store_dwordx4 v[48:49], v[32:35], off offset:256
	s_nop 1
	v_lshl_add_u64 v[32:33], v[144:145], 0, s[2:3]
	s_mov_b32 s2, 0xa0000
	v_add_co_u32_e32 v38, vcc, s2, v144
	s_mov_b64 s[2:3], 0xb0000
	s_nop 0
	v_addc_co_u32_e32 v39, vcc, 0, v145, vcc
	global_load_dwordx4 v[34:37], v[38:39], off
	s_waitcnt vmcnt(0) lgkmcnt(0)
	v_lshlrev_b32_e32 v40, 16, v34
	v_and_b32_e32 v41, 0xffff0000, v34
	v_lshlrev_b32_e32 v34, 16, v35
	v_and_b32_e32 v35, 0xffff0000, v35
	v_lshlrev_b32_e32 v42, 16, v36
	v_and_b32_e32 v43, 0xffff0000, v36
	v_lshlrev_b32_e32 v36, 16, v37
	v_and_b32_e32 v37, 0xffff0000, v37
	v_pk_add_f32 v[30:31], v[30:31], v[34:35]
	v_pk_add_f32 v[28:29], v[28:29], v[40:41]
	v_pk_add_f32 v[34:35], v[26:27], v[36:37]
	v_pk_add_f32 v[26:27], v[24:25], v[42:43]
	v_cvt_pk_bf16_f32 v24, v28, v29
	v_cvt_pk_bf16_f32 v25, v30, v31
	v_cvt_pk_bf16_f32 v26, v26, v27
	v_cvt_pk_bf16_f32 v27, v34, v35
	global_store_dwordx4 v[38:39], v[24:27], off
	global_load_dwordx4 v[24:27], v[32:33], off offset:256
	s_waitcnt vmcnt(0) lgkmcnt(0)
	v_lshlrev_b32_e32 v28, 16, v24
	v_and_b32_e32 v29, 0xffff0000, v24
	v_lshlrev_b32_e32 v24, 16, v25
	v_and_b32_e32 v25, 0xffff0000, v25
	v_lshlrev_b32_e32 v30, 16, v26
	v_and_b32_e32 v31, 0xffff0000, v26
	v_lshlrev_b32_e32 v26, 16, v27
	v_and_b32_e32 v27, 0xffff0000, v27
	v_pk_add_f32 v[22:23], v[22:23], v[24:25]
	v_pk_add_f32 v[20:21], v[20:21], v[28:29]
	v_pk_add_f32 v[24:25], v[18:19], v[26:27]
	v_pk_add_f32 v[18:19], v[16:17], v[30:31]
	v_cvt_pk_bf16_f32 v16, v20, v21
	v_cvt_pk_bf16_f32 v17, v22, v23
	v_cvt_pk_bf16_f32 v18, v18, v19
	v_cvt_pk_bf16_f32 v19, v24, v25
	global_store_dwordx4 v[32:33], v[16:19], off offset:256
	s_nop 1
	v_lshl_add_u64 v[16:17], v[144:145], 0, s[2:3]
	s_mov_b32 s2, 0xb0000
	v_add_co_u32_e32 v22, vcc, s2, v144
	s_mov_b32 s2, s55
	s_nop 0
	v_addc_co_u32_e32 v23, vcc, 0, v145, vcc
	global_load_dwordx4 v[18:21], v[22:23], off
	s_and_b64 vcc, exec, s[40:41]
	s_waitcnt vmcnt(0) lgkmcnt(0)
	v_lshlrev_b32_e32 v24, 16, v18
	v_and_b32_e32 v25, 0xffff0000, v18
	v_lshlrev_b32_e32 v18, 16, v19
	v_and_b32_e32 v19, 0xffff0000, v19
	v_lshlrev_b32_e32 v26, 16, v20
	v_and_b32_e32 v27, 0xffff0000, v20
	v_lshlrev_b32_e32 v20, 16, v21
	v_and_b32_e32 v21, 0xffff0000, v21
	v_pk_add_f32 v[14:15], v[14:15], v[18:19]
	v_pk_add_f32 v[12:13], v[12:13], v[24:25]
	v_pk_add_f32 v[18:19], v[10:11], v[20:21]
	v_pk_add_f32 v[10:11], v[8:9], v[26:27]
	v_cvt_pk_bf16_f32 v8, v12, v13
	v_cvt_pk_bf16_f32 v9, v14, v15
	v_cvt_pk_bf16_f32 v10, v10, v11
	v_cvt_pk_bf16_f32 v11, v18, v19
	global_store_dwordx4 v[22:23], v[8:11], off
	global_load_dwordx4 v[8:11], v[16:17], off offset:256
	s_waitcnt vmcnt(0) lgkmcnt(0)
	v_lshlrev_b32_e32 v12, 16, v8
	v_and_b32_e32 v13, 0xffff0000, v8
	v_lshlrev_b32_e32 v8, 16, v9
	v_and_b32_e32 v9, 0xffff0000, v9
	v_lshlrev_b32_e32 v14, 16, v10
	v_and_b32_e32 v15, 0xffff0000, v10
	v_lshlrev_b32_e32 v10, 16, v11
	v_and_b32_e32 v11, 0xffff0000, v11
	v_pk_add_f32 v[6:7], v[6:7], v[8:9]
	v_pk_add_f32 v[4:5], v[4:5], v[12:13]
	v_pk_add_f32 v[8:9], v[2:3], v[10:11]
	v_pk_add_f32 v[2:3], v[0:1], v[14:15]
	v_cvt_pk_bf16_f32 v0, v4, v5
	v_cvt_pk_bf16_f32 v1, v6, v7
	v_cvt_pk_bf16_f32 v2, v2, v3
	v_cvt_pk_bf16_f32 v3, v8, v9
	global_store_dwordx4 v[16:17], v[0:3], off offset:256
	s_cbranch_vccz .LBB1_1232
	s_waitcnt vmcnt(0)
	s_cmpk_gt_u32 s17, 0xff
	s_cbranch_scc1 .LBB1_1243
	s_barrier

; #define PG8_STAGE(bufoff, gbase, voff) do { _Pragma("unroll") for (int _i = 0; _i < 2; ++_i) \
;         __builtin_amdgcn_global_load_lds((const unsigned*)((const char*)(gbase) + (voff)[_i]), (LAS unsigned*)(lds + (bufoff) + ldsw + _i * 8192), 16, 0, 0); } while (0)
; #define PG8_LDA(dst, b, h) do { _Pragma("unroll") for (int m = 0; m < 4; ++m) _Pragma("unroll") for (int k = 0; k < 2; ++k) dst[m][k] = *(const LAS bf16x8*)(lds + PG8_SA(b, h) + aoff + m * 2048 + k * 1024); } while (0)
; #define PG8_LDB(dst, b, h) do { _Pragma("unroll") for (int n = 0; n < 2; ++n) _Pragma("unroll") for (int k = 0; k < 2; ++k) dst[n][k] = *(const LAS bf16x8*)(lds + PG8_SB(b, h) + boff + n * 2048 + k * 1024); } while (0)
; #define PG8_MMA(ai, bj, At, Bt) do { __builtin_amdgcn_s_setprio(1); _Pragma("unroll") for (int m = 0; m < 4; ++m) _Pragma("unroll") for (int n = 0; n < 2; ++n) _Pragma("unroll") for (int k = 0; k < 2; ++k) \
;         acc[ai][bj][m][n] = __builtin_amdgcn_mfma_f32_16x16x32_bf16(Bt[n][k], At[m][k], acc[ai][bj][m][n], 0, 0, 0); __builtin_amdgcn_s_setprio(0); } while (0)
; #define PG8_WAIT_L(n) asm volatile("s_waitcnt lgkmcnt(" #n ")" ::: "memory")
; #define PG8_BAR __builtin_amdgcn_s_barrier()
; #define PG8_SCHED __builtin_amdgcn_sched_barrier(0)
; template <class Map, class Epi>
; DI void gemm_phase(LAS unsigned char* lds, const Map& MP, const Epi& E, const int nM, const int nN, const int K, const int lda, const int ldb) {
;     ...
;             const bool last = (t == nt - 2);
;             const char* a1 = cA + (size_t)(t + 1) * kstep;
;             const char* a2 = last ? nA : cA + (size_t)(t + 2) * kstep; const char* b2 = last ? nB : cB + (size_t)(t + 2) * kstep;
;             const char* a3 = a2 + kstep; const char* b3 = b2 + kstep;
;             PG8_LDB(B0, 0, 0); PG8_SCHED; PG8_LDA(At, 0, 0); PG8_STAGE(PG8_SA(1, 1), a1 + hstepA, voffA);
;             PG8_WAIT_L(8); PG8_BAR; PG8_WAIT_L(0); PG8_MMA(0, 0, At, B0); PG8_BAR; PG8_SCHED;
;             PG8_LDB(B1, 0, 1); PG8_STAGE(PG8_SB(0, 0), b2, voffB);
;             PG8_BAR; PG8_WAIT_L(0); PG8_MMA(0, 1, At, B1); PG8_BAR;
;             PG8_LDA(At, 0, 1); PG8_STAGE(PG8_SA(0, 0), a2, voffA);
;             PG8_BAR; PG8_WAIT_L(0); PG8_MMA(1, 0, At, B0); PG8_BAR; PG8_SCHED;
.LBB1_1382:
	ds_read_b128 v[150:153], v147
	ds_read_b128 v[154:157], v147 offset:1024
	ds_read_b128 v[158:161], v147 offset:2048
	ds_read_b128 v[162:165], v147 offset:3072
	s_add_u32 s22, s20, 0xfff80080
	s_addc_u32 s23, s21, -1
	s_cmp_eq_u32 s3, 28
	s_cselect_b32 s25, s15, s23
	s_cselect_b32 s24, s48, s22
	s_cselect_b32 s23, s13, s53
	s_cselect_b32 s22, s49, s52
	v_lshl_add_u64 v[194:195], s[20:21], 0, v[138:139]
	s_add_i32 m0, s31, 0xc000
	ds_read_b128 v[166:169], v148
	ds_read_b128 v[170:173], v148 offset:1024
	ds_read_b128 v[174:177], v148 offset:2048
	ds_read_b128 v[178:181], v148 offset:3072
	ds_read_b128 v[182:185], v148 offset:4096
	ds_read_b128 v[186:189], v148 offset:5120
	ds_read_b128 v[190:193], v148 offset:6144
	ds_read_b128 v[198:201], v148 offset:7168
	global_load_lds_dwordx4 v[194:195], off
	v_lshl_add_u64 v[194:195], s[20:21], 0, v[136:137]
	s_add_i32 m0, s31, 0xe000
	s_nop 0
	global_load_lds_dwordx4 v[194:195], off
	s_waitcnt lgkmcnt(8)
	s_barrier
	s_setprio 1
	s_waitcnt lgkmcnt(7)
	v_mfma_f32_16x16x32_bf16 v[124:127], v[150:153], v[166:169], v[124:127]
	v_mfma_f32_16x16x32_bf16 v[120:123], v[158:161], v[166:169], v[120:123]
	s_waitcnt lgkmcnt(5)
	v_mfma_f32_16x16x32_bf16 v[116:119], v[150:153], v[174:177], v[116:119]
	v_mfma_f32_16x16x32_bf16 v[112:115], v[158:161], v[174:177], v[112:115]
	s_waitcnt lgkmcnt(3)
	v_mfma_f32_16x16x32_bf16 v[100:103], v[150:153], v[182:185], v[100:103]
	v_mfma_f32_16x16x32_bf16 v[96:99], v[158:161], v[182:185], v[96:99]
	s_waitcnt lgkmcnt(1)
	v_mfma_f32_16x16x32_bf16 v[84:87], v[150:153], v[190:193], v[84:87]
	v_mfma_f32_16x16x32_bf16 v[80:83], v[158:161], v[190:193], v[80:83]
	v_mfma_f32_16x16x32_bf16 v[124:127], v[154:157], v[170:173], v[124:127]
	v_mfma_f32_16x16x32_bf16 v[120:123], v[162:165], v[170:173], v[120:123]
	v_mfma_f32_16x16x32_bf16 v[116:119], v[154:157], v[178:181], v[116:119]
	v_mfma_f32_16x16x32_bf16 v[112:115], v[162:165], v[178:181], v[112:115]
	v_mfma_f32_16x16x32_bf16 v[100:103], v[154:157], v[186:189], v[100:103]
	v_mfma_f32_16x16x32_bf16 v[96:99], v[162:165], v[186:189], v[96:99]
	s_waitcnt lgkmcnt(0)
	v_mfma_f32_16x16x32_bf16 v[84:87], v[154:157], v[198:201], v[84:87]
	v_mfma_f32_16x16x32_bf16 v[80:83], v[162:165], v[198:201], v[80:83]
	s_setprio 0
	s_barrier
	s_add_i32 s54, s44, s29
	v_lshl_add_u64 v[194:195], s[22:23], 0, v[132:133]
	s_mov_b32 m0, s54
	ds_read_b128 v[202:205], v149
	ds_read_b128 v[206:209], v149 offset:1024
	ds_read_b128 v[210:213], v149 offset:2048
	ds_read_b128 v[214:217], v149 offset:3072
	global_load_lds_dwordx4 v[194:195], off
	v_lshl_add_u64 v[218:219], s[22:23], 0, v[128:129]
	s_add_i32 m0, s54, 0x2000
	s_nop 0
	global_load_lds_dwordx4 v[218:219], off
	s_barrier
	s_setprio 1
	s_waitcnt lgkmcnt(3)
	v_mfma_f32_16x16x32_bf16 v[108:111], v[202:205], v[166:169], v[108:111]
	s_waitcnt lgkmcnt(1)
	v_mfma_f32_16x16x32_bf16 v[104:107], v[210:213], v[166:169], v[104:107]
	v_mfma_f32_16x16x32_bf16 v[92:95], v[202:205], v[174:177], v[92:95]
	v_mfma_f32_16x16x32_bf16 v[88:91], v[210:213], v[174:177], v[88:91]
	v_mfma_f32_16x16x32_bf16 v[76:79], v[202:205], v[182:185], v[76:79]
	v_mfma_f32_16x16x32_bf16 v[72:75], v[210:213], v[182:185], v[72:75]
	v_mfma_f32_16x16x32_bf16 v[68:71], v[202:205], v[190:193], v[68:71]
	v_mfma_f32_16x16x32_bf16 v[64:67], v[210:213], v[190:193], v[64:67]
	v_mfma_f32_16x16x32_bf16 v[108:111], v[206:209], v[170:173], v[108:111]
	s_waitcnt lgkmcnt(0)
	v_mfma_f32_16x16x32_bf16 v[104:107], v[214:217], v[170:173], v[104:107]
	v_mfma_f32_16x16x32_bf16 v[92:95], v[206:209], v[178:181], v[92:95]
	v_mfma_f32_16x16x32_bf16 v[88:91], v[214:217], v[178:181], v[88:91]
	v_mfma_f32_16x16x32_bf16 v[76:79], v[206:209], v[186:189], v[76:79]
	v_mfma_f32_16x16x32_bf16 v[72:75], v[214:217], v[186:189], v[72:75]
	v_mfma_f32_16x16x32_bf16 v[68:71], v[206:209], v[198:201], v[68:71]
	v_mfma_f32_16x16x32_bf16 v[64:67], v[214:217], v[198:201], v[64:67]
	s_setprio 0
	s_mov_b32 m0, s31
	v_lshl_add_u64 v[220:221], s[24:25], 0, v[134:135]
	s_barrier
	ds_read_b128 v[166:169], v148 offset:16384
	ds_read_b128 v[170:173], v148 offset:17408
	ds_read_b128 v[174:177], v148 offset:18432
	ds_read_b128 v[178:181], v148 offset:19456
	ds_read_b128 v[182:185], v148 offset:20480
	ds_read_b128 v[186:189], v148 offset:21504
	ds_read_b128 v[190:193], v148 offset:22528
	ds_read_b128 v[198:201], v148 offset:23552
	global_load_lds_dwordx4 v[220:221], off
	v_lshl_add_u64 v[222:223], s[24:25], 0, v[130:131]
	s_mov_b32 m0, s11
	s_nop 0
	global_load_lds_dwordx4 v[222:223], off
	s_barrier
	s_setprio 1
	s_waitcnt lgkmcnt(7)
	v_mfma_f32_16x16x32_bf16 v[60:63], v[150:153], v[166:169], v[60:63]
	v_mfma_f32_16x16x32_bf16 v[56:59], v[158:161], v[166:169], v[56:59]
	s_waitcnt lgkmcnt(5)
	v_mfma_f32_16x16x32_bf16 v[52:55], v[150:153], v[174:177], v[52:55]
	v_mfma_f32_16x16x32_bf16 v[48:51], v[158:161], v[174:177], v[48:51]
	s_waitcnt lgkmcnt(3)
	v_mfma_f32_16x16x32_bf16 v[36:39], v[150:153], v[182:185], v[36:39]
	v_mfma_f32_16x16x32_bf16 v[32:35], v[158:161], v[182:185], v[32:35]
	s_waitcnt lgkmcnt(1)
	v_mfma_f32_16x16x32_bf16 v[20:23], v[150:153], v[190:193], v[20:23]
	v_mfma_f32_16x16x32_bf16 v[16:19], v[158:161], v[190:193], v[16:19]
	v_mfma_f32_16x16x32_bf16 v[60:63], v[154:157], v[170:173], v[60:63]
	v_mfma_f32_16x16x32_bf16 v[56:59], v[162:165], v[170:173], v[56:59]
	v_mfma_f32_16x16x32_bf16 v[52:55], v[154:157], v[178:181], v[52:55]
	v_mfma_f32_16x16x32_bf16 v[48:51], v[162:165], v[178:181], v[48:51]
	v_mfma_f32_16x16x32_bf16 v[36:39], v[154:157], v[186:189], v[36:39]
	v_mfma_f32_16x16x32_bf16 v[32:35], v[162:165], v[186:189], v[32:35]
	s_waitcnt lgkmcnt(0)
	v_mfma_f32_16x16x32_bf16 v[20:23], v[154:157], v[198:201], v[20:23]
	v_mfma_f32_16x16x32_bf16 v[16:19], v[162:165], v[198:201], v[16:19]
	s_setprio 0
	s_barrier
; #define PG8_STAGE(bufoff, gbase, voff) do { _Pragma("unroll") for (int _i = 0; _i < 2; ++_i) \
;         __builtin_amdgcn_global_load_lds((const unsigned*)((const char*)(gbase) + (voff)[_i]), (LAS unsigned*)(lds + (bufoff) + ldsw + _i * 8192), 16, 0, 0); } while (0)
; #define PG8_LDA(dst, b, h) do { _Pragma("unroll") for (int m = 0; m < 4; ++m) _Pragma("unroll") for (int k = 0; k < 2; ++k) dst[m][k] = *(const LAS bf16x8*)(lds + PG8_SA(b, h) + aoff + m * 2048 + k * 1024); } while (0)
; #define PG8_WAIT_V(n) asm volatile("s_waitcnt vmcnt(" #n ")" ::: "memory")
; #define PG8_BAR __builtin_amdgcn_s_barrier()
; template <class Map, class Epi>
; DI void gemm_phase(LAS unsigned char* lds, const Map& MP, const Epi& E, const int nM, const int nN, const int K, const int lda, const int ldb) {
;     ...
;         for (int t = 0; t < nt; t += 2) {
;             const bool last = (t == nt - 2);
;             const char* a1 = cA + (size_t)(t + 1) * kstep;
;             const char* a2 = last ? nA : cA + (size_t)(t + 2) * kstep; const char* b2 = last ? nB : cB + (size_t)(t + 2) * kstep;
;             const char* a3 = a2 + kstep; const char* b3 = b2 + kstep;
;             PG8_LDB(B0, 0, 0); PG8_SCHED; PG8_LDA(At, 0, 0); PG8_STAGE(PG8_SA(1, 1), a1 + hstepA, voffA);
;             PG8_WAIT_L(8); PG8_BAR; PG8_WAIT_L(0); PG8_MMA(0, 0, At, B0); PG8_BAR; PG8_SCHED;
;             PG8_LDB(B1, 0, 1); PG8_STAGE(PG8_SB(0, 0), b2, voffB);
;             PG8_BAR; PG8_WAIT_L(0); PG8_MMA(0, 1, At, B1); PG8_BAR;
;             PG8_LDA(At, 0, 1); PG8_STAGE(PG8_SA(0, 0), a2, voffA);
;             PG8_BAR; PG8_WAIT_L(0); PG8_MMA(1, 0, At, B0); PG8_BAR; PG8_SCHED;
;             PG8_STAGE(PG8_SB(0, 1), b2 + hstepB, voffB);
;             PG8_WAIT_V(6); PG8_BAR; PG8_MMA(1, 1, At, B1); PG8_BAR;
;             PG8_LDB(B0, 1, 0); PG8_SCHED; PG8_LDA(At, 1, 0); PG8_STAGE(PG8_SA(0, 1), a2 + hstepA, voffA);
;             PG8_WAIT_L(8); PG8_BAR; PG8_WAIT_L(0); PG8_MMA(0, 0, At, B0); PG8_BAR; PG8_SCHED;
;             PG8_LDB(B1, 1, 1); PG8_STAGE(PG8_SB(1, 0), b3, voffB);
;             PG8_BAR; PG8_WAIT_L(0); PG8_MMA(0, 1, At, B1); PG8_BAR;
;             PG8_LDA(At, 1, 1); PG8_STAGE(PG8_SA(1, 0), a3, voffA);
;             PG8_BAR; PG8_WAIT_L(0); PG8_MMA(1, 0, At, B0); PG8_BAR; PG8_SCHED;
;             PG8_STAGE(PG8_SB(1, 1), b3 + hstepB, voffB);
;             PG8_WAIT_V(6); PG8_BAR; PG8_MMA(1, 1, At, B1); PG8_BAR;
	s_add_u32 s54, s22, 0x80000
	s_addc_u32 s55, s23, 0
	s_add_i32 s56, s45, s29
	v_lshl_add_u64 v[150:151], s[54:55], 0, v[132:133]
	s_mov_b32 m0, s56
	s_nop 0
	global_load_lds_dwordx4 v[150:151], off
	v_lshl_add_u64 v[150:151], s[54:55], 0, v[128:129]
	s_add_i32 m0, s56, 0x2000
	s_nop 0
	global_load_lds_dwordx4 v[150:151], off
	s_waitcnt vmcnt(6)
	s_barrier
	s_setprio 1
	v_mfma_f32_16x16x32_bf16 v[44:47], v[202:205], v[166:169], v[44:47]
	v_mfma_f32_16x16x32_bf16 v[40:43], v[210:213], v[166:169], v[40:43]
	v_mfma_f32_16x16x32_bf16 v[28:31], v[202:205], v[174:177], v[28:31]
	v_mfma_f32_16x16x32_bf16 v[24:27], v[210:213], v[174:177], v[24:27]
	v_mfma_f32_16x16x32_bf16 v[12:15], v[202:205], v[182:185], v[12:15]
	v_mfma_f32_16x16x32_bf16 v[8:11], v[210:213], v[182:185], v[8:11]
	v_mfma_f32_16x16x32_bf16 v[4:7], v[202:205], v[190:193], v[4:7]
	v_mfma_f32_16x16x32_bf16 v[0:3], v[210:213], v[190:193], v[0:3]
	v_mfma_f32_16x16x32_bf16 v[44:47], v[206:209], v[170:173], v[44:47]
	v_mfma_f32_16x16x32_bf16 v[40:43], v[214:217], v[170:173], v[40:43]
	v_mfma_f32_16x16x32_bf16 v[28:31], v[206:209], v[178:181], v[28:31]
	v_mfma_f32_16x16x32_bf16 v[24:27], v[214:217], v[178:181], v[24:27]
	v_mfma_f32_16x16x32_bf16 v[12:15], v[206:209], v[186:189], v[12:15]
	v_mfma_f32_16x16x32_bf16 v[8:11], v[214:217], v[186:189], v[8:11]
	v_mfma_f32_16x16x32_bf16 v[4:7], v[206:209], v[198:201], v[4:7]
	v_mfma_f32_16x16x32_bf16 v[0:3], v[214:217], v[198:201], v[0:3]
	s_setprio 0
	s_add_i32 s54, 0, 0x18000
	v_add_u32_e32 v162, s54, v146
	s_barrier
	ds_read_b128 v[150:153], v162
	ds_read_b128 v[154:157], v162 offset:1024
	ds_read_b128 v[158:161], v162 offset:2048
	ds_read_b128 v[162:165], v162 offset:3072
	s_add_u32 s24, s24, 0x80000
	s_addc_u32 s25, s25, 0
	s_mov_b32 m0, s34
	v_lshl_add_u64 v[202:203], s[24:25], 0, v[134:135]
	ds_read_b128 v[166:169], v148 offset:32768
	ds_read_b128 v[170:173], v148 offset:33792
	ds_read_b128 v[174:177], v148 offset:34816
	ds_read_b128 v[178:181], v148 offset:35840
	ds_read_b128 v[182:185], v148 offset:36864
	ds_read_b128 v[186:189], v148 offset:37888
	ds_read_b128 v[190:193], v148 offset:38912
	ds_read_b128 v[198:201], v148 offset:39936
	global_load_lds_dwordx4 v[202:203], off
	v_lshl_add_u64 v[202:203], s[24:25], 0, v[130:131]
	s_mov_b32 m0, s35
	s_nop 0
	global_load_lds_dwordx4 v[202:203], off
	s_waitcnt lgkmcnt(8)
	s_barrier
	s_setprio 1
	s_waitcnt lgkmcnt(7)
	v_mfma_f32_16x16x32_bf16 v[124:127], v[150:153], v[166:169], v[124:127]
	v_mfma_f32_16x16x32_bf16 v[120:123], v[158:161], v[166:169], v[120:123]
	s_waitcnt lgkmcnt(5)
	v_mfma_f32_16x16x32_bf16 v[116:119], v[150:153], v[174:177], v[116:119]
	v_mfma_f32_16x16x32_bf16 v[112:115], v[158:161], v[174:177], v[112:115]
	s_waitcnt lgkmcnt(3)
	v_mfma_f32_16x16x32_bf16 v[100:103], v[150:153], v[182:185], v[100:103]
	v_mfma_f32_16x16x32_bf16 v[96:99], v[158:161], v[182:185], v[96:99]
	s_waitcnt lgkmcnt(1)
	v_mfma_f32_16x16x32_bf16 v[84:87], v[150:153], v[190:193], v[84:87]
	v_mfma_f32_16x16x32_bf16 v[80:83], v[158:161], v[190:193], v[80:83]
	v_mfma_f32_16x16x32_bf16 v[124:127], v[154:157], v[170:173], v[124:127]
	v_mfma_f32_16x16x32_bf16 v[120:123], v[162:165], v[170:173], v[120:123]
	v_mfma_f32_16x16x32_bf16 v[116:119], v[154:157], v[178:181], v[116:119]
	v_mfma_f32_16x16x32_bf16 v[112:115], v[162:165], v[178:181], v[112:115]
	v_mfma_f32_16x16x32_bf16 v[100:103], v[154:157], v[186:189], v[100:103]
	v_mfma_f32_16x16x32_bf16 v[96:99], v[162:165], v[186:189], v[96:99]
	s_waitcnt lgkmcnt(0)
	v_mfma_f32_16x16x32_bf16 v[84:87], v[154:157], v[198:201], v[84:87]
	v_mfma_f32_16x16x32_bf16 v[80:83], v[162:165], v[198:201], v[80:83]
	s_setprio 0
	s_barrier
	s_add_i32 s24, 0, 0x1c000
	s_add_i32 s25, s54, s29
	v_add_u32_e32 v196, s24, v146
	v_lshl_add_u64 v[194:195], v[194:195], 0, s[8:9]
	s_mov_b32 m0, s25
	ds_read_b128 v[202:205], v196
	ds_read_b128 v[206:209], v196 offset:1024
	ds_read_b128 v[210:213], v196 offset:2048
	ds_read_b128 v[214:217], v196 offset:3072
	global_load_lds_dwordx4 v[194:195], off
	v_lshl_add_u64 v[194:195], v[218:219], 0, s[8:9]
	s_add_i32 m0, s25, 0x2000
	s_nop 0
	global_load_lds_dwordx4 v[194:195], off
	s_barrier
	s_setprio 1
	s_waitcnt lgkmcnt(3)
	v_mfma_f32_16x16x32_bf16 v[108:111], v[202:205], v[166:169], v[108:111]
	s_waitcnt lgkmcnt(1)
	v_mfma_f32_16x16x32_bf16 v[104:107], v[210:213], v[166:169], v[104:107]
	v_mfma_f32_16x16x32_bf16 v[92:95], v[202:205], v[174:177], v[92:95]
	v_mfma_f32_16x16x32_bf16 v[88:91], v[210:213], v[174:177], v[88:91]
	v_mfma_f32_16x16x32_bf16 v[76:79], v[202:205], v[182:185], v[76:79]
	v_mfma_f32_16x16x32_bf16 v[72:75], v[210:213], v[182:185], v[72:75]
	v_mfma_f32_16x16x32_bf16 v[68:71], v[202:205], v[190:193], v[68:71]
	v_mfma_f32_16x16x32_bf16 v[64:67], v[210:213], v[190:193], v[64:67]
	v_mfma_f32_16x16x32_bf16 v[108:111], v[206:209], v[170:173], v[108:111]
	s_waitcnt lgkmcnt(0)
	v_mfma_f32_16x16x32_bf16 v[104:107], v[214:217], v[170:173], v[104:107]
	v_mfma_f32_16x16x32_bf16 v[92:95], v[206:209], v[178:181], v[92:95]
	v_mfma_f32_16x16x32_bf16 v[88:91], v[214:217], v[178:181], v[88:91]
	v_mfma_f32_16x16x32_bf16 v[76:79], v[206:209], v[186:189], v[76:79]
	v_mfma_f32_16x16x32_bf16 v[72:75], v[214:217], v[186:189], v[72:75]
	v_mfma_f32_16x16x32_bf16 v[68:71], v[206:209], v[198:201], v[68:71]
	v_mfma_f32_16x16x32_bf16 v[64:67], v[214:217], v[198:201], v[64:67]
	s_setprio 0
	s_mov_b32 m0, s39
	v_lshl_add_u64 v[194:195], v[220:221], 0, s[8:9]
	s_barrier
; #define PG8_STAGE(bufoff, gbase, voff) do { _Pragma("unroll") for (int _i = 0; _i < 2; ++_i) \
;         __builtin_amdgcn_global_load_lds((const unsigned*)((const char*)(gbase) + (voff)[_i]), (LAS unsigned*)(lds + (bufoff) + ldsw + _i * 8192), 16, 0, 0); } while (0)
; #define PG8_LDA(dst, b, h) do { _Pragma("unroll") for (int m = 0; m < 4; ++m) _Pragma("unroll") for (int k = 0; k < 2; ++k) dst[m][k] = *(const LAS bf16x8*)(lds + PG8_SA(b, h) + aoff + m * 2048 + k * 1024); } while (0)
; #define PG8_WAIT_V(n) asm volatile("s_waitcnt vmcnt(" #n ")" ::: "memory")
; #define PG8_BAR __builtin_amdgcn_s_barrier()
; template <class Map, class Epi>
; DI void gemm_phase(LAS unsigned char* lds, const Map& MP, const Epi& E, const int nM, const int nN, const int K, const int lda, const int ldb) {
;     ...
;         for (int t = 0; t < nt; t += 2) {
;             const bool last = (t == nt - 2);
;             const char* a1 = cA + (size_t)(t + 1) * kstep;
;             const char* a2 = last ? nA : cA + (size_t)(t + 2) * kstep; const char* b2 = last ? nB : cB + (size_t)(t + 2) * kstep;
;             const char* a3 = a2 + kstep; const char* b3 = b2 + kstep;
;             PG8_LDB(B0, 0, 0); PG8_SCHED; PG8_LDA(At, 0, 0); PG8_STAGE(PG8_SA(1, 1), a1 + hstepA, voffA);
;             PG8_WAIT_L(8); PG8_BAR; PG8_WAIT_L(0); PG8_MMA(0, 0, At, B0); PG8_BAR; PG8_SCHED;
;             PG8_LDB(B1, 0, 1); PG8_STAGE(PG8_SB(0, 0), b2, voffB);
;             PG8_BAR; PG8_WAIT_L(0); PG8_MMA(0, 1, At, B1); PG8_BAR;
;             PG8_LDA(At, 0, 1); PG8_STAGE(PG8_SA(0, 0), a2, voffA);
;             PG8_BAR; PG8_WAIT_L(0); PG8_MMA(1, 0, At, B0); PG8_BAR; PG8_SCHED;
;             PG8_STAGE(PG8_SB(0, 1), b2 + hstepB, voffB);
;             PG8_WAIT_V(6); PG8_BAR; PG8_MMA(1, 1, At, B1); PG8_BAR;
;             PG8_LDB(B0, 1, 0); PG8_SCHED; PG8_LDA(At, 1, 0); PG8_STAGE(PG8_SA(0, 1), a2 + hstepA, voffA);
;             PG8_WAIT_L(8); PG8_BAR; PG8_WAIT_L(0); PG8_MMA(0, 0, At, B0); PG8_BAR; PG8_SCHED;
;             PG8_LDB(B1, 1, 1); PG8_STAGE(PG8_SB(1, 0), b3, voffB);
;             PG8_BAR; PG8_WAIT_L(0); PG8_MMA(0, 1, At, B1); PG8_BAR;
;             PG8_LDA(At, 1, 1); PG8_STAGE(PG8_SA(1, 0), a3, voffA);
;             PG8_BAR; PG8_WAIT_L(0); PG8_MMA(1, 0, At, B0); PG8_BAR; PG8_SCHED;
;             PG8_STAGE(PG8_SB(1, 1), b3 + hstepB, voffB);
;             PG8_WAIT_V(6); PG8_BAR; PG8_MMA(1, 1, At, B1); PG8_BAR;
	ds_read_b128 v[166:169], v148 offset:49152
	ds_read_b128 v[170:173], v148 offset:50176
	ds_read_b128 v[174:177], v148 offset:51200
	ds_read_b128 v[178:181], v148 offset:52224
	ds_read_b128 v[182:185], v148 offset:53248
	ds_read_b128 v[186:189], v148 offset:54272
	ds_read_b128 v[190:193], v148 offset:55296
	ds_read_b128 v[198:201], v148 offset:56320
	global_load_lds_dwordx4 v[194:195], off
	v_lshl_add_u64 v[194:195], v[222:223], 0, s[8:9]
	s_mov_b32 m0, s42
	s_nop 0
	global_load_lds_dwordx4 v[194:195], off
	s_barrier
	s_setprio 1
	s_waitcnt lgkmcnt(7)
	v_mfma_f32_16x16x32_bf16 v[60:63], v[150:153], v[166:169], v[60:63]
	v_mfma_f32_16x16x32_bf16 v[56:59], v[158:161], v[166:169], v[56:59]
	s_waitcnt lgkmcnt(5)
	v_mfma_f32_16x16x32_bf16 v[52:55], v[150:153], v[174:177], v[52:55]
	v_mfma_f32_16x16x32_bf16 v[48:51], v[158:161], v[174:177], v[48:51]
	s_waitcnt lgkmcnt(3)
	v_mfma_f32_16x16x32_bf16 v[36:39], v[150:153], v[182:185], v[36:39]
	v_mfma_f32_16x16x32_bf16 v[32:35], v[158:161], v[182:185], v[32:35]
	s_waitcnt lgkmcnt(1)
	v_mfma_f32_16x16x32_bf16 v[20:23], v[150:153], v[190:193], v[20:23]
	v_mfma_f32_16x16x32_bf16 v[16:19], v[158:161], v[190:193], v[16:19]
	v_mfma_f32_16x16x32_bf16 v[60:63], v[154:157], v[170:173], v[60:63]
	v_mfma_f32_16x16x32_bf16 v[56:59], v[162:165], v[170:173], v[56:59]
	v_mfma_f32_16x16x32_bf16 v[52:55], v[154:157], v[178:181], v[52:55]
	v_mfma_f32_16x16x32_bf16 v[48:51], v[162:165], v[178:181], v[48:51]
	v_mfma_f32_16x16x32_bf16 v[36:39], v[154:157], v[186:189], v[36:39]
	v_mfma_f32_16x16x32_bf16 v[32:35], v[162:165], v[186:189], v[32:35]
	s_waitcnt lgkmcnt(0)
	v_mfma_f32_16x16x32_bf16 v[20:23], v[154:157], v[198:201], v[20:23]
	v_mfma_f32_16x16x32_bf16 v[16:19], v[162:165], v[198:201], v[16:19]
	s_setprio 0
	s_barrier
	s_add_u32 s22, s22, 0x80080
	s_addc_u32 s23, s23, 0
	s_add_i32 s24, s24, s29
	v_lshl_add_u64 v[150:151], s[22:23], 0, v[132:133]
	s_mov_b32 m0, s24
	s_nop 0
	global_load_lds_dwordx4 v[150:151], off
	v_lshl_add_u64 v[150:151], s[22:23], 0, v[128:129]
	s_add_i32 m0, s24, 0x2000
	s_nop 0
	global_load_lds_dwordx4 v[150:151], off
	s_waitcnt vmcnt(6)
	s_barrier
	s_setprio 1
	v_mfma_f32_16x16x32_bf16 v[44:47], v[202:205], v[166:169], v[44:47]
	v_mfma_f32_16x16x32_bf16 v[40:43], v[210:213], v[166:169], v[40:43]
	v_mfma_f32_16x16x32_bf16 v[28:31], v[202:205], v[174:177], v[28:31]
	v_mfma_f32_16x16x32_bf16 v[24:27], v[210:213], v[174:177], v[24:27]
	v_mfma_f32_16x16x32_bf16 v[12:15], v[202:205], v[182:185], v[12:15]
	v_mfma_f32_16x16x32_bf16 v[8:11], v[210:213], v[182:185], v[8:11]
	v_mfma_f32_16x16x32_bf16 v[4:7], v[202:205], v[190:193], v[4:7]
	v_mfma_f32_16x16x32_bf16 v[0:3], v[210:213], v[190:193], v[0:3]
	v_mfma_f32_16x16x32_bf16 v[44:47], v[206:209], v[170:173], v[44:47]
	v_mfma_f32_16x16x32_bf16 v[40:43], v[214:217], v[170:173], v[40:43]
	v_mfma_f32_16x16x32_bf16 v[28:31], v[206:209], v[178:181], v[28:31]
	v_mfma_f32_16x16x32_bf16 v[24:27], v[214:217], v[178:181], v[24:27]
	v_mfma_f32_16x16x32_bf16 v[12:15], v[206:209], v[186:189], v[12:15]
	v_mfma_f32_16x16x32_bf16 v[8:11], v[214:217], v[186:189], v[8:11]
	v_mfma_f32_16x16x32_bf16 v[4:7], v[206:209], v[198:201], v[4:7]
	v_mfma_f32_16x16x32_bf16 v[0:3], v[214:217], v[198:201], v[0:3]
	s_setprio 0
	s_add_i32 s3, s3, 2
	s_add_u32 s52, s52, 0x100
	s_addc_u32 s53, s53, 0
	s_add_u32 s20, s20, 0x100
	s_addc_u32 s21, s21, 0
	s_cmp_gt_u32 s3, 29
	s_barrier
	s_cbranch_scc0 .LBB1_1382
; DI unsigned pack2(float a, float b) { f32x2 v = {a, b}; hwbf16x2 r = __builtin_convertvector(v, hwbf16x2); return __builtin_bit_cast(unsigned, r); }
;     DI const char* a(const Unit& u) const { return (const char*)(A + (size_t)u.pm * BM * lda); }
;     DI const char* a(const Unit& u) const { return (const char*)(A + (size_t)u.pm * BM * 2048 + (u.pn >> 1) * 512); }
;     DI const char* a(const Unit& u) const { return (const char*)((u.pn < 12 ? A1 : A2) + (size_t)u.pm * BM * 512); }
;     DI void operator()(const f32x4 (&acc)[2][2][4][2], const Unit& u, int wr, int wc, int fr, int fq) const {
;         bf16_t* O = O1; int ldc = ldc1, pn = u.pn; if (pn >= split) { O = O2; ldc = ldc2; pn -= split; }
;         const int row0 = u.pm * BM + wr * 64 + fr, col0 = pn * BM + wc * 32 + 8 * fq;
; #pragma unroll
;         for (int ai = 0; ai < 2; ++ai)
; #pragma unroll
;             for (int m = 0; m < 4; ++m) { bf16_t* rowp = O + (size_t)(row0 + ai * HALF + m * 16) * ldc + col0;
; #pragma unroll
;                 for (int bj = 0; bj < 2; ++bj) { const f32x4 v0 = acc[ai][bj][m][0], v1 = acc[ai][bj][m][1];
;                     u32x4 o; o[0] = pack2(v0[0], v0[1]); o[1] = pack2(v0[2], v0[3]); o[2] = pack2(v1[0], v1[1]); o[3] = pack2(v1[2], v1[3]);
;                     *(u32x4*)(rowp + bj * HALF) = o; } }
;     }
; template <class Map, class Epi>
; DI void gemm_phase(LAS unsigned char* lds, const Map& MP, const Epi& E, const int nM, const int nN, const int K, const int lda, const int ldb) {
;     ...
;         { int frr = fr, fqq = fq; asm volatile("" : "+v"(frr), "+v"(fqq)); E(acc, cur, wr, wc, frr, fqq); }
;         if (!has_next) break;
; #pragma unroll
;         for (int a = 0; a < 2; ++a)
; #pragma unroll
;             for (int b = 0; b < 2; ++b)
; #pragma unroll
;                 for (int m = 0; m < 4; ++m)
; #pragma unroll
;                     for (int n = 0; n < 2; ++n) acc[a][b][m][n] = (f32x4){0.f, 0.f, 0.f, 0.f};
;         cur = nxt; cA = nA; cB = nB; ++ui;
;     }
	s_lshl_b32 s3, s10, 8
	v_mov_b32_e32 v150, v144
	v_mov_b32_e32 v151, v145
	s_add_i32 s3, s3, s37
	v_cvt_pk_bf16_f32 v68, v68, v69
	v_add_u32_e32 v154, s3, v150
	s_lshl_b32 s3, s47, 8
	s_or_b32 s3, s3, s38
	v_lshl_add_u32 v150, v151, 3, s3
	v_ashrrev_i32_e32 v151, 31, v150
	v_lshl_add_u64 v[150:151], v[150:151], 1, s[6:7]
	v_cvt_pk_bf16_f32 v69, v70, v71
	v_cvt_pk_bf16_f32 v70, v64, v65
	v_add_u32_e32 v64, 0x80, v154
	v_mad_i64_i32 v[152:153], s[20:21], v154, s46, v[150:151]
	v_cvt_pk_bf16_f32 v108, v108, v109
	v_cvt_pk_bf16_f32 v109, v110, v111
	v_cvt_pk_bf16_f32 v110, v104, v105
	v_cvt_pk_bf16_f32 v111, v106, v107
	v_add_u32_e32 v104, 16, v154
	v_mad_i64_i32 v[64:65], s[20:21], v64, s46, v[150:151]
	v_cvt_pk_bf16_f32 v44, v44, v45
	v_cvt_pk_bf16_f32 v45, v46, v47
	v_cvt_pk_bf16_f32 v46, v40, v41
	v_cvt_pk_bf16_f32 v47, v42, v43
	v_add_u32_e32 v40, 0x90, v154
	global_store_dwordx4 v[152:153], v[108:111], off offset:256
	v_cvt_pk_bf16_f32 v92, v92, v93
	v_cvt_pk_bf16_f32 v93, v94, v95
	v_mad_i64_i32 v[108:109], s[20:21], v104, s46, v[150:151]
	v_cvt_pk_bf16_f32 v94, v88, v89
	v_cvt_pk_bf16_f32 v95, v90, v91
	v_add_u32_e32 v88, 32, v154
	global_store_dwordx4 v[64:65], v[44:47], off offset:256
	v_cvt_pk_bf16_f32 v28, v28, v29
	v_cvt_pk_bf16_f32 v29, v30, v31
	v_mad_i64_i32 v[44:45], s[20:21], v40, s46, v[150:151]
	v_cvt_pk_bf16_f32 v30, v24, v25
	v_cvt_pk_bf16_f32 v31, v26, v27
	v_add_u32_e32 v24, 0xa0, v154
	global_store_dwordx4 v[108:109], v[92:95], off offset:256
	v_cvt_pk_bf16_f32 v76, v76, v77
	v_cvt_pk_bf16_f32 v77, v78, v79
	v_mad_i64_i32 v[92:93], s[20:21], v88, s46, v[150:151]
	v_cvt_pk_bf16_f32 v78, v72, v73
	v_cvt_pk_bf16_f32 v79, v74, v75
	v_add_u32_e32 v72, 48, v154
	global_store_dwordx4 v[44:45], v[28:31], off offset:256
	v_cvt_pk_bf16_f32 v12, v12, v13
	v_cvt_pk_bf16_f32 v13, v14, v15
	v_mad_i64_i32 v[28:29], s[20:21], v24, s46, v[150:151]
	v_cvt_pk_bf16_f32 v14, v8, v9
	v_cvt_pk_bf16_f32 v15, v10, v11
	v_add_u32_e32 v8, 0xb0, v154
	global_store_dwordx4 v[92:93], v[76:79], off offset:256
	global_store_dwordx4 v[28:29], v[12:15], off offset:256
	v_cvt_pk_bf16_f32 v124, v124, v125
	v_mad_i64_i32 v[76:77], s[20:21], v72, s46, v[150:151]
	v_mad_i64_i32 v[12:13], s[20:21], v8, s46, v[150:151]
	v_cvt_pk_bf16_f32 v125, v126, v127
	v_cvt_pk_bf16_f32 v126, v120, v121
	v_cvt_pk_bf16_f32 v127, v122, v123
	v_cvt_pk_bf16_f32 v104, v116, v117
	v_cvt_pk_bf16_f32 v105, v118, v119
	v_cvt_pk_bf16_f32 v106, v112, v113
	v_cvt_pk_bf16_f32 v107, v114, v115
	v_cvt_pk_bf16_f32 v88, v100, v101
	v_cvt_pk_bf16_f32 v89, v102, v103
	v_cvt_pk_bf16_f32 v90, v96, v97
	v_cvt_pk_bf16_f32 v91, v98, v99
	v_cvt_pk_bf16_f32 v72, v84, v85
	v_cvt_pk_bf16_f32 v73, v86, v87
	v_cvt_pk_bf16_f32 v74, v80, v81
	v_cvt_pk_bf16_f32 v75, v82, v83
	v_cvt_pk_bf16_f32 v71, v66, v67
	v_cvt_pk_bf16_f32 v60, v60, v61
	v_cvt_pk_bf16_f32 v61, v62, v63
	v_cvt_pk_bf16_f32 v62, v56, v57
	v_cvt_pk_bf16_f32 v63, v58, v59
	v_cvt_pk_bf16_f32 v40, v52, v53
	v_cvt_pk_bf16_f32 v41, v54, v55
	v_cvt_pk_bf16_f32 v42, v48, v49
	v_cvt_pk_bf16_f32 v43, v50, v51
	v_cvt_pk_bf16_f32 v24, v36, v37
	v_cvt_pk_bf16_f32 v25, v38, v39
	v_cvt_pk_bf16_f32 v26, v32, v33
	v_cvt_pk_bf16_f32 v27, v34, v35
	v_cvt_pk_bf16_f32 v8, v20, v21
	v_cvt_pk_bf16_f32 v9, v22, v23
	v_cvt_pk_bf16_f32 v10, v16, v17
	v_cvt_pk_bf16_f32 v11, v18, v19
	v_cvt_pk_bf16_f32 v4, v4, v5
	v_cvt_pk_bf16_f32 v5, v6, v7
	v_cvt_pk_bf16_f32 v6, v0, v1
	v_cvt_pk_bf16_f32 v7, v2, v3
	s_and_b64 vcc, exec, s[40:41]
	s_mov_b32 s47, s12
	s_mov_b32 s10, s14
	s_mov_b64 s[20:21], s[18:19]
	s_mov_b64 s[22:23], s[16:17]
	global_store_dwordx4 v[152:153], v[124:127], off
	global_store_dwordx4 v[108:109], v[104:107], off
	global_store_dwordx4 v[92:93], v[88:91], off
	global_store_dwordx4 v[76:77], v[72:75], off
	global_store_dwordx4 v[76:77], v[68:71], off offset:256
	global_store_dwordx4 v[64:65], v[60:63], off
	global_store_dwordx4 v[44:45], v[40:43], off
	global_store_dwordx4 v[28:29], v[24:27], off
	global_store_dwordx4 v[12:13], v[8:11], off
	global_store_dwordx4 v[12:13], v[4:7], off offset:256
	s_cbranch_vccz .LBB1_1379
	s_waitcnt vmcnt(0)
	s_cmpk_gt_u32 s4, 0xff
	s_cbranch_scc1 .LBB1_1386
	s_barrier

; DI unsigned pack2(float a, float b) { f32x2 v = {a, b}; hwbf16x2 r = __builtin_convertvector(v, hwbf16x2); return __builtin_bit_cast(unsigned, r); }
; DI float bflo(unsigned w) { return __uint_as_float(w << 16); }
; DI float bfhi(unsigned w) { return __uint_as_float(w & 0xffff0000u); }
; DI float wave_sum(float v) { for (int o = 32; o; o >>= 1) v += __shfl_xor(v, o); return v; }
;     DI const char* a(const Unit& u) const { return (const char*)(A + (size_t)u.pm * BM * lda); }
; DI void mla_prep1_phase(const Params& p) {
;     ...
;     for (int t0 = bid * 8 + wid; t0 < T; t0 += 2 * tstep)
;       {
;         u32x2 wl[2][4]; unsigned short kx[2];
; #pragma unroll
;         for (int q2 = 0; q2 < 2; ++q2) { const int tq = t0 + q2 * tstep; if (tq < T) { const bf16_t* rw = D32 + (size_t)tq * 1280;
; #pragma unroll
;             for (int part = 0; part < 2; ++part) { wl[q2][2 * part] = *(const u32x2*)(rw + part * 512 + lane * 4); wl[q2][2 * part + 1] = *(const u32x2*)(rw + part * 512 + 256 + lane * 4); }
;             kx[q2] = rw[1024 + lane]; } }
; #pragma unroll
;       for (int q2 = 0; q2 < 2; ++q2) { const int t = t0 + q2 * tstep; if (t < T) {
;         const int s = t & (S - 1);
; #pragma unroll
;         for (int part = 0; part < 2; ++part) {
;             const u32x2 wa = wl[q2][2 * part], wc2 = wl[q2][2 * part + 1];
;             const f32x4 a = {bflo(wa[0]), bfhi(wa[0]), bflo(wa[1]), bfhi(wa[1])}, c = {bflo(wc2[0]), bfhi(wc2[0]), bflo(wc2[1]), bfhi(wc2[1])};
;             float ss = a[0] * a[0] + a[1] * a[1] + a[2] * a[2] + a[3] * a[3] + c[0] * c[0] + c[1] * c[1] + c[2] * c[2] + c[3] * c[3];
;             ss = wave_sum(ss);
;             const float rs = rsqrtf(ss * (1.0f / 512.f) + EPS);
;             const float* gp = part ? p.mla_kv_a_gain : p.mla_q_a_gain; bf16_t* dst = (part ? CKV : CQ) + (size_t)t * 512;
;             const f32x4 g0 = *(const f32x4*)(gp + lane * 4), g1 = *(const f32x4*)(gp + 256 + lane * 4);
;             u32x2 o0, o1; o0[0] = pack2(a[0] * rs * g0[0], a[1] * rs * g0[1]); o0[1] = pack2(a[2] * rs * g0[2], a[3] * rs * g0[3]);
;             o1[0] = pack2(c[0] * rs * g1[0], c[1] * rs * g1[1]); o1[1] = pack2(c[2] * rs * g1[2], c[3] * rs * g1[3]);
;             *(u32x2*)(dst + lane * 4) = o0; *(u32x2*)(dst + 256 + lane * 4) = o1;
;         }
.LBB1_1454:
	v_mad_i64_i32 v[26:27], s[20:21], v28, s5, v[10:11]
	v_lshl_add_u64 v[32:33], v[26:27], 0, v[0:1]
	v_lshl_add_u64 v[26:27], v[26:27], 0, v[14:15]
	global_load_ushort v13, v[26:27], off offset:2048
	global_load_dwordx2 v[34:35], v[32:33], off
	global_load_dwordx2 v[36:37], v[32:33], off offset:512
	global_load_dwordx2 v[30:31], v[32:33], off offset:1024
	s_nop 0
	global_load_dwordx2 v[32:33], v[32:33], off offset:1536
	v_add_u32_e32 v26, s33, v28
	s_mov_b32 s3, 0xffff
	v_cmp_gt_i32_e64 s[40:41], s2, v26
	s_waitcnt vmcnt(0) lgkmcnt(0)
	v_bfi_b32 v45, s3, v13, v45
	s_and_saveexec_b64 s[20:21], s[40:41]
	s_cbranch_execz .LBB1_1456
	v_mov_b64_e32 v[18:19], s[10:11]
	v_mad_i64_i32 v[18:19], s[26:27], v26, s5, v[18:19]
	v_mov_b32_e32 v13, v1
	v_lshl_add_u64 v[46:47], v[18:19], 0, v[0:1]
	v_lshl_add_u64 v[18:19], v[18:19], 0, v[12:13]
	global_load_ushort v13, v[18:19], off offset:2048
	global_load_dwordx2 v[24:25], v[46:47], off
	global_load_dwordx2 v[22:23], v[46:47], off offset:512
	global_load_dwordx2 v[20:21], v[46:47], off offset:1024
	s_nop 0
	global_load_dwordx2 v[18:19], v[46:47], off offset:1536
	s_mov_b32 s3, 0x5040100
	s_waitcnt vmcnt(0) lgkmcnt(0)
	v_perm_b32 v45, v13, v45, s3
.LBB1_1456:
	s_or_b64 exec, exec, s[20:21]
	v_ashrrev_i32_e32 v29, 31, v28
	v_lshlrev_b64 v[46:47], 10, v[28:29]
	v_lshl_add_u64 v[54:55], s[6:7], 0, v[46:47]
	global_load_dwordx4 v[46:49], v[4:5], off
	global_load_dwordx4 v[50:53], v[4:5], off offset:1024
	v_lshlrev_b32_e32 v66, 16, v34
	v_and_b32_e32 v67, 0xffff0000, v34
	v_lshlrev_b32_e32 v62, 16, v35
	v_and_b32_e32 v63, 0xffff0000, v35
	v_pk_mul_f32 v[34:35], v[66:67], v[66:67]
	v_pk_mul_f32 v[64:65], v[62:63], v[62:63]
	v_add_f32_e32 v13, v34, v35
	v_lshlrev_b32_e32 v60, 16, v36
	v_and_b32_e32 v61, 0xffff0000, v36
	v_add_f32_e32 v13, v64, v13
	v_lshlrev_b32_e32 v56, 16, v37
	v_and_b32_e32 v57, 0xffff0000, v37
	v_pk_mul_f32 v[36:37], v[60:61], v[60:61]
	v_add_f32_e32 v13, v65, v13
	v_add_f32_e32 v13, v36, v13
	v_pk_mul_f32 v[58:59], v[56:57], v[56:57]
	v_add_f32_e32 v13, v37, v13
	v_add_f32_e32 v13, v58, v13
	v_add_f32_e32 v13, v59, v13
	ds_bpermute_b32 v27, v38, v13
	v_lshlrev_b64 v[28:29], 7, v[28:29]
	v_lshl_add_u64 v[28:29], v[2:3], 0, v[28:29]
	s_waitcnt lgkmcnt(0)
	v_add_f32_e32 v13, v13, v27
	ds_bpermute_b32 v27, v39, v13
	s_waitcnt lgkmcnt(0)
	v_add_f32_e32 v13, v13, v27
	ds_bpermute_b32 v27, v40, v13
	s_waitcnt lgkmcnt(0)
	v_add_f32_e32 v13, v13, v27
	ds_bpermute_b32 v27, v41, v13
	s_waitcnt lgkmcnt(0)
	v_add_f32_e32 v13, v13, v27
	ds_bpermute_b32 v27, v42, v13
	s_waitcnt lgkmcnt(0)
	v_add_f32_e32 v13, v13, v27
	ds_bpermute_b32 v27, v43, v13
	s_waitcnt lgkmcnt(0)
	v_add_f32_e32 v13, v13, v27
	v_fmamk_f32 v13, v13, 0x3b000000, v16
	v_cmp_gt_f32_e64 s[42:43], s22, v13
	v_mul_f32_e32 v27, 0x4b800000, v13
	s_nop 0
	v_cndmask_b32_e64 v13, v13, v27, s[42:43]
	v_rsq_f32_e32 v13, v13
	s_nop 0
	v_mul_f32_e32 v27, 0x45800000, v13
	v_cndmask_b32_e64 v34, v13, v27, s[42:43]
	v_pk_mul_f32 v[36:37], v[34:35], v[66:67] op_sel_hi:[0,1]
	v_lshlrev_b32_e32 v13, 16, v45
	s_waitcnt vmcnt(1)
	v_pk_mul_f32 v[36:37], v[46:47], v[36:37]
	v_pk_mul_f32 v[46:47], v[34:35], v[62:63] op_sel_hi:[0,1]
	v_pk_mul_f32 v[46:47], v[48:49], v[46:47]
	v_cvt_pk_bf16_f32 v36, v36, v37
	v_cvt_pk_bf16_f32 v37, v46, v47
	v_pk_mul_f32 v[46:47], v[34:35], v[60:61] op_sel_hi:[0,1]
	v_pk_mul_f32 v[34:35], v[34:35], v[56:57] op_sel_hi:[0,1]
	s_waitcnt vmcnt(0)
	v_pk_mul_f32 v[46:47], v[50:51], v[46:47]
	v_pk_mul_f32 v[34:35], v[52:53], v[34:35]
	v_cvt_pk_bf16_f32 v46, v46, v47
	v_cvt_pk_bf16_f32 v47, v34, v35
	v_lshl_add_u64 v[34:35], v[54:55], 0, v[0:1]
	v_add_co_u32_e64 v48, s[42:43], s23, v34
	v_and_b32_e32 v57, 0xffff0000, v30
	s_nop 0
	v_addc_co_u32_e64 v49, s[42:43], 0, v35, s[42:43]
	global_store_dwordx2 v[48:49], v[36:37], off
	global_store_dwordx2 v[48:49], v[46:47], off offset:512
	global_load_dwordx4 v[46:49], v[6:7], off
	s_nop 0
	global_load_dwordx4 v[50:53], v[6:7], off offset:1024
	v_lshlrev_b32_e32 v56, 16, v30
	v_mul_f32_e32 v30, v57, v57
	v_lshlrev_b32_e32 v36, 16, v33
	v_and_b32_e32 v37, 0xffff0000, v33
	v_lshlrev_b32_e32 v54, 16, v32
	v_and_b32_e32 v55, 0xffff0000, v32
	v_lshlrev_b32_e32 v32, 16, v31
	v_and_b32_e32 v33, 0xffff0000, v31
	v_pk_fma_f32 v[30:31], v[56:57], v[56:57], v[30:31] op_sel_hi:[1,1,0]
	v_mul_f32_e32 v58, v33, v33
	v_pk_fma_f32 v[30:31], v[32:33], v[32:33], v[30:31]
	v_mul_f32_e32 v60, v13, v13
	v_pk_add_f32 v[30:31], v[58:59], v[30:31] op_sel_hi:[0,1]
	v_pk_fma_f32 v[30:31], v[54:55], v[54:55], v[30:31]
	v_mul_f32_e32 v58, v55, v55
	v_pk_add_f32 v[30:31], v[58:59], v[30:31] op_sel_hi:[0,1]
	v_pk_fma_f32 v[30:31], v[36:37], v[36:37], v[30:31]
	v_mul_f32_e32 v58, v37, v37
	v_pk_add_f32 v[30:31], v[58:59], v[30:31] op_sel_hi:[0,1]
	ds_bpermute_b32 v59, v38, v30
	ds_bpermute_b32 v58, v38, v60
	v_mov_b32_e32 v61, v30
	s_waitcnt lgkmcnt(0)
	v_pk_add_f32 v[30:31], v[60:61], v[58:59]
	ds_bpermute_b32 v59, v39, v31
	ds_bpermute_b32 v58, v39, v30
	s_waitcnt lgkmcnt(0)
	v_pk_add_f32 v[30:31], v[30:31], v[58:59]
	ds_bpermute_b32 v59, v40, v31
	ds_bpermute_b32 v58, v40, v30
	s_waitcnt lgkmcnt(0)
	v_pk_add_f32 v[30:31], v[30:31], v[58:59]
	ds_bpermute_b32 v59, v41, v31
	ds_bpermute_b32 v58, v41, v30
	s_waitcnt lgkmcnt(0)
	v_pk_add_f32 v[30:31], v[30:31], v[58:59]
	ds_bpermute_b32 v59, v42, v31
	ds_bpermute_b32 v58, v42, v30
	s_waitcnt lgkmcnt(0)
	v_pk_add_f32 v[30:31], v[30:31], v[58:59]
	ds_bpermute_b32 v59, v43, v31
	ds_bpermute_b32 v58, v43, v30
	s_waitcnt lgkmcnt(0)
; DI unsigned pack2(float a, float b) { f32x2 v = {a, b}; hwbf16x2 r = __builtin_convertvector(v, hwbf16x2); return __builtin_bit_cast(unsigned, r); }
; DI bf16_t f2bf(float a) { return (bf16_t)(pack2(a, 0.f) & 0xffffu); }
; DI float bf2f(unsigned short b) { return __uint_as_float(((unsigned)b) << 16); }
; DI float wave_sum(float v) { for (int o = 32; o; o >>= 1) v += __shfl_xor(v, o); return v; }
;     DI const char* a(const Unit& u) const { return (const char*)(A + (size_t)u.pm * BM * lda); }
;     DI const char* a(const Unit& u) const { return (const char*)(A + (size_t)u.pm * BM * 2048 + (u.pn >> 1) * 512); }
;     DI const char* a(const Unit& u) const { return (const char*)((u.pn < 12 ? A1 : A2) + (size_t)u.pm * BM * 512); }
; DI void mla_prep1_phase(const Params& p) {
;     ...
;             u32x2 o0, o1; o0[0] = pack2(a[0] * rs * g0[0], a[1] * rs * g0[1]); o0[1] = pack2(a[2] * rs * g0[2], a[3] * rs * g0[3]);
;             o1[0] = pack2(c[0] * rs * g1[0], c[1] * rs * g1[1]); o1[1] = pack2(c[2] * rs * g1[2], c[3] * rs * g1[3]);
;             *(u32x2*)(dst + lane * 4) = o0; *(u32x2*)(dst + 256 + lane * 4) = o1;
;         }
;         const float x = bf2f(kx[q2]);
;         const float ss = wave_sum(x * x);
;         const float xn = x * rsqrtf(ss * (1.0f / 64.f) + EPS) * p.mla_kr_gain[lane];
;         const float pr = __shfl_xor(xn, 32);
;         const float cc = ct[s * 32 + (lane & 31)], sn = st[s * 32 + (lane & 31)];
;         const float o = lane < 32 ? xn * cc - pr * sn : xn * cc + pr * sn;
;         KPE[(size_t)t * 64 + lane] = f2bf(o);
	v_pk_add_f32 v[30:31], v[30:31], v[58:59]
	s_nop 0
	v_pk_fma_f32 v[30:31], v[30:31], s[18:19], v[16:17] op_sel_hi:[1,1,0]
	s_nop 0
	v_mul_f32_e32 v27, 0x4b800000, v31
	v_cmp_gt_f32_e64 s[44:45], s22, v31
	v_cmp_gt_f32_e64 s[42:43], s22, v30
	s_nop 0
	v_cndmask_b32_e64 v27, v31, v27, s[44:45]
	v_rsq_f32_e32 v27, v27
	s_nop 0
	v_mul_f32_e32 v31, 0x45800000, v27
	v_cndmask_b32_e64 v58, v27, v31, s[44:45]
	v_mul_f32_e32 v27, 0x4b800000, v30
	v_cndmask_b32_e64 v27, v30, v27, s[42:43]
	v_rsq_f32_e32 v27, v27
	v_pk_mul_f32 v[56:57], v[58:59], v[56:57] op_sel_hi:[0,1]
	v_pk_mul_f32 v[32:33], v[58:59], v[32:33] op_sel_hi:[0,1]
	s_waitcnt vmcnt(0)
	v_pk_mul_f32 v[46:47], v[46:47], v[56:57]
	v_pk_mul_f32 v[32:33], v[48:49], v[32:33]
	v_cvt_pk_bf16_f32 v46, v46, v47
	v_cvt_pk_bf16_f32 v47, v32, v33
	v_pk_mul_f32 v[32:33], v[58:59], v[54:55] op_sel_hi:[0,1]
	v_pk_mul_f32 v[36:37], v[58:59], v[36:37] op_sel_hi:[0,1]
	v_add_co_u32_e64 v34, s[44:45], s24, v34
	v_pk_mul_f32 v[32:33], v[50:51], v[32:33]
	v_pk_mul_f32 v[36:37], v[52:53], v[36:37]
	v_addc_co_u32_e64 v35, s[44:45], 0, v35, s[44:45]
	v_mul_f32_e32 v30, 0x45800000, v27
	v_cvt_pk_bf16_f32 v32, v32, v33
	v_cvt_pk_bf16_f32 v33, v36, v37
	global_store_dwordx2 v[34:35], v[46:47], off
	global_store_dwordx2 v[34:35], v[32:33], off offset:512
	v_cndmask_b32_e64 v27, v27, v30, s[42:43]
	v_mul_f32_e32 v13, v27, v13
	global_load_dword v27, v[8:9], off
	v_and_or_b32 v30, v44, s25, v17
	v_lshlrev_b32_e32 v30, 2, v30
	v_mov_b32_e32 v31, v1
	v_lshl_add_u64 v[32:33], s[12:13], 0, v[30:31]
	v_lshl_add_u64 v[30:31], s[14:15], 0, v[30:31]
	global_load_dword v32, v[32:33], off
	s_waitcnt vmcnt(0)
	v_mul_f32_e32 v13, v27, v13
	global_load_dword v30, v[30:31], off
	ds_bpermute_b32 v27, v38, v13
	s_waitcnt vmcnt(0) lgkmcnt(0)
	v_mul_f32_e32 v27, v30, v27
	v_cndmask_b32_e64 v27, v27, -v27, vcc
	v_fmac_f32_e32 v27, v32, v13
	v_cvt_pk_bf16_f32 v13, v27, s0
	global_store_short v[28:29], v13, off
	s_and_saveexec_b64 s[20:21], s[40:41]
	s_cbranch_execz .LBB1_1453
; DI unsigned pack2(float a, float b) { f32x2 v = {a, b}; hwbf16x2 r = __builtin_convertvector(v, hwbf16x2); return __builtin_bit_cast(unsigned, r); }
; DI bf16_t f2bf(float a) { return (bf16_t)(pack2(a, 0.f) & 0xffffu); }
; DI float bf2f(unsigned short b) { return __uint_as_float(((unsigned)b) << 16); }
; DI float bflo(unsigned w) { return __uint_as_float(w << 16); }
; DI float bfhi(unsigned w) { return __uint_as_float(w & 0xffff0000u); }
; DI float wave_sum(float v) { for (int o = 32; o; o >>= 1) v += __shfl_xor(v, o); return v; }
;     DI const char* a(const Unit& u) const { return (const char*)(A + (size_t)u.pm * BM * lda); }
; DI void mla_prep1_phase(const Params& p) {
;     ...
;       for (int q2 = 0; q2 < 2; ++q2) { const int t = t0 + q2 * tstep; if (t < T) {
;         const int s = t & (S - 1);
; #pragma unroll
;         for (int part = 0; part < 2; ++part) {
;             const u32x2 wa = wl[q2][2 * part], wc2 = wl[q2][2 * part + 1];
;             const f32x4 a = {bflo(wa[0]), bfhi(wa[0]), bflo(wa[1]), bfhi(wa[1])}, c = {bflo(wc2[0]), bfhi(wc2[0]), bflo(wc2[1]), bfhi(wc2[1])};
;             float ss = a[0] * a[0] + a[1] * a[1] + a[2] * a[2] + a[3] * a[3] + c[0] * c[0] + c[1] * c[1] + c[2] * c[2] + c[3] * c[3];
;             ss = wave_sum(ss);
;             const float rs = rsqrtf(ss * (1.0f / 512.f) + EPS);
;             const float* gp = part ? p.mla_kv_a_gain : p.mla_q_a_gain; bf16_t* dst = (part ? CKV : CQ) + (size_t)t * 512;
;             const f32x4 g0 = *(const f32x4*)(gp + lane * 4), g1 = *(const f32x4*)(gp + 256 + lane * 4);
;             u32x2 o0, o1; o0[0] = pack2(a[0] * rs * g0[0], a[1] * rs * g0[1]); o0[1] = pack2(a[2] * rs * g0[2], a[3] * rs * g0[3]);
;             o1[0] = pack2(c[0] * rs * g1[0], c[1] * rs * g1[1]); o1[1] = pack2(c[2] * rs * g1[2], c[3] * rs * g1[3]);
;             *(u32x2*)(dst + lane * 4) = o0; *(u32x2*)(dst + 256 + lane * 4) = o1;
;         }
;         const float x = bf2f(kx[q2]);
;         const float ss = wave_sum(x * x);
;         const float xn = x * rsqrtf(ss * (1.0f / 64.f) + EPS) * p.mla_kr_gain[lane];
;         const float pr = __shfl_xor(xn, 32);
;         const float cc = ct[s * 32 + (lane & 31)], sn = st[s * 32 + (lane & 31)];
;         const float o = lane < 32 ? xn * cc - pr * sn : xn * cc + pr * sn;
;         KPE[(size_t)t * 64 + lane] = f2bf(o);
;       } }
	v_ashrrev_i32_e32 v27, 31, v26
	v_lshlrev_b64 v[28:29], 10, v[26:27]
	v_lshl_add_u64 v[36:37], s[6:7], 0, v[28:29]
	global_load_dwordx4 v[28:31], v[4:5], off
	global_load_dwordx4 v[32:35], v[4:5], off offset:1024
	v_lshlrev_b32_e32 v58, 16, v24
	v_and_b32_e32 v59, 0xffff0000, v24
	v_lshlrev_b32_e32 v54, 16, v25
	v_and_b32_e32 v55, 0xffff0000, v25
	v_pk_mul_f32 v[60:61], v[58:59], v[58:59]
	v_pk_mul_f32 v[56:57], v[54:55], v[54:55]
	v_add_f32_e32 v13, v60, v61
	v_lshlrev_b32_e32 v50, 16, v22
	v_and_b32_e32 v51, 0xffff0000, v22
	v_add_f32_e32 v13, v56, v13
	v_pk_mul_f32 v[52:53], v[50:51], v[50:51]
	v_add_f32_e32 v13, v57, v13
	v_lshlrev_b32_e32 v46, 16, v23
	v_and_b32_e32 v47, 0xffff0000, v23
	v_add_f32_e32 v13, v52, v13
	v_pk_mul_f32 v[48:49], v[46:47], v[46:47]
	v_add_f32_e32 v13, v53, v13
	v_add_f32_e32 v13, v48, v13
	v_add_f32_e32 v13, v49, v13
	ds_bpermute_b32 v48, v38, v13
	s_waitcnt lgkmcnt(0)
	v_add_f32_e32 v13, v13, v48
	ds_bpermute_b32 v48, v39, v13
	s_waitcnt lgkmcnt(0)
	v_add_f32_e32 v13, v13, v48
	ds_bpermute_b32 v48, v40, v13
	s_waitcnt lgkmcnt(0)
	v_add_f32_e32 v13, v13, v48
	ds_bpermute_b32 v48, v41, v13
	s_waitcnt lgkmcnt(0)
	v_add_f32_e32 v13, v13, v48
	ds_bpermute_b32 v48, v42, v13
	s_waitcnt lgkmcnt(0)
	v_add_f32_e32 v13, v13, v48
	ds_bpermute_b32 v48, v43, v13
	s_waitcnt lgkmcnt(0)
	v_add_f32_e32 v13, v13, v48
	v_fmamk_f32 v13, v13, 0x3b000000, v16
	v_cmp_gt_f32_e64 s[40:41], s22, v13
	v_mul_f32_e32 v48, 0x4b800000, v13
	s_nop 0
	v_cndmask_b32_e64 v13, v13, v48, s[40:41]
	v_rsq_f32_e32 v13, v13
	s_nop 0
	v_mul_f32_e32 v48, 0x45800000, v13
	v_cndmask_b32_e64 v48, v13, v48, s[40:41]
	v_pk_mul_f32 v[52:53], v[48:49], v[58:59] op_sel_hi:[0,1]
	v_and_b32_e32 v13, 0xffff0000, v45
	v_mul_f32_e32 v58, v13, v13
	s_waitcnt vmcnt(0)
	v_pk_mul_f32 v[28:29], v[28:29], v[52:53]
	s_nop 0
	v_cvt_pk_bf16_f32 v52, v28, v29
	v_pk_mul_f32 v[28:29], v[48:49], v[54:55] op_sel_hi:[0,1]
	v_pk_mul_f32 v[28:29], v[30:31], v[28:29]
	s_nop 0
	v_cvt_pk_bf16_f32 v53, v28, v29
	v_pk_mul_f32 v[28:29], v[48:49], v[50:51] op_sel_hi:[0,1]
	v_pk_mul_f32 v[28:29], v[32:33], v[28:29]
	v_lshlrev_b32_e32 v50, 16, v21
	v_cvt_pk_bf16_f32 v30, v28, v29
	v_pk_mul_f32 v[28:29], v[48:49], v[46:47] op_sel_hi:[0,1]
	v_pk_mul_f32 v[28:29], v[34:35], v[28:29]
	v_and_b32_e32 v51, 0xffff0000, v21
	v_cvt_pk_bf16_f32 v31, v28, v29
	v_lshl_add_u64 v[28:29], v[36:37], 0, v[0:1]
	v_add_co_u32_e64 v32, s[40:41], s23, v28
	v_mul_f32_e32 v56, v51, v51
	s_nop 0
	v_addc_co_u32_e64 v33, s[40:41], 0, v29, s[40:41]
	global_store_dwordx2 v[32:33], v[52:53], off
	global_store_dwordx2 v[32:33], v[30:31], off offset:512
	global_load_dwordx4 v[30:33], v[6:7], off
	s_nop 0
	global_load_dwordx4 v[34:37], v[6:7], off offset:1024
	v_and_b32_e32 v53, 0xffff0000, v20
	v_lshlrev_b32_e32 v52, 16, v20
	v_mul_f32_e32 v54, v53, v53
	v_pk_fma_f32 v[54:55], v[52:53], v[52:53], v[54:55] op_sel_hi:[1,1,0]
	v_lshlrev_b32_e32 v48, 16, v18
	v_pk_fma_f32 v[54:55], v[50:51], v[50:51], v[54:55]
	v_and_b32_e32 v49, 0xffff0000, v18
	v_pk_add_f32 v[54:55], v[56:57], v[54:55] op_sel_hi:[0,1]
	v_pk_fma_f32 v[54:55], v[48:49], v[48:49], v[54:55]
	v_mul_f32_e32 v56, v49, v49
	v_lshlrev_b32_e32 v46, 16, v19
	v_and_b32_e32 v47, 0xffff0000, v19
	v_pk_add_f32 v[54:55], v[56:57], v[54:55] op_sel_hi:[0,1]
	v_pk_fma_f32 v[54:55], v[46:47], v[46:47], v[54:55]
	v_mul_f32_e32 v56, v47, v47
	v_pk_add_f32 v[54:55], v[56:57], v[54:55] op_sel_hi:[0,1]
	ds_bpermute_b32 v57, v38, v54
	ds_bpermute_b32 v56, v38, v58
	v_mov_b32_e32 v59, v54
	s_waitcnt lgkmcnt(0)
	v_pk_add_f32 v[54:55], v[58:59], v[56:57]
	ds_bpermute_b32 v57, v39, v55
	ds_bpermute_b32 v56, v39, v54
	s_waitcnt lgkmcnt(0)
	v_pk_add_f32 v[54:55], v[54:55], v[56:57]
	ds_bpermute_b32 v57, v40, v55
	ds_bpermute_b32 v56, v40, v54
	s_waitcnt lgkmcnt(0)
	v_pk_add_f32 v[54:55], v[54:55], v[56:57]
	ds_bpermute_b32 v57, v41, v55
	ds_bpermute_b32 v56, v41, v54
	s_waitcnt lgkmcnt(0)
	v_pk_add_f32 v[54:55], v[54:55], v[56:57]
	ds_bpermute_b32 v57, v42, v55
	ds_bpermute_b32 v56, v42, v54
	s_waitcnt lgkmcnt(0)
	v_pk_add_f32 v[54:55], v[54:55], v[56:57]
	ds_bpermute_b32 v57, v43, v55
	ds_bpermute_b32 v56, v43, v54
	s_waitcnt lgkmcnt(0)
	v_pk_add_f32 v[54:55], v[54:55], v[56:57]
	s_nop 0
	v_pk_fma_f32 v[54:55], v[54:55], s[18:19], v[16:17] op_sel_hi:[1,1,0]
	s_nop 0
	v_mul_f32_e32 v56, 0x4b800000, v55
	v_cmp_gt_f32_e64 s[42:43], s22, v55
	v_cmp_gt_f32_e64 s[40:41], s22, v54
	s_nop 0
	v_cndmask_b32_e64 v55, v55, v56, s[42:43]
	v_rsq_f32_e32 v55, v55
	s_nop 0
	v_mul_f32_e32 v56, 0x45800000, v55
	v_cndmask_b32_e64 v56, v55, v56, s[42:43]
	v_pk_mul_f32 v[52:53], v[56:57], v[52:53] op_sel_hi:[0,1]
	v_pk_mul_f32 v[50:51], v[56:57], v[50:51] op_sel_hi:[0,1]
	v_add_co_u32_e64 v28, s[42:43], s24, v28
	s_waitcnt vmcnt(0)
	v_pk_mul_f32 v[30:31], v[30:31], v[52:53]
	v_pk_mul_f32 v[32:33], v[32:33], v[50:51]
	v_cvt_pk_bf16_f32 v30, v30, v31
	v_cvt_pk_bf16_f32 v31, v32, v33
	v_pk_mul_f32 v[32:33], v[56:57], v[48:49] op_sel_hi:[0,1]
	v_pk_mul_f32 v[32:33], v[34:35], v[32:33]
	v_pk_mul_f32 v[34:35], v[56:57], v[46:47] op_sel_hi:[0,1]
	v_pk_mul_f32 v[34:35], v[36:37], v[34:35]
	v_addc_co_u32_e64 v29, s[42:43], 0, v29, s[42:43]
	v_cvt_pk_bf16_f32 v32, v32, v33
	v_cvt_pk_bf16_f32 v33, v34, v35
	global_store_dwordx2 v[28:29], v[30:31], off
	global_store_dwordx2 v[28:29], v[32:33], off offset:512
	v_mul_f32_e32 v28, 0x4b800000, v54
	v_cndmask_b32_e64 v28, v54, v28, s[40:41]
	v_rsq_f32_e32 v28, v28
	s_nop 0
	v_mul_f32_e32 v29, 0x45800000, v28
	v_cndmask_b32_e64 v28, v28, v29, s[40:41]
	v_mul_f32_e32 v13, v28, v13
	global_load_dword v28, v[8:9], off
	v_mov_b32_e32 v29, v1
	s_waitcnt vmcnt(0)
	v_mul_f32_e32 v13, v28, v13
	v_add_u32_e32 v28, s4, v44
	v_and_or_b32 v28, v28, s25, v17
	v_lshlrev_b32_e32 v28, 2, v28
	v_lshl_add_u64 v[30:31], s[12:13], 0, v[28:29]
	v_lshl_add_u64 v[28:29], s[14:15], 0, v[28:29]
	global_load_dword v30, v[30:31], off
	ds_bpermute_b32 v32, v38, v13
	global_load_dword v28, v[28:29], off
	s_waitcnt vmcnt(0) lgkmcnt(0)
	v_mul_f32_e32 v28, v28, v32
	v_cndmask_b32_e64 v28, v28, -v28, vcc
	v_fmac_f32_e32 v28, v30, v13
	v_cvt_pk_bf16_f32 v13, v28, s0
	v_lshlrev_b64 v[28:29], 7, v[26:27]
	v_lshl_add_u64 v[28:29], v[2:3], 0, v[28:29]
	global_store_short v[28:29], v13, off
	s_branch .LBB1_1453

; #define PG8_STAGE(bufoff, gbase, voff) do { _Pragma("unroll") for (int _i = 0; _i < 2; ++_i) \
;         __builtin_amdgcn_global_load_lds((const unsigned*)((const char*)(gbase) + (voff)[_i]), (LAS unsigned*)(lds + (bufoff) + ldsw + _i * 8192), 16, 0, 0); } while (0)
; #define PG8_LDA(dst, b, h) do { _Pragma("unroll") for (int m = 0; m < 4; ++m) _Pragma("unroll") for (int k = 0; k < 2; ++k) dst[m][k] = *(const LAS bf16x8*)(lds + PG8_SA(b, h) + aoff + m * 2048 + k * 1024); } while (0)
; #define PG8_WAIT_V(n) asm volatile("s_waitcnt vmcnt(" #n ")" ::: "memory")
; #define PG8_BAR __builtin_amdgcn_s_barrier()
; template <class Map, class Epi>
; DI void gemm_phase(LAS unsigned char* lds, const Map& MP, const Epi& E, const int nM, const int nN, const int K, const int lda, const int ldb) {
;     ...
;         for (int t = 0; t < nt; t += 2) {
;             const bool last = (t == nt - 2);
;             const char* a1 = cA + (size_t)(t + 1) * kstep;
;             const char* a2 = last ? nA : cA + (size_t)(t + 2) * kstep; const char* b2 = last ? nB : cB + (size_t)(t + 2) * kstep;
;             const char* a3 = a2 + kstep; const char* b3 = b2 + kstep;
;             PG8_LDB(B0, 0, 0); PG8_SCHED; PG8_LDA(At, 0, 0); PG8_STAGE(PG8_SA(1, 1), a1 + hstepA, voffA);
;             PG8_WAIT_L(8); PG8_BAR; PG8_WAIT_L(0); PG8_MMA(0, 0, At, B0); PG8_BAR; PG8_SCHED;
;             PG8_LDB(B1, 0, 1); PG8_STAGE(PG8_SB(0, 0), b2, voffB);
;             PG8_BAR; PG8_WAIT_L(0); PG8_MMA(0, 1, At, B1); PG8_BAR;
;             PG8_LDA(At, 0, 1); PG8_STAGE(PG8_SA(0, 0), a2, voffA);
;             PG8_BAR; PG8_WAIT_L(0); PG8_MMA(1, 0, At, B0); PG8_BAR; PG8_SCHED;
;             PG8_STAGE(PG8_SB(0, 1), b2 + hstepB, voffB);
;             PG8_WAIT_V(6); PG8_BAR; PG8_MMA(1, 1, At, B1); PG8_BAR;
;             PG8_LDB(B0, 1, 0); PG8_SCHED; PG8_LDA(At, 1, 0); PG8_STAGE(PG8_SA(0, 1), a2 + hstepA, voffA);
;             PG8_WAIT_L(8); PG8_BAR; PG8_WAIT_L(0); PG8_MMA(0, 0, At, B0); PG8_BAR; PG8_SCHED;
;             PG8_LDB(B1, 1, 1); PG8_STAGE(PG8_SB(1, 0), b3, voffB);
;             PG8_BAR; PG8_WAIT_L(0); PG8_MMA(0, 1, At, B1); PG8_BAR;
;             PG8_LDA(At, 1, 1); PG8_STAGE(PG8_SA(1, 0), a3, voffA);
;             PG8_BAR; PG8_WAIT_L(0); PG8_MMA(1, 0, At, B0); PG8_BAR; PG8_SCHED;
;             PG8_STAGE(PG8_SB(1, 1), b3 + hstepB, voffB);
;             PG8_WAIT_V(6); PG8_BAR; PG8_MMA(1, 1, At, B1); PG8_BAR;
.LBB1_1529:
	ds_read_b128 v[150:153], v147
	ds_read_b128 v[154:157], v147 offset:1024
	ds_read_b128 v[158:161], v147 offset:2048
	ds_read_b128 v[162:165], v147 offset:3072
	s_add_u32 s20, s18, 0xfffe0080
	s_addc_u32 s21, s19, -1
	s_cmp_eq_u32 s3, 4
	s_cselect_b32 s23, s13, s21
	s_cselect_b32 s22, s52, s20
	s_cselect_b32 s21, s53, s56
	s_cselect_b32 s20, s54, s55
	v_lshl_add_u64 v[194:195], s[18:19], 0, v[138:139]
	s_add_i32 m0, s11, 0xc000
	ds_read_b128 v[166:169], v148
	ds_read_b128 v[170:173], v148 offset:1024
	ds_read_b128 v[174:177], v148 offset:2048
	ds_read_b128 v[178:181], v148 offset:3072
	ds_read_b128 v[182:185], v148 offset:4096
	ds_read_b128 v[186:189], v148 offset:5120
	ds_read_b128 v[190:193], v148 offset:6144
	ds_read_b128 v[198:201], v148 offset:7168
	global_load_lds_dwordx4 v[194:195], off
	v_lshl_add_u64 v[194:195], s[18:19], 0, v[136:137]
	s_add_i32 m0, s11, 0xe000
	s_nop 0
	global_load_lds_dwordx4 v[194:195], off
	s_waitcnt lgkmcnt(8)
	s_barrier
	s_setprio 1
	s_waitcnt lgkmcnt(7)
	v_mfma_f32_16x16x32_bf16 v[124:127], v[150:153], v[166:169], v[124:127]
	v_mfma_f32_16x16x32_bf16 v[120:123], v[158:161], v[166:169], v[120:123]
	s_waitcnt lgkmcnt(5)
	v_mfma_f32_16x16x32_bf16 v[116:119], v[150:153], v[174:177], v[116:119]
	v_mfma_f32_16x16x32_bf16 v[112:115], v[158:161], v[174:177], v[112:115]
	s_waitcnt lgkmcnt(3)
	v_mfma_f32_16x16x32_bf16 v[100:103], v[150:153], v[182:185], v[100:103]
	v_mfma_f32_16x16x32_bf16 v[96:99], v[158:161], v[182:185], v[96:99]
	s_waitcnt lgkmcnt(1)
	v_mfma_f32_16x16x32_bf16 v[84:87], v[150:153], v[190:193], v[84:87]
	v_mfma_f32_16x16x32_bf16 v[80:83], v[158:161], v[190:193], v[80:83]
	v_mfma_f32_16x16x32_bf16 v[124:127], v[154:157], v[170:173], v[124:127]
	v_mfma_f32_16x16x32_bf16 v[120:123], v[162:165], v[170:173], v[120:123]
	v_mfma_f32_16x16x32_bf16 v[116:119], v[154:157], v[178:181], v[116:119]
	v_mfma_f32_16x16x32_bf16 v[112:115], v[162:165], v[178:181], v[112:115]
	v_mfma_f32_16x16x32_bf16 v[100:103], v[154:157], v[186:189], v[100:103]
	v_mfma_f32_16x16x32_bf16 v[96:99], v[162:165], v[186:189], v[96:99]
	s_waitcnt lgkmcnt(0)
	v_mfma_f32_16x16x32_bf16 v[84:87], v[154:157], v[198:201], v[84:87]
	v_mfma_f32_16x16x32_bf16 v[80:83], v[162:165], v[198:201], v[80:83]
	s_setprio 0
	s_barrier
	s_add_i32 s57, s47, s31
	v_lshl_add_u64 v[194:195], s[20:21], 0, v[132:133]
	s_mov_b32 m0, s57
	ds_read_b128 v[202:205], v149
	ds_read_b128 v[206:209], v149 offset:1024
	ds_read_b128 v[210:213], v149 offset:2048
	ds_read_b128 v[214:217], v149 offset:3072
	global_load_lds_dwordx4 v[194:195], off
	v_lshl_add_u64 v[218:219], s[20:21], 0, v[128:129]
	s_add_i32 m0, s57, 0x2000
	s_nop 0
	global_load_lds_dwordx4 v[218:219], off
	s_barrier
	s_setprio 1
	s_waitcnt lgkmcnt(3)
	v_mfma_f32_16x16x32_bf16 v[108:111], v[202:205], v[166:169], v[108:111]
	s_waitcnt lgkmcnt(1)
	v_mfma_f32_16x16x32_bf16 v[104:107], v[210:213], v[166:169], v[104:107]
	v_mfma_f32_16x16x32_bf16 v[92:95], v[202:205], v[174:177], v[92:95]
	v_mfma_f32_16x16x32_bf16 v[88:91], v[210:213], v[174:177], v[88:91]
	v_mfma_f32_16x16x32_bf16 v[76:79], v[202:205], v[182:185], v[76:79]
	v_mfma_f32_16x16x32_bf16 v[72:75], v[210:213], v[182:185], v[72:75]
	v_mfma_f32_16x16x32_bf16 v[68:71], v[202:205], v[190:193], v[68:71]
	v_mfma_f32_16x16x32_bf16 v[64:67], v[210:213], v[190:193], v[64:67]
	v_mfma_f32_16x16x32_bf16 v[108:111], v[206:209], v[170:173], v[108:111]
	s_waitcnt lgkmcnt(0)
	v_mfma_f32_16x16x32_bf16 v[104:107], v[214:217], v[170:173], v[104:107]
	v_mfma_f32_16x16x32_bf16 v[92:95], v[206:209], v[178:181], v[92:95]
	v_mfma_f32_16x16x32_bf16 v[88:91], v[214:217], v[178:181], v[88:91]
	v_mfma_f32_16x16x32_bf16 v[76:79], v[206:209], v[186:189], v[76:79]
	v_mfma_f32_16x16x32_bf16 v[72:75], v[214:217], v[186:189], v[72:75]
	v_mfma_f32_16x16x32_bf16 v[68:71], v[206:209], v[198:201], v[68:71]
	v_mfma_f32_16x16x32_bf16 v[64:67], v[214:217], v[198:201], v[64:67]
	s_setprio 0
	s_mov_b32 m0, s11
	v_lshl_add_u64 v[220:221], s[22:23], 0, v[134:135]
	s_barrier
	ds_read_b128 v[166:169], v148 offset:16384
	ds_read_b128 v[170:173], v148 offset:17408
	ds_read_b128 v[174:177], v148 offset:18432
	ds_read_b128 v[178:181], v148 offset:19456
	ds_read_b128 v[182:185], v148 offset:20480
	ds_read_b128 v[186:189], v148 offset:21504
	ds_read_b128 v[190:193], v148 offset:22528
	ds_read_b128 v[198:201], v148 offset:23552
	global_load_lds_dwordx4 v[220:221], off
	v_lshl_add_u64 v[222:223], s[22:23], 0, v[130:131]
	s_mov_b32 m0, s35
	s_nop 0
	global_load_lds_dwordx4 v[222:223], off
	s_barrier
	s_setprio 1
	s_waitcnt lgkmcnt(7)
	v_mfma_f32_16x16x32_bf16 v[60:63], v[150:153], v[166:169], v[60:63]
	v_mfma_f32_16x16x32_bf16 v[56:59], v[158:161], v[166:169], v[56:59]
	s_waitcnt lgkmcnt(5)
	v_mfma_f32_16x16x32_bf16 v[52:55], v[150:153], v[174:177], v[52:55]
	v_mfma_f32_16x16x32_bf16 v[48:51], v[158:161], v[174:177], v[48:51]
	s_waitcnt lgkmcnt(3)
	v_mfma_f32_16x16x32_bf16 v[36:39], v[150:153], v[182:185], v[36:39]
	v_mfma_f32_16x16x32_bf16 v[32:35], v[158:161], v[182:185], v[32:35]
	s_waitcnt lgkmcnt(1)
	v_mfma_f32_16x16x32_bf16 v[20:23], v[150:153], v[190:193], v[20:23]
	v_mfma_f32_16x16x32_bf16 v[16:19], v[158:161], v[190:193], v[16:19]
	v_mfma_f32_16x16x32_bf16 v[60:63], v[154:157], v[170:173], v[60:63]
	v_mfma_f32_16x16x32_bf16 v[56:59], v[162:165], v[170:173], v[56:59]
	v_mfma_f32_16x16x32_bf16 v[52:55], v[154:157], v[178:181], v[52:55]
	v_mfma_f32_16x16x32_bf16 v[48:51], v[162:165], v[178:181], v[48:51]
	v_mfma_f32_16x16x32_bf16 v[36:39], v[154:157], v[186:189], v[36:39]
	v_mfma_f32_16x16x32_bf16 v[32:35], v[162:165], v[186:189], v[32:35]
	s_waitcnt lgkmcnt(0)
	v_mfma_f32_16x16x32_bf16 v[20:23], v[154:157], v[198:201], v[20:23]
	v_mfma_f32_16x16x32_bf16 v[16:19], v[162:165], v[198:201], v[16:19]
	s_setprio 0
	s_barrier
; #define PG8_STAGE(bufoff, gbase, voff) do { _Pragma("unroll") for (int _i = 0; _i < 2; ++_i) \
;         __builtin_amdgcn_global_load_lds((const unsigned*)((const char*)(gbase) + (voff)[_i]), (LAS unsigned*)(lds + (bufoff) + ldsw + _i * 8192), 16, 0, 0); } while (0)
; #define PG8_LDA(dst, b, h) do { _Pragma("unroll") for (int m = 0; m < 4; ++m) _Pragma("unroll") for (int k = 0; k < 2; ++k) dst[m][k] = *(const LAS bf16x8*)(lds + PG8_SA(b, h) + aoff + m * 2048 + k * 1024); } while (0)
; #define PG8_WAIT_V(n) asm volatile("s_waitcnt vmcnt(" #n ")" ::: "memory")
; #define PG8_BAR __builtin_amdgcn_s_barrier()
; template <class Map, class Epi>
; DI void gemm_phase(LAS unsigned char* lds, const Map& MP, const Epi& E, const int nM, const int nN, const int K, const int lda, const int ldb) {
;     ...
;         for (int t = 0; t < nt; t += 2) {
;             const bool last = (t == nt - 2);
;             const char* a1 = cA + (size_t)(t + 1) * kstep;
;             const char* a2 = last ? nA : cA + (size_t)(t + 2) * kstep; const char* b2 = last ? nB : cB + (size_t)(t + 2) * kstep;
;             const char* a3 = a2 + kstep; const char* b3 = b2 + kstep;
;             PG8_LDB(B0, 0, 0); PG8_SCHED; PG8_LDA(At, 0, 0); PG8_STAGE(PG8_SA(1, 1), a1 + hstepA, voffA);
;             PG8_WAIT_L(8); PG8_BAR; PG8_WAIT_L(0); PG8_MMA(0, 0, At, B0); PG8_BAR; PG8_SCHED;
;             PG8_LDB(B1, 0, 1); PG8_STAGE(PG8_SB(0, 0), b2, voffB);
;             PG8_BAR; PG8_WAIT_L(0); PG8_MMA(0, 1, At, B1); PG8_BAR;
;             PG8_LDA(At, 0, 1); PG8_STAGE(PG8_SA(0, 0), a2, voffA);
;             PG8_BAR; PG8_WAIT_L(0); PG8_MMA(1, 0, At, B0); PG8_BAR; PG8_SCHED;
;             PG8_STAGE(PG8_SB(0, 1), b2 + hstepB, voffB);
;             PG8_WAIT_V(6); PG8_BAR; PG8_MMA(1, 1, At, B1); PG8_BAR;
;             PG8_LDB(B0, 1, 0); PG8_SCHED; PG8_LDA(At, 1, 0); PG8_STAGE(PG8_SA(0, 1), a2 + hstepA, voffA);
;             PG8_WAIT_L(8); PG8_BAR; PG8_WAIT_L(0); PG8_MMA(0, 0, At, B0); PG8_BAR; PG8_SCHED;
;             PG8_LDB(B1, 1, 1); PG8_STAGE(PG8_SB(1, 0), b3, voffB);
;             PG8_BAR; PG8_WAIT_L(0); PG8_MMA(0, 1, At, B1); PG8_BAR;
;             PG8_LDA(At, 1, 1); PG8_STAGE(PG8_SA(1, 0), a3, voffA);
;             PG8_BAR; PG8_WAIT_L(0); PG8_MMA(1, 0, At, B0); PG8_BAR; PG8_SCHED;
;             PG8_STAGE(PG8_SB(1, 1), b3 + hstepB, voffB);
;             PG8_WAIT_V(6); PG8_BAR; PG8_MMA(1, 1, At, B1); PG8_BAR;
	s_add_u32 s58, s20, 0x20000
	s_addc_u32 s59, s21, 0
	s_add_i32 s57, s48, s31
	v_lshl_add_u64 v[150:151], s[58:59], 0, v[132:133]
	s_mov_b32 m0, s57
	s_nop 0
	global_load_lds_dwordx4 v[150:151], off
	v_lshl_add_u64 v[150:151], s[58:59], 0, v[128:129]
	s_add_i32 m0, s57, 0x2000
	s_nop 0
	global_load_lds_dwordx4 v[150:151], off
	s_waitcnt vmcnt(6)
	s_barrier
	s_setprio 1
	v_mfma_f32_16x16x32_bf16 v[44:47], v[202:205], v[166:169], v[44:47]
	v_mfma_f32_16x16x32_bf16 v[40:43], v[210:213], v[166:169], v[40:43]
	v_mfma_f32_16x16x32_bf16 v[28:31], v[202:205], v[174:177], v[28:31]
	v_mfma_f32_16x16x32_bf16 v[24:27], v[210:213], v[174:177], v[24:27]
	v_mfma_f32_16x16x32_bf16 v[12:15], v[202:205], v[182:185], v[12:15]
	v_mfma_f32_16x16x32_bf16 v[8:11], v[210:213], v[182:185], v[8:11]
	v_mfma_f32_16x16x32_bf16 v[4:7], v[202:205], v[190:193], v[4:7]
	v_mfma_f32_16x16x32_bf16 v[0:3], v[210:213], v[190:193], v[0:3]
	v_mfma_f32_16x16x32_bf16 v[44:47], v[206:209], v[170:173], v[44:47]
	v_mfma_f32_16x16x32_bf16 v[40:43], v[214:217], v[170:173], v[40:43]
	v_mfma_f32_16x16x32_bf16 v[28:31], v[206:209], v[178:181], v[28:31]
	v_mfma_f32_16x16x32_bf16 v[24:27], v[214:217], v[178:181], v[24:27]
	v_mfma_f32_16x16x32_bf16 v[12:15], v[206:209], v[186:189], v[12:15]
	v_mfma_f32_16x16x32_bf16 v[8:11], v[214:217], v[186:189], v[8:11]
	v_mfma_f32_16x16x32_bf16 v[4:7], v[206:209], v[198:201], v[4:7]
	v_mfma_f32_16x16x32_bf16 v[0:3], v[214:217], v[198:201], v[0:3]
	s_setprio 0
	s_add_i32 s57, 0, 0x18000
	v_add_u32_e32 v162, s57, v146
	s_barrier
	ds_read_b128 v[150:153], v162
	ds_read_b128 v[154:157], v162 offset:1024
	ds_read_b128 v[158:161], v162 offset:2048
	ds_read_b128 v[162:165], v162 offset:3072
	s_add_u32 s22, s22, 0x20000
	s_addc_u32 s23, s23, 0
	s_mov_b32 m0, s36
	v_lshl_add_u64 v[202:203], s[22:23], 0, v[134:135]
	ds_read_b128 v[166:169], v148 offset:32768
	ds_read_b128 v[170:173], v148 offset:33792
	ds_read_b128 v[174:177], v148 offset:34816
	ds_read_b128 v[178:181], v148 offset:35840
	ds_read_b128 v[182:185], v148 offset:36864
	ds_read_b128 v[186:189], v148 offset:37888
	ds_read_b128 v[190:193], v148 offset:38912
	ds_read_b128 v[198:201], v148 offset:39936
	global_load_lds_dwordx4 v[202:203], off
	v_lshl_add_u64 v[202:203], s[22:23], 0, v[130:131]
	s_mov_b32 m0, s37
	s_nop 0
	global_load_lds_dwordx4 v[202:203], off
	s_waitcnt lgkmcnt(8)
	s_barrier
	s_setprio 1
	s_waitcnt lgkmcnt(7)
	v_mfma_f32_16x16x32_bf16 v[124:127], v[150:153], v[166:169], v[124:127]
	v_mfma_f32_16x16x32_bf16 v[120:123], v[158:161], v[166:169], v[120:123]
	s_waitcnt lgkmcnt(5)
	v_mfma_f32_16x16x32_bf16 v[116:119], v[150:153], v[174:177], v[116:119]
	v_mfma_f32_16x16x32_bf16 v[112:115], v[158:161], v[174:177], v[112:115]
	s_waitcnt lgkmcnt(3)
	v_mfma_f32_16x16x32_bf16 v[100:103], v[150:153], v[182:185], v[100:103]
	v_mfma_f32_16x16x32_bf16 v[96:99], v[158:161], v[182:185], v[96:99]
	s_waitcnt lgkmcnt(1)
	v_mfma_f32_16x16x32_bf16 v[84:87], v[150:153], v[190:193], v[84:87]
	v_mfma_f32_16x16x32_bf16 v[80:83], v[158:161], v[190:193], v[80:83]
	v_mfma_f32_16x16x32_bf16 v[124:127], v[154:157], v[170:173], v[124:127]
	v_mfma_f32_16x16x32_bf16 v[120:123], v[162:165], v[170:173], v[120:123]
	v_mfma_f32_16x16x32_bf16 v[116:119], v[154:157], v[178:181], v[116:119]
	v_mfma_f32_16x16x32_bf16 v[112:115], v[162:165], v[178:181], v[112:115]
	v_mfma_f32_16x16x32_bf16 v[100:103], v[154:157], v[186:189], v[100:103]
	v_mfma_f32_16x16x32_bf16 v[96:99], v[162:165], v[186:189], v[96:99]
	s_waitcnt lgkmcnt(0)
	v_mfma_f32_16x16x32_bf16 v[84:87], v[154:157], v[198:201], v[84:87]
	v_mfma_f32_16x16x32_bf16 v[80:83], v[162:165], v[198:201], v[80:83]
	s_setprio 0
	s_barrier
	s_add_i32 s22, 0, 0x1c000
	s_add_i32 s23, s57, s31
	v_add_u32_e32 v196, s22, v146
	v_lshl_add_u64 v[194:195], v[194:195], 0, s[8:9]
	s_mov_b32 m0, s23
	ds_read_b128 v[202:205], v196
	ds_read_b128 v[206:209], v196 offset:1024
	ds_read_b128 v[210:213], v196 offset:2048
	ds_read_b128 v[214:217], v196 offset:3072
	global_load_lds_dwordx4 v[194:195], off
	v_lshl_add_u64 v[194:195], v[218:219], 0, s[8:9]
	s_add_i32 m0, s23, 0x2000
	s_nop 0
	global_load_lds_dwordx4 v[194:195], off
	s_barrier
	s_setprio 1
	s_waitcnt lgkmcnt(3)
	v_mfma_f32_16x16x32_bf16 v[108:111], v[202:205], v[166:169], v[108:111]
	s_waitcnt lgkmcnt(1)
	v_mfma_f32_16x16x32_bf16 v[104:107], v[210:213], v[166:169], v[104:107]
	v_mfma_f32_16x16x32_bf16 v[92:95], v[202:205], v[174:177], v[92:95]
	v_mfma_f32_16x16x32_bf16 v[88:91], v[210:213], v[174:177], v[88:91]
	v_mfma_f32_16x16x32_bf16 v[76:79], v[202:205], v[182:185], v[76:79]
	v_mfma_f32_16x16x32_bf16 v[72:75], v[210:213], v[182:185], v[72:75]
	v_mfma_f32_16x16x32_bf16 v[68:71], v[202:205], v[190:193], v[68:71]
	v_mfma_f32_16x16x32_bf16 v[64:67], v[210:213], v[190:193], v[64:67]
	v_mfma_f32_16x16x32_bf16 v[108:111], v[206:209], v[170:173], v[108:111]
	s_waitcnt lgkmcnt(0)
	v_mfma_f32_16x16x32_bf16 v[104:107], v[214:217], v[170:173], v[104:107]
	v_mfma_f32_16x16x32_bf16 v[92:95], v[206:209], v[178:181], v[92:95]
	v_mfma_f32_16x16x32_bf16 v[88:91], v[214:217], v[178:181], v[88:91]
	v_mfma_f32_16x16x32_bf16 v[76:79], v[206:209], v[186:189], v[76:79]
	v_mfma_f32_16x16x32_bf16 v[72:75], v[214:217], v[186:189], v[72:75]
	v_mfma_f32_16x16x32_bf16 v[68:71], v[206:209], v[198:201], v[68:71]
	v_mfma_f32_16x16x32_bf16 v[64:67], v[214:217], v[198:201], v[64:67]
	s_setprio 0
	s_mov_b32 m0, s43
	v_lshl_add_u64 v[194:195], v[220:221], 0, s[8:9]
	s_barrier
; #define PG8_STAGE(bufoff, gbase, voff) do { _Pragma("unroll") for (int _i = 0; _i < 2; ++_i) \
;         __builtin_amdgcn_global_load_lds((const unsigned*)((const char*)(gbase) + (voff)[_i]), (LAS unsigned*)(lds + (bufoff) + ldsw + _i * 8192), 16, 0, 0); } while (0)
; #define PG8_LDA(dst, b, h) do { _Pragma("unroll") for (int m = 0; m < 4; ++m) _Pragma("unroll") for (int k = 0; k < 2; ++k) dst[m][k] = *(const LAS bf16x8*)(lds + PG8_SA(b, h) + aoff + m * 2048 + k * 1024); } while (0)
; #define PG8_WAIT_V(n) asm volatile("s_waitcnt vmcnt(" #n ")" ::: "memory")
; #define PG8_BAR __builtin_amdgcn_s_barrier()
; template <class Map, class Epi>
; DI void gemm_phase(LAS unsigned char* lds, const Map& MP, const Epi& E, const int nM, const int nN, const int K, const int lda, const int ldb) {
;     ...
;         for (int t = 0; t < nt; t += 2) {
;             const bool last = (t == nt - 2);
;             const char* a1 = cA + (size_t)(t + 1) * kstep;
;             const char* a2 = last ? nA : cA + (size_t)(t + 2) * kstep; const char* b2 = last ? nB : cB + (size_t)(t + 2) * kstep;
;             const char* a3 = a2 + kstep; const char* b3 = b2 + kstep;
;             PG8_LDB(B0, 0, 0); PG8_SCHED; PG8_LDA(At, 0, 0); PG8_STAGE(PG8_SA(1, 1), a1 + hstepA, voffA);
;             PG8_WAIT_L(8); PG8_BAR; PG8_WAIT_L(0); PG8_MMA(0, 0, At, B0); PG8_BAR; PG8_SCHED;
;             PG8_LDB(B1, 0, 1); PG8_STAGE(PG8_SB(0, 0), b2, voffB);
;             PG8_BAR; PG8_WAIT_L(0); PG8_MMA(0, 1, At, B1); PG8_BAR;
;             PG8_LDA(At, 0, 1); PG8_STAGE(PG8_SA(0, 0), a2, voffA);
;             PG8_BAR; PG8_WAIT_L(0); PG8_MMA(1, 0, At, B0); PG8_BAR; PG8_SCHED;
;             PG8_STAGE(PG8_SB(0, 1), b2 + hstepB, voffB);
;             PG8_WAIT_V(6); PG8_BAR; PG8_MMA(1, 1, At, B1); PG8_BAR;
;             PG8_LDB(B0, 1, 0); PG8_SCHED; PG8_LDA(At, 1, 0); PG8_STAGE(PG8_SA(0, 1), a2 + hstepA, voffA);
;             PG8_WAIT_L(8); PG8_BAR; PG8_WAIT_L(0); PG8_MMA(0, 0, At, B0); PG8_BAR; PG8_SCHED;
;             PG8_LDB(B1, 1, 1); PG8_STAGE(PG8_SB(1, 0), b3, voffB);
;             PG8_BAR; PG8_WAIT_L(0); PG8_MMA(0, 1, At, B1); PG8_BAR;
;             PG8_LDA(At, 1, 1); PG8_STAGE(PG8_SA(1, 0), a3, voffA);
;             PG8_BAR; PG8_WAIT_L(0); PG8_MMA(1, 0, At, B0); PG8_BAR; PG8_SCHED;
;             PG8_STAGE(PG8_SB(1, 1), b3 + hstepB, voffB);
;             PG8_WAIT_V(6); PG8_BAR; PG8_MMA(1, 1, At, B1); PG8_BAR;
	ds_read_b128 v[166:169], v148 offset:49152
	ds_read_b128 v[170:173], v148 offset:50176
	ds_read_b128 v[174:177], v148 offset:51200
	ds_read_b128 v[178:181], v148 offset:52224
	ds_read_b128 v[182:185], v148 offset:53248
	ds_read_b128 v[186:189], v148 offset:54272
	ds_read_b128 v[190:193], v148 offset:55296
	ds_read_b128 v[198:201], v148 offset:56320
	global_load_lds_dwordx4 v[194:195], off
	v_lshl_add_u64 v[194:195], v[222:223], 0, s[8:9]
	s_mov_b32 m0, s44
	s_nop 0
	global_load_lds_dwordx4 v[194:195], off
	s_barrier
	s_setprio 1
	s_waitcnt lgkmcnt(7)
	v_mfma_f32_16x16x32_bf16 v[60:63], v[150:153], v[166:169], v[60:63]
	v_mfma_f32_16x16x32_bf16 v[56:59], v[158:161], v[166:169], v[56:59]
	s_waitcnt lgkmcnt(5)
	v_mfma_f32_16x16x32_bf16 v[52:55], v[150:153], v[174:177], v[52:55]
	v_mfma_f32_16x16x32_bf16 v[48:51], v[158:161], v[174:177], v[48:51]
	s_waitcnt lgkmcnt(3)
	v_mfma_f32_16x16x32_bf16 v[36:39], v[150:153], v[182:185], v[36:39]
	v_mfma_f32_16x16x32_bf16 v[32:35], v[158:161], v[182:185], v[32:35]
	s_waitcnt lgkmcnt(1)
	v_mfma_f32_16x16x32_bf16 v[20:23], v[150:153], v[190:193], v[20:23]
	v_mfma_f32_16x16x32_bf16 v[16:19], v[158:161], v[190:193], v[16:19]
	v_mfma_f32_16x16x32_bf16 v[60:63], v[154:157], v[170:173], v[60:63]
	v_mfma_f32_16x16x32_bf16 v[56:59], v[162:165], v[170:173], v[56:59]
	v_mfma_f32_16x16x32_bf16 v[52:55], v[154:157], v[178:181], v[52:55]
	v_mfma_f32_16x16x32_bf16 v[48:51], v[162:165], v[178:181], v[48:51]
	v_mfma_f32_16x16x32_bf16 v[36:39], v[154:157], v[186:189], v[36:39]
	v_mfma_f32_16x16x32_bf16 v[32:35], v[162:165], v[186:189], v[32:35]
	s_waitcnt lgkmcnt(0)
	v_mfma_f32_16x16x32_bf16 v[20:23], v[154:157], v[198:201], v[20:23]
	v_mfma_f32_16x16x32_bf16 v[16:19], v[162:165], v[198:201], v[16:19]
	s_setprio 0
	s_barrier
	s_add_u32 s20, s20, 0x20080
	s_addc_u32 s21, s21, 0
	s_add_i32 s22, s22, s31
	v_lshl_add_u64 v[150:151], s[20:21], 0, v[132:133]
	s_mov_b32 m0, s22
	s_nop 0
	global_load_lds_dwordx4 v[150:151], off
	v_lshl_add_u64 v[150:151], s[20:21], 0, v[128:129]
	s_add_i32 m0, s22, 0x2000
	s_nop 0
	global_load_lds_dwordx4 v[150:151], off
	s_waitcnt vmcnt(6)
	s_barrier
	s_setprio 1
	v_mfma_f32_16x16x32_bf16 v[44:47], v[202:205], v[166:169], v[44:47]
	v_mfma_f32_16x16x32_bf16 v[40:43], v[210:213], v[166:169], v[40:43]
	v_mfma_f32_16x16x32_bf16 v[28:31], v[202:205], v[174:177], v[28:31]
	v_mfma_f32_16x16x32_bf16 v[24:27], v[210:213], v[174:177], v[24:27]
	v_mfma_f32_16x16x32_bf16 v[12:15], v[202:205], v[182:185], v[12:15]
	v_mfma_f32_16x16x32_bf16 v[8:11], v[210:213], v[182:185], v[8:11]
	v_mfma_f32_16x16x32_bf16 v[4:7], v[202:205], v[190:193], v[4:7]
	v_mfma_f32_16x16x32_bf16 v[0:3], v[210:213], v[190:193], v[0:3]
	v_mfma_f32_16x16x32_bf16 v[44:47], v[206:209], v[170:173], v[44:47]
	v_mfma_f32_16x16x32_bf16 v[40:43], v[214:217], v[170:173], v[40:43]
	v_mfma_f32_16x16x32_bf16 v[28:31], v[206:209], v[178:181], v[28:31]
	v_mfma_f32_16x16x32_bf16 v[24:27], v[214:217], v[178:181], v[24:27]
	v_mfma_f32_16x16x32_bf16 v[12:15], v[206:209], v[186:189], v[12:15]
	v_mfma_f32_16x16x32_bf16 v[8:11], v[214:217], v[186:189], v[8:11]
	v_mfma_f32_16x16x32_bf16 v[4:7], v[206:209], v[198:201], v[4:7]
	v_mfma_f32_16x16x32_bf16 v[0:3], v[214:217], v[198:201], v[0:3]
	s_setprio 0
	s_add_i32 s3, s3, 2
	s_add_u32 s55, s55, 0x100
	s_addc_u32 s56, s56, 0
	s_add_u32 s18, s18, 0x100
	s_addc_u32 s19, s19, 0
	s_cmp_gt_u32 s3, 5
	s_barrier
	s_cbranch_scc0 .LBB1_1529
; DI unsigned pack2(float a, float b) { f32x2 v = {a, b}; hwbf16x2 r = __builtin_convertvector(v, hwbf16x2); return __builtin_bit_cast(unsigned, r); }
;     DI const char* a(const Unit& u) const { return (const char*)(A + (size_t)u.pm * BM * lda); }
;     DI const char* a(const Unit& u) const { return (const char*)(A + (size_t)u.pm * BM * 2048 + (u.pn >> 1) * 512); }
;     DI const char* a(const Unit& u) const { return (const char*)((u.pn < 12 ? A1 : A2) + (size_t)u.pm * BM * 512); }
;     DI void operator()(const f32x4 (&acc)[2][2][4][2], const Unit& u, int wr, int wc, int fr, int fq) const {
;         bf16_t* O = O1; int ldc = ldc1, pn = u.pn; if (pn >= split) { O = O2; ldc = ldc2; pn -= split; }
;         const int row0 = u.pm * BM + wr * 64 + fr, col0 = pn * BM + wc * 32 + 8 * fq;
; #pragma unroll
;         for (int ai = 0; ai < 2; ++ai)
; #pragma unroll
;             for (int m = 0; m < 4; ++m) { bf16_t* rowp = O + (size_t)(row0 + ai * HALF + m * 16) * ldc + col0;
; #pragma unroll
;                 for (int bj = 0; bj < 2; ++bj) { const f32x4 v0 = acc[ai][bj][m][0], v1 = acc[ai][bj][m][1];
;                     u32x4 o; o[0] = pack2(v0[0], v0[1]); o[1] = pack2(v0[2], v0[3]); o[2] = pack2(v1[0], v1[1]); o[3] = pack2(v1[2], v1[3]);
;                     *(u32x4*)(rowp + bj * HALF) = o; } }
;     }
; template <class Map, class Epi>
; DI void gemm_phase(LAS unsigned char* lds, const Map& MP, const Epi& E, const int nM, const int nN, const int K, const int lda, const int ldb) {
;     ...
;         { int frr = fr, fqq = fq; asm volatile("" : "+v"(frr), "+v"(fqq)); E(acc, cur, wr, wc, frr, fqq); }
;         if (!has_next) break;
; #pragma unroll
;         for (int a = 0; a < 2; ++a)
; #pragma unroll
;             for (int b = 0; b < 2; ++b)
; #pragma unroll
;                 for (int m = 0; m < 4; ++m)
; #pragma unroll
;                     for (int n = 0; n < 2; ++n) acc[a][b][m][n] = (f32x4){0.f, 0.f, 0.f, 0.f};
;         cur = nxt; cA = nA; cB = nB; ++ui;
	s_cmp_lt_i32 s45, 12
	s_cselect_b32 s3, 0, -12
	s_mov_b32 s13, 0x1e510000
	s_movk_i32 s18, 0xc00
	s_cselect_b32 s13, s13, 0x2a510000
	s_cselect_b32 s20, s18, 0x1000
	s_add_i32 s3, s3, s45
	s_add_u32 s18, s6, s13
	v_mov_b32_e32 v150, v144
	v_mov_b32_e32 v151, v145
	s_addc_u32 s19, s7, 0
	s_lshl_b32 s10, s10, 8
	s_lshl_b32 s3, s3, 8
	s_add_i32 s10, s10, s39
	s_or_b32 s3, s3, s42
	v_add_u32_e32 v154, s10, v150
	v_lshl_add_u32 v150, v151, 3, s3
	v_ashrrev_i32_e32 v151, 31, v150
	v_lshl_add_u64 v[150:151], v[150:151], 1, s[18:19]
	v_mad_i64_i32 v[152:153], s[18:19], s20, v154, 0
	v_cvt_pk_bf16_f32 v108, v108, v109
	v_cvt_pk_bf16_f32 v109, v110, v111
	v_cvt_pk_bf16_f32 v110, v104, v105
	v_add_u32_e32 v104, 16, v154
	v_lshl_add_u64 v[152:153], v[152:153], 1, v[150:151]
	v_cvt_pk_bf16_f32 v111, v106, v107
	v_mad_i64_i32 v[104:105], s[18:19], s20, v104, 0
	v_cvt_pk_bf16_f32 v92, v92, v93
	v_cvt_pk_bf16_f32 v93, v94, v95
	v_cvt_pk_bf16_f32 v94, v88, v89
	v_add_u32_e32 v88, 32, v154
	v_cvt_pk_bf16_f32 v124, v124, v125
	v_cvt_pk_bf16_f32 v125, v126, v127
	v_cvt_pk_bf16_f32 v126, v120, v121
	v_cvt_pk_bf16_f32 v127, v122, v123
	global_store_dwordx4 v[152:153], v[108:111], off offset:256
	v_cvt_pk_bf16_f32 v95, v90, v91
	v_mad_i64_i32 v[88:89], s[18:19], s20, v88, 0
	v_lshl_add_u64 v[108:109], v[104:105], 1, v[150:151]
	v_cvt_pk_bf16_f32 v76, v76, v77
	v_cvt_pk_bf16_f32 v77, v78, v79
	v_cvt_pk_bf16_f32 v78, v72, v73
	v_add_u32_e32 v72, 48, v154
	v_cvt_pk_bf16_f32 v68, v68, v69
	v_cvt_pk_bf16_f32 v69, v70, v71
	v_cvt_pk_bf16_f32 v70, v64, v65
	v_add_u32_e32 v64, 0x80, v154
	global_store_dwordx4 v[152:153], v[124:127], off
	v_cvt_pk_bf16_f32 v104, v116, v117
	v_cvt_pk_bf16_f32 v105, v118, v119
	v_cvt_pk_bf16_f32 v106, v112, v113
	v_cvt_pk_bf16_f32 v107, v114, v115
	global_store_dwordx4 v[108:109], v[92:95], off offset:256
	v_cvt_pk_bf16_f32 v79, v74, v75
	v_mad_i64_i32 v[72:73], s[18:19], s20, v72, 0
	v_lshl_add_u64 v[92:93], v[88:89], 1, v[150:151]
	v_mad_i64_i32 v[64:65], s[18:19], s20, v64, 0
	v_cvt_pk_bf16_f32 v44, v44, v45
	v_cvt_pk_bf16_f32 v45, v46, v47
	v_cvt_pk_bf16_f32 v46, v40, v41
	v_add_u32_e32 v40, 0x90, v154
	global_store_dwordx4 v[108:109], v[104:107], off
	v_cvt_pk_bf16_f32 v88, v100, v101
	v_cvt_pk_bf16_f32 v89, v102, v103
	v_cvt_pk_bf16_f32 v90, v96, v97
	v_cvt_pk_bf16_f32 v91, v98, v99
	global_store_dwordx4 v[92:93], v[76:79], off offset:256
	v_cvt_pk_bf16_f32 v74, v80, v81
	v_cvt_pk_bf16_f32 v75, v82, v83
	v_lshl_add_u64 v[76:77], v[72:73], 1, v[150:151]
	v_cvt_pk_bf16_f32 v72, v84, v85
	v_cvt_pk_bf16_f32 v73, v86, v87
	v_cvt_pk_bf16_f32 v71, v66, v67
	v_lshl_add_u64 v[64:65], v[64:65], 1, v[150:151]
	v_cvt_pk_bf16_f32 v47, v42, v43
	v_mad_i64_i32 v[40:41], s[18:19], s20, v40, 0
	v_cvt_pk_bf16_f32 v28, v28, v29
	v_cvt_pk_bf16_f32 v29, v30, v31
	v_cvt_pk_bf16_f32 v30, v24, v25
	v_add_u32_e32 v24, 0xa0, v154
	global_store_dwordx4 v[92:93], v[88:91], off
	global_store_dwordx4 v[76:77], v[72:75], off
	global_store_dwordx4 v[76:77], v[68:71], off offset:256
	v_cvt_pk_bf16_f32 v60, v60, v61
	v_cvt_pk_bf16_f32 v61, v62, v63
	v_cvt_pk_bf16_f32 v62, v56, v57
	v_cvt_pk_bf16_f32 v63, v58, v59
	global_store_dwordx4 v[64:65], v[44:47], off offset:256
	v_cvt_pk_bf16_f32 v31, v26, v27
	v_mad_i64_i32 v[24:25], s[18:19], s20, v24, 0
	v_lshl_add_u64 v[44:45], v[40:41], 1, v[150:151]
	v_cvt_pk_bf16_f32 v12, v12, v13
	v_cvt_pk_bf16_f32 v13, v14, v15
	v_cvt_pk_bf16_f32 v14, v8, v9
	v_add_u32_e32 v8, 0xb0, v154
	global_store_dwordx4 v[64:65], v[60:63], off
	v_cvt_pk_bf16_f32 v40, v52, v53
	v_cvt_pk_bf16_f32 v41, v54, v55
	v_cvt_pk_bf16_f32 v42, v48, v49
	v_cvt_pk_bf16_f32 v43, v50, v51
	global_store_dwordx4 v[44:45], v[28:31], off offset:256
	v_cvt_pk_bf16_f32 v15, v10, v11
	v_mad_i64_i32 v[8:9], s[18:19], s20, v8, 0
	v_lshl_add_u64 v[28:29], v[24:25], 1, v[150:151]
	global_store_dwordx4 v[44:45], v[40:43], off
	v_cvt_pk_bf16_f32 v24, v36, v37
	v_cvt_pk_bf16_f32 v25, v38, v39
	v_cvt_pk_bf16_f32 v26, v32, v33
	v_cvt_pk_bf16_f32 v27, v34, v35
	global_store_dwordx4 v[28:29], v[12:15], off offset:256
	v_cvt_pk_bf16_f32 v10, v16, v17
	v_cvt_pk_bf16_f32 v11, v18, v19
	v_lshl_add_u64 v[12:13], v[8:9], 1, v[150:151]
	v_cvt_pk_bf16_f32 v8, v20, v21
	v_cvt_pk_bf16_f32 v9, v22, v23
	v_cvt_pk_bf16_f32 v4, v4, v5
	v_cvt_pk_bf16_f32 v5, v6, v7
	v_cvt_pk_bf16_f32 v6, v0, v1
	v_cvt_pk_bf16_f32 v7, v2, v3
	s_and_b64 vcc, exec, s[40:41]
	s_mov_b32 s45, s49
	s_mov_b32 s10, s12
	s_mov_b64 s[18:19], s[16:17]
	s_mov_b64 s[20:21], s[14:15]
	global_store_dwordx4 v[28:29], v[24:27], off
	global_store_dwordx4 v[12:13], v[8:11], off
	global_store_dwordx4 v[12:13], v[4:7], off offset:256
	s_cbranch_vccz .LBB1_1526
	s_waitcnt vmcnt(0)
	s_cmpk_gt_u32 s4, 0xff
	s_cbranch_scc1 .LBB1_1533
	s_barrier

; DI unsigned pack2(float a, float b) { f32x2 v = {a, b}; hwbf16x2 r = __builtin_convertvector(v, hwbf16x2); return __builtin_bit_cast(unsigned, r); }
; DI void mla_prep2_phase(const Params& p) {
;     ...
;     for (int task0 = bid * 8 + wid; task0 < T * 4; task0 += 4 * tstride) {
;         u32x4 wq4[4], wk4[4]; u32x2 wp4[4], kp4[4];
; #pragma unroll
;         for (int u = 0; u < 4; ++u) {
;             const int task = task0 + u * tstride;
;             if (task < T * 4) {
;                 const int t = task >> 2, hh = (task & 3) * 4 + hsub;
;                 const bf16_t* qrow = Q32 + (size_t)t * 3072 + hh * 192; const bf16_t* kvrow = KV32 + (size_t)t * 4096 + hh * 256;
;                 wq4[u] = *(const u32x4*)(qrow + 8 * j); wk4[u] = *(const u32x4*)(kvrow + 8 * j);
;                 wp4[u] = *(const u32x2*)(qrow + 128 + 4 * j); kp4[u] = *(const u32x2*)(KPE + (size_t)t * 64 + 4 * j);
;             }
;         }
; #pragma unroll
;         for (int u = 0; u < 4; ++u) {
;             const int task = task0 + u * tstride;
;             if (task < T * 4) {
;                 const int t = task >> 2, hh = (task & 3) * 4 + hsub, b = t / S, s = t - b * S;
;                 const size_t ob = ((size_t)(b * 16 + hh) * S + s) * 192;
;                 const u32x4 wq = wq4[u], wk = wk4[u]; const u32x2 wp = wp4[u], kp = kp4[u];
;                 float q[8], k[8], x[4];
; #pragma unroll
;                 for (int e = 0; e < 4; ++e) { q[2 * e] = bflo(wq[e]); q[2 * e + 1] = bfhi(wq[e]); k[2 * e] = bflo(wk[e]); k[2 * e + 1] = bfhi(wk[e]); }
;                 x[0] = bflo(wp[0]); x[1] = bfhi(wp[0]); x[2] = bflo(wp[1]); x[3] = bfhi(wp[1]);
;                 float sq = 0.f, sk = 0.f, sx = 0.f;
; #pragma unroll
;                 for (int e = 0; e < 8; ++e) { sq += q[e] * q[e]; sk += k[e] * k[e]; }
; #pragma unroll
;                 for (int e = 0; e < 4; ++e) sx += x[e] * x[e];
;                 sq = sum16(sq); sk = sum16(sk); sx = sum16(sx);
;                 const float fq = rsqrtf(sq * (1.0f / 128.f) + EPS) * qsc, fk = rsqrtf(sk * (1.0f / 128.f) + EPS), fx = rsqrtf(sx * (1.0f / 64.f) + EPS);
;                 u32x4 oq, ok;
; #pragma unroll
;                 for (int e = 0; e < 4; ++e) { oq[e] = pack2(q[2 * e] * fq * gqn[2 * e], q[2 * e + 1] * fq * gqn[2 * e + 1]); ok[e] = pack2(k[2 * e] * fk * gkn[2 * e], k[2 * e + 1] * fk * gkn[2 * e + 1]); }
.LBB1_1601:
	v_and_b32_e32 v96, 12, v95
	v_or_b32_e32 v46, v96, v93
	v_mul_u32_u24_e32 v44, 0xc0, v46
	v_lshlrev_b32_e32 v44, 1, v44
	v_mov_b32_e32 v45, v53
	v_ashrrev_i32_e32 v86, 2, v92
	v_lshl_add_u64 v[90:91], s[12:13], 0, v[44:45]
	v_lshlrev_b32_e32 v44, 9, v46
	v_ashrrev_i32_e32 v87, 31, v86
	v_lshl_add_u64 v[88:89], v[54:55], 0, v[44:45]
	v_mad_i64_i32 v[76:77], s[28:29], v86, s31, v[90:91]
	v_lshlrev_b64 v[44:45], 13, v[86:87]
	v_lshl_add_u64 v[46:47], v[76:77], 0, v[62:63]
	v_lshl_add_u64 v[44:45], v[88:89], 0, v[44:45]
	v_lshl_add_u64 v[76:77], v[76:77], 0, v[52:53]
	global_load_dwordx4 v[48:51], v[46:47], off
	s_nop 0
	global_load_dwordx4 v[44:47], v[44:45], off
	v_add_u32_e32 v97, s33, v92
	global_load_dwordx2 v[84:85], v[76:77], off offset:256
	v_lshlrev_b64 v[76:77], 7, v[86:87]
	v_lshl_add_u64 v[76:77], v[56:57], 0, v[76:77]
	global_load_dwordx2 v[82:83], v[76:77], off
	v_cmp_gt_i32_e64 s[44:45], s4, v97
	v_ashrrev_i32_e32 v80, 2, v97
	s_and_saveexec_b64 s[28:29], s[44:45]
	s_cbranch_execz .LBB1_1603
	v_ashrrev_i32_e32 v81, 31, v80
	v_mad_i64_i32 v[64:65], s[36:37], v80, s31, v[90:91]
	v_lshlrev_b64 v[28:29], 13, v[80:81]
	v_mov_b32_e32 v59, v53
	v_lshlrev_b64 v[70:71], 7, v[80:81]
	v_lshl_add_u64 v[30:31], v[64:65], 0, v[58:59]
	v_lshl_add_u64 v[40:41], v[88:89], 0, v[28:29]
	v_lshl_add_u64 v[64:65], v[64:65], 0, v[52:53]
	v_lshl_add_u64 v[70:71], v[56:57], 0, v[70:71]
	global_load_dwordx4 v[28:31], v[30:31], off
	s_nop 0
	global_load_dwordx4 v[40:43], v[40:41], off
	s_nop 0
	global_load_dwordx2 v[64:65], v[64:65], off offset:256
	s_nop 0
	global_load_dwordx2 v[70:71], v[70:71], off
.LBB1_1603:
	s_or_b64 exec, exec, s[28:29]
	v_add_u32_e32 v81, s27, v92
	v_cmp_gt_i32_e64 s[42:43], s4, v81
	v_ashrrev_i32_e32 v78, 2, v81
	s_and_saveexec_b64 s[28:29], s[42:43]
	s_cbranch_execz .LBB1_1605
	v_ashrrev_i32_e32 v79, 31, v78
	v_mad_i64_i32 v[68:69], s[36:37], v78, s31, v[90:91]
	v_lshlrev_b64 v[24:25], 13, v[78:79]
	v_mov_b32_e32 v59, v53
	v_lshlrev_b64 v[74:75], 7, v[78:79]
	v_lshl_add_u64 v[26:27], v[68:69], 0, v[58:59]
	v_lshl_add_u64 v[36:37], v[88:89], 0, v[24:25]
	v_lshl_add_u64 v[68:69], v[68:69], 0, v[52:53]
	v_lshl_add_u64 v[74:75], v[56:57], 0, v[74:75]
	global_load_dwordx4 v[24:27], v[26:27], off
	s_nop 0
	global_load_dwordx4 v[36:39], v[36:37], off
	s_nop 0
	global_load_dwordx2 v[68:69], v[68:69], off offset:256
	s_nop 0
	global_load_dwordx2 v[74:75], v[74:75], off
.LBB1_1605:
	s_or_b64 exec, exec, s[28:29]
	s_mul_i32 s3, s50, 24
	v_add_u32_e32 v79, s3, v92
	v_cmp_gt_i32_e64 s[40:41], s4, v79
	v_ashrrev_i32_e32 v76, 2, v79
	s_and_saveexec_b64 s[28:29], s[40:41]
	s_cbranch_execz .LBB1_1607
	v_ashrrev_i32_e32 v77, 31, v76
	v_mad_i64_i32 v[66:67], s[36:37], v76, s31, v[90:91]
	v_lshlrev_b64 v[20:21], 13, v[76:77]
	v_mov_b32_e32 v59, v53
	v_lshlrev_b64 v[72:73], 7, v[76:77]
	v_lshl_add_u64 v[22:23], v[66:67], 0, v[58:59]
	v_lshl_add_u64 v[32:33], v[88:89], 0, v[20:21]
	v_lshl_add_u64 v[66:67], v[66:67], 0, v[52:53]
	v_lshl_add_u64 v[72:73], v[56:57], 0, v[72:73]
	global_load_dwordx4 v[20:23], v[22:23], off
	s_nop 0
	global_load_dwordx4 v[32:35], v[32:33], off
	s_nop 0
	global_load_dwordx2 v[66:67], v[66:67], off offset:256
	s_nop 0
	global_load_dwordx2 v[72:73], v[72:73], off
.LBB1_1607:
	s_or_b64 exec, exec, s[28:29]
	s_waitcnt vmcnt(0) lgkmcnt(0)
	v_lshlrev_b32_e32 v106, 16, v48
	v_and_b32_e32 v107, 0xffff0000, v48
	v_lshlrev_b32_e32 v102, 16, v49
	v_and_b32_e32 v103, 0xffff0000, v49
	v_pk_mul_f32 v[48:49], v[106:107], v[106:107]
	v_pk_mul_f32 v[104:105], v[102:103], v[102:103]
	v_add_f32_e32 v48, v48, v49
	v_lshlrev_b32_e32 v100, 16, v50
	v_and_b32_e32 v101, 0xffff0000, v50
	v_add_f32_e32 v48, v104, v48
	v_lshlrev_b32_e32 v90, 16, v51
	v_and_b32_e32 v91, 0xffff0000, v51
	v_pk_mul_f32 v[50:51], v[100:101], v[100:101]
	v_add_f32_e32 v48, v105, v48
	v_add_f32_e32 v48, v50, v48
	v_pk_mul_f32 v[98:99], v[90:91], v[90:91]
	v_add_f32_e32 v48, v51, v48
	v_add_f32_e32 v48, v98, v48
	v_add_f32_e32 v48, v99, v48
	v_lshrrev_b32_e32 v59, 20, v87
	v_add_u32_e32 v59, v86, v59
	v_add_f32_dpp v48, v48, v48 row_ror:8 row_mask:0xf bank_mask:0xf bound_ctrl:1
	v_ashrrev_i32_e32 v77, 12, v59
	v_and_b32_e32 v59, 0xfffff000, v59
	v_add_f32_dpp v48, v48, v48 row_ror:4 row_mask:0xf bank_mask:0xf bound_ctrl:1
	v_sub_u32_e32 v86, v86, v59
	v_lshlrev_b32_e32 v59, 4, v77
	v_add_f32_dpp v48, v48, v48 row_ror:2 row_mask:0xf bank_mask:0xf bound_ctrl:1
	v_or3_b32 v88, v59, v96, v93
	v_ashrrev_i32_e32 v89, 31, v88
	v_add_f32_dpp v48, v48, v48 row_ror:1 row_mask:0xf bank_mask:0xf bound_ctrl:1
	v_fmamk_f32 v48, v48, 0x3c000000, v60
	v_mul_f32_e32 v49, 0x4b800000, v48
	v_cmp_gt_f32_e64 s[46:47], s34, v48
	v_ashrrev_i32_e32 v87, 31, v86
	v_and_b32_e32 v105, 0xffff0000, v44
	v_cndmask_b32_e64 v48, v48, v49, s[46:47]
	v_rsq_f32_e32 v50, v48
	v_lshlrev_b64 v[48:49], 12, v[88:89]
	v_lshl_add_u64 v[88:89], v[48:49], 0, v[86:87]
	v_lshlrev_b32_e32 v104, 16, v44
	v_mul_f32_e32 v48, 0x45800000, v50
	v_cndmask_b32_e64 v48, v50, v48, s[46:47]
	v_mul_f32_e32 v98, 0x3dd53b94, v48
	v_pk_mul_f32 v[48:49], v[98:99], v[106:107] op_sel_hi:[0,1]
	v_pk_mul_f32 v[50:51], v[98:99], v[102:103] op_sel_hi:[0,1]
	v_pk_mul_f32 v[48:49], v[4:5], v[48:49]
	v_pk_mul_f32 v[50:51], v[6:7], v[50:51]
	v_cvt_pk_bf16_f32 v48, v48, v49
	v_cvt_pk_bf16_f32 v49, v50, v51
	v_pk_mul_f32 v[50:51], v[98:99], v[100:101] op_sel_hi:[0,1]
	v_pk_mul_f32 v[90:91], v[98:99], v[90:91] op_sel_hi:[0,1]
	v_pk_mul_f32 v[50:51], v[0:1], v[50:51]
	v_pk_mul_f32 v[90:91], v[2:3], v[90:91]
; DI unsigned pack2(float a, float b) { f32x2 v = {a, b}; hwbf16x2 r = __builtin_convertvector(v, hwbf16x2); return __builtin_bit_cast(unsigned, r); }
; template <int CTRL> DI float dppf(float v) { return __builtin_bit_cast(float, __builtin_amdgcn_update_dpp(0, __builtin_bit_cast(int, v), CTRL, 0xf, 0xf, false)); }
; DI void mla_prep2_phase(const Params& p) {
;     ...
;                 const float fq = rsqrtf(sq * (1.0f / 128.f) + EPS) * qsc, fk = rsqrtf(sk * (1.0f / 128.f) + EPS), fx = rsqrtf(sx * (1.0f / 64.f) + EPS);
;                 u32x4 oq, ok;
; #pragma unroll
;                 for (int e = 0; e < 4; ++e) { oq[e] = pack2(q[2 * e] * fq * gqn[2 * e], q[2 * e + 1] * fq * gqn[2 * e + 1]); ok[e] = pack2(k[2 * e] * fk * gkn[2 * e], k[2 * e + 1] * fk * gkn[2 * e + 1]); }
;                 *(u32x4*)(QN + ob + 8 * j) = oq; *(u32x4*)(KC + ob + 8 * j) = ok;
;                 float ro[4];
; #pragma unroll
;                 for (int e = 0; e < 4; ++e) { const float xn = x[e] * fx * gqr[e], pr = dppf<0x128>(xn);
;                     const int fi = (4 * j + e) & 31; const float cc = ct[s * 32 + fi], sn = st[s * 32 + fi];
;                     ro[e] = (j < 8 ? xn * cc - pr * sn : xn * cc + pr * sn) * qsc; }
;                 u32x2 op; op[0] = pack2(ro[0], ro[1]); op[1] = pack2(ro[2], ro[3]);
;                 *(u32x2*)(QN + ob + 128 + 4 * j) = op;
;                 *(u32x2*)(KC + ob + 128 + 4 * j) = kp;
	v_mov_b64_e32 v[106:107], s[18:19]
	v_cvt_pk_bf16_f32 v50, v50, v51
	v_cvt_pk_bf16_f32 v51, v90, v91
	v_lshlrev_b32_e32 v90, 16, v47
	v_and_b32_e32 v91, 0xffff0000, v47
	v_lshlrev_b32_e32 v100, 16, v46
	v_and_b32_e32 v47, 0xffff0000, v46
	v_and_b32_e32 v46, s0, v46
	v_mul_f32_e32 v44, v105, v105
	v_mad_u64_u32 v[106:107], s[28:29], v88, s35, v[106:107]
	v_mov_b32_e32 v101, v47
	v_pk_mul_f32 v[46:47], v[46:47], v[46:47]
	v_lshlrev_b32_e32 v102, 16, v45
	v_and_b32_e32 v103, 0xffff0000, v45
	v_pk_fma_f32 v[44:45], v[104:105], v[104:105], v[44:45] op_sel_hi:[1,1,0]
	v_mad_i32_i24 v107, v89, s35, v107
	v_mov_b32_e32 v59, v53
	v_pk_fma_f32 v[44:45], v[102:103], v[102:103], v[44:45]
	v_mul_f32_e32 v46, v103, v103
	v_lshl_add_u64 v[108:109], v[106:107], 0, v[58:59]
	v_pk_add_f32 v[44:45], v[46:47], v[44:45] op_sel_hi:[0,1]
	global_store_dwordx4 v[108:109], v[48:51], off
	v_lshlrev_b32_e32 v110, 16, v84
	v_and_b32_e32 v111, 0xffff0000, v84
	v_mov_b64_e32 v[48:49], s[14:15]
	v_pk_fma_f32 v[44:45], v[100:101], v[100:101], v[44:45]
	v_mad_u64_u32 v[108:109], s[28:29], v88, s35, v[48:49]
	v_lshl_or_b32 v50, v86, 5, v94
	v_lshlrev_b32_e32 v86, 16, v85
	v_and_b32_e32 v87, 0xffff0000, v85
	v_pk_mul_f32 v[84:85], v[110:111], v[110:111]
	v_pk_mul_f32 v[98:99], v[90:91], v[90:91]
	v_mad_i32_i24 v109, v89, s35, v109
	v_pk_mul_f32 v[88:89], v[86:87], v[86:87]
	v_mov_b32_e32 v46, v84
	v_pk_mov_b32 v[44:45], v[84:85], v[44:45] op_sel:[1,0]
	v_ashrrev_i32_e32 v51, 31, v50
	v_pk_add_f32 v[44:45], v[46:47], v[44:45]
	v_mov_b32_e32 v46, v88
	v_mov_b32_e32 v47, v98
	v_pk_add_f32 v[44:45], v[46:47], v[44:45]
	v_mov_b32_e32 v98, v89
	v_pk_add_f32 v[44:45], v[98:99], v[44:45]
	v_mov_b32_e32 v47, v53
	v_mov_b32_e32 v46, v53
	v_lshl_add_u64 v[48:49], v[108:109], 0, v[58:59]
	v_mov_b32_dpp v47, v45 row_ror:8 row_mask:0xf bank_mask:0xf
	v_mov_b32_dpp v46, v44 row_ror:8 row_mask:0xf bank_mask:0xf
	v_pk_add_f32 v[44:45], v[44:45], v[46:47]
	v_mov_b32_e32 v47, v53
	v_mov_b32_e32 v46, v53
	v_lshlrev_b64 v[50:51], 2, v[50:51]
	v_mov_b32_dpp v47, v45 row_ror:4 row_mask:0xf bank_mask:0xf
	v_mov_b32_dpp v46, v44 row_ror:4 row_mask:0xf bank_mask:0xf
	v_pk_add_f32 v[44:45], v[44:45], v[46:47]
	v_mov_b32_e32 v47, v53
	v_mov_b32_e32 v46, v53
	v_lshl_add_u64 v[88:89], s[20:21], 0, v[50:51]
	v_mov_b32_dpp v47, v45 row_ror:2 row_mask:0xf bank_mask:0xf
	v_mov_b32_dpp v46, v44 row_ror:2 row_mask:0xf bank_mask:0xf
	v_pk_add_f32 v[44:45], v[44:45], v[46:47]
	v_mov_b32_e32 v47, v53
	v_mov_b32_e32 v46, v53
	s_nop 0
	v_mov_b32_dpp v47, v45 row_ror:1 row_mask:0xf bank_mask:0xf
	v_mov_b32_dpp v46, v44 row_ror:1 row_mask:0xf bank_mask:0xf
	v_pk_add_f32 v[44:45], v[44:45], v[46:47]
	s_nop 0
	v_pk_fma_f32 v[84:85], v[44:45], s[24:25], v[60:61] op_sel_hi:[1,1,0]
	s_nop 0
	v_mul_f32_e32 v44, 0x4b800000, v85
	v_cmp_gt_f32_e64 s[46:47], s34, v85
	v_mul_f32_e32 v77, 0x4b800000, v84
	s_nop 0
	v_cndmask_b32_e64 v44, v85, v44, s[46:47]
	v_rsq_f32_e32 v44, v44
	s_nop 0
	v_mul_f32_e32 v45, 0x45800000, v44
	v_cndmask_b32_e64 v98, v44, v45, s[46:47]
	v_pk_mul_f32 v[44:45], v[98:99], v[104:105] op_sel_hi:[0,1]
	v_pk_mul_f32 v[46:47], v[98:99], v[102:103] op_sel_hi:[0,1]
	v_pk_mul_f32 v[44:45], v[12:13], v[44:45]
	v_pk_mul_f32 v[46:47], v[14:15], v[46:47]
	v_cvt_pk_bf16_f32 v44, v44, v45
	v_cvt_pk_bf16_f32 v45, v46, v47
	v_pk_mul_f32 v[46:47], v[98:99], v[100:101] op_sel_hi:[0,1]
	v_pk_mul_f32 v[90:91], v[98:99], v[90:91] op_sel_hi:[0,1]
	v_pk_mul_f32 v[46:47], v[8:9], v[46:47]
	v_pk_mul_f32 v[90:91], v[10:11], v[90:91]
	v_cvt_pk_bf16_f32 v46, v46, v47
	v_cvt_pk_bf16_f32 v47, v90, v91
	global_store_dwordx4 v[48:49], v[44:47], off
	global_load_dwordx4 v[44:47], v[88:89], off
	v_lshl_add_u64 v[48:49], s[16:17], 0, v[50:51]
	global_load_dwordx4 v[48:51], v[48:49], off
	v_cmp_gt_f32_e64 s[46:47], s34, v84
	v_mov_b32_e32 v90, v53
	v_mov_b32_e32 v91, v53
	v_cndmask_b32_e64 v77, v84, v77, s[46:47]
	v_rsq_f32_e32 v77, v77
	s_nop 0
	v_mul_f32_e32 v84, 0x45800000, v77
	v_cndmask_b32_e64 v84, v77, v84, s[46:47]
	v_pk_mul_f32 v[88:89], v[84:85], v[110:111] op_sel_hi:[0,1]
	v_pk_mul_f32 v[88:89], v[16:17], v[88:89]
	s_nop 1
	v_mov_b32_dpp v90, v88 row_ror:8 row_mask:0xf bank_mask:0xf
	v_mov_b32_dpp v91, v89 row_ror:8 row_mask:0xf bank_mask:0xf
	s_waitcnt vmcnt(0) lgkmcnt(0)
	v_pk_mul_f32 v[44:45], v[44:45], v[90:91]
	s_nop 0
	v_cndmask_b32_e64 v45, v45, -v45, vcc
	v_cndmask_b32_e64 v44, v44, -v44, vcc
	v_pk_fma_f32 v[44:45], v[48:49], v[88:89], v[44:45]
	v_pk_mul_f32 v[48:49], v[84:85], v[86:87] op_sel_hi:[0,1]
	v_pk_mul_f32 v[48:49], v[18:19], v[48:49]
	v_mov_b32_e32 v84, v53
	v_mov_b32_e32 v85, v53
	v_pk_mul_f32 v[44:45], v[44:45], s[26:27] op_sel_hi:[1,0]
	v_mov_b32_dpp v84, v48 row_ror:8 row_mask:0xf bank_mask:0xf
	v_mov_b32_dpp v85, v49 row_ror:8 row_mask:0xf bank_mask:0xf
	v_pk_mul_f32 v[46:47], v[46:47], v[84:85]
	v_cvt_pk_bf16_f32 v44, v44, v45
	v_cndmask_b32_e64 v47, v47, -v47, vcc
	v_cndmask_b32_e64 v46, v46, -v46, vcc
	v_pk_fma_f32 v[46:47], v[50:51], v[48:49], v[46:47]
	s_nop 0
	v_pk_mul_f32 v[46:47], v[46:47], s[26:27] op_sel_hi:[1,0]
	s_nop 0
	v_cvt_pk_bf16_f32 v45, v46, v47
	v_lshl_add_u64 v[46:47], v[106:107], 0, v[52:53]
	global_store_dwordx2 v[46:47], v[44:45], off offset:256
	v_lshl_add_u64 v[44:45], v[108:109], 0, v[52:53]
	global_store_dwordx2 v[44:45], v[82:83], off offset:256
	s_and_saveexec_b64 s[28:29], s[44:45]
	s_cbranch_execnz .LBB1_1610
	s_or_b64 exec, exec, s[28:29]
	s_and_saveexec_b64 s[28:29], s[42:43]
	s_cbranch_execnz .LBB1_1611

; DI unsigned pack2(float a, float b) { f32x2 v = {a, b}; hwbf16x2 r = __builtin_convertvector(v, hwbf16x2); return __builtin_bit_cast(unsigned, r); }
; DI float bflo(unsigned w) { return __uint_as_float(w << 16); }
; DI float bfhi(unsigned w) { return __uint_as_float(w & 0xffff0000u); }
; DI void mla_prep2_phase(const Params& p) {
;     ...
;         for (int u = 0; u < 4; ++u) {
;             const int task = task0 + u * tstride;
;             if (task < T * 4) {
;                 const int t = task >> 2, hh = (task & 3) * 4 + hsub, b = t / S, s = t - b * S;
;                 const size_t ob = ((size_t)(b * 16 + hh) * S + s) * 192;
;                 const u32x4 wq = wq4[u], wk = wk4[u]; const u32x2 wp = wp4[u], kp = kp4[u];
;                 float q[8], k[8], x[4];
; #pragma unroll
;                 for (int e = 0; e < 4; ++e) { q[2 * e] = bflo(wq[e]); q[2 * e + 1] = bfhi(wq[e]); k[2 * e] = bflo(wk[e]); k[2 * e + 1] = bfhi(wk[e]); }
;                 x[0] = bflo(wp[0]); x[1] = bfhi(wp[0]); x[2] = bflo(wp[1]); x[3] = bfhi(wp[1]);
;                 float sq = 0.f, sk = 0.f, sx = 0.f;
; #pragma unroll
;                 for (int e = 0; e < 8; ++e) { sq += q[e] * q[e]; sk += k[e] * k[e]; }
; #pragma unroll
;                 for (int e = 0; e < 4; ++e) sx += x[e] * x[e];
;                 sq = sum16(sq); sk = sum16(sk); sx = sum16(sx);
;                 const float fq = rsqrtf(sq * (1.0f / 128.f) + EPS) * qsc, fk = rsqrtf(sk * (1.0f / 128.f) + EPS), fx = rsqrtf(sx * (1.0f / 64.f) + EPS);
;                 u32x4 oq, ok;
; #pragma unroll
;                 for (int e = 0; e < 4; ++e) { oq[e] = pack2(q[2 * e] * fq * gqn[2 * e], q[2 * e + 1] * fq * gqn[2 * e + 1]); ok[e] = pack2(k[2 * e] * fk * gkn[2 * e], k[2 * e + 1] * fk * gkn[2 * e + 1]); }
;                 *(u32x4*)(QN + ob + 8 * j) = oq; *(u32x4*)(KC + ob + 8 * j) = ok;
;                 float ro[4];
; #pragma unroll
;                 for (int e = 0; e < 4; ++e) { const float xn = x[e] * fx * gqr[e], pr = dppf<0x128>(xn);
;                     const int fi = (4 * j + e) & 31; const float cc = ct[s * 32 + fi], sn = st[s * 32 + fi];
;                     ro[e] = (j < 8 ? xn * cc - pr * sn : xn * cc + pr * sn) * qsc; }
;                 u32x2 op; op[0] = pack2(ro[0], ro[1]); op[1] = pack2(ro[2], ro[3]);
;                 *(u32x2*)(QN + ob + 128 + 4 * j) = op;
;                 *(u32x2*)(KC + ob + 128 + 4 * j) = kp;
.LBB1_1610:
	v_lshlrev_b32_e32 v90, 16, v28
	v_and_b32_e32 v91, 0xffff0000, v28
	v_lshlrev_b32_e32 v86, 16, v29
	v_and_b32_e32 v87, 0xffff0000, v29
	v_pk_mul_f32 v[98:99], v[90:91], v[90:91]
	v_pk_mul_f32 v[88:89], v[86:87], v[86:87]
	v_add_f32_e32 v49, v98, v99
	v_lshlrev_b32_e32 v82, 16, v30
	v_and_b32_e32 v83, 0xffff0000, v30
	v_add_f32_e32 v49, v88, v49
	v_pk_mul_f32 v[84:85], v[82:83], v[82:83]
	v_add_f32_e32 v49, v89, v49
	v_lshlrev_b32_e32 v50, 16, v31
	v_and_b32_e32 v51, 0xffff0000, v31
	v_add_f32_e32 v49, v84, v49
	v_pk_mul_f32 v[46:47], v[50:51], v[50:51]
	v_add_f32_e32 v49, v85, v49
	v_add_f32_e32 v46, v46, v49
	v_add_f32_e32 v46, v47, v46
	v_ashrrev_i32_e32 v44, 31, v97
	v_lshrrev_b32_e32 v44, 20, v44
	v_add_f32_dpp v46, v46, v46 row_ror:8 row_mask:0xf bank_mask:0xf bound_ctrl:1
	v_add_u32_e32 v44, v80, v44
	v_ashrrev_i32_e32 v45, 12, v44
	v_add_f32_dpp v46, v46, v46 row_ror:4 row_mask:0xf bank_mask:0xf bound_ctrl:1
	v_and_b32_e32 v44, 0xfffff000, v44
	v_sub_u32_e32 v48, v80, v44
	v_add_f32_dpp v46, v46, v46 row_ror:2 row_mask:0xf bank_mask:0xf bound_ctrl:1
	v_lshlrev_b32_e32 v44, 4, v45
	v_or3_b32 v44, v44, v96, v93
	v_add_f32_dpp v46, v46, v46 row_ror:1 row_mask:0xf bank_mask:0xf bound_ctrl:1
	v_fmamk_f32 v46, v46, 0x3c000000, v60
	v_mul_f32_e32 v47, 0x4b800000, v46
	v_cmp_gt_f32_e64 s[44:45], s34, v46
	v_ashrrev_i32_e32 v45, 31, v44
	v_lshlrev_b64 v[44:45], 12, v[44:45]
	v_cndmask_b32_e64 v46, v46, v47, s[44:45]
	v_rsq_f32_e32 v46, v46
	v_ashrrev_i32_e32 v49, 31, v48
	v_lshl_add_u64 v[84:85], v[44:45], 0, v[48:49]
	v_and_b32_e32 v99, 0xffff0000, v40
	v_mul_f32_e32 v44, 0x45800000, v46
	v_cndmask_b32_e64 v44, v46, v44, s[44:45]
	v_mul_f32_e32 v80, 0x3dd53b94, v44
	v_pk_mul_f32 v[44:45], v[80:81], v[90:91] op_sel_hi:[0,1]
	v_pk_mul_f32 v[46:47], v[80:81], v[86:87] op_sel_hi:[0,1]
	v_pk_mul_f32 v[44:45], v[4:5], v[44:45]
	v_pk_mul_f32 v[46:47], v[6:7], v[46:47]
	v_mov_b64_e32 v[102:103], s[18:19]
	v_cvt_pk_bf16_f32 v44, v44, v45
	v_cvt_pk_bf16_f32 v45, v46, v47
	v_pk_mul_f32 v[46:47], v[80:81], v[82:83] op_sel_hi:[0,1]
	v_pk_mul_f32 v[50:51], v[80:81], v[50:51] op_sel_hi:[0,1]
	v_lshlrev_b32_e32 v98, 16, v40
	v_mul_f32_e32 v80, v99, v99
	v_mad_u64_u32 v[102:103], s[36:37], v84, s35, v[102:103]
	v_pk_mul_f32 v[46:47], v[0:1], v[46:47]
	v_pk_mul_f32 v[50:51], v[2:3], v[50:51]
	v_lshlrev_b32_e32 v90, 16, v41
	v_and_b32_e32 v91, 0xffff0000, v41
	v_pk_fma_f32 v[100:101], v[98:99], v[98:99], v[80:81] op_sel_hi:[1,1,0]
	v_mad_i32_i24 v103, v85, s35, v103
	v_cvt_pk_bf16_f32 v46, v46, v47
	v_cvt_pk_bf16_f32 v47, v50, v51
	v_and_b32_e32 v89, 0xffff0000, v42
	v_pk_fma_f32 v[100:101], v[90:91], v[90:91], v[100:101]
	v_mul_f32_e32 v80, v91, v91
	v_lshl_add_u64 v[104:105], v[102:103], 0, v[58:59]
	v_lshlrev_b32_e32 v86, 16, v42
	v_and_b32_e32 v88, s0, v42
	v_mov_b32_e32 v87, v89
	v_pk_add_f32 v[100:101], v[80:81], v[100:101] op_sel_hi:[0,1]
	global_store_dwordx4 v[104:105], v[44:47], off
	v_lshlrev_b32_e32 v108, 16, v64
	v_and_b32_e32 v109, 0xffff0000, v64
	v_mov_b64_e32 v[44:45], s[14:15]
	v_lshlrev_b32_e32 v50, 16, v43
	v_and_b32_e32 v51, 0xffff0000, v43
	v_pk_mul_f32 v[88:89], v[88:89], v[88:89]
	v_pk_fma_f32 v[100:101], v[86:87], v[86:87], v[100:101]
	v_mad_u64_u32 v[104:105], s[36:37], v84, s35, v[44:45]
	v_lshl_or_b32 v44, v48, 5, v94
	v_lshlrev_b32_e32 v106, 16, v65
	v_and_b32_e32 v107, 0xffff0000, v65
	v_pk_mul_f32 v[48:49], v[108:109], v[108:109]
	v_pk_mul_f32 v[82:83], v[50:51], v[50:51]
	v_pk_mul_f32 v[46:47], v[106:107], v[106:107]
	v_mov_b32_e32 v88, v48
	v_pk_mov_b32 v[48:49], v[48:49], v[100:101] op_sel:[1,0]
	v_mad_i32_i24 v105, v85, s35, v105
	v_pk_add_f32 v[48:49], v[88:89], v[48:49]
	v_mov_b32_e32 v88, v46
	v_mov_b32_e32 v89, v82
	v_pk_add_f32 v[48:49], v[88:89], v[48:49]
	v_mov_b32_e32 v82, v47
	v_pk_add_f32 v[46:47], v[82:83], v[48:49]
	v_mov_b32_e32 v49, v53
	v_mov_b32_e32 v48, v53
	v_lshl_add_u64 v[84:85], v[104:105], 0, v[58:59]
	v_mov_b32_dpp v49, v47 row_ror:8 row_mask:0xf bank_mask:0xf
	v_mov_b32_dpp v48, v46 row_ror:8 row_mask:0xf bank_mask:0xf
	v_pk_add_f32 v[46:47], v[46:47], v[48:49]
	v_mov_b32_e32 v49, v53
	v_mov_b32_e32 v48, v53
	s_nop 0
	v_mov_b32_dpp v49, v47 row_ror:4 row_mask:0xf bank_mask:0xf
	v_mov_b32_dpp v48, v46 row_ror:4 row_mask:0xf bank_mask:0xf
	v_pk_add_f32 v[46:47], v[46:47], v[48:49]
	v_mov_b32_e32 v49, v53
	v_mov_b32_e32 v48, v53
	s_nop 0
	v_mov_b32_dpp v49, v47 row_ror:2 row_mask:0xf bank_mask:0xf
	v_mov_b32_dpp v48, v46 row_ror:2 row_mask:0xf bank_mask:0xf
	v_pk_add_f32 v[46:47], v[46:47], v[48:49]
	v_mov_b32_e32 v49, v53
	v_mov_b32_e32 v48, v53
	s_nop 0
	v_mov_b32_dpp v49, v47 row_ror:1 row_mask:0xf bank_mask:0xf
	v_mov_b32_dpp v48, v46 row_ror:1 row_mask:0xf bank_mask:0xf
	v_pk_add_f32 v[46:47], v[46:47], v[48:49]
	s_nop 0
	v_pk_fma_f32 v[82:83], v[46:47], s[24:25], v[60:61] op_sel_hi:[1,1,0]
	s_nop 0
	v_mul_f32_e32 v45, 0x4b800000, v83
	v_cmp_gt_f32_e64 s[44:45], s34, v83
	v_mul_f32_e32 v59, 0x4b800000, v82
	s_nop 0
	v_cndmask_b32_e64 v45, v83, v45, s[44:45]
	v_rsq_f32_e32 v46, v45
	v_ashrrev_i32_e32 v45, 31, v44
	v_lshlrev_b64 v[48:49], 2, v[44:45]
	v_lshl_add_u64 v[88:89], s[20:21], 0, v[48:49]
	v_mul_f32_e32 v44, 0x45800000, v46
	v_cndmask_b32_e64 v80, v46, v44, s[44:45]
	v_pk_mul_f32 v[44:45], v[80:81], v[98:99] op_sel_hi:[0,1]
	v_pk_mul_f32 v[46:47], v[80:81], v[90:91] op_sel_hi:[0,1]
	v_pk_mul_f32 v[44:45], v[12:13], v[44:45]
	v_pk_mul_f32 v[46:47], v[14:15], v[46:47]
	v_cvt_pk_bf16_f32 v44, v44, v45
	v_cvt_pk_bf16_f32 v45, v46, v47
	v_pk_mul_f32 v[46:47], v[80:81], v[86:87] op_sel_hi:[0,1]
	v_pk_mul_f32 v[50:51], v[80:81], v[50:51] op_sel_hi:[0,1]
	v_pk_mul_f32 v[46:47], v[8:9], v[46:47]
	v_pk_mul_f32 v[50:51], v[10:11], v[50:51]
	v_cvt_pk_bf16_f32 v46, v46, v47
	v_cvt_pk_bf16_f32 v47, v50, v51
	global_store_dwordx4 v[84:85], v[44:47], off
	global_load_dwordx4 v[44:47], v[88:89], off
	v_lshl_add_u64 v[48:49], s[16:17], 0, v[48:49]
	global_load_dwordx4 v[48:51], v[48:49], off
	v_cmp_gt_f32_e64 s[44:45], s34, v82
	v_mov_b32_e32 v84, v53
	v_mov_b32_e32 v85, v53
	v_cndmask_b32_e64 v59, v82, v59, s[44:45]
	v_rsq_f32_e32 v59, v59
	s_nop 0
	v_mul_f32_e32 v77, 0x45800000, v59
	v_cndmask_b32_e64 v80, v59, v77, s[44:45]
	v_pk_mul_f32 v[82:83], v[80:81], v[108:109] op_sel_hi:[0,1]
	v_pk_mul_f32 v[82:83], v[16:17], v[82:83]
	s_nop 1
	v_mov_b32_dpp v84, v82 row_ror:8 row_mask:0xf bank_mask:0xf
	v_mov_b32_dpp v85, v83 row_ror:8 row_mask:0xf bank_mask:0xf
	s_waitcnt vmcnt(0) lgkmcnt(0)
; DI unsigned pack2(float a, float b) { f32x2 v = {a, b}; hwbf16x2 r = __builtin_convertvector(v, hwbf16x2); return __builtin_bit_cast(unsigned, r); }
; template <int CTRL> DI float dppf(float v) { return __builtin_bit_cast(float, __builtin_amdgcn_update_dpp(0, __builtin_bit_cast(int, v), CTRL, 0xf, 0xf, false)); }
; DI void mla_prep2_phase(const Params& p) {
;     ...
;                 u32x4 oq, ok;
; #pragma unroll
;                 for (int e = 0; e < 4; ++e) { oq[e] = pack2(q[2 * e] * fq * gqn[2 * e], q[2 * e + 1] * fq * gqn[2 * e + 1]); ok[e] = pack2(k[2 * e] * fk * gkn[2 * e], k[2 * e + 1] * fk * gkn[2 * e + 1]); }
;                 *(u32x4*)(QN + ob + 8 * j) = oq; *(u32x4*)(KC + ob + 8 * j) = ok;
;                 float ro[4];
; #pragma unroll
;                 for (int e = 0; e < 4; ++e) { const float xn = x[e] * fx * gqr[e], pr = dppf<0x128>(xn);
;                     const int fi = (4 * j + e) & 31; const float cc = ct[s * 32 + fi], sn = st[s * 32 + fi];
;                     ro[e] = (j < 8 ? xn * cc - pr * sn : xn * cc + pr * sn) * qsc; }
;                 u32x2 op; op[0] = pack2(ro[0], ro[1]); op[1] = pack2(ro[2], ro[3]);
;                 *(u32x2*)(QN + ob + 128 + 4 * j) = op;
;                 *(u32x2*)(KC + ob + 128 + 4 * j) = kp;
	v_pk_mul_f32 v[44:45], v[44:45], v[84:85]
	s_nop 0
	v_cndmask_b32_e64 v45, v45, -v45, vcc
	v_cndmask_b32_e64 v44, v44, -v44, vcc
	v_pk_fma_f32 v[44:45], v[48:49], v[82:83], v[44:45]
	v_pk_mul_f32 v[48:49], v[80:81], v[106:107] op_sel_hi:[0,1]
	v_pk_mul_f32 v[48:49], v[18:19], v[48:49]
	v_mov_b32_e32 v82, v53
	v_mov_b32_e32 v83, v53
	v_pk_mul_f32 v[44:45], v[44:45], s[26:27] op_sel_hi:[1,0]
	v_mov_b32_dpp v82, v48 row_ror:8 row_mask:0xf bank_mask:0xf
	v_mov_b32_dpp v83, v49 row_ror:8 row_mask:0xf bank_mask:0xf
	v_pk_mul_f32 v[46:47], v[46:47], v[82:83]
	v_cvt_pk_bf16_f32 v44, v44, v45
	v_cndmask_b32_e64 v47, v47, -v47, vcc
	v_cndmask_b32_e64 v46, v46, -v46, vcc
	v_pk_fma_f32 v[46:47], v[50:51], v[48:49], v[46:47]
	s_nop 0
	v_pk_mul_f32 v[46:47], v[46:47], s[26:27] op_sel_hi:[1,0]
	s_nop 0
	v_cvt_pk_bf16_f32 v45, v46, v47
	v_lshl_add_u64 v[46:47], v[102:103], 0, v[52:53]
	global_store_dwordx2 v[46:47], v[44:45], off offset:256
	v_lshl_add_u64 v[44:45], v[104:105], 0, v[52:53]
	global_store_dwordx2 v[44:45], v[70:71], off offset:256
	s_or_b64 exec, exec, s[28:29]
	s_and_saveexec_b64 s[28:29], s[42:43]
	s_cbranch_execz .LBB1_1609
.LBB1_1611:
	v_lshlrev_b32_e32 v88, 16, v24
	v_and_b32_e32 v89, 0xffff0000, v24
	v_lshlrev_b32_e32 v84, 16, v25
	v_and_b32_e32 v85, 0xffff0000, v25
	v_pk_mul_f32 v[90:91], v[88:89], v[88:89]
	v_pk_mul_f32 v[86:87], v[84:85], v[84:85]
	v_add_f32_e32 v49, v90, v91
	v_ashrrev_i32_e32 v44, 31, v81
	v_lshlrev_b32_e32 v80, 16, v26
	v_and_b32_e32 v81, 0xffff0000, v26
	v_add_f32_e32 v49, v86, v49
	v_pk_mul_f32 v[82:83], v[80:81], v[80:81]
	v_add_f32_e32 v49, v87, v49
	v_lshlrev_b32_e32 v50, 16, v27
	v_and_b32_e32 v51, 0xffff0000, v27
	v_add_f32_e32 v49, v82, v49
	v_pk_mul_f32 v[46:47], v[50:51], v[50:51]
	v_add_f32_e32 v49, v83, v49
	v_add_f32_e32 v46, v46, v49
	v_add_f32_e32 v46, v47, v46
	v_lshrrev_b32_e32 v44, 20, v44
	v_add_u32_e32 v44, v78, v44
	v_add_f32_dpp v46, v46, v46 row_ror:8 row_mask:0xf bank_mask:0xf bound_ctrl:1
	v_ashrrev_i32_e32 v45, 12, v44
	v_and_b32_e32 v44, 0xfffff000, v44
	v_add_f32_dpp v46, v46, v46 row_ror:4 row_mask:0xf bank_mask:0xf bound_ctrl:1
	v_sub_u32_e32 v48, v78, v44
	v_lshlrev_b32_e32 v44, 4, v45
	v_add_f32_dpp v46, v46, v46 row_ror:2 row_mask:0xf bank_mask:0xf bound_ctrl:1
	v_or3_b32 v44, v44, v96, v93
	v_ashrrev_i32_e32 v45, 31, v44
	v_add_f32_dpp v46, v46, v46 row_ror:1 row_mask:0xf bank_mask:0xf bound_ctrl:1
	v_fmamk_f32 v46, v46, 0x3c000000, v60
	v_mul_f32_e32 v47, 0x4b800000, v46
	v_cmp_gt_f32_e64 s[42:43], s34, v46
	v_lshlrev_b64 v[44:45], 12, v[44:45]
	v_ashrrev_i32_e32 v49, 31, v48
	v_cndmask_b32_e64 v46, v46, v47, s[42:43]
	v_rsq_f32_e32 v46, v46
	v_lshl_add_u64 v[82:83], v[44:45], 0, v[48:49]
	v_and_b32_e32 v91, 0xffff0000, v36
	v_mov_b64_e32 v[100:101], s[18:19]
	v_mul_f32_e32 v44, 0x45800000, v46
	v_cndmask_b32_e64 v44, v46, v44, s[42:43]
	v_mul_f32_e32 v78, 0x3dd53b94, v44
	v_pk_mul_f32 v[44:45], v[78:79], v[88:89] op_sel_hi:[0,1]
	v_pk_mul_f32 v[46:47], v[78:79], v[84:85] op_sel_hi:[0,1]
	v_pk_mul_f32 v[44:45], v[4:5], v[44:45]
	v_pk_mul_f32 v[46:47], v[6:7], v[46:47]
	v_cvt_pk_bf16_f32 v44, v44, v45
	v_cvt_pk_bf16_f32 v45, v46, v47
	v_pk_mul_f32 v[46:47], v[78:79], v[80:81] op_sel_hi:[0,1]
	v_pk_mul_f32 v[50:51], v[78:79], v[50:51] op_sel_hi:[0,1]
	v_lshlrev_b32_e32 v90, 16, v36
	v_mul_f32_e32 v78, v91, v91
	v_mad_u64_u32 v[100:101], s[36:37], v82, s35, v[100:101]
	v_pk_mul_f32 v[46:47], v[0:1], v[46:47]
	v_pk_mul_f32 v[50:51], v[2:3], v[50:51]
	v_lshlrev_b32_e32 v88, 16, v37
	v_and_b32_e32 v89, 0xffff0000, v37
	v_pk_fma_f32 v[98:99], v[90:91], v[90:91], v[78:79] op_sel_hi:[1,1,0]
	v_mad_i32_i24 v101, v83, s35, v101
	v_mov_b32_e32 v59, v53
	v_cvt_pk_bf16_f32 v46, v46, v47
	v_cvt_pk_bf16_f32 v47, v50, v51
	v_and_b32_e32 v87, 0xffff0000, v38
	v_pk_fma_f32 v[98:99], v[88:89], v[88:89], v[98:99]
	v_mul_f32_e32 v78, v89, v89
	v_lshl_add_u64 v[102:103], v[100:101], 0, v[58:59]
	v_lshlrev_b32_e32 v84, 16, v38
	v_and_b32_e32 v86, s0, v38
	v_mov_b32_e32 v85, v87
	v_pk_add_f32 v[98:99], v[78:79], v[98:99] op_sel_hi:[0,1]
	global_store_dwordx4 v[102:103], v[44:47], off
	v_lshlrev_b32_e32 v106, 16, v68
	v_and_b32_e32 v107, 0xffff0000, v68
	v_mov_b64_e32 v[44:45], s[14:15]
	v_lshlrev_b32_e32 v50, 16, v39
	v_and_b32_e32 v51, 0xffff0000, v39
	v_pk_mul_f32 v[86:87], v[86:87], v[86:87]
	v_pk_fma_f32 v[98:99], v[84:85], v[84:85], v[98:99]
	v_mad_u64_u32 v[102:103], s[36:37], v82, s35, v[44:45]
	v_lshl_or_b32 v44, v48, 5, v94
	v_lshlrev_b32_e32 v104, 16, v69
	v_and_b32_e32 v105, 0xffff0000, v69
	v_pk_mul_f32 v[48:49], v[106:107], v[106:107]
	v_pk_mul_f32 v[80:81], v[50:51], v[50:51]
	v_pk_mul_f32 v[46:47], v[104:105], v[104:105]
	v_mov_b32_e32 v86, v48
	v_pk_mov_b32 v[48:49], v[48:49], v[98:99] op_sel:[1,0]
	v_mad_i32_i24 v103, v83, s35, v103
	v_pk_add_f32 v[48:49], v[86:87], v[48:49]
	v_mov_b32_e32 v86, v46
	v_mov_b32_e32 v87, v80
	v_pk_add_f32 v[48:49], v[86:87], v[48:49]
	v_mov_b32_e32 v80, v47
	v_pk_add_f32 v[46:47], v[80:81], v[48:49]
	v_mov_b32_e32 v49, v53
	v_mov_b32_e32 v48, v53
	v_lshl_add_u64 v[82:83], v[102:103], 0, v[58:59]
	v_mov_b32_dpp v49, v47 row_ror:8 row_mask:0xf bank_mask:0xf
	v_mov_b32_dpp v48, v46 row_ror:8 row_mask:0xf bank_mask:0xf
	v_pk_add_f32 v[46:47], v[46:47], v[48:49]
	v_mov_b32_e32 v49, v53
	v_mov_b32_e32 v48, v53
	s_nop 0
	v_mov_b32_dpp v49, v47 row_ror:4 row_mask:0xf bank_mask:0xf
	v_mov_b32_dpp v48, v46 row_ror:4 row_mask:0xf bank_mask:0xf
	v_pk_add_f32 v[46:47], v[46:47], v[48:49]
	v_mov_b32_e32 v49, v53
	v_mov_b32_e32 v48, v53
	s_nop 0
	v_mov_b32_dpp v49, v47 row_ror:2 row_mask:0xf bank_mask:0xf
	v_mov_b32_dpp v48, v46 row_ror:2 row_mask:0xf bank_mask:0xf
; DI unsigned pack2(float a, float b) { f32x2 v = {a, b}; hwbf16x2 r = __builtin_convertvector(v, hwbf16x2); return __builtin_bit_cast(unsigned, r); }
; template <int CTRL> DI float dppf(float v) { return __builtin_bit_cast(float, __builtin_amdgcn_update_dpp(0, __builtin_bit_cast(int, v), CTRL, 0xf, 0xf, false)); }
; DI void mla_prep2_phase(const Params& p) {
;     ...
;                 u32x4 oq, ok;
; #pragma unroll
;                 for (int e = 0; e < 4; ++e) { oq[e] = pack2(q[2 * e] * fq * gqn[2 * e], q[2 * e + 1] * fq * gqn[2 * e + 1]); ok[e] = pack2(k[2 * e] * fk * gkn[2 * e], k[2 * e + 1] * fk * gkn[2 * e + 1]); }
;                 *(u32x4*)(QN + ob + 8 * j) = oq; *(u32x4*)(KC + ob + 8 * j) = ok;
;                 float ro[4];
; #pragma unroll
;                 for (int e = 0; e < 4; ++e) { const float xn = x[e] * fx * gqr[e], pr = dppf<0x128>(xn);
;                     const int fi = (4 * j + e) & 31; const float cc = ct[s * 32 + fi], sn = st[s * 32 + fi];
;                     ro[e] = (j < 8 ? xn * cc - pr * sn : xn * cc + pr * sn) * qsc; }
;                 u32x2 op; op[0] = pack2(ro[0], ro[1]); op[1] = pack2(ro[2], ro[3]);
;                 *(u32x2*)(QN + ob + 128 + 4 * j) = op;
;                 *(u32x2*)(KC + ob + 128 + 4 * j) = kp;
	v_pk_add_f32 v[46:47], v[46:47], v[48:49]
	v_mov_b32_e32 v49, v53
	v_mov_b32_e32 v48, v53
	s_nop 0
	v_mov_b32_dpp v49, v47 row_ror:1 row_mask:0xf bank_mask:0xf
	v_mov_b32_dpp v48, v46 row_ror:1 row_mask:0xf bank_mask:0xf
	v_pk_add_f32 v[46:47], v[46:47], v[48:49]
	s_nop 0
	v_pk_fma_f32 v[80:81], v[46:47], s[24:25], v[60:61] op_sel_hi:[1,1,0]
	s_nop 0
	v_mul_f32_e32 v45, 0x4b800000, v81
	v_cmp_gt_f32_e64 s[42:43], s34, v81
	v_mul_f32_e32 v59, 0x4b800000, v80
	s_nop 0
	v_cndmask_b32_e64 v45, v81, v45, s[42:43]
	v_rsq_f32_e32 v46, v45
	v_ashrrev_i32_e32 v45, 31, v44
	v_lshlrev_b64 v[48:49], 2, v[44:45]
	v_lshl_add_u64 v[86:87], s[20:21], 0, v[48:49]
	v_mul_f32_e32 v44, 0x45800000, v46
	v_cndmask_b32_e64 v78, v46, v44, s[42:43]
	v_pk_mul_f32 v[44:45], v[78:79], v[90:91] op_sel_hi:[0,1]
	v_pk_mul_f32 v[46:47], v[78:79], v[88:89] op_sel_hi:[0,1]
	v_pk_mul_f32 v[44:45], v[12:13], v[44:45]
	v_pk_mul_f32 v[46:47], v[14:15], v[46:47]
	v_cvt_pk_bf16_f32 v44, v44, v45
	v_cvt_pk_bf16_f32 v45, v46, v47
	v_pk_mul_f32 v[46:47], v[78:79], v[84:85] op_sel_hi:[0,1]
	v_pk_mul_f32 v[50:51], v[78:79], v[50:51] op_sel_hi:[0,1]
	v_pk_mul_f32 v[46:47], v[8:9], v[46:47]
	v_pk_mul_f32 v[50:51], v[10:11], v[50:51]
	v_cvt_pk_bf16_f32 v46, v46, v47
	v_cvt_pk_bf16_f32 v47, v50, v51
	global_store_dwordx4 v[82:83], v[44:47], off
	global_load_dwordx4 v[44:47], v[86:87], off
	v_lshl_add_u64 v[48:49], s[16:17], 0, v[48:49]
	global_load_dwordx4 v[48:51], v[48:49], off
	v_cmp_gt_f32_e64 s[42:43], s34, v80
	v_mov_b32_e32 v82, v53
	v_mov_b32_e32 v83, v53
	v_cndmask_b32_e64 v59, v80, v59, s[42:43]
	v_rsq_f32_e32 v59, v59
	s_nop 0
	v_mul_f32_e32 v77, 0x45800000, v59
	v_cndmask_b32_e64 v78, v59, v77, s[42:43]
	v_pk_mul_f32 v[80:81], v[78:79], v[106:107] op_sel_hi:[0,1]
	v_pk_mul_f32 v[80:81], v[16:17], v[80:81]
	s_nop 1
	v_mov_b32_dpp v82, v80 row_ror:8 row_mask:0xf bank_mask:0xf
	v_mov_b32_dpp v83, v81 row_ror:8 row_mask:0xf bank_mask:0xf
	s_waitcnt vmcnt(0) lgkmcnt(0)
	v_pk_mul_f32 v[44:45], v[44:45], v[82:83]
	s_nop 0
	v_cndmask_b32_e64 v45, v45, -v45, vcc
	v_cndmask_b32_e64 v44, v44, -v44, vcc
	v_pk_fma_f32 v[44:45], v[48:49], v[80:81], v[44:45]
	v_pk_mul_f32 v[48:49], v[78:79], v[104:105] op_sel_hi:[0,1]
	v_pk_mul_f32 v[48:49], v[18:19], v[48:49]
	v_mov_b32_e32 v80, v53
	v_mov_b32_e32 v81, v53
	v_pk_mul_f32 v[44:45], v[44:45], s[26:27] op_sel_hi:[1,0]
	v_mov_b32_dpp v80, v48 row_ror:8 row_mask:0xf bank_mask:0xf
	v_mov_b32_dpp v81, v49 row_ror:8 row_mask:0xf bank_mask:0xf
	v_pk_mul_f32 v[46:47], v[46:47], v[80:81]
	v_cvt_pk_bf16_f32 v44, v44, v45
	v_cndmask_b32_e64 v47, v47, -v47, vcc
	v_cndmask_b32_e64 v46, v46, -v46, vcc
	v_pk_fma_f32 v[46:47], v[50:51], v[48:49], v[46:47]
	s_nop 0
	v_pk_mul_f32 v[46:47], v[46:47], s[26:27] op_sel_hi:[1,0]
	s_nop 0
	v_cvt_pk_bf16_f32 v45, v46, v47
	v_lshl_add_u64 v[46:47], v[100:101], 0, v[52:53]
	global_store_dwordx2 v[46:47], v[44:45], off offset:256
	v_lshl_add_u64 v[44:45], v[102:103], 0, v[52:53]
	global_store_dwordx2 v[44:45], v[74:75], off offset:256
	s_or_b64 exec, exec, s[28:29]
	s_and_saveexec_b64 s[28:29], s[40:41]
	s_cbranch_execz .LBB1_1600
.LBB1_1612:
	v_ashrrev_i32_e32 v44, 31, v79
	v_lshrrev_b32_e32 v44, 20, v44
	v_lshlrev_b32_e32 v84, 16, v20
	v_and_b32_e32 v85, 0xffff0000, v20
	v_add_u32_e32 v44, v76, v44
	v_lshlrev_b32_e32 v80, 16, v21
	v_and_b32_e32 v81, 0xffff0000, v21
	v_pk_mul_f32 v[86:87], v[84:85], v[84:85]
	v_ashrrev_i32_e32 v45, 12, v44
	v_and_b32_e32 v44, 0xfffff000, v44
	v_pk_mul_f32 v[82:83], v[80:81], v[80:81]
	v_add_f32_e32 v49, v86, v87
	v_sub_u32_e32 v48, v76, v44
	v_lshlrev_b32_e32 v76, 16, v22
	v_and_b32_e32 v77, 0xffff0000, v22
	v_add_f32_e32 v49, v82, v49
	v_pk_mul_f32 v[78:79], v[76:77], v[76:77]
	v_add_f32_e32 v49, v83, v49
	v_lshlrev_b32_e32 v50, 16, v23
	v_and_b32_e32 v51, 0xffff0000, v23
	v_add_f32_e32 v49, v78, v49
	v_pk_mul_f32 v[46:47], v[50:51], v[50:51]
	v_add_f32_e32 v49, v79, v49
	v_add_f32_e32 v46, v46, v49
	v_add_f32_e32 v46, v47, v46
	v_lshlrev_b32_e32 v44, 4, v45
	v_or3_b32 v44, v44, v96, v93
	v_add_f32_dpp v46, v46, v46 row_ror:8 row_mask:0xf bank_mask:0xf bound_ctrl:1
	v_ashrrev_i32_e32 v45, 31, v44
	v_lshlrev_b64 v[44:45], 12, v[44:45]
	v_add_f32_dpp v46, v46, v46 row_ror:4 row_mask:0xf bank_mask:0xf bound_ctrl:1
	v_ashrrev_i32_e32 v49, 31, v48
	v_lshl_add_u64 v[78:79], v[44:45], 0, v[48:49]
	v_add_f32_dpp v46, v46, v46 row_ror:2 row_mask:0xf bank_mask:0xf bound_ctrl:1
	v_and_b32_e32 v87, 0xffff0000, v32
	v_mov_b64_e32 v[90:91], s[18:19]
	v_add_f32_dpp v46, v46, v46 row_ror:1 row_mask:0xf bank_mask:0xf bound_ctrl:1
	v_fmamk_f32 v46, v46, 0x3c000000, v60
	v_mul_f32_e32 v47, 0x4b800000, v46
	v_cmp_gt_f32_e64 s[40:41], s34, v46
	v_lshlrev_b32_e32 v86, 16, v32
	v_mad_u64_u32 v[90:91], s[36:37], v78, s35, v[90:91]
	v_cndmask_b32_e64 v46, v46, v47, s[40:41]
	v_rsq_f32_e32 v46, v46
	v_mad_i32_i24 v91, v79, s35, v91
	v_mov_b32_e32 v59, v53
	v_lshl_add_u64 v[96:97], v[90:91], 0, v[58:59]
	v_mul_f32_e32 v44, 0x45800000, v46
	v_cndmask_b32_e64 v44, v46, v44, s[40:41]
	v_mul_f32_e32 v82, 0x3dd53b94, v44
	v_pk_mul_f32 v[44:45], v[82:83], v[84:85] op_sel_hi:[0,1]
	v_pk_mul_f32 v[46:47], v[82:83], v[80:81] op_sel_hi:[0,1]
	v_pk_mul_f32 v[44:45], v[4:5], v[44:45]
	v_pk_mul_f32 v[46:47], v[6:7], v[46:47]
	v_cvt_pk_bf16_f32 v44, v44, v45
	v_cvt_pk_bf16_f32 v45, v46, v47
; DI unsigned pack2(float a, float b) { f32x2 v = {a, b}; hwbf16x2 r = __builtin_convertvector(v, hwbf16x2); return __builtin_bit_cast(unsigned, r); }
; template <int CTRL> DI float dppf(float v) { return __builtin_bit_cast(float, __builtin_amdgcn_update_dpp(0, __builtin_bit_cast(int, v), CTRL, 0xf, 0xf, false)); }
; DI void mla_prep2_phase(const Params& p) {
;     ...
;                 u32x4 oq, ok;
; #pragma unroll
;                 for (int e = 0; e < 4; ++e) { oq[e] = pack2(q[2 * e] * fq * gqn[2 * e], q[2 * e + 1] * fq * gqn[2 * e + 1]); ok[e] = pack2(k[2 * e] * fk * gkn[2 * e], k[2 * e + 1] * fk * gkn[2 * e + 1]); }
;                 *(u32x4*)(QN + ob + 8 * j) = oq; *(u32x4*)(KC + ob + 8 * j) = ok;
;                 float ro[4];
; #pragma unroll
;                 for (int e = 0; e < 4; ++e) { const float xn = x[e] * fx * gqr[e], pr = dppf<0x128>(xn);
;                     const int fi = (4 * j + e) & 31; const float cc = ct[s * 32 + fi], sn = st[s * 32 + fi];
;                     ro[e] = (j < 8 ? xn * cc - pr * sn : xn * cc + pr * sn) * qsc; }
;                 u32x2 op; op[0] = pack2(ro[0], ro[1]); op[1] = pack2(ro[2], ro[3]);
;                 *(u32x2*)(QN + ob + 128 + 4 * j) = op;
;                 *(u32x2*)(KC + ob + 128 + 4 * j) = kp;
	v_pk_mul_f32 v[46:47], v[82:83], v[76:77] op_sel_hi:[0,1]
	v_pk_mul_f32 v[50:51], v[82:83], v[50:51] op_sel_hi:[0,1]
	v_and_b32_e32 v83, 0xffff0000, v34
	v_and_b32_e32 v82, s0, v34
	v_mov_b32_e32 v81, v83
	v_pk_mul_f32 v[82:83], v[82:83], v[82:83]
	v_pk_mul_f32 v[46:47], v[0:1], v[46:47]
	v_mul_f32_e32 v82, v87, v87
	v_pk_mul_f32 v[50:51], v[2:3], v[50:51]
	v_lshlrev_b32_e32 v84, 16, v33
	v_and_b32_e32 v85, 0xffff0000, v33
	v_pk_fma_f32 v[88:89], v[86:87], v[86:87], v[82:83] op_sel_hi:[1,1,0]
	v_cvt_pk_bf16_f32 v46, v46, v47
	v_cvt_pk_bf16_f32 v47, v50, v51
	v_pk_fma_f32 v[88:89], v[84:85], v[84:85], v[88:89]
	v_mul_f32_e32 v82, v85, v85
	v_lshlrev_b32_e32 v80, 16, v34
	v_pk_add_f32 v[88:89], v[82:83], v[88:89] op_sel_hi:[0,1]
	global_store_dwordx4 v[96:97], v[44:47], off
	v_lshlrev_b32_e32 v100, 16, v66
	v_and_b32_e32 v101, 0xffff0000, v66
	v_mov_b64_e32 v[44:45], s[14:15]
	v_lshlrev_b32_e32 v50, 16, v35
	v_and_b32_e32 v51, 0xffff0000, v35
	v_pk_fma_f32 v[88:89], v[80:81], v[80:81], v[88:89]
	v_mad_u64_u32 v[96:97], s[36:37], v78, s35, v[44:45]
	v_lshl_or_b32 v44, v48, 5, v94
	v_lshlrev_b32_e32 v98, 16, v67
	v_and_b32_e32 v99, 0xffff0000, v67
	v_pk_mul_f32 v[48:49], v[100:101], v[100:101]
	v_pk_mul_f32 v[76:77], v[50:51], v[50:51]
	v_pk_mul_f32 v[46:47], v[98:99], v[98:99]
	v_mov_b32_e32 v82, v48
	v_pk_mov_b32 v[48:49], v[48:49], v[88:89] op_sel:[1,0]
	v_mad_i32_i24 v97, v79, s35, v97
	v_pk_add_f32 v[48:49], v[82:83], v[48:49]
	v_mov_b32_e32 v82, v46
	v_mov_b32_e32 v83, v76
	v_pk_add_f32 v[48:49], v[82:83], v[48:49]
	v_mov_b32_e32 v76, v47
	v_pk_add_f32 v[46:47], v[76:77], v[48:49]
	v_mov_b32_e32 v49, v53
	v_mov_b32_e32 v48, v53
	v_lshl_add_u64 v[78:79], v[96:97], 0, v[58:59]
	v_mov_b32_dpp v49, v47 row_ror:8 row_mask:0xf bank_mask:0xf
	v_mov_b32_dpp v48, v46 row_ror:8 row_mask:0xf bank_mask:0xf
	v_pk_add_f32 v[46:47], v[46:47], v[48:49]
	v_mov_b32_e32 v49, v53
	v_mov_b32_e32 v48, v53
	s_nop 0
	v_mov_b32_dpp v49, v47 row_ror:4 row_mask:0xf bank_mask:0xf
	v_mov_b32_dpp v48, v46 row_ror:4 row_mask:0xf bank_mask:0xf
	v_pk_add_f32 v[46:47], v[46:47], v[48:49]
	v_mov_b32_e32 v49, v53
	v_mov_b32_e32 v48, v53
	s_nop 0
	v_mov_b32_dpp v49, v47 row_ror:2 row_mask:0xf bank_mask:0xf
	v_mov_b32_dpp v48, v46 row_ror:2 row_mask:0xf bank_mask:0xf
	v_pk_add_f32 v[46:47], v[46:47], v[48:49]
	v_mov_b32_e32 v49, v53
	v_mov_b32_e32 v48, v53
	s_nop 0
	v_mov_b32_dpp v49, v47 row_ror:1 row_mask:0xf bank_mask:0xf
	v_mov_b32_dpp v48, v46 row_ror:1 row_mask:0xf bank_mask:0xf
	v_pk_add_f32 v[46:47], v[46:47], v[48:49]
	s_nop 0
	v_pk_fma_f32 v[76:77], v[46:47], s[24:25], v[60:61] op_sel_hi:[1,1,0]
	s_nop 0
	v_mul_f32_e32 v45, 0x4b800000, v77
	v_cmp_gt_f32_e64 s[40:41], s34, v77
	v_mul_f32_e32 v59, 0x4b800000, v76
	s_nop 0
	v_cndmask_b32_e64 v45, v77, v45, s[40:41]
	v_rsq_f32_e32 v46, v45
	v_ashrrev_i32_e32 v45, 31, v44
	v_lshlrev_b64 v[48:49], 2, v[44:45]
	v_lshl_add_u64 v[82:83], s[20:21], 0, v[48:49]
	v_mul_f32_e32 v44, 0x45800000, v46
	v_cndmask_b32_e64 v88, v46, v44, s[40:41]
	v_pk_mul_f32 v[44:45], v[88:89], v[86:87] op_sel_hi:[0,1]
	v_pk_mul_f32 v[46:47], v[88:89], v[84:85] op_sel_hi:[0,1]
	v_pk_mul_f32 v[44:45], v[12:13], v[44:45]
	v_pk_mul_f32 v[46:47], v[14:15], v[46:47]
	v_cvt_pk_bf16_f32 v44, v44, v45
	v_cvt_pk_bf16_f32 v45, v46, v47
	v_pk_mul_f32 v[46:47], v[88:89], v[80:81] op_sel_hi:[0,1]
	v_pk_mul_f32 v[50:51], v[88:89], v[50:51] op_sel_hi:[0,1]
	v_pk_mul_f32 v[46:47], v[8:9], v[46:47]
	v_pk_mul_f32 v[50:51], v[10:11], v[50:51]
	v_cvt_pk_bf16_f32 v46, v46, v47
	v_cvt_pk_bf16_f32 v47, v50, v51
	global_store_dwordx4 v[78:79], v[44:47], off
	global_load_dwordx4 v[44:47], v[82:83], off
	v_lshl_add_u64 v[48:49], s[16:17], 0, v[48:49]
	global_load_dwordx4 v[48:51], v[48:49], off
	v_cmp_gt_f32_e64 s[40:41], s34, v76
	v_mov_b32_e32 v80, v53
	v_mov_b32_e32 v81, v53
	v_cndmask_b32_e64 v59, v76, v59, s[40:41]
	v_rsq_f32_e32 v59, v59
	s_nop 0
	v_mul_f32_e32 v76, 0x45800000, v59
	v_cndmask_b32_e64 v76, v59, v76, s[40:41]
	v_pk_mul_f32 v[78:79], v[76:77], v[100:101] op_sel_hi:[0,1]
	v_pk_mul_f32 v[78:79], v[16:17], v[78:79]
	s_nop 1
	v_mov_b32_dpp v80, v78 row_ror:8 row_mask:0xf bank_mask:0xf
	v_mov_b32_dpp v81, v79 row_ror:8 row_mask:0xf bank_mask:0xf
	s_waitcnt vmcnt(0) lgkmcnt(0)
	v_pk_mul_f32 v[44:45], v[44:45], v[80:81]
	s_nop 0
	v_cndmask_b32_e64 v45, v45, -v45, vcc
	v_cndmask_b32_e64 v44, v44, -v44, vcc
	v_pk_fma_f32 v[44:45], v[48:49], v[78:79], v[44:45]
	v_pk_mul_f32 v[48:49], v[76:77], v[98:99] op_sel_hi:[0,1]
	v_pk_mul_f32 v[48:49], v[18:19], v[48:49]
	v_mov_b32_e32 v76, v53
	v_mov_b32_e32 v77, v53
	v_pk_mul_f32 v[44:45], v[44:45], s[26:27] op_sel_hi:[1,0]
	v_mov_b32_dpp v76, v48 row_ror:8 row_mask:0xf bank_mask:0xf
	v_mov_b32_dpp v77, v49 row_ror:8 row_mask:0xf bank_mask:0xf
	v_pk_mul_f32 v[46:47], v[46:47], v[76:77]
	v_cvt_pk_bf16_f32 v44, v44, v45
	v_cndmask_b32_e64 v47, v47, -v47, vcc
	v_cndmask_b32_e64 v46, v46, -v46, vcc
	v_pk_fma_f32 v[46:47], v[50:51], v[48:49], v[46:47]
	s_nop 0
	v_pk_mul_f32 v[46:47], v[46:47], s[26:27] op_sel_hi:[1,0]
	s_nop 0
	v_cvt_pk_bf16_f32 v45, v46, v47
	v_lshl_add_u64 v[46:47], v[90:91], 0, v[52:53]
	global_store_dwordx2 v[46:47], v[44:45], off offset:256
	v_lshl_add_u64 v[44:45], v[96:97], 0, v[52:53]
	global_store_dwordx2 v[44:45], v[72:73], off offset:256
	s_branch .LBB1_1600

; DI void mla_prep2_phase(const Params& p) {
;     ...
;     for (int bt = bid; bt < (T / 64) * 16; bt += gridDim.x) {
;         const int ch = bt >> 4, hh = bt & 15, dv = tid & 127, tq = tid >> 7;
; #pragma unroll
;         for (int gi = 0; gi < 2; ++gi) {
;             const int t0 = ch * 64 + (tq + 4 * gi) * 8, b = t0 / S, s0 = t0 - b * S;
;             unsigned v[8];
; #pragma unroll
;             for (int e = 0; e < 8; ++e) v[e] = KV32[(size_t)(t0 + e) * 4096 + hh * 256 + 128 + dv];
;             u32x4 o; o[0] = v[0] | (v[1] << 16); o[1] = v[2] | (v[3] << 16); o[2] = v[4] | (v[5] << 16); o[3] = v[6] | (v[7] << 16);
;             *(u32x4*)(VT + ((size_t)(b * 16 + hh) * 128 + dv) * S + s0) = o;
;         }
;     }
.LBB1_1615:
	s_and_b32 s6, s3, 0xffffffc0
	s_and_b32 s5, s2, 15
	v_add_u32_e32 v6, s6, v4
	s_lshl_b32 s6, s5, 9
	v_ashrrev_i32_e32 v7, 31, v6
	v_or_b32_e32 v10, 1, v6
	v_or_b32_e32 v12, 2, v6
	v_or_b32_e32 v14, 3, v6
	v_or_b32_e32 v16, 4, v6
	v_or_b32_e32 v18, 5, v6
	v_or_b32_e32 v20, 6, v6
	v_or_b32_e32 v22, 7, v6
	v_lshl_add_u64 v[8:9], v[0:1], 0, s[6:7]
	v_lshlrev_b64 v[24:25], 13, v[6:7]
	v_ashrrev_i32_e32 v11, 31, v10
	v_ashrrev_i32_e32 v13, 31, v12
	v_ashrrev_i32_e32 v15, 31, v14
	v_ashrrev_i32_e32 v17, 31, v16
	v_ashrrev_i32_e32 v19, 31, v18
	v_ashrrev_i32_e32 v21, 31, v20
	v_ashrrev_i32_e32 v23, 31, v22
	v_lshl_add_u64 v[24:25], v[8:9], 0, v[24:25]
	v_lshlrev_b64 v[10:11], 13, v[10:11]
	v_lshlrev_b64 v[12:13], 13, v[12:13]
	v_lshlrev_b64 v[14:15], 13, v[14:15]
	v_lshlrev_b64 v[16:17], 13, v[16:17]
	v_lshlrev_b64 v[18:19], 13, v[18:19]
	v_lshlrev_b64 v[20:21], 13, v[20:21]
	v_lshlrev_b64 v[22:23], 13, v[22:23]
	v_lshl_add_u64 v[10:11], v[8:9], 0, v[10:11]
	v_lshl_add_u64 v[12:13], v[8:9], 0, v[12:13]
	v_lshl_add_u64 v[14:15], v[8:9], 0, v[14:15]
	v_lshl_add_u64 v[16:17], v[8:9], 0, v[16:17]
	v_lshl_add_u64 v[18:19], v[8:9], 0, v[18:19]
	v_lshl_add_u64 v[20:21], v[8:9], 0, v[20:21]
	v_lshl_add_u64 v[22:23], v[8:9], 0, v[22:23]
	global_load_ushort v5, v[24:25], off offset:256
	global_load_ushort v30, v[10:11], off offset:256
	global_load_ushort v31, v[12:13], off offset:256
	global_load_ushort v32, v[14:15], off offset:256
	global_load_ushort v33, v[16:17], off offset:256
	global_load_ushort v34, v[18:19], off offset:256
	global_load_ushort v35, v[20:21], off offset:256
	global_load_ushort v36, v[22:23], off offset:256
	v_add_u32_e32 v10, 32, v6
	v_add_u32_e32 v12, 33, v6
	v_add_u32_e32 v14, 34, v6
	v_add_u32_e32 v16, 35, v6
	v_add_u32_e32 v18, 36, v6
	v_add_u32_e32 v20, 37, v6
	v_add_u32_e32 v22, 38, v6
	v_add_u32_e32 v24, 39, v6
	v_lshrrev_b32_e32 v7, 20, v7
	v_ashrrev_i32_e32 v11, 31, v10
	v_ashrrev_i32_e32 v13, 31, v12
	v_ashrrev_i32_e32 v15, 31, v14
	v_ashrrev_i32_e32 v17, 31, v16
	v_ashrrev_i32_e32 v19, 31, v18
	v_ashrrev_i32_e32 v21, 31, v20
	v_ashrrev_i32_e32 v23, 31, v22
	v_ashrrev_i32_e32 v25, 31, v24
	v_add_u32_e32 v7, v6, v7
	v_lshlrev_b64 v[26:27], 13, v[10:11]
	v_lshlrev_b64 v[12:13], 13, v[12:13]
	v_lshlrev_b64 v[14:15], 13, v[14:15]
	v_lshlrev_b64 v[16:17], 13, v[16:17]
	v_lshlrev_b64 v[18:19], 13, v[18:19]
	v_lshlrev_b64 v[20:21], 13, v[20:21]
	v_lshlrev_b64 v[22:23], 13, v[22:23]
	v_lshlrev_b64 v[24:25], 13, v[24:25]
	v_ashrrev_i32_e32 v28, 12, v7
	v_lshl_add_u64 v[26:27], v[8:9], 0, v[26:27]
	v_lshl_add_u64 v[12:13], v[8:9], 0, v[12:13]
	v_lshl_add_u64 v[14:15], v[8:9], 0, v[14:15]
	v_lshl_add_u64 v[16:17], v[8:9], 0, v[16:17]
	v_lshl_add_u64 v[18:19], v[8:9], 0, v[18:19]
	v_lshl_add_u64 v[20:21], v[8:9], 0, v[20:21]
	v_lshl_add_u64 v[22:23], v[8:9], 0, v[22:23]
	v_lshl_add_u64 v[24:25], v[8:9], 0, v[24:25]
	v_lshl_or_b32 v8, v28, 4, s5
	v_and_b32_e32 v7, 0xfffff000, v7
	v_ashrrev_i32_e32 v9, 31, v8
	v_sub_u32_e32 v6, v6, v7
	v_lshlrev_b64 v[8:9], 20, v[8:9]
	v_ashrrev_i32_e32 v7, 31, v6
	v_lshl_add_u64 v[8:9], v[2:3], 0, v[8:9]
	v_lshl_add_u64 v[28:29], v[6:7], 1, v[8:9]
	s_add_i32 s2, s2, s50
	s_add_i32 s3, s3, s4
	s_cmpk_lt_i32 s2, 0x1000
	s_waitcnt vmcnt(0) lgkmcnt(0)
	v_lshl_or_b32 v6, v30, 16, v5
	v_lshl_or_b32 v7, v32, 16, v31
	v_lshl_or_b32 v8, v34, 16, v33
	v_lshl_or_b32 v9, v36, 16, v35
	global_store_dwordx4 v[28:29], v[6:9], off
	global_load_ushort v5, v[26:27], off offset:256
	s_nop 0
	global_load_ushort v12, v[12:13], off offset:256
	s_nop 0
	global_load_ushort v13, v[14:15], off offset:256
	s_nop 0
	global_load_ushort v14, v[16:17], off offset:256
	global_load_ushort v15, v[18:19], off offset:256
	s_nop 0
	global_load_ushort v16, v[20:21], off offset:256
	global_load_ushort v17, v[22:23], off offset:256
	global_load_ushort v18, v[24:25], off offset:256
	v_lshrrev_b32_e32 v6, 20, v11
	v_add_u32_e32 v6, v10, v6
	v_ashrrev_i32_e32 v7, 12, v6
	v_lshl_or_b32 v8, v7, 4, s5
	v_and_b32_e32 v6, 0xfffff000, v6
	v_ashrrev_i32_e32 v9, 31, v8
	v_sub_u32_e32 v6, v10, v6
	v_lshlrev_b64 v[8:9], 20, v[8:9]
	v_ashrrev_i32_e32 v7, 31, v6
	v_lshl_add_u64 v[8:9], v[2:3], 0, v[8:9]
	v_lshl_add_u64 v[10:11], v[6:7], 1, v[8:9]
	s_waitcnt vmcnt(0) lgkmcnt(0)
	v_lshl_or_b32 v6, v12, 16, v5
	v_lshl_or_b32 v7, v14, 16, v13
	v_lshl_or_b32 v8, v16, 16, v15
	v_lshl_or_b32 v9, v18, 16, v17
	global_store_dwordx4 v[10:11], v[6:9], off
	s_cbranch_scc1 .LBB1_1615

; DI unsigned pack2(float a, float b) { f32x2 v = {a, b}; hwbf16x2 r = __builtin_convertvector(v, hwbf16x2); return __builtin_bit_cast(unsigned, r); }
; DI float xsum32(float v) { return v + __shfl_xor(v, 32); }
; DI float fast_exp2(float x) { return __builtin_amdgcn_exp2f(x); }
; #define MLA_STORE(bufp) do { _Pragma("unroll") for (int i = 0; i < 3; ++i) *(LAS u32x4*)((bufp) + klds[i]) = kreg[i]; \
;                              _Pragma("unroll") for (int i = 0; i < 2; ++i) { LAS u32x2* dp = (LAS u32x2*)((bufp) + vlds[i]); \
;                                  dp[0] = (u32x2){vreg[i][0], vreg[i][1]}; dp[2] = (u32x2){vreg[i][2], vreg[i][3]}; } } while (0)
; template <int NDB>
; DI void softmax_only(f32x16& sacc, float& m, float& l, f32x16 (&oacc)[NDB], bf16x8 (&pf)[2]) {
;     ...
;     float pv[16], ls = 0.f;
; #pragma unroll
;     for (int i = 0; i < 16; ++i) { pv[i] = fast_exp2(sacc[i]); ls += pv[i]; }
;     l += ls;
; #pragma unroll
;     for (int s2 = 0; s2 < 2; ++s2) {
;         u32x4 pw;
; #pragma unroll
;         for (int q = 0; q < 4; ++q) pw[q] = pack2(pv[8 * s2 + 2 * q], pv[8 * s2 + 2 * q + 1]);
;         pf[s2] = __builtin_bit_cast(bf16x8, pw);
;     }
; DI void mla_attn_phase(const Params& p, LAS unsigned char* lds) {
;     ...
;                 for (int s2 = 0; s2 < 2; ++s2)
; #pragma unroll
;                     for (int db = 0; db < 4; ++db) oacc[db] = __builtin_amdgcn_mfma_f32_32x32x16_bf16(vf[s2][db], pf[s2], oacc[db], 0, 0, 0);
;             }
;             if (t + 1 < NT) MLA_STORE(lds + ((t + 1) & 1) * BUF);
;             __syncthreads();
;         }
;     ...
;         const float lt = xsum32(l), inv = 1.0f / lt;
;         bf16_t* Op = O + (size_t)(b * S + q0 + r) * 2048 + hh * 128 + 4 * h;
; #pragma unroll
;         for (int db = 0; db < 4; ++db)
; #pragma unroll
;             for (int g = 0; g < 4; ++g) { u32x2 o; o[0] = pack2(oacc[db][4 * g] * inv, oacc[db][4 * g + 1] * inv); o[1] = pack2(oacc[db][4 * g + 2] * inv, oacc[db][4 * g + 3] * inv);
;                 *(u32x2*)(Op + db * 32 + 8 * g) = o; }
.LBB1_1682:
	v_exp_f32_e32 v112, v64
	v_exp_f32_e32 v113, v65
	v_exp_f32_e32 v114, v66
	v_exp_f32_e32 v115, v67
	v_exp_f32_e32 v116, v68
	v_exp_f32_e32 v117, v69
	v_exp_f32_e32 v118, v70
	v_exp_f32_e32 v119, v71
	v_cvt_pk_bf16_f32 v64, v112, v113
	v_cvt_pk_bf16_f32 v65, v114, v115
	v_cvt_pk_bf16_f32 v66, v116, v117
	v_cvt_pk_bf16_f32 v67, v118, v119
	v_exp_f32_e32 v72, v72
	v_exp_f32_e32 v73, v73
	v_mfma_f32_32x32x16_bf16 v[48:63], v[108:111], v[64:67], v[48:63]
	v_exp_f32_e32 v74, v74
	v_exp_f32_e32 v75, v75
	v_exp_f32_e32 v76, v76
	v_exp_f32_e32 v77, v77
	v_exp_f32_e32 v78, v78
	v_exp_f32_e32 v79, v79
	v_cvt_pk_bf16_f32 v68, v72, v73
	v_mfma_f32_32x32x16_bf16 v[32:47], v[104:107], v[64:67], v[32:47]
	v_cvt_pk_bf16_f32 v69, v74, v75
	v_cvt_pk_bf16_f32 v70, v76, v77
	v_cvt_pk_bf16_f32 v71, v78, v79
	s_barrier
	s_add_i32 s6, s6, s50
	v_mfma_f32_32x32x16_bf16 v[16:31], v[84:87], v[64:67], v[16:31]
	v_mfma_f32_32x32x16_bf16 v[0:15], v[88:91], v[64:67], v[0:15]
	v_add_f32_e32 v64, 0, v112
	v_add_f32_e32 v64, v64, v113
	v_add_f32_e32 v64, v114, v64
	v_add_f32_e32 v64, v115, v64
	v_add_f32_e32 v64, v116, v64
	v_add_f32_e32 v64, v117, v64
	v_add_f32_e32 v64, v118, v64
	v_add_f32_e32 v64, v119, v64
	v_add_f32_e32 v64, v72, v64
	v_add_f32_e32 v64, v73, v64
	v_add_f32_e32 v64, v74, v64
	v_add_f32_e32 v64, v75, v64
	v_add_f32_e32 v64, v76, v64
	v_add_f32_e32 v64, v77, v64
	v_add_f32_e32 v64, v78, v64
	v_add_f32_e32 v64, v79, v64
	v_add_f32_e32 v64, v144, v64
	ds_bpermute_b32 v65, v234, v64
	v_mfma_f32_32x32x16_bf16 v[48:63], v[80:83], v[68:71], v[48:63]
	s_waitcnt lgkmcnt(0)
	v_add_f32_e32 v64, v64, v65
	v_div_scale_f32 v65, s[2:3], v64, v64, 1.0
	v_rcp_f32_e32 v66, v65
	v_mfma_f32_32x32x16_bf16 v[32:47], v[92:95], v[68:71], v[32:47]
	s_lshl_b32 s2, s11, 4
	s_and_b32 s2, s2, 0xfffff000
	v_fma_f32 v67, -v65, v66, 1.0
	v_fmac_f32_e32 v66, v67, v66
	v_div_scale_f32 v67, vcc, 1.0, v64, 1.0
	v_mfma_f32_32x32x16_bf16 v[16:31], v[96:99], v[68:71], v[16:31]
	v_mfma_f32_32x32x16_bf16 v[0:15], v[100:103], v[68:71], v[0:15]
	v_mul_f32_e32 v68, v67, v66
	v_fma_f32 v69, -v65, v68, v67
	v_fmac_f32_e32 v68, v69, v66
	v_fma_f32 v65, -v65, v68, v67
	v_div_fmas_f32 v65, v65, v66, v68
	v_div_fixup_f32 v64, v65, v64, 1.0
	v_add_u32_e32 v65, s2, v220
	v_or_b32_e32 v66, v65, v196
	v_ashrrev_i32_e32 v67, 31, v66
	v_lshlrev_b64 v[66:67], 12, v[66:67]
	s_lshl_b32 s2, s52, 8
	v_lshl_add_u64 v[66:67], s[42:43], 0, v[66:67]
	s_and_b32 s44, s2, 0xf00
	v_lshl_add_u64 v[66:67], v[66:67], 0, s[44:45]
	v_pk_mul_f32 v[48:49], v[48:49], v[64:65] op_sel_hi:[1,0]
	v_pk_mul_f32 v[50:51], v[50:51], v[64:65] op_sel_hi:[1,0]
	v_pk_mul_f32 v[32:33], v[32:33], v[64:65] op_sel_hi:[1,0]
	v_pk_mul_f32 v[34:35], v[34:35], v[64:65] op_sel_hi:[1,0]
	v_pk_mul_f32 v[16:17], v[16:17], v[64:65] op_sel_hi:[1,0]
	v_pk_mul_f32 v[18:19], v[18:19], v[64:65] op_sel_hi:[1,0]
	v_pk_mul_f32 v[0:1], v[0:1], v[64:65] op_sel_hi:[1,0]
	v_pk_mul_f32 v[2:3], v[2:3], v[64:65] op_sel_hi:[1,0]
	v_lshl_add_u64 v[66:67], v[66:67], 0, v[204:205]
	v_cvt_pk_bf16_f32 v48, v48, v49
	v_cvt_pk_bf16_f32 v49, v50, v51
	v_cvt_pk_bf16_f32 v32, v32, v33
	v_cvt_pk_bf16_f32 v33, v34, v35
	v_cvt_pk_bf16_f32 v16, v16, v17
	v_cvt_pk_bf16_f32 v17, v18, v19
	v_cvt_pk_bf16_f32 v0, v0, v1
	v_cvt_pk_bf16_f32 v1, v2, v3
	global_store_dwordx2 v[66:67], v[48:49], off
	v_pk_mul_f32 v[48:49], v[52:53], v[64:65] op_sel_hi:[1,0]
	v_pk_mul_f32 v[50:51], v[54:55], v[64:65] op_sel_hi:[1,0]
	global_store_dwordx2 v[66:67], v[32:33], off offset:64
	v_pk_mul_f32 v[32:33], v[36:37], v[64:65] op_sel_hi:[1,0]
	v_pk_mul_f32 v[34:35], v[38:39], v[64:65] op_sel_hi:[1,0]
	global_store_dwordx2 v[66:67], v[16:17], off offset:128
	v_pk_mul_f32 v[16:17], v[20:21], v[64:65] op_sel_hi:[1,0]
	v_pk_mul_f32 v[18:19], v[22:23], v[64:65] op_sel_hi:[1,0]
	global_store_dwordx2 v[66:67], v[0:1], off offset:192
	v_pk_mul_f32 v[0:1], v[4:5], v[64:65] op_sel_hi:[1,0]
	v_pk_mul_f32 v[2:3], v[6:7], v[64:65] op_sel_hi:[1,0]
	v_cvt_pk_bf16_f32 v48, v48, v49
	v_cvt_pk_bf16_f32 v49, v50, v51
	v_cvt_pk_bf16_f32 v32, v32, v33
	v_cvt_pk_bf16_f32 v33, v34, v35
	v_cvt_pk_bf16_f32 v16, v16, v17
	v_cvt_pk_bf16_f32 v17, v18, v19
	v_cvt_pk_bf16_f32 v0, v0, v1
	v_cvt_pk_bf16_f32 v1, v2, v3
	global_store_dwordx2 v[66:67], v[48:49], off offset:16
	v_pk_mul_f32 v[48:49], v[56:57], v[64:65] op_sel_hi:[1,0]
	v_pk_mul_f32 v[50:51], v[58:59], v[64:65] op_sel_hi:[1,0]
	global_store_dwordx2 v[66:67], v[32:33], off offset:80
	v_pk_mul_f32 v[32:33], v[40:41], v[64:65] op_sel_hi:[1,0]
	v_pk_mul_f32 v[34:35], v[42:43], v[64:65] op_sel_hi:[1,0]
	global_store_dwordx2 v[66:67], v[16:17], off offset:144
	v_pk_mul_f32 v[16:17], v[24:25], v[64:65] op_sel_hi:[1,0]
	v_pk_mul_f32 v[18:19], v[26:27], v[64:65] op_sel_hi:[1,0]
	global_store_dwordx2 v[66:67], v[0:1], off offset:208
	v_pk_mul_f32 v[0:1], v[8:9], v[64:65] op_sel_hi:[1,0]
	v_pk_mul_f32 v[2:3], v[10:11], v[64:65] op_sel_hi:[1,0]
	v_cvt_pk_bf16_f32 v48, v48, v49
	v_cvt_pk_bf16_f32 v49, v50, v51
	v_cvt_pk_bf16_f32 v32, v32, v33
	v_cvt_pk_bf16_f32 v33, v34, v35
	v_cvt_pk_bf16_f32 v16, v16, v17
	v_cvt_pk_bf16_f32 v17, v18, v19
	v_cvt_pk_bf16_f32 v0, v0, v1
	v_cvt_pk_bf16_f32 v1, v2, v3
	global_store_dwordx2 v[66:67], v[48:49], off offset:32
	v_pk_mul_f32 v[48:49], v[60:61], v[64:65] op_sel_hi:[1,0]
	v_pk_mul_f32 v[50:51], v[62:63], v[64:65] op_sel_hi:[1,0]
	global_store_dwordx2 v[66:67], v[32:33], off offset:96
	v_pk_mul_f32 v[32:33], v[44:45], v[64:65] op_sel_hi:[1,0]
	v_pk_mul_f32 v[34:35], v[46:47], v[64:65] op_sel_hi:[1,0]
	global_store_dwordx2 v[66:67], v[16:17], off offset:160
	v_pk_mul_f32 v[16:17], v[28:29], v[64:65] op_sel_hi:[1,0]
	v_pk_mul_f32 v[18:19], v[30:31], v[64:65] op_sel_hi:[1,0]
	global_store_dwordx2 v[66:67], v[0:1], off offset:224
	v_pk_mul_f32 v[0:1], v[12:13], v[64:65] op_sel_hi:[1,0]
	v_pk_mul_f32 v[2:3], v[14:15], v[64:65] op_sel_hi:[1,0]
	v_cvt_pk_bf16_f32 v48, v48, v49
	v_cvt_pk_bf16_f32 v49, v50, v51
	v_cvt_pk_bf16_f32 v32, v32, v33
	v_cvt_pk_bf16_f32 v33, v34, v35
	v_cvt_pk_bf16_f32 v16, v16, v17
	v_cvt_pk_bf16_f32 v17, v18, v19
	v_cvt_pk_bf16_f32 v0, v0, v1
	v_cvt_pk_bf16_f32 v1, v2, v3
	s_cmpk_gt_i32 s6, 0x3ff
	global_store_dwordx2 v[66:67], v[48:49], off offset:48
	global_store_dwordx2 v[66:67], v[32:33], off offset:112
	global_store_dwordx2 v[66:67], v[16:17], off offset:176
	global_store_dwordx2 v[66:67], v[0:1], off offset:240
	s_cbranch_scc1 .LBB1_1693
; #define MLA_LOAD(k0) do { const char* kt_ = Kg + (size_t)(k0) * 384; const char* vt_ = Vg + (size_t)(k0) * 2; \
;                           _Pragma("unroll") for (int i = 0; i < 3; ++i) kreg[i] = *(const u32x4*)(kt_ + kgo + i * 8192); \
;                           _Pragma("unroll") for (int i = 0; i < 2; ++i) vreg[i] = *(const u32x4*)(vt_ + vgo[i]); } while (0)
; #define MLA_STORE(bufp) do { _Pragma("unroll") for (int i = 0; i < 3; ++i) *(LAS u32x4*)((bufp) + klds[i]) = kreg[i]; \
;                              _Pragma("unroll") for (int i = 0; i < 2; ++i) { LAS u32x2* dp = (LAS u32x2*)((bufp) + vlds[i]); \
;                                  dp[0] = (u32x2){vreg[i][0], vreg[i][1]}; dp[2] = (u32x2){vreg[i][2], vreg[i][3]}; } } while (0)
; DI void mla_attn_phase(const Params& p, LAS unsigned char* lds) {
;     ...
;     for (int it0 = bid; it0 < 1024; it0 += gridDim.x) {
;         const int item = (gridDim.x == 256) ? (((it0 >> 8) * 8 + (it0 & 7)) * 32 + ((it0 & 255) >> 3)) : it0;
;         const int bh = item >> 4, qb = item & 15, b = bh >> 4, hh = bh & 15, q0 = qb * 256 + wid * 32;
;         const char* Kg = (const char*)(KC + (size_t)bh * S * 192); const char* Vg = (const char*)(VT + (size_t)bh * 128 * S);
;         const bf16_t* Qp = QN + ((size_t)bh * S + q0 + r) * 192 + 8 * h;
;         bf16x8 qf[12];
; #pragma unroll
;         for (int ks = 0; ks < 12; ++ks) qf[ks] = *(const bf16x8*)(Qp + 16 * ks);
;         u32x4 kreg[3], vreg[2];
;     ...
;         MLA_LOAD(0); MLA_STORE(lds);
;         __syncthreads();
;         float m = 0.f, l = 0.f;
;         f32x16 oacc[4];
; #pragma unroll
;         for (int db = 0; db < 4; ++db)
; #pragma unroll
;             for (int i = 0; i < 16; ++i) oacc[db][i] = 0.f;
.LBB1_1683:
	s_lshl_b32 s2, s6, 5
	s_and_b32 s2, s2, 0xe0
	s_and_b32 s3, s6, 0xffffff00
	s_or_b32 s2, s2, s3
	s_bfe_u32 s3, s6, 0x50003
	s_or_b32 s4, s2, s3
	v_readlane_b32 s2, v246, 54
	v_readlane_b32 s3, v246, 55
	s_and_b64 s[2:3], s[2:3], exec
	s_cselect_b32 s11, s4, s6
	s_lshl_b32 s2, s11, 8
	s_ashr_i32 s52, s11, 4
	s_and_b32 s2, s2, 0xf00
	v_add_u32_e32 v220, s2, v233
	s_ashr_i32 s53, s52, 31
	s_lshl_b64 s[2:3], s[52:53], 12
	v_ashrrev_i32_e32 v221, 31, v220
	v_lshl_add_u64 v[0:1], s[2:3], 0, v[220:221]
	v_or_b32_e32 v0, v0, v196
	v_mad_u64_u32 v[2:3], s[2:3], v0, s9, v[208:209]
	v_mad_i32_i24 v3, v1, s9, v3
	global_load_dwordx4 v[140:143], v[2:3], off
	global_load_dwordx4 v[136:139], v[2:3], off offset:32
	global_load_dwordx4 v[132:135], v[2:3], off offset:64
	global_load_dwordx4 v[128:131], v[2:3], off offset:96
	global_load_dwordx4 v[124:127], v[2:3], off offset:128
	global_load_dwordx4 v[120:123], v[2:3], off offset:160
	global_load_dwordx4 v[116:119], v[2:3], off offset:192
	global_load_dwordx4 v[112:115], v[2:3], off offset:224
	global_load_dwordx4 v[108:111], v[2:3], off offset:256
	global_load_dwordx4 v[104:107], v[2:3], off offset:288
	global_load_dwordx4 v[100:103], v[2:3], off offset:320
	global_load_dwordx4 v[96:99], v[2:3], off offset:352
	v_mad_i64_i32 v[8:9], s[2:3], s52, v215, v[210:211]
	s_movk_i32 s2, 0x2000
	s_nop 0
	v_add_co_u32_e32 v4, vcc, s2, v8
	s_lshl_b64 s[4:5], s[52:53], 20
	s_nop 0
	v_addc_co_u32_e32 v5, vcc, 0, v9, vcc
	s_movk_i32 s2, 0x4000
	global_load_dwordx4 v[0:3], v[8:9], off
	v_lshl_add_u64 v[222:223], v[216:217], 0, s[4:5]
	global_load_dwordx4 v[4:7], v[4:5], off
	v_add_co_u32_e32 v8, vcc, s2, v8
	s_add_u32 s2, s7, s4
	s_nop 0
	v_addc_co_u32_e32 v9, vcc, 0, v9, vcc
	s_addc_u32 s3, s8, s5
	global_load_dwordx4 v[8:11], v[8:9], off
	v_lshl_add_u64 v[12:13], s[2:3], 0, v[202:203]
	global_load_dwordx4 v[12:15], v[12:13], off
	v_lshl_add_u64 v[16:17], s[2:3], 0, v[200:201]
	global_load_dwordx4 v[16:19], v[16:17], off
	v_mad_i64_i32 v[226:227], s[2:3], s52, v215, v[198:199]
	v_lshl_add_u64 v[224:225], v[218:219], 0, s[4:5]
	s_mov_b32 s2, 0
	v_mov_b32_e32 v242, 0
	v_mov_b32_e32 v221, 0
	s_waitcnt vmcnt(0) lgkmcnt(0)
	ds_write_b128 v235, v[0:3]
	ds_write_b128 v236, v[4:7]
	ds_write_b128 v237, v[8:11]
	ds_write2_b64 v238, v[12:13], v[14:15] offset0:128 offset1:130
	ds_write2_b64 v239, v[16:17], v[18:19] offset0:128 offset1:130
	v_mov_b32_e32 v14, v205
	v_mov_b32_e32 v15, v205
	v_mov_b32_e32 v0, v205
	v_mov_b32_e32 v1, v205
	v_mov_b32_e32 v2, v205
	v_mov_b32_e32 v3, v205
	v_mov_b32_e32 v4, v205
	v_mov_b32_e32 v5, v205
	v_mov_b32_e32 v6, v205
	v_mov_b32_e32 v7, v205
	v_mov_b32_e32 v8, v205
	v_mov_b32_e32 v9, v205
	v_mov_b32_e32 v10, v205
	v_mov_b32_e32 v11, v205
	v_mov_b32_e32 v12, v205
	v_mov_b32_e32 v13, v205
	v_mov_b64_e32 v[30:31], v[14:15]
	v_mov_b64_e32 v[46:47], v[14:15]
	v_mov_b64_e32 v[62:63], v[14:15]
	v_mov_b64_e32 v[28:29], v[12:13]
	v_mov_b64_e32 v[26:27], v[10:11]
	v_mov_b64_e32 v[24:25], v[8:9]
	v_mov_b64_e32 v[22:23], v[6:7]
	v_mov_b64_e32 v[20:21], v[4:5]
	v_mov_b64_e32 v[18:19], v[2:3]
	v_mov_b64_e32 v[16:17], v[0:1]
	v_mov_b64_e32 v[44:45], v[12:13]
	v_mov_b64_e32 v[42:43], v[10:11]
	v_mov_b64_e32 v[40:41], v[8:9]
	v_mov_b64_e32 v[38:39], v[6:7]
	v_mov_b64_e32 v[36:37], v[4:5]
	v_mov_b64_e32 v[34:35], v[2:3]
	v_mov_b64_e32 v[32:33], v[0:1]
	v_mov_b64_e32 v[60:61], v[12:13]
	v_mov_b64_e32 v[58:59], v[10:11]
	v_mov_b64_e32 v[56:57], v[8:9]
	v_mov_b64_e32 v[54:55], v[6:7]
	v_mov_b64_e32 v[52:53], v[4:5]
	v_mov_b64_e32 v[50:51], v[2:3]
	v_mov_b64_e32 v[48:49], v[0:1]
	s_waitcnt lgkmcnt(0)
	s_barrier
	s_branch .LBB1_1685

; #define LAS __attribute__((address_space(3)))
; DI float xmax32(float v) { return fmaxf(v, __shfl_xor(v, 32)); }
; DI float fast_exp2(float x) { return __builtin_amdgcn_exp2f(x); }
; template <int NDB>
; DI void softmax_only(f32x16& sacc, float& m, float& l, f32x16 (&oacc)[NDB], bf16x8 (&pf)[2]) {
;     float mx = sacc[0];
; #pragma unroll
;     for (int i = 1; i < 16; ++i) mx = fmaxf(mx, sacc[i]);
;     mx = xmax32(mx);
;     if (__any(mx > 8.0f)) {
;         const float d = fmaxf(mx, 0.f), alpha = fast_exp2(-d);
;         l *= alpha; m += d;
; #pragma unroll
;         for (int i = 0; i < 16; ++i) sacc[i] -= d;
; #pragma unroll
;         for (int db = 0; db < NDB; ++db)
; #pragma unroll
;             for (int i = 0; i < 16; ++i) oacc[db][i] *= alpha;
;     }
; DI void mla_attn_phase(const Params& p, LAS unsigned char* lds) {
;     ...
;         for (int t = 0; t < NT; ++t) {
;             if (t + 1 < NT) MLA_LOAD((t + 1) * 64);
;             LAS unsigned char* kb = lds + (t & 1) * BUF;
; #pragma unroll
;             for (int blk = 0; blk < 2; ++blk) {
;                 bf16x8 kf[12];
;                 LAS const unsigned char* kp = kb + (blk * 32 + r) * KSTR + h * 16;
; #pragma unroll
;                 for (int ks = 0; ks < 4; ++ks) kf[ks] = *(LAS const bf16x8*)(kp + ks * 32);
;                 f32x16 sacc;
; #pragma unroll
;                 for (int i = 0; i < 16; ++i) sacc[i] = -m;
; #pragma unroll
;                 for (int kg = 0; kg < 3; ++kg) {
;                     if (kg < 2) {
; #pragma unroll
;                         for (int ks = 0; ks < 4; ++ks) kf[4 * (kg + 1) + ks] = *(LAS const bf16x8*)(kp + (4 * (kg + 1) + ks) * 32);
;                     }
; #pragma unroll
;                     for (int ks = 0; ks < 4; ++ks) sacc = __builtin_amdgcn_mfma_f32_32x32x16_bf16(kf[4 * kg + ks], qf[4 * kg + ks], sacc, 0, 0, 0);
;                 }
;                 bf16x8 vf[2][4], pf[2];
;                 load_vfrags<4, VSTR>(vf, kb + KBUF + r * VSTR + blk * 64 + h * 16);
;                 softmax_only<4>(sacc, m, l, oacc, pf);
.LBB1_1685:
	v_lshl_add_u64 v[64:65], s[40:41], 0, v[226:227]
	v_add_co_u32_e32 v66, vcc, 0x40516000, v64
	s_bitcmp1_b32 s2, 0
	s_nop 0
	v_addc_co_u32_e32 v67, vcc, 0, v65, vcc
	global_load_dwordx4 v[156:159], v[66:67], off
	v_add_co_u32_e32 v66, vcc, 0x40518000, v64
	s_cselect_b32 s3, 0xac00, 0
	s_nop 0
	v_addc_co_u32_e32 v67, vcc, 0, v65, vcc
	v_add_co_u32_e32 v64, vcc, 0x4051a000, v64
	global_load_dwordx4 v[152:155], v[66:67], off
	s_nop 0
	v_addc_co_u32_e32 v65, vcc, 0, v65, vcc
	global_load_dwordx4 v[160:163], v[64:65], off
	v_lshl_add_u64 v[64:65], s[40:41], 0, v[224:225]
	global_load_dwordx4 v[148:151], v[64:65], off
	v_lshl_add_u64 v[64:65], s[40:41], 0, v[222:223]
	s_add_i32 s3, s3, 0
	global_load_dwordx4 v[144:147], v[64:65], off
	v_add_u32_e32 v64, s3, v206
	v_add_u32_e32 v244, v64, v213
	v_xor_b32_e32 v64, 0x80000000, v221
	v_add_u32_e32 v65, s3, v207
	v_mov_b32_e32 v78, v64
	v_mov_b32_e32 v79, v64
	v_add_u32_e32 v243, v65, v206
	ds_read_b128 v[164:167], v244
	ds_read_b128 v[168:171], v244 offset:32
	ds_read_b128 v[172:175], v244 offset:64
	ds_read_b128 v[176:179], v244 offset:96
	v_mov_b32_e32 v65, v64
	v_mov_b32_e32 v66, v64
	v_mov_b32_e32 v67, v64
	v_mov_b32_e32 v68, v64
	v_mov_b32_e32 v69, v64
	v_mov_b32_e32 v70, v64
	v_mov_b32_e32 v71, v64
	v_mov_b32_e32 v72, v64
	v_mov_b32_e32 v73, v64
	v_mov_b32_e32 v74, v64
	v_mov_b32_e32 v75, v64
	v_mov_b32_e32 v76, v64
	v_mov_b32_e32 v77, v64
	v_mov_b64_e32 v[94:95], v[78:79]
	v_mov_b64_e32 v[92:93], v[76:77]
	v_mov_b64_e32 v[90:91], v[74:75]
	v_mov_b64_e32 v[88:89], v[72:73]
	v_mov_b64_e32 v[86:87], v[70:71]
	v_mov_b64_e32 v[84:85], v[68:69]
	v_mov_b64_e32 v[82:83], v[66:67]
	v_mov_b64_e32 v[80:81], v[64:65]
	ds_read_b128 v[180:183], v244 offset:128
	ds_read_b128 v[184:187], v244 offset:160
	ds_read_b128 v[188:191], v244 offset:192
	ds_read_b128 v[192:195], v244 offset:224
	s_waitcnt lgkmcnt(0)
	v_mfma_f32_32x32x16_bf16 v[80:95], v[164:167], v[140:143], v[80:95]
	ds_read_b128 v[66:69], v244 offset:256
	ds_read_b128 v[70:73], v244 offset:288
	ds_read_b128 v[74:77], v244 offset:320
	ds_read_b128 v[164:167], v244 offset:352
	v_mfma_f32_32x32x16_bf16 v[80:95], v[168:171], v[136:139], v[80:95]
	v_mfma_f32_32x32x16_bf16 v[80:95], v[172:175], v[132:135], v[80:95]
	v_mfma_f32_32x32x16_bf16 v[80:95], v[176:179], v[128:131], v[80:95]
	v_mfma_f32_32x32x16_bf16 v[80:95], v[180:183], v[124:127], v[80:95]
	v_mfma_f32_32x32x16_bf16 v[80:95], v[184:187], v[120:123], v[80:95]
	v_mfma_f32_32x32x16_bf16 v[80:95], v[188:191], v[116:119], v[80:95]
	v_mfma_f32_32x32x16_bf16 v[80:95], v[192:195], v[112:115], v[80:95]
	s_waitcnt lgkmcnt(0)
	v_mfma_f32_32x32x16_bf16 v[80:95], v[66:69], v[108:111], v[80:95]
	v_mfma_f32_32x32x16_bf16 v[80:95], v[70:73], v[104:107], v[80:95]
	v_mfma_f32_32x32x16_bf16 v[80:95], v[74:77], v[100:103], v[80:95]
	v_mfma_f32_32x32x16_bf16 v[80:95], v[164:167], v[96:99], v[80:95]
	ds_read_b128 v[192:195], v243 offset:25600
	ds_read_b128 v[164:167], v243 offset:25632
	ds_read_b128 v[188:191], v243 offset:30208
	ds_read_b128 v[184:187], v243 offset:34816
	ds_read_b128 v[168:171], v243 offset:39424
	ds_read_b128 v[172:175], v243 offset:30240
	ds_read_b128 v[176:179], v243 offset:34848
	ds_read_b128 v[180:183], v243 offset:39456
	s_nop 3
	v_max_f32_e32 v65, v81, v81
	v_max_f32_e32 v66, v80, v80
	v_max_f32_e32 v65, v66, v65
	v_max3_f32 v65, v65, v82, v83
	v_max3_f32 v65, v65, v84, v85
	v_max3_f32 v65, v65, v86, v87
	v_max3_f32 v65, v65, v88, v89
	v_max3_f32 v65, v65, v90, v91
	v_max3_f32 v65, v65, v92, v93
	v_max3_f32 v65, v65, v94, v95
	ds_bpermute_b32 v66, v234, v65
	s_waitcnt lgkmcnt(0)
	v_max_f32_e32 v66, v66, v66
	v_max_f32_e32 v65, v65, v66
	v_cmp_lt_f32_e32 vcc, s10, v65
	s_cbranch_vccz .LBB1_1687
	v_max_f32_e32 v64, v65, v65
	v_max_f32_e32 v64, 0, v64
	v_exp_f32_e64 v66, -v64
	v_add_f32_e32 v221, v221, v64
	v_pk_add_f32 v[80:81], v[80:81], v[64:65] op_sel_hi:[1,0] neg_lo:[0,1] neg_hi:[0,1]
	v_pk_add_f32 v[82:83], v[82:83], v[64:65] op_sel_hi:[1,0] neg_lo:[0,1] neg_hi:[0,1]
	v_mul_f32_e32 v242, v242, v66
	v_pk_add_f32 v[84:85], v[84:85], v[64:65] op_sel_hi:[1,0] neg_lo:[0,1] neg_hi:[0,1]
	v_pk_add_f32 v[86:87], v[86:87], v[64:65] op_sel_hi:[1,0] neg_lo:[0,1] neg_hi:[0,1]
	v_pk_add_f32 v[88:89], v[88:89], v[64:65] op_sel_hi:[1,0] neg_lo:[0,1] neg_hi:[0,1]
	v_pk_add_f32 v[90:91], v[90:91], v[64:65] op_sel_hi:[1,0] neg_lo:[0,1] neg_hi:[0,1]
	v_pk_add_f32 v[92:93], v[92:93], v[64:65] op_sel_hi:[1,0] neg_lo:[0,1] neg_hi:[0,1]
	v_pk_add_f32 v[94:95], v[94:95], v[64:65] op_sel_hi:[1,0] neg_lo:[0,1] neg_hi:[0,1]
	v_pk_mul_f32 v[62:63], v[62:63], v[66:67] op_sel_hi:[1,0]
	v_pk_mul_f32 v[60:61], v[60:61], v[66:67] op_sel_hi:[1,0]
	v_pk_mul_f32 v[58:59], v[58:59], v[66:67] op_sel_hi:[1,0]
	v_pk_mul_f32 v[56:57], v[56:57], v[66:67] op_sel_hi:[1,0]
	v_pk_mul_f32 v[54:55], v[54:55], v[66:67] op_sel_hi:[1,0]
	v_pk_mul_f32 v[52:53], v[52:53], v[66:67] op_sel_hi:[1,0]
	v_pk_mul_f32 v[50:51], v[50:51], v[66:67] op_sel_hi:[1,0]
	v_pk_mul_f32 v[48:49], v[48:49], v[66:67] op_sel_hi:[1,0]
	v_pk_mul_f32 v[46:47], v[46:47], v[66:67] op_sel_hi:[1,0]
	v_pk_mul_f32 v[44:45], v[44:45], v[66:67] op_sel_hi:[1,0]
	v_pk_mul_f32 v[42:43], v[42:43], v[66:67] op_sel_hi:[1,0]
	v_pk_mul_f32 v[40:41], v[40:41], v[66:67] op_sel_hi:[1,0]
	v_pk_mul_f32 v[38:39], v[38:39], v[66:67] op_sel_hi:[1,0]
	v_pk_mul_f32 v[36:37], v[36:37], v[66:67] op_sel_hi:[1,0]
	v_pk_mul_f32 v[34:35], v[34:35], v[66:67] op_sel_hi:[1,0]
	v_pk_mul_f32 v[32:33], v[32:33], v[66:67] op_sel_hi:[1,0]
	v_pk_mul_f32 v[30:31], v[30:31], v[66:67] op_sel_hi:[1,0]
	v_pk_mul_f32 v[28:29], v[28:29], v[66:67] op_sel_hi:[1,0]
	v_pk_mul_f32 v[26:27], v[26:27], v[66:67] op_sel_hi:[1,0]
	v_pk_mul_f32 v[24:25], v[24:25], v[66:67] op_sel_hi:[1,0]
	v_pk_mul_f32 v[22:23], v[22:23], v[66:67] op_sel_hi:[1,0]
	v_pk_mul_f32 v[20:21], v[20:21], v[66:67] op_sel_hi:[1,0]
	v_pk_mul_f32 v[18:19], v[18:19], v[66:67] op_sel_hi:[1,0]
	v_pk_mul_f32 v[16:17], v[16:17], v[66:67] op_sel_hi:[1,0]
	v_pk_mul_f32 v[14:15], v[14:15], v[66:67] op_sel_hi:[1,0]
	v_pk_mul_f32 v[12:13], v[12:13], v[66:67] op_sel_hi:[1,0]
	v_pk_mul_f32 v[10:11], v[10:11], v[66:67] op_sel_hi:[1,0]
	v_pk_mul_f32 v[8:9], v[8:9], v[66:67] op_sel_hi:[1,0]
	v_pk_mul_f32 v[6:7], v[6:7], v[66:67] op_sel_hi:[1,0]
	v_pk_mul_f32 v[4:5], v[4:5], v[66:67] op_sel_hi:[1,0]
	v_pk_mul_f32 v[2:3], v[2:3], v[66:67] op_sel_hi:[1,0]
	v_pk_mul_f32 v[0:1], v[0:1], v[66:67] op_sel_hi:[1,0]
	v_xor_b32_e32 v64, 0x80000000, v221

; #define PG8_STAGE(bufoff, gbase, voff) do { _Pragma("unroll") for (int _i = 0; _i < 2; ++_i) \
;         __builtin_amdgcn_global_load_lds((const unsigned*)((const char*)(gbase) + (voff)[_i]), (LAS unsigned*)(lds + (bufoff) + ldsw + _i * 8192), 16, 0, 0); } while (0)
; #define PG8_LDA(dst, b, h) do { _Pragma("unroll") for (int m = 0; m < 4; ++m) _Pragma("unroll") for (int k = 0; k < 2; ++k) dst[m][k] = *(const LAS bf16x8*)(lds + PG8_SA(b, h) + aoff + m * 2048 + k * 1024); } while (0)
; #define PG8_WAIT_V(n) asm volatile("s_waitcnt vmcnt(" #n ")" ::: "memory")
; #define PG8_BAR __builtin_amdgcn_s_barrier()
; template <class Map, class Epi>
; DI void gemm_phase(LAS unsigned char* lds, const Map& MP, const Epi& E, const int nM, const int nN, const int K, const int lda, const int ldb) {
;     ...
;         for (int t = 0; t < nt; t += 2) {
;             const bool last = (t == nt - 2);
;             const char* a1 = cA + (size_t)(t + 1) * kstep;
;             const char* a2 = last ? nA : cA + (size_t)(t + 2) * kstep; const char* b2 = last ? nB : cB + (size_t)(t + 2) * kstep;
;             const char* a3 = a2 + kstep; const char* b3 = b2 + kstep;
;             PG8_LDB(B0, 0, 0); PG8_SCHED; PG8_LDA(At, 0, 0); PG8_STAGE(PG8_SA(1, 1), a1 + hstepA, voffA);
;             PG8_WAIT_L(8); PG8_BAR; PG8_WAIT_L(0); PG8_MMA(0, 0, At, B0); PG8_BAR; PG8_SCHED;
;             PG8_LDB(B1, 0, 1); PG8_STAGE(PG8_SB(0, 0), b2, voffB);
;             PG8_BAR; PG8_WAIT_L(0); PG8_MMA(0, 1, At, B1); PG8_BAR;
;             PG8_LDA(At, 0, 1); PG8_STAGE(PG8_SA(0, 0), a2, voffA);
;             PG8_BAR; PG8_WAIT_L(0); PG8_MMA(1, 0, At, B0); PG8_BAR; PG8_SCHED;
;             PG8_STAGE(PG8_SB(0, 1), b2 + hstepB, voffB);
;             PG8_WAIT_V(6); PG8_BAR; PG8_MMA(1, 1, At, B1); PG8_BAR;
;             PG8_LDB(B0, 1, 0); PG8_SCHED; PG8_LDA(At, 1, 0); PG8_STAGE(PG8_SA(0, 1), a2 + hstepA, voffA);
;             PG8_WAIT_L(8); PG8_BAR; PG8_WAIT_L(0); PG8_MMA(0, 0, At, B0); PG8_BAR; PG8_SCHED;
;             PG8_LDB(B1, 1, 1); PG8_STAGE(PG8_SB(1, 0), b3, voffB);
;             PG8_BAR; PG8_WAIT_L(0); PG8_MMA(0, 1, At, B1); PG8_BAR;
;             PG8_LDA(At, 1, 1); PG8_STAGE(PG8_SA(1, 0), a3, voffA);
;             PG8_BAR; PG8_WAIT_L(0); PG8_MMA(1, 0, At, B0); PG8_BAR; PG8_SCHED;
;             PG8_STAGE(PG8_SB(1, 1), b3 + hstepB, voffB);
;             PG8_WAIT_V(6); PG8_BAR; PG8_MMA(1, 1, At, B1); PG8_BAR;
.LBB1_1764:
	ds_read_b128 v[152:155], v149
	ds_read_b128 v[156:159], v149 offset:1024
	ds_read_b128 v[160:163], v149 offset:2048
	ds_read_b128 v[164:167], v149 offset:3072
	s_add_u32 s12, s10, 0xfff80080
	s_addc_u32 s13, s11, -1
	s_cmp_eq_u32 s3, 28
	s_cselect_b32 s15, s37, s13
	s_cselect_b32 s14, s38, s12
	s_cselect_b32 s13, s39, s48
	s_cselect_b32 s12, s45, s47
	v_lshl_add_u64 v[144:145], s[10:11], 0, v[138:139]
	s_add_i32 m0, s24, 0xc000
	ds_read_b128 v[168:171], v150
	ds_read_b128 v[172:175], v150 offset:1024
	ds_read_b128 v[176:179], v150 offset:2048
	ds_read_b128 v[180:183], v150 offset:3072
	ds_read_b128 v[184:187], v150 offset:4096
	ds_read_b128 v[188:191], v150 offset:5120
	ds_read_b128 v[192:195], v150 offset:6144
	ds_read_b128 v[198:201], v150 offset:7168
	global_load_lds_dwordx4 v[144:145], off
	v_lshl_add_u64 v[144:145], s[10:11], 0, v[136:137]
	s_add_i32 m0, s24, 0xe000
	s_nop 0
	global_load_lds_dwordx4 v[144:145], off
	s_waitcnt lgkmcnt(8)
	s_barrier
	s_setprio 1
	s_waitcnt lgkmcnt(7)
	v_mfma_f32_16x16x32_bf16 v[124:127], v[152:155], v[168:171], v[124:127]
	v_mfma_f32_16x16x32_bf16 v[120:123], v[160:163], v[168:171], v[120:123]
	s_waitcnt lgkmcnt(5)
	v_mfma_f32_16x16x32_bf16 v[108:111], v[152:155], v[176:179], v[108:111]
	v_mfma_f32_16x16x32_bf16 v[104:107], v[160:163], v[176:179], v[104:107]
	s_waitcnt lgkmcnt(3)
	v_mfma_f32_16x16x32_bf16 v[92:95], v[152:155], v[184:187], v[92:95]
	v_mfma_f32_16x16x32_bf16 v[88:91], v[160:163], v[184:187], v[88:91]
	s_waitcnt lgkmcnt(1)
	v_mfma_f32_16x16x32_bf16 v[76:79], v[152:155], v[192:195], v[76:79]
	v_mfma_f32_16x16x32_bf16 v[72:75], v[160:163], v[192:195], v[72:75]
	v_mfma_f32_16x16x32_bf16 v[124:127], v[156:159], v[172:175], v[124:127]
	v_mfma_f32_16x16x32_bf16 v[120:123], v[164:167], v[172:175], v[120:123]
	v_mfma_f32_16x16x32_bf16 v[108:111], v[156:159], v[180:183], v[108:111]
	v_mfma_f32_16x16x32_bf16 v[104:107], v[164:167], v[180:183], v[104:107]
	v_mfma_f32_16x16x32_bf16 v[92:95], v[156:159], v[188:191], v[92:95]
	v_mfma_f32_16x16x32_bf16 v[88:91], v[164:167], v[188:191], v[88:91]
	s_waitcnt lgkmcnt(0)
	v_mfma_f32_16x16x32_bf16 v[76:79], v[156:159], v[198:201], v[76:79]
	v_mfma_f32_16x16x32_bf16 v[72:75], v[164:167], v[198:201], v[72:75]
	s_setprio 0
	s_barrier
	s_add_i32 s49, s35, s22
	v_lshl_add_u64 v[144:145], s[12:13], 0, v[132:133]
	s_mov_b32 m0, s49
	ds_read_b128 v[202:205], v151
	ds_read_b128 v[206:209], v151 offset:1024
	ds_read_b128 v[210:213], v151 offset:2048
	ds_read_b128 v[214:217], v151 offset:3072
	global_load_lds_dwordx4 v[144:145], off
	v_lshl_add_u64 v[218:219], s[12:13], 0, v[128:129]
	s_add_i32 m0, s49, 0x2000
	s_nop 0
	global_load_lds_dwordx4 v[218:219], off
	s_barrier
	s_setprio 1
	s_waitcnt lgkmcnt(3)
	v_mfma_f32_16x16x32_bf16 v[116:119], v[202:205], v[168:171], v[116:119]
	s_waitcnt lgkmcnt(1)
	v_mfma_f32_16x16x32_bf16 v[112:115], v[210:213], v[168:171], v[112:115]
	v_mfma_f32_16x16x32_bf16 v[100:103], v[202:205], v[176:179], v[100:103]
	v_mfma_f32_16x16x32_bf16 v[96:99], v[210:213], v[176:179], v[96:99]
	v_mfma_f32_16x16x32_bf16 v[84:87], v[202:205], v[184:187], v[84:87]
	v_mfma_f32_16x16x32_bf16 v[80:83], v[210:213], v[184:187], v[80:83]
	v_mfma_f32_16x16x32_bf16 v[68:71], v[202:205], v[192:195], v[68:71]
	v_mfma_f32_16x16x32_bf16 v[64:67], v[210:213], v[192:195], v[64:67]
	v_mfma_f32_16x16x32_bf16 v[116:119], v[206:209], v[172:175], v[116:119]
	s_waitcnt lgkmcnt(0)
	v_mfma_f32_16x16x32_bf16 v[112:115], v[214:217], v[172:175], v[112:115]
	v_mfma_f32_16x16x32_bf16 v[100:103], v[206:209], v[180:183], v[100:103]
	v_mfma_f32_16x16x32_bf16 v[96:99], v[214:217], v[180:183], v[96:99]
	v_mfma_f32_16x16x32_bf16 v[84:87], v[206:209], v[188:191], v[84:87]
	v_mfma_f32_16x16x32_bf16 v[80:83], v[214:217], v[188:191], v[80:83]
	v_mfma_f32_16x16x32_bf16 v[68:71], v[206:209], v[198:201], v[68:71]
	v_mfma_f32_16x16x32_bf16 v[64:67], v[214:217], v[198:201], v[64:67]
	s_setprio 0
	s_mov_b32 m0, s24
	v_lshl_add_u64 v[220:221], s[14:15], 0, v[134:135]
	s_barrier
	ds_read_b128 v[168:171], v150 offset:16384
	ds_read_b128 v[172:175], v150 offset:17408
	ds_read_b128 v[176:179], v150 offset:18432
	ds_read_b128 v[180:183], v150 offset:19456
	ds_read_b128 v[184:187], v150 offset:20480
	ds_read_b128 v[188:191], v150 offset:21504
	ds_read_b128 v[192:195], v150 offset:22528
	ds_read_b128 v[198:201], v150 offset:23552
	global_load_lds_dwordx4 v[220:221], off
	v_lshl_add_u64 v[222:223], s[14:15], 0, v[130:131]
	s_mov_b32 m0, s9
	s_nop 0
	global_load_lds_dwordx4 v[222:223], off
	s_barrier
	s_setprio 1
	s_waitcnt lgkmcnt(7)
	v_mfma_f32_16x16x32_bf16 v[60:63], v[152:155], v[168:171], v[60:63]
	v_mfma_f32_16x16x32_bf16 v[56:59], v[160:163], v[168:171], v[56:59]
	s_waitcnt lgkmcnt(5)
	v_mfma_f32_16x16x32_bf16 v[44:47], v[152:155], v[176:179], v[44:47]
	v_mfma_f32_16x16x32_bf16 v[40:43], v[160:163], v[176:179], v[40:43]
	s_waitcnt lgkmcnt(3)
	v_mfma_f32_16x16x32_bf16 v[28:31], v[152:155], v[184:187], v[28:31]
	v_mfma_f32_16x16x32_bf16 v[24:27], v[160:163], v[184:187], v[24:27]
	s_waitcnt lgkmcnt(1)
	v_mfma_f32_16x16x32_bf16 v[12:15], v[152:155], v[192:195], v[12:15]
	v_mfma_f32_16x16x32_bf16 v[8:11], v[160:163], v[192:195], v[8:11]
	v_mfma_f32_16x16x32_bf16 v[60:63], v[156:159], v[172:175], v[60:63]
	v_mfma_f32_16x16x32_bf16 v[56:59], v[164:167], v[172:175], v[56:59]
	v_mfma_f32_16x16x32_bf16 v[44:47], v[156:159], v[180:183], v[44:47]
	v_mfma_f32_16x16x32_bf16 v[40:43], v[164:167], v[180:183], v[40:43]
	v_mfma_f32_16x16x32_bf16 v[28:31], v[156:159], v[188:191], v[28:31]
	v_mfma_f32_16x16x32_bf16 v[24:27], v[164:167], v[188:191], v[24:27]
	s_waitcnt lgkmcnt(0)
	v_mfma_f32_16x16x32_bf16 v[12:15], v[156:159], v[198:201], v[12:15]
	v_mfma_f32_16x16x32_bf16 v[8:11], v[164:167], v[198:201], v[8:11]
	s_setprio 0
	s_barrier
; #define PG8_STAGE(bufoff, gbase, voff) do { _Pragma("unroll") for (int _i = 0; _i < 2; ++_i) \
;         __builtin_amdgcn_global_load_lds((const unsigned*)((const char*)(gbase) + (voff)[_i]), (LAS unsigned*)(lds + (bufoff) + ldsw + _i * 8192), 16, 0, 0); } while (0)
; #define PG8_LDA(dst, b, h) do { _Pragma("unroll") for (int m = 0; m < 4; ++m) _Pragma("unroll") for (int k = 0; k < 2; ++k) dst[m][k] = *(const LAS bf16x8*)(lds + PG8_SA(b, h) + aoff + m * 2048 + k * 1024); } while (0)
; #define PG8_WAIT_V(n) asm volatile("s_waitcnt vmcnt(" #n ")" ::: "memory")
; #define PG8_BAR __builtin_amdgcn_s_barrier()
; template <class Map, class Epi>
; DI void gemm_phase(LAS unsigned char* lds, const Map& MP, const Epi& E, const int nM, const int nN, const int K, const int lda, const int ldb) {
;     ...
;         for (int t = 0; t < nt; t += 2) {
;             const bool last = (t == nt - 2);
;             const char* a1 = cA + (size_t)(t + 1) * kstep;
;             const char* a2 = last ? nA : cA + (size_t)(t + 2) * kstep; const char* b2 = last ? nB : cB + (size_t)(t + 2) * kstep;
;             const char* a3 = a2 + kstep; const char* b3 = b2 + kstep;
;             PG8_LDB(B0, 0, 0); PG8_SCHED; PG8_LDA(At, 0, 0); PG8_STAGE(PG8_SA(1, 1), a1 + hstepA, voffA);
;             PG8_WAIT_L(8); PG8_BAR; PG8_WAIT_L(0); PG8_MMA(0, 0, At, B0); PG8_BAR; PG8_SCHED;
;             PG8_LDB(B1, 0, 1); PG8_STAGE(PG8_SB(0, 0), b2, voffB);
;             PG8_BAR; PG8_WAIT_L(0); PG8_MMA(0, 1, At, B1); PG8_BAR;
;             PG8_LDA(At, 0, 1); PG8_STAGE(PG8_SA(0, 0), a2, voffA);
;             PG8_BAR; PG8_WAIT_L(0); PG8_MMA(1, 0, At, B0); PG8_BAR; PG8_SCHED;
;             PG8_STAGE(PG8_SB(0, 1), b2 + hstepB, voffB);
;             PG8_WAIT_V(6); PG8_BAR; PG8_MMA(1, 1, At, B1); PG8_BAR;
;             PG8_LDB(B0, 1, 0); PG8_SCHED; PG8_LDA(At, 1, 0); PG8_STAGE(PG8_SA(0, 1), a2 + hstepA, voffA);
;             PG8_WAIT_L(8); PG8_BAR; PG8_WAIT_L(0); PG8_MMA(0, 0, At, B0); PG8_BAR; PG8_SCHED;
;             PG8_LDB(B1, 1, 1); PG8_STAGE(PG8_SB(1, 0), b3, voffB);
;             PG8_BAR; PG8_WAIT_L(0); PG8_MMA(0, 1, At, B1); PG8_BAR;
;             PG8_LDA(At, 1, 1); PG8_STAGE(PG8_SA(1, 0), a3, voffA);
;             PG8_BAR; PG8_WAIT_L(0); PG8_MMA(1, 0, At, B0); PG8_BAR; PG8_SCHED;
;             PG8_STAGE(PG8_SB(1, 1), b3 + hstepB, voffB);
;             PG8_WAIT_V(6); PG8_BAR; PG8_MMA(1, 1, At, B1); PG8_BAR;
	s_add_u32 s54, s12, 0x80000
	s_addc_u32 s55, s13, 0
	s_add_i32 s49, s36, s22
	v_lshl_add_u64 v[152:153], s[54:55], 0, v[132:133]
	s_mov_b32 m0, s49
	s_nop 0
	global_load_lds_dwordx4 v[152:153], off
	v_lshl_add_u64 v[152:153], s[54:55], 0, v[128:129]
	s_add_i32 m0, s49, 0x2000
	s_nop 0
	global_load_lds_dwordx4 v[152:153], off
	s_waitcnt vmcnt(6)
	s_barrier
	s_setprio 1
	v_mfma_f32_16x16x32_bf16 v[52:55], v[202:205], v[168:171], v[52:55]
	v_mfma_f32_16x16x32_bf16 v[48:51], v[210:213], v[168:171], v[48:51]
	v_mfma_f32_16x16x32_bf16 v[36:39], v[202:205], v[176:179], v[36:39]
	v_mfma_f32_16x16x32_bf16 v[32:35], v[210:213], v[176:179], v[32:35]
	v_mfma_f32_16x16x32_bf16 v[20:23], v[202:205], v[184:187], v[20:23]
	v_mfma_f32_16x16x32_bf16 v[16:19], v[210:213], v[184:187], v[16:19]
	v_mfma_f32_16x16x32_bf16 v[4:7], v[202:205], v[192:195], v[4:7]
	v_mfma_f32_16x16x32_bf16 v[0:3], v[210:213], v[192:195], v[0:3]
	v_mfma_f32_16x16x32_bf16 v[52:55], v[206:209], v[172:175], v[52:55]
	v_mfma_f32_16x16x32_bf16 v[48:51], v[214:217], v[172:175], v[48:51]
	v_mfma_f32_16x16x32_bf16 v[36:39], v[206:209], v[180:183], v[36:39]
	v_mfma_f32_16x16x32_bf16 v[32:35], v[214:217], v[180:183], v[32:35]
	v_mfma_f32_16x16x32_bf16 v[20:23], v[206:209], v[188:191], v[20:23]
	v_mfma_f32_16x16x32_bf16 v[16:19], v[214:217], v[188:191], v[16:19]
	v_mfma_f32_16x16x32_bf16 v[4:7], v[206:209], v[198:201], v[4:7]
	v_mfma_f32_16x16x32_bf16 v[0:3], v[214:217], v[198:201], v[0:3]
	s_setprio 0
	s_add_i32 s49, 0, 0x18000
	v_add_u32_e32 v164, s49, v148
	s_barrier
	ds_read_b128 v[152:155], v164
	ds_read_b128 v[156:159], v164 offset:1024
	ds_read_b128 v[160:163], v164 offset:2048
	ds_read_b128 v[164:167], v164 offset:3072
	s_add_u32 s14, s14, 0x80000
	s_addc_u32 s15, s15, 0
	s_mov_b32 m0, s25
	v_lshl_add_u64 v[202:203], s[14:15], 0, v[134:135]
	ds_read_b128 v[168:171], v150 offset:32768
	ds_read_b128 v[172:175], v150 offset:33792
	ds_read_b128 v[176:179], v150 offset:34816
	ds_read_b128 v[180:183], v150 offset:35840
	ds_read_b128 v[184:187], v150 offset:36864
	ds_read_b128 v[188:191], v150 offset:37888
	ds_read_b128 v[192:195], v150 offset:38912
	ds_read_b128 v[198:201], v150 offset:39936
	global_load_lds_dwordx4 v[202:203], off
	v_lshl_add_u64 v[202:203], s[14:15], 0, v[130:131]
	s_mov_b32 m0, s26
	s_nop 0
	global_load_lds_dwordx4 v[202:203], off
	s_waitcnt lgkmcnt(8)
	s_barrier
	s_setprio 1
	s_waitcnt lgkmcnt(7)
	v_mfma_f32_16x16x32_bf16 v[124:127], v[152:155], v[168:171], v[124:127]
	v_mfma_f32_16x16x32_bf16 v[120:123], v[160:163], v[168:171], v[120:123]
	s_waitcnt lgkmcnt(5)
	v_mfma_f32_16x16x32_bf16 v[108:111], v[152:155], v[176:179], v[108:111]
	v_mfma_f32_16x16x32_bf16 v[104:107], v[160:163], v[176:179], v[104:107]
	s_waitcnt lgkmcnt(3)
	v_mfma_f32_16x16x32_bf16 v[92:95], v[152:155], v[184:187], v[92:95]
	v_mfma_f32_16x16x32_bf16 v[88:91], v[160:163], v[184:187], v[88:91]
	s_waitcnt lgkmcnt(1)
	v_mfma_f32_16x16x32_bf16 v[76:79], v[152:155], v[192:195], v[76:79]
	v_mfma_f32_16x16x32_bf16 v[72:75], v[160:163], v[192:195], v[72:75]
	v_mfma_f32_16x16x32_bf16 v[124:127], v[156:159], v[172:175], v[124:127]
	v_mfma_f32_16x16x32_bf16 v[120:123], v[164:167], v[172:175], v[120:123]
	v_mfma_f32_16x16x32_bf16 v[108:111], v[156:159], v[180:183], v[108:111]
	v_mfma_f32_16x16x32_bf16 v[104:107], v[164:167], v[180:183], v[104:107]
	v_mfma_f32_16x16x32_bf16 v[92:95], v[156:159], v[188:191], v[92:95]
	v_mfma_f32_16x16x32_bf16 v[88:91], v[164:167], v[188:191], v[88:91]
	s_waitcnt lgkmcnt(0)
	v_mfma_f32_16x16x32_bf16 v[76:79], v[156:159], v[198:201], v[76:79]
	v_mfma_f32_16x16x32_bf16 v[72:75], v[164:167], v[198:201], v[72:75]
	s_setprio 0
	s_barrier
	s_add_i32 s14, 0, 0x1c000
	s_add_i32 s15, s49, s22
	v_add_u32_e32 v196, s14, v148
	v_lshl_add_u64 v[144:145], v[144:145], 0, s[42:43]
	s_mov_b32 m0, s15
	ds_read_b128 v[202:205], v196
	ds_read_b128 v[206:209], v196 offset:1024
	ds_read_b128 v[210:213], v196 offset:2048
	ds_read_b128 v[214:217], v196 offset:3072
	global_load_lds_dwordx4 v[144:145], off
	v_lshl_add_u64 v[144:145], v[218:219], 0, s[42:43]
	s_add_i32 m0, s15, 0x2000
	s_nop 0
	global_load_lds_dwordx4 v[144:145], off
	s_barrier
	s_setprio 1
	s_waitcnt lgkmcnt(3)
	v_mfma_f32_16x16x32_bf16 v[116:119], v[202:205], v[168:171], v[116:119]
	s_waitcnt lgkmcnt(1)
	v_mfma_f32_16x16x32_bf16 v[112:115], v[210:213], v[168:171], v[112:115]
	v_mfma_f32_16x16x32_bf16 v[100:103], v[202:205], v[176:179], v[100:103]
	v_mfma_f32_16x16x32_bf16 v[96:99], v[210:213], v[176:179], v[96:99]
	v_mfma_f32_16x16x32_bf16 v[84:87], v[202:205], v[184:187], v[84:87]
	v_mfma_f32_16x16x32_bf16 v[80:83], v[210:213], v[184:187], v[80:83]
	v_mfma_f32_16x16x32_bf16 v[68:71], v[202:205], v[192:195], v[68:71]
	v_mfma_f32_16x16x32_bf16 v[64:67], v[210:213], v[192:195], v[64:67]
	v_mfma_f32_16x16x32_bf16 v[116:119], v[206:209], v[172:175], v[116:119]
	s_waitcnt lgkmcnt(0)
	v_mfma_f32_16x16x32_bf16 v[112:115], v[214:217], v[172:175], v[112:115]
	v_mfma_f32_16x16x32_bf16 v[100:103], v[206:209], v[180:183], v[100:103]
	v_mfma_f32_16x16x32_bf16 v[96:99], v[214:217], v[180:183], v[96:99]
	v_mfma_f32_16x16x32_bf16 v[84:87], v[206:209], v[188:191], v[84:87]
	v_mfma_f32_16x16x32_bf16 v[80:83], v[214:217], v[188:191], v[80:83]
	v_mfma_f32_16x16x32_bf16 v[68:71], v[206:209], v[198:201], v[68:71]
	v_mfma_f32_16x16x32_bf16 v[64:67], v[214:217], v[198:201], v[64:67]
	s_setprio 0
	s_mov_b32 m0, s30
	v_lshl_add_u64 v[144:145], v[220:221], 0, s[42:43]
	s_barrier
; DI unsigned pack2(float a, float b) { f32x2 v = {a, b}; hwbf16x2 r = __builtin_convertvector(v, hwbf16x2); return __builtin_bit_cast(unsigned, r); }
; DI float bflo(unsigned w) { return __uint_as_float(w << 16); }
; DI float bfhi(unsigned w) { return __uint_as_float(w & 0xffff0000u); }
; #define PG8_STAGE(bufoff, gbase, voff) do { _Pragma("unroll") for (int _i = 0; _i < 2; ++_i) \
;         __builtin_amdgcn_global_load_lds((const unsigned*)((const char*)(gbase) + (voff)[_i]), (LAS unsigned*)(lds + (bufoff) + ldsw + _i * 8192), 16, 0, 0); } while (0)
; #define PG8_BAR __builtin_amdgcn_s_barrier()
;     DI void operator()(const f32x4 (&acc)[2][2][4][2], const Unit& u, int wr, int wc, int fr, int fq) const {
;     ...
;             for (int m = 0; m < 4; ++m) { const size_t ro = (size_t)(row0 + ai * HALF + m * 16) * D + col0;
; #pragma unroll
;                 for (int bj = 0; bj < 2; ++bj) {
;                     f32x4 x0, x1;
;                     if constexpr (IB) { const u32x4 w = *(const u32x4*)((const bf16_t*)Xin + ro + bj * HALF);
;                         x0 = (f32x4){bflo(w[0]), bfhi(w[0]), bflo(w[1]), bfhi(w[1])}; x1 = (f32x4){bflo(w[2]), bfhi(w[2]), bflo(w[3]), bfhi(w[3])}; }
;                     else { x0 = *(const f32x4*)((const float*)Xin + ro + bj * HALF); x1 = *(const f32x4*)((const float*)Xin + ro + bj * HALF + 4); }
;                     x0 += acc[ai][bj][m][0] * sc[bj][0]; x1 += acc[ai][bj][m][1] * sc[bj][1];
;                     if constexpr (OB) { u32x4 o; o[0] = pack2(x0[0], x0[1]); o[1] = pack2(x0[2], x0[3]); o[2] = pack2(x1[0], x1[1]); o[3] = pack2(x1[2], x1[3]);
;                         *(u32x4*)((bf16_t*)Xout + ro + bj * HALF) = o; }
; template <class Map, class Epi>
; DI void gemm_phase(LAS unsigned char* lds, const Map& MP, const Epi& E, const int nM, const int nN, const int K, const int lda, const int ldb) {
;     ...
;             PG8_WAIT_L(8); PG8_BAR; PG8_WAIT_L(0); PG8_MMA(0, 0, At, B0); PG8_BAR; PG8_SCHED;
;             PG8_LDB(B1, 1, 1); PG8_STAGE(PG8_SB(1, 0), b3, voffB);
;             PG8_BAR; PG8_WAIT_L(0); PG8_MMA(0, 1, At, B1); PG8_BAR;
;             PG8_LDA(At, 1, 1); PG8_STAGE(PG8_SA(1, 0), a3, voffA);
;             PG8_BAR; PG8_WAIT_L(0); PG8_MMA(1, 0, At, B0); PG8_BAR; PG8_SCHED;
;             PG8_STAGE(PG8_SB(1, 1), b3 + hstepB, voffB);
;             PG8_WAIT_V(6); PG8_BAR; PG8_MMA(1, 1, At, B1); PG8_BAR;
	ds_read_b128 v[168:171], v150 offset:49152
	ds_read_b128 v[172:175], v150 offset:50176
	ds_read_b128 v[176:179], v150 offset:51200
	ds_read_b128 v[180:183], v150 offset:52224
	ds_read_b128 v[184:187], v150 offset:53248
	ds_read_b128 v[188:191], v150 offset:54272
	ds_read_b128 v[192:195], v150 offset:55296
	ds_read_b128 v[198:201], v150 offset:56320
	global_load_lds_dwordx4 v[144:145], off
	v_lshl_add_u64 v[144:145], v[222:223], 0, s[42:43]
	s_mov_b32 m0, s31
	s_nop 0
	global_load_lds_dwordx4 v[144:145], off
	s_barrier
	s_setprio 1
	s_waitcnt lgkmcnt(7)
	v_mfma_f32_16x16x32_bf16 v[60:63], v[152:155], v[168:171], v[60:63]
	v_mfma_f32_16x16x32_bf16 v[56:59], v[160:163], v[168:171], v[56:59]
	s_waitcnt lgkmcnt(5)
	v_mfma_f32_16x16x32_bf16 v[44:47], v[152:155], v[176:179], v[44:47]
	v_mfma_f32_16x16x32_bf16 v[40:43], v[160:163], v[176:179], v[40:43]
	s_waitcnt lgkmcnt(3)
	v_mfma_f32_16x16x32_bf16 v[28:31], v[152:155], v[184:187], v[28:31]
	v_mfma_f32_16x16x32_bf16 v[24:27], v[160:163], v[184:187], v[24:27]
	s_waitcnt lgkmcnt(1)
	v_mfma_f32_16x16x32_bf16 v[12:15], v[152:155], v[192:195], v[12:15]
	v_mfma_f32_16x16x32_bf16 v[8:11], v[160:163], v[192:195], v[8:11]
	v_mfma_f32_16x16x32_bf16 v[60:63], v[156:159], v[172:175], v[60:63]
	v_mfma_f32_16x16x32_bf16 v[56:59], v[164:167], v[172:175], v[56:59]
	v_mfma_f32_16x16x32_bf16 v[44:47], v[156:159], v[180:183], v[44:47]
	v_mfma_f32_16x16x32_bf16 v[40:43], v[164:167], v[180:183], v[40:43]
	v_mfma_f32_16x16x32_bf16 v[28:31], v[156:159], v[188:191], v[28:31]
	v_mfma_f32_16x16x32_bf16 v[24:27], v[164:167], v[188:191], v[24:27]
	s_waitcnt lgkmcnt(0)
	v_mfma_f32_16x16x32_bf16 v[12:15], v[156:159], v[198:201], v[12:15]
	v_mfma_f32_16x16x32_bf16 v[8:11], v[164:167], v[198:201], v[8:11]
	s_setprio 0
	s_barrier
	s_add_u32 s12, s12, 0x80080
	s_addc_u32 s13, s13, 0
	s_add_i32 s14, s14, s22
	v_lshl_add_u64 v[144:145], s[12:13], 0, v[132:133]
	s_mov_b32 m0, s14
	s_nop 0
	global_load_lds_dwordx4 v[144:145], off
	v_lshl_add_u64 v[144:145], s[12:13], 0, v[128:129]
	s_add_i32 m0, s14, 0x2000
	s_nop 0
	global_load_lds_dwordx4 v[144:145], off
	s_waitcnt vmcnt(6)
	s_barrier
	s_setprio 1
	v_mfma_f32_16x16x32_bf16 v[52:55], v[202:205], v[168:171], v[52:55]
	v_mfma_f32_16x16x32_bf16 v[48:51], v[210:213], v[168:171], v[48:51]
	v_mfma_f32_16x16x32_bf16 v[36:39], v[202:205], v[176:179], v[36:39]
	v_mfma_f32_16x16x32_bf16 v[32:35], v[210:213], v[176:179], v[32:35]
	v_mfma_f32_16x16x32_bf16 v[20:23], v[202:205], v[184:187], v[20:23]
	v_mfma_f32_16x16x32_bf16 v[16:19], v[210:213], v[184:187], v[16:19]
	v_mfma_f32_16x16x32_bf16 v[4:7], v[202:205], v[192:195], v[4:7]
	v_mfma_f32_16x16x32_bf16 v[0:3], v[210:213], v[192:195], v[0:3]
	v_mfma_f32_16x16x32_bf16 v[52:55], v[206:209], v[172:175], v[52:55]
	v_mfma_f32_16x16x32_bf16 v[48:51], v[214:217], v[172:175], v[48:51]
	v_mfma_f32_16x16x32_bf16 v[36:39], v[206:209], v[180:183], v[36:39]
	v_mfma_f32_16x16x32_bf16 v[32:35], v[214:217], v[180:183], v[32:35]
	v_mfma_f32_16x16x32_bf16 v[20:23], v[206:209], v[188:191], v[20:23]
	v_mfma_f32_16x16x32_bf16 v[16:19], v[214:217], v[188:191], v[16:19]
	v_mfma_f32_16x16x32_bf16 v[4:7], v[206:209], v[198:201], v[4:7]
	v_mfma_f32_16x16x32_bf16 v[0:3], v[214:217], v[198:201], v[0:3]
	s_setprio 0
	s_add_i32 s3, s3, 2
	s_add_u32 s47, s47, 0x100
	s_addc_u32 s48, s48, 0
	s_add_u32 s10, s10, 0x100
	s_addc_u32 s11, s11, 0
	s_cmp_gt_u32 s3, 29
	s_barrier
	s_cbranch_scc0 .LBB1_1764
	v_mov_b32_e32 v152, v147
	v_mov_b32_e32 v144, v146
	s_lshl_b32 s2, s2, 8
	s_or_b32 s2, s2, s29
	v_lshl_add_u32 v144, v144, 3, s2
	s_lshl_b32 s2, s8, 8
	s_add_i32 s2, s2, s28
	v_add_u32_e32 v152, s2, v152
	v_ashrrev_i32_e32 v153, 31, v152
	v_lshlrev_b64 v[152:153], 12, v[152:153]
	v_ashrrev_i32_e32 v145, 31, v144
	v_lshl_add_u64 v[152:153], s[4:5], 0, v[152:153]
	v_lshl_add_u64 v[144:145], v[144:145], 1, v[152:153]
	global_load_dwordx4 v[152:155], v[144:145], off
	s_mov_b64 s[2:3], 0x10000
	s_mov_b32 s8, s46
	s_mov_b64 s[10:11], s[6:7]
	s_mov_b64 s[12:13], s[52:53]
	s_waitcnt vmcnt(0) lgkmcnt(0)
	v_lshlrev_b32_e32 v156, 16, v152
	v_and_b32_e32 v157, 0xffff0000, v152
	v_lshlrev_b32_e32 v152, 16, v153
	v_and_b32_e32 v153, 0xffff0000, v153
	v_lshlrev_b32_e32 v158, 16, v154
	v_and_b32_e32 v159, 0xffff0000, v154
	v_lshlrev_b32_e32 v154, 16, v155
	v_and_b32_e32 v155, 0xffff0000, v155
	v_pk_add_f32 v[126:127], v[126:127], v[152:153]
	v_pk_add_f32 v[124:125], v[124:125], v[156:157]
	v_pk_add_f32 v[152:153], v[122:123], v[154:155]
	v_pk_add_f32 v[122:123], v[120:121], v[158:159]
	v_cvt_pk_bf16_f32 v120, v124, v125
	v_cvt_pk_bf16_f32 v121, v126, v127
	v_cvt_pk_bf16_f32 v122, v122, v123
	v_cvt_pk_bf16_f32 v123, v152, v153
	global_store_dwordx4 v[144:145], v[120:123], off
	global_load_dwordx4 v[120:123], v[144:145], off offset:256
	s_waitcnt vmcnt(0) lgkmcnt(0)
	v_lshlrev_b32_e32 v124, 16, v120
	v_and_b32_e32 v125, 0xffff0000, v120
	v_lshlrev_b32_e32 v120, 16, v121
	v_and_b32_e32 v121, 0xffff0000, v121
	v_lshlrev_b32_e32 v126, 16, v122
	v_and_b32_e32 v127, 0xffff0000, v122
	v_lshlrev_b32_e32 v122, 16, v123
	v_and_b32_e32 v123, 0xffff0000, v123
	v_pk_add_f32 v[116:117], v[116:117], v[124:125]
	v_pk_add_f32 v[118:119], v[118:119], v[120:121]
	v_pk_add_f32 v[120:121], v[114:115], v[122:123]
	v_pk_add_f32 v[114:115], v[112:113], v[126:127]
	v_cvt_pk_bf16_f32 v112, v116, v117
	v_lshl_add_u64 v[116:117], v[144:145], 0, s[2:3]
	s_mov_b32 s2, 0x10000
	v_cvt_pk_bf16_f32 v113, v118, v119
	v_add_co_u32_e32 v118, vcc, s2, v144
	v_cvt_pk_bf16_f32 v114, v114, v115
	v_cvt_pk_bf16_f32 v115, v120, v121
	v_addc_co_u32_e32 v119, vcc, 0, v145, vcc
	global_store_dwordx4 v[144:145], v[112:115], off offset:256
	global_load_dwordx4 v[112:115], v[118:119], off
	s_mov_b64 s[2:3], 0x20000
	s_waitcnt vmcnt(0) lgkmcnt(0)
; DI unsigned pack2(float a, float b) { f32x2 v = {a, b}; hwbf16x2 r = __builtin_convertvector(v, hwbf16x2); return __builtin_bit_cast(unsigned, r); }
; DI float bflo(unsigned w) { return __uint_as_float(w << 16); }
; DI float bfhi(unsigned w) { return __uint_as_float(w & 0xffff0000u); }
;     DI void operator()(const f32x4 (&acc)[2][2][4][2], const Unit& u, int wr, int wc, int fr, int fq) const {
;     ...
;             for (int m = 0; m < 4; ++m) { const size_t ro = (size_t)(row0 + ai * HALF + m * 16) * D + col0;
; #pragma unroll
;                 for (int bj = 0; bj < 2; ++bj) {
;                     f32x4 x0, x1;
;                     if constexpr (IB) { const u32x4 w = *(const u32x4*)((const bf16_t*)Xin + ro + bj * HALF);
;                         x0 = (f32x4){bflo(w[0]), bfhi(w[0]), bflo(w[1]), bfhi(w[1])}; x1 = (f32x4){bflo(w[2]), bfhi(w[2]), bflo(w[3]), bfhi(w[3])}; }
;                     else { x0 = *(const f32x4*)((const float*)Xin + ro + bj * HALF); x1 = *(const f32x4*)((const float*)Xin + ro + bj * HALF + 4); }
;                     x0 += acc[ai][bj][m][0] * sc[bj][0]; x1 += acc[ai][bj][m][1] * sc[bj][1];
;                     if constexpr (OB) { u32x4 o; o[0] = pack2(x0[0], x0[1]); o[1] = pack2(x0[2], x0[3]); o[2] = pack2(x1[0], x1[1]); o[3] = pack2(x1[2], x1[3]);
;                         *(u32x4*)((bf16_t*)Xout + ro + bj * HALF) = o; }
	v_lshlrev_b32_e32 v120, 16, v112
	v_and_b32_e32 v121, 0xffff0000, v112
	v_lshlrev_b32_e32 v112, 16, v113
	v_and_b32_e32 v113, 0xffff0000, v113
	v_lshlrev_b32_e32 v122, 16, v114
	v_and_b32_e32 v123, 0xffff0000, v114
	v_lshlrev_b32_e32 v114, 16, v115
	v_and_b32_e32 v115, 0xffff0000, v115
	v_pk_add_f32 v[110:111], v[110:111], v[112:113]
	v_pk_add_f32 v[108:109], v[108:109], v[120:121]
	v_pk_add_f32 v[112:113], v[106:107], v[114:115]
	v_pk_add_f32 v[106:107], v[104:105], v[122:123]
	v_cvt_pk_bf16_f32 v104, v108, v109
	v_cvt_pk_bf16_f32 v105, v110, v111
	v_cvt_pk_bf16_f32 v106, v106, v107
	v_cvt_pk_bf16_f32 v107, v112, v113
	global_store_dwordx4 v[118:119], v[104:107], off
	global_load_dwordx4 v[104:107], v[116:117], off offset:256
	s_waitcnt vmcnt(0) lgkmcnt(0)
	v_lshlrev_b32_e32 v108, 16, v104
	v_and_b32_e32 v109, 0xffff0000, v104
	v_lshlrev_b32_e32 v104, 16, v105
	v_and_b32_e32 v105, 0xffff0000, v105
	v_lshlrev_b32_e32 v110, 16, v106
	v_and_b32_e32 v111, 0xffff0000, v106
	v_lshlrev_b32_e32 v106, 16, v107
	v_and_b32_e32 v107, 0xffff0000, v107
	v_pk_add_f32 v[100:101], v[100:101], v[108:109]
	v_pk_add_f32 v[102:103], v[102:103], v[104:105]
	v_pk_add_f32 v[104:105], v[98:99], v[106:107]
	v_pk_add_f32 v[98:99], v[96:97], v[110:111]
	v_cvt_pk_bf16_f32 v96, v100, v101
	v_lshl_add_u64 v[100:101], v[144:145], 0, s[2:3]
	s_mov_b32 s2, 0x20000
	v_cvt_pk_bf16_f32 v97, v102, v103
	v_add_co_u32_e32 v102, vcc, s2, v144
	v_cvt_pk_bf16_f32 v98, v98, v99
	v_cvt_pk_bf16_f32 v99, v104, v105
	v_addc_co_u32_e32 v103, vcc, 0, v145, vcc
	global_store_dwordx4 v[116:117], v[96:99], off offset:256
	global_load_dwordx4 v[96:99], v[102:103], off
	s_mov_b64 s[2:3], 0x30000
	s_waitcnt vmcnt(0) lgkmcnt(0)
	v_lshlrev_b32_e32 v104, 16, v96
	v_and_b32_e32 v105, 0xffff0000, v96
	v_lshlrev_b32_e32 v96, 16, v97
	v_and_b32_e32 v97, 0xffff0000, v97
	v_lshlrev_b32_e32 v106, 16, v98
	v_and_b32_e32 v107, 0xffff0000, v98
	v_lshlrev_b32_e32 v98, 16, v99
	v_and_b32_e32 v99, 0xffff0000, v99
	v_pk_add_f32 v[94:95], v[94:95], v[96:97]
	v_pk_add_f32 v[92:93], v[92:93], v[104:105]
	v_pk_add_f32 v[96:97], v[90:91], v[98:99]
	v_pk_add_f32 v[90:91], v[88:89], v[106:107]
	v_cvt_pk_bf16_f32 v88, v92, v93
	v_cvt_pk_bf16_f32 v89, v94, v95
	v_cvt_pk_bf16_f32 v90, v90, v91
	v_cvt_pk_bf16_f32 v91, v96, v97
	global_store_dwordx4 v[102:103], v[88:91], off
	global_load_dwordx4 v[88:91], v[100:101], off offset:256
	s_waitcnt vmcnt(0) lgkmcnt(0)
	v_lshlrev_b32_e32 v92, 16, v88
	v_and_b32_e32 v93, 0xffff0000, v88
	v_lshlrev_b32_e32 v88, 16, v89
	v_and_b32_e32 v89, 0xffff0000, v89
	v_lshlrev_b32_e32 v94, 16, v90
	v_and_b32_e32 v95, 0xffff0000, v90
	v_lshlrev_b32_e32 v90, 16, v91
	v_and_b32_e32 v91, 0xffff0000, v91
	v_pk_add_f32 v[86:87], v[86:87], v[88:89]
	v_pk_add_f32 v[84:85], v[84:85], v[92:93]
	v_pk_add_f32 v[88:89], v[82:83], v[90:91]
	v_pk_add_f32 v[82:83], v[80:81], v[94:95]
	v_cvt_pk_bf16_f32 v80, v84, v85
	v_cvt_pk_bf16_f32 v81, v86, v87
	v_cvt_pk_bf16_f32 v82, v82, v83
	v_cvt_pk_bf16_f32 v83, v88, v89
	global_store_dwordx4 v[100:101], v[80:83], off offset:256
	s_nop 1
	v_lshl_add_u64 v[80:81], v[144:145], 0, s[2:3]
	s_mov_b32 s2, 0x30000
	v_add_co_u32_e32 v86, vcc, s2, v144
	s_mov_b64 s[2:3], 0x80000
	s_nop 0
	v_addc_co_u32_e32 v87, vcc, 0, v145, vcc
	global_load_dwordx4 v[82:85], v[86:87], off
	s_waitcnt vmcnt(0) lgkmcnt(0)
	v_lshlrev_b32_e32 v88, 16, v82
	v_and_b32_e32 v89, 0xffff0000, v82
	v_lshlrev_b32_e32 v82, 16, v83
	v_and_b32_e32 v83, 0xffff0000, v83
	v_lshlrev_b32_e32 v90, 16, v84
	v_and_b32_e32 v91, 0xffff0000, v84
	v_lshlrev_b32_e32 v84, 16, v85
	v_and_b32_e32 v85, 0xffff0000, v85
	v_pk_add_f32 v[78:79], v[78:79], v[82:83]
	v_pk_add_f32 v[76:77], v[76:77], v[88:89]
	v_pk_add_f32 v[82:83], v[74:75], v[84:85]
	v_pk_add_f32 v[74:75], v[72:73], v[90:91]
	v_cvt_pk_bf16_f32 v72, v76, v77
	v_cvt_pk_bf16_f32 v73, v78, v79
	v_cvt_pk_bf16_f32 v74, v74, v75
	v_cvt_pk_bf16_f32 v75, v82, v83
	global_store_dwordx4 v[86:87], v[72:75], off
	global_load_dwordx4 v[72:75], v[80:81], off offset:256
	s_waitcnt vmcnt(0) lgkmcnt(0)
	v_lshlrev_b32_e32 v76, 16, v72
	v_and_b32_e32 v77, 0xffff0000, v72
	v_lshlrev_b32_e32 v72, 16, v73
	v_and_b32_e32 v73, 0xffff0000, v73
	v_lshlrev_b32_e32 v78, 16, v74
	v_and_b32_e32 v79, 0xffff0000, v74
	v_lshlrev_b32_e32 v74, 16, v75
	v_and_b32_e32 v75, 0xffff0000, v75
	v_pk_add_f32 v[70:71], v[70:71], v[72:73]
	v_pk_add_f32 v[68:69], v[68:69], v[76:77]
	v_pk_add_f32 v[72:73], v[66:67], v[74:75]
	v_pk_add_f32 v[66:67], v[64:65], v[78:79]
	v_cvt_pk_bf16_f32 v64, v68, v69
	v_cvt_pk_bf16_f32 v65, v70, v71
	v_cvt_pk_bf16_f32 v66, v66, v67
	v_cvt_pk_bf16_f32 v67, v72, v73
	global_store_dwordx4 v[80:81], v[64:67], off offset:256
	s_nop 1
	v_lshl_add_u64 v[64:65], v[144:145], 0, s[2:3]
	s_mov_b32 s2, 0x80000
	v_add_co_u32_e32 v70, vcc, s2, v144
	s_mov_b64 s[2:3], 0x90000
	s_nop 0
	v_addc_co_u32_e32 v71, vcc, 0, v145, vcc
	global_load_dwordx4 v[66:69], v[70:71], off
	s_waitcnt vmcnt(0) lgkmcnt(0)
	v_lshlrev_b32_e32 v72, 16, v66
	v_and_b32_e32 v73, 0xffff0000, v66
	v_lshlrev_b32_e32 v66, 16, v67
	v_and_b32_e32 v67, 0xffff0000, v67
	v_lshlrev_b32_e32 v74, 16, v68
	v_and_b32_e32 v75, 0xffff0000, v68
	v_lshlrev_b32_e32 v68, 16, v69
	v_and_b32_e32 v69, 0xffff0000, v69
	v_pk_add_f32 v[62:63], v[62:63], v[66:67]
	v_pk_add_f32 v[60:61], v[60:61], v[72:73]
	v_pk_add_f32 v[66:67], v[58:59], v[68:69]
	v_pk_add_f32 v[58:59], v[56:57], v[74:75]
	v_cvt_pk_bf16_f32 v56, v60, v61
	v_cvt_pk_bf16_f32 v57, v62, v63
	v_cvt_pk_bf16_f32 v58, v58, v59
	v_cvt_pk_bf16_f32 v59, v66, v67
	global_store_dwordx4 v[70:71], v[56:59], off
	global_load_dwordx4 v[56:59], v[64:65], off offset:256
	s_waitcnt vmcnt(0) lgkmcnt(0)
; DI unsigned pack2(float a, float b) { f32x2 v = {a, b}; hwbf16x2 r = __builtin_convertvector(v, hwbf16x2); return __builtin_bit_cast(unsigned, r); }
; DI float bflo(unsigned w) { return __uint_as_float(w << 16); }
; DI float bfhi(unsigned w) { return __uint_as_float(w & 0xffff0000u); }
;     DI const char* a(const Unit& u) const { return (const char*)(A + (size_t)u.pm * BM * lda); }
;     DI const char* a(const Unit& u) const { return (const char*)(A + (size_t)u.pm * BM * 2048 + (u.pn >> 1) * 512); }
; #define PG8_BAR __builtin_amdgcn_s_barrier()
;     DI void operator()(const f32x4 (&acc)[2][2][4][2], const Unit& u, int wr, int wc, int fr, int fq) const {
;     ...
;             for (int m = 0; m < 4; ++m) { const size_t ro = (size_t)(row0 + ai * HALF + m * 16) * D + col0;
; #pragma unroll
;                 for (int bj = 0; bj < 2; ++bj) {
;                     f32x4 x0, x1;
;                     if constexpr (IB) { const u32x4 w = *(const u32x4*)((const bf16_t*)Xin + ro + bj * HALF);
;                         x0 = (f32x4){bflo(w[0]), bfhi(w[0]), bflo(w[1]), bfhi(w[1])}; x1 = (f32x4){bflo(w[2]), bfhi(w[2]), bflo(w[3]), bfhi(w[3])}; }
;                     else { x0 = *(const f32x4*)((const float*)Xin + ro + bj * HALF); x1 = *(const f32x4*)((const float*)Xin + ro + bj * HALF + 4); }
;                     x0 += acc[ai][bj][m][0] * sc[bj][0]; x1 += acc[ai][bj][m][1] * sc[bj][1];
;                     if constexpr (OB) { u32x4 o; o[0] = pack2(x0[0], x0[1]); o[1] = pack2(x0[2], x0[3]); o[2] = pack2(x1[0], x1[1]); o[3] = pack2(x1[2], x1[3]);
;                         *(u32x4*)((bf16_t*)Xout + ro + bj * HALF) = o; }
;                     else { *(f32x4*)((float*)Xout + ro + bj * HALF) = x0; *(f32x4*)((float*)Xout + ro + bj * HALF + 4) = x1; } } }
; template <class Map, class Epi>
; DI void gemm_phase(LAS unsigned char* lds, const Map& MP, const Epi& E, const int nM, const int nN, const int K, const int lda, const int ldb) {
;     ...
;         if (!has_next) break;
; #pragma unroll
;         for (int a = 0; a < 2; ++a)
; #pragma unroll
;             for (int b = 0; b < 2; ++b)
; #pragma unroll
;                 for (int m = 0; m < 4; ++m)
; #pragma unroll
;                     for (int n = 0; n < 2; ++n) acc[a][b][m][n] = (f32x4){0.f, 0.f, 0.f, 0.f};
;         cur = nxt; cA = nA; cB = nB; ++ui;
;     }
;     PG8_WAIT_V(0);
;     if (wr == 0) PG8_BAR;
;     PG8_BAR;
	v_lshlrev_b32_e32 v60, 16, v56
	v_and_b32_e32 v61, 0xffff0000, v56
	v_lshlrev_b32_e32 v56, 16, v57
	v_and_b32_e32 v57, 0xffff0000, v57
	v_lshlrev_b32_e32 v62, 16, v58
	v_and_b32_e32 v63, 0xffff0000, v58
	v_lshlrev_b32_e32 v58, 16, v59
	v_and_b32_e32 v59, 0xffff0000, v59
	v_pk_add_f32 v[54:55], v[54:55], v[56:57]
	v_pk_add_f32 v[52:53], v[52:53], v[60:61]
	v_pk_add_f32 v[56:57], v[50:51], v[58:59]
	v_pk_add_f32 v[50:51], v[48:49], v[62:63]
	v_cvt_pk_bf16_f32 v48, v52, v53
	v_cvt_pk_bf16_f32 v49, v54, v55
	v_cvt_pk_bf16_f32 v50, v50, v51
	v_cvt_pk_bf16_f32 v51, v56, v57
	global_store_dwordx4 v[64:65], v[48:51], off offset:256
	s_nop 1
	v_lshl_add_u64 v[48:49], v[144:145], 0, s[2:3]
	s_mov_b32 s2, 0x90000
	v_add_co_u32_e32 v54, vcc, s2, v144
	s_mov_b64 s[2:3], 0xa0000
	s_nop 0
	v_addc_co_u32_e32 v55, vcc, 0, v145, vcc
	global_load_dwordx4 v[50:53], v[54:55], off
	s_waitcnt vmcnt(0) lgkmcnt(0)
	v_lshlrev_b32_e32 v56, 16, v50
	v_and_b32_e32 v57, 0xffff0000, v50
	v_lshlrev_b32_e32 v50, 16, v51
	v_and_b32_e32 v51, 0xffff0000, v51
	v_lshlrev_b32_e32 v58, 16, v52
	v_and_b32_e32 v59, 0xffff0000, v52
	v_lshlrev_b32_e32 v52, 16, v53
	v_and_b32_e32 v53, 0xffff0000, v53
	v_pk_add_f32 v[46:47], v[46:47], v[50:51]
	v_pk_add_f32 v[44:45], v[44:45], v[56:57]
	v_pk_add_f32 v[50:51], v[42:43], v[52:53]
	v_pk_add_f32 v[42:43], v[40:41], v[58:59]
	v_cvt_pk_bf16_f32 v40, v44, v45
	v_cvt_pk_bf16_f32 v41, v46, v47
	v_cvt_pk_bf16_f32 v42, v42, v43
	v_cvt_pk_bf16_f32 v43, v50, v51
	global_store_dwordx4 v[54:55], v[40:43], off
	global_load_dwordx4 v[40:43], v[48:49], off offset:256
	s_waitcnt vmcnt(0) lgkmcnt(0)
	v_lshlrev_b32_e32 v44, 16, v40
	v_and_b32_e32 v45, 0xffff0000, v40
	v_lshlrev_b32_e32 v40, 16, v41
	v_and_b32_e32 v41, 0xffff0000, v41
	v_lshlrev_b32_e32 v46, 16, v42
	v_and_b32_e32 v47, 0xffff0000, v42
	v_lshlrev_b32_e32 v42, 16, v43
	v_and_b32_e32 v43, 0xffff0000, v43
	v_pk_add_f32 v[38:39], v[38:39], v[40:41]
	v_pk_add_f32 v[36:37], v[36:37], v[44:45]
	v_pk_add_f32 v[40:41], v[34:35], v[42:43]
	v_pk_add_f32 v[34:35], v[32:33], v[46:47]
	v_cvt_pk_bf16_f32 v32, v36, v37
	v_cvt_pk_bf16_f32 v33, v38, v39
	v_cvt_pk_bf16_f32 v34, v34, v35
	v_cvt_pk_bf16_f32 v35, v40, v41
	global_store_dwordx4 v[48:49], v[32:35], off offset:256
	s_nop 1
	v_lshl_add_u64 v[32:33], v[144:145], 0, s[2:3]
	s_mov_b32 s2, 0xa0000
	v_add_co_u32_e32 v38, vcc, s2, v144
	s_mov_b64 s[2:3], 0xb0000
	s_nop 0
	v_addc_co_u32_e32 v39, vcc, 0, v145, vcc
	global_load_dwordx4 v[34:37], v[38:39], off
	s_waitcnt vmcnt(0) lgkmcnt(0)
	v_lshlrev_b32_e32 v40, 16, v34
	v_and_b32_e32 v41, 0xffff0000, v34
	v_lshlrev_b32_e32 v34, 16, v35
	v_and_b32_e32 v35, 0xffff0000, v35
	v_lshlrev_b32_e32 v42, 16, v36
	v_and_b32_e32 v43, 0xffff0000, v36
	v_lshlrev_b32_e32 v36, 16, v37
	v_and_b32_e32 v37, 0xffff0000, v37
	v_pk_add_f32 v[30:31], v[30:31], v[34:35]
	v_pk_add_f32 v[28:29], v[28:29], v[40:41]
	v_pk_add_f32 v[34:35], v[26:27], v[36:37]
	v_pk_add_f32 v[26:27], v[24:25], v[42:43]
	v_cvt_pk_bf16_f32 v24, v28, v29
	v_cvt_pk_bf16_f32 v25, v30, v31
	v_cvt_pk_bf16_f32 v26, v26, v27
	v_cvt_pk_bf16_f32 v27, v34, v35
	global_store_dwordx4 v[38:39], v[24:27], off
	global_load_dwordx4 v[24:27], v[32:33], off offset:256
	s_waitcnt vmcnt(0) lgkmcnt(0)
	v_lshlrev_b32_e32 v28, 16, v24
	v_and_b32_e32 v29, 0xffff0000, v24
	v_lshlrev_b32_e32 v24, 16, v25
	v_and_b32_e32 v25, 0xffff0000, v25
	v_lshlrev_b32_e32 v30, 16, v26
	v_and_b32_e32 v31, 0xffff0000, v26
	v_lshlrev_b32_e32 v26, 16, v27
	v_and_b32_e32 v27, 0xffff0000, v27
	v_pk_add_f32 v[22:23], v[22:23], v[24:25]
	v_pk_add_f32 v[20:21], v[20:21], v[28:29]
	v_pk_add_f32 v[24:25], v[18:19], v[26:27]
	v_pk_add_f32 v[18:19], v[16:17], v[30:31]
	v_cvt_pk_bf16_f32 v16, v20, v21
	v_cvt_pk_bf16_f32 v17, v22, v23
	v_cvt_pk_bf16_f32 v18, v18, v19
	v_cvt_pk_bf16_f32 v19, v24, v25
	global_store_dwordx4 v[32:33], v[16:19], off offset:256
	s_nop 1
	v_lshl_add_u64 v[16:17], v[144:145], 0, s[2:3]
	s_mov_b32 s2, 0xb0000
	v_add_co_u32_e32 v22, vcc, s2, v144
	s_mov_b32 s2, s44
	s_nop 0
	v_addc_co_u32_e32 v23, vcc, 0, v145, vcc
	global_load_dwordx4 v[18:21], v[22:23], off
	s_and_b64 vcc, exec, s[40:41]
	s_waitcnt vmcnt(0) lgkmcnt(0)
	v_lshlrev_b32_e32 v24, 16, v18
	v_and_b32_e32 v25, 0xffff0000, v18
	v_lshlrev_b32_e32 v18, 16, v19
	v_and_b32_e32 v19, 0xffff0000, v19
	v_lshlrev_b32_e32 v26, 16, v20
	v_and_b32_e32 v27, 0xffff0000, v20
	v_lshlrev_b32_e32 v20, 16, v21
	v_and_b32_e32 v21, 0xffff0000, v21
	v_pk_add_f32 v[14:15], v[14:15], v[18:19]
	v_pk_add_f32 v[12:13], v[12:13], v[24:25]
	v_pk_add_f32 v[18:19], v[10:11], v[20:21]
	v_pk_add_f32 v[10:11], v[8:9], v[26:27]
	v_cvt_pk_bf16_f32 v8, v12, v13
	v_cvt_pk_bf16_f32 v9, v14, v15
	v_cvt_pk_bf16_f32 v10, v10, v11
	v_cvt_pk_bf16_f32 v11, v18, v19
	global_store_dwordx4 v[22:23], v[8:11], off
	global_load_dwordx4 v[8:11], v[16:17], off offset:256
	s_waitcnt vmcnt(0) lgkmcnt(0)
	v_lshlrev_b32_e32 v12, 16, v8
	v_and_b32_e32 v13, 0xffff0000, v8
	v_lshlrev_b32_e32 v8, 16, v9
	v_and_b32_e32 v9, 0xffff0000, v9
	v_lshlrev_b32_e32 v14, 16, v10
	v_and_b32_e32 v15, 0xffff0000, v10
	v_lshlrev_b32_e32 v10, 16, v11
	v_and_b32_e32 v11, 0xffff0000, v11
	v_pk_add_f32 v[6:7], v[6:7], v[8:9]
	v_pk_add_f32 v[4:5], v[4:5], v[12:13]
	v_pk_add_f32 v[8:9], v[2:3], v[10:11]
	v_pk_add_f32 v[2:3], v[0:1], v[14:15]
	v_cvt_pk_bf16_f32 v0, v4, v5
	v_cvt_pk_bf16_f32 v1, v6, v7
	v_cvt_pk_bf16_f32 v2, v2, v3
	v_cvt_pk_bf16_f32 v3, v8, v9
	global_store_dwordx4 v[16:17], v[0:3], off offset:256
	s_cbranch_vccz .LBB1_1761
	s_waitcnt vmcnt(0)
	s_cmpk_gt_u32 s17, 0xff
	s_cbranch_scc1 .LBB1_1768
	s_barrier

; DI float bflo(unsigned w) { return __uint_as_float(w << 16); }
; DI float bfhi(unsigned w) { return __uint_as_float(w & 0xffff0000u); }
; DI float wave_sum(float v) { for (int o = 32; o; o >>= 1) v += __shfl_xor(v, o); return v; }
; template <bool BF> DI void norm_phase(const Params& p, const void* x, const float* gain) {
;     ...
;     for (int t = bid * 8 + wid; t < T; t += 2 * step) {
;         const int t2 = (t + step < T) ? t + step : t;
;         f32x4 v[2][8];
; #pragma unroll
;         for (int q = 0; q < 2; ++q) {
;             const int tt = q ? t2 : t;
; #pragma unroll
;             for (int i = 0; i < 4; ++i) {
;                 const size_t e = (size_t)tt * D + (i * 64 + lane) * 8;
;                 if constexpr (BF) { const u32x4 w = *(const u32x4*)((const bf16_t*)x + e);
;                     v[q][2 * i] = (f32x4){bflo(w[0]), bfhi(w[0]), bflo(w[1]), bfhi(w[1])}; v[q][2 * i + 1] = (f32x4){bflo(w[2]), bfhi(w[2]), bflo(w[3]), bfhi(w[3])}; }
;                 else { v[q][2 * i] = *(const f32x4*)((const float*)x + e); v[q][2 * i + 1] = *(const f32x4*)((const float*)x + e + 4); }
;             }
;         }
;         float ss[2] = {0.f, 0.f};
; #pragma unroll
;         for (int q = 0; q < 2; ++q)
; #pragma unroll
;             for (int i = 0; i < 8; ++i) ss[q] += v[q][i][0] * v[q][i][0] + v[q][i][1] * v[q][i][1] + v[q][i][2] * v[q][i][2] + v[q][i][3] * v[q][i][3];
;         ss[0] = wave_sum(ss[0]); ss[1] = wave_sum(ss[1]);
.LBB1_1835:
	v_add_u32_e32 v87, s33, v14
	v_cmp_gt_i32_e32 vcc, s2, v87
	v_ashrrev_i32_e32 v15, 31, v14
	global_load_dwordx4 v[88:91], v[0:1], off offset:16
	global_load_dwordx4 v[92:95], v[0:1], off
	v_cndmask_b32_e32 v30, v14, v87, vcc
	v_ashrrev_i32_e32 v31, 31, v30
	v_lshlrev_b64 v[14:15], 12, v[14:15]
	v_lshlrev_b64 v[36:37], 12, v[30:31]
	v_lshl_add_u64 v[26:27], v[8:9], 0, v[14:15]
	v_lshl_add_u64 v[30:31], v[8:9], 0, v[36:37]
	v_lshl_add_u64 v[60:61], v[10:11], 0, v[14:15]
	global_load_dwordx4 v[14:17], v[26:27], off offset:2048
	global_load_dwordx4 v[18:21], v[26:27], off offset:3072
	global_load_dwordx4 v[22:25], v[26:27], off
	s_nop 0
	global_load_dwordx4 v[26:29], v[26:27], off offset:1024
	s_nop 0
	global_load_dwordx4 v[96:99], v[30:31], off offset:2048
	global_load_dwordx4 v[100:103], v[30:31], off
	global_load_dwordx4 v[104:107], v[30:31], off offset:1024
	global_load_dwordx4 v[108:111], v[30:31], off offset:3072
	v_lshl_add_u64 v[36:37], v[10:11], 0, v[36:37]
	s_waitcnt vmcnt(0) lgkmcnt(0)
	v_and_b32_e32 v79, 0xffff0000, v14
	v_and_b32_e32 v78, 0xffff0000, v16
	v_and_b32_e32 v71, 0xffff0000, v18
	v_and_b32_e32 v70, 0xffff0000, v20
	v_and_b32_e32 v49, 0xffff0000, v22
	v_and_b32_e32 v53, 0xffff0000, v24
	v_and_b32_e32 v48, 0xffff0000, v100
	v_and_b32_e32 v52, 0xffff0000, v102
	v_lshlrev_b32_e32 v75, 16, v14
	v_lshlrev_b32_e32 v74, 16, v16
	v_lshlrev_b32_e32 v77, 16, v15
	v_and_b32_e32 v81, 0xffff0000, v15
	v_lshlrev_b32_e32 v67, 16, v18
	v_lshlrev_b32_e32 v66, 16, v20
	v_lshlrev_b32_e32 v68, 16, v21
	v_and_b32_e32 v72, 0xffff0000, v21
	v_lshlrev_b32_e32 v41, 16, v22
	v_lshlrev_b32_e32 v45, 16, v24
	v_lshlrev_b32_e32 v47, 16, v25
	v_and_b32_e32 v55, 0xffff0000, v25
	v_lshlrev_b32_e32 v15, 16, v26
	v_and_b32_e32 v39, 0xffff0000, v26
	v_pk_mul_f32 v[20:21], v[78:79], v[78:79]
	v_pk_mul_f32 v[24:25], v[70:71], v[70:71]
	v_and_b32_e32 v63, 0xffff0000, v96
	v_and_b32_e32 v62, 0xffff0000, v98
	v_lshlrev_b32_e32 v40, 16, v100
	v_lshlrev_b32_e32 v44, 16, v102
	v_lshlrev_b32_e32 v46, 16, v103
	v_and_b32_e32 v54, 0xffff0000, v103
	v_lshlrev_b32_e32 v14, 16, v104
	v_and_b32_e32 v38, 0xffff0000, v104
	v_lshlrev_b32_e32 v16, 16, v105
	v_and_b32_e32 v26, 0xffff0000, v105
	v_and_b32_e32 v31, 0xffff0000, v108
	v_and_b32_e32 v30, 0xffff0000, v110
	v_pk_mul_f32 v[102:103], v[48:49], v[48:49]
	v_pk_mul_f32 v[104:105], v[52:53], v[52:53]
	v_lshlrev_b32_e32 v69, 16, v19
	v_and_b32_e32 v73, 0xffff0000, v19
	v_lshlrev_b32_e32 v43, 16, v23
	v_lshlrev_b32_e32 v19, 16, v28
	v_and_b32_e32 v33, 0xffff0000, v28
	v_pk_fma_f32 v[120:121], v[74:75], v[74:75], v[20:21]
	v_pk_fma_f32 v[122:123], v[66:67], v[66:67], v[24:25]
	v_lshlrev_b32_e32 v57, 16, v96
	v_lshlrev_b32_e32 v56, 16, v98
	v_lshlrev_b32_e32 v42, 16, v101
	v_and_b32_e32 v50, 0xffff0000, v101
	v_lshlrev_b32_e32 v18, 16, v106
	v_and_b32_e32 v32, 0xffff0000, v106
	v_lshlrev_b32_e32 v22, 16, v107
	v_and_b32_e32 v28, 0xffff0000, v107
	v_lshlrev_b32_e32 v21, 16, v108
	v_lshlrev_b32_e32 v20, 16, v110
	v_lshlrev_b32_e32 v24, 16, v111
	v_and_b32_e32 v34, 0xffff0000, v111
	v_pk_mul_f32 v[100:101], v[62:63], v[62:63]
	v_pk_mul_f32 v[106:107], v[38:39], v[38:39]
	v_pk_mul_f32 v[110:111], v[30:31], v[30:31]
	v_pk_fma_f32 v[102:103], v[40:41], v[40:41], v[102:103]
	v_pk_fma_f32 v[104:105], v[44:45], v[44:45], v[104:105]
	v_lshlrev_b32_e32 v76, 16, v17
	v_and_b32_e32 v80, 0xffff0000, v17
	v_and_b32_e32 v51, 0xffff0000, v23
	v_lshlrev_b32_e32 v17, 16, v27
	v_lshlrev_b32_e32 v59, 16, v97
	v_lshlrev_b32_e32 v58, 16, v99
	v_lshlrev_b32_e32 v25, 16, v109
	v_and_b32_e32 v35, 0xffff0000, v109
	v_pk_mul_f32 v[108:109], v[32:33], v[32:33]
	v_pk_fma_f32 v[100:101], v[56:57], v[56:57], v[100:101]
	v_pk_fma_f32 v[106:107], v[14:15], v[14:15], v[106:107]
	v_pk_fma_f32 v[110:111], v[20:21], v[20:21], v[110:111]
	v_pk_fma_f32 v[102:103], v[42:43], v[42:43], v[102:103]
	v_pk_fma_f32 v[104:105], v[46:47], v[46:47], v[104:105]
	v_and_b32_e32 v27, 0xffff0000, v27
	v_lshlrev_b32_e32 v23, 16, v29
	v_and_b32_e32 v65, 0xffff0000, v97
	v_and_b32_e32 v64, 0xffff0000, v99
	v_pk_fma_f32 v[96:97], v[76:77], v[76:77], v[120:121]
	v_pk_fma_f32 v[98:99], v[68:69], v[68:69], v[122:123]
	v_pk_fma_f32 v[108:109], v[18:19], v[18:19], v[108:109]
	v_pk_fma_f32 v[100:101], v[58:59], v[58:59], v[100:101]
	v_pk_fma_f32 v[106:107], v[16:17], v[16:17], v[106:107]
	v_pk_fma_f32 v[110:111], v[24:25], v[24:25], v[110:111]
	v_pk_fma_f32 v[102:103], v[50:51], v[50:51], v[102:103]
	v_pk_fma_f32 v[104:105], v[54:55], v[54:55], v[104:105]
	v_and_b32_e32 v29, 0xffff0000, v29
	v_pk_fma_f32 v[96:97], v[80:81], v[80:81], v[96:97]
	v_pk_fma_f32 v[98:99], v[72:73], v[72:73], v[98:99]
	v_pk_fma_f32 v[108:109], v[22:23], v[22:23], v[108:109]
	v_pk_fma_f32 v[100:101], v[64:65], v[64:65], v[100:101]
	v_pk_fma_f32 v[106:107], v[26:27], v[26:27], v[106:107]
	v_pk_fma_f32 v[110:111], v[34:35], v[34:35], v[110:111]
	v_pk_add_f32 v[102:103], v[102:103], v[104:105]
	v_mov_b32_e32 v121, v97
	v_mov_b32_e32 v97, v99
	v_pk_fma_f32 v[108:109], v[28:29], v[28:29], v[108:109]
	v_mov_b32_e32 v120, v101
	v_mov_b32_e32 v101, v96
	v_mov_b32_e32 v96, v111
	v_mov_b32_e32 v111, v98
	v_pk_add_f32 v[98:99], v[102:103], v[106:107]
	v_mov_b32_e32 v112, v41
	v_pk_add_f32 v[98:99], v[108:109], v[98:99]
	v_mov_b32_e32 v114, v43
	v_pk_add_f32 v[98:99], v[120:121], v[98:99]
	v_mov_b32_e32 v113, v49
	v_pk_add_f32 v[98:99], v[100:101], v[98:99]
	v_mov_b32_e32 v115, v51
	v_pk_add_f32 v[96:97], v[96:97], v[98:99]
	v_mov_b32_e32 v116, v45
	v_pk_add_f32 v[96:97], v[110:111], v[96:97]
	ds_bpermute_b32 v99, v13, v97
	ds_bpermute_b32 v98, v13, v96
	v_mov_b32_e32 v117, v53
	v_mov_b32_e32 v118, v47
	v_mov_b32_e32 v119, v55
	v_mov_b32_e32 v45, v52
	s_waitcnt lgkmcnt(0)
; DI unsigned pack2(float a, float b) { f32x2 v = {a, b}; hwbf16x2 r = __builtin_convertvector(v, hwbf16x2); return __builtin_bit_cast(unsigned, r); }
; DI float wave_sum(float v) { for (int o = 32; o; o >>= 1) v += __shfl_xor(v, o); return v; }
;     DI const char* a(const Unit& u) const { return (const char*)(A + (size_t)u.pm * BM * lda); }
;     DI const char* a(const Unit& u) const { return (const char*)(A + (size_t)u.pm * BM * 2048 + (u.pn >> 1) * 512); }
;     DI const char* a(const Unit& u) const { return (const char*)((u.pn < 12 ? A1 : A2) + (size_t)u.pm * BM * 512); }
; template <bool BF> DI void norm_phase(const Params& p, const void* x, const float* gain) {
;     ...
;         ss[0] = wave_sum(ss[0]); ss[1] = wave_sum(ss[1]);
; #pragma unroll
;         for (int q = 0; q < 2; ++q) {
;             const int tt = q ? t2 : t;
;             const float rs = rsqrtf(ss[q] * (1.0f / D) + EPS);
; #pragma unroll
;             for (int i = 0; i < 4; ++i) { const int c = (i * 64 + lane) * 8;
;                 const f32x4 g0 = *(const f32x4*)(gain + c), g1 = *(const f32x4*)(gain + c + 4);
;                 const f32x4 a = v[q][2 * i] * rs * g0, d = v[q][2 * i + 1] * rs * g1;
;                 u32x4 o; o[0] = pack2(a[0], a[1]); o[1] = pack2(a[2], a[3]); o[2] = pack2(d[0], d[1]); o[3] = pack2(d[2], d[3]);
;                 *(u32x4*)(H + (size_t)tt * D + c) = o; }
	v_pk_add_f32 v[96:97], v[96:97], v[98:99]
	ds_bpermute_b32 v99, v82, v97
	ds_bpermute_b32 v98, v82, v96
	v_mov_b32_e32 v47, v54
	s_waitcnt lgkmcnt(0)
	v_pk_add_f32 v[96:97], v[96:97], v[98:99]
	ds_bpermute_b32 v99, v83, v97
	ds_bpermute_b32 v98, v83, v96
	s_waitcnt lgkmcnt(0)
	v_pk_add_f32 v[96:97], v[96:97], v[98:99]
	ds_bpermute_b32 v99, v84, v97
	ds_bpermute_b32 v98, v84, v96
	s_waitcnt lgkmcnt(0)
	v_pk_add_f32 v[96:97], v[96:97], v[98:99]
	ds_bpermute_b32 v99, v85, v97
	ds_bpermute_b32 v98, v85, v96
	s_waitcnt lgkmcnt(0)
	v_pk_add_f32 v[96:97], v[96:97], v[98:99]
	ds_bpermute_b32 v99, v86, v97
	ds_bpermute_b32 v98, v86, v96
	s_waitcnt lgkmcnt(0)
	v_pk_add_f32 v[96:97], v[96:97], v[98:99]
	s_nop 0
	v_pk_fma_f32 v[96:97], v[96:97], s[8:9], v[12:13] op_sel_hi:[1,0,0]
	s_nop 0
	v_mul_f32_e32 v41, 0x4b800000, v97
	v_cmp_gt_f32_e32 vcc, s3, v97
	s_nop 1
	v_cndmask_b32_e32 v41, v97, v41, vcc
	v_rsq_f32_e32 v41, v41
	s_nop 0
	v_mul_f32_e32 v43, 0x45800000, v41
	v_cndmask_b32_e32 v98, v41, v43, vcc
	v_pk_mul_f32 v[100:101], v[98:99], v[112:113] op_sel_hi:[0,1]
	v_pk_mul_f32 v[102:103], v[98:99], v[114:115] op_sel_hi:[0,1]
	v_pk_mul_f32 v[104:105], v[98:99], v[116:117] op_sel_hi:[0,1]
	v_pk_mul_f32 v[106:107], v[98:99], v[118:119] op_sel_hi:[0,1]
	v_pk_mul_f32 v[94:95], v[94:95], v[102:103]
	v_pk_mul_f32 v[92:93], v[92:93], v[100:101]
	v_pk_mul_f32 v[100:101], v[90:91], v[106:107]
	v_pk_mul_f32 v[90:91], v[88:89], v[104:105]
	v_cvt_pk_bf16_f32 v88, v92, v93
	v_cvt_pk_bf16_f32 v89, v94, v95
	v_cvt_pk_bf16_f32 v90, v90, v91
	v_cvt_pk_bf16_f32 v91, v100, v101
	global_store_dwordx4 v[60:61], v[88:91], off
	global_load_dwordx4 v[88:91], v[2:3], off
	s_nop 0
	global_load_dwordx4 v[92:95], v[2:3], off offset:16
	v_mov_b32_e32 v100, v15
	v_mov_b32_e32 v101, v39
	v_mov_b32_e32 v102, v17
	v_mov_b32_e32 v103, v27
	v_mov_b32_e32 v104, v19
	v_mov_b32_e32 v105, v33
	v_mov_b32_e32 v106, v23
	v_mov_b32_e32 v107, v29
	v_pk_mul_f32 v[100:101], v[98:99], v[100:101] op_sel_hi:[0,1]
	v_pk_mul_f32 v[102:103], v[98:99], v[102:103] op_sel_hi:[0,1]
	v_pk_mul_f32 v[104:105], v[98:99], v[104:105] op_sel_hi:[0,1]
	v_pk_mul_f32 v[106:107], v[98:99], v[106:107] op_sel_hi:[0,1]
	v_mul_f32_e32 v15, 0x4b800000, v96
	v_cmp_gt_f32_e32 vcc, s3, v96
	v_mov_b32_e32 v41, v48
	v_mov_b32_e32 v43, v50
	v_cndmask_b32_e32 v15, v96, v15, vcc
	v_rsq_f32_e32 v15, v15
	v_mov_b32_e32 v19, v32
	v_mov_b32_e32 v23, v28
	v_mul_f32_e32 v17, 0x45800000, v15
	v_cndmask_b32_e32 v48, v15, v17, vcc
	v_pk_mul_f32 v[40:41], v[48:49], v[40:41] op_sel_hi:[0,1]
	v_pk_mul_f32 v[42:43], v[48:49], v[42:43] op_sel_hi:[0,1]
	v_pk_mul_f32 v[44:45], v[48:49], v[44:45] op_sel_hi:[0,1]
	v_pk_mul_f32 v[46:47], v[48:49], v[46:47] op_sel_hi:[0,1]
	v_mov_b32_e32 v15, v38
	v_mov_b32_e32 v17, v26
	v_pk_mul_f32 v[14:15], v[48:49], v[14:15] op_sel_hi:[0,1]
	v_pk_mul_f32 v[16:17], v[48:49], v[16:17] op_sel_hi:[0,1]
	v_pk_mul_f32 v[18:19], v[48:49], v[18:19] op_sel_hi:[0,1]
	v_pk_mul_f32 v[22:23], v[48:49], v[22:23] op_sel_hi:[0,1]
	s_waitcnt vmcnt(0)
	v_pk_mul_f32 v[90:91], v[90:91], v[102:103]
	v_pk_mul_f32 v[88:89], v[88:89], v[100:101]
	v_pk_mul_f32 v[94:95], v[94:95], v[106:107]
	v_pk_mul_f32 v[92:93], v[92:93], v[104:105]
	v_cvt_pk_bf16_f32 v88, v88, v89
	v_cvt_pk_bf16_f32 v89, v90, v91
	v_cvt_pk_bf16_f32 v90, v92, v93
	v_cvt_pk_bf16_f32 v91, v94, v95
	global_store_dwordx4 v[60:61], v[88:91], off offset:1024
	global_load_dwordx4 v[88:91], v[4:5], off
	s_nop 0
	global_load_dwordx4 v[92:95], v[4:5], off offset:16
	v_mov_b32_e32 v100, v75
	v_mov_b32_e32 v101, v79
	v_mov_b32_e32 v102, v77
	v_mov_b32_e32 v103, v81
	v_mov_b32_e32 v75, v78
	v_mov_b32_e32 v77, v80
	v_pk_mul_f32 v[78:79], v[98:99], v[100:101] op_sel_hi:[0,1]
	v_pk_mul_f32 v[80:81], v[98:99], v[102:103] op_sel_hi:[0,1]
	v_pk_mul_f32 v[74:75], v[98:99], v[74:75] op_sel_hi:[0,1]
	v_pk_mul_f32 v[76:77], v[98:99], v[76:77] op_sel_hi:[0,1]
	s_waitcnt vmcnt(0)
; DI unsigned pack2(float a, float b) { f32x2 v = {a, b}; hwbf16x2 r = __builtin_convertvector(v, hwbf16x2); return __builtin_bit_cast(unsigned, r); }
;     DI const char* a(const Unit& u) const { return (const char*)(A + (size_t)u.pm * BM * lda); }
;     DI const char* a(const Unit& u) const { return (const char*)(A + (size_t)u.pm * BM * 2048 + (u.pn >> 1) * 512); }
;     DI const char* a(const Unit& u) const { return (const char*)((u.pn < 12 ? A1 : A2) + (size_t)u.pm * BM * 512); }
; template <bool BF> DI void norm_phase(const Params& p, const void* x, const float* gain) {
;     ...
;     for (int t = bid * 8 + wid; t < T; t += 2 * step) {
;     ...
;         for (int q = 0; q < 2; ++q) {
;             const int tt = q ? t2 : t;
;             const float rs = rsqrtf(ss[q] * (1.0f / D) + EPS);
; #pragma unroll
;             for (int i = 0; i < 4; ++i) { const int c = (i * 64 + lane) * 8;
;                 const f32x4 g0 = *(const f32x4*)(gain + c), g1 = *(const f32x4*)(gain + c + 4);
;                 const f32x4 a = v[q][2 * i] * rs * g0, d = v[q][2 * i + 1] * rs * g1;
;                 u32x4 o; o[0] = pack2(a[0], a[1]); o[1] = pack2(a[2], a[3]); o[2] = pack2(d[0], d[1]); o[3] = pack2(d[2], d[3]);
;                 *(u32x4*)(H + (size_t)tt * D + c) = o; }
;         }
	v_pk_mul_f32 v[80:81], v[90:91], v[80:81]
	v_pk_mul_f32 v[78:79], v[88:89], v[78:79]
	v_pk_mul_f32 v[88:89], v[94:95], v[76:77]
	v_pk_mul_f32 v[76:77], v[92:93], v[74:75]
	v_cvt_pk_bf16_f32 v74, v78, v79
	v_cvt_pk_bf16_f32 v75, v80, v81
	v_cvt_pk_bf16_f32 v76, v76, v77
	v_cvt_pk_bf16_f32 v77, v88, v89
	global_store_dwordx4 v[60:61], v[74:77], off offset:2048
	global_load_dwordx4 v[74:77], v[6:7], off
	s_nop 0
	global_load_dwordx4 v[78:81], v[6:7], off offset:16
	v_mov_b32_e32 v88, v67
	v_mov_b32_e32 v89, v71
	v_mov_b32_e32 v90, v69
	v_mov_b32_e32 v91, v73
	v_mov_b32_e32 v67, v70
	v_mov_b32_e32 v69, v72
	v_pk_mul_f32 v[70:71], v[98:99], v[88:89] op_sel_hi:[0,1]
	v_pk_mul_f32 v[72:73], v[98:99], v[90:91] op_sel_hi:[0,1]
	v_pk_mul_f32 v[66:67], v[98:99], v[66:67] op_sel_hi:[0,1]
	v_pk_mul_f32 v[68:69], v[98:99], v[68:69] op_sel_hi:[0,1]
	s_waitcnt vmcnt(0)
	v_pk_mul_f32 v[72:73], v[76:77], v[72:73]
	v_pk_mul_f32 v[70:71], v[74:75], v[70:71]
	v_pk_mul_f32 v[74:75], v[80:81], v[68:69]
	v_pk_mul_f32 v[68:69], v[78:79], v[66:67]
	v_cvt_pk_bf16_f32 v66, v70, v71
	v_cvt_pk_bf16_f32 v67, v72, v73
	v_cvt_pk_bf16_f32 v68, v68, v69
	v_cvt_pk_bf16_f32 v69, v74, v75
	global_store_dwordx4 v[60:61], v[66:69], off offset:3072
	global_load_dwordx4 v[66:69], v[0:1], off
	s_nop 0
	global_load_dwordx4 v[70:73], v[0:1], off offset:16
	s_waitcnt vmcnt(0)
	v_pk_mul_f32 v[42:43], v[68:69], v[42:43]
	v_pk_mul_f32 v[40:41], v[66:67], v[40:41]
	v_pk_mul_f32 v[46:47], v[72:73], v[46:47]
	v_pk_mul_f32 v[44:45], v[70:71], v[44:45]
	v_cvt_pk_bf16_f32 v40, v40, v41
	v_cvt_pk_bf16_f32 v41, v42, v43
	v_cvt_pk_bf16_f32 v42, v44, v45
	v_cvt_pk_bf16_f32 v43, v46, v47
	global_store_dwordx4 v[36:37], v[40:43], off
	global_load_dwordx4 v[40:43], v[2:3], off
	s_nop 0
	global_load_dwordx4 v[44:47], v[2:3], off offset:16
	s_waitcnt vmcnt(0)
	v_pk_mul_f32 v[16:17], v[16:17], v[42:43]
	v_pk_mul_f32 v[14:15], v[14:15], v[40:41]
	v_pk_mul_f32 v[22:23], v[22:23], v[46:47]
	v_pk_mul_f32 v[18:19], v[18:19], v[44:45]
	v_cvt_pk_bf16_f32 v14, v14, v15
	v_cvt_pk_bf16_f32 v15, v16, v17
	v_cvt_pk_bf16_f32 v16, v18, v19
	v_cvt_pk_bf16_f32 v17, v22, v23
	global_store_dwordx4 v[36:37], v[14:17], off offset:1024
	global_load_dwordx4 v[14:17], v[4:5], off
	s_nop 0
	global_load_dwordx4 v[26:29], v[4:5], off offset:16
	v_mov_b32_e32 v18, v57
	v_mov_b32_e32 v19, v63
	v_mov_b32_e32 v22, v59
	v_mov_b32_e32 v23, v65
	v_mov_b32_e32 v57, v62
	v_mov_b32_e32 v59, v64
	v_pk_mul_f32 v[18:19], v[48:49], v[18:19] op_sel_hi:[0,1]
	v_pk_mul_f32 v[22:23], v[48:49], v[22:23] op_sel_hi:[0,1]
	v_pk_mul_f32 v[32:33], v[48:49], v[56:57] op_sel_hi:[0,1]
	v_pk_mul_f32 v[38:39], v[48:49], v[58:59] op_sel_hi:[0,1]
	s_waitcnt vmcnt(0)
	v_pk_mul_f32 v[16:17], v[22:23], v[16:17]
	v_pk_mul_f32 v[14:15], v[18:19], v[14:15]
	v_pk_mul_f32 v[18:19], v[38:39], v[28:29]
	v_pk_mul_f32 v[22:23], v[32:33], v[26:27]
	v_cvt_pk_bf16_f32 v14, v14, v15
	v_cvt_pk_bf16_f32 v15, v16, v17
	v_cvt_pk_bf16_f32 v16, v22, v23
	v_cvt_pk_bf16_f32 v17, v18, v19
	global_store_dwordx4 v[36:37], v[14:17], off offset:2048
	global_load_dwordx4 v[16:19], v[6:7], off
	s_nop 0
	global_load_dwordx4 v[26:29], v[6:7], off offset:16
	v_mov_b32_e32 v22, v21
	v_mov_b32_e32 v23, v31
	v_mov_b32_e32 v32, v25
	v_mov_b32_e32 v33, v35
	v_mov_b32_e32 v21, v30
	v_mov_b32_e32 v25, v34
	v_add_u32_e32 v14, s33, v87
	v_pk_mul_f32 v[22:23], v[48:49], v[22:23] op_sel_hi:[0,1]
	v_pk_mul_f32 v[30:31], v[48:49], v[32:33] op_sel_hi:[0,1]
	v_pk_mul_f32 v[20:21], v[48:49], v[20:21] op_sel_hi:[0,1]
	v_pk_mul_f32 v[24:25], v[48:49], v[24:25] op_sel_hi:[0,1]
	v_cmp_lt_i32_e32 vcc, s9, v14
	s_or_b64 s[6:7], vcc, s[6:7]
	s_waitcnt vmcnt(0)
	v_pk_mul_f32 v[18:19], v[30:31], v[18:19]
	v_pk_mul_f32 v[16:17], v[22:23], v[16:17]
	v_pk_mul_f32 v[22:23], v[24:25], v[28:29]
	v_pk_mul_f32 v[20:21], v[20:21], v[26:27]
	v_cvt_pk_bf16_f32 v16, v16, v17
	v_cvt_pk_bf16_f32 v17, v18, v19
	v_cvt_pk_bf16_f32 v18, v20, v21
	v_cvt_pk_bf16_f32 v19, v22, v23
	global_store_dwordx4 v[36:37], v[16:19], off offset:3072
	s_andn2_b64 exec, exec, s[6:7]
	s_cbranch_execnz .LBB1_1835

; #define PG8_STAGE(bufoff, gbase, voff) do { _Pragma("unroll") for (int _i = 0; _i < 2; ++_i) \
;         __builtin_amdgcn_global_load_lds((const unsigned*)((const char*)(gbase) + (voff)[_i]), (LAS unsigned*)(lds + (bufoff) + ldsw + _i * 8192), 16, 0, 0); } while (0)
; #define PG8_LDA(dst, b, h) do { _Pragma("unroll") for (int m = 0; m < 4; ++m) _Pragma("unroll") for (int k = 0; k < 2; ++k) dst[m][k] = *(const LAS bf16x8*)(lds + PG8_SA(b, h) + aoff + m * 2048 + k * 1024); } while (0)
; #define PG8_LDB(dst, b, h) do { _Pragma("unroll") for (int n = 0; n < 2; ++n) _Pragma("unroll") for (int k = 0; k < 2; ++k) dst[n][k] = *(const LAS bf16x8*)(lds + PG8_SB(b, h) + boff + n * 2048 + k * 1024); } while (0)
; #define PG8_MMA(ai, bj, At, Bt) do { __builtin_amdgcn_s_setprio(1); _Pragma("unroll") for (int m = 0; m < 4; ++m) _Pragma("unroll") for (int n = 0; n < 2; ++n) _Pragma("unroll") for (int k = 0; k < 2; ++k) \
;         acc[ai][bj][m][n] = __builtin_amdgcn_mfma_f32_16x16x32_bf16(Bt[n][k], At[m][k], acc[ai][bj][m][n], 0, 0, 0); __builtin_amdgcn_s_setprio(0); } while (0)
; #define PG8_WAIT_V(n) asm volatile("s_waitcnt vmcnt(" #n ")" ::: "memory")
; #define PG8_WAIT_L(n) asm volatile("s_waitcnt lgkmcnt(" #n ")" ::: "memory")
; #define PG8_BAR __builtin_amdgcn_s_barrier()
; #define PG8_SCHED __builtin_amdgcn_sched_barrier(0)
; template <class Map, class Epi>
; DI void gemm_phase(LAS unsigned char* lds, const Map& MP, const Epi& E, const int nM, const int nN, const int K, const int lda, const int ldb) {
;     ...
;             PG8_LDB(B0, 0, 0); PG8_SCHED; PG8_LDA(At, 0, 0); PG8_STAGE(PG8_SA(1, 1), a1 + hstepA, voffA);
;             PG8_WAIT_L(8); PG8_BAR; PG8_WAIT_L(0); PG8_MMA(0, 0, At, B0); PG8_BAR; PG8_SCHED;
;             PG8_LDB(B1, 0, 1); PG8_STAGE(PG8_SB(0, 0), b2, voffB);
;             PG8_BAR; PG8_WAIT_L(0); PG8_MMA(0, 1, At, B1); PG8_BAR;
;             PG8_LDA(At, 0, 1); PG8_STAGE(PG8_SA(0, 0), a2, voffA);
;             PG8_BAR; PG8_WAIT_L(0); PG8_MMA(1, 0, At, B0); PG8_BAR; PG8_SCHED;
;             PG8_STAGE(PG8_SB(0, 1), b2 + hstepB, voffB);
;             PG8_WAIT_V(6); PG8_BAR; PG8_MMA(1, 1, At, B1); PG8_BAR;
.LBB1_1908:
	ds_read_b128 v[80:83], v189
	ds_read_b128 v[84:87], v189 offset:1024
	ds_read_b128 v[88:91], v189 offset:2048
	ds_read_b128 v[92:95], v189 offset:3072
	s_add_u32 s28, s42, 0xfff80080
	s_addc_u32 s29, s43, -1
	s_cmp_eq_u32 s3, 28
	s_cselect_b32 s47, s23, s29
	s_cselect_b32 s46, s58, s28
	s_cselect_b32 s29, s21, vcc_hi
	s_cselect_b32 s28, s59, vcc_lo
	v_lshl_add_u64 v[184:185], s[42:43], 0, v[178:179]
	s_add_i32 m0, s38, 0xc000
	ds_read_b128 v[96:99], v190
	ds_read_b128 v[100:103], v190 offset:1024
	ds_read_b128 v[108:111], v190 offset:2048
	ds_read_b128 v[112:115], v190 offset:3072
	ds_read_b128 v[160:163], v190 offset:4096
	ds_read_b128 v[164:167], v190 offset:5120
	ds_read_b128 v[198:201], v190 offset:6144
	ds_read_b128 v[202:205], v190 offset:7168
	global_load_lds_dwordx4 v[184:185], off
	v_lshl_add_u64 v[184:185], s[42:43], 0, v[176:177]
	s_add_i32 m0, s38, 0xe000
	s_nop 0
	global_load_lds_dwordx4 v[184:185], off
	s_waitcnt lgkmcnt(8)
	s_barrier
	s_setprio 1
	s_waitcnt lgkmcnt(7)
	v_mfma_f32_16x16x32_bf16 v[148:151], v[80:83], v[96:99], v[148:151]
	v_mfma_f32_16x16x32_bf16 v[144:147], v[88:91], v[96:99], v[144:147]
	s_waitcnt lgkmcnt(5)
	v_mfma_f32_16x16x32_bf16 v[136:139], v[80:83], v[108:111], v[136:139]
	v_mfma_f32_16x16x32_bf16 v[128:131], v[88:91], v[108:111], v[128:131]
	s_waitcnt lgkmcnt(3)
	v_mfma_f32_16x16x32_bf16 v[120:123], v[80:83], v[160:163], v[120:123]
	v_mfma_f32_16x16x32_bf16 v[104:107], v[88:91], v[160:163], v[104:107]
	s_waitcnt lgkmcnt(1)
	v_mfma_f32_16x16x32_bf16 v[76:79], v[80:83], v[198:201], v[76:79]
	v_mfma_f32_16x16x32_bf16 v[72:75], v[88:91], v[198:201], v[72:75]
	v_mfma_f32_16x16x32_bf16 v[148:151], v[84:87], v[100:103], v[148:151]
	v_mfma_f32_16x16x32_bf16 v[144:147], v[92:95], v[100:103], v[144:147]
	v_mfma_f32_16x16x32_bf16 v[136:139], v[84:87], v[112:115], v[136:139]
	v_mfma_f32_16x16x32_bf16 v[128:131], v[92:95], v[112:115], v[128:131]
	v_mfma_f32_16x16x32_bf16 v[120:123], v[84:87], v[164:167], v[120:123]
	v_mfma_f32_16x16x32_bf16 v[104:107], v[92:95], v[164:167], v[104:107]
	s_waitcnt lgkmcnt(0)
	v_mfma_f32_16x16x32_bf16 v[76:79], v[84:87], v[202:205], v[76:79]
	v_mfma_f32_16x16x32_bf16 v[72:75], v[92:95], v[202:205], v[72:75]
	s_setprio 0
	s_barrier
	s_add_i32 s68, s2, s54
	v_lshl_add_u64 v[184:185], s[28:29], 0, v[172:173]
	s_mov_b32 m0, s68
	ds_read_b128 v[206:209], v191
	ds_read_b128 v[210:213], v191 offset:1024
	ds_read_b128 v[214:217], v191 offset:2048
	ds_read_b128 v[218:221], v191 offset:3072
	global_load_lds_dwordx4 v[184:185], off
	v_lshl_add_u64 v[194:195], s[28:29], 0, v[168:169]
	s_add_i32 m0, s68, 0x2000
	s_nop 0
	global_load_lds_dwordx4 v[194:195], off
	s_barrier
	s_setprio 1
	s_waitcnt lgkmcnt(3)
	v_mfma_f32_16x16x32_bf16 v[156:159], v[206:209], v[96:99], v[156:159]
	s_waitcnt lgkmcnt(1)
	v_mfma_f32_16x16x32_bf16 v[96:99], v[214:217], v[96:99], v[152:155]
	v_mfma_f32_16x16x32_bf16 v[156:159], v[210:213], v[100:103], v[156:159]
	s_waitcnt lgkmcnt(0)
	v_mfma_f32_16x16x32_bf16 v[96:99], v[218:221], v[100:103], v[96:99]
	v_mfma_f32_16x16x32_bf16 v[100:103], v[206:209], v[108:111], v[140:143]
	v_mfma_f32_16x16x32_bf16 v[108:111], v[214:217], v[108:111], v[132:135]
	v_mfma_f32_16x16x32_bf16 v[116:119], v[214:217], v[160:163], v[116:119]
	v_mfma_f32_16x16x32_bf16 v[68:71], v[206:209], v[198:201], v[68:71]
	v_mfma_f32_16x16x32_bf16 v[64:67], v[214:217], v[198:201], v[64:67]
	v_mfma_f32_16x16x32_bf16 v[100:103], v[210:213], v[112:115], v[100:103]
	v_mfma_f32_16x16x32_bf16 v[108:111], v[218:221], v[112:115], v[108:111]
	v_mfma_f32_16x16x32_bf16 v[112:115], v[206:209], v[160:163], v[124:127]
	v_mfma_f32_16x16x32_bf16 v[116:119], v[218:221], v[164:167], v[116:119]
	v_mfma_f32_16x16x32_bf16 v[68:71], v[210:213], v[202:205], v[68:71]
	v_mfma_f32_16x16x32_bf16 v[64:67], v[218:221], v[202:205], v[64:67]
	v_mfma_f32_16x16x32_bf16 v[112:115], v[210:213], v[164:167], v[112:115]
	s_setprio 0
	s_mov_b32 m0, s38
	v_lshl_add_u64 v[226:227], s[46:47], 0, v[174:175]
	s_barrier
	ds_read_b128 v[124:127], v190 offset:16384
	ds_read_b128 v[132:135], v190 offset:17408
	ds_read_b128 v[140:143], v190 offset:18432
	ds_read_b128 v[152:155], v190 offset:19456
	ds_read_b128 v[160:163], v190 offset:20480
	ds_read_b128 v[164:167], v190 offset:21504
	ds_read_b128 v[198:201], v190 offset:22528
	ds_read_b128 v[202:205], v190 offset:23552
	global_load_lds_dwordx4 v[226:227], off
	v_lshl_add_u64 v[234:235], s[46:47], 0, v[170:171]
	s_mov_b32 m0, s39
	s_nop 0
	global_load_lds_dwordx4 v[234:235], off
	s_barrier
	s_setprio 1
	s_waitcnt lgkmcnt(7)
	v_mfma_f32_16x16x32_bf16 v[60:63], v[80:83], v[124:127], v[60:63]
	v_mfma_f32_16x16x32_bf16 v[48:51], v[88:91], v[124:127], v[48:51]
	s_waitcnt lgkmcnt(5)
	v_mfma_f32_16x16x32_bf16 v[40:43], v[80:83], v[140:143], v[40:43]
	v_mfma_f32_16x16x32_bf16 v[32:35], v[88:91], v[140:143], v[32:35]
	s_waitcnt lgkmcnt(3)
	v_mfma_f32_16x16x32_bf16 v[24:27], v[80:83], v[160:163], v[24:27]
	v_mfma_f32_16x16x32_bf16 v[16:19], v[88:91], v[160:163], v[16:19]
	s_waitcnt lgkmcnt(1)
	v_mfma_f32_16x16x32_bf16 v[12:15], v[80:83], v[198:201], v[12:15]
	v_mfma_f32_16x16x32_bf16 v[8:11], v[88:91], v[198:201], v[8:11]
	v_mfma_f32_16x16x32_bf16 v[60:63], v[84:87], v[132:135], v[60:63]
	v_mfma_f32_16x16x32_bf16 v[48:51], v[92:95], v[132:135], v[48:51]
	v_mfma_f32_16x16x32_bf16 v[40:43], v[84:87], v[152:155], v[40:43]
	v_mfma_f32_16x16x32_bf16 v[32:35], v[92:95], v[152:155], v[32:35]
	v_mfma_f32_16x16x32_bf16 v[24:27], v[84:87], v[164:167], v[24:27]
	v_mfma_f32_16x16x32_bf16 v[16:19], v[92:95], v[164:167], v[16:19]
	s_waitcnt lgkmcnt(0)
	v_mfma_f32_16x16x32_bf16 v[12:15], v[84:87], v[202:205], v[12:15]
	v_mfma_f32_16x16x32_bf16 v[8:11], v[92:95], v[202:205], v[8:11]
	s_setprio 0
	s_barrier
; #define PG8_STAGE(bufoff, gbase, voff) do { _Pragma("unroll") for (int _i = 0; _i < 2; ++_i) \
;         __builtin_amdgcn_global_load_lds((const unsigned*)((const char*)(gbase) + (voff)[_i]), (LAS unsigned*)(lds + (bufoff) + ldsw + _i * 8192), 16, 0, 0); } while (0)
; #define PG8_LDA(dst, b, h) do { _Pragma("unroll") for (int m = 0; m < 4; ++m) _Pragma("unroll") for (int k = 0; k < 2; ++k) dst[m][k] = *(const LAS bf16x8*)(lds + PG8_SA(b, h) + aoff + m * 2048 + k * 1024); } while (0)
; #define PG8_LDB(dst, b, h) do { _Pragma("unroll") for (int n = 0; n < 2; ++n) _Pragma("unroll") for (int k = 0; k < 2; ++k) dst[n][k] = *(const LAS bf16x8*)(lds + PG8_SB(b, h) + boff + n * 2048 + k * 1024); } while (0)
; #define PG8_MMA(ai, bj, At, Bt) do { __builtin_amdgcn_s_setprio(1); _Pragma("unroll") for (int m = 0; m < 4; ++m) _Pragma("unroll") for (int n = 0; n < 2; ++n) _Pragma("unroll") for (int k = 0; k < 2; ++k) \
;         acc[ai][bj][m][n] = __builtin_amdgcn_mfma_f32_16x16x32_bf16(Bt[n][k], At[m][k], acc[ai][bj][m][n], 0, 0, 0); __builtin_amdgcn_s_setprio(0); } while (0)
; #define PG8_WAIT_V(n) asm volatile("s_waitcnt vmcnt(" #n ")" ::: "memory")
; #define PG8_WAIT_L(n) asm volatile("s_waitcnt lgkmcnt(" #n ")" ::: "memory")
; #define PG8_BAR __builtin_amdgcn_s_barrier()
; #define PG8_SCHED __builtin_amdgcn_sched_barrier(0)
; template <class Map, class Epi>
; DI void gemm_phase(LAS unsigned char* lds, const Map& MP, const Epi& E, const int nM, const int nN, const int K, const int lda, const int ldb) {
;     ...
;             PG8_WAIT_V(6); PG8_BAR; PG8_MMA(1, 1, At, B1); PG8_BAR;
;             PG8_LDB(B0, 1, 0); PG8_SCHED; PG8_LDA(At, 1, 0); PG8_STAGE(PG8_SA(0, 1), a2 + hstepA, voffA);
;             PG8_WAIT_L(8); PG8_BAR; PG8_WAIT_L(0); PG8_MMA(0, 0, At, B0); PG8_BAR; PG8_SCHED;
;             PG8_LDB(B1, 1, 1); PG8_STAGE(PG8_SB(1, 0), b3, voffB);
;             PG8_BAR; PG8_WAIT_L(0); PG8_MMA(0, 1, At, B1); PG8_BAR;
;             PG8_LDA(At, 1, 1); PG8_STAGE(PG8_SA(1, 0), a3, voffA);
;             PG8_BAR; PG8_WAIT_L(0); PG8_MMA(1, 0, At, B0); PG8_BAR; PG8_SCHED;
	s_add_u32 s68, s28, 0x80000
	s_addc_u32 s69, s29, 0
	s_add_i32 s70, s31, s54
	v_lshl_add_u64 v[80:81], s[68:69], 0, v[172:173]
	s_mov_b32 m0, s70
	s_nop 0
	global_load_lds_dwordx4 v[80:81], off
	v_lshl_add_u64 v[80:81], s[68:69], 0, v[168:169]
	s_add_i32 m0, s70, 0x2000
	s_nop 0
	global_load_lds_dwordx4 v[80:81], off
	s_waitcnt vmcnt(6)
	s_barrier
	s_setprio 1
	v_mfma_f32_16x16x32_bf16 v[56:59], v[206:209], v[124:127], v[56:59]
	v_mfma_f32_16x16x32_bf16 v[52:55], v[214:217], v[124:127], v[52:55]
	v_mfma_f32_16x16x32_bf16 v[44:47], v[206:209], v[140:143], v[44:47]
	v_mfma_f32_16x16x32_bf16 v[36:39], v[214:217], v[140:143], v[36:39]
	v_mfma_f32_16x16x32_bf16 v[28:31], v[206:209], v[160:163], v[28:31]
	v_mfma_f32_16x16x32_bf16 v[20:23], v[214:217], v[160:163], v[20:23]
	v_mfma_f32_16x16x32_bf16 v[4:7], v[206:209], v[198:201], v[4:7]
	v_mfma_f32_16x16x32_bf16 v[0:3], v[214:217], v[198:201], v[0:3]
	v_mfma_f32_16x16x32_bf16 v[56:59], v[210:213], v[132:135], v[56:59]
	v_mfma_f32_16x16x32_bf16 v[52:55], v[218:221], v[132:135], v[52:55]
	v_mfma_f32_16x16x32_bf16 v[44:47], v[210:213], v[152:155], v[44:47]
	v_mfma_f32_16x16x32_bf16 v[36:39], v[218:221], v[152:155], v[36:39]
	v_mfma_f32_16x16x32_bf16 v[28:31], v[210:213], v[164:167], v[28:31]
	v_mfma_f32_16x16x32_bf16 v[20:23], v[218:221], v[164:167], v[20:23]
	v_mfma_f32_16x16x32_bf16 v[4:7], v[210:213], v[202:205], v[4:7]
	v_mfma_f32_16x16x32_bf16 v[0:3], v[218:221], v[202:205], v[0:3]
	s_setprio 0
	s_add_i32 s68, 0, 0x18000
	v_add_u32_e32 v92, s68, v188
	s_barrier
	ds_read_b128 v[80:83], v92
	ds_read_b128 v[84:87], v92 offset:1024
	ds_read_b128 v[88:91], v92 offset:2048
	ds_read_b128 v[92:95], v92 offset:3072
	s_add_u32 s46, s46, 0x80000
	s_addc_u32 s47, s47, 0
	s_mov_b32 m0, s56
	v_lshl_add_u64 v[140:141], s[46:47], 0, v[174:175]
	ds_read_b128 v[124:127], v190 offset:32768
	ds_read_b128 v[132:135], v190 offset:33792
	ds_read_b128 v[160:163], v190 offset:34816
	ds_read_b128 v[164:167], v190 offset:35840
	ds_read_b128 v[198:201], v190 offset:36864
	ds_read_b128 v[202:205], v190 offset:37888
	ds_read_b128 v[206:209], v190 offset:38912
	ds_read_b128 v[210:213], v190 offset:39936
	global_load_lds_dwordx4 v[140:141], off
	v_lshl_add_u64 v[140:141], s[46:47], 0, v[170:171]
	s_mov_b32 m0, s57
	s_nop 0
	global_load_lds_dwordx4 v[140:141], off
	s_waitcnt lgkmcnt(8)
	s_barrier
	s_setprio 1
	s_waitcnt lgkmcnt(7)
	v_mfma_f32_16x16x32_bf16 v[140:143], v[80:83], v[124:127], v[148:151]
	s_waitcnt lgkmcnt(6)
	v_mfma_f32_16x16x32_bf16 v[148:151], v[84:87], v[132:135], v[140:143]
	v_mfma_f32_16x16x32_bf16 v[140:143], v[88:91], v[124:127], v[144:147]
	s_waitcnt lgkmcnt(5)
	v_mfma_f32_16x16x32_bf16 v[136:139], v[80:83], v[160:163], v[136:139]
	v_mfma_f32_16x16x32_bf16 v[128:131], v[88:91], v[160:163], v[128:131]
	s_waitcnt lgkmcnt(3)
	v_mfma_f32_16x16x32_bf16 v[120:123], v[80:83], v[198:201], v[120:123]
	v_mfma_f32_16x16x32_bf16 v[104:107], v[88:91], v[198:201], v[104:107]
	s_waitcnt lgkmcnt(1)
	v_mfma_f32_16x16x32_bf16 v[76:79], v[80:83], v[206:209], v[76:79]
	v_mfma_f32_16x16x32_bf16 v[72:75], v[88:91], v[206:209], v[72:75]
	v_mfma_f32_16x16x32_bf16 v[144:147], v[92:95], v[132:135], v[140:143]
	v_mfma_f32_16x16x32_bf16 v[136:139], v[84:87], v[164:167], v[136:139]
	v_mfma_f32_16x16x32_bf16 v[128:131], v[92:95], v[164:167], v[128:131]
	v_mfma_f32_16x16x32_bf16 v[120:123], v[84:87], v[202:205], v[120:123]
	v_mfma_f32_16x16x32_bf16 v[104:107], v[92:95], v[202:205], v[104:107]
	s_waitcnt lgkmcnt(0)
	v_mfma_f32_16x16x32_bf16 v[76:79], v[84:87], v[210:213], v[76:79]
	v_mfma_f32_16x16x32_bf16 v[72:75], v[92:95], v[210:213], v[72:75]
	s_setprio 0
	s_barrier
	s_add_i32 s46, 0, 0x1c000
	v_add_u32_e32 v140, s46, v188
	s_add_i32 s47, s68, s54
	ds_read_b128 v[214:217], v140
	ds_read_b128 v[218:221], v140 offset:1024
	ds_read_b128 v[222:225], v140 offset:2048
	ds_read_b128 v[230:233], v140 offset:3072
	v_lshl_add_u64 v[140:141], v[184:185], 0, s[14:15]
	s_mov_b32 m0, s47
	s_nop 0
	global_load_lds_dwordx4 v[140:141], off
	v_lshl_add_u64 v[140:141], v[194:195], 0, s[14:15]
	s_add_i32 m0, s47, 0x2000
	s_nop 0
	global_load_lds_dwordx4 v[140:141], off
	s_barrier
	s_setprio 1
	s_waitcnt lgkmcnt(1)
	v_mfma_f32_16x16x32_bf16 v[96:99], v[222:225], v[124:127], v[96:99]
	v_mfma_f32_16x16x32_bf16 v[140:143], v[214:217], v[124:127], v[156:159]
	s_waitcnt lgkmcnt(0)
	v_mfma_f32_16x16x32_bf16 v[152:155], v[230:233], v[132:135], v[96:99]
	v_mfma_f32_16x16x32_bf16 v[96:99], v[214:217], v[160:163], v[100:103]
	v_mfma_f32_16x16x32_bf16 v[156:159], v[218:221], v[132:135], v[140:143]
	v_mfma_f32_16x16x32_bf16 v[140:143], v[218:221], v[164:167], v[96:99]
	v_mfma_f32_16x16x32_bf16 v[96:99], v[222:225], v[160:163], v[108:111]
	v_mfma_f32_16x16x32_bf16 v[132:135], v[230:233], v[164:167], v[96:99]
	v_mfma_f32_16x16x32_bf16 v[96:99], v[214:217], v[198:201], v[112:115]
	v_mfma_f32_16x16x32_bf16 v[124:127], v[218:221], v[202:205], v[96:99]
	v_mfma_f32_16x16x32_bf16 v[96:99], v[222:225], v[198:201], v[116:119]
	v_mfma_f32_16x16x32_bf16 v[68:71], v[214:217], v[206:209], v[68:71]
	v_mfma_f32_16x16x32_bf16 v[64:67], v[222:225], v[206:209], v[64:67]
	v_mfma_f32_16x16x32_bf16 v[116:119], v[230:233], v[202:205], v[96:99]
	v_mfma_f32_16x16x32_bf16 v[68:71], v[218:221], v[210:213], v[68:71]
	v_mfma_f32_16x16x32_bf16 v[64:67], v[230:233], v[210:213], v[64:67]
	s_setprio 0
	s_mov_b32 m0, s63
	v_lshl_add_u64 v[184:185], v[226:227], 0, s[14:15]
	s_barrier
; DI float dpp_ror1(float v)  { return __builtin_bit_cast(float, __builtin_amdgcn_update_dpp(0, __builtin_bit_cast(int, v), 0x121, 0xf, 0xf, false)); }
; DI float dpp_ror15(float v) { return __builtin_bit_cast(float, __builtin_amdgcn_update_dpp(0, __builtin_bit_cast(int, v), 0x12F, 0xf, 0xf, false)); }
; #define PG8_WAIT_V(n) asm volatile("s_waitcnt vmcnt(" #n ")" ::: "memory")
;     DI void operator()(const f32x4 (&acc)[2][2][4][2], const Unit& u, int wr, int wc, int fr, int fq) const {
;         const int row0 = u.pm * BM + wr * 64 + fr, ch0 = u.pn * 128 + wc * 32 + 8 * fq;
;         f32x4 w0[2], w1[2], w2[2], bb[2];
; #pragma unroll
;         for (int n = 0; n < 2; ++n) { w0[n] = *(const f32x4*)(cw + ch0 + 4 * n); w1[n] = *(const f32x4*)(cw + DFF + ch0 + 4 * n); w2[n] = *(const f32x4*)(cw + 2 * DFF + ch0 + 4 * n); bb[n] = *(const f32x4*)(cb + ch0 + 4 * n); }
; #pragma unroll
;         for (int ai = 0; ai < 2; ++ai)
; #pragma unroll
;             for (int m = 0; m < 4; ++m) {
;                 const bool efirst = (m == 0) && (fr == 0), elast = (m == 3) && (fr == 15);
;                 const int row = row0 + ai * HALF + m * 16;
;                 f32x4 gc[2];
; #pragma unroll
;                 for (int n = 0; n < 2; ++n) {
;                     const f32x4 g = acc[ai][0][m][n];
;                     const f32x4 gprev = acc[ai][0][m > 0 ? m - 1 : 0][n], gnext = acc[ai][0][m < 3 ? m + 1 : 3][n];
;                     f32x4 up, dn;
; #pragma unroll
;                     for (int e = 0; e < 4; ++e) {
;                         const float pu = (m > 0 && fr == 15) ? gprev[e] : g[e];
;                         const float pd = (m < 3 && fr == 0) ? gnext[e] : g[e];
;                         up[e] = dpp_ror1(pu); dn[e] = dpp_ror15(pd);
;                     }
;                     if (efirst) up = (f32x4){0.f, 0.f, 0.f, 0.f};
;                     if (elast) dn = (f32x4){0.f, 0.f, 0.f, 0.f};
;                     gc[n] = w0[n] * up + w1[n] * g + w2[n] * dn + bb[n];
; template <class Map, class Epi>
; DI void gemm_phase(LAS unsigned char* lds, const Map& MP, const Epi& E, const int nM, const int nN, const int K, const int lda, const int ldb) {
;     ...
;             PG8_BAR; PG8_WAIT_L(0); PG8_MMA(1, 0, At, B0); PG8_BAR; PG8_SCHED;
;             PG8_STAGE(PG8_SB(1, 1), b3 + hstepB, voffB);
;             PG8_WAIT_V(6); PG8_BAR; PG8_MMA(1, 1, At, B1); PG8_BAR;
	ds_read_b128 v[96:99], v190 offset:49152
	ds_read_b128 v[100:103], v190 offset:50176
	ds_read_b128 v[108:111], v190 offset:51200
	ds_read_b128 v[112:115], v190 offset:52224
	ds_read_b128 v[160:163], v190 offset:53248
	ds_read_b128 v[164:167], v190 offset:54272
	ds_read_b128 v[198:201], v190 offset:55296
	ds_read_b128 v[202:205], v190 offset:56320
	global_load_lds_dwordx4 v[184:185], off
	v_lshl_add_u64 v[184:185], v[234:235], 0, s[14:15]
	s_mov_b32 m0, s66
	s_nop 0
	global_load_lds_dwordx4 v[184:185], off
	s_barrier
	s_setprio 1
	s_waitcnt lgkmcnt(7)
	v_mfma_f32_16x16x32_bf16 v[60:63], v[80:83], v[96:99], v[60:63]
	v_mfma_f32_16x16x32_bf16 v[48:51], v[88:91], v[96:99], v[48:51]
	s_waitcnt lgkmcnt(5)
	v_mfma_f32_16x16x32_bf16 v[40:43], v[80:83], v[108:111], v[40:43]
	v_mfma_f32_16x16x32_bf16 v[32:35], v[88:91], v[108:111], v[32:35]
	s_waitcnt lgkmcnt(3)
	v_mfma_f32_16x16x32_bf16 v[24:27], v[80:83], v[160:163], v[24:27]
	v_mfma_f32_16x16x32_bf16 v[16:19], v[88:91], v[160:163], v[16:19]
	s_waitcnt lgkmcnt(1)
	v_mfma_f32_16x16x32_bf16 v[12:15], v[80:83], v[198:201], v[12:15]
	v_mfma_f32_16x16x32_bf16 v[8:11], v[88:91], v[198:201], v[8:11]
	v_mfma_f32_16x16x32_bf16 v[60:63], v[84:87], v[100:103], v[60:63]
	v_mfma_f32_16x16x32_bf16 v[48:51], v[92:95], v[100:103], v[48:51]
	v_mfma_f32_16x16x32_bf16 v[40:43], v[84:87], v[112:115], v[40:43]
	v_mfma_f32_16x16x32_bf16 v[32:35], v[92:95], v[112:115], v[32:35]
	v_mfma_f32_16x16x32_bf16 v[24:27], v[84:87], v[164:167], v[24:27]
	v_mfma_f32_16x16x32_bf16 v[16:19], v[92:95], v[164:167], v[16:19]
	s_waitcnt lgkmcnt(0)
	v_mfma_f32_16x16x32_bf16 v[12:15], v[84:87], v[202:205], v[12:15]
	v_mfma_f32_16x16x32_bf16 v[8:11], v[92:95], v[202:205], v[8:11]
	s_setprio 0
	s_barrier
	s_add_u32 s28, s28, 0x80080
	s_addc_u32 s29, s29, 0
	s_add_i32 s46, s46, s54
	v_lshl_add_u64 v[80:81], s[28:29], 0, v[172:173]
	s_mov_b32 m0, s46
	s_nop 0
	global_load_lds_dwordx4 v[80:81], off
	v_lshl_add_u64 v[80:81], s[28:29], 0, v[168:169]
	s_add_i32 m0, s46, 0x2000
	s_nop 0
	global_load_lds_dwordx4 v[80:81], off
	s_waitcnt vmcnt(6)
	s_barrier
	s_setprio 1
	v_mfma_f32_16x16x32_bf16 v[56:59], v[214:217], v[96:99], v[56:59]
	v_mfma_f32_16x16x32_bf16 v[52:55], v[222:225], v[96:99], v[52:55]
	v_mfma_f32_16x16x32_bf16 v[44:47], v[214:217], v[108:111], v[44:47]
	v_mfma_f32_16x16x32_bf16 v[36:39], v[222:225], v[108:111], v[36:39]
	v_mfma_f32_16x16x32_bf16 v[28:31], v[214:217], v[160:163], v[28:31]
	v_mfma_f32_16x16x32_bf16 v[20:23], v[222:225], v[160:163], v[20:23]
	v_mfma_f32_16x16x32_bf16 v[4:7], v[214:217], v[198:201], v[4:7]
	v_mfma_f32_16x16x32_bf16 v[0:3], v[222:225], v[198:201], v[0:3]
	v_mfma_f32_16x16x32_bf16 v[56:59], v[218:221], v[100:103], v[56:59]
	v_mfma_f32_16x16x32_bf16 v[52:55], v[230:233], v[100:103], v[52:55]
	v_mfma_f32_16x16x32_bf16 v[44:47], v[218:221], v[112:115], v[44:47]
	v_mfma_f32_16x16x32_bf16 v[36:39], v[230:233], v[112:115], v[36:39]
	v_mfma_f32_16x16x32_bf16 v[28:31], v[218:221], v[164:167], v[28:31]
	v_mfma_f32_16x16x32_bf16 v[20:23], v[230:233], v[164:167], v[20:23]
	v_mfma_f32_16x16x32_bf16 v[4:7], v[218:221], v[202:205], v[4:7]
	v_mfma_f32_16x16x32_bf16 v[0:3], v[230:233], v[202:205], v[0:3]
	s_setprio 0
	s_add_i32 s3, s3, 2
	s_add_u32 vcc_lo, vcc_lo, 0x100
	s_addc_u32 vcc_hi, vcc_hi, 0
	s_add_u32 s42, s42, 0x100
	s_addc_u32 s43, s43, 0
	s_cmp_gt_u32 s3, 29
	s_barrier
	s_cbranch_scc0 .LBB1_1908
	s_lshl_b32 s21, s45, 7
	v_mov_b32_e32 v194, v186
	v_mov_b32_e32 v80, v187
	s_or_b32 s21, s21, s62
	v_mov_b32_e32 v160, 0
	v_lshl_add_u32 v184, v80, 3, s21
	v_ashrrev_i32_e32 v185, 31, v184
	v_lshlrev_b64 v[80:81], 2, v[184:185]
	v_lshl_add_u64 v[84:85], s[4:5], 0, v[80:81]
	v_lshl_add_u64 v[88:89], s[16:17], 0, v[80:81]
	v_lshl_add_u64 v[92:93], s[18:19], 0, v[80:81]
	v_lshl_add_u64 v[112:113], s[6:7], 0, v[80:81]
	global_load_dwordx4 v[80:83], v[84:85], off offset:16
	global_load_dwordx4 v[96:99], v[84:85], off
	s_nop 0
	global_load_dwordx4 v[84:87], v[88:89], off offset:16
	global_load_dwordx4 v[100:103], v[88:89], off
	s_nop 0
	global_load_dwordx4 v[88:91], v[92:93], off offset:16
	global_load_dwordx4 v[108:111], v[92:93], off
	s_nop 0
	global_load_dwordx4 v[92:95], v[112:113], off offset:16
	s_nop 0
	global_load_dwordx4 v[112:115], v[112:113], off
	v_cmp_eq_u32_e32 vcc, 0, v194
	v_mov_b32_e32 v164, 0
	v_mov_b32_e32 v195, 0
	v_cndmask_b32_e32 v161, v148, v136, vcc
	v_cndmask_b32_e32 v162, v149, v137, vcc
	v_cndmask_b32_e32 v163, v150, v138, vcc
	v_mov_b32_dpp v160, v161 row_ror:15 row_mask:0xf bank_mask:0xf
	v_mov_b32_e32 v161, 0
	v_mov_b32_e32 v166, 0
	v_mov_b32_e32 v167, 0
	v_mov_b32_dpp v161, v162 row_ror:15 row_mask:0xf bank_mask:0xf
	v_mov_b32_e32 v162, 0
	v_mov_b32_dpp v164, v150 row_ror:1 row_mask:0xf bank_mask:0xf
	v_cndmask_b32_e32 v165, v151, v139, vcc
	v_mov_b32_dpp v162, v163 row_ror:15 row_mask:0xf bank_mask:0xf
	v_mov_b32_dpp v195, v151 row_ror:1 row_mask:0xf bank_mask:0xf
	v_mov_b32_e32 v163, 0
	v_mov_b32_dpp v166, v148 row_ror:1 row_mask:0xf bank_mask:0xf
	v_mov_b32_dpp v167, v149 row_ror:1 row_mask:0xf bank_mask:0xf
	v_mov_b32_dpp v163, v165 row_ror:15 row_mask:0xf bank_mask:0xf
	v_cndmask_b32_e64 v165, v195, 0, vcc
	v_cndmask_b32_e64 v164, v164, 0, vcc
	v_cndmask_b32_e64 v167, v167, 0, vcc
	v_cndmask_b32_e64 v166, v166, 0, vcc
	v_mov_b32_e32 v195, 0
	v_mov_b32_e32 v196, 0
	v_mov_b32_e32 v198, 0
	v_mov_b32_e32 v200, 0
	v_mov_b32_dpp v195, v144 row_ror:1 row_mask:0xf bank_mask:0xf
	v_mov_b32_dpp v196, v145 row_ror:1 row_mask:0xf bank_mask:0xf
	v_mov_b32_dpp v198, v146 row_ror:1 row_mask:0xf bank_mask:0xf
	v_cndmask_b32_e32 v199, v147, v131, vcc
	v_mov_b32_dpp v200, v147 row_ror:1 row_mask:0xf bank_mask:0xf
	v_cndmask_b32_e64 v198, v198, 0, vcc
	v_cndmask_b32_e64 v201, v196, 0, vcc
	s_lshl_b32 s3, s44, 8
	s_add_i32 s3, s3, s49
	v_add_u32_e32 v193, s3, v194
	v_cmp_ne_u32_e64 s[46:47], 0, v194
	s_waitcnt vmcnt(0)
; DI unsigned pack2(float a, float b) { f32x2 v = {a, b}; hwbf16x2 r = __builtin_convertvector(v, hwbf16x2); return __builtin_bit_cast(unsigned, r); }
; DI float dpp_ror1(float v)  { return __builtin_bit_cast(float, __builtin_amdgcn_update_dpp(0, __builtin_bit_cast(int, v), 0x121, 0xf, 0xf, false)); }
; DI float dpp_ror15(float v) { return __builtin_bit_cast(float, __builtin_amdgcn_update_dpp(0, __builtin_bit_cast(int, v), 0x12F, 0xf, 0xf, false)); }
; DI float silu_mul(float g, float v) { return g * v * __builtin_amdgcn_rcpf(1.0f + __builtin_amdgcn_exp2f(-LOG2E * g)); }
;     DI void operator()(const f32x4 (&acc)[2][2][4][2], const Unit& u, int wr, int wc, int fr, int fq) const {
;     ...
;                 for (int n = 0; n < 2; ++n) {
;                     const f32x4 g = acc[ai][0][m][n];
;                     const f32x4 gprev = acc[ai][0][m > 0 ? m - 1 : 0][n], gnext = acc[ai][0][m < 3 ? m + 1 : 3][n];
;                     f32x4 up, dn;
; #pragma unroll
;                     for (int e = 0; e < 4; ++e) {
;                         const float pu = (m > 0 && fr == 15) ? gprev[e] : g[e];
;                         const float pd = (m < 3 && fr == 0) ? gnext[e] : g[e];
;                         up[e] = dpp_ror1(pu); dn[e] = dpp_ror15(pd);
;                     }
;                     if (efirst) up = (f32x4){0.f, 0.f, 0.f, 0.f};
;                     if (elast) dn = (f32x4){0.f, 0.f, 0.f, 0.f};
;                     gc[n] = w0[n] * up + w1[n] * g + w2[n] * dn + bb[n];
;                 }
;                 if (efirst || elast) {
;                     const size_t eo = (size_t)((row >> 6) * 2 + (elast ? 1 : 0)) * DFF + ch0;
; #pragma unroll
;                     for (int n = 0; n < 2; ++n) { *(f32x4*)(EP + eo + 4 * n) = gc[n]; *(f32x4*)(ER + eo + 4 * n) = acc[ai][0][m][n]; *(f32x4*)(EV + eo + 4 * n) = acc[ai][1][m][n]; }
;                 } else {
;                     const f32x4 v0 = acc[ai][1][m][0], v1 = acc[ai][1][m][1];
;                     u32x4 o;
;                     o[0] = pack2(silu_mul(gc[0][0], v0[0]), silu_mul(gc[0][1], v0[1])); o[1] = pack2(silu_mul(gc[0][2], v0[2]), silu_mul(gc[0][3], v0[3]));
;                     o[2] = pack2(silu_mul(gc[1][0], v1[0]), silu_mul(gc[1][1], v1[1])); o[3] = pack2(silu_mul(gc[1][2], v1[2]), silu_mul(gc[1][3], v1[3]));
;                     *(u32x4*)(ACT + (size_t)row * DFF + ch0) = o;
;                 }
	v_pk_mul_f32 v[164:165], v[98:99], v[164:165]
	v_pk_mul_f32 v[166:167], v[96:97], v[166:167]
	v_pk_fma_f32 v[164:165], v[150:151], v[102:103], v[164:165]
	v_pk_fma_f32 v[166:167], v[148:149], v[100:101], v[166:167]
	v_pk_fma_f32 v[162:163], v[110:111], v[162:163], v[164:165]
	v_cndmask_b32_e32 v165, v144, v128, vcc
	v_mov_b32_e32 v164, 0
	v_pk_fma_f32 v[160:161], v[108:109], v[160:161], v[166:167]
	v_cndmask_b32_e32 v166, v145, v129, vcc
	v_mov_b32_dpp v164, v165 row_ror:15 row_mask:0xf bank_mask:0xf
	v_mov_b32_e32 v165, 0
	v_cndmask_b32_e32 v167, v146, v130, vcc
	v_pk_add_f32 v[162:163], v[114:115], v[162:163]
	v_mov_b32_dpp v165, v166 row_ror:15 row_mask:0xf bank_mask:0xf
	v_mov_b32_e32 v166, 0
	v_pk_add_f32 v[160:161], v[112:113], v[160:161]
	s_nop 0
	v_mov_b32_dpp v166, v167 row_ror:15 row_mask:0xf bank_mask:0xf
	v_mov_b32_e32 v167, 0
	s_nop 1
	v_mov_b32_dpp v167, v199 row_ror:15 row_mask:0xf bank_mask:0xf
	v_cndmask_b32_e64 v199, v200, 0, vcc
	v_cndmask_b32_e64 v200, v195, 0, vcc
	v_pk_mul_f32 v[200:201], v[80:81], v[200:201]
	v_pk_mul_f32 v[198:199], v[82:83], v[198:199]
	v_pk_fma_f32 v[200:201], v[144:145], v[84:85], v[200:201]
	v_pk_fma_f32 v[198:199], v[146:147], v[86:87], v[198:199]
	v_pk_fma_f32 v[164:165], v[88:89], v[164:165], v[200:201]
	v_pk_fma_f32 v[166:167], v[90:91], v[166:167], v[198:199]
	v_pk_add_f32 v[164:165], v[92:93], v[164:165]
	v_pk_add_f32 v[166:167], v[94:95], v[166:167]
	s_and_saveexec_b64 s[28:29], s[46:47]
	s_xor_b64 s[28:29], exec, s[28:29]
	s_cbranch_execz .LBB1_1911
	v_mul_f32_e32 v195, 0xbfb8aa3b, v160
	v_exp_f32_e32 v195, v195
	v_mul_f32_e32 v196, 0xbfb8aa3b, v161
	v_exp_f32_e32 v196, v196
	v_pk_mul_f32 v[160:161], v[156:157], v[160:161]
	v_add_f32_e32 v195, 1.0, v195
	v_rcp_f32_e32 v198, v195
	v_add_f32_e32 v196, 1.0, v196
	v_mul_f32_e32 v195, 0xbfb8aa3b, v162
	v_rcp_f32_e32 v199, v196
	v_exp_f32_e32 v195, v195
	v_mul_f32_e32 v196, 0xbfb8aa3b, v163
	v_exp_f32_e32 v196, v196
	v_pk_mul_f32 v[160:161], v[160:161], v[198:199]
	v_add_f32_e32 v195, 1.0, v195
	v_rcp_f32_e32 v200, v195
	v_add_f32_e32 v195, 1.0, v196
	v_rcp_f32_e32 v201, v195
	v_cvt_pk_bf16_f32 v160, v160, v161
	v_mul_f32_e32 v161, 0xbfb8aa3b, v164
	v_exp_f32_e32 v195, v161
	v_mul_f32_e32 v161, 0xbfb8aa3b, v165
	v_exp_f32_e32 v196, v161
	v_pk_mul_f32 v[162:163], v[158:159], v[162:163]
	v_pk_mul_f32 v[164:165], v[152:153], v[164:165]
	v_pk_mul_f32 v[162:163], v[162:163], v[200:201]
	s_nop 0
	v_cvt_pk_bf16_f32 v161, v162, v163
	v_add_f32_e32 v162, 1.0, v195
	v_mul_f32_e32 v195, 0xbfb8aa3b, v166
	v_add_f32_e32 v163, 1.0, v196
	v_exp_f32_e32 v195, v195
	v_mul_f32_e32 v196, 0xbfb8aa3b, v167
	v_exp_f32_e32 v196, v196
	v_rcp_f32_e32 v162, v162
	v_add_f32_e32 v195, 1.0, v195
	v_rcp_f32_e32 v198, v195
	v_add_f32_e32 v195, 1.0, v196
	v_rcp_f32_e32 v163, v163
	v_rcp_f32_e32 v199, v195
	v_pk_mul_f32 v[166:167], v[154:155], v[166:167]
	v_pk_mul_f32 v[162:163], v[164:165], v[162:163]
	v_pk_mul_f32 v[164:165], v[166:167], v[198:199]
	v_cvt_pk_bf16_f32 v162, v162, v163
	v_cvt_pk_bf16_f32 v163, v164, v165
	v_mov_b64_e32 v[164:165], s[52:53]
	v_mad_i64_i32 v[164:165], s[42:43], v193, s60, v[164:165]
	v_lshl_add_u64 v[164:165], v[184:185], 1, v[164:165]
	global_store_dwordx4 v[164:165], v[160:163], off
.LBB1_1911:
	s_andn2_saveexec_b64 s[28:29], s[28:29]
	s_cbranch_execz .LBB1_1913
	s_ashr_i32 s3, s3, 5
	v_mad_i64_i32 v[198:199], s[42:43], s3, v192, v[184:185]
	v_lshlrev_b64 v[198:199], 2, v[198:199]
	v_lshl_add_u64 v[200:201], s[8:9], 0, v[198:199]
	global_store_dwordx4 v[200:201], v[160:163], off
	s_nop 1
	v_lshl_add_u64 v[160:161], s[10:11], 0, v[198:199]
	v_lshl_add_u64 v[162:163], s[12:13], 0, v[198:199]
	global_store_dwordx4 v[160:161], v[148:151], off
	global_store_dwordx4 v[162:163], v[156:159], off
	global_store_dwordx4 v[200:201], v[164:167], off offset:16
	global_store_dwordx4 v[160:161], v[144:147], off offset:16
	global_store_dwordx4 v[162:163], v[152:155], off offset:16
.LBB1_1913:
	s_or_b64 exec, exec, s[28:29]
	v_cmp_eq_u32_e64 s[44:45], 15, v194
	v_cndmask_b32_e32 v153, v136, v120, vcc
	v_cndmask_b32_e32 v154, v137, v121, vcc
	v_cndmask_b32_e64 v152, v136, v148, s[44:45]
	v_mov_b32_e32 v148, 0
	v_cndmask_b32_e32 v155, v138, v122, vcc
	v_cndmask_b32_e32 v156, v139, v123, vcc
	v_mov_b32_dpp v148, v152 row_ror:1 row_mask:0xf bank_mask:0xf
	v_mov_b32_e32 v152, 0
	v_cndmask_b32_e32 v157, v128, v104, vcc
	v_cndmask_b32_e32 v158, v129, v105, vcc
	v_mov_b32_dpp v152, v153 row_ror:15 row_mask:0xf bank_mask:0xf
	v_cndmask_b32_e64 v153, v137, v149, s[44:45]
	v_mov_b32_e32 v149, 0
	v_cndmask_b32_e32 v159, v130, v106, vcc
	v_cndmask_b32_e32 v160, v131, v107, vcc
	v_mov_b32_dpp v149, v153 row_ror:1 row_mask:0xf bank_mask:0xf
	v_mov_b32_e32 v153, 0
	v_pk_mul_f32 v[148:149], v[96:97], v[148:149]
	v_cmp_ne_u32_e64 s[42:43], 15, v194
	v_mov_b32_dpp v153, v154 row_ror:15 row_mask:0xf bank_mask:0xf
	v_pk_fma_f32 v[148:149], v[136:137], v[100:101], v[148:149]
	v_cndmask_b32_e64 v154, v138, v150, s[44:45]
	v_mov_b32_e32 v150, 0
	v_pk_fma_f32 v[148:149], v[108:109], v[152:153], v[148:149]
	s_nop 0
	v_mov_b32_dpp v150, v154 row_ror:1 row_mask:0xf bank_mask:0xf
	v_mov_b32_e32 v154, 0
	v_pk_add_f32 v[148:149], v[112:113], v[148:149]
	s_nop 0
	v_mov_b32_dpp v154, v155 row_ror:15 row_mask:0xf bank_mask:0xf
	v_cndmask_b32_e64 v155, v139, v151, s[44:45]
	v_mov_b32_e32 v151, 0
	v_mul_f32_e32 v152, 0xbfb8aa3b, v148
	v_mul_f32_e32 v153, 0xbfb8aa3b, v149
	v_mov_b32_dpp v151, v155 row_ror:1 row_mask:0xf bank_mask:0xf
	v_exp_f32_e32 v152, v152
	v_exp_f32_e32 v153, v153
	v_mov_b32_e32 v155, 0
	v_pk_mul_f32 v[150:151], v[98:99], v[150:151]
	v_add_f32_e32 v152, 1.0, v152
; DI unsigned pack2(float a, float b) { f32x2 v = {a, b}; hwbf16x2 r = __builtin_convertvector(v, hwbf16x2); return __builtin_bit_cast(unsigned, r); }
; DI float dpp_ror1(float v)  { return __builtin_bit_cast(float, __builtin_amdgcn_update_dpp(0, __builtin_bit_cast(int, v), 0x121, 0xf, 0xf, false)); }
; DI float dpp_ror15(float v) { return __builtin_bit_cast(float, __builtin_amdgcn_update_dpp(0, __builtin_bit_cast(int, v), 0x12F, 0xf, 0xf, false)); }
; DI float silu_mul(float g, float v) { return g * v * __builtin_amdgcn_rcpf(1.0f + __builtin_amdgcn_exp2f(-LOG2E * g)); }
;     DI void operator()(const f32x4 (&acc)[2][2][4][2], const Unit& u, int wr, int wc, int fr, int fq) const {
;     ...
;                 for (int n = 0; n < 2; ++n) {
;                     const f32x4 g = acc[ai][0][m][n];
;                     const f32x4 gprev = acc[ai][0][m > 0 ? m - 1 : 0][n], gnext = acc[ai][0][m < 3 ? m + 1 : 3][n];
;                     f32x4 up, dn;
; #pragma unroll
;                     for (int e = 0; e < 4; ++e) {
;                         const float pu = (m > 0 && fr == 15) ? gprev[e] : g[e];
;                         const float pd = (m < 3 && fr == 0) ? gnext[e] : g[e];
;                         up[e] = dpp_ror1(pu); dn[e] = dpp_ror15(pd);
;                     }
;                     if (efirst) up = (f32x4){0.f, 0.f, 0.f, 0.f};
;                     if (elast) dn = (f32x4){0.f, 0.f, 0.f, 0.f};
;                     gc[n] = w0[n] * up + w1[n] * g + w2[n] * dn + bb[n];
;                 }
;                 if (efirst || elast) {
;                     const size_t eo = (size_t)((row >> 6) * 2 + (elast ? 1 : 0)) * DFF + ch0;
; #pragma unroll
;                     for (int n = 0; n < 2; ++n) { *(f32x4*)(EP + eo + 4 * n) = gc[n]; *(f32x4*)(ER + eo + 4 * n) = acc[ai][0][m][n]; *(f32x4*)(EV + eo + 4 * n) = acc[ai][1][m][n]; }
;                 } else {
;                     const f32x4 v0 = acc[ai][1][m][0], v1 = acc[ai][1][m][1];
;                     u32x4 o;
;                     o[0] = pack2(silu_mul(gc[0][0], v0[0]), silu_mul(gc[0][1], v0[1])); o[1] = pack2(silu_mul(gc[0][2], v0[2]), silu_mul(gc[0][3], v0[3]));
;                     o[2] = pack2(silu_mul(gc[1][0], v1[0]), silu_mul(gc[1][1], v1[1])); o[3] = pack2(silu_mul(gc[1][2], v1[2]), silu_mul(gc[1][3], v1[3]));
;                     *(u32x4*)(ACT + (size_t)row * DFF + ch0) = o;
	v_mov_b32_dpp v155, v156 row_ror:15 row_mask:0xf bank_mask:0xf
	v_cndmask_b32_e64 v156, v128, v144, s[44:45]
	v_mov_b32_e32 v144, 0
	v_pk_fma_f32 v[150:151], v[138:139], v[102:103], v[150:151]
	v_add_f32_e32 v153, 1.0, v153
	v_mov_b32_dpp v144, v156 row_ror:1 row_mask:0xf bank_mask:0xf
	v_mov_b32_e32 v156, 0
	v_pk_fma_f32 v[150:151], v[110:111], v[154:155], v[150:151]
	v_rcp_f32_e32 v152, v152
	v_mov_b32_dpp v156, v157 row_ror:15 row_mask:0xf bank_mask:0xf
	v_cndmask_b32_e64 v157, v129, v145, s[44:45]
	v_mov_b32_e32 v145, 0
	v_pk_add_f32 v[150:151], v[114:115], v[150:151]
	v_rcp_f32_e32 v153, v153
	v_mov_b32_dpp v145, v157 row_ror:1 row_mask:0xf bank_mask:0xf
	v_mul_f32_e32 v154, 0xbfb8aa3b, v150
	v_mul_f32_e32 v155, 0xbfb8aa3b, v151
	v_mov_b32_e32 v157, 0
	v_pk_mul_f32 v[144:145], v[80:81], v[144:145]
	v_exp_f32_e32 v154, v154
	v_exp_f32_e32 v155, v155
	v_mov_b32_dpp v157, v158 row_ror:15 row_mask:0xf bank_mask:0xf
	v_pk_fma_f32 v[144:145], v[128:129], v[84:85], v[144:145]
	v_cndmask_b32_e64 v158, v130, v146, s[44:45]
	v_mov_b32_e32 v146, 0
	v_pk_fma_f32 v[144:145], v[88:89], v[156:157], v[144:145]
	v_pk_mul_f32 v[140:141], v[140:141], v[148:149]
	v_mov_b32_dpp v146, v158 row_ror:1 row_mask:0xf bank_mask:0xf
	v_mov_b32_e32 v158, 0
	v_pk_add_f32 v[144:145], v[92:93], v[144:145]
	v_pk_mul_f32 v[140:141], v[140:141], v[152:153]
	v_mov_b32_dpp v158, v159 row_ror:15 row_mask:0xf bank_mask:0xf
	v_cndmask_b32_e64 v159, v131, v147, s[44:45]
	v_mov_b32_e32 v147, 0
	v_pk_mul_f32 v[142:143], v[142:143], v[150:151]
	v_add_f32_e32 v150, 1.0, v154
	v_add_f32_e32 v151, 1.0, v155
	v_cvt_pk_bf16_f32 v140, v140, v141
	v_mul_f32_e32 v141, 0xbfb8aa3b, v144
	v_mov_b32_dpp v147, v159 row_ror:1 row_mask:0xf bank_mask:0xf
	v_rcp_f32_e32 v150, v150
	v_rcp_f32_e32 v151, v151
	v_exp_f32_e32 v148, v141
	v_mul_f32_e32 v141, 0xbfb8aa3b, v145
	v_mov_b32_e32 v159, 0
	v_pk_mul_f32 v[146:147], v[82:83], v[146:147]
	v_exp_f32_e32 v149, v141
	v_mov_b32_dpp v159, v160 row_ror:15 row_mask:0xf bank_mask:0xf
	v_pk_fma_f32 v[146:147], v[130:131], v[86:87], v[146:147]
	v_pk_mul_f32 v[142:143], v[142:143], v[150:151]
	v_pk_fma_f32 v[146:147], v[90:91], v[158:159], v[146:147]
	v_cvt_pk_bf16_f32 v141, v142, v143
	v_pk_add_f32 v[146:147], v[94:95], v[146:147]
	v_add_f32_e32 v142, 1.0, v148
	v_add_f32_e32 v143, 1.0, v149
	v_mul_f32_e32 v148, 0xbfb8aa3b, v146
	v_mul_f32_e32 v149, 0xbfb8aa3b, v147
	v_exp_f32_e32 v148, v148
	v_exp_f32_e32 v149, v149
	v_rcp_f32_e32 v142, v142
	v_rcp_f32_e32 v143, v143
	v_pk_mul_f32 v[134:135], v[134:135], v[146:147]
	v_add_f32_e32 v146, 1.0, v148
	v_add_f32_e32 v147, 1.0, v149
	v_rcp_f32_e32 v146, v146
	v_rcp_f32_e32 v147, v147
	v_pk_mul_f32 v[132:133], v[132:133], v[144:145]
	v_add_u32_e32 v160, 16, v193
	v_pk_mul_f32 v[132:133], v[132:133], v[142:143]
	v_cndmask_b32_e32 v148, v107, v75, vcc
	v_cvt_pk_bf16_f32 v142, v132, v133
	v_pk_mul_f32 v[132:133], v[134:135], v[146:147]
	v_mov_b64_e32 v[134:135], s[52:53]
	v_cvt_pk_bf16_f32 v143, v132, v133
	v_mad_i64_i32 v[144:145], s[28:29], v160, s60, v[134:135]
	v_lshlrev_b64 v[132:133], 1, v[184:185]
	v_lshl_add_u64 v[144:145], v[144:145], 0, v[132:133]
	global_store_dwordx4 v[144:145], v[140:143], off
	v_cndmask_b32_e32 v144, v123, v79, vcc
	v_cndmask_b32_e32 v145, v104, v72, vcc
	v_cndmask_b32_e64 v140, v120, v136, s[44:45]
	v_mov_b32_e32 v136, 0
	v_cndmask_b32_e32 v141, v120, v76, vcc
	v_cndmask_b32_e32 v142, v121, v77, vcc
	v_mov_b32_dpp v136, v140 row_ror:1 row_mask:0xf bank_mask:0xf
	v_mov_b32_e32 v140, 0
	v_cndmask_b32_e32 v143, v122, v78, vcc
	v_cndmask_b32_e32 v146, v105, v73, vcc
	v_mov_b32_dpp v140, v141 row_ror:15 row_mask:0xf bank_mask:0xf
	v_cndmask_b32_e64 v141, v121, v137, s[44:45]
	v_mov_b32_e32 v137, 0
	v_cndmask_b32_e32 v147, v106, v74, vcc
	s_nop 0
	v_mov_b32_dpp v137, v141 row_ror:1 row_mask:0xf bank_mask:0xf
	v_mov_b32_e32 v141, 0
	v_pk_mul_f32 v[136:137], v[96:97], v[136:137]
	s_nop 0
	v_mov_b32_dpp v141, v142 row_ror:15 row_mask:0xf bank_mask:0xf
	v_pk_fma_f32 v[136:137], v[120:121], v[100:101], v[136:137]
	v_cndmask_b32_e64 v142, v122, v138, s[44:45]
	v_mov_b32_e32 v138, 0
	v_pk_fma_f32 v[136:137], v[108:109], v[140:141], v[136:137]
	s_nop 0
	v_mov_b32_dpp v138, v142 row_ror:1 row_mask:0xf bank_mask:0xf
	v_mov_b32_e32 v142, 0
	v_pk_add_f32 v[136:137], v[112:113], v[136:137]
	s_nop 0
	v_mov_b32_dpp v142, v143 row_ror:15 row_mask:0xf bank_mask:0xf
	v_cndmask_b32_e64 v143, v123, v139, s[44:45]
	v_mov_b32_e32 v139, 0
	v_mul_f32_e32 v140, 0xbfb8aa3b, v136
	v_mul_f32_e32 v141, 0xbfb8aa3b, v137
	v_mov_b32_dpp v139, v143 row_ror:1 row_mask:0xf bank_mask:0xf
	v_exp_f32_e32 v140, v140
	v_exp_f32_e32 v141, v141
	v_mov_b32_e32 v143, 0
	v_pk_mul_f32 v[138:139], v[98:99], v[138:139]
	v_add_f32_e32 v140, 1.0, v140
	v_mov_b32_dpp v143, v144 row_ror:15 row_mask:0xf bank_mask:0xf
	v_cndmask_b32_e64 v144, v104, v128, s[44:45]
	v_mov_b32_e32 v128, 0
	v_pk_fma_f32 v[138:139], v[122:123], v[102:103], v[138:139]
	v_add_f32_e32 v141, 1.0, v141
	v_mov_b32_dpp v128, v144 row_ror:1 row_mask:0xf bank_mask:0xf
	v_mov_b32_e32 v144, 0
	v_pk_fma_f32 v[138:139], v[110:111], v[142:143], v[138:139]
	v_rcp_f32_e32 v140, v140
	v_mov_b32_dpp v144, v145 row_ror:15 row_mask:0xf bank_mask:0xf
	v_cndmask_b32_e64 v145, v105, v129, s[44:45]
	v_mov_b32_e32 v129, 0
	v_pk_add_f32 v[138:139], v[114:115], v[138:139]
	v_rcp_f32_e32 v141, v141
	v_mov_b32_dpp v129, v145 row_ror:1 row_mask:0xf bank_mask:0xf
	v_mul_f32_e32 v142, 0xbfb8aa3b, v138
	v_mul_f32_e32 v143, 0xbfb8aa3b, v139
	v_mov_b32_e32 v145, 0
	v_pk_mul_f32 v[128:129], v[80:81], v[128:129]
	v_exp_f32_e32 v142, v142
	v_exp_f32_e32 v143, v143
; DI unsigned pack2(float a, float b) { f32x2 v = {a, b}; hwbf16x2 r = __builtin_convertvector(v, hwbf16x2); return __builtin_bit_cast(unsigned, r); }
; DI float dpp_ror1(float v)  { return __builtin_bit_cast(float, __builtin_amdgcn_update_dpp(0, __builtin_bit_cast(int, v), 0x121, 0xf, 0xf, false)); }
; DI float dpp_ror15(float v) { return __builtin_bit_cast(float, __builtin_amdgcn_update_dpp(0, __builtin_bit_cast(int, v), 0x12F, 0xf, 0xf, false)); }
; DI float silu_mul(float g, float v) { return g * v * __builtin_amdgcn_rcpf(1.0f + __builtin_amdgcn_exp2f(-LOG2E * g)); }
;     DI void operator()(const f32x4 (&acc)[2][2][4][2], const Unit& u, int wr, int wc, int fr, int fq) const {
;     ...
;                 for (int n = 0; n < 2; ++n) {
;                     const f32x4 g = acc[ai][0][m][n];
;                     const f32x4 gprev = acc[ai][0][m > 0 ? m - 1 : 0][n], gnext = acc[ai][0][m < 3 ? m + 1 : 3][n];
;                     f32x4 up, dn;
; #pragma unroll
;                     for (int e = 0; e < 4; ++e) {
;                         const float pu = (m > 0 && fr == 15) ? gprev[e] : g[e];
;                         const float pd = (m < 3 && fr == 0) ? gnext[e] : g[e];
;                         up[e] = dpp_ror1(pu); dn[e] = dpp_ror15(pd);
;                     }
;                     if (efirst) up = (f32x4){0.f, 0.f, 0.f, 0.f};
;                     if (elast) dn = (f32x4){0.f, 0.f, 0.f, 0.f};
;                     gc[n] = w0[n] * up + w1[n] * g + w2[n] * dn + bb[n];
;                 }
;                 if (efirst || elast) {
;                     const size_t eo = (size_t)((row >> 6) * 2 + (elast ? 1 : 0)) * DFF + ch0;
; #pragma unroll
;                     for (int n = 0; n < 2; ++n) { *(f32x4*)(EP + eo + 4 * n) = gc[n]; *(f32x4*)(ER + eo + 4 * n) = acc[ai][0][m][n]; *(f32x4*)(EV + eo + 4 * n) = acc[ai][1][m][n]; }
;                 } else {
;                     const f32x4 v0 = acc[ai][1][m][0], v1 = acc[ai][1][m][1];
;                     u32x4 o;
;                     o[0] = pack2(silu_mul(gc[0][0], v0[0]), silu_mul(gc[0][1], v0[1])); o[1] = pack2(silu_mul(gc[0][2], v0[2]), silu_mul(gc[0][3], v0[3]));
;                     o[2] = pack2(silu_mul(gc[1][0], v1[0]), silu_mul(gc[1][1], v1[1])); o[3] = pack2(silu_mul(gc[1][2], v1[2]), silu_mul(gc[1][3], v1[3]));
;                     *(u32x4*)(ACT + (size_t)row * DFF + ch0) = o;
;                 }
	v_mov_b32_dpp v145, v146 row_ror:15 row_mask:0xf bank_mask:0xf
	v_pk_fma_f32 v[128:129], v[104:105], v[84:85], v[128:129]
	v_cndmask_b32_e64 v146, v106, v130, s[44:45]
	v_mov_b32_e32 v130, 0
	v_pk_fma_f32 v[128:129], v[88:89], v[144:145], v[128:129]
	v_pk_mul_f32 v[124:125], v[124:125], v[136:137]
	v_mov_b32_dpp v130, v146 row_ror:1 row_mask:0xf bank_mask:0xf
	v_mov_b32_e32 v146, 0
	v_pk_add_f32 v[128:129], v[92:93], v[128:129]
	v_pk_mul_f32 v[124:125], v[124:125], v[140:141]
	v_mov_b32_dpp v146, v147 row_ror:15 row_mask:0xf bank_mask:0xf
	v_cndmask_b32_e64 v147, v107, v131, s[44:45]
	v_mov_b32_e32 v131, 0
	v_pk_mul_f32 v[126:127], v[126:127], v[138:139]
	v_add_f32_e32 v138, 1.0, v142
	v_add_f32_e32 v139, 1.0, v143
	v_cvt_pk_bf16_f32 v124, v124, v125
	v_mul_f32_e32 v125, 0xbfb8aa3b, v128
	v_mov_b32_dpp v131, v147 row_ror:1 row_mask:0xf bank_mask:0xf
	v_rcp_f32_e32 v138, v138
	v_rcp_f32_e32 v139, v139
	v_exp_f32_e32 v136, v125
	v_mul_f32_e32 v125, 0xbfb8aa3b, v129
	v_mov_b32_e32 v147, 0
	v_pk_mul_f32 v[130:131], v[82:83], v[130:131]
	v_exp_f32_e32 v137, v125
	v_mov_b32_dpp v147, v148 row_ror:15 row_mask:0xf bank_mask:0xf
	v_pk_fma_f32 v[130:131], v[106:107], v[86:87], v[130:131]
	v_pk_mul_f32 v[126:127], v[126:127], v[138:139]
	v_pk_fma_f32 v[130:131], v[90:91], v[146:147], v[130:131]
	v_cvt_pk_bf16_f32 v125, v126, v127
	v_pk_add_f32 v[130:131], v[94:95], v[130:131]
	v_add_f32_e32 v126, 1.0, v136
	v_add_f32_e32 v127, 1.0, v137
	v_mul_f32_e32 v136, 0xbfb8aa3b, v130
	v_mul_f32_e32 v137, 0xbfb8aa3b, v131
	v_exp_f32_e32 v136, v136
	v_exp_f32_e32 v137, v137
	v_rcp_f32_e32 v126, v126
	v_rcp_f32_e32 v127, v127
	v_pk_mul_f32 v[118:119], v[118:119], v[130:131]
	v_add_f32_e32 v130, 1.0, v136
	v_add_f32_e32 v131, 1.0, v137
	v_rcp_f32_e32 v130, v130
	v_rcp_f32_e32 v131, v131
	v_pk_mul_f32 v[116:117], v[116:117], v[128:129]
	v_add_u32_e32 v148, 32, v193
	v_pk_mul_f32 v[116:117], v[116:117], v[126:127]
	s_nop 0
	v_cvt_pk_bf16_f32 v126, v116, v117
	v_pk_mul_f32 v[116:117], v[118:119], v[130:131]
	v_cndmask_b32_e64 v118, v77, v121, s[44:45]
	v_cvt_pk_bf16_f32 v127, v116, v117
	v_mad_i64_i32 v[116:117], s[28:29], v148, s60, v[134:135]
	v_lshl_add_u64 v[116:117], v[116:117], 0, v[132:133]
	global_store_dwordx4 v[116:117], v[124:127], off
	v_cndmask_b32_e64 v117, v76, v120, s[44:45]
	v_mov_b32_e32 v116, 0
	v_cndmask_b32_e64 v119, v78, v122, s[44:45]
	v_cndmask_b32_e64 v121, v79, v123, s[44:45]
	v_mov_b32_dpp v116, v117 row_ror:1 row_mask:0xf bank_mask:0xf
	v_mov_b32_e32 v117, 0
	v_mov_b32_e32 v120, 0
	v_mov_b32_e32 v124, 0
	v_mov_b32_dpp v117, v118 row_ror:1 row_mask:0xf bank_mask:0xf
	v_mov_b32_e32 v118, 0
	v_mov_b32_dpp v120, v78 row_ror:15 row_mask:0xf bank_mask:0xf
	v_cndmask_b32_e64 v120, v120, 0, s[44:45]
	v_mov_b32_dpp v118, v119 row_ror:1 row_mask:0xf bank_mask:0xf
	v_mov_b32_e32 v119, 0
	v_mov_b32_e32 v125, 0
	v_mov_b32_dpp v124, v76 row_ror:15 row_mask:0xf bank_mask:0xf
	v_mov_b32_dpp v119, v121 row_ror:1 row_mask:0xf bank_mask:0xf
	v_mov_b32_e32 v121, 0
	v_pk_mul_f32 v[118:119], v[98:99], v[118:119]
	v_mov_b32_dpp v125, v77 row_ror:15 row_mask:0xf bank_mask:0xf
	v_mov_b32_dpp v121, v79 row_ror:15 row_mask:0xf bank_mask:0xf
	v_cndmask_b32_e64 v121, v121, 0, s[44:45]
	v_pk_fma_f32 v[118:119], v[78:79], v[102:103], v[118:119]
	v_pk_mul_f32 v[116:117], v[96:97], v[116:117]
	v_pk_fma_f32 v[118:119], v[110:111], v[120:121], v[118:119]
	v_cndmask_b32_e64 v120, v72, v104, s[44:45]
	v_mov_b32_e32 v104, 0
	v_cndmask_b32_e64 v123, v125, 0, s[44:45]
	v_cndmask_b32_e64 v122, v124, 0, s[44:45]
	v_mov_b32_dpp v104, v120 row_ror:1 row_mask:0xf bank_mask:0xf
	v_cndmask_b32_e64 v120, v73, v105, s[44:45]
	v_mov_b32_e32 v105, 0
	v_pk_fma_f32 v[116:117], v[76:77], v[100:101], v[116:117]
	v_cndmask_b32_e64 v121, v75, v107, s[44:45]
	v_mov_b32_dpp v105, v120 row_ror:1 row_mask:0xf bank_mask:0xf
	v_cndmask_b32_e64 v120, v74, v106, s[44:45]
	v_mov_b32_e32 v106, 0
	v_mov_b32_e32 v107, 0
	v_pk_fma_f32 v[116:117], v[108:109], v[122:123], v[116:117]
	v_mov_b32_e32 v122, 0
	v_mov_b32_e32 v123, 0
	v_mov_b32_dpp v106, v120 row_ror:1 row_mask:0xf bank_mask:0xf
	v_mov_b32_e32 v120, 0
	v_mov_b32_dpp v107, v121 row_ror:1 row_mask:0xf bank_mask:0xf
	v_mov_b32_e32 v121, 0
	v_mov_b32_dpp v122, v72 row_ror:15 row_mask:0xf bank_mask:0xf
	v_mov_b32_dpp v123, v73 row_ror:15 row_mask:0xf bank_mask:0xf
	v_mov_b32_dpp v120, v74 row_ror:15 row_mask:0xf bank_mask:0xf
	v_mov_b32_dpp v121, v75 row_ror:15 row_mask:0xf bank_mask:0xf
	v_pk_mul_f32 v[104:105], v[80:81], v[104:105]
	v_pk_mul_f32 v[106:107], v[82:83], v[106:107]
	v_cndmask_b32_e64 v121, v121, 0, s[44:45]
	v_cndmask_b32_e64 v120, v120, 0, s[44:45]
	v_cndmask_b32_e64 v123, v123, 0, s[44:45]
	v_cndmask_b32_e64 v122, v122, 0, s[44:45]
	v_pk_fma_f32 v[106:107], v[74:75], v[86:87], v[106:107]
	v_pk_fma_f32 v[104:105], v[72:73], v[84:85], v[104:105]
	v_pk_fma_f32 v[106:107], v[90:91], v[120:121], v[106:107]
	v_pk_fma_f32 v[104:105], v[88:89], v[122:123], v[104:105]
	v_pk_add_f32 v[118:119], v[114:115], v[118:119]
	v_pk_add_f32 v[116:117], v[112:113], v[116:117]
	v_pk_add_f32 v[106:107], v[94:95], v[106:107]
	v_pk_add_f32 v[104:105], v[92:93], v[104:105]
	v_add_u32_e32 v120, 48, v193
	s_and_saveexec_b64 s[28:29], s[42:43]
	s_xor_b64 s[28:29], exec, s[28:29]
	s_cbranch_execz .LBB1_1915
	v_mul_f32_e32 v121, 0xbfb8aa3b, v116
	v_exp_f32_e32 v121, v121
	v_mul_f32_e32 v122, 0xbfb8aa3b, v117
	v_exp_f32_e32 v122, v122
	v_mul_f32_e32 v124, 0xbfb8aa3b, v119
	v_add_f32_e32 v121, 1.0, v121
	v_exp_f32_e32 v125, v124
	v_add_f32_e32 v123, 1.0, v122
	v_rcp_f32_e32 v122, v121
	v_mul_f32_e32 v121, 0xbfb8aa3b, v118
	v_exp_f32_e32 v121, v121
	v_rcp_f32_e32 v123, v123
	v_pk_mul_f32 v[116:117], v[68:69], v[116:117]
	v_pk_mul_f32 v[118:119], v[70:71], v[118:119]
	v_add_f32_e32 v121, 1.0, v121
	v_rcp_f32_e32 v124, v121
	v_add_f32_e32 v121, 1.0, v125
	v_pk_mul_f32 v[116:117], v[116:117], v[122:123]
	v_rcp_f32_e32 v125, v121
	v_cvt_pk_bf16_f32 v116, v116, v117
	v_mul_f32_e32 v117, 0xbfb8aa3b, v104
	v_exp_f32_e32 v121, v117
	v_mul_f32_e32 v117, 0xbfb8aa3b, v105
	v_exp_f32_e32 v122, v117
	v_pk_mul_f32 v[118:119], v[118:119], v[124:125]
	v_pk_mul_f32 v[104:105], v[64:65], v[104:105]
	v_cvt_pk_bf16_f32 v117, v118, v119
	v_add_f32_e32 v118, 1.0, v121
	v_mul_f32_e32 v121, 0xbfb8aa3b, v106
	v_add_f32_e32 v119, 1.0, v122
	v_exp_f32_e32 v121, v121
	v_mul_f32_e32 v122, 0xbfb8aa3b, v107
	v_exp_f32_e32 v123, v122
	v_rcp_f32_e32 v118, v118
	v_add_f32_e32 v121, 1.0, v121
	v_rcp_f32_e32 v119, v119
	v_rcp_f32_e32 v122, v121
	v_add_f32_e32 v121, 1.0, v123
	v_rcp_f32_e32 v123, v121
	v_pk_mul_f32 v[106:107], v[66:67], v[106:107]
	v_pk_mul_f32 v[104:105], v[104:105], v[118:119]
	s_nop 0
	v_cvt_pk_bf16_f32 v118, v104, v105
	v_pk_mul_f32 v[104:105], v[106:107], v[122:123]
	s_nop 0
	v_cvt_pk_bf16_f32 v119, v104, v105
	v_mov_b64_e32 v[104:105], s[52:53]
	v_mad_i64_i32 v[104:105], s[58:59], v120, s60, v[104:105]
	v_lshl_add_u64 v[104:105], v[184:185], 1, v[104:105]
	global_store_dwordx4 v[104:105], v[116:119], off
; DI unsigned pack2(float a, float b) { f32x2 v = {a, b}; hwbf16x2 r = __builtin_convertvector(v, hwbf16x2); return __builtin_bit_cast(unsigned, r); }
; DI float dpp_ror1(float v)  { return __builtin_bit_cast(float, __builtin_amdgcn_update_dpp(0, __builtin_bit_cast(int, v), 0x121, 0xf, 0xf, false)); }
; DI float dpp_ror15(float v) { return __builtin_bit_cast(float, __builtin_amdgcn_update_dpp(0, __builtin_bit_cast(int, v), 0x12F, 0xf, 0xf, false)); }
; DI float silu_mul(float g, float v) { return g * v * __builtin_amdgcn_rcpf(1.0f + __builtin_amdgcn_exp2f(-LOG2E * g)); }
;     DI void operator()(const f32x4 (&acc)[2][2][4][2], const Unit& u, int wr, int wc, int fr, int fq) const {
;     ...
;                 for (int n = 0; n < 2; ++n) {
;                     const f32x4 g = acc[ai][0][m][n];
;                     const f32x4 gprev = acc[ai][0][m > 0 ? m - 1 : 0][n], gnext = acc[ai][0][m < 3 ? m + 1 : 3][n];
;                     f32x4 up, dn;
; #pragma unroll
;                     for (int e = 0; e < 4; ++e) {
;                         const float pu = (m > 0 && fr == 15) ? gprev[e] : g[e];
;                         const float pd = (m < 3 && fr == 0) ? gnext[e] : g[e];
;                         up[e] = dpp_ror1(pu); dn[e] = dpp_ror15(pd);
;                     }
;                     if (efirst) up = (f32x4){0.f, 0.f, 0.f, 0.f};
;                     if (elast) dn = (f32x4){0.f, 0.f, 0.f, 0.f};
;                     gc[n] = w0[n] * up + w1[n] * g + w2[n] * dn + bb[n];
;                 }
;                 if (efirst || elast) {
;                     const size_t eo = (size_t)((row >> 6) * 2 + (elast ? 1 : 0)) * DFF + ch0;
; #pragma unroll
;                     for (int n = 0; n < 2; ++n) { *(f32x4*)(EP + eo + 4 * n) = gc[n]; *(f32x4*)(ER + eo + 4 * n) = acc[ai][0][m][n]; *(f32x4*)(EV + eo + 4 * n) = acc[ai][1][m][n]; }
;                 } else {
;                     const f32x4 v0 = acc[ai][1][m][0], v1 = acc[ai][1][m][1];
;                     u32x4 o;
;                     o[0] = pack2(silu_mul(gc[0][0], v0[0]), silu_mul(gc[0][1], v0[1])); o[1] = pack2(silu_mul(gc[0][2], v0[2]), silu_mul(gc[0][3], v0[3]));
;                     o[2] = pack2(silu_mul(gc[1][0], v1[0]), silu_mul(gc[1][1], v1[1])); o[3] = pack2(silu_mul(gc[1][2], v1[2]), silu_mul(gc[1][3], v1[3]));
;                     *(u32x4*)(ACT + (size_t)row * DFF + ch0) = o;
;                 }
.LBB1_1915:
	s_or_saveexec_b64 s[28:29], s[28:29]
	s_mov_b64 s[68:69], s[72:73]
	s_xor_b64 exec, exec, s[28:29]
	s_cbranch_execz .LBB1_1917
	v_ashrrev_i32_e32 v120, 5, v120
	v_mad_i64_i32 v[120:121], s[58:59], v120, s61, v[184:185]
	v_lshlrev_b64 v[120:121], 2, v[120:121]
	v_lshl_add_u64 v[122:123], s[8:9], 0, v[120:121]
	global_store_dwordx4 v[122:123], v[116:119], off
	s_nop 1
	v_lshl_add_u64 v[116:117], s[10:11], 0, v[120:121]
	global_store_dwordx4 v[116:117], v[76:79], off
	s_nop 1
	v_lshl_add_u64 v[76:77], s[12:13], 0, v[120:121]
	global_store_dwordx4 v[76:77], v[68:71], off
	global_store_dwordx4 v[122:123], v[104:107], off offset:16
	global_store_dwordx4 v[116:117], v[72:75], off offset:16
	global_store_dwordx4 v[76:77], v[64:67], off offset:16
.LBB1_1917:
	s_or_b64 exec, exec, s[28:29]
	s_nop 0
	v_cndmask_b32_e32 v65, v60, v40, vcc
	v_mov_b32_e32 v64, 0
	v_cndmask_b32_e32 v66, v61, v41, vcc
	v_cndmask_b32_e32 v67, v62, v42, vcc
	v_mov_b32_dpp v64, v65 row_ror:15 row_mask:0xf bank_mask:0xf
	v_mov_b32_e32 v65, 0
	v_mov_b32_e32 v68, 0
	v_mov_b32_e32 v73, 0
	v_mov_b32_dpp v65, v66 row_ror:15 row_mask:0xf bank_mask:0xf
	v_mov_b32_e32 v66, 0
	v_mov_b32_e32 v70, 0
	v_mov_b32_e32 v71, 0
	v_mov_b32_dpp v68, v62 row_ror:1 row_mask:0xf bank_mask:0xf
	v_mov_b32_dpp v66, v67 row_ror:15 row_mask:0xf bank_mask:0xf
	v_cndmask_b32_e32 v69, v63, v43, vcc
	v_mov_b32_dpp v73, v63 row_ror:1 row_mask:0xf bank_mask:0xf
	v_mov_b32_e32 v67, 0
	v_mov_b32_dpp v70, v60 row_ror:1 row_mask:0xf bank_mask:0xf
	v_mov_b32_dpp v71, v61 row_ror:1 row_mask:0xf bank_mask:0xf
	v_mov_b32_dpp v67, v69 row_ror:15 row_mask:0xf bank_mask:0xf
	v_cndmask_b32_e64 v69, v73, 0, vcc
	v_cndmask_b32_e64 v68, v68, 0, vcc
	v_cndmask_b32_e64 v71, v71, 0, vcc
	v_cndmask_b32_e64 v70, v70, 0, vcc
	v_pk_mul_f32 v[68:69], v[98:99], v[68:69]
	v_pk_mul_f32 v[70:71], v[96:97], v[70:71]
	v_pk_fma_f32 v[68:69], v[62:63], v[102:103], v[68:69]
	v_pk_fma_f32 v[70:71], v[60:61], v[100:101], v[70:71]
	v_pk_fma_f32 v[66:67], v[110:111], v[66:67], v[68:69]
	v_cndmask_b32_e32 v69, v48, v32, vcc
	v_mov_b32_e32 v68, 0
	v_pk_fma_f32 v[64:65], v[108:109], v[64:65], v[70:71]
	v_cndmask_b32_e32 v70, v49, v33, vcc
	v_mov_b32_dpp v68, v69 row_ror:15 row_mask:0xf bank_mask:0xf
	v_mov_b32_e32 v69, 0
	v_mov_b32_e32 v73, 0
	v_mov_b32_e32 v76, 0
	v_mov_b32_dpp v69, v70 row_ror:15 row_mask:0xf bank_mask:0xf
	v_cndmask_b32_e32 v71, v50, v34, vcc
	v_mov_b32_e32 v74, 0
	v_mov_b32_e32 v70, 0
	v_mov_b32_e32 v77, 0
	v_mov_b32_dpp v73, v48 row_ror:1 row_mask:0xf bank_mask:0xf
	v_mov_b32_dpp v76, v49 row_ror:1 row_mask:0xf bank_mask:0xf
	v_mov_b32_dpp v74, v50 row_ror:1 row_mask:0xf bank_mask:0xf
	v_mov_b32_dpp v70, v71 row_ror:15 row_mask:0xf bank_mask:0xf
	v_cndmask_b32_e32 v75, v51, v35, vcc
	v_mov_b32_dpp v77, v51 row_ror:1 row_mask:0xf bank_mask:0xf
	v_mov_b32_e32 v71, 0
	v_cndmask_b32_e64 v74, v74, 0, vcc
	v_add_u32_e32 v72, 0x80, v193
	v_mov_b32_dpp v71, v75 row_ror:15 row_mask:0xf bank_mask:0xf
	v_cndmask_b32_e64 v75, v77, 0, vcc
	v_cndmask_b32_e64 v77, v76, 0, vcc
	v_cndmask_b32_e64 v76, v73, 0, vcc
	v_pk_mul_f32 v[76:77], v[80:81], v[76:77]
	v_pk_mul_f32 v[74:75], v[82:83], v[74:75]
	v_pk_fma_f32 v[76:77], v[48:49], v[84:85], v[76:77]
	v_pk_fma_f32 v[74:75], v[50:51], v[86:87], v[74:75]
	v_pk_fma_f32 v[68:69], v[88:89], v[68:69], v[76:77]
	v_pk_fma_f32 v[70:71], v[90:91], v[70:71], v[74:75]
	v_pk_add_f32 v[66:67], v[114:115], v[66:67]
	v_pk_add_f32 v[64:65], v[112:113], v[64:65]
	v_pk_add_f32 v[70:71], v[94:95], v[70:71]
	v_pk_add_f32 v[68:69], v[92:93], v[68:69]
	s_and_saveexec_b64 s[28:29], s[46:47]
	s_xor_b64 s[28:29], exec, s[28:29]
	s_cbranch_execz .LBB1_1919
	v_mul_f32_e32 v73, 0xbfb8aa3b, v64
	v_exp_f32_e32 v73, v73
	v_mul_f32_e32 v74, 0xbfb8aa3b, v65
	v_exp_f32_e32 v74, v74
	v_mul_f32_e32 v76, 0xbfb8aa3b, v67
	v_add_f32_e32 v73, 1.0, v73
	v_exp_f32_e32 v77, v76
	v_add_f32_e32 v75, 1.0, v74
	v_rcp_f32_e32 v74, v73
	v_mul_f32_e32 v73, 0xbfb8aa3b, v66
	v_exp_f32_e32 v73, v73
	v_rcp_f32_e32 v75, v75
	v_pk_mul_f32 v[64:65], v[56:57], v[64:65]
	v_pk_mul_f32 v[66:67], v[58:59], v[66:67]
	v_add_f32_e32 v73, 1.0, v73
	v_rcp_f32_e32 v76, v73
	v_add_f32_e32 v73, 1.0, v77
	v_pk_mul_f32 v[64:65], v[64:65], v[74:75]
	v_rcp_f32_e32 v77, v73
	v_cvt_pk_bf16_f32 v64, v64, v65
	v_mul_f32_e32 v65, 0xbfb8aa3b, v68
	v_exp_f32_e32 v73, v65
	v_mul_f32_e32 v65, 0xbfb8aa3b, v69
	v_exp_f32_e32 v74, v65
	v_pk_mul_f32 v[66:67], v[66:67], v[76:77]
	v_pk_mul_f32 v[68:69], v[52:53], v[68:69]
	v_cvt_pk_bf16_f32 v65, v66, v67
	v_add_f32_e32 v66, 1.0, v73
	v_mul_f32_e32 v73, 0xbfb8aa3b, v70
	v_add_f32_e32 v67, 1.0, v74
	v_exp_f32_e32 v73, v73
	v_mul_f32_e32 v74, 0xbfb8aa3b, v71
	v_exp_f32_e32 v75, v74
	v_rcp_f32_e32 v66, v66
	v_add_f32_e32 v73, 1.0, v73
	v_rcp_f32_e32 v74, v73
	v_add_f32_e32 v73, 1.0, v75
	v_rcp_f32_e32 v67, v67
	v_rcp_f32_e32 v75, v73
	v_pk_mul_f32 v[70:71], v[54:55], v[70:71]
	v_pk_mul_f32 v[66:67], v[68:69], v[66:67]
	v_pk_mul_f32 v[68:69], v[70:71], v[74:75]
	v_cvt_pk_bf16_f32 v66, v66, v67
	v_cvt_pk_bf16_f32 v67, v68, v69
	v_mov_b64_e32 v[68:69], s[52:53]
	v_mad_i64_i32 v[68:69], s[46:47], v72, s60, v[68:69]
	v_lshl_add_u64 v[68:69], v[184:185], 1, v[68:69]
	global_store_dwordx4 v[68:69], v[64:67], off
.LBB1_1919:
	s_andn2_saveexec_b64 s[28:29], s[28:29]
	s_cbranch_execz .LBB1_1921
	v_ashrrev_i32_e32 v72, 5, v72
	v_mad_i64_i32 v[72:73], s[46:47], v72, s61, v[184:185]
	v_lshlrev_b64 v[72:73], 2, v[72:73]
	v_lshl_add_u64 v[74:75], s[8:9], 0, v[72:73]
	global_store_dwordx4 v[74:75], v[64:67], off
	s_nop 1
	v_lshl_add_u64 v[64:65], s[10:11], 0, v[72:73]
	v_lshl_add_u64 v[66:67], s[12:13], 0, v[72:73]
	global_store_dwordx4 v[64:65], v[60:63], off
	global_store_dwordx4 v[66:67], v[56:59], off
	global_store_dwordx4 v[74:75], v[68:71], off offset:16
	global_store_dwordx4 v[64:65], v[48:51], off offset:16
	global_store_dwordx4 v[66:67], v[52:55], off offset:16
; DI unsigned pack2(float a, float b) { f32x2 v = {a, b}; hwbf16x2 r = __builtin_convertvector(v, hwbf16x2); return __builtin_bit_cast(unsigned, r); }
; DI float dpp_ror1(float v)  { return __builtin_bit_cast(float, __builtin_amdgcn_update_dpp(0, __builtin_bit_cast(int, v), 0x121, 0xf, 0xf, false)); }
; DI float dpp_ror15(float v) { return __builtin_bit_cast(float, __builtin_amdgcn_update_dpp(0, __builtin_bit_cast(int, v), 0x12F, 0xf, 0xf, false)); }
; DI float silu_mul(float g, float v) { return g * v * __builtin_amdgcn_rcpf(1.0f + __builtin_amdgcn_exp2f(-LOG2E * g)); }
;     DI void operator()(const f32x4 (&acc)[2][2][4][2], const Unit& u, int wr, int wc, int fr, int fq) const {
;     ...
;                 for (int n = 0; n < 2; ++n) {
;                     const f32x4 g = acc[ai][0][m][n];
;                     const f32x4 gprev = acc[ai][0][m > 0 ? m - 1 : 0][n], gnext = acc[ai][0][m < 3 ? m + 1 : 3][n];
;                     f32x4 up, dn;
; #pragma unroll
;                     for (int e = 0; e < 4; ++e) {
;                         const float pu = (m > 0 && fr == 15) ? gprev[e] : g[e];
;                         const float pd = (m < 3 && fr == 0) ? gnext[e] : g[e];
;                         up[e] = dpp_ror1(pu); dn[e] = dpp_ror15(pd);
;                     }
;                     if (efirst) up = (f32x4){0.f, 0.f, 0.f, 0.f};
;                     if (elast) dn = (f32x4){0.f, 0.f, 0.f, 0.f};
;                     gc[n] = w0[n] * up + w1[n] * g + w2[n] * dn + bb[n];
;                 }
;                 if (efirst || elast) {
;                     const size_t eo = (size_t)((row >> 6) * 2 + (elast ? 1 : 0)) * DFF + ch0;
; #pragma unroll
;                     for (int n = 0; n < 2; ++n) { *(f32x4*)(EP + eo + 4 * n) = gc[n]; *(f32x4*)(ER + eo + 4 * n) = acc[ai][0][m][n]; *(f32x4*)(EV + eo + 4 * n) = acc[ai][1][m][n]; }
;                 } else {
;                     const f32x4 v0 = acc[ai][1][m][0], v1 = acc[ai][1][m][1];
;                     u32x4 o;
;                     o[0] = pack2(silu_mul(gc[0][0], v0[0]), silu_mul(gc[0][1], v0[1])); o[1] = pack2(silu_mul(gc[0][2], v0[2]), silu_mul(gc[0][3], v0[3]));
;                     o[2] = pack2(silu_mul(gc[1][0], v1[0]), silu_mul(gc[1][1], v1[1])); o[3] = pack2(silu_mul(gc[1][2], v1[2]), silu_mul(gc[1][3], v1[3]));
;                     *(u32x4*)(ACT + (size_t)row * DFF + ch0) = o;
.LBB1_1921:
	s_or_b64 exec, exec, s[28:29]
	s_nop 0
	v_cndmask_b32_e64 v53, v40, v60, s[44:45]
	v_cndmask_b32_e32 v55, v40, v24, vcc
	v_mov_b32_e32 v52, 0
	v_mov_b32_e32 v54, 0
	v_cndmask_b32_e32 v56, v41, v25, vcc
	v_mov_b32_dpp v52, v53 row_ror:1 row_mask:0xf bank_mask:0xf
	v_mov_b32_dpp v54, v55 row_ror:15 row_mask:0xf bank_mask:0xf
	v_cndmask_b32_e64 v55, v41, v61, s[44:45]
	v_mov_b32_e32 v53, 0
	v_cndmask_b32_e64 v57, v42, v62, s[44:45]
	v_cndmask_b32_e32 v59, v42, v26, vcc
	v_mov_b32_dpp v53, v55 row_ror:1 row_mask:0xf bank_mask:0xf
	v_mov_b32_e32 v55, 0
	v_mov_b32_e32 v58, 0
	v_pk_mul_f32 v[52:53], v[96:97], v[52:53]
	v_mov_b32_dpp v55, v56 row_ror:15 row_mask:0xf bank_mask:0xf
	v_mov_b32_e32 v56, 0
	v_mov_b32_dpp v58, v59 row_ror:15 row_mask:0xf bank_mask:0xf
	v_cndmask_b32_e64 v59, v43, v63, s[44:45]
	v_mov_b32_dpp v56, v57 row_ror:1 row_mask:0xf bank_mask:0xf
	v_mov_b32_e32 v57, 0
	v_pk_fma_f32 v[52:53], v[40:41], v[100:101], v[52:53]
	v_cndmask_b32_e32 v60, v43, v27, vcc
	v_mov_b32_dpp v57, v59 row_ror:1 row_mask:0xf bank_mask:0xf
	v_pk_fma_f32 v[52:53], v[108:109], v[54:55], v[52:53]
	v_mov_b32_e32 v59, 0
	v_pk_mul_f32 v[56:57], v[98:99], v[56:57]
	v_pk_add_f32 v[52:53], v[112:113], v[52:53]
	v_mov_b32_dpp v59, v60 row_ror:15 row_mask:0xf bank_mask:0xf
	v_pk_fma_f32 v[56:57], v[42:43], v[102:103], v[56:57]
	v_mul_f32_e32 v54, 0xbfb8aa3b, v52
	v_pk_fma_f32 v[56:57], v[110:111], v[58:59], v[56:57]
	v_exp_f32_e32 v58, v54
	v_mul_f32_e32 v54, 0xbfb8aa3b, v53
	v_exp_f32_e32 v59, v54
	v_cndmask_b32_e64 v60, v32, v48, s[44:45]
	v_mov_b32_e32 v48, 0
	v_cndmask_b32_e32 v61, v32, v16, vcc
	v_pk_add_f32 v[54:55], v[114:115], v[56:57]
	v_mov_b32_dpp v48, v60 row_ror:1 row_mask:0xf bank_mask:0xf
	v_mov_b32_e32 v60, 0
	v_add_f32_e32 v56, 1.0, v58
	v_add_f32_e32 v57, 1.0, v59
	v_mov_b32_dpp v60, v61 row_ror:15 row_mask:0xf bank_mask:0xf
	v_cndmask_b32_e64 v61, v33, v49, s[44:45]
	v_mov_b32_e32 v49, 0
	v_rcp_f32_e32 v56, v56
	v_rcp_f32_e32 v57, v57
	v_mov_b32_dpp v49, v61 row_ror:1 row_mask:0xf bank_mask:0xf
	v_mul_f32_e32 v58, 0xbfb8aa3b, v54
	v_mul_f32_e32 v59, 0xbfb8aa3b, v55
	v_cndmask_b32_e32 v62, v33, v17, vcc
	v_mov_b32_e32 v61, 0
	v_pk_mul_f32 v[48:49], v[80:81], v[48:49]
	v_exp_f32_e32 v58, v58
	v_exp_f32_e32 v59, v59
	v_mov_b32_dpp v61, v62 row_ror:15 row_mask:0xf bank_mask:0xf
	v_pk_fma_f32 v[48:49], v[32:33], v[84:85], v[48:49]
	v_cndmask_b32_e64 v62, v34, v50, s[44:45]
	v_mov_b32_e32 v50, 0
	v_pk_fma_f32 v[48:49], v[88:89], v[60:61], v[48:49]
	v_pk_mul_f32 v[44:45], v[44:45], v[52:53]
	v_cndmask_b32_e32 v63, v34, v18, vcc
	v_mov_b32_dpp v50, v62 row_ror:1 row_mask:0xf bank_mask:0xf
	v_mov_b32_e32 v62, 0
	v_pk_add_f32 v[48:49], v[92:93], v[48:49]
	v_pk_mul_f32 v[44:45], v[44:45], v[56:57]
	v_mov_b32_dpp v62, v63 row_ror:15 row_mask:0xf bank_mask:0xf
	v_cndmask_b32_e64 v63, v35, v51, s[44:45]
	v_mov_b32_e32 v51, 0
	v_pk_mul_f32 v[46:47], v[46:47], v[54:55]
	v_add_f32_e32 v54, 1.0, v58
	v_add_f32_e32 v55, 1.0, v59
	v_cvt_pk_bf16_f32 v44, v44, v45
	v_mul_f32_e32 v45, 0xbfb8aa3b, v48
	v_mov_b32_dpp v51, v63 row_ror:1 row_mask:0xf bank_mask:0xf
	v_rcp_f32_e32 v54, v54
	v_rcp_f32_e32 v55, v55
	v_exp_f32_e32 v52, v45
	v_mul_f32_e32 v45, 0xbfb8aa3b, v49
	v_cndmask_b32_e32 v64, v35, v19, vcc
	v_mov_b32_e32 v63, 0
	v_pk_mul_f32 v[50:51], v[82:83], v[50:51]
	v_exp_f32_e32 v53, v45
	v_mov_b32_dpp v63, v64 row_ror:15 row_mask:0xf bank_mask:0xf
	v_pk_fma_f32 v[50:51], v[34:35], v[86:87], v[50:51]
	v_pk_mul_f32 v[46:47], v[46:47], v[54:55]
	v_pk_fma_f32 v[50:51], v[90:91], v[62:63], v[50:51]
	v_cvt_pk_bf16_f32 v45, v46, v47
	v_pk_add_f32 v[50:51], v[94:95], v[50:51]
	v_add_f32_e32 v46, 1.0, v52
	v_add_f32_e32 v47, 1.0, v53
	v_mul_f32_e32 v52, 0xbfb8aa3b, v50
	v_mul_f32_e32 v53, 0xbfb8aa3b, v51
	v_exp_f32_e32 v52, v52
	v_exp_f32_e32 v53, v53
	v_rcp_f32_e32 v46, v46
	v_rcp_f32_e32 v47, v47
	v_pk_mul_f32 v[38:39], v[38:39], v[50:51]
	v_add_f32_e32 v50, 1.0, v52
	v_add_f32_e32 v51, 1.0, v53
	v_rcp_f32_e32 v50, v50
	v_rcp_f32_e32 v51, v51
	v_pk_mul_f32 v[36:37], v[36:37], v[48:49]
	v_add_u32_e32 v64, 0x90, v193
	v_pk_mul_f32 v[36:37], v[36:37], v[46:47]
	v_cndmask_b32_e64 v41, v25, v41, s[44:45]
	v_cvt_pk_bf16_f32 v46, v36, v37
	v_pk_mul_f32 v[36:37], v[38:39], v[50:51]
	v_cndmask_b32_e32 v48, v17, v9, vcc
	v_cvt_pk_bf16_f32 v47, v36, v37
	v_mov_b64_e32 v[36:37], s[52:53]
	v_mad_i64_i32 v[38:39], s[28:29], v64, s60, v[36:37]
	v_lshl_add_u64 v[38:39], v[38:39], 0, v[132:133]
	global_store_dwordx4 v[38:39], v[44:47], off
	v_cndmask_b32_e64 v39, v24, v40, s[44:45]
	v_mov_b32_e32 v38, 0
	v_cndmask_b32_e32 v44, v24, v12, vcc
	v_mov_b32_e32 v40, 0
	v_mov_b32_dpp v38, v39 row_ror:1 row_mask:0xf bank_mask:0xf
	v_mov_b32_e32 v39, 0
	v_mov_b32_dpp v40, v44 row_ror:15 row_mask:0xf bank_mask:0xf
	v_cndmask_b32_e32 v44, v25, v13, vcc
	v_mov_b32_dpp v39, v41 row_ror:1 row_mask:0xf bank_mask:0xf
	v_mov_b32_e32 v41, 0
	v_cndmask_b32_e32 v45, v26, v14, vcc
	v_pk_mul_f32 v[38:39], v[96:97], v[38:39]
	v_mov_b32_dpp v41, v44 row_ror:15 row_mask:0xf bank_mask:0xf
	v_cndmask_b32_e64 v44, v26, v42, s[44:45]
	v_mov_b32_e32 v42, 0
	v_pk_fma_f32 v[38:39], v[24:25], v[100:101], v[38:39]
	v_cndmask_b32_e32 v46, v27, v15, vcc
	v_mov_b32_dpp v42, v44 row_ror:1 row_mask:0xf bank_mask:0xf
	v_mov_b32_e32 v44, 0
	v_pk_fma_f32 v[38:39], v[108:109], v[40:41], v[38:39]
	v_cndmask_b32_e32 v47, v16, v8, vcc
	v_mov_b32_dpp v44, v45 row_ror:15 row_mask:0xf bank_mask:0xf
	v_cndmask_b32_e64 v45, v27, v43, s[44:45]
	v_mov_b32_e32 v43, 0
	v_pk_add_f32 v[38:39], v[112:113], v[38:39]
	v_cndmask_b32_e32 v49, v18, v10, vcc
	v_mov_b32_dpp v43, v45 row_ror:1 row_mask:0xf bank_mask:0xf
; DI unsigned pack2(float a, float b) { f32x2 v = {a, b}; hwbf16x2 r = __builtin_convertvector(v, hwbf16x2); return __builtin_bit_cast(unsigned, r); }
; DI float dpp_ror1(float v)  { return __builtin_bit_cast(float, __builtin_amdgcn_update_dpp(0, __builtin_bit_cast(int, v), 0x121, 0xf, 0xf, false)); }
; DI float dpp_ror15(float v) { return __builtin_bit_cast(float, __builtin_amdgcn_update_dpp(0, __builtin_bit_cast(int, v), 0x12F, 0xf, 0xf, false)); }
; DI float silu_mul(float g, float v) { return g * v * __builtin_amdgcn_rcpf(1.0f + __builtin_amdgcn_exp2f(-LOG2E * g)); }
;     DI void operator()(const f32x4 (&acc)[2][2][4][2], const Unit& u, int wr, int wc, int fr, int fq) const {
;     ...
;                 for (int n = 0; n < 2; ++n) {
;                     const f32x4 g = acc[ai][0][m][n];
;                     const f32x4 gprev = acc[ai][0][m > 0 ? m - 1 : 0][n], gnext = acc[ai][0][m < 3 ? m + 1 : 3][n];
;                     f32x4 up, dn;
; #pragma unroll
;                     for (int e = 0; e < 4; ++e) {
;                         const float pu = (m > 0 && fr == 15) ? gprev[e] : g[e];
;                         const float pd = (m < 3 && fr == 0) ? gnext[e] : g[e];
;                         up[e] = dpp_ror1(pu); dn[e] = dpp_ror15(pd);
;                     }
;                     if (efirst) up = (f32x4){0.f, 0.f, 0.f, 0.f};
;                     if (elast) dn = (f32x4){0.f, 0.f, 0.f, 0.f};
;                     gc[n] = w0[n] * up + w1[n] * g + w2[n] * dn + bb[n];
;                 }
;                 if (efirst || elast) {
;                     const size_t eo = (size_t)((row >> 6) * 2 + (elast ? 1 : 0)) * DFF + ch0;
; #pragma unroll
;                     for (int n = 0; n < 2; ++n) { *(f32x4*)(EP + eo + 4 * n) = gc[n]; *(f32x4*)(ER + eo + 4 * n) = acc[ai][0][m][n]; *(f32x4*)(EV + eo + 4 * n) = acc[ai][1][m][n]; }
;                 } else {
;                     const f32x4 v0 = acc[ai][1][m][0], v1 = acc[ai][1][m][1];
;                     u32x4 o;
;                     o[0] = pack2(silu_mul(gc[0][0], v0[0]), silu_mul(gc[0][1], v0[1])); o[1] = pack2(silu_mul(gc[0][2], v0[2]), silu_mul(gc[0][3], v0[3]));
;                     o[2] = pack2(silu_mul(gc[1][0], v1[0]), silu_mul(gc[1][1], v1[1])); o[3] = pack2(silu_mul(gc[1][2], v1[2]), silu_mul(gc[1][3], v1[3]));
;                     *(u32x4*)(ACT + (size_t)row * DFF + ch0) = o;
	v_mov_b32_e32 v45, 0
	v_pk_mul_f32 v[42:43], v[98:99], v[42:43]
	v_mul_f32_e32 v40, 0xbfb8aa3b, v38
	v_mov_b32_dpp v45, v46 row_ror:15 row_mask:0xf bank_mask:0xf
	v_pk_fma_f32 v[42:43], v[26:27], v[102:103], v[42:43]
	v_cndmask_b32_e64 v46, v16, v32, s[44:45]
	v_pk_fma_f32 v[42:43], v[110:111], v[44:45], v[42:43]
	v_exp_f32_e32 v44, v40
	v_mul_f32_e32 v40, 0xbfb8aa3b, v39
	v_exp_f32_e32 v45, v40
	v_mov_b32_e32 v32, 0
	v_pk_add_f32 v[40:41], v[114:115], v[42:43]
	v_add_f32_e32 v42, 1.0, v44
	v_mov_b32_dpp v32, v46 row_ror:1 row_mask:0xf bank_mask:0xf
	v_mov_b32_e32 v46, 0
	v_add_f32_e32 v43, 1.0, v45
	v_rcp_f32_e32 v42, v42
	v_mov_b32_dpp v46, v47 row_ror:15 row_mask:0xf bank_mask:0xf
	v_cndmask_b32_e64 v47, v17, v33, s[44:45]
	v_mov_b32_e32 v33, 0
	v_rcp_f32_e32 v43, v43
	v_mul_f32_e32 v44, 0xbfb8aa3b, v40
	v_mov_b32_dpp v33, v47 row_ror:1 row_mask:0xf bank_mask:0xf
	v_mul_f32_e32 v45, 0xbfb8aa3b, v41
	v_mov_b32_e32 v47, 0
	v_pk_mul_f32 v[32:33], v[80:81], v[32:33]
	v_exp_f32_e32 v44, v44
	v_exp_f32_e32 v45, v45
	v_mov_b32_dpp v47, v48 row_ror:15 row_mask:0xf bank_mask:0xf
	v_pk_fma_f32 v[32:33], v[16:17], v[84:85], v[32:33]
	v_cndmask_b32_e64 v48, v18, v34, s[44:45]
	v_mov_b32_e32 v34, 0
	v_pk_fma_f32 v[32:33], v[88:89], v[46:47], v[32:33]
	v_pk_mul_f32 v[28:29], v[28:29], v[38:39]
	v_mov_b32_dpp v34, v48 row_ror:1 row_mask:0xf bank_mask:0xf
	v_mov_b32_e32 v48, 0
	v_pk_add_f32 v[32:33], v[92:93], v[32:33]
	v_pk_mul_f32 v[28:29], v[28:29], v[42:43]
	v_mov_b32_dpp v48, v49 row_ror:15 row_mask:0xf bank_mask:0xf
	v_cndmask_b32_e64 v49, v19, v35, s[44:45]
	v_mov_b32_e32 v35, 0
	v_pk_mul_f32 v[30:31], v[30:31], v[40:41]
	v_add_f32_e32 v40, 1.0, v44
	v_add_f32_e32 v41, 1.0, v45
	v_cvt_pk_bf16_f32 v28, v28, v29
	v_mul_f32_e32 v29, 0xbfb8aa3b, v32
	v_mov_b32_dpp v35, v49 row_ror:1 row_mask:0xf bank_mask:0xf
	v_rcp_f32_e32 v40, v40
	v_rcp_f32_e32 v41, v41
	v_exp_f32_e32 v38, v29
	v_mul_f32_e32 v29, 0xbfb8aa3b, v33
	v_cndmask_b32_e32 v50, v19, v11, vcc
	v_mov_b32_e32 v49, 0
	v_pk_mul_f32 v[34:35], v[82:83], v[34:35]
	v_exp_f32_e32 v39, v29
	v_mov_b32_dpp v49, v50 row_ror:15 row_mask:0xf bank_mask:0xf
	v_pk_fma_f32 v[34:35], v[18:19], v[86:87], v[34:35]
	v_pk_mul_f32 v[30:31], v[30:31], v[40:41]
	v_pk_fma_f32 v[34:35], v[90:91], v[48:49], v[34:35]
	v_cvt_pk_bf16_f32 v29, v30, v31
	v_pk_add_f32 v[34:35], v[94:95], v[34:35]
	v_add_f32_e32 v30, 1.0, v38
	v_add_f32_e32 v31, 1.0, v39
	v_mul_f32_e32 v38, 0xbfb8aa3b, v34
	v_mul_f32_e32 v39, 0xbfb8aa3b, v35
	v_exp_f32_e32 v38, v38
	v_exp_f32_e32 v39, v39
	v_rcp_f32_e32 v30, v30
	v_rcp_f32_e32 v31, v31
	v_pk_mul_f32 v[22:23], v[22:23], v[34:35]
	v_add_f32_e32 v34, 1.0, v38
	v_add_f32_e32 v35, 1.0, v39
	v_rcp_f32_e32 v34, v34
	v_rcp_f32_e32 v35, v35
	v_pk_mul_f32 v[20:21], v[20:21], v[32:33]
	v_add_u32_e32 v50, 0xa0, v193
	v_pk_mul_f32 v[20:21], v[20:21], v[30:31]
	s_nop 0
	v_cvt_pk_bf16_f32 v30, v20, v21
	v_pk_mul_f32 v[20:21], v[22:23], v[34:35]
	v_cndmask_b32_e64 v22, v13, v25, s[44:45]
	v_cvt_pk_bf16_f32 v31, v20, v21
	v_mad_i64_i32 v[20:21], s[28:29], v50, s60, v[36:37]
	v_lshl_add_u64 v[20:21], v[20:21], 0, v[132:133]
	global_store_dwordx4 v[20:21], v[28:31], off
	v_cndmask_b32_e64 v21, v12, v24, s[44:45]
	v_mov_b32_e32 v20, 0
	v_cndmask_b32_e64 v23, v14, v26, s[44:45]
	v_cndmask_b32_e64 v25, v15, v27, s[44:45]
	v_mov_b32_dpp v20, v21 row_ror:1 row_mask:0xf bank_mask:0xf
	v_mov_b32_e32 v21, 0
	v_mov_b32_e32 v24, 0
	v_mov_b32_e32 v28, 0
	v_mov_b32_dpp v21, v22 row_ror:1 row_mask:0xf bank_mask:0xf
	v_mov_b32_e32 v22, 0
	v_mov_b32_dpp v24, v14 row_ror:15 row_mask:0xf bank_mask:0xf
	v_cndmask_b32_e64 v24, v24, 0, s[44:45]
	v_mov_b32_dpp v22, v23 row_ror:1 row_mask:0xf bank_mask:0xf
	v_mov_b32_e32 v23, 0
	v_mov_b32_e32 v29, 0
	v_mov_b32_dpp v28, v12 row_ror:15 row_mask:0xf bank_mask:0xf
	v_mov_b32_dpp v23, v25 row_ror:1 row_mask:0xf bank_mask:0xf
	v_mov_b32_e32 v25, 0
	v_pk_mul_f32 v[22:23], v[98:99], v[22:23]
	v_mov_b32_dpp v29, v13 row_ror:15 row_mask:0xf bank_mask:0xf
	v_mov_b32_dpp v25, v15 row_ror:15 row_mask:0xf bank_mask:0xf
	v_cndmask_b32_e64 v25, v25, 0, s[44:45]
	v_pk_fma_f32 v[22:23], v[14:15], v[102:103], v[22:23]
	v_pk_mul_f32 v[20:21], v[96:97], v[20:21]
	v_pk_fma_f32 v[22:23], v[110:111], v[24:25], v[22:23]
	v_cndmask_b32_e64 v24, v8, v16, s[44:45]
	v_mov_b32_e32 v16, 0
	v_cndmask_b32_e64 v27, v29, 0, s[44:45]
	v_cndmask_b32_e64 v26, v28, 0, s[44:45]
	v_mov_b32_dpp v16, v24 row_ror:1 row_mask:0xf bank_mask:0xf
	v_cndmask_b32_e64 v24, v9, v17, s[44:45]
	v_mov_b32_e32 v17, 0
	v_pk_fma_f32 v[20:21], v[12:13], v[100:101], v[20:21]
	v_cndmask_b32_e64 v25, v11, v19, s[44:45]
	v_mov_b32_dpp v17, v24 row_ror:1 row_mask:0xf bank_mask:0xf
	v_cndmask_b32_e64 v24, v10, v18, s[44:45]
	v_mov_b32_e32 v18, 0
	v_mov_b32_e32 v19, 0
	v_pk_fma_f32 v[20:21], v[108:109], v[26:27], v[20:21]
	v_mov_b32_e32 v26, 0
	v_mov_b32_e32 v27, 0
	v_mov_b32_dpp v18, v24 row_ror:1 row_mask:0xf bank_mask:0xf
	v_mov_b32_e32 v24, 0
	v_mov_b32_dpp v19, v25 row_ror:1 row_mask:0xf bank_mask:0xf
	v_mov_b32_e32 v25, 0
	v_mov_b32_dpp v26, v8 row_ror:15 row_mask:0xf bank_mask:0xf
	v_mov_b32_dpp v27, v9 row_ror:15 row_mask:0xf bank_mask:0xf
	v_mov_b32_dpp v24, v10 row_ror:15 row_mask:0xf bank_mask:0xf
	v_mov_b32_dpp v25, v11 row_ror:15 row_mask:0xf bank_mask:0xf
	v_pk_mul_f32 v[16:17], v[80:81], v[16:17]
	v_pk_mul_f32 v[18:19], v[82:83], v[18:19]
	v_cndmask_b32_e64 v25, v25, 0, s[44:45]
	v_cndmask_b32_e64 v24, v24, 0, s[44:45]
	v_cndmask_b32_e64 v27, v27, 0, s[44:45]
	v_cndmask_b32_e64 v26, v26, 0, s[44:45]
	v_pk_fma_f32 v[18:19], v[10:11], v[86:87], v[18:19]
	v_pk_fma_f32 v[16:17], v[8:9], v[84:85], v[16:17]
	v_pk_fma_f32 v[18:19], v[90:91], v[24:25], v[18:19]
	v_pk_fma_f32 v[16:17], v[88:89], v[26:27], v[16:17]
	v_pk_add_f32 v[22:23], v[114:115], v[22:23]
	v_pk_add_f32 v[20:21], v[112:113], v[20:21]
	v_pk_add_f32 v[18:19], v[94:95], v[18:19]
	v_pk_add_f32 v[16:17], v[92:93], v[16:17]
	v_add_u32_e32 v24, 0xb0, v193
	s_and_saveexec_b64 s[28:29], s[42:43]
	s_xor_b64 s[28:29], exec, s[28:29]
	s_cbranch_execz .LBB1_1923
; DI unsigned pack2(float a, float b) { f32x2 v = {a, b}; hwbf16x2 r = __builtin_convertvector(v, hwbf16x2); return __builtin_bit_cast(unsigned, r); }
; DI float silu_mul(float g, float v) { return g * v * __builtin_amdgcn_rcpf(1.0f + __builtin_amdgcn_exp2f(-LOG2E * g)); }
;     DI void operator()(const f32x4 (&acc)[2][2][4][2], const Unit& u, int wr, int wc, int fr, int fq) const {
;     ...
;                 if (efirst || elast) {
;                     const size_t eo = (size_t)((row >> 6) * 2 + (elast ? 1 : 0)) * DFF + ch0;
; #pragma unroll
;                     for (int n = 0; n < 2; ++n) { *(f32x4*)(EP + eo + 4 * n) = gc[n]; *(f32x4*)(ER + eo + 4 * n) = acc[ai][0][m][n]; *(f32x4*)(EV + eo + 4 * n) = acc[ai][1][m][n]; }
;                 } else {
;                     const f32x4 v0 = acc[ai][1][m][0], v1 = acc[ai][1][m][1];
;                     u32x4 o;
;                     o[0] = pack2(silu_mul(gc[0][0], v0[0]), silu_mul(gc[0][1], v0[1])); o[1] = pack2(silu_mul(gc[0][2], v0[2]), silu_mul(gc[0][3], v0[3]));
;                     o[2] = pack2(silu_mul(gc[1][0], v1[0]), silu_mul(gc[1][1], v1[1])); o[3] = pack2(silu_mul(gc[1][2], v1[2]), silu_mul(gc[1][3], v1[3]));
;                     *(u32x4*)(ACT + (size_t)row * DFF + ch0) = o;
;                 }
	v_mul_f32_e32 v25, 0xbfb8aa3b, v20
	v_exp_f32_e32 v25, v25
	v_mul_f32_e32 v26, 0xbfb8aa3b, v21
	v_exp_f32_e32 v26, v26
	v_mul_f32_e32 v28, 0xbfb8aa3b, v23
	v_add_f32_e32 v25, 1.0, v25
	v_exp_f32_e32 v29, v28
	v_add_f32_e32 v27, 1.0, v26
	v_rcp_f32_e32 v26, v25
	v_mul_f32_e32 v25, 0xbfb8aa3b, v22
	v_exp_f32_e32 v25, v25
	v_rcp_f32_e32 v27, v27
	v_pk_mul_f32 v[20:21], v[4:5], v[20:21]
	v_pk_mul_f32 v[22:23], v[6:7], v[22:23]
	v_add_f32_e32 v25, 1.0, v25
	v_rcp_f32_e32 v28, v25
	v_add_f32_e32 v25, 1.0, v29
	v_pk_mul_f32 v[20:21], v[20:21], v[26:27]
	v_rcp_f32_e32 v29, v25
	v_cvt_pk_bf16_f32 v20, v20, v21
	v_mul_f32_e32 v21, 0xbfb8aa3b, v16
	v_exp_f32_e32 v25, v21
	v_mul_f32_e32 v21, 0xbfb8aa3b, v17
	v_exp_f32_e32 v26, v21
	v_pk_mul_f32 v[22:23], v[22:23], v[28:29]
	v_pk_mul_f32 v[16:17], v[0:1], v[16:17]
	v_cvt_pk_bf16_f32 v21, v22, v23
	v_add_f32_e32 v22, 1.0, v25
	v_mul_f32_e32 v25, 0xbfb8aa3b, v18
	v_add_f32_e32 v23, 1.0, v26
	v_exp_f32_e32 v25, v25
	v_mul_f32_e32 v26, 0xbfb8aa3b, v19
	v_exp_f32_e32 v27, v26
	v_rcp_f32_e32 v22, v22
	v_add_f32_e32 v25, 1.0, v25
	v_rcp_f32_e32 v23, v23
	v_rcp_f32_e32 v26, v25
	v_add_f32_e32 v25, 1.0, v27
	v_rcp_f32_e32 v27, v25
	v_pk_mul_f32 v[18:19], v[2:3], v[18:19]
	v_pk_mul_f32 v[16:17], v[16:17], v[22:23]
	s_nop 0
	v_cvt_pk_bf16_f32 v22, v16, v17
	v_pk_mul_f32 v[16:17], v[18:19], v[26:27]
	s_nop 0
	v_cvt_pk_bf16_f32 v23, v16, v17
	v_mov_b64_e32 v[16:17], s[52:53]
	v_mad_i64_i32 v[16:17], s[42:43], v24, s60, v[16:17]
	v_lshl_add_u64 v[16:17], v[184:185], 1, v[16:17]
	global_store_dwordx4 v[16:17], v[20:23], off
.LBB1_1923:
	s_andn2_saveexec_b64 s[28:29], s[28:29]
	s_cbranch_execz .LBB1_1904
	v_ashrrev_i32_e32 v24, 5, v24
	v_mad_i64_i32 v[24:25], s[42:43], v24, s61, v[184:185]
	v_lshlrev_b64 v[24:25], 2, v[24:25]
	v_lshl_add_u64 v[26:27], s[8:9], 0, v[24:25]
	global_store_dwordx4 v[26:27], v[20:23], off
	s_nop 1
	v_lshl_add_u64 v[20:21], s[10:11], 0, v[24:25]
	global_store_dwordx4 v[20:21], v[12:15], off
	s_nop 1
	v_lshl_add_u64 v[12:13], s[12:13], 0, v[24:25]
	global_store_dwordx4 v[12:13], v[4:7], off
	global_store_dwordx4 v[26:27], v[16:19], off offset:16
	global_store_dwordx4 v[20:21], v[8:11], off offset:16
	global_store_dwordx4 v[12:13], v[0:3], off offset:16
	s_branch .LBB1_1904

; DI void glu_fix_phase(const Params& p, int layer) {
;     ...
;     for (int task0 = bid * 512 + tid; task0 < NTASK; task0 += 3 * tstride) {
;         f32x4 gc[3], vv[3], nb[3], wv[3]; int rowc[3], cc[3];
; #pragma unroll
;         for (int u = 0; u < 3; ++u) {
;             const int task = task0 + u * tstride;
;             if (task < NTASK) {
;                 const int e = task / NC4, c = (task - e * NC4) * 4, b64 = e >> 1, last = e & 1, row = b64 * 64 + (last ? 63 : 0), sq = row & (S - 1);
;                 const bool valid = last ? (sq != S - 1) : (sq != 0);
;                 const int en = valid ? (last ? e + 1 : e - 1) : e;
;                 gc[u] = *(const f32x4*)(EP + (size_t)e * DFF + c); vv[u] = *(const f32x4*)(EV + (size_t)e * DFF + c);
;                 nb[u] = *(const f32x4*)(ER + (size_t)en * DFF + c);
;                 wv[u] = *(const f32x4*)(cw + (last ? 2 * DFF : 0) + c);
;                 if (!valid) wv[u] = (f32x4){0.f, 0.f, 0.f, 0.f};
;                 rowc[u] = row; cc[u] = c;
;             }
;         }
.LBB1_1995:
	v_mul_hi_i32 v32, v51, s20
	v_lshrrev_b32_e32 v33, 31, v32
	v_ashrrev_i32_e32 v32, 8, v32
	v_add_u32_e32 v32, v32, v33
	v_mul_i32_i24_e32 v33, 0xfffffa80, v32
	v_bfe_i32 v59, v32, 0, 1
	v_lshlrev_b32_e32 v60, 5, v32
	v_add_lshl_u32 v54, v33, v51, 2
	v_and_b32_e32 v33, 1, v32
	v_and_b32_e32 v34, 0xffffffc0, v60
	v_and_b32_e32 v35, 63, v59
	v_bitop3_b32 v34, v35, s22, v34 bitop3:0xc8
	v_and_b32_e32 v35, 0xfff, v59
	v_cmp_eq_u32_e32 vcc, 0, v33
	v_cmp_eq_u32_e64 s[40:41], v34, v35
	v_ashrrev_i32_e32 v55, 31, v54
	v_cndmask_b32_e64 v33, 1, -1, vcc
	v_cndmask_b32_e64 v33, v33, 0, s[40:41]
	v_add_u32_e32 v40, v33, v32
	v_mul_hi_i32_i24_e32 v33, 0x1600, v32
	v_mul_i32_i24_e32 v32, 0x1600, v32
	v_lshlrev_b64 v[32:33], 2, v[32:33]
	v_mul_hi_i32_i24_e32 v41, 0x5800, v40
	v_mul_i32_i24_e32 v40, 0x5800, v40
	v_and_b32_e32 v48, 0xb000, v59
	v_lshl_add_u64 v[34:35], s[8:9], 0, v[32:33]
	v_lshlrev_b64 v[44:45], 2, v[54:55]
	v_lshl_add_u64 v[32:33], s[12:13], 0, v[32:33]
	v_lshl_add_u64 v[40:41], s[10:11], 0, v[40:41]
	v_lshl_add_u64 v[46:47], s[14:15], 0, v[48:49]
	v_lshl_add_u64 v[34:35], v[34:35], 0, v[44:45]
	v_lshl_add_u64 v[32:33], v[32:33], 0, v[44:45]
	v_lshl_add_u64 v[40:41], v[40:41], 0, v[44:45]
	v_lshl_add_u64 v[44:45], v[46:47], 0, v[44:45]
	global_load_dwordx4 v[36:39], v[34:35], off
	s_nop 0
	global_load_dwordx4 v[32:35], v[32:33], off
	v_add_u32_e32 v58, s60, v51
	global_load_dwordx4 v[40:43], v[40:41], off
	v_cmp_gt_i32_e32 vcc, s2, v58
	global_load_dwordx4 v[44:47], v[44:45], off
	s_and_saveexec_b64 s[18:19], vcc
	s_cbranch_execz .LBB1_1997
	v_mul_hi_i32 v0, v58, s20
	v_lshrrev_b32_e32 v1, 31, v0
	v_ashrrev_i32_e32 v0, 8, v0
	v_add_u32_e32 v0, v0, v1
	v_mov_b32_e32 v1, s60
	v_mad_i32_i24 v1, v0, s21, v1
	v_bfe_i32 v57, v0, 0, 1
	v_lshlrev_b32_e32 v61, 5, v0
	v_add_lshl_u32 v52, v1, v51, 2
	v_and_b32_e32 v1, 1, v0
	v_and_b32_e32 v2, 0xffffffc0, v61
	v_and_b32_e32 v3, 63, v57
	v_bitop3_b32 v2, v3, s22, v2 bitop3:0xc8
	v_and_b32_e32 v3, 0xfff, v57
	v_cmp_eq_u32_e64 s[42:43], 0, v1
	v_ashrrev_i32_e32 v53, 31, v52
	v_and_b32_e32 v48, 0xb000, v57
	v_cndmask_b32_e64 v1, 1, -1, s[42:43]
	v_cmp_eq_u32_e64 s[42:43], v2, v3
	v_lshlrev_b64 v[16:17], 2, v[52:53]
	v_lshl_add_u64 v[28:29], s[14:15], 0, v[48:49]
	v_cndmask_b32_e64 v1, v1, 0, s[42:43]
	v_add_u32_e32 v18, v1, v0
	v_mul_hi_i32_i24_e32 v1, 0x1600, v0
	v_mul_i32_i24_e32 v0, 0x1600, v0
	v_lshlrev_b64 v[0:1], 2, v[0:1]
	v_lshl_add_u64 v[2:3], s[8:9], 0, v[0:1]
	v_lshl_add_u64 v[0:1], s[12:13], 0, v[0:1]
	v_mul_hi_i32_i24_e32 v19, 0x5800, v18
	v_mul_i32_i24_e32 v18, 0x5800, v18
	v_lshl_add_u64 v[2:3], v[2:3], 0, v[16:17]
	v_lshl_add_u64 v[12:13], v[0:1], 0, v[16:17]
	v_lshl_add_u64 v[28:29], v[28:29], 0, v[16:17]
	v_lshl_add_u64 v[18:19], s[10:11], 0, v[18:19]
	global_load_dwordx4 v[0:3], v[2:3], off
	s_nop 0
	global_load_dwordx4 v[12:15], v[12:13], off
	v_lshl_add_u64 v[16:17], v[18:19], 0, v[16:17]
	global_load_dwordx4 v[28:31], v[28:29], off
	v_bfi_b32 v57, 63, v57, v61
	global_load_dwordx4 v[16:19], v[16:17], off
	s_waitcnt vmcnt(0)
	v_cndmask_b32_e64 v31, v31, 0, s[42:43]
	v_cndmask_b32_e64 v30, v30, 0, s[42:43]
	v_cndmask_b32_e64 v29, v29, 0, s[42:43]
	v_cndmask_b32_e64 v28, v28, 0, s[42:43]
.LBB1_1997:
	s_or_b64 exec, exec, s[18:19]
	v_add_u32_e32 v48, s3, v51
	v_cmp_gt_i32_e64 s[42:43], s2, v48
	s_and_saveexec_b64 s[18:19], s[42:43]
	s_cbranch_execz .LBB1_1999
	v_mul_hi_i32 v4, v48, s20
	v_lshrrev_b32_e32 v5, 31, v4
	v_ashrrev_i32_e32 v4, 8, v4
	v_add_u32_e32 v4, v4, v5
	v_mov_b32_e32 v5, s3
	v_mad_i32_i24 v5, v4, s21, v5
	v_bfe_i32 v53, v4, 0, 1
	v_lshlrev_b32_e32 v56, 5, v4
	v_add_lshl_u32 v50, v5, v51, 2
	v_and_b32_e32 v5, 1, v4
	v_and_b32_e32 v6, 0xffffffc0, v56
	v_and_b32_e32 v7, 63, v53
	v_bitop3_b32 v6, v7, s22, v6 bitop3:0xc8
	v_and_b32_e32 v7, 0xfff, v53
	v_cmp_eq_u32_e64 s[44:45], 0, v5
	v_ashrrev_i32_e32 v51, 31, v50
	v_lshlrev_b64 v[8:9], 2, v[50:51]
	v_cndmask_b32_e64 v5, 1, -1, s[44:45]
	v_cmp_eq_u32_e64 s[44:45], v6, v7
	v_and_b32_e32 v48, 0xb000, v53
	v_lshl_add_u64 v[20:21], s[14:15], 0, v[48:49]
	v_cndmask_b32_e64 v5, v5, 0, s[44:45]
	v_add_u32_e32 v61, v5, v4
	v_mul_hi_i32_i24_e32 v5, 0x1600, v4
	v_mul_i32_i24_e32 v4, 0x1600, v4
	v_lshlrev_b64 v[4:5], 2, v[4:5]
	v_lshl_add_u64 v[6:7], s[8:9], 0, v[4:5]
	v_lshl_add_u64 v[4:5], s[12:13], 0, v[4:5]
	v_lshl_add_u64 v[6:7], v[6:7], 0, v[8:9]
	v_lshl_add_u64 v[10:11], v[4:5], 0, v[8:9]
	global_load_dwordx4 v[4:7], v[6:7], off
	s_nop 0
	global_load_dwordx4 v[24:27], v[10:11], off
	v_mul_hi_i32_i24_e32 v11, 0x5800, v61
	v_mul_i32_i24_e32 v10, 0x5800, v61
	v_lshl_add_u64 v[20:21], v[20:21], 0, v[8:9]
	v_lshl_add_u64 v[10:11], s[10:11], 0, v[10:11]
	global_load_dwordx4 v[20:23], v[20:21], off
	v_lshl_add_u64 v[8:9], v[10:11], 0, v[8:9]
	global_load_dwordx4 v[8:11], v[8:9], off
	v_bfi_b32 v56, 63, v53, v56
	s_waitcnt vmcnt(0)
	v_cndmask_b32_e64 v23, v23, 0, s[44:45]
	v_cndmask_b32_e64 v22, v22, 0, s[44:45]
	v_cndmask_b32_e64 v21, v21, 0, s[44:45]
	v_cndmask_b32_e64 v20, v20, 0, s[44:45]
; DI unsigned pack2(float a, float b) { f32x2 v = {a, b}; hwbf16x2 r = __builtin_convertvector(v, hwbf16x2); return __builtin_bit_cast(unsigned, r); }
; DI float silu_mul(float g, float v) { return g * v * __builtin_amdgcn_rcpf(1.0f + __builtin_amdgcn_exp2f(-LOG2E * g)); }
; DI void glu_fix_phase(const Params& p, int layer) {
;     ...
; #pragma unroll
;         for (int u = 0; u < 3; ++u) {
;             const int task = task0 + u * tstride;
;             if (task < NTASK) {
;                 const f32x4 g = gc[u] + wv[u] * nb[u], v = vv[u];
;                 u32x2 o;
;                 o[0] = pack2(silu_mul(g[0], v[0]), silu_mul(g[1], v[1]));
;                 o[1] = pack2(silu_mul(g[2], v[2]), silu_mul(g[3], v[3]));
;                 *(u32x2*)(ACT + (size_t)rowc[u] * DFF + cc[u]) = o;
;             }
;         }
.LBB1_1999:
	s_or_b64 exec, exec, s[18:19]
	s_waitcnt vmcnt(0)
	v_cndmask_b32_e64 v45, v45, 0, s[40:41]
	v_cndmask_b32_e64 v44, v44, 0, s[40:41]
	v_cndmask_b32_e64 v47, v47, 0, s[40:41]
	v_cndmask_b32_e64 v46, v46, 0, s[40:41]
	s_waitcnt lgkmcnt(0)
	v_pk_fma_f32 v[36:37], v[40:41], v[44:45], v[36:37]
	v_pk_fma_f32 v[38:39], v[42:43], v[46:47], v[38:39]
	v_mul_f32_e32 v40, 0xbfb8aa3b, v36
	v_mul_f32_e32 v41, 0xbfb8aa3b, v37
	v_mul_f32_e32 v42, 0xbfb8aa3b, v38
	v_mul_f32_e32 v43, 0xbfb8aa3b, v39
	v_exp_f32_e32 v40, v40
	v_exp_f32_e32 v41, v41
	v_exp_f32_e32 v42, v42
	v_exp_f32_e32 v43, v43
	v_add_f32_e32 v40, 1.0, v40
	v_add_f32_e32 v41, 1.0, v41
	v_pk_mul_f32 v[32:33], v[32:33], v[36:37]
	v_add_f32_e32 v36, 1.0, v42
	v_add_f32_e32 v37, 1.0, v43
	v_rcp_f32_e32 v40, v40
	v_rcp_f32_e32 v41, v41
	v_rcp_f32_e32 v36, v36
	v_rcp_f32_e32 v37, v37
	v_pk_mul_f32 v[34:35], v[34:35], v[38:39]
	v_pk_mul_f32 v[32:33], v[32:33], v[40:41]
	v_bfi_b32 v48, 63, v59, v60
	v_pk_mul_f32 v[34:35], v[34:35], v[36:37]
	v_cvt_pk_bf16_f32 v32, v32, v33
	v_cvt_pk_bf16_f32 v33, v34, v35
	v_mov_b64_e32 v[34:35], s[6:7]
	v_mad_i64_i32 v[34:35], s[18:19], v48, s23, v[34:35]
	v_lshl_add_u64 v[34:35], v[54:55], 1, v[34:35]
	global_store_dwordx2 v[34:35], v[32:33], off
	s_and_saveexec_b64 s[18:19], vcc
	s_cbranch_execz .LBB1_2001
	v_pk_fma_f32 v[34:35], v[16:17], v[28:29], v[0:1]
	v_pk_fma_f32 v[32:33], v[18:19], v[30:31], v[2:3]
	v_mul_f32_e32 v36, 0xbfb8aa3b, v34
	v_mul_f32_e32 v37, 0xbfb8aa3b, v35
	v_exp_f32_e32 v36, v36
	v_exp_f32_e32 v37, v37
	v_pk_mul_f32 v[34:35], v[12:13], v[34:35]
	v_ashrrev_i32_e32 v53, 31, v52
	v_add_f32_e32 v36, 1.0, v36
	v_add_f32_e32 v37, 1.0, v37
	v_rcp_f32_e32 v36, v36
	v_rcp_f32_e32 v37, v37
	s_nop 0
	v_pk_mul_f32 v[34:35], v[34:35], v[36:37]
	s_nop 0
	v_cvt_pk_bf16_f32 v34, v34, v35
	v_mul_f32_e32 v35, 0xbfb8aa3b, v32
	v_exp_f32_e32 v35, v35
	s_nop 0
	v_add_f32_e32 v35, 1.0, v35
	v_rcp_f32_e32 v36, v35
	v_mul_f32_e32 v35, 0xbfb8aa3b, v33
	v_exp_f32_e32 v35, v35
	v_pk_mul_f32 v[32:33], v[14:15], v[32:33]
	v_add_f32_e32 v35, 1.0, v35
	v_rcp_f32_e32 v37, v35
	s_nop 0
	v_pk_mul_f32 v[32:33], v[32:33], v[36:37]
	s_nop 0
	v_cvt_pk_bf16_f32 v35, v32, v33
	v_mov_b64_e32 v[32:33], s[6:7]
	v_mad_i64_i32 v[32:33], s[26:27], v57, s23, v[32:33]
	v_lshl_add_u64 v[32:33], v[52:53], 1, v[32:33]
	global_store_dwordx2 v[32:33], v[34:35], off
.LBB1_2001:
	s_or_b64 exec, exec, s[18:19]
	s_and_saveexec_b64 s[18:19], s[42:43]
	s_cbranch_execz .LBB1_1994
	v_pk_fma_f32 v[34:35], v[8:9], v[20:21], v[4:5]
	v_pk_fma_f32 v[32:33], v[10:11], v[22:23], v[6:7]
	v_mul_f32_e32 v36, 0xbfb8aa3b, v34
	v_mul_f32_e32 v37, 0xbfb8aa3b, v35
	v_exp_f32_e32 v36, v36
	v_exp_f32_e32 v37, v37
	v_pk_mul_f32 v[34:35], v[24:25], v[34:35]
	v_ashrrev_i32_e32 v51, 31, v50
	v_add_f32_e32 v36, 1.0, v36
	v_add_f32_e32 v37, 1.0, v37
	v_rcp_f32_e32 v36, v36
	v_rcp_f32_e32 v37, v37
	s_nop 0
	v_pk_mul_f32 v[34:35], v[34:35], v[36:37]
	s_nop 0
	v_cvt_pk_bf16_f32 v34, v34, v35
	v_mul_f32_e32 v35, 0xbfb8aa3b, v32
	v_exp_f32_e32 v35, v35
	s_nop 0
	v_add_f32_e32 v35, 1.0, v35
	v_rcp_f32_e32 v36, v35
	v_mul_f32_e32 v35, 0xbfb8aa3b, v33
	v_exp_f32_e32 v35, v35
	v_pk_mul_f32 v[32:33], v[26:27], v[32:33]
	v_add_f32_e32 v35, 1.0, v35
	v_rcp_f32_e32 v37, v35
	s_nop 0
	v_pk_mul_f32 v[32:33], v[32:33], v[36:37]
	s_nop 0
	v_cvt_pk_bf16_f32 v35, v32, v33
	v_mov_b64_e32 v[32:33], s[6:7]
	v_mad_i64_i32 v[32:33], s[26:27], v56, s23, v[32:33]
	v_lshl_add_u64 v[32:33], v[50:51], 1, v[32:33]
	global_store_dwordx2 v[32:33], v[34:35], off
	s_branch .LBB1_1994

; #define PG8_STAGE(bufoff, gbase, voff) do { _Pragma("unroll") for (int _i = 0; _i < 2; ++_i) \
;         __builtin_amdgcn_global_load_lds((const unsigned*)((const char*)(gbase) + (voff)[_i]), (LAS unsigned*)(lds + (bufoff) + ldsw + _i * 8192), 16, 0, 0); } while (0)
; #define PG8_LDA(dst, b, h) do { _Pragma("unroll") for (int m = 0; m < 4; ++m) _Pragma("unroll") for (int k = 0; k < 2; ++k) dst[m][k] = *(const LAS bf16x8*)(lds + PG8_SA(b, h) + aoff + m * 2048 + k * 1024); } while (0)
; #define PG8_LDB(dst, b, h) do { _Pragma("unroll") for (int n = 0; n < 2; ++n) _Pragma("unroll") for (int k = 0; k < 2; ++k) dst[n][k] = *(const LAS bf16x8*)(lds + PG8_SB(b, h) + boff + n * 2048 + k * 1024); } while (0)
; #define PG8_MMA(ai, bj, At, Bt) do { __builtin_amdgcn_s_setprio(1); _Pragma("unroll") for (int m = 0; m < 4; ++m) _Pragma("unroll") for (int n = 0; n < 2; ++n) _Pragma("unroll") for (int k = 0; k < 2; ++k) \
;         acc[ai][bj][m][n] = __builtin_amdgcn_mfma_f32_16x16x32_bf16(Bt[n][k], At[m][k], acc[ai][bj][m][n], 0, 0, 0); __builtin_amdgcn_s_setprio(0); } while (0)
; #define PG8_WAIT_V(n) asm volatile("s_waitcnt vmcnt(" #n ")" ::: "memory")
; #define PG8_WAIT_L(n) asm volatile("s_waitcnt lgkmcnt(" #n ")" ::: "memory")
; #define PG8_BAR __builtin_amdgcn_s_barrier()
; #define PG8_SCHED __builtin_amdgcn_sched_barrier(0)
; template <class Map, class Epi>
; DI void gemm_phase(LAS unsigned char* lds, const Map& MP, const Epi& E, const int nM, const int nN, const int K, const int lda, const int ldb) {
;     ...
;             PG8_LDB(B0, 0, 0); PG8_SCHED; PG8_LDA(At, 0, 0); PG8_STAGE(PG8_SA(1, 1), a1 + hstepA, voffA);
;             PG8_WAIT_L(8); PG8_BAR; PG8_WAIT_L(0); PG8_MMA(0, 0, At, B0); PG8_BAR; PG8_SCHED;
;             PG8_LDB(B1, 0, 1); PG8_STAGE(PG8_SB(0, 0), b2, voffB);
;             PG8_BAR; PG8_WAIT_L(0); PG8_MMA(0, 1, At, B1); PG8_BAR;
;             PG8_LDA(At, 0, 1); PG8_STAGE(PG8_SA(0, 0), a2, voffA);
;             PG8_BAR; PG8_WAIT_L(0); PG8_MMA(1, 0, At, B0); PG8_BAR; PG8_SCHED;
;             PG8_STAGE(PG8_SB(0, 1), b2 + hstepB, voffB);
;             PG8_WAIT_V(6); PG8_BAR; PG8_MMA(1, 1, At, B1); PG8_BAR;
;             PG8_LDB(B0, 1, 0); PG8_SCHED; PG8_LDA(At, 1, 0); PG8_STAGE(PG8_SA(0, 1), a2 + hstepA, voffA);
;             PG8_WAIT_L(8); PG8_BAR; PG8_WAIT_L(0); PG8_MMA(0, 0, At, B0); PG8_BAR; PG8_SCHED;
.LBB1_2078:
	ds_read_b128 v[152:155], v149
	ds_read_b128 v[156:159], v149 offset:1024
	ds_read_b128 v[160:163], v149 offset:2048
	ds_read_b128 v[164:167], v149 offset:3072
	s_add_u32 s10, s8, 0x100
	s_addc_u32 s11, s9, 0
	s_cmpk_eq_i32 s3, 0x54
	s_cselect_b32 s15, s43, s11
	s_cselect_b32 s14, s42, s10
	s_cselect_b32 s13, s7, s44
	s_cselect_b32 s12, s6, s39
	v_lshl_add_u64 v[144:145], s[8:9], 0, v[138:139]
	s_add_i32 m0, s24, 0xc000
	ds_read_b128 v[168:171], v150
	ds_read_b128 v[172:175], v150 offset:1024
	ds_read_b128 v[176:179], v150 offset:2048
	ds_read_b128 v[180:183], v150 offset:3072
	ds_read_b128 v[184:187], v150 offset:4096
	ds_read_b128 v[188:191], v150 offset:5120
	ds_read_b128 v[192:195], v150 offset:6144
	ds_read_b128 v[198:201], v150 offset:7168
	global_load_lds_dwordx4 v[144:145], off
	v_lshl_add_u64 v[144:145], s[8:9], 0, v[136:137]
	s_add_i32 m0, s24, 0xe000
	s_nop 0
	global_load_lds_dwordx4 v[144:145], off
	s_waitcnt lgkmcnt(8)
	s_barrier
	s_setprio 1
	s_waitcnt lgkmcnt(7)
	v_mfma_f32_16x16x32_bf16 v[124:127], v[152:155], v[168:171], v[124:127]
	v_mfma_f32_16x16x32_bf16 v[120:123], v[160:163], v[168:171], v[120:123]
	s_waitcnt lgkmcnt(5)
	v_mfma_f32_16x16x32_bf16 v[108:111], v[152:155], v[176:179], v[108:111]
	v_mfma_f32_16x16x32_bf16 v[104:107], v[160:163], v[176:179], v[104:107]
	s_waitcnt lgkmcnt(3)
	v_mfma_f32_16x16x32_bf16 v[92:95], v[152:155], v[184:187], v[92:95]
	v_mfma_f32_16x16x32_bf16 v[88:91], v[160:163], v[184:187], v[88:91]
	s_waitcnt lgkmcnt(1)
	v_mfma_f32_16x16x32_bf16 v[76:79], v[152:155], v[192:195], v[76:79]
	v_mfma_f32_16x16x32_bf16 v[72:75], v[160:163], v[192:195], v[72:75]
	v_mfma_f32_16x16x32_bf16 v[124:127], v[156:159], v[172:175], v[124:127]
	v_mfma_f32_16x16x32_bf16 v[120:123], v[164:167], v[172:175], v[120:123]
	v_mfma_f32_16x16x32_bf16 v[108:111], v[156:159], v[180:183], v[108:111]
	v_mfma_f32_16x16x32_bf16 v[104:107], v[164:167], v[180:183], v[104:107]
	v_mfma_f32_16x16x32_bf16 v[92:95], v[156:159], v[188:191], v[92:95]
	v_mfma_f32_16x16x32_bf16 v[88:91], v[164:167], v[188:191], v[88:91]
	s_waitcnt lgkmcnt(0)
	v_mfma_f32_16x16x32_bf16 v[76:79], v[156:159], v[198:201], v[76:79]
	v_mfma_f32_16x16x32_bf16 v[72:75], v[164:167], v[198:201], v[72:75]
	s_setprio 0
	s_barrier
	s_add_i32 s8, s35, s22
	v_lshl_add_u64 v[144:145], s[12:13], 0, v[132:133]
	s_mov_b32 m0, s8
	ds_read_b128 v[202:205], v151
	ds_read_b128 v[206:209], v151 offset:1024
	ds_read_b128 v[210:213], v151 offset:2048
	ds_read_b128 v[214:217], v151 offset:3072
	global_load_lds_dwordx4 v[144:145], off
	v_lshl_add_u64 v[218:219], s[12:13], 0, v[128:129]
	s_add_i32 m0, s8, 0x2000
	s_nop 0
	global_load_lds_dwordx4 v[218:219], off
	s_barrier
	s_setprio 1
	s_waitcnt lgkmcnt(3)
	v_mfma_f32_16x16x32_bf16 v[116:119], v[202:205], v[168:171], v[116:119]
	s_waitcnt lgkmcnt(1)
	v_mfma_f32_16x16x32_bf16 v[112:115], v[210:213], v[168:171], v[112:115]
	v_mfma_f32_16x16x32_bf16 v[100:103], v[202:205], v[176:179], v[100:103]
	v_mfma_f32_16x16x32_bf16 v[96:99], v[210:213], v[176:179], v[96:99]
	v_mfma_f32_16x16x32_bf16 v[84:87], v[202:205], v[184:187], v[84:87]
	v_mfma_f32_16x16x32_bf16 v[80:83], v[210:213], v[184:187], v[80:83]
	v_mfma_f32_16x16x32_bf16 v[68:71], v[202:205], v[192:195], v[68:71]
	v_mfma_f32_16x16x32_bf16 v[64:67], v[210:213], v[192:195], v[64:67]
	v_mfma_f32_16x16x32_bf16 v[116:119], v[206:209], v[172:175], v[116:119]
	s_waitcnt lgkmcnt(0)
	v_mfma_f32_16x16x32_bf16 v[112:115], v[214:217], v[172:175], v[112:115]
	v_mfma_f32_16x16x32_bf16 v[100:103], v[206:209], v[180:183], v[100:103]
	v_mfma_f32_16x16x32_bf16 v[96:99], v[214:217], v[180:183], v[96:99]
	v_mfma_f32_16x16x32_bf16 v[84:87], v[206:209], v[188:191], v[84:87]
	v_mfma_f32_16x16x32_bf16 v[80:83], v[214:217], v[188:191], v[80:83]
	v_mfma_f32_16x16x32_bf16 v[68:71], v[206:209], v[198:201], v[68:71]
	v_mfma_f32_16x16x32_bf16 v[64:67], v[214:217], v[198:201], v[64:67]
	s_setprio 0
	s_mov_b32 m0, s24
	v_lshl_add_u64 v[220:221], s[14:15], 0, v[134:135]
	s_barrier
	ds_read_b128 v[168:171], v150 offset:16384
	ds_read_b128 v[172:175], v150 offset:17408
	ds_read_b128 v[176:179], v150 offset:18432
	ds_read_b128 v[180:183], v150 offset:19456
	ds_read_b128 v[184:187], v150 offset:20480
	ds_read_b128 v[188:191], v150 offset:21504
	ds_read_b128 v[192:195], v150 offset:22528
	ds_read_b128 v[198:201], v150 offset:23552
	global_load_lds_dwordx4 v[220:221], off
	v_lshl_add_u64 v[222:223], s[14:15], 0, v[130:131]
	s_mov_b32 m0, s25
	s_nop 0
	global_load_lds_dwordx4 v[222:223], off
	s_barrier
	s_setprio 1
	s_waitcnt lgkmcnt(7)
	v_mfma_f32_16x16x32_bf16 v[60:63], v[152:155], v[168:171], v[60:63]
	v_mfma_f32_16x16x32_bf16 v[56:59], v[160:163], v[168:171], v[56:59]
	s_waitcnt lgkmcnt(5)
	v_mfma_f32_16x16x32_bf16 v[44:47], v[152:155], v[176:179], v[44:47]
	v_mfma_f32_16x16x32_bf16 v[40:43], v[160:163], v[176:179], v[40:43]
	s_waitcnt lgkmcnt(3)
	v_mfma_f32_16x16x32_bf16 v[28:31], v[152:155], v[184:187], v[28:31]
	v_mfma_f32_16x16x32_bf16 v[24:27], v[160:163], v[184:187], v[24:27]
	s_waitcnt lgkmcnt(1)
	v_mfma_f32_16x16x32_bf16 v[12:15], v[152:155], v[192:195], v[12:15]
	v_mfma_f32_16x16x32_bf16 v[8:11], v[160:163], v[192:195], v[8:11]
	v_mfma_f32_16x16x32_bf16 v[60:63], v[156:159], v[172:175], v[60:63]
	v_mfma_f32_16x16x32_bf16 v[56:59], v[164:167], v[172:175], v[56:59]
	v_mfma_f32_16x16x32_bf16 v[44:47], v[156:159], v[180:183], v[44:47]
	v_mfma_f32_16x16x32_bf16 v[40:43], v[164:167], v[180:183], v[40:43]
	v_mfma_f32_16x16x32_bf16 v[28:31], v[156:159], v[188:191], v[28:31]
	v_mfma_f32_16x16x32_bf16 v[24:27], v[164:167], v[188:191], v[24:27]
	s_waitcnt lgkmcnt(0)
	v_mfma_f32_16x16x32_bf16 v[12:15], v[156:159], v[198:201], v[12:15]
	v_mfma_f32_16x16x32_bf16 v[8:11], v[164:167], v[198:201], v[8:11]
	s_setprio 0
	s_barrier
; #define PG8_STAGE(bufoff, gbase, voff) do { _Pragma("unroll") for (int _i = 0; _i < 2; ++_i) \
;         __builtin_amdgcn_global_load_lds((const unsigned*)((const char*)(gbase) + (voff)[_i]), (LAS unsigned*)(lds + (bufoff) + ldsw + _i * 8192), 16, 0, 0); } while (0)
; #define PG8_LDA(dst, b, h) do { _Pragma("unroll") for (int m = 0; m < 4; ++m) _Pragma("unroll") for (int k = 0; k < 2; ++k) dst[m][k] = *(const LAS bf16x8*)(lds + PG8_SA(b, h) + aoff + m * 2048 + k * 1024); } while (0)
; #define PG8_LDB(dst, b, h) do { _Pragma("unroll") for (int n = 0; n < 2; ++n) _Pragma("unroll") for (int k = 0; k < 2; ++k) dst[n][k] = *(const LAS bf16x8*)(lds + PG8_SB(b, h) + boff + n * 2048 + k * 1024); } while (0)
; #define PG8_MMA(ai, bj, At, Bt) do { __builtin_amdgcn_s_setprio(1); _Pragma("unroll") for (int m = 0; m < 4; ++m) _Pragma("unroll") for (int n = 0; n < 2; ++n) _Pragma("unroll") for (int k = 0; k < 2; ++k) \
;         acc[ai][bj][m][n] = __builtin_amdgcn_mfma_f32_16x16x32_bf16(Bt[n][k], At[m][k], acc[ai][bj][m][n], 0, 0, 0); __builtin_amdgcn_s_setprio(0); } while (0)
; #define PG8_WAIT_L(n) asm volatile("s_waitcnt lgkmcnt(" #n ")" ::: "memory")
; #define PG8_BAR __builtin_amdgcn_s_barrier()
; #define PG8_SCHED __builtin_amdgcn_sched_barrier(0)
; template <class Map, class Epi>
; DI void gemm_phase(LAS unsigned char* lds, const Map& MP, const Epi& E, const int nM, const int nN, const int K, const int lda, const int ldb) {
;     ...
;             PG8_WAIT_L(8); PG8_BAR; PG8_WAIT_L(0); PG8_MMA(0, 0, At, B0); PG8_BAR; PG8_SCHED;
;             PG8_LDB(B1, 1, 1); PG8_STAGE(PG8_SB(1, 0), b3, voffB);
;             PG8_BAR; PG8_WAIT_L(0); PG8_MMA(0, 1, At, B1); PG8_BAR;
;             PG8_LDA(At, 1, 1); PG8_STAGE(PG8_SA(1, 0), a3, voffA);
;             PG8_BAR; PG8_WAIT_L(0); PG8_MMA(1, 0, At, B0); PG8_BAR; PG8_SCHED;
	s_add_u32 s8, s12, 0x160000
	s_addc_u32 s9, s13, 0
	s_add_i32 s45, s36, s22
	v_lshl_add_u64 v[152:153], s[8:9], 0, v[132:133]
	s_mov_b32 m0, s45
	s_nop 0
	global_load_lds_dwordx4 v[152:153], off
	v_lshl_add_u64 v[152:153], s[8:9], 0, v[128:129]
	s_add_i32 m0, s45, 0x2000
	s_nop 0
	global_load_lds_dwordx4 v[152:153], off
	s_waitcnt vmcnt(6)
	s_barrier
	s_setprio 1
	v_mfma_f32_16x16x32_bf16 v[52:55], v[202:205], v[168:171], v[52:55]
	v_mfma_f32_16x16x32_bf16 v[48:51], v[210:213], v[168:171], v[48:51]
	v_mfma_f32_16x16x32_bf16 v[36:39], v[202:205], v[176:179], v[36:39]
	v_mfma_f32_16x16x32_bf16 v[32:35], v[210:213], v[176:179], v[32:35]
	v_mfma_f32_16x16x32_bf16 v[20:23], v[202:205], v[184:187], v[20:23]
	v_mfma_f32_16x16x32_bf16 v[16:19], v[210:213], v[184:187], v[16:19]
	v_mfma_f32_16x16x32_bf16 v[4:7], v[202:205], v[192:195], v[4:7]
	v_mfma_f32_16x16x32_bf16 v[0:3], v[210:213], v[192:195], v[0:3]
	v_mfma_f32_16x16x32_bf16 v[52:55], v[206:209], v[172:175], v[52:55]
	v_mfma_f32_16x16x32_bf16 v[48:51], v[214:217], v[172:175], v[48:51]
	v_mfma_f32_16x16x32_bf16 v[36:39], v[206:209], v[180:183], v[36:39]
	v_mfma_f32_16x16x32_bf16 v[32:35], v[214:217], v[180:183], v[32:35]
	v_mfma_f32_16x16x32_bf16 v[20:23], v[206:209], v[188:191], v[20:23]
	v_mfma_f32_16x16x32_bf16 v[16:19], v[214:217], v[188:191], v[16:19]
	v_mfma_f32_16x16x32_bf16 v[4:7], v[206:209], v[198:201], v[4:7]
	v_mfma_f32_16x16x32_bf16 v[0:3], v[214:217], v[198:201], v[0:3]
	s_setprio 0
	s_add_i32 s45, 0, 0x18000
	v_add_u32_e32 v164, s45, v148
	s_barrier
	ds_read_b128 v[152:155], v164
	ds_read_b128 v[156:159], v164 offset:1024
	ds_read_b128 v[160:163], v164 offset:2048
	ds_read_b128 v[164:167], v164 offset:3072
	s_add_u32 s8, s14, 0x160000
	s_addc_u32 s9, s15, 0
	s_mov_b32 m0, s26
	v_lshl_add_u64 v[202:203], s[8:9], 0, v[134:135]
	ds_read_b128 v[168:171], v150 offset:32768
	ds_read_b128 v[172:175], v150 offset:33792
	ds_read_b128 v[176:179], v150 offset:34816
	ds_read_b128 v[180:183], v150 offset:35840
	ds_read_b128 v[184:187], v150 offset:36864
	ds_read_b128 v[188:191], v150 offset:37888
	ds_read_b128 v[192:195], v150 offset:38912
	ds_read_b128 v[198:201], v150 offset:39936
	global_load_lds_dwordx4 v[202:203], off
	v_lshl_add_u64 v[202:203], s[8:9], 0, v[130:131]
	s_mov_b32 m0, s27
	s_nop 0
	global_load_lds_dwordx4 v[202:203], off
	s_waitcnt lgkmcnt(8)
	s_barrier
	s_setprio 1
	s_waitcnt lgkmcnt(7)
	v_mfma_f32_16x16x32_bf16 v[124:127], v[152:155], v[168:171], v[124:127]
	v_mfma_f32_16x16x32_bf16 v[120:123], v[160:163], v[168:171], v[120:123]
	s_waitcnt lgkmcnt(5)
	v_mfma_f32_16x16x32_bf16 v[108:111], v[152:155], v[176:179], v[108:111]
	v_mfma_f32_16x16x32_bf16 v[104:107], v[160:163], v[176:179], v[104:107]
	s_waitcnt lgkmcnt(3)
	v_mfma_f32_16x16x32_bf16 v[92:95], v[152:155], v[184:187], v[92:95]
	v_mfma_f32_16x16x32_bf16 v[88:91], v[160:163], v[184:187], v[88:91]
	s_waitcnt lgkmcnt(1)
	v_mfma_f32_16x16x32_bf16 v[76:79], v[152:155], v[192:195], v[76:79]
	v_mfma_f32_16x16x32_bf16 v[72:75], v[160:163], v[192:195], v[72:75]
	v_mfma_f32_16x16x32_bf16 v[124:127], v[156:159], v[172:175], v[124:127]
	v_mfma_f32_16x16x32_bf16 v[120:123], v[164:167], v[172:175], v[120:123]
	v_mfma_f32_16x16x32_bf16 v[108:111], v[156:159], v[180:183], v[108:111]
	v_mfma_f32_16x16x32_bf16 v[104:107], v[164:167], v[180:183], v[104:107]
	v_mfma_f32_16x16x32_bf16 v[92:95], v[156:159], v[188:191], v[92:95]
	v_mfma_f32_16x16x32_bf16 v[88:91], v[164:167], v[188:191], v[88:91]
	s_waitcnt lgkmcnt(0)
	v_mfma_f32_16x16x32_bf16 v[76:79], v[156:159], v[198:201], v[76:79]
	v_mfma_f32_16x16x32_bf16 v[72:75], v[164:167], v[198:201], v[72:75]
	s_setprio 0
	s_barrier
	s_add_i32 s14, 0, 0x1c000
	s_add_i32 s8, s45, s22
	v_add_u32_e32 v196, s14, v148
	v_lshl_add_u64 v[144:145], v[144:145], 0, s[46:47]
	s_mov_b32 m0, s8
	ds_read_b128 v[202:205], v196
	ds_read_b128 v[206:209], v196 offset:1024
	ds_read_b128 v[210:213], v196 offset:2048
	ds_read_b128 v[214:217], v196 offset:3072
	global_load_lds_dwordx4 v[144:145], off
	v_lshl_add_u64 v[144:145], v[218:219], 0, s[46:47]
	s_add_i32 m0, s8, 0x2000
	s_nop 0
	global_load_lds_dwordx4 v[144:145], off
	s_barrier
	s_setprio 1
	s_waitcnt lgkmcnt(3)
	v_mfma_f32_16x16x32_bf16 v[116:119], v[202:205], v[168:171], v[116:119]
	s_waitcnt lgkmcnt(1)
	v_mfma_f32_16x16x32_bf16 v[112:115], v[210:213], v[168:171], v[112:115]
	v_mfma_f32_16x16x32_bf16 v[100:103], v[202:205], v[176:179], v[100:103]
	v_mfma_f32_16x16x32_bf16 v[96:99], v[210:213], v[176:179], v[96:99]
	v_mfma_f32_16x16x32_bf16 v[84:87], v[202:205], v[184:187], v[84:87]
	v_mfma_f32_16x16x32_bf16 v[80:83], v[210:213], v[184:187], v[80:83]
	v_mfma_f32_16x16x32_bf16 v[68:71], v[202:205], v[192:195], v[68:71]
	v_mfma_f32_16x16x32_bf16 v[64:67], v[210:213], v[192:195], v[64:67]
	v_mfma_f32_16x16x32_bf16 v[116:119], v[206:209], v[172:175], v[116:119]
	s_waitcnt lgkmcnt(0)
	v_mfma_f32_16x16x32_bf16 v[112:115], v[214:217], v[172:175], v[112:115]
	v_mfma_f32_16x16x32_bf16 v[100:103], v[206:209], v[180:183], v[100:103]
	v_mfma_f32_16x16x32_bf16 v[96:99], v[214:217], v[180:183], v[96:99]
	v_mfma_f32_16x16x32_bf16 v[84:87], v[206:209], v[188:191], v[84:87]
	v_mfma_f32_16x16x32_bf16 v[80:83], v[214:217], v[188:191], v[80:83]
	v_mfma_f32_16x16x32_bf16 v[68:71], v[206:209], v[198:201], v[68:71]
	v_mfma_f32_16x16x32_bf16 v[64:67], v[214:217], v[198:201], v[64:67]
	s_setprio 0
	s_mov_b32 m0, s30
	v_lshl_add_u64 v[144:145], v[220:221], 0, s[46:47]
	s_barrier
; DI unsigned pack2(float a, float b) { f32x2 v = {a, b}; hwbf16x2 r = __builtin_convertvector(v, hwbf16x2); return __builtin_bit_cast(unsigned, r); }
; DI float bflo(unsigned w) { return __uint_as_float(w << 16); }
; DI float bfhi(unsigned w) { return __uint_as_float(w & 0xffff0000u); }
; #define PG8_STAGE(bufoff, gbase, voff) do { _Pragma("unroll") for (int _i = 0; _i < 2; ++_i) \
;         __builtin_amdgcn_global_load_lds((const unsigned*)((const char*)(gbase) + (voff)[_i]), (LAS unsigned*)(lds + (bufoff) + ldsw + _i * 8192), 16, 0, 0); } while (0)
; #define PG8_MMA(ai, bj, At, Bt) do { __builtin_amdgcn_s_setprio(1); _Pragma("unroll") for (int m = 0; m < 4; ++m) _Pragma("unroll") for (int n = 0; n < 2; ++n) _Pragma("unroll") for (int k = 0; k < 2; ++k) \
;         acc[ai][bj][m][n] = __builtin_amdgcn_mfma_f32_16x16x32_bf16(Bt[n][k], At[m][k], acc[ai][bj][m][n], 0, 0, 0); __builtin_amdgcn_s_setprio(0); } while (0)
;     DI void operator()(const f32x4 (&acc)[2][2][4][2], const Unit& u, int wr, int wc, int fr, int fq) const {
;     ...
;             for (int m = 0; m < 4; ++m) { const size_t ro = (size_t)(row0 + ai * HALF + m * 16) * D + col0;
; #pragma unroll
;                 for (int bj = 0; bj < 2; ++bj) {
;                     f32x4 x0, x1;
;                     if constexpr (IB) { const u32x4 w = *(const u32x4*)((const bf16_t*)Xin + ro + bj * HALF);
;                         x0 = (f32x4){bflo(w[0]), bfhi(w[0]), bflo(w[1]), bfhi(w[1])}; x1 = (f32x4){bflo(w[2]), bfhi(w[2]), bflo(w[3]), bfhi(w[3])}; }
;                     else { x0 = *(const f32x4*)((const float*)Xin + ro + bj * HALF); x1 = *(const f32x4*)((const float*)Xin + ro + bj * HALF + 4); }
;                     x0 += acc[ai][bj][m][0] * sc[bj][0]; x1 += acc[ai][bj][m][1] * sc[bj][1];
;                     if constexpr (OB) { u32x4 o; o[0] = pack2(x0[0], x0[1]); o[1] = pack2(x0[2], x0[3]); o[2] = pack2(x1[0], x1[1]); o[3] = pack2(x1[2], x1[3]);
;                         *(u32x4*)((bf16_t*)Xout + ro + bj * HALF) = o; }
; template <class Map, class Epi>
; DI void gemm_phase(LAS unsigned char* lds, const Map& MP, const Epi& E, const int nM, const int nN, const int K, const int lda, const int ldb) {
;     ...
;             PG8_BAR; PG8_WAIT_L(0); PG8_MMA(1, 0, At, B0); PG8_BAR; PG8_SCHED;
;             PG8_STAGE(PG8_SB(1, 1), b3 + hstepB, voffB);
;             PG8_WAIT_V(6); PG8_BAR; PG8_MMA(1, 1, At, B1); PG8_BAR;
	ds_read_b128 v[168:171], v150 offset:49152
	ds_read_b128 v[172:175], v150 offset:50176
	ds_read_b128 v[176:179], v150 offset:51200
	ds_read_b128 v[180:183], v150 offset:52224
	ds_read_b128 v[184:187], v150 offset:53248
	ds_read_b128 v[188:191], v150 offset:54272
	ds_read_b128 v[192:195], v150 offset:55296
	ds_read_b128 v[198:201], v150 offset:56320
	global_load_lds_dwordx4 v[144:145], off
	v_lshl_add_u64 v[144:145], v[222:223], 0, s[46:47]
	s_mov_b32 m0, s31
	s_nop 0
	global_load_lds_dwordx4 v[144:145], off
	s_barrier
	s_setprio 1
	s_waitcnt lgkmcnt(7)
	v_mfma_f32_16x16x32_bf16 v[60:63], v[152:155], v[168:171], v[60:63]
	v_mfma_f32_16x16x32_bf16 v[56:59], v[160:163], v[168:171], v[56:59]
	s_waitcnt lgkmcnt(5)
	v_mfma_f32_16x16x32_bf16 v[44:47], v[152:155], v[176:179], v[44:47]
	v_mfma_f32_16x16x32_bf16 v[40:43], v[160:163], v[176:179], v[40:43]
	s_waitcnt lgkmcnt(3)
	v_mfma_f32_16x16x32_bf16 v[28:31], v[152:155], v[184:187], v[28:31]
	v_mfma_f32_16x16x32_bf16 v[24:27], v[160:163], v[184:187], v[24:27]
	s_waitcnt lgkmcnt(1)
	v_mfma_f32_16x16x32_bf16 v[12:15], v[152:155], v[192:195], v[12:15]
	v_mfma_f32_16x16x32_bf16 v[8:11], v[160:163], v[192:195], v[8:11]
	v_mfma_f32_16x16x32_bf16 v[60:63], v[156:159], v[172:175], v[60:63]
	v_mfma_f32_16x16x32_bf16 v[56:59], v[164:167], v[172:175], v[56:59]
	v_mfma_f32_16x16x32_bf16 v[44:47], v[156:159], v[180:183], v[44:47]
	v_mfma_f32_16x16x32_bf16 v[40:43], v[164:167], v[180:183], v[40:43]
	v_mfma_f32_16x16x32_bf16 v[28:31], v[156:159], v[188:191], v[28:31]
	v_mfma_f32_16x16x32_bf16 v[24:27], v[164:167], v[188:191], v[24:27]
	s_waitcnt lgkmcnt(0)
	v_mfma_f32_16x16x32_bf16 v[12:15], v[156:159], v[198:201], v[12:15]
	v_mfma_f32_16x16x32_bf16 v[8:11], v[164:167], v[198:201], v[8:11]
	s_setprio 0
	s_barrier
	s_add_u32 s8, s12, 0x160080
	s_addc_u32 s9, s13, 0
	s_add_i32 s12, s14, s22
	v_lshl_add_u64 v[144:145], s[8:9], 0, v[132:133]
	s_mov_b32 m0, s12
	s_nop 0
	global_load_lds_dwordx4 v[144:145], off
	v_lshl_add_u64 v[144:145], s[8:9], 0, v[128:129]
	s_add_i32 m0, s12, 0x2000
	s_nop 0
	global_load_lds_dwordx4 v[144:145], off
	s_waitcnt vmcnt(6)
	s_barrier
	s_setprio 1
	v_mfma_f32_16x16x32_bf16 v[52:55], v[202:205], v[168:171], v[52:55]
	v_mfma_f32_16x16x32_bf16 v[48:51], v[210:213], v[168:171], v[48:51]
	v_mfma_f32_16x16x32_bf16 v[36:39], v[202:205], v[176:179], v[36:39]
	v_mfma_f32_16x16x32_bf16 v[32:35], v[210:213], v[176:179], v[32:35]
	v_mfma_f32_16x16x32_bf16 v[20:23], v[202:205], v[184:187], v[20:23]
	v_mfma_f32_16x16x32_bf16 v[16:19], v[210:213], v[184:187], v[16:19]
	v_mfma_f32_16x16x32_bf16 v[4:7], v[202:205], v[192:195], v[4:7]
	v_mfma_f32_16x16x32_bf16 v[0:3], v[210:213], v[192:195], v[0:3]
	v_mfma_f32_16x16x32_bf16 v[52:55], v[206:209], v[172:175], v[52:55]
	v_mfma_f32_16x16x32_bf16 v[48:51], v[214:217], v[172:175], v[48:51]
	v_mfma_f32_16x16x32_bf16 v[36:39], v[206:209], v[180:183], v[36:39]
	v_mfma_f32_16x16x32_bf16 v[32:35], v[214:217], v[180:183], v[32:35]
	v_mfma_f32_16x16x32_bf16 v[20:23], v[206:209], v[188:191], v[20:23]
	v_mfma_f32_16x16x32_bf16 v[16:19], v[214:217], v[188:191], v[16:19]
	v_mfma_f32_16x16x32_bf16 v[4:7], v[206:209], v[198:201], v[4:7]
	v_mfma_f32_16x16x32_bf16 v[0:3], v[214:217], v[198:201], v[0:3]
	s_setprio 0
	s_add_i32 s3, s3, 2
	s_add_u32 s39, s39, 0x100
	s_addc_u32 s44, s44, 0
	s_cmpk_gt_u32 s3, 0x55
	s_mov_b64 s[8:9], s[10:11]
	s_barrier
	s_cbranch_scc0 .LBB1_2078
	v_mov_b32_e32 v152, v147
	v_mov_b32_e32 v144, v146
	s_lshl_b32 s2, s2, 8
	s_add_i32 s2, s2, s29
	s_lshl_b32 s3, s38, 8
	v_add_u32_e32 v152, s2, v152
	s_or_b32 s3, s3, s52
	v_ashrrev_i32_e32 v153, 31, v152
	v_lshl_add_u32 v144, v144, 3, s3
	v_lshlrev_b64 v[152:153], 12, v[152:153]
	v_ashrrev_i32_e32 v145, 31, v144
	v_lshl_add_u64 v[152:153], s[4:5], 0, v[152:153]
	v_lshl_add_u64 v[144:145], v[144:145], 1, v[152:153]
	global_load_dwordx4 v[152:155], v[144:145], off
	s_mov_b64 s[2:3], 0x10000
	s_mov_b32 s38, s37
	s_mov_b64 s[10:11], s[6:7]
	s_mov_b64 s[8:9], s[42:43]
	s_waitcnt vmcnt(0) lgkmcnt(0)
	v_lshlrev_b32_e32 v156, 16, v152
	v_and_b32_e32 v157, 0xffff0000, v152
	v_lshlrev_b32_e32 v152, 16, v153
	v_and_b32_e32 v153, 0xffff0000, v153
	v_lshlrev_b32_e32 v158, 16, v154
	v_and_b32_e32 v159, 0xffff0000, v154
	v_lshlrev_b32_e32 v154, 16, v155
	v_and_b32_e32 v155, 0xffff0000, v155
	v_pk_add_f32 v[126:127], v[126:127], v[152:153]
	v_pk_add_f32 v[124:125], v[124:125], v[156:157]
	v_pk_add_f32 v[152:153], v[122:123], v[154:155]
	v_pk_add_f32 v[122:123], v[120:121], v[158:159]
	v_cvt_pk_bf16_f32 v120, v124, v125
	v_cvt_pk_bf16_f32 v121, v126, v127
	v_cvt_pk_bf16_f32 v122, v122, v123
	v_cvt_pk_bf16_f32 v123, v152, v153
	global_store_dwordx4 v[144:145], v[120:123], off
	global_load_dwordx4 v[120:123], v[144:145], off offset:256
	s_waitcnt vmcnt(0) lgkmcnt(0)
	v_lshlrev_b32_e32 v124, 16, v120
	v_and_b32_e32 v125, 0xffff0000, v120
	v_lshlrev_b32_e32 v120, 16, v121
	v_and_b32_e32 v121, 0xffff0000, v121
	v_lshlrev_b32_e32 v126, 16, v122
	v_and_b32_e32 v127, 0xffff0000, v122
	v_lshlrev_b32_e32 v122, 16, v123
	v_and_b32_e32 v123, 0xffff0000, v123
	v_pk_add_f32 v[116:117], v[116:117], v[124:125]
	v_pk_add_f32 v[118:119], v[118:119], v[120:121]
	v_pk_add_f32 v[120:121], v[114:115], v[122:123]
	v_pk_add_f32 v[114:115], v[112:113], v[126:127]
	v_cvt_pk_bf16_f32 v112, v116, v117
	v_lshl_add_u64 v[116:117], v[144:145], 0, s[2:3]
	s_mov_b32 s2, 0x10000
	v_cvt_pk_bf16_f32 v113, v118, v119
	v_add_co_u32_e32 v118, vcc, s2, v144
	v_cvt_pk_bf16_f32 v114, v114, v115
	v_cvt_pk_bf16_f32 v115, v120, v121
	v_addc_co_u32_e32 v119, vcc, 0, v145, vcc
	global_store_dwordx4 v[144:145], v[112:115], off offset:256
	global_load_dwordx4 v[112:115], v[118:119], off
	s_mov_b64 s[2:3], 0x20000
	s_waitcnt vmcnt(0) lgkmcnt(0)
; DI unsigned pack2(float a, float b) { f32x2 v = {a, b}; hwbf16x2 r = __builtin_convertvector(v, hwbf16x2); return __builtin_bit_cast(unsigned, r); }
; DI float bflo(unsigned w) { return __uint_as_float(w << 16); }
; DI float bfhi(unsigned w) { return __uint_as_float(w & 0xffff0000u); }
;     DI void operator()(const f32x4 (&acc)[2][2][4][2], const Unit& u, int wr, int wc, int fr, int fq) const {
;     ...
;             for (int m = 0; m < 4; ++m) { const size_t ro = (size_t)(row0 + ai * HALF + m * 16) * D + col0;
; #pragma unroll
;                 for (int bj = 0; bj < 2; ++bj) {
;                     f32x4 x0, x1;
;                     if constexpr (IB) { const u32x4 w = *(const u32x4*)((const bf16_t*)Xin + ro + bj * HALF);
;                         x0 = (f32x4){bflo(w[0]), bfhi(w[0]), bflo(w[1]), bfhi(w[1])}; x1 = (f32x4){bflo(w[2]), bfhi(w[2]), bflo(w[3]), bfhi(w[3])}; }
;                     else { x0 = *(const f32x4*)((const float*)Xin + ro + bj * HALF); x1 = *(const f32x4*)((const float*)Xin + ro + bj * HALF + 4); }
;                     x0 += acc[ai][bj][m][0] * sc[bj][0]; x1 += acc[ai][bj][m][1] * sc[bj][1];
;                     if constexpr (OB) { u32x4 o; o[0] = pack2(x0[0], x0[1]); o[1] = pack2(x0[2], x0[3]); o[2] = pack2(x1[0], x1[1]); o[3] = pack2(x1[2], x1[3]);
;                         *(u32x4*)((bf16_t*)Xout + ro + bj * HALF) = o; }
	v_lshlrev_b32_e32 v120, 16, v112
	v_and_b32_e32 v121, 0xffff0000, v112
	v_lshlrev_b32_e32 v112, 16, v113
	v_and_b32_e32 v113, 0xffff0000, v113
	v_lshlrev_b32_e32 v122, 16, v114
	v_and_b32_e32 v123, 0xffff0000, v114
	v_lshlrev_b32_e32 v114, 16, v115
	v_and_b32_e32 v115, 0xffff0000, v115
	v_pk_add_f32 v[110:111], v[110:111], v[112:113]
	v_pk_add_f32 v[108:109], v[108:109], v[120:121]
	v_pk_add_f32 v[112:113], v[106:107], v[114:115]
	v_pk_add_f32 v[106:107], v[104:105], v[122:123]
	v_cvt_pk_bf16_f32 v104, v108, v109
	v_cvt_pk_bf16_f32 v105, v110, v111
	v_cvt_pk_bf16_f32 v106, v106, v107
	v_cvt_pk_bf16_f32 v107, v112, v113
	global_store_dwordx4 v[118:119], v[104:107], off
	global_load_dwordx4 v[104:107], v[116:117], off offset:256
	s_waitcnt vmcnt(0) lgkmcnt(0)
	v_lshlrev_b32_e32 v108, 16, v104
	v_and_b32_e32 v109, 0xffff0000, v104
	v_lshlrev_b32_e32 v104, 16, v105
	v_and_b32_e32 v105, 0xffff0000, v105
	v_lshlrev_b32_e32 v110, 16, v106
	v_and_b32_e32 v111, 0xffff0000, v106
	v_lshlrev_b32_e32 v106, 16, v107
	v_and_b32_e32 v107, 0xffff0000, v107
	v_pk_add_f32 v[100:101], v[100:101], v[108:109]
	v_pk_add_f32 v[102:103], v[102:103], v[104:105]
	v_pk_add_f32 v[104:105], v[98:99], v[106:107]
	v_pk_add_f32 v[98:99], v[96:97], v[110:111]
	v_cvt_pk_bf16_f32 v96, v100, v101
	v_lshl_add_u64 v[100:101], v[144:145], 0, s[2:3]
	s_mov_b32 s2, 0x20000
	v_cvt_pk_bf16_f32 v97, v102, v103
	v_add_co_u32_e32 v102, vcc, s2, v144
	v_cvt_pk_bf16_f32 v98, v98, v99
	v_cvt_pk_bf16_f32 v99, v104, v105
	v_addc_co_u32_e32 v103, vcc, 0, v145, vcc
	global_store_dwordx4 v[116:117], v[96:99], off offset:256
	global_load_dwordx4 v[96:99], v[102:103], off
	s_mov_b64 s[2:3], 0x30000
	s_waitcnt vmcnt(0) lgkmcnt(0)
	v_lshlrev_b32_e32 v104, 16, v96
	v_and_b32_e32 v105, 0xffff0000, v96
	v_lshlrev_b32_e32 v96, 16, v97
	v_and_b32_e32 v97, 0xffff0000, v97
	v_lshlrev_b32_e32 v106, 16, v98
	v_and_b32_e32 v107, 0xffff0000, v98
	v_lshlrev_b32_e32 v98, 16, v99
	v_and_b32_e32 v99, 0xffff0000, v99
	v_pk_add_f32 v[94:95], v[94:95], v[96:97]
	v_pk_add_f32 v[92:93], v[92:93], v[104:105]
	v_pk_add_f32 v[96:97], v[90:91], v[98:99]
	v_pk_add_f32 v[90:91], v[88:89], v[106:107]
	v_cvt_pk_bf16_f32 v88, v92, v93
	v_cvt_pk_bf16_f32 v89, v94, v95
	v_cvt_pk_bf16_f32 v90, v90, v91
	v_cvt_pk_bf16_f32 v91, v96, v97
	global_store_dwordx4 v[102:103], v[88:91], off
	global_load_dwordx4 v[88:91], v[100:101], off offset:256
	s_waitcnt vmcnt(0) lgkmcnt(0)
	v_lshlrev_b32_e32 v92, 16, v88
	v_and_b32_e32 v93, 0xffff0000, v88
	v_lshlrev_b32_e32 v88, 16, v89
	v_and_b32_e32 v89, 0xffff0000, v89
	v_lshlrev_b32_e32 v94, 16, v90
	v_and_b32_e32 v95, 0xffff0000, v90
	v_lshlrev_b32_e32 v90, 16, v91
	v_and_b32_e32 v91, 0xffff0000, v91
	v_pk_add_f32 v[86:87], v[86:87], v[88:89]
	v_pk_add_f32 v[84:85], v[84:85], v[92:93]
	v_pk_add_f32 v[88:89], v[82:83], v[90:91]
	v_pk_add_f32 v[82:83], v[80:81], v[94:95]
	v_cvt_pk_bf16_f32 v80, v84, v85
	v_cvt_pk_bf16_f32 v81, v86, v87
	v_cvt_pk_bf16_f32 v82, v82, v83
	v_cvt_pk_bf16_f32 v83, v88, v89
	global_store_dwordx4 v[100:101], v[80:83], off offset:256
	s_nop 1
	v_lshl_add_u64 v[80:81], v[144:145], 0, s[2:3]
	s_mov_b32 s2, 0x30000
	v_add_co_u32_e32 v86, vcc, s2, v144
	s_mov_b64 s[2:3], 0x80000
	s_nop 0
	v_addc_co_u32_e32 v87, vcc, 0, v145, vcc
	global_load_dwordx4 v[82:85], v[86:87], off
	s_waitcnt vmcnt(0) lgkmcnt(0)
	v_lshlrev_b32_e32 v88, 16, v82
	v_and_b32_e32 v89, 0xffff0000, v82
	v_lshlrev_b32_e32 v82, 16, v83
	v_and_b32_e32 v83, 0xffff0000, v83
	v_lshlrev_b32_e32 v90, 16, v84
	v_and_b32_e32 v91, 0xffff0000, v84
	v_lshlrev_b32_e32 v84, 16, v85
	v_and_b32_e32 v85, 0xffff0000, v85
	v_pk_add_f32 v[78:79], v[78:79], v[82:83]
	v_pk_add_f32 v[76:77], v[76:77], v[88:89]
	v_pk_add_f32 v[82:83], v[74:75], v[84:85]
	v_pk_add_f32 v[74:75], v[72:73], v[90:91]
	v_cvt_pk_bf16_f32 v72, v76, v77
	v_cvt_pk_bf16_f32 v73, v78, v79
	v_cvt_pk_bf16_f32 v74, v74, v75
	v_cvt_pk_bf16_f32 v75, v82, v83
	global_store_dwordx4 v[86:87], v[72:75], off
	global_load_dwordx4 v[72:75], v[80:81], off offset:256
	s_waitcnt vmcnt(0) lgkmcnt(0)
	v_lshlrev_b32_e32 v76, 16, v72
	v_and_b32_e32 v77, 0xffff0000, v72
	v_lshlrev_b32_e32 v72, 16, v73
	v_and_b32_e32 v73, 0xffff0000, v73
	v_lshlrev_b32_e32 v78, 16, v74
	v_and_b32_e32 v79, 0xffff0000, v74
	v_lshlrev_b32_e32 v74, 16, v75
	v_and_b32_e32 v75, 0xffff0000, v75
	v_pk_add_f32 v[70:71], v[70:71], v[72:73]
	v_pk_add_f32 v[68:69], v[68:69], v[76:77]
	v_pk_add_f32 v[72:73], v[66:67], v[74:75]
	v_pk_add_f32 v[66:67], v[64:65], v[78:79]
	v_cvt_pk_bf16_f32 v64, v68, v69
	v_cvt_pk_bf16_f32 v65, v70, v71
	v_cvt_pk_bf16_f32 v66, v66, v67
	v_cvt_pk_bf16_f32 v67, v72, v73
	global_store_dwordx4 v[80:81], v[64:67], off offset:256
	s_nop 1
	v_lshl_add_u64 v[64:65], v[144:145], 0, s[2:3]
	s_mov_b32 s2, 0x80000
	v_add_co_u32_e32 v70, vcc, s2, v144
	s_mov_b64 s[2:3], 0x90000
	s_nop 0
	v_addc_co_u32_e32 v71, vcc, 0, v145, vcc
	global_load_dwordx4 v[66:69], v[70:71], off
	s_waitcnt vmcnt(0) lgkmcnt(0)
	v_lshlrev_b32_e32 v72, 16, v66
	v_and_b32_e32 v73, 0xffff0000, v66
	v_lshlrev_b32_e32 v66, 16, v67
	v_and_b32_e32 v67, 0xffff0000, v67
	v_lshlrev_b32_e32 v74, 16, v68
	v_and_b32_e32 v75, 0xffff0000, v68
	v_lshlrev_b32_e32 v68, 16, v69
	v_and_b32_e32 v69, 0xffff0000, v69
	v_pk_add_f32 v[62:63], v[62:63], v[66:67]
	v_pk_add_f32 v[60:61], v[60:61], v[72:73]
	v_pk_add_f32 v[66:67], v[58:59], v[68:69]
	v_pk_add_f32 v[58:59], v[56:57], v[74:75]
	v_cvt_pk_bf16_f32 v56, v60, v61
	v_cvt_pk_bf16_f32 v57, v62, v63
	v_cvt_pk_bf16_f32 v58, v58, v59
	v_cvt_pk_bf16_f32 v59, v66, v67
	global_store_dwordx4 v[70:71], v[56:59], off
	global_load_dwordx4 v[56:59], v[64:65], off offset:256
	s_waitcnt vmcnt(0) lgkmcnt(0)
; DI unsigned pack2(float a, float b) { f32x2 v = {a, b}; hwbf16x2 r = __builtin_convertvector(v, hwbf16x2); return __builtin_bit_cast(unsigned, r); }
; DI float bflo(unsigned w) { return __uint_as_float(w << 16); }
; DI float bfhi(unsigned w) { return __uint_as_float(w & 0xffff0000u); }
; #define PG8_WAIT_V(n) asm volatile("s_waitcnt vmcnt(" #n ")" ::: "memory")
; #define PG8_BAR __builtin_amdgcn_s_barrier()
;     DI void operator()(const f32x4 (&acc)[2][2][4][2], const Unit& u, int wr, int wc, int fr, int fq) const {
;     ...
;         for (int ai = 0; ai < 2; ++ai)
; #pragma unroll
;             for (int m = 0; m < 4; ++m) { const size_t ro = (size_t)(row0 + ai * HALF + m * 16) * D + col0;
; #pragma unroll
;                 for (int bj = 0; bj < 2; ++bj) {
;                     f32x4 x0, x1;
;                     if constexpr (IB) { const u32x4 w = *(const u32x4*)((const bf16_t*)Xin + ro + bj * HALF);
;                         x0 = (f32x4){bflo(w[0]), bfhi(w[0]), bflo(w[1]), bfhi(w[1])}; x1 = (f32x4){bflo(w[2]), bfhi(w[2]), bflo(w[3]), bfhi(w[3])}; }
;                     else { x0 = *(const f32x4*)((const float*)Xin + ro + bj * HALF); x1 = *(const f32x4*)((const float*)Xin + ro + bj * HALF + 4); }
;                     x0 += acc[ai][bj][m][0] * sc[bj][0]; x1 += acc[ai][bj][m][1] * sc[bj][1];
;                     if constexpr (OB) { u32x4 o; o[0] = pack2(x0[0], x0[1]); o[1] = pack2(x0[2], x0[3]); o[2] = pack2(x1[0], x1[1]); o[3] = pack2(x1[2], x1[3]);
;                         *(u32x4*)((bf16_t*)Xout + ro + bj * HALF) = o; }
;                     else { *(f32x4*)((float*)Xout + ro + bj * HALF) = x0; *(f32x4*)((float*)Xout + ro + bj * HALF + 4) = x1; } } }
; template <class Map, class Epi>
; DI void gemm_phase(LAS unsigned char* lds, const Map& MP, const Epi& E, const int nM, const int nN, const int K, const int lda, const int ldb) {
;     ...
;     PG8_WAIT_V(0);
;     if (wr == 0) PG8_BAR;
;     PG8_BAR;
	v_lshlrev_b32_e32 v60, 16, v56
	v_and_b32_e32 v61, 0xffff0000, v56
	v_lshlrev_b32_e32 v56, 16, v57
	v_and_b32_e32 v57, 0xffff0000, v57
	v_lshlrev_b32_e32 v62, 16, v58
	v_and_b32_e32 v63, 0xffff0000, v58
	v_lshlrev_b32_e32 v58, 16, v59
	v_and_b32_e32 v59, 0xffff0000, v59
	v_pk_add_f32 v[54:55], v[54:55], v[56:57]
	v_pk_add_f32 v[52:53], v[52:53], v[60:61]
	v_pk_add_f32 v[56:57], v[50:51], v[58:59]
	v_pk_add_f32 v[50:51], v[48:49], v[62:63]
	v_cvt_pk_bf16_f32 v48, v52, v53
	v_cvt_pk_bf16_f32 v49, v54, v55
	v_cvt_pk_bf16_f32 v50, v50, v51
	v_cvt_pk_bf16_f32 v51, v56, v57
	global_store_dwordx4 v[64:65], v[48:51], off offset:256
	s_nop 1
	v_lshl_add_u64 v[48:49], v[144:145], 0, s[2:3]
	s_mov_b32 s2, 0x90000
	v_add_co_u32_e32 v54, vcc, s2, v144
	s_mov_b64 s[2:3], 0xa0000
	s_nop 0
	v_addc_co_u32_e32 v55, vcc, 0, v145, vcc
	global_load_dwordx4 v[50:53], v[54:55], off
	s_waitcnt vmcnt(0) lgkmcnt(0)
	v_lshlrev_b32_e32 v56, 16, v50
	v_and_b32_e32 v57, 0xffff0000, v50
	v_lshlrev_b32_e32 v50, 16, v51
	v_and_b32_e32 v51, 0xffff0000, v51
	v_lshlrev_b32_e32 v58, 16, v52
	v_and_b32_e32 v59, 0xffff0000, v52
	v_lshlrev_b32_e32 v52, 16, v53
	v_and_b32_e32 v53, 0xffff0000, v53
	v_pk_add_f32 v[46:47], v[46:47], v[50:51]
	v_pk_add_f32 v[44:45], v[44:45], v[56:57]
	v_pk_add_f32 v[50:51], v[42:43], v[52:53]
	v_pk_add_f32 v[42:43], v[40:41], v[58:59]
	v_cvt_pk_bf16_f32 v40, v44, v45
	v_cvt_pk_bf16_f32 v41, v46, v47
	v_cvt_pk_bf16_f32 v42, v42, v43
	v_cvt_pk_bf16_f32 v43, v50, v51
	global_store_dwordx4 v[54:55], v[40:43], off
	global_load_dwordx4 v[40:43], v[48:49], off offset:256
	s_waitcnt vmcnt(0) lgkmcnt(0)
	v_lshlrev_b32_e32 v44, 16, v40
	v_and_b32_e32 v45, 0xffff0000, v40
	v_lshlrev_b32_e32 v40, 16, v41
	v_and_b32_e32 v41, 0xffff0000, v41
	v_lshlrev_b32_e32 v46, 16, v42
	v_and_b32_e32 v47, 0xffff0000, v42
	v_lshlrev_b32_e32 v42, 16, v43
	v_and_b32_e32 v43, 0xffff0000, v43
	v_pk_add_f32 v[38:39], v[38:39], v[40:41]
	v_pk_add_f32 v[36:37], v[36:37], v[44:45]
	v_pk_add_f32 v[40:41], v[34:35], v[42:43]
	v_pk_add_f32 v[34:35], v[32:33], v[46:47]
	v_cvt_pk_bf16_f32 v32, v36, v37
	v_cvt_pk_bf16_f32 v33, v38, v39
	v_cvt_pk_bf16_f32 v34, v34, v35
	v_cvt_pk_bf16_f32 v35, v40, v41
	global_store_dwordx4 v[48:49], v[32:35], off offset:256
	s_nop 1
	v_lshl_add_u64 v[32:33], v[144:145], 0, s[2:3]
	s_mov_b32 s2, 0xa0000
	v_add_co_u32_e32 v38, vcc, s2, v144
	s_mov_b64 s[2:3], 0xb0000
	s_nop 0
	v_addc_co_u32_e32 v39, vcc, 0, v145, vcc
	global_load_dwordx4 v[34:37], v[38:39], off
	s_waitcnt vmcnt(0) lgkmcnt(0)
	v_lshlrev_b32_e32 v40, 16, v34
	v_and_b32_e32 v41, 0xffff0000, v34
	v_lshlrev_b32_e32 v34, 16, v35
	v_and_b32_e32 v35, 0xffff0000, v35
	v_lshlrev_b32_e32 v42, 16, v36
	v_and_b32_e32 v43, 0xffff0000, v36
	v_lshlrev_b32_e32 v36, 16, v37
	v_and_b32_e32 v37, 0xffff0000, v37
	v_pk_add_f32 v[30:31], v[30:31], v[34:35]
	v_pk_add_f32 v[28:29], v[28:29], v[40:41]
	v_pk_add_f32 v[34:35], v[26:27], v[36:37]
	v_pk_add_f32 v[26:27], v[24:25], v[42:43]
	v_cvt_pk_bf16_f32 v24, v28, v29
	v_cvt_pk_bf16_f32 v25, v30, v31
	v_cvt_pk_bf16_f32 v26, v26, v27
	v_cvt_pk_bf16_f32 v27, v34, v35
	global_store_dwordx4 v[38:39], v[24:27], off
	global_load_dwordx4 v[24:27], v[32:33], off offset:256
	s_waitcnt vmcnt(0) lgkmcnt(0)
	v_lshlrev_b32_e32 v28, 16, v24
	v_and_b32_e32 v29, 0xffff0000, v24
	v_lshlrev_b32_e32 v24, 16, v25
	v_and_b32_e32 v25, 0xffff0000, v25
	v_lshlrev_b32_e32 v30, 16, v26
	v_and_b32_e32 v31, 0xffff0000, v26
	v_lshlrev_b32_e32 v26, 16, v27
	v_and_b32_e32 v27, 0xffff0000, v27
	v_pk_add_f32 v[22:23], v[22:23], v[24:25]
	v_pk_add_f32 v[20:21], v[20:21], v[28:29]
	v_pk_add_f32 v[24:25], v[18:19], v[26:27]
	v_pk_add_f32 v[18:19], v[16:17], v[30:31]
	v_cvt_pk_bf16_f32 v16, v20, v21
	v_cvt_pk_bf16_f32 v17, v22, v23
	v_cvt_pk_bf16_f32 v18, v18, v19
	v_cvt_pk_bf16_f32 v19, v24, v25
	global_store_dwordx4 v[32:33], v[16:19], off offset:256
	s_nop 1
	v_lshl_add_u64 v[16:17], v[144:145], 0, s[2:3]
	s_mov_b32 s2, 0xb0000
	v_add_co_u32_e32 v22, vcc, s2, v144
	s_mov_b32 s2, s53
	s_nop 0
	v_addc_co_u32_e32 v23, vcc, 0, v145, vcc
	global_load_dwordx4 v[18:21], v[22:23], off
	s_and_b64 vcc, exec, s[40:41]
	s_waitcnt vmcnt(0) lgkmcnt(0)
	v_lshlrev_b32_e32 v24, 16, v18
	v_and_b32_e32 v25, 0xffff0000, v18
	v_lshlrev_b32_e32 v18, 16, v19
	v_and_b32_e32 v19, 0xffff0000, v19
	v_lshlrev_b32_e32 v26, 16, v20
	v_and_b32_e32 v27, 0xffff0000, v20
	v_lshlrev_b32_e32 v20, 16, v21
	v_and_b32_e32 v21, 0xffff0000, v21
	v_pk_add_f32 v[14:15], v[14:15], v[18:19]
	v_pk_add_f32 v[12:13], v[12:13], v[24:25]
	v_pk_add_f32 v[18:19], v[10:11], v[20:21]
	v_pk_add_f32 v[10:11], v[8:9], v[26:27]
	v_cvt_pk_bf16_f32 v8, v12, v13
	v_cvt_pk_bf16_f32 v9, v14, v15
	v_cvt_pk_bf16_f32 v10, v10, v11
	v_cvt_pk_bf16_f32 v11, v18, v19
	global_store_dwordx4 v[22:23], v[8:11], off
	global_load_dwordx4 v[8:11], v[16:17], off offset:256
	s_waitcnt vmcnt(0) lgkmcnt(0)
	v_lshlrev_b32_e32 v12, 16, v8
	v_and_b32_e32 v13, 0xffff0000, v8
	v_lshlrev_b32_e32 v8, 16, v9
	v_and_b32_e32 v9, 0xffff0000, v9
	v_lshlrev_b32_e32 v14, 16, v10
	v_and_b32_e32 v15, 0xffff0000, v10
	v_lshlrev_b32_e32 v10, 16, v11
	v_and_b32_e32 v11, 0xffff0000, v11
	v_pk_add_f32 v[6:7], v[6:7], v[8:9]
	v_pk_add_f32 v[4:5], v[4:5], v[12:13]
	v_pk_add_f32 v[8:9], v[2:3], v[10:11]
	v_pk_add_f32 v[2:3], v[0:1], v[14:15]
	v_cvt_pk_bf16_f32 v0, v4, v5
	v_cvt_pk_bf16_f32 v1, v6, v7
	v_cvt_pk_bf16_f32 v2, v2, v3
	v_cvt_pk_bf16_f32 v3, v8, v9
	global_store_dwordx4 v[16:17], v[0:3], off offset:256
	s_cbranch_vccz .LBB1_2071
	s_waitcnt vmcnt(0)
	s_cmpk_gt_u32 s17, 0xff
	s_cbranch_scc1 .LBB1_2082
	s_barrier

; DI float wave_sum(float v) { for (int o = 32; o; o >>= 1) v += __shfl_xor(v, o); return v; }
; template <bool BF> DI f32x4 ldx4(const void* base, size_t e) {
;     if constexpr (BF) { const u32x2 w = *(const u32x2*)((const bf16_t*)base + e); return (f32x4){__uint_as_float(w[0] << 16), __uint_as_float(w[0] & 0xffff0000u), __uint_as_float(w[1] << 16), __uint_as_float(w[1] & 0xffff0000u)}; }
; template <bool BF> DI void rstd_phase(const Params& p, const void* x) {
;     ...
;     for (int t = bid * 8 + wid; t < T; t += 2 * step) {
;         const int t2 = (t + step < T) ? t + step : t;
;         f32x4 v[2][8];
; #pragma unroll
;         for (int q = 0; q < 2; ++q)
; #pragma unroll
;             for (int i = 0; i < 8; ++i) v[q][i] = ldx4<BF>(x, (size_t)(q ? t2 : t) * D + (i * 64 + lane) * 4);
;         float ss[2] = {0.f, 0.f};
; #pragma unroll
;         for (int q = 0; q < 2; ++q)
; #pragma unroll
;             for (int i = 0; i < 8; ++i) ss[q] += v[q][i][0] * v[q][i][0] + v[q][i][1] * v[q][i][1] + v[q][i][2] * v[q][i][2] + v[q][i][3] * v[q][i][3];
;         ss[0] = wave_sum(ss[0]); ss[1] = wave_sum(ss[1]);
;         if (lane == 0) { rstd[t] = rsqrtf(ss[0] * (1.0f / D) + EPS); rstd[t2] = rsqrtf(ss[1] * (1.0f / D) + EPS); }
;     }
.LBB1_2150:
	v_add_u32_e32 v29, s33, v0
	v_cmp_gt_i32_e64 s[40:41], s2, v29
	v_ashrrev_i32_e32 v1, 31, v0
	v_lshlrev_b64 v[8:9], 12, v[0:1]
	v_cndmask_b32_e64 v6, v0, v29, s[40:41]
	v_ashrrev_i32_e32 v7, 31, v6
	v_lshlrev_b64 v[12:13], 12, v[6:7]
	v_lshl_add_u64 v[8:9], v[2:3], 0, v[8:9]
	v_lshl_add_u64 v[12:13], v[2:3], 0, v[12:13]
	global_load_dwordx2 v[20:21], v[8:9], off
	global_load_dwordx2 v[22:23], v[8:9], off offset:512
	global_load_dwordx2 v[30:31], v[8:9], off offset:1024
	global_load_dwordx2 v[32:33], v[8:9], off offset:1536
	global_load_dwordx2 v[34:35], v[8:9], off offset:2048
	global_load_dwordx2 v[14:15], v[8:9], off offset:2560
	s_waitcnt lgkmcnt(0)
	global_load_dwordx2 v[10:11], v[8:9], off offset:3072
	s_nop 0
	global_load_dwordx2 v[8:9], v[8:9], off offset:3584
	s_nop 0
	global_load_dwordx2 v[36:37], v[12:13], off
	global_load_dwordx2 v[38:39], v[12:13], off offset:512
	global_load_dwordx2 v[40:41], v[12:13], off offset:1024
	global_load_dwordx2 v[42:43], v[12:13], off offset:1536
	global_load_dwordx2 v[44:45], v[12:13], off offset:2048
	global_load_dwordx2 v[18:19], v[12:13], off offset:2560
	global_load_dwordx2 v[16:17], v[12:13], off offset:3072
	s_nop 0
	global_load_dwordx2 v[12:13], v[12:13], off offset:3584
	s_waitcnt vmcnt(0) lgkmcnt(0)
	v_and_b32_e32 v49, 0xffff0000, v20
	v_and_b32_e32 v48, 0xffff0000, v36
	v_lshlrev_b32_e32 v46, 16, v36
	v_lshlrev_b32_e32 v47, 16, v20
	v_lshlrev_b32_e32 v50, 16, v37
	v_and_b32_e32 v20, 0xffff0000, v37
	v_lshlrev_b32_e32 v36, 16, v38
	v_lshlrev_b32_e32 v37, 16, v22
	v_and_b32_e32 v53, 0xffff0000, v22
	v_and_b32_e32 v52, 0xffff0000, v38
	v_lshlrev_b32_e32 v54, 16, v39
	v_and_b32_e32 v22, 0xffff0000, v39
	v_lshlrev_b32_e32 v38, 16, v40
	v_lshlrev_b32_e32 v39, 16, v30
	v_and_b32_e32 v57, 0xffff0000, v30
	v_and_b32_e32 v56, 0xffff0000, v40
	v_lshlrev_b32_e32 v58, 16, v41
	v_and_b32_e32 v30, 0xffff0000, v41
	v_lshlrev_b32_e32 v40, 16, v42
	v_lshlrev_b32_e32 v41, 16, v32
	v_and_b32_e32 v61, 0xffff0000, v32
	v_and_b32_e32 v60, 0xffff0000, v42
	v_lshlrev_b32_e32 v62, 16, v43
	v_and_b32_e32 v32, 0xffff0000, v43
	v_lshlrev_b32_e32 v42, 16, v44
	v_lshlrev_b32_e32 v43, 16, v34
	v_and_b32_e32 v65, 0xffff0000, v34
	v_and_b32_e32 v64, 0xffff0000, v44
	v_lshlrev_b32_e32 v66, 16, v45
	v_and_b32_e32 v34, 0xffff0000, v45
	v_pk_mul_f32 v[44:45], v[48:49], v[48:49]
	v_lshlrev_b32_e32 v51, 16, v21
	v_pk_fma_f32 v[44:45], v[46:47], v[46:47], v[44:45]
	v_and_b32_e32 v21, 0xffff0000, v21
	v_pk_fma_f32 v[44:45], v[50:51], v[50:51], v[44:45]
	v_lshlrev_b32_e32 v55, 16, v23
	v_pk_fma_f32 v[20:21], v[20:21], v[20:21], v[44:45]
	v_pk_mul_f32 v[44:45], v[52:53], v[52:53]
	v_and_b32_e32 v23, 0xffff0000, v23
	v_pk_fma_f32 v[36:37], v[36:37], v[36:37], v[44:45]
	v_lshlrev_b32_e32 v59, 16, v31
	v_pk_fma_f32 v[36:37], v[54:55], v[54:55], v[36:37]
	v_and_b32_e32 v31, 0xffff0000, v31
	v_pk_fma_f32 v[22:23], v[22:23], v[22:23], v[36:37]
	v_lshlrev_b32_e32 v63, 16, v33
	v_pk_add_f32 v[20:21], v[20:21], v[22:23]
	v_pk_mul_f32 v[22:23], v[56:57], v[56:57]
	v_and_b32_e32 v33, 0xffff0000, v33
	v_pk_fma_f32 v[22:23], v[38:39], v[38:39], v[22:23]
	v_lshlrev_b32_e32 v67, 16, v35
	v_pk_fma_f32 v[22:23], v[58:59], v[58:59], v[22:23]
	v_and_b32_e32 v35, 0xffff0000, v35
	v_pk_fma_f32 v[22:23], v[30:31], v[30:31], v[22:23]
	v_and_b32_e32 v31, 0xffff0000, v14
	v_pk_add_f32 v[20:21], v[20:21], v[22:23]
	v_pk_mul_f32 v[22:23], v[60:61], v[60:61]
	v_and_b32_e32 v30, 0xffff0000, v18
	v_pk_fma_f32 v[22:23], v[40:41], v[40:41], v[22:23]
	s_nop 0
	v_pk_fma_f32 v[22:23], v[62:63], v[62:63], v[22:23]
	s_nop 0
	v_pk_fma_f32 v[22:23], v[32:33], v[32:33], v[22:23]
	v_lshlrev_b32_e32 v32, 16, v19
	v_pk_add_f32 v[20:21], v[20:21], v[22:23]
	v_pk_mul_f32 v[22:23], v[64:65], v[64:65]
	v_lshlrev_b32_e32 v33, 16, v15
	v_pk_fma_f32 v[22:23], v[42:43], v[42:43], v[22:23]
	v_and_b32_e32 v15, 0xffff0000, v15
	v_pk_fma_f32 v[22:23], v[66:67], v[66:67], v[22:23]
	s_nop 0
	v_pk_fma_f32 v[22:23], v[34:35], v[34:35], v[22:23]
	s_nop 0
	v_pk_add_f32 v[20:21], v[20:21], v[22:23]
	v_lshlrev_b32_e32 v22, 16, v18
	v_lshlrev_b32_e32 v23, 16, v14
	v_and_b32_e32 v14, 0xffff0000, v19
	v_pk_mul_f32 v[18:19], v[30:31], v[30:31]
	v_lshlrev_b32_e32 v30, 16, v17
	v_pk_fma_f32 v[18:19], v[22:23], v[22:23], v[18:19]
	v_and_b32_e32 v23, 0xffff0000, v10
	v_pk_fma_f32 v[18:19], v[32:33], v[32:33], v[18:19]
	v_and_b32_e32 v22, 0xffff0000, v16
	v_pk_fma_f32 v[14:15], v[14:15], v[14:15], v[18:19]
	v_lshlrev_b32_e32 v18, 16, v16
	v_lshlrev_b32_e32 v19, 16, v10
	v_pk_mul_f32 v[22:23], v[22:23], v[22:23]
	v_lshlrev_b32_e32 v31, 16, v11
	v_pk_fma_f32 v[18:19], v[18:19], v[18:19], v[22:23]
	v_and_b32_e32 v23, 0xffff0000, v8
	v_and_b32_e32 v22, 0xffff0000, v12
	v_pk_fma_f32 v[18:19], v[30:31], v[30:31], v[18:19]
	v_and_b32_e32 v11, 0xffff0000, v11
	v_and_b32_e32 v10, 0xffff0000, v17
	v_lshlrev_b32_e32 v16, 16, v12
	v_lshlrev_b32_e32 v17, 16, v8
	v_pk_mul_f32 v[22:23], v[22:23], v[22:23]
	v_and_b32_e32 v8, 0xffff0000, v13
	v_pk_fma_f32 v[16:17], v[16:17], v[16:17], v[22:23]
	v_lshlrev_b32_e32 v22, 16, v13
	v_lshlrev_b32_e32 v23, 16, v9
	v_pk_add_f32 v[12:13], v[20:21], v[14:15]
	v_pk_fma_f32 v[10:11], v[10:11], v[10:11], v[18:19]
	v_and_b32_e32 v9, 0xffff0000, v9
	v_pk_add_f32 v[10:11], v[12:13], v[10:11]
	v_pk_fma_f32 v[12:13], v[22:23], v[22:23], v[16:17]
	s_nop 0
	v_pk_fma_f32 v[8:9], v[8:9], v[8:9], v[12:13]
	s_nop 0
	v_pk_add_f32 v[8:9], v[10:11], v[8:9]
	ds_bpermute_b32 v11, v5, v9
	ds_bpermute_b32 v10, v5, v8
	s_waitcnt lgkmcnt(0)
	v_pk_add_f32 v[8:9], v[8:9], v[10:11]
	ds_bpermute_b32 v11, v24, v9
	ds_bpermute_b32 v10, v24, v8
	s_waitcnt lgkmcnt(0)
	v_pk_add_f32 v[8:9], v[8:9], v[10:11]
	ds_bpermute_b32 v11, v25, v9
	ds_bpermute_b32 v10, v25, v8
	s_waitcnt lgkmcnt(0)
	v_pk_add_f32 v[8:9], v[8:9], v[10:11]
	ds_bpermute_b32 v11, v26, v9
	ds_bpermute_b32 v10, v26, v8
	s_waitcnt lgkmcnt(0)
	v_pk_add_f32 v[8:9], v[8:9], v[10:11]
	ds_bpermute_b32 v11, v27, v9
	ds_bpermute_b32 v10, v27, v8
	s_waitcnt lgkmcnt(0)
	v_pk_add_f32 v[8:9], v[8:9], v[10:11]
	ds_bpermute_b32 v11, v28, v9
	ds_bpermute_b32 v10, v28, v8
	s_and_saveexec_b64 s[12:13], vcc
	s_cbranch_execz .LBB1_2149
	s_waitcnt lgkmcnt(0)
	v_pk_add_f32 v[8:9], v[8:9], v[10:11]
	s_mov_b32 s14, 0x3a000000
	v_pk_fma_f32 v[8:9], v[8:9], s[14:15], v[4:5] op_sel_hi:[1,0,0]
	v_lshl_add_u64 v[0:1], v[0:1], 2, s[8:9]
	v_mul_f32_e32 v10, 0x4b800000, v9
	v_cmp_gt_f32_e64 s[40:41], s3, v9
	v_cmp_gt_f32_e64 s[42:43], s3, v8
	s_nop 0
	v_cndmask_b32_e64 v9, v9, v10, s[40:41]
	v_rsq_f32_e32 v9, v9
	v_mul_f32_e32 v10, 0x4b800000, v8
	v_cndmask_b32_e64 v8, v8, v10, s[42:43]
	v_rsq_f32_e32 v8, v8
	v_mul_f32_e32 v10, 0x45800000, v9
	v_cndmask_b32_e64 v9, v9, v10, s[40:41]
	global_store_dword v[0:1], v9, off
	v_mul_f32_e32 v0, 0x45800000, v8
	v_cndmask_b32_e64 v8, v8, v0, s[42:43]
	v_lshl_add_u64 v[0:1], v[6:7], 2, s[8:9]
	global_store_dword v[0:1], v8, off
	s_branch .LBB1_2149

; DI unsigned pack2(float a, float b) { f32x2 v = {a, b}; hwbf16x2 r = __builtin_convertvector(v, hwbf16x2); return __builtin_bit_cast(unsigned, r); }
; template <bool BF> DI void pool_phase(const Params& p, const void* x, const float* gain) {
;     ...
;     for (int t = t0; t < t1; ++t) {
;         const int b = t / S, s = t - b * S;
;         const int lo = max(s - left, 0), hi = min(s + right + 1, S);
;         if (t == t0 || s == 0) {
;             sum = (f32x4){0.f, 0.f, 0.f, 0.f};
;             for (int u = lo; u < hi; ++u) { const int tu = b * S + u; const float r = rstd[tu]; const f32x4 v = ldx4<BF>(x, (size_t)tu * D + tid * 4); sum += v * r; }
;         } else {
;             if (hi > phi) { const int tu = b * S + hi - 1; sum += ldx4<BF>(x, (size_t)tu * D + tid * 4) * rstd[tu]; }
;             if (lo > plo) { const int tu = b * S + plo;    sum -= ldx4<BF>(x, (size_t)tu * D + tid * 4) * rstd[tu]; }
;         }
;         plo = lo; phi = hi;
;         const float rc = 1.0f / (float)(hi - lo);
;         const f32x4 me = ldx4<BF>(x, (size_t)t * D + tid * 4) * rstd[t];
;         const f32x4 o = (sum * rc - me) * gn;
;         u32x2 w; w[0] = pack2(o[0], o[1]); w[1] = pack2(o[2], o[3]);
;         *(u32x2*)(H + (size_t)t * D + tid * 4) = w;
.LBB1_2220:
	v_sub_u32_e32 v16, v20, v21
	v_cvt_f32_i32_e32 v16, v16
	s_lshl_b64 s[14:15], s[8:9], 2
	v_add_u32_e32 v5, 1, v5
	v_div_scale_f32 v17, s[12:13], v16, v16, 1.0
	v_rcp_f32_e32 v18, v17
	s_lshl_b64 s[12:13], s[8:9], 12
	s_add_u32 s14, s40, s14
	s_addc_u32 s15, s41, s15
	v_fma_f32 v19, -v17, v18, 1.0
	v_fmac_f32_e32 v18, v19, v18
	v_div_scale_f32 v19, vcc, 1.0, v16, 1.0
	v_mul_f32_e32 v22, v19, v18
	v_fma_f32 v23, -v17, v22, v19
	v_fmac_f32_e32 v22, v23, v18
	v_fma_f32 v17, -v17, v22, v19
	v_div_fmas_f32 v17, v17, v18, v22
	v_lshl_add_u64 v[18:19], v[6:7], 0, s[12:13]
	global_load_dwordx2 v[18:19], v[18:19], off
	v_mov_b64_e32 v[24:25], s[14:15]
	global_load_dword v24, v[24:25], off
	v_div_fixup_f32 v16, v17, v16, 1.0
	s_add_i32 s8, s8, 1
	s_cmp_lt_i32 s8, s16
	s_waitcnt vmcnt(0) lgkmcnt(0)
	v_lshlrev_b32_e32 v22, 16, v18
	v_and_b32_e32 v23, 0xffff0000, v18
	v_lshlrev_b32_e32 v18, 16, v19
	v_and_b32_e32 v19, 0xffff0000, v19
	v_pk_mul_f32 v[18:19], v[24:25], v[18:19] op_sel_hi:[0,1]
	v_pk_mul_f32 v[22:23], v[24:25], v[22:23] op_sel_hi:[0,1]
	v_pk_fma_f32 v[22:23], v[16:17], v[12:13], v[22:23] op_sel_hi:[0,1,1] neg_lo:[0,0,1] neg_hi:[0,0,1]
	v_pk_fma_f32 v[16:17], v[16:17], v[14:15], v[18:19] op_sel_hi:[0,1,1] neg_lo:[0,0,1] neg_hi:[0,0,1]
	v_pk_mul_f32 v[16:17], v[2:3], v[16:17]
	v_pk_mul_f32 v[18:19], v[0:1], v[22:23]
	s_nop 0
	v_cvt_pk_bf16_f32 v18, v18, v19
	v_cvt_pk_bf16_f32 v19, v16, v17
	v_lshl_add_u64 v[16:17], v[8:9], 0, s[12:13]
	global_store_dwordx2 v[16:17], v[18:19], off
	v_mov_b32_e32 v17, v20
	s_cbranch_scc0 .LBB1_2232
.LBB1_2221:
	s_ashr_i32 s9, s8, 31
	s_lshr_b32 s12, s9, 20
	s_add_i32 s12, s8, s12
	s_and_b32 s14, s12, 0xfffff000
	s_sub_i32 s12, s8, s14
	s_cmp_lg_u32 s8, s3
	v_sub_u32_e32 v16, s12, v39
	v_add_u32_e32 v18, s12, v39
	s_cselect_b64 s[12:13], -1, 0
	s_cmp_lg_u32 s8, s14
	s_cselect_b64 s[18:19], -1, 0
	s_and_b64 s[18:19], s[12:13], s[18:19]
	v_min_i32_e32 v20, 0x1000, v18
	s_mov_b64 s[12:13], -1
	s_and_b64 vcc, exec, s[18:19]
	s_cbranch_vccz .LBB1_2227
	v_cmp_gt_i32_e32 vcc, v20, v17
	s_and_saveexec_b64 s[12:13], vcc
	s_cbranch_execz .LBB1_2224
	v_add3_u32 v18, s14, -1, v20
	v_ashrrev_i32_e32 v19, 31, v18
	v_lshlrev_b64 v[22:23], 12, v[18:19]
	v_lshl_add_u64 v[22:23], v[6:7], 0, v[22:23]
	global_load_dwordx2 v[22:23], v[22:23], off
	v_lshl_add_u64 v[18:19], v[18:19], 2, s[40:41]
	global_load_dword v18, v[18:19], off
	s_waitcnt vmcnt(0) lgkmcnt(0)
	v_lshlrev_b32_e32 v24, 16, v22
	v_and_b32_e32 v25, 0xffff0000, v22
	v_lshlrev_b32_e32 v22, 16, v23
	v_and_b32_e32 v23, 0xffff0000, v23
	v_pk_fma_f32 v[14:15], v[18:19], v[22:23], v[14:15] op_sel_hi:[0,1,1]
	v_pk_fma_f32 v[12:13], v[18:19], v[24:25], v[12:13] op_sel_hi:[0,1,1]
.LBB1_2224:
	s_or_b64 exec, exec, s[12:13]
	v_cmp_gt_i32_e32 vcc, v16, v21
	s_and_saveexec_b64 s[12:13], vcc
	s_cbranch_execz .LBB1_2226
	v_add_u32_e32 v18, s14, v21
	v_ashrrev_i32_e32 v19, 31, v18
	v_lshlrev_b64 v[22:23], 12, v[18:19]
	v_lshl_add_u64 v[22:23], v[6:7], 0, v[22:23]
	global_load_dwordx2 v[22:23], v[22:23], off
	v_lshl_add_u64 v[18:19], v[18:19], 2, s[40:41]
	global_load_dword v18, v[18:19], off
	s_waitcnt vmcnt(0) lgkmcnt(0)
	v_lshlrev_b32_e32 v24, 16, v22
	v_and_b32_e32 v25, 0xffff0000, v22
	v_lshlrev_b32_e32 v22, 16, v23
	v_and_b32_e32 v23, 0xffff0000, v23
	v_pk_fma_f32 v[14:15], v[18:19], v[22:23], v[14:15] op_sel_hi:[0,1,1] neg_lo:[1,0,0] neg_hi:[1,0,0]
	v_pk_fma_f32 v[12:13], v[18:19], v[24:25], v[12:13] op_sel_hi:[0,1,1] neg_lo:[1,0,0] neg_hi:[1,0,0]

; template <bool BF> DI void pool_phase(const Params& p, const void* x, const float* gain) {
;     ...
;             for (int u = lo; u < hi; ++u) { const int tu = b * S + u; const float r = rstd[tu]; const f32x4 v = ldx4<BF>(x, (size_t)tu * D + tid * 4); sum += v * r; }
.LBB1_2230:
	global_load_dwordx2 v[24:25], v[16:17], off
	global_load_dword v26, v[18:19], off
	v_add_u32_e32 v22, 1, v22
	s_mov_b64 s[18:19], 0x1000
	v_cmp_ge_i32_e32 vcc, v22, v20
	v_lshl_add_u64 v[16:17], v[16:17], 0, s[18:19]
	v_lshl_add_u64 v[18:19], v[18:19], 0, 4
	s_or_b64 s[14:15], vcc, s[14:15]
	s_waitcnt vmcnt(0) lgkmcnt(0)
	v_lshlrev_b32_e32 v28, 16, v24
	v_and_b32_e32 v29, 0xffff0000, v24
	v_lshlrev_b32_e32 v24, 16, v25
	v_and_b32_e32 v25, 0xffff0000, v25
	v_pk_fma_f32 v[14:15], v[26:27], v[24:25], v[14:15] op_sel_hi:[0,1,1]
	v_pk_fma_f32 v[12:13], v[26:27], v[28:29], v[12:13] op_sel_hi:[0,1,1]
	s_andn2_b64 exec, exec, s[14:15]
	s_cbranch_execnz .LBB1_2230
	s_or_b64 exec, exec, s[14:15]
	s_branch .LBB1_2219

; template <bool BF> DI void pool_phase(const Params& p, const void* x, const float* gain) {
;     ...
;             for (int u = lo; u < hi; ++u) { const int tu = b * S + u; sm[c] += ldx4<BF>(x, (size_t)tu * D + tid * 4) * rstd[tu]; }
.LBB1_2236:
	v_add_u32_e32 v12, s21, v10
	v_ashrrev_i32_e32 v13, 31, v12
	v_lshlrev_b64 v[14:15], 12, v[12:13]
	v_lshl_add_u64 v[14:15], v[4:5], 0, v[14:15]
	global_load_dwordx2 v[14:15], v[14:15], off
	v_lshl_add_u64 v[12:13], v[12:13], 2, s[40:41]
	global_load_dword v12, v[12:13], off
	v_add_u32_e32 v10, 1, v10
	v_cmp_ge_i32_e32 vcc, v10, v86
	s_or_b64 s[14:15], vcc, s[14:15]
	s_waitcnt vmcnt(0) lgkmcnt(0)
	v_lshlrev_b32_e32 v16, 16, v14
	v_and_b32_e32 v17, 0xffff0000, v14
	v_lshlrev_b32_e32 v14, 16, v15
	v_and_b32_e32 v15, 0xffff0000, v15
	v_pk_fma_f32 v[8:9], v[12:13], v[14:15], v[8:9] op_sel_hi:[0,1,1]
	v_pk_fma_f32 v[6:7], v[12:13], v[16:17], v[6:7] op_sel_hi:[0,1,1]
	s_andn2_b64 exec, exec, s[14:15]
	s_cbranch_execnz .LBB1_2236
	s_or_b64 exec, exec, s[14:15]

; template <bool BF> DI void pool_phase(const Params& p, const void* x, const float* gain) {
;     ...
;             for (int u = lo; u < hi; ++u) { const int tu = b * S + u; sm[c] += ldx4<BF>(x, (size_t)tu * D + tid * 4) * rstd[tu]; }
.LBB1_2240:
	v_add_u32_e32 v16, s19, v14
	v_ashrrev_i32_e32 v17, 31, v16
	v_lshlrev_b64 v[18:19], 12, v[16:17]
	v_lshl_add_u64 v[18:19], v[4:5], 0, v[18:19]
	global_load_dwordx2 v[18:19], v[18:19], off
	v_lshl_add_u64 v[16:17], v[16:17], 2, s[40:41]
	global_load_dword v16, v[16:17], off
	v_add_u32_e32 v14, 1, v14
	v_cmp_ge_i32_e32 vcc, v14, v73
	s_or_b64 s[14:15], vcc, s[14:15]
	s_waitcnt vmcnt(0) lgkmcnt(0)
	v_lshlrev_b32_e32 v20, 16, v18
	v_and_b32_e32 v21, 0xffff0000, v18
	v_lshlrev_b32_e32 v18, 16, v19
	v_and_b32_e32 v19, 0xffff0000, v19
	v_pk_fma_f32 v[12:13], v[16:17], v[18:19], v[12:13] op_sel_hi:[0,1,1]
	v_pk_fma_f32 v[10:11], v[16:17], v[20:21], v[10:11] op_sel_hi:[0,1,1]
	s_andn2_b64 exec, exec, s[14:15]
	s_cbranch_execnz .LBB1_2240
	s_or_b64 exec, exec, s[14:15]
	s_mov_b32 s3, 0
	v_mov_b32_e32 v14, s3
	v_mov_b32_e32 v15, s3
	v_mov_b32_e32 v16, s3
	v_mov_b32_e32 v17, s3
	v_mov_b32_e32 v18, s3
	v_mov_b32_e32 v19, s3
	v_mov_b32_e32 v20, s3
	v_mov_b32_e32 v21, s3

; template <bool BF> DI void pool_phase(const Params& p, const void* x, const float* gain) {
;     ...
;             for (int u = lo; u < hi; ++u) { const int tu = b * S + u; sm[c] += ldx4<BF>(x, (size_t)tu * D + tid * 4) * rstd[tu]; }
.LBB1_2244:
	v_add_u32_e32 v20, s3, v18
	v_ashrrev_i32_e32 v21, 31, v20
	v_lshlrev_b64 v[24:25], 12, v[20:21]
	v_lshl_add_u64 v[24:25], v[4:5], 0, v[24:25]
	global_load_dwordx2 v[24:25], v[24:25], off
	v_lshl_add_u64 v[20:21], v[20:21], 2, s[40:41]
	global_load_dword v20, v[20:21], off
	v_add_u32_e32 v18, 1, v18
	v_cmp_ge_i32_e32 vcc, v18, v88
	s_or_b64 s[14:15], vcc, s[14:15]
	s_waitcnt vmcnt(0) lgkmcnt(0)
	v_lshlrev_b32_e32 v26, 16, v24
	v_and_b32_e32 v27, 0xffff0000, v24
	v_lshlrev_b32_e32 v24, 16, v25
	v_and_b32_e32 v25, 0xffff0000, v25
	v_pk_fma_f32 v[16:17], v[20:21], v[24:25], v[16:17] op_sel_hi:[0,1,1]
	v_pk_fma_f32 v[14:15], v[20:21], v[26:27], v[14:15] op_sel_hi:[0,1,1]
	s_andn2_b64 exec, exec, s[14:15]
	s_cbranch_execnz .LBB1_2244
	s_or_b64 exec, exec, s[14:15]
	s_mov_b32 s14, 0
	v_mov_b32_e32 v18, s14
	v_mov_b32_e32 v19, s14
	v_mov_b32_e32 v20, s14
	v_mov_b32_e32 v21, s14

; template <bool BF> DI void pool_phase(const Params& p, const void* x, const float* gain) {
;     ...
;             for (int u = lo; u < hi; ++u) { const int tu = b * S + u; sm[c] += ldx4<BF>(x, (size_t)tu * D + tid * 4) * rstd[tu]; }
;     ...
;             for (int c = 0; c < 4; ++c) {
;                 const int t = tb + 16 * c + i, b = t / S, s = t - b * S;
;                 const int lo = max(s - left, 0), hi = min(s + right + 1, S);
;                 const int ta = b * S + hi - 1, ts = b * S + pl[c];
;                 va[c] = ldx4<BF>(x, (size_t)ta * D + tid * 4); vs[c] = ldx4<BF>(x, (size_t)ts * D + tid * 4); vm[c] = ldx4<BF>(x, (size_t)t * D + tid * 4);
;                 ra[c] = (i > 0 && hi > ph[c]) ? rstd[ta] : 0.f; rs[c] = (i > 0 && lo > pl[c]) ? rstd[ts] : 0.f; rm[c] = rstd[t];
;                 rc[c] = 1.0f / (float)(hi - lo); pl[c] = lo; ph[c] = hi;
.LBB1_2248:
	v_add_u32_e32 v26, s2, v24
	v_ashrrev_i32_e32 v27, 31, v26
	v_lshlrev_b64 v[28:29], 12, v[26:27]
	v_lshl_add_u64 v[28:29], v[4:5], 0, v[28:29]
	global_load_dwordx2 v[28:29], v[28:29], off
	v_lshl_add_u64 v[26:27], v[26:27], 2, s[40:41]
	global_load_dword v26, v[26:27], off
	v_add_u32_e32 v24, 1, v24
	v_cmp_ge_i32_e32 vcc, v24, v89
	s_or_b64 s[16:17], vcc, s[16:17]
	s_waitcnt vmcnt(0) lgkmcnt(0)
	v_lshlrev_b32_e32 v30, 16, v28
	v_and_b32_e32 v31, 0xffff0000, v28
	v_lshlrev_b32_e32 v28, 16, v29
	v_and_b32_e32 v29, 0xffff0000, v29
	v_pk_fma_f32 v[20:21], v[26:27], v[28:29], v[20:21] op_sel_hi:[0,1,1]
	v_pk_fma_f32 v[18:19], v[26:27], v[30:31], v[18:19] op_sel_hi:[0,1,1]
	s_andn2_b64 exec, exec, s[16:17]
	s_cbranch_execnz .LBB1_2248
	s_or_b64 exec, exec, s[16:17]
.LBB1_2250:
	s_or_b64 exec, exec, s[12:13]
	v_lshlrev_b64 v[22:23], 1, v[22:23]
	v_sub_u32_e32 v40, v86, v41
	v_lshl_add_u64 v[24:25], s[10:11], 0, v[22:23]
	s_lshl_b64 s[12:13], s[8:9], 12
	s_lshl_b64 s[10:11], s[8:9], 2
	v_cvt_f32_i32_e32 v40, v40
	s_add_u32 s16, s40, s10
	s_addc_u32 s17, s41, s11
	v_mov_b64_e32 v[42:43], s[16:17]
	global_load_dword v38, v[42:43], off
	v_div_scale_f32 v42, s[16:17], v40, v40, 1.0
	v_rcp_f32_e32 v43, v42
	v_add3_u32 v26, s21, -1, v86
	v_add_u32_e32 v30, s21, v41
	v_ashrrev_i32_e32 v27, 31, v26
	v_fma_f32 v44, -v42, v43, 1.0
	v_fmac_f32_e32 v43, v44, v43
	v_div_scale_f32 v44, vcc, 1.0, v40, 1.0
	v_mul_f32_e32 v45, v44, v43
	v_fma_f32 v46, -v42, v45, v44
	v_fmac_f32_e32 v45, v46, v43
	v_fma_f32 v42, -v42, v45, v44
	v_div_fmas_f32 v42, v42, v43, v45
	v_div_fixup_f32 v40, v42, v40, 1.0
	v_add3_u32 v42, s19, -1, v73
	v_add_u32_e32 v46, s19, v67
	s_ashr_i32 s19, s18, 31
	s_lshl_b64 s[16:17], s[18:19], 12
	s_lshl_b64 s[18:19], s[18:19], 2
	s_add_u32 s18, s40, s18
	s_addc_u32 s19, s41, s19
	v_mov_b64_e32 v[54:55], s[18:19]
	global_load_dword v54, v[54:55], off
	v_sub_u32_e32 v55, v73, v67
	v_cvt_f32_i32_e32 v55, v55
	v_ashrrev_i32_e32 v31, 31, v30
	v_lshlrev_b64 v[26:27], 12, v[26:27]
	v_lshlrev_b64 v[30:31], 12, v[30:31]
	v_div_scale_f32 v56, s[18:19], v55, v55, 1.0
	v_rcp_f32_e32 v57, v56
	v_lshl_add_u64 v[26:27], v[4:5], 0, v[26:27]
	v_lshl_add_u64 v[30:31], v[4:5], 0, v[30:31]
	global_load_dwordx2 v[26:27], v[26:27], off
	v_fma_f32 v58, -v56, v57, 1.0
	v_fmac_f32_e32 v57, v58, v57
	v_div_scale_f32 v58, vcc, 1.0, v55, 1.0
	v_mul_f32_e32 v59, v58, v57
	v_fma_f32 v60, -v56, v59, v58
	v_fmac_f32_e32 v59, v60, v57
	v_fma_f32 v56, -v56, v59, v58
	v_add3_u32 v58, s3, -1, v88
	v_add_u32_e32 v60, s3, v87
	v_div_fmas_f32 v56, v56, v57, v59
	v_ashrrev_i32_e32 v59, 31, v58
	v_ashrrev_i32_e32 v61, 31, v60
	v_lshlrev_b64 v[58:59], 12, v[58:59]
	v_lshlrev_b64 v[60:61], 12, v[60:61]
	v_lshl_add_u64 v[58:59], v[4:5], 0, v[58:59]
	v_lshl_add_u64 v[60:61], v[4:5], 0, v[60:61]
	global_load_dwordx2 v[58:59], v[58:59], off
	v_div_fixup_f32 v56, v56, v55, 1.0
	global_load_dwordx2 v[60:61], v[60:61], off
	v_sub_u32_e32 v55, v88, v87
	global_load_dwordx2 v[32:33], v[30:31], off
	s_ashr_i32 s21, s20, 31
	v_cvt_f32_i32_e32 v55, v55
	v_lshl_add_u64 v[34:35], v[4:5], 0, s[12:13]
	s_lshl_b64 s[18:19], s[20:21], 12
	s_lshl_b64 s[20:21], s[20:21], 2
	global_load_dwordx2 v[36:37], v[34:35], off
	s_add_u32 s20, s40, s20
	v_ashrrev_i32_e32 v43, 31, v42
	v_ashrrev_i32_e32 v47, 31, v46
	s_addc_u32 s21, s41, s21
	v_lshlrev_b64 v[42:43], 12, v[42:43]
	v_lshlrev_b64 v[46:47], 12, v[46:47]
	v_mov_b64_e32 v[74:75], s[20:21]
	v_div_scale_f32 v57, s[20:21], v55, v55, 1.0
	v_lshl_add_u64 v[42:43], v[4:5], 0, v[42:43]
	v_lshl_add_u64 v[46:47], v[4:5], 0, v[46:47]
	v_rcp_f32_e32 v72, v57
	global_load_dwordx2 v[42:43], v[42:43], off
	v_lshl_add_u64 v[50:51], v[4:5], 0, s[16:17]
	global_load_dwordx2 v[48:49], v[46:47], off
	global_load_dwordx2 v[52:53], v[50:51], off
	global_load_dword v66, v[74:75], off
	v_fma_f32 v74, -v57, v72, 1.0
	v_fmac_f32_e32 v72, v74, v72
	v_div_scale_f32 v74, vcc, 1.0, v55, 1.0
	v_mul_f32_e32 v75, v74, v72
	v_fma_f32 v76, -v57, v75, v74
	v_fmac_f32_e32 v75, v76, v72
	v_fma_f32 v57, -v57, v75, v74
	v_add3_u32 v74, s2, -1, v89
	v_add_u32_e32 v78, s2, v90
	v_div_fmas_f32 v57, v57, v72, v75
	v_ashrrev_i32_e32 v75, 31, v74
	v_ashrrev_i32_e32 v79, 31, v78
	v_lshlrev_b64 v[74:75], 12, v[74:75]
	v_lshlrev_b64 v[78:79], 12, v[78:79]
	s_ashr_i32 s15, s14, 31
	v_lshl_add_u64 v[74:75], v[4:5], 0, v[74:75]
	v_lshl_add_u64 v[78:79], v[4:5], 0, v[78:79]
	s_lshl_b64 s[20:21], s[14:15], 12
	s_lshl_b64 s[2:3], s[14:15], 2
	global_load_dwordx2 v[74:75], v[74:75], off
	s_add_u32 s2, s40, s2
	global_load_dwordx2 v[80:81], v[78:79], off
	v_lshl_add_u64 v[82:83], v[4:5], 0, s[20:21]
	s_addc_u32 s3, s41, s3
	global_load_dwordx2 v[84:85], v[82:83], off
	v_mov_b64_e32 v[92:93], s[2:3]
	global_load_dword v92, v[92:93], off
	v_div_fixup_f32 v72, v57, v55, 1.0
	v_sub_u32_e32 v55, v89, v90
	v_cvt_f32_i32_e32 v55, v55
	v_lshl_add_u64 v[22:23], s[12:13], 0, v[22:23]
	v_div_scale_f32 v57, s[2:3], v55, v55, 1.0
	v_rcp_f32_e32 v91, v57
	s_waitcnt vmcnt(0) lgkmcnt(0)
; DI unsigned pack2(float a, float b) { f32x2 v = {a, b}; hwbf16x2 r = __builtin_convertvector(v, hwbf16x2); return __builtin_bit_cast(unsigned, r); }
; template <bool BF> DI void pool_phase(const Params& p, const void* x, const float* gain) {
;     ...
; #pragma unroll
;             for (int c = 0; c < 4; ++c) {
;                 const int t = tb + 16 * c + i;
;                 sm[c] += va[c] * ra[c] - vs[c] * rs[c];
;                 const f32x4 o = (sm[c] * rc[c] - vm[c] * rm[c]) * gn;
;                 u32x2 w; w[0] = pack2(o[0], o[1]); w[1] = pack2(o[2], o[3]);
;                 *(u32x2*)(H + (size_t)t * D + tid * 4) = w;
;             }
	v_lshlrev_b32_e32 v28, 16, v26
	v_and_b32_e32 v29, 0xffff0000, v26
	v_lshlrev_b32_e32 v26, 16, v27
	v_and_b32_e32 v27, 0xffff0000, v27
	v_fma_f32 v93, -v57, v91, 1.0
	v_fmac_f32_e32 v91, v93, v91
	v_div_scale_f32 v93, vcc, 1.0, v55, 1.0
	v_mul_f32_e32 v94, v93, v91
	v_fma_f32 v95, -v57, v94, v93
	v_fmac_f32_e32 v94, v95, v91
	v_fma_f32 v57, -v57, v94, v93
	v_div_fmas_f32 v57, v57, v91, v94
	v_div_fixup_f32 v94, v57, v55, 1.0
	s_mov_b32 s2, 0
	v_lshlrev_b32_e32 v62, 16, v58
	v_and_b32_e32 v63, 0xffff0000, v58
	v_lshlrev_b32_e32 v68, 16, v60
	v_and_b32_e32 v69, 0xffff0000, v60
	v_lshlrev_b32_e32 v70, 16, v61
	v_and_b32_e32 v71, 0xffff0000, v61
	v_lshl_add_u64 v[60:61], v[4:5], 0, s[18:19]
	global_load_dwordx2 v[64:65], v[60:61], off
	v_lshlrev_b32_e32 v30, 16, v32
	v_and_b32_e32 v31, 0xffff0000, v32
	v_lshlrev_b32_e32 v32, 16, v33
	v_and_b32_e32 v33, 0xffff0000, v33
	v_pk_mul_f32 v[32:33], v[32:33], 0 op_sel_hi:[1,0]
	v_pk_mul_f32 v[30:31], v[30:31], 0 op_sel_hi:[1,0]
	v_lshlrev_b32_e32 v34, 16, v36
	v_and_b32_e32 v35, 0xffff0000, v36
	v_lshlrev_b32_e32 v36, 16, v37
	v_and_b32_e32 v37, 0xffff0000, v37
	v_pk_fma_f32 v[28:29], v[28:29], 0, v[30:31] op_sel_hi:[1,0,1] neg_lo:[0,0,1] neg_hi:[0,0,1]
	v_pk_fma_f32 v[26:27], v[26:27], 0, v[32:33] op_sel_hi:[1,0,1] neg_lo:[0,0,1] neg_hi:[0,0,1]
	v_pk_add_f32 v[6:7], v[6:7], v[28:29]
	v_pk_add_f32 v[8:9], v[8:9], v[26:27]
	v_pk_mul_f32 v[26:27], v[38:39], v[36:37] op_sel_hi:[0,1]
	v_pk_mul_f32 v[28:29], v[38:39], v[34:35] op_sel_hi:[0,1]
	v_pk_fma_f32 v[28:29], v[40:41], v[6:7], v[28:29] op_sel_hi:[0,1,1] neg_lo:[0,0,1] neg_hi:[0,0,1]
	v_pk_fma_f32 v[26:27], v[40:41], v[8:9], v[26:27] op_sel_hi:[0,1,1] neg_lo:[0,0,1] neg_hi:[0,0,1]
	v_pk_mul_f32 v[26:27], v[2:3], v[26:27]
	v_pk_mul_f32 v[28:29], v[0:1], v[28:29]
	v_lshlrev_b32_e32 v46, 16, v48
	v_and_b32_e32 v47, 0xffff0000, v48
	v_lshlrev_b32_e32 v48, 16, v49
	v_and_b32_e32 v49, 0xffff0000, v49
	v_cvt_pk_bf16_f32 v28, v28, v29
	v_cvt_pk_bf16_f32 v29, v26, v27
	v_lshl_add_u64 v[26:27], v[24:25], 0, s[12:13]
	v_lshlrev_b32_e32 v44, 16, v42
	v_and_b32_e32 v45, 0xffff0000, v42
	v_lshlrev_b32_e32 v42, 16, v43
	v_and_b32_e32 v43, 0xffff0000, v43
	global_store_dwordx2 v[26:27], v[28:29], off
	v_pk_mul_f32 v[26:27], v[48:49], 0 op_sel_hi:[1,0]
	v_pk_mul_f32 v[28:29], v[46:47], 0 op_sel_hi:[1,0]
	v_lshlrev_b32_e32 v50, 16, v52
	v_and_b32_e32 v51, 0xffff0000, v52
	v_lshlrev_b32_e32 v52, 16, v53
	v_and_b32_e32 v53, 0xffff0000, v53
	v_pk_fma_f32 v[28:29], v[44:45], 0, v[28:29] op_sel_hi:[1,0,1] neg_lo:[0,0,1] neg_hi:[0,0,1]
	v_pk_fma_f32 v[26:27], v[42:43], 0, v[26:27] op_sel_hi:[1,0,1] neg_lo:[0,0,1] neg_hi:[0,0,1]
	v_pk_add_f32 v[10:11], v[10:11], v[28:29]
	v_pk_add_f32 v[12:13], v[12:13], v[26:27]
	v_pk_mul_f32 v[26:27], v[54:55], v[52:53] op_sel_hi:[0,1]
	v_pk_mul_f32 v[28:29], v[54:55], v[50:51] op_sel_hi:[0,1]
	v_pk_fma_f32 v[28:29], v[56:57], v[10:11], v[28:29] op_sel_hi:[0,1,1] neg_lo:[0,0,1] neg_hi:[0,0,1]
	v_pk_fma_f32 v[26:27], v[56:57], v[12:13], v[26:27] op_sel_hi:[0,1,1] neg_lo:[0,0,1] neg_hi:[0,0,1]
	v_pk_mul_f32 v[26:27], v[2:3], v[26:27]
	v_pk_mul_f32 v[28:29], v[0:1], v[28:29]
	v_lshlrev_b32_e32 v58, 16, v59
	v_cvt_pk_bf16_f32 v28, v28, v29
	v_cvt_pk_bf16_f32 v29, v26, v27
	v_lshl_add_u64 v[26:27], v[24:25], 0, s[16:17]
	v_and_b32_e32 v59, 0xffff0000, v59
	global_store_dwordx2 v[26:27], v[28:29], off
	v_pk_mul_f32 v[26:27], v[70:71], 0 op_sel_hi:[1,0]
	v_pk_mul_f32 v[28:29], v[68:69], 0 op_sel_hi:[1,0]
	v_pk_fma_f32 v[26:27], v[58:59], 0, v[26:27] op_sel_hi:[1,0,1] neg_lo:[0,0,1] neg_hi:[0,0,1]
	v_pk_fma_f32 v[28:29], v[62:63], 0, v[28:29] op_sel_hi:[1,0,1] neg_lo:[0,0,1] neg_hi:[0,0,1]
	v_pk_add_f32 v[16:17], v[16:17], v[26:27]
	v_pk_add_f32 v[14:15], v[14:15], v[28:29]
	v_lshlrev_b32_e32 v78, 16, v80
	v_and_b32_e32 v79, 0xffff0000, v80
	v_lshlrev_b32_e32 v80, 16, v81
	v_and_b32_e32 v81, 0xffff0000, v81
	v_lshlrev_b32_e32 v76, 16, v74
	v_and_b32_e32 v77, 0xffff0000, v74
	v_lshlrev_b32_e32 v74, 16, v75
	v_and_b32_e32 v75, 0xffff0000, v75
	v_lshlrev_b32_e32 v82, 16, v84
	v_and_b32_e32 v83, 0xffff0000, v84
	v_lshlrev_b32_e32 v84, 16, v85
	v_and_b32_e32 v85, 0xffff0000, v85
	s_waitcnt vmcnt(0) lgkmcnt(0)
	v_lshlrev_b32_e32 v60, 16, v64
	v_and_b32_e32 v61, 0xffff0000, v64
	v_lshlrev_b32_e32 v64, 16, v65
	v_and_b32_e32 v65, 0xffff0000, v65
	v_pk_mul_f32 v[26:27], v[66:67], v[64:65] op_sel_hi:[0,1]
	v_pk_mul_f32 v[28:29], v[66:67], v[60:61] op_sel_hi:[0,1]
	v_pk_fma_f32 v[28:29], v[72:73], v[14:15], v[28:29] op_sel_hi:[0,1,1] neg_lo:[0,0,1] neg_hi:[0,0,1]
	v_pk_fma_f32 v[26:27], v[72:73], v[16:17], v[26:27] op_sel_hi:[0,1,1] neg_lo:[0,0,1] neg_hi:[0,0,1]
	v_pk_mul_f32 v[26:27], v[2:3], v[26:27]
	v_pk_mul_f32 v[28:29], v[0:1], v[28:29]
	s_nop 0
	v_cvt_pk_bf16_f32 v28, v28, v29
	v_cvt_pk_bf16_f32 v29, v26, v27
	v_lshl_add_u64 v[26:27], v[24:25], 0, s[18:19]
	global_store_dwordx2 v[26:27], v[28:29], off
	v_pk_mul_f32 v[26:27], v[80:81], 0 op_sel_hi:[1,0]
	v_pk_mul_f32 v[28:29], v[78:79], 0 op_sel_hi:[1,0]
	v_pk_fma_f32 v[26:27], v[74:75], 0, v[26:27] op_sel_hi:[1,0,1] neg_lo:[0,0,1] neg_hi:[0,0,1]
	v_pk_fma_f32 v[28:29], v[76:77], 0, v[28:29] op_sel_hi:[1,0,1] neg_lo:[0,0,1] neg_hi:[0,0,1]
	v_pk_add_f32 v[20:21], v[20:21], v[26:27]
	v_pk_add_f32 v[18:19], v[18:19], v[28:29]
	v_pk_mul_f32 v[26:27], v[92:93], v[84:85] op_sel_hi:[0,1]
	v_pk_mul_f32 v[28:29], v[92:93], v[82:83] op_sel_hi:[0,1]
	v_pk_fma_f32 v[28:29], v[94:95], v[18:19], v[28:29] op_sel_hi:[0,1,1] neg_lo:[0,0,1] neg_hi:[0,0,1]
	v_pk_fma_f32 v[26:27], v[94:95], v[20:21], v[26:27] op_sel_hi:[0,1,1] neg_lo:[0,0,1] neg_hi:[0,0,1]
	v_pk_mul_f32 v[26:27], v[2:3], v[26:27]
	v_pk_mul_f32 v[28:29], v[0:1], v[28:29]
	v_lshl_add_u64 v[24:25], v[24:25], 0, s[20:21]
	v_cvt_pk_bf16_f32 v28, v28, v29
	v_cvt_pk_bf16_f32 v29, v26, v27
	global_store_dwordx2 v[24:25], v[28:29], off
	v_add_u32_e32 v25, s8, v39
	v_sub_u32_e32 v27, s8, v39
	s_branch .LBB1_2252
; DI unsigned pack2(float a, float b) { f32x2 v = {a, b}; hwbf16x2 r = __builtin_convertvector(v, hwbf16x2); return __builtin_bit_cast(unsigned, r); }
; template <bool BF> DI void pool_phase(const Params& p, const void* x, const float* gain) {
;     ...
;                 ra[c] = (i > 0 && hi > ph[c]) ? rstd[ta] : 0.f; rs[c] = (i > 0 && lo > pl[c]) ? rstd[ts] : 0.f; rm[c] = rstd[t];
;                 rc[c] = 1.0f / (float)(hi - lo); pl[c] = lo; ph[c] = hi;
;     ...
; #pragma unroll
;             for (int c = 0; c < 4; ++c) {
;                 const int t = tb + 16 * c + i;
;                 sm[c] += va[c] * ra[c] - vs[c] * rs[c];
;                 const f32x4 o = (sm[c] * rc[c] - vm[c] * rm[c]) * gn;
;                 u32x2 w; w[0] = pack2(o[0], o[1]); w[1] = pack2(o[2], o[3]);
;                 *(u32x2*)(H + (size_t)t * D + tid * 4) = w;
;             }
.LBB1_2251:
	s_or_b64 exec, exec, s[12:13]
	v_sub_u32_e32 v49, v41, v43
	v_cvt_f32_i32_e32 v49, v49
	s_waitcnt vmcnt(0) lgkmcnt(0)
	v_lshlrev_b32_e32 v58, 16, v62
	v_and_b32_e32 v59, 0xffff0000, v62
	v_lshlrev_b32_e32 v98, 16, v34
	v_div_scale_f32 v51, s[12:13], v49, v49, 1.0
	v_rcp_f32_e32 v72, v51
	v_div_scale_f32 v62, vcc, 1.0, v49, 1.0
	v_and_b32_e32 v99, 0xffff0000, v34
	v_fma_f32 v73, -v51, v72, 1.0
	v_fmac_f32_e32 v72, v73, v72
	v_mul_f32_e32 v73, v62, v72
	v_fma_f32 v74, -v51, v73, v62
	v_fmac_f32_e32 v73, v74, v72
	v_fma_f32 v51, -v51, v73, v62
	v_div_fmas_f32 v51, v51, v72, v73
	v_div_fixup_f32 v72, v51, v49, 1.0
	v_sub_u32_e32 v49, v31, v39
	v_cvt_f32_i32_e32 v49, v49
	v_lshlrev_b32_e32 v34, 16, v35
	v_and_b32_e32 v35, 0xffff0000, v35
	v_lshlrev_b32_e32 v96, 16, v36
	v_div_scale_f32 v51, s[12:13], v49, v49, 1.0
	v_rcp_f32_e32 v73, v51
	v_and_b32_e32 v97, 0xffff0000, v36
	v_lshlrev_b32_e32 v36, 16, v37
	v_and_b32_e32 v37, 0xffff0000, v37
	v_fma_f32 v78, -v51, v73, 1.0
	v_fmac_f32_e32 v73, v78, v73
	v_div_scale_f32 v78, vcc, 1.0, v49, 1.0
	v_mul_f32_e32 v79, v78, v73
	v_fma_f32 v80, -v51, v79, v78
	v_fmac_f32_e32 v79, v80, v73
	v_fma_f32 v51, -v51, v79, v78
	v_div_fmas_f32 v51, v51, v73, v79
	v_div_fixup_f32 v78, v51, v49, 1.0
	v_sub_u32_e32 v49, v86, v33
	v_cvt_f32_i32_e32 v49, v49
	v_pk_mul_f32 v[34:35], v[26:27], v[34:35] op_sel_hi:[0,1]
	v_pk_mul_f32 v[98:99], v[26:27], v[98:99] op_sel_hi:[0,1]
	v_lshlrev_b32_e32 v100, 16, v28
	v_div_scale_f32 v51, s[12:13], v49, v49, 1.0
	v_rcp_f32_e32 v73, v51
	v_and_b32_e32 v101, 0xffff0000, v28
	v_lshlrev_b32_e32 v28, 16, v29
	v_and_b32_e32 v29, 0xffff0000, v29
	v_fma_f32 v79, -v51, v73, 1.0
	v_fmac_f32_e32 v73, v79, v73
	v_div_scale_f32 v79, vcc, 1.0, v49, 1.0
	v_mul_f32_e32 v87, v79, v73
	v_fma_f32 v88, -v51, v87, v79
	v_fmac_f32_e32 v87, v88, v73
	v_fma_f32 v51, -v51, v87, v79
	v_div_fmas_f32 v51, v51, v73, v87
	v_div_fixup_f32 v88, v51, v49, 1.0
	v_mov_b32_e32 v49, s9
	v_mov_b32_e32 v51, s3
	s_mov_b32 s3, 0x13300000
	v_add_co_u32_e32 v102, vcc, s3, v49
	v_sub_u32_e32 v73, v45, v47
	s_nop 0
	v_addc_co_u32_e32 v103, vcc, 0, v51, vcc
	global_load_dword v102, v[102:103], off offset:196
	v_cvt_f32_i32_e32 v73, v73
	v_pk_fma_f32 v[96:97], v[24:25], v[96:97], v[98:99] op_sel_hi:[0,1,1] neg_lo:[0,0,1] neg_hi:[0,0,1]
	v_pk_fma_f32 v[34:35], v[24:25], v[36:37], v[34:35] op_sel_hi:[0,1,1] neg_lo:[0,0,1] neg_hi:[0,0,1]
	v_pk_add_f32 v[8:9], v[8:9], v[34:35]
	v_div_scale_f32 v49, s[12:13], v73, v73, 1.0
	v_rcp_f32_e32 v51, v49
	v_pk_add_f32 v[6:7], v[6:7], v[96:97]
	v_pk_mul_f32 v[28:29], v[30:31], v[28:29] op_sel_hi:[0,1]
	v_pk_mul_f32 v[34:35], v[30:31], v[100:101] op_sel_hi:[0,1]
	v_fma_f32 v79, -v49, v51, 1.0
	v_fmac_f32_e32 v51, v79, v51
	v_div_scale_f32 v79, vcc, 1.0, v73, 1.0
	v_mul_f32_e32 v87, v79, v51
	v_fma_f32 v89, -v49, v87, v79
	v_pk_fma_f32 v[34:35], v[88:89], v[6:7], v[34:35] op_sel_hi:[0,1,1] neg_lo:[0,0,1] neg_hi:[0,0,1]
	v_pk_fma_f32 v[28:29], v[88:89], v[8:9], v[28:29] op_sel_hi:[0,1,1] neg_lo:[0,0,1] neg_hi:[0,0,1]
	v_fmac_f32_e32 v87, v89, v51
	v_pk_mul_f32 v[28:29], v[2:3], v[28:29]
	v_pk_mul_f32 v[34:35], v[0:1], v[34:35]
	v_fma_f32 v49, -v49, v87, v79
	v_cvt_pk_bf16_f32 v34, v34, v35
	v_cvt_pk_bf16_f32 v35, v28, v29
	v_lshl_add_u64 v[28:29], s[6:7], 0, v[22:23]
	s_mov_b32 s3, 0x13311000
	v_div_fmas_f32 v49, v49, v51, v87
	v_add_co_u32_e32 v36, vcc, s3, v28
	v_lshlrev_b32_e32 v92, 16, v52
	v_and_b32_e32 v93, 0xffff0000, v52
	v_lshlrev_b32_e32 v52, 16, v53
	v_and_b32_e32 v53, 0xffff0000, v53
	v_addc_co_u32_e32 v37, vcc, 0, v29, vcc
	v_lshlrev_b32_e32 v90, 16, v54
	v_and_b32_e32 v91, 0xffff0000, v54
	v_lshlrev_b32_e32 v54, 16, v55
	v_and_b32_e32 v55, 0xffff0000, v55
	global_store_dwordx2 v[36:37], v[34:35], off
	v_pk_mul_f32 v[34:35], v[38:39], v[52:53] op_sel_hi:[0,1]
	v_pk_mul_f32 v[36:37], v[38:39], v[92:93] op_sel_hi:[0,1]
	v_lshlrev_b32_e32 v94, 16, v56
	v_and_b32_e32 v95, 0xffff0000, v56
	v_lshlrev_b32_e32 v56, 16, v57
	v_and_b32_e32 v57, 0xffff0000, v57
	v_pk_fma_f32 v[36:37], v[32:33], v[90:91], v[36:37] op_sel_hi:[0,1,1] neg_lo:[0,0,1] neg_hi:[0,0,1]
	v_pk_fma_f32 v[34:35], v[32:33], v[54:55], v[34:35] op_sel_hi:[0,1,1] neg_lo:[0,0,1] neg_hi:[0,0,1]
	v_pk_add_f32 v[12:13], v[12:13], v[34:35]
	v_pk_add_f32 v[10:11], v[10:11], v[36:37]
	v_pk_mul_f32 v[34:35], v[40:41], v[56:57] op_sel_hi:[0,1]
	v_pk_mul_f32 v[36:37], v[40:41], v[94:95] op_sel_hi:[0,1]
	v_pk_fma_f32 v[36:37], v[78:79], v[10:11], v[36:37] op_sel_hi:[0,1,1] neg_lo:[0,0,1] neg_hi:[0,0,1]
	v_pk_fma_f32 v[34:35], v[78:79], v[12:13], v[34:35] op_sel_hi:[0,1,1] neg_lo:[0,0,1] neg_hi:[0,0,1]
	v_pk_mul_f32 v[34:35], v[2:3], v[34:35]
	v_pk_mul_f32 v[36:37], v[0:1], v[36:37]
	s_mov_b32 s3, 0x13321000
	v_cvt_pk_bf16_f32 v36, v36, v37
	v_cvt_pk_bf16_f32 v37, v34, v35
	v_add_co_u32_e32 v34, vcc, s3, v28
	v_lshlrev_b32_e32 v82, 16, v66
	v_and_b32_e32 v83, 0xffff0000, v66
	v_lshlrev_b32_e32 v66, 16, v67
	v_and_b32_e32 v67, 0xffff0000, v67
	v_addc_co_u32_e32 v35, vcc, 0, v29, vcc
	v_lshlrev_b32_e32 v80, 16, v70
	v_and_b32_e32 v81, 0xffff0000, v70
	v_lshlrev_b32_e32 v70, 16, v71
	v_and_b32_e32 v71, 0xffff0000, v71
	global_store_dwordx2 v[34:35], v[36:37], off
	v_pk_mul_f32 v[34:35], v[44:45], v[66:67] op_sel_hi:[0,1]
	v_pk_mul_f32 v[36:37], v[44:45], v[82:83] op_sel_hi:[0,1]
	v_lshlrev_b32_e32 v84, 16, v68
	v_and_b32_e32 v85, 0xffff0000, v68
	v_lshlrev_b32_e32 v68, 16, v69
	v_and_b32_e32 v69, 0xffff0000, v69
	v_pk_fma_f32 v[36:37], v[42:43], v[80:81], v[36:37] op_sel_hi:[0,1,1] neg_lo:[0,0,1] neg_hi:[0,0,1]
	v_pk_fma_f32 v[34:35], v[42:43], v[70:71], v[34:35] op_sel_hi:[0,1,1] neg_lo:[0,0,1] neg_hi:[0,0,1]
; DI unsigned pack2(float a, float b) { f32x2 v = {a, b}; hwbf16x2 r = __builtin_convertvector(v, hwbf16x2); return __builtin_bit_cast(unsigned, r); }
; template <bool BF> DI void pool_phase(const Params& p, const void* x, const float* gain) {
;     ...
;             for (int c = 0; c < 4; ++c) {
;                 const int t = tb + 16 * c + i, b = t / S, s = t - b * S;
;                 const int lo = max(s - left, 0), hi = min(s + right + 1, S);
;                 const int ta = b * S + hi - 1, ts = b * S + pl[c];
;                 va[c] = ldx4<BF>(x, (size_t)ta * D + tid * 4); vs[c] = ldx4<BF>(x, (size_t)ts * D + tid * 4); vm[c] = ldx4<BF>(x, (size_t)t * D + tid * 4);
;                 ra[c] = (i > 0 && hi > ph[c]) ? rstd[ta] : 0.f; rs[c] = (i > 0 && lo > pl[c]) ? rstd[ts] : 0.f; rm[c] = rstd[t];
;                 rc[c] = 1.0f / (float)(hi - lo); pl[c] = lo; ph[c] = hi;
;     ...
; #pragma unroll
;             for (int c = 0; c < 4; ++c) {
;                 const int t = tb + 16 * c + i;
;                 sm[c] += va[c] * ra[c] - vs[c] * rs[c];
;                 const f32x4 o = (sm[c] * rc[c] - vm[c] * rm[c]) * gn;
;                 u32x2 w; w[0] = pack2(o[0], o[1]); w[1] = pack2(o[2], o[3]);
;                 *(u32x2*)(H + (size_t)t * D + tid * 4) = w;
;             }
	v_pk_add_f32 v[16:17], v[16:17], v[34:35]
	v_pk_add_f32 v[14:15], v[14:15], v[36:37]
	v_pk_mul_f32 v[34:35], v[46:47], v[68:69] op_sel_hi:[0,1]
	v_pk_mul_f32 v[36:37], v[46:47], v[84:85] op_sel_hi:[0,1]
	v_pk_fma_f32 v[36:37], v[72:73], v[14:15], v[36:37] op_sel_hi:[0,1,1] neg_lo:[0,0,1] neg_hi:[0,0,1]
	v_pk_fma_f32 v[34:35], v[72:73], v[16:17], v[34:35] op_sel_hi:[0,1,1] neg_lo:[0,0,1] neg_hi:[0,0,1]
	v_pk_mul_f32 v[34:35], v[2:3], v[34:35]
	v_pk_mul_f32 v[36:37], v[0:1], v[36:37]
	s_mov_b32 s3, 0x13331000
	v_cvt_pk_bf16_f32 v36, v36, v37
	v_cvt_pk_bf16_f32 v37, v34, v35
	v_add_co_u32_e32 v34, vcc, s3, v28
	v_lshlrev_b32_e32 v74, 16, v60
	v_and_b32_e32 v75, 0xffff0000, v60
	v_lshlrev_b32_e32 v76, 16, v61
	v_and_b32_e32 v77, 0xffff0000, v61
	v_addc_co_u32_e32 v35, vcc, 0, v29, vcc
	v_lshlrev_b32_e32 v62, 16, v63
	v_and_b32_e32 v63, 0xffff0000, v63
	global_store_dwordx2 v[34:35], v[36:37], off
	v_pk_mul_f32 v[34:35], v[50:51], v[76:77] op_sel_hi:[0,1]
	v_pk_mul_f32 v[36:37], v[50:51], v[74:75] op_sel_hi:[0,1]
	v_lshlrev_b32_e32 v60, 16, v64
	v_and_b32_e32 v61, 0xffff0000, v64
	v_lshlrev_b32_e32 v64, 16, v65
	v_and_b32_e32 v65, 0xffff0000, v65
	v_pk_fma_f32 v[36:37], v[48:49], v[58:59], v[36:37] op_sel_hi:[0,1,1] neg_lo:[0,0,1] neg_hi:[0,0,1]
	v_pk_fma_f32 v[34:35], v[48:49], v[62:63], v[34:35] op_sel_hi:[0,1,1] neg_lo:[0,0,1] neg_hi:[0,0,1]
	v_div_fixup_f32 v104, v49, v73, 1.0
	v_pk_add_f32 v[20:21], v[20:21], v[34:35]
	v_pk_add_f32 v[18:19], v[18:19], v[36:37]
	s_waitcnt vmcnt(0) lgkmcnt(0)
	v_pk_mul_f32 v[34:35], v[102:103], v[64:65] op_sel_hi:[0,1]
	v_pk_mul_f32 v[36:37], v[102:103], v[60:61] op_sel_hi:[0,1]
	v_pk_fma_f32 v[36:37], v[104:105], v[18:19], v[36:37] op_sel_hi:[0,1,1] neg_lo:[0,0,1] neg_hi:[0,0,1]
	v_pk_fma_f32 v[34:35], v[104:105], v[20:21], v[34:35] op_sel_hi:[0,1,1] neg_lo:[0,0,1] neg_hi:[0,0,1]
	s_mov_b32 s3, 0x13341000
	s_add_u32 s10, s10, 4
	v_pk_mul_f32 v[34:35], v[2:3], v[34:35]
	v_pk_mul_f32 v[36:37], v[0:1], v[36:37]
	v_add_co_u32_e32 v28, vcc, s3, v28
	s_addc_u32 s11, s11, 0
	s_add_i32 s2, s2, 1
	s_mov_b64 s[12:13], 0x1000
	v_cvt_pk_bf16_f32 v36, v36, v37
	v_cvt_pk_bf16_f32 v37, v34, v35
	v_addc_co_u32_e32 v29, vcc, 0, v29, vcc
	v_lshl_add_u64 v[22:23], v[22:23], 0, s[12:13]
	s_cmp_eq_u32 s2, 15
	v_mov_b32_e32 v89, v45
	v_mov_b32_e32 v88, v41
	v_mov_b32_e32 v73, v31
	v_mov_b32_e32 v41, v33
	v_mov_b32_e32 v67, v39
	v_mov_b32_e32 v87, v43
	v_mov_b32_e32 v90, v47
	global_store_dwordx2 v[28:29], v[36:37], off
	s_cbranch_scc1 .LBB1_2268
.LBB1_2252:
	s_add_i32 s14, s8, s2
	s_add_i32 s3, s14, 1
	s_ashr_i32 s9, s3, 31
	s_lshr_b32 s9, s9, 20
	s_add_i32 s3, s3, s9
	s_and_b32 s3, s3, 0xfffff000
	v_add_u32_e32 v45, s2, v25
	v_subrev_u32_e32 v26, s3, v45
	v_add_u32_e32 v26, 1, v26
	v_mov_b32_e32 v24, v86
	v_min_i32_e32 v86, 0x1000, v26
	v_add3_u32 v32, s3, -1, v86
	v_add_u32_e32 v30, s3, v41
	v_ashrrev_i32_e32 v33, 31, v32
	v_ashrrev_i32_e32 v31, 31, v30
	v_lshlrev_b64 v[28:29], 12, v[32:33]
	v_lshlrev_b64 v[34:35], 12, v[30:31]
	v_lshl_add_u64 v[28:29], v[4:5], 0, v[28:29]
	v_lshl_add_u64 v[34:35], v[4:5], 0, v[34:35]
	v_lshl_add_u64 v[48:49], s[44:45], 0, v[22:23]
	global_load_dwordx2 v[36:37], v[28:29], off
	s_nop 0
	global_load_dwordx2 v[34:35], v[34:35], off
	v_add_co_u32_e32 v28, vcc, 0x4c615000, v48
	v_mov_b32_e32 v26, 0
	s_nop 0
	v_addc_co_u32_e32 v29, vcc, 0, v49, vcc
	global_load_dwordx2 v[28:29], v[28:29], off
	v_cmp_gt_i32_e32 vcc, v86, v24
	v_mov_b32_e32 v24, 0
	s_and_saveexec_b64 s[12:13], vcc
	s_cbranch_execz .LBB1_2254
	v_lshl_add_u64 v[32:33], v[32:33], 2, s[40:41]
	global_load_dword v24, v[32:33], off
.LBB1_2254:
	s_or_b64 exec, exec, s[12:13]
	s_sub_i32 s3, 0, s3
	v_add_u32_e32 v74, s2, v27
	v_add3_u32 v32, v74, s3, 1
	v_max_i32_e32 v33, 0, v32
	v_cmp_gt_i32_e32 vcc, v33, v41
	s_and_saveexec_b64 s[12:13], vcc
	s_cbranch_execz .LBB1_2256
	v_lshl_add_u64 v[30:31], v[30:31], 2, s[40:41]
	global_load_dword v26, v[30:31], off
; template <bool BF> DI void pool_phase(const Params& p, const void* x, const float* gain) {
;     ...
;             for (int c = 0; c < 4; ++c) {
;                 const int t = tb + 16 * c + i, b = t / S, s = t - b * S;
;                 const int lo = max(s - left, 0), hi = min(s + right + 1, S);
;                 const int ta = b * S + hi - 1, ts = b * S + pl[c];
;                 va[c] = ldx4<BF>(x, (size_t)ta * D + tid * 4); vs[c] = ldx4<BF>(x, (size_t)ts * D + tid * 4); vm[c] = ldx4<BF>(x, (size_t)t * D + tid * 4);
;                 ra[c] = (i > 0 && hi > ph[c]) ? rstd[ta] : 0.f; rs[c] = (i > 0 && lo > pl[c]) ? rstd[ts] : 0.f; rm[c] = rstd[t];
;                 rc[c] = 1.0f / (float)(hi - lo); pl[c] = lo; ph[c] = hi;
.LBB1_2256:
	s_or_b64 exec, exec, s[12:13]
	s_add_u32 s9, s6, s10
	s_addc_u32 s3, s7, s11
	s_add_i32 s12, s14, 17
	s_ashr_i32 s13, s12, 31
	v_mov_b32_e32 v30, s9
	s_lshr_b32 s13, s13, 20
	v_add_co_u32_e32 v30, vcc, 0x13300000, v30
	v_mov_b32_e32 v31, s3
	s_add_i32 s12, s12, s13
	v_addc_co_u32_e32 v31, vcc, 0, v31, vcc
	s_and_b32 s15, s12, 0xfffff000
	global_load_dword v30, v[30:31], off offset:4
	v_subrev_u32_e32 v31, s15, v45
	v_add_u32_e32 v31, 17, v31
	v_min_i32_e32 v31, 0x1000, v31
	v_add3_u32 v42, s15, -1, v31
	v_add_u32_e32 v40, s15, v67
	v_ashrrev_i32_e32 v43, 31, v42
	v_lshlrev_b64 v[38:39], 12, v[42:43]
	v_ashrrev_i32_e32 v41, 31, v40
	v_lshl_add_u64 v[38:39], v[4:5], 0, v[38:39]
	v_lshlrev_b64 v[46:47], 12, v[40:41]
	v_lshl_add_u64 v[46:47], v[4:5], 0, v[46:47]
	global_load_dwordx2 v[54:55], v[38:39], off
	global_load_dwordx2 v[52:53], v[46:47], off
	v_add_co_u32_e32 v38, vcc, 0x4c625000, v48
	v_mov_b32_e32 v32, 0
	s_nop 0
	v_addc_co_u32_e32 v39, vcc, 0, v49, vcc
	global_load_dwordx2 v[56:57], v[38:39], off
	v_cmp_gt_i32_e32 vcc, v31, v73
	v_mov_b32_e32 v38, 0
	s_and_saveexec_b64 s[12:13], vcc
	s_cbranch_execz .LBB1_2258
	v_lshl_add_u64 v[42:43], v[42:43], 2, s[40:41]
	global_load_dword v32, v[42:43], off
.LBB1_2258:
	s_or_b64 exec, exec, s[12:13]
	s_sub_i32 s12, 0, s15
	v_add3_u32 v39, v74, s12, 17
	v_max_i32_e32 v39, 0, v39
	v_cmp_gt_i32_e32 vcc, v39, v67
	s_and_saveexec_b64 s[12:13], vcc
	s_cbranch_execz .LBB1_2260
	v_lshl_add_u64 v[40:41], v[40:41], 2, s[40:41]
	global_load_dword v38, v[40:41], off
.LBB1_2260:
	s_or_b64 exec, exec, s[12:13]
	s_add_i32 s12, s14, 33
	s_ashr_i32 s13, s12, 31
	v_mov_b32_e32 v40, s9
	s_lshr_b32 s13, s13, 20
	v_add_co_u32_e32 v40, vcc, 0x13300000, v40
	v_mov_b32_e32 v41, s3
	s_add_i32 s12, s12, s13
	v_addc_co_u32_e32 v41, vcc, 0, v41, vcc
	s_and_b32 s15, s12, 0xfffff000
	global_load_dword v40, v[40:41], off offset:68
	v_subrev_u32_e32 v41, s15, v45
	v_add_u32_e32 v41, 33, v41
	v_min_i32_e32 v41, 0x1000, v41
	v_add3_u32 v50, s15, -1, v41
	v_add_u32_e32 v46, s15, v87
	v_ashrrev_i32_e32 v51, 31, v50
	v_lshlrev_b64 v[42:43], 12, v[50:51]
	v_ashrrev_i32_e32 v47, 31, v46
	v_lshl_add_u64 v[42:43], v[4:5], 0, v[42:43]
	v_lshlrev_b64 v[58:59], 12, v[46:47]
	v_lshl_add_u64 v[58:59], v[4:5], 0, v[58:59]
	global_load_dwordx2 v[70:71], v[42:43], off
	global_load_dwordx2 v[66:67], v[58:59], off
	v_add_co_u32_e32 v42, vcc, 0x4c635000, v48
	v_mov_b32_e32 v44, 0
	s_nop 0
	v_addc_co_u32_e32 v43, vcc, 0, v49, vcc
	global_load_dwordx2 v[68:69], v[42:43], off
	v_cmp_gt_i32_e32 vcc, v41, v88
	v_mov_b32_e32 v42, 0
	s_and_saveexec_b64 s[12:13], vcc
	s_cbranch_execz .LBB1_2262
	v_lshl_add_u64 v[42:43], v[50:51], 2, s[40:41]
	global_load_dword v42, v[42:43], off
.LBB1_2262:
	s_or_b64 exec, exec, s[12:13]
	s_sub_i32 s12, 0, s15
	v_add3_u32 v43, v74, s12, 33
	v_max_i32_e32 v43, 0, v43
	v_cmp_gt_i32_e32 vcc, v43, v87
	s_and_saveexec_b64 s[12:13], vcc
	s_cbranch_execz .LBB1_2264
	v_lshl_add_u64 v[46:47], v[46:47], 2, s[40:41]
	global_load_dword v44, v[46:47], off
.LBB1_2264:
	s_or_b64 exec, exec, s[12:13]
	s_add_i32 s12, s14, 49
	s_ashr_i32 s13, s12, 31
	s_lshr_b32 s13, s13, 20
	s_add_i32 s12, s12, s13
	s_and_b32 s14, s12, 0xfffff000
	v_subrev_u32_e32 v45, s14, v45
	v_add_u32_e32 v45, 49, v45
	v_mov_b32_e32 v46, s9
	v_min_i32_e32 v45, 0x1000, v45
	v_add_co_u32_e32 v46, vcc, 0x13300000, v46
	v_mov_b32_e32 v47, s3
	v_add3_u32 v72, s14, -1, v45
	v_add_u32_e32 v58, s14, v90
	v_addc_co_u32_e32 v47, vcc, 0, v47, vcc
	v_ashrrev_i32_e32 v73, 31, v72
	v_ashrrev_i32_e32 v59, 31, v58
	v_lshlrev_b64 v[50:51], 12, v[72:73]
	v_lshlrev_b64 v[60:61], 12, v[58:59]
	v_add_co_u32_e32 v48, vcc, 0x4c645000, v48
	v_lshl_add_u64 v[50:51], v[4:5], 0, v[50:51]
	v_lshl_add_u64 v[60:61], v[4:5], 0, v[60:61]
	v_addc_co_u32_e32 v49, vcc, 0, v49, vcc
	global_load_dword v46, v[46:47], off offset:132
	s_nop 0
	global_load_dwordx2 v[62:63], v[50:51], off
	s_nop 0
	global_load_dwordx2 v[60:61], v[60:61], off
	v_cmp_gt_i32_e32 vcc, v45, v89
	global_load_dwordx2 v[64:65], v[48:49], off
	v_mov_b32_e32 v50, 0
	v_mov_b32_e32 v48, 0
	s_and_saveexec_b64 s[12:13], vcc
	s_cbranch_execz .LBB1_2266
	v_lshl_add_u64 v[48:49], v[72:73], 2, s[40:41]
	global_load_dword v48, v[48:49], off
.LBB1_2266:
	s_or_b64 exec, exec, s[12:13]
	s_sub_i32 s12, 0, s14
	v_add3_u32 v47, v74, s12, 49
	v_max_i32_e32 v47, 0, v47
	v_cmp_gt_i32_e32 vcc, v47, v90
	s_and_saveexec_b64 s[12:13], vcc
	s_cbranch_execz .LBB1_2251
	v_lshl_add_u64 v[50:51], v[58:59], 2, s[40:41]
	global_load_dword v50, v[50:51], off
	s_branch .LBB1_2251

; #define PG8_STAGE(bufoff, gbase, voff) do { _Pragma("unroll") for (int _i = 0; _i < 2; ++_i) \
;         __builtin_amdgcn_global_load_lds((const unsigned*)((const char*)(gbase) + (voff)[_i]), (LAS unsigned*)(lds + (bufoff) + ldsw + _i * 8192), 16, 0, 0); } while (0)
; #define PG8_LDA(dst, b, h) do { _Pragma("unroll") for (int m = 0; m < 4; ++m) _Pragma("unroll") for (int k = 0; k < 2; ++k) dst[m][k] = *(const LAS bf16x8*)(lds + PG8_SA(b, h) + aoff + m * 2048 + k * 1024); } while (0)
; #define PG8_LDB(dst, b, h) do { _Pragma("unroll") for (int n = 0; n < 2; ++n) _Pragma("unroll") for (int k = 0; k < 2; ++k) dst[n][k] = *(const LAS bf16x8*)(lds + PG8_SB(b, h) + boff + n * 2048 + k * 1024); } while (0)
; #define PG8_MMA(ai, bj, At, Bt) do { __builtin_amdgcn_s_setprio(1); _Pragma("unroll") for (int m = 0; m < 4; ++m) _Pragma("unroll") for (int n = 0; n < 2; ++n) _Pragma("unroll") for (int k = 0; k < 2; ++k) \
;         acc[ai][bj][m][n] = __builtin_amdgcn_mfma_f32_16x16x32_bf16(Bt[n][k], At[m][k], acc[ai][bj][m][n], 0, 0, 0); __builtin_amdgcn_s_setprio(0); } while (0)
; #define PG8_WAIT_V(n) asm volatile("s_waitcnt vmcnt(" #n ")" ::: "memory")
; #define PG8_WAIT_L(n) asm volatile("s_waitcnt lgkmcnt(" #n ")" ::: "memory")
; #define PG8_BAR __builtin_amdgcn_s_barrier()
; #define PG8_SCHED __builtin_amdgcn_sched_barrier(0)
; template <class Map, class Epi>
; DI void gemm_phase(LAS unsigned char* lds, const Map& MP, const Epi& E, const int nM, const int nN, const int K, const int lda, const int ldb) {
;     ...
;             PG8_LDB(B0, 0, 0); PG8_SCHED; PG8_LDA(At, 0, 0); PG8_STAGE(PG8_SA(1, 1), a1 + hstepA, voffA);
;             PG8_WAIT_L(8); PG8_BAR; PG8_WAIT_L(0); PG8_MMA(0, 0, At, B0); PG8_BAR; PG8_SCHED;
;             PG8_LDB(B1, 0, 1); PG8_STAGE(PG8_SB(0, 0), b2, voffB);
;             PG8_BAR; PG8_WAIT_L(0); PG8_MMA(0, 1, At, B1); PG8_BAR;
;             PG8_LDA(At, 0, 1); PG8_STAGE(PG8_SA(0, 0), a2, voffA);
;             PG8_BAR; PG8_WAIT_L(0); PG8_MMA(1, 0, At, B0); PG8_BAR; PG8_SCHED;
;             PG8_STAGE(PG8_SB(0, 1), b2 + hstepB, voffB);
;             PG8_WAIT_V(6); PG8_BAR; PG8_MMA(1, 1, At, B1); PG8_BAR;
.LBB1_2339:
	ds_read_b128 v[40:43], v165
	ds_read_b128 v[44:47], v165 offset:1024
	ds_read_b128 v[56:59], v165 offset:2048
	ds_read_b128 v[60:63], v165 offset:3072
	s_add_u32 s12, s10, 0xfff80080
	s_addc_u32 s13, s11, -1
	s_cmp_eq_u32 s3, 4
	s_cselect_b32 s15, s38, s13
	s_cselect_b32 s14, s39, s12
	s_cselect_b32 s13, s48, s56
	s_cselect_b32 s12, s49, s53
	v_lshl_add_u64 v[160:161], s[10:11], 0, v[154:155]
	s_add_i32 m0, s9, 0xc000
	ds_read_b128 v[168:171], v166
	ds_read_b128 v[172:175], v166 offset:1024
	ds_read_b128 v[176:179], v166 offset:2048
	ds_read_b128 v[180:183], v166 offset:3072
	ds_read_b128 v[184:187], v166 offset:4096
	ds_read_b128 v[188:191], v166 offset:5120
	ds_read_b128 v[192:195], v166 offset:6144
	ds_read_b128 v[198:201], v166 offset:7168
	global_load_lds_dwordx4 v[160:161], off
	v_lshl_add_u64 v[160:161], s[10:11], 0, v[152:153]
	s_add_i32 m0, s9, 0xe000
	s_nop 0
	global_load_lds_dwordx4 v[160:161], off
	s_waitcnt lgkmcnt(8)
	s_barrier
	s_setprio 1
	s_waitcnt lgkmcnt(7)
	v_mfma_f32_16x16x32_bf16 v[140:143], v[40:43], v[168:171], v[140:143]
	v_mfma_f32_16x16x32_bf16 v[136:139], v[56:59], v[168:171], v[136:139]
	s_waitcnt lgkmcnt(5)
	v_mfma_f32_16x16x32_bf16 v[124:127], v[40:43], v[176:179], v[124:127]
	v_mfma_f32_16x16x32_bf16 v[120:123], v[56:59], v[176:179], v[120:123]
	s_waitcnt lgkmcnt(3)
	v_mfma_f32_16x16x32_bf16 v[108:111], v[40:43], v[184:187], v[108:111]
	v_mfma_f32_16x16x32_bf16 v[104:107], v[56:59], v[184:187], v[104:107]
	s_waitcnt lgkmcnt(1)
	v_mfma_f32_16x16x32_bf16 v[92:95], v[40:43], v[192:195], v[92:95]
	v_mfma_f32_16x16x32_bf16 v[88:91], v[56:59], v[192:195], v[88:91]
	v_mfma_f32_16x16x32_bf16 v[140:143], v[44:47], v[172:175], v[140:143]
	v_mfma_f32_16x16x32_bf16 v[136:139], v[60:63], v[172:175], v[136:139]
	v_mfma_f32_16x16x32_bf16 v[124:127], v[44:47], v[180:183], v[124:127]
	v_mfma_f32_16x16x32_bf16 v[120:123], v[60:63], v[180:183], v[120:123]
	v_mfma_f32_16x16x32_bf16 v[108:111], v[44:47], v[188:191], v[108:111]
	v_mfma_f32_16x16x32_bf16 v[104:107], v[60:63], v[188:191], v[104:107]
	s_waitcnt lgkmcnt(0)
	v_mfma_f32_16x16x32_bf16 v[92:95], v[44:47], v[198:201], v[92:95]
	v_mfma_f32_16x16x32_bf16 v[88:91], v[60:63], v[198:201], v[88:91]
	s_setprio 0
	s_barrier
	s_add_i32 s57, s35, s22
	v_lshl_add_u64 v[160:161], s[12:13], 0, v[148:149]
	s_mov_b32 m0, s57
	ds_read_b128 v[202:205], v167
	ds_read_b128 v[206:209], v167 offset:1024
	ds_read_b128 v[210:213], v167 offset:2048
	ds_read_b128 v[214:217], v167 offset:3072
	global_load_lds_dwordx4 v[160:161], off
	v_lshl_add_u64 v[218:219], s[12:13], 0, v[144:145]
	s_add_i32 m0, s57, 0x2000
	s_nop 0
	global_load_lds_dwordx4 v[218:219], off
	s_barrier
	s_setprio 1
	s_waitcnt lgkmcnt(3)
	v_mfma_f32_16x16x32_bf16 v[132:135], v[202:205], v[168:171], v[132:135]
	s_waitcnt lgkmcnt(1)
	v_mfma_f32_16x16x32_bf16 v[128:131], v[210:213], v[168:171], v[128:131]
	v_mfma_f32_16x16x32_bf16 v[116:119], v[202:205], v[176:179], v[116:119]
	v_mfma_f32_16x16x32_bf16 v[112:115], v[210:213], v[176:179], v[112:115]
	v_mfma_f32_16x16x32_bf16 v[100:103], v[202:205], v[184:187], v[100:103]
	v_mfma_f32_16x16x32_bf16 v[96:99], v[210:213], v[184:187], v[96:99]
	v_mfma_f32_16x16x32_bf16 v[84:87], v[202:205], v[192:195], v[84:87]
	v_mfma_f32_16x16x32_bf16 v[80:83], v[210:213], v[192:195], v[80:83]
	v_mfma_f32_16x16x32_bf16 v[132:135], v[206:209], v[172:175], v[132:135]
	s_waitcnt lgkmcnt(0)
	v_mfma_f32_16x16x32_bf16 v[128:131], v[214:217], v[172:175], v[128:131]
	v_mfma_f32_16x16x32_bf16 v[116:119], v[206:209], v[180:183], v[116:119]
	v_mfma_f32_16x16x32_bf16 v[112:115], v[214:217], v[180:183], v[112:115]
	v_mfma_f32_16x16x32_bf16 v[100:103], v[206:209], v[188:191], v[100:103]
	v_mfma_f32_16x16x32_bf16 v[96:99], v[214:217], v[188:191], v[96:99]
	v_mfma_f32_16x16x32_bf16 v[84:87], v[206:209], v[198:201], v[84:87]
	v_mfma_f32_16x16x32_bf16 v[80:83], v[214:217], v[198:201], v[80:83]
	s_setprio 0
	s_mov_b32 m0, s9
	v_lshl_add_u64 v[220:221], s[14:15], 0, v[150:151]
	s_barrier
	ds_read_b128 v[168:171], v166 offset:16384
	ds_read_b128 v[172:175], v166 offset:17408
	ds_read_b128 v[176:179], v166 offset:18432
	ds_read_b128 v[180:183], v166 offset:19456
	ds_read_b128 v[184:187], v166 offset:20480
	ds_read_b128 v[188:191], v166 offset:21504
	ds_read_b128 v[192:195], v166 offset:22528
	ds_read_b128 v[198:201], v166 offset:23552
	global_load_lds_dwordx4 v[220:221], off
	v_lshl_add_u64 v[222:223], s[14:15], 0, v[146:147]
	s_mov_b32 m0, s24
	s_nop 0
	global_load_lds_dwordx4 v[222:223], off
	s_barrier
	s_setprio 1
	s_waitcnt lgkmcnt(7)
	v_mfma_f32_16x16x32_bf16 v[76:79], v[40:43], v[168:171], v[76:79]
	v_mfma_f32_16x16x32_bf16 v[72:75], v[56:59], v[168:171], v[72:75]
	s_waitcnt lgkmcnt(5)
	v_mfma_f32_16x16x32_bf16 v[52:55], v[40:43], v[176:179], v[52:55]
	v_mfma_f32_16x16x32_bf16 v[48:51], v[56:59], v[176:179], v[48:51]
	s_waitcnt lgkmcnt(3)
	v_mfma_f32_16x16x32_bf16 v[28:31], v[40:43], v[184:187], v[28:31]
	v_mfma_f32_16x16x32_bf16 v[24:27], v[56:59], v[184:187], v[24:27]
	s_waitcnt lgkmcnt(1)
	v_mfma_f32_16x16x32_bf16 v[12:15], v[40:43], v[192:195], v[12:15]
	v_mfma_f32_16x16x32_bf16 v[8:11], v[56:59], v[192:195], v[8:11]
	v_mfma_f32_16x16x32_bf16 v[76:79], v[44:47], v[172:175], v[76:79]
	v_mfma_f32_16x16x32_bf16 v[72:75], v[60:63], v[172:175], v[72:75]
	v_mfma_f32_16x16x32_bf16 v[52:55], v[44:47], v[180:183], v[52:55]
	v_mfma_f32_16x16x32_bf16 v[48:51], v[60:63], v[180:183], v[48:51]
	v_mfma_f32_16x16x32_bf16 v[28:31], v[44:47], v[188:191], v[28:31]
	v_mfma_f32_16x16x32_bf16 v[24:27], v[60:63], v[188:191], v[24:27]
	s_waitcnt lgkmcnt(0)
	v_mfma_f32_16x16x32_bf16 v[12:15], v[44:47], v[198:201], v[12:15]
	v_mfma_f32_16x16x32_bf16 v[8:11], v[60:63], v[198:201], v[8:11]
	s_setprio 0
	s_barrier
; #define PG8_STAGE(bufoff, gbase, voff) do { _Pragma("unroll") for (int _i = 0; _i < 2; ++_i) \
;         __builtin_amdgcn_global_load_lds((const unsigned*)((const char*)(gbase) + (voff)[_i]), (LAS unsigned*)(lds + (bufoff) + ldsw + _i * 8192), 16, 0, 0); } while (0)
; #define PG8_LDA(dst, b, h) do { _Pragma("unroll") for (int m = 0; m < 4; ++m) _Pragma("unroll") for (int k = 0; k < 2; ++k) dst[m][k] = *(const LAS bf16x8*)(lds + PG8_SA(b, h) + aoff + m * 2048 + k * 1024); } while (0)
; #define PG8_LDB(dst, b, h) do { _Pragma("unroll") for (int n = 0; n < 2; ++n) _Pragma("unroll") for (int k = 0; k < 2; ++k) dst[n][k] = *(const LAS bf16x8*)(lds + PG8_SB(b, h) + boff + n * 2048 + k * 1024); } while (0)
; #define PG8_MMA(ai, bj, At, Bt) do { __builtin_amdgcn_s_setprio(1); _Pragma("unroll") for (int m = 0; m < 4; ++m) _Pragma("unroll") for (int n = 0; n < 2; ++n) _Pragma("unroll") for (int k = 0; k < 2; ++k) \
;         acc[ai][bj][m][n] = __builtin_amdgcn_mfma_f32_16x16x32_bf16(Bt[n][k], At[m][k], acc[ai][bj][m][n], 0, 0, 0); __builtin_amdgcn_s_setprio(0); } while (0)
; #define PG8_WAIT_V(n) asm volatile("s_waitcnt vmcnt(" #n ")" ::: "memory")
; #define PG8_WAIT_L(n) asm volatile("s_waitcnt lgkmcnt(" #n ")" ::: "memory")
; #define PG8_BAR __builtin_amdgcn_s_barrier()
; #define PG8_SCHED __builtin_amdgcn_sched_barrier(0)
; template <class Map, class Epi>
; DI void gemm_phase(LAS unsigned char* lds, const Map& MP, const Epi& E, const int nM, const int nN, const int K, const int lda, const int ldb) {
;     ...
;             PG8_BAR; PG8_WAIT_L(0); PG8_MMA(1, 0, At, B0); PG8_BAR; PG8_SCHED;
;             PG8_STAGE(PG8_SB(0, 1), b2 + hstepB, voffB);
;             PG8_WAIT_V(6); PG8_BAR; PG8_MMA(1, 1, At, B1); PG8_BAR;
;             PG8_LDB(B0, 1, 0); PG8_SCHED; PG8_LDA(At, 1, 0); PG8_STAGE(PG8_SA(0, 1), a2 + hstepA, voffA);
;             PG8_WAIT_L(8); PG8_BAR; PG8_WAIT_L(0); PG8_MMA(0, 0, At, B0); PG8_BAR; PG8_SCHED;
;             PG8_LDB(B1, 1, 1); PG8_STAGE(PG8_SB(1, 0), b3, voffB);
;             PG8_BAR; PG8_WAIT_L(0); PG8_MMA(0, 1, At, B1); PG8_BAR;
	s_add_u32 s58, s12, 0x20000
	s_addc_u32 s59, s13, 0
	s_add_i32 s57, s36, s22
	v_lshl_add_u64 v[40:41], s[58:59], 0, v[148:149]
	s_mov_b32 m0, s57
	s_nop 0
	global_load_lds_dwordx4 v[40:41], off
	v_lshl_add_u64 v[40:41], s[58:59], 0, v[144:145]
	s_add_i32 m0, s57, 0x2000
	s_nop 0
	global_load_lds_dwordx4 v[40:41], off
	s_waitcnt vmcnt(6)
	s_barrier
	s_setprio 1
	v_mfma_f32_16x16x32_bf16 v[36:39], v[202:205], v[176:179], v[36:39]
	v_mfma_f32_16x16x32_bf16 v[32:35], v[210:213], v[176:179], v[32:35]
	v_mfma_f32_16x16x32_bf16 v[20:23], v[202:205], v[184:187], v[20:23]
	v_mfma_f32_16x16x32_bf16 v[16:19], v[210:213], v[184:187], v[16:19]
	v_mfma_f32_16x16x32_bf16 v[4:7], v[202:205], v[192:195], v[4:7]
	v_mfma_f32_16x16x32_bf16 v[0:3], v[210:213], v[192:195], v[0:3]
	v_mfma_f32_16x16x32_bf16 v[40:43], v[202:205], v[168:171], v[68:71]
	v_mfma_f32_16x16x32_bf16 v[44:47], v[210:213], v[168:171], v[64:67]
	v_mfma_f32_16x16x32_bf16 v[36:39], v[206:209], v[180:183], v[36:39]
	v_mfma_f32_16x16x32_bf16 v[32:35], v[214:217], v[180:183], v[32:35]
	v_mfma_f32_16x16x32_bf16 v[20:23], v[206:209], v[188:191], v[20:23]
	v_mfma_f32_16x16x32_bf16 v[16:19], v[214:217], v[188:191], v[16:19]
	v_mfma_f32_16x16x32_bf16 v[4:7], v[206:209], v[198:201], v[4:7]
	v_mfma_f32_16x16x32_bf16 v[0:3], v[214:217], v[198:201], v[0:3]
	v_mfma_f32_16x16x32_bf16 v[40:43], v[206:209], v[172:175], v[40:43]
	v_mfma_f32_16x16x32_bf16 v[44:47], v[214:217], v[172:175], v[44:47]
	s_setprio 0
	s_add_i32 s57, 0, 0x18000
	v_add_u32_e32 v68, s57, v164
	s_barrier
	ds_read_b128 v[56:59], v68
	ds_read_b128 v[60:63], v68 offset:1024
	ds_read_b128 v[64:67], v68 offset:2048
	ds_read_b128 v[68:71], v68 offset:3072
	s_add_u32 s14, s14, 0x80000
	s_addc_u32 s15, s15, 0
	s_mov_b32 m0, s25
	v_lshl_add_u64 v[202:203], s[14:15], 0, v[150:151]
	ds_read_b128 v[168:171], v166 offset:32768
	ds_read_b128 v[172:175], v166 offset:33792
	ds_read_b128 v[176:179], v166 offset:34816
	ds_read_b128 v[180:183], v166 offset:35840
	ds_read_b128 v[184:187], v166 offset:36864
	ds_read_b128 v[188:191], v166 offset:37888
	ds_read_b128 v[192:195], v166 offset:38912
	ds_read_b128 v[198:201], v166 offset:39936
	global_load_lds_dwordx4 v[202:203], off
	v_lshl_add_u64 v[202:203], s[14:15], 0, v[146:147]
	s_mov_b32 m0, s26
	s_nop 0
	global_load_lds_dwordx4 v[202:203], off
	s_waitcnt lgkmcnt(8)
	s_barrier
	s_setprio 1
	s_waitcnt lgkmcnt(7)
	v_mfma_f32_16x16x32_bf16 v[140:143], v[56:59], v[168:171], v[140:143]
	v_mfma_f32_16x16x32_bf16 v[136:139], v[64:67], v[168:171], v[136:139]
	s_waitcnt lgkmcnt(5)
	v_mfma_f32_16x16x32_bf16 v[124:127], v[56:59], v[176:179], v[124:127]
	v_mfma_f32_16x16x32_bf16 v[120:123], v[64:67], v[176:179], v[120:123]
	s_waitcnt lgkmcnt(3)
	v_mfma_f32_16x16x32_bf16 v[108:111], v[56:59], v[184:187], v[108:111]
	v_mfma_f32_16x16x32_bf16 v[104:107], v[64:67], v[184:187], v[104:107]
	s_waitcnt lgkmcnt(1)
	v_mfma_f32_16x16x32_bf16 v[92:95], v[56:59], v[192:195], v[92:95]
	v_mfma_f32_16x16x32_bf16 v[88:91], v[64:67], v[192:195], v[88:91]
	v_mfma_f32_16x16x32_bf16 v[140:143], v[60:63], v[172:175], v[140:143]
	v_mfma_f32_16x16x32_bf16 v[136:139], v[68:71], v[172:175], v[136:139]
	v_mfma_f32_16x16x32_bf16 v[124:127], v[60:63], v[180:183], v[124:127]
	v_mfma_f32_16x16x32_bf16 v[120:123], v[68:71], v[180:183], v[120:123]
	v_mfma_f32_16x16x32_bf16 v[108:111], v[60:63], v[188:191], v[108:111]
	v_mfma_f32_16x16x32_bf16 v[104:107], v[68:71], v[188:191], v[104:107]
	s_waitcnt lgkmcnt(0)
	v_mfma_f32_16x16x32_bf16 v[92:95], v[60:63], v[198:201], v[92:95]
	v_mfma_f32_16x16x32_bf16 v[88:91], v[68:71], v[198:201], v[88:91]
	s_setprio 0
	s_barrier
	s_add_i32 s14, 0, 0x1c000
	s_add_i32 s15, s57, s22
	v_add_u32_e32 v196, s14, v164
	v_lshl_add_u64 v[160:161], v[160:161], 0, s[46:47]
	s_mov_b32 m0, s15
	ds_read_b128 v[202:205], v196
	ds_read_b128 v[206:209], v196 offset:1024
	ds_read_b128 v[210:213], v196 offset:2048
	ds_read_b128 v[214:217], v196 offset:3072
	global_load_lds_dwordx4 v[160:161], off
	v_lshl_add_u64 v[160:161], v[218:219], 0, s[46:47]
	s_add_i32 m0, s15, 0x2000
	s_nop 0
	global_load_lds_dwordx4 v[160:161], off
	s_barrier
	s_setprio 1
	s_waitcnt lgkmcnt(3)
	v_mfma_f32_16x16x32_bf16 v[132:135], v[202:205], v[168:171], v[132:135]
	s_waitcnt lgkmcnt(1)
	v_mfma_f32_16x16x32_bf16 v[128:131], v[210:213], v[168:171], v[128:131]
	v_mfma_f32_16x16x32_bf16 v[116:119], v[202:205], v[176:179], v[116:119]
	v_mfma_f32_16x16x32_bf16 v[112:115], v[210:213], v[176:179], v[112:115]
	v_mfma_f32_16x16x32_bf16 v[100:103], v[202:205], v[184:187], v[100:103]
	v_mfma_f32_16x16x32_bf16 v[96:99], v[210:213], v[184:187], v[96:99]
	v_mfma_f32_16x16x32_bf16 v[84:87], v[202:205], v[192:195], v[84:87]
	v_mfma_f32_16x16x32_bf16 v[80:83], v[210:213], v[192:195], v[80:83]
	v_mfma_f32_16x16x32_bf16 v[132:135], v[206:209], v[172:175], v[132:135]
	s_waitcnt lgkmcnt(0)
	v_mfma_f32_16x16x32_bf16 v[128:131], v[214:217], v[172:175], v[128:131]
	v_mfma_f32_16x16x32_bf16 v[116:119], v[206:209], v[180:183], v[116:119]
	v_mfma_f32_16x16x32_bf16 v[112:115], v[214:217], v[180:183], v[112:115]
	v_mfma_f32_16x16x32_bf16 v[100:103], v[206:209], v[188:191], v[100:103]
	v_mfma_f32_16x16x32_bf16 v[96:99], v[214:217], v[188:191], v[96:99]
	v_mfma_f32_16x16x32_bf16 v[84:87], v[206:209], v[198:201], v[84:87]
	v_mfma_f32_16x16x32_bf16 v[80:83], v[214:217], v[198:201], v[80:83]
	s_setprio 0
	s_mov_b32 m0, s30
	v_lshl_add_u64 v[160:161], v[220:221], 0, s[46:47]
	s_barrier
; DI unsigned pack2(float a, float b) { f32x2 v = {a, b}; hwbf16x2 r = __builtin_convertvector(v, hwbf16x2); return __builtin_bit_cast(unsigned, r); }
; DI float bflo(unsigned w) { return __uint_as_float(w << 16); }
; DI float bfhi(unsigned w) { return __uint_as_float(w & 0xffff0000u); }
; #define PG8_WAIT_V(n) asm volatile("s_waitcnt vmcnt(" #n ")" ::: "memory")
; #define PG8_WAIT_L(n) asm volatile("s_waitcnt lgkmcnt(" #n ")" ::: "memory")
; #define PG8_BAR __builtin_amdgcn_s_barrier()
;     DI void operator()(const f32x4 (&acc)[2][2][4][2], const Unit& u, int wr, int wc, int fr, int fq) const {
;         const int row0 = u.pm * BM + wr * 64 + fr, col0 = u.pn * BM + wc * 32 + 8 * fq;
;         f32x4 sc[2][2];
; #pragma unroll
;         for (int bj = 0; bj < 2; ++bj)
; #pragma unroll
;             for (int n = 0; n < 2; ++n) sc[bj][n] = scale ? *(const f32x4*)(scale + col0 + bj * HALF + 4 * n) : (f32x4){1.f, 1.f, 1.f, 1.f};
; #pragma unroll
;         for (int ai = 0; ai < 2; ++ai)
; #pragma unroll
;             for (int m = 0; m < 4; ++m) { const size_t ro = (size_t)(row0 + ai * HALF + m * 16) * D + col0;
; #pragma unroll
;                 for (int bj = 0; bj < 2; ++bj) {
;                     f32x4 x0, x1;
;                     if constexpr (IB) { const u32x4 w = *(const u32x4*)((const bf16_t*)Xin + ro + bj * HALF);
;                         x0 = (f32x4){bflo(w[0]), bfhi(w[0]), bflo(w[1]), bfhi(w[1])}; x1 = (f32x4){bflo(w[2]), bfhi(w[2]), bflo(w[3]), bfhi(w[3])}; }
;                     else { x0 = *(const f32x4*)((const float*)Xin + ro + bj * HALF); x1 = *(const f32x4*)((const float*)Xin + ro + bj * HALF + 4); }
;                     x0 += acc[ai][bj][m][0] * sc[bj][0]; x1 += acc[ai][bj][m][1] * sc[bj][1];
;                     if constexpr (OB) { u32x4 o; o[0] = pack2(x0[0], x0[1]); o[1] = pack2(x0[2], x0[3]); o[2] = pack2(x1[0], x1[1]); o[3] = pack2(x1[2], x1[3]);
;                         *(u32x4*)((bf16_t*)Xout + ro + bj * HALF) = o; }
; template <class Map, class Epi>
; DI void gemm_phase(LAS unsigned char* lds, const Map& MP, const Epi& E, const int nM, const int nN, const int K, const int lda, const int ldb) {
;     ...
;             PG8_BAR; PG8_WAIT_L(0); PG8_MMA(1, 0, At, B0); PG8_BAR; PG8_SCHED;
;             PG8_STAGE(PG8_SB(1, 1), b3 + hstepB, voffB);
;             PG8_WAIT_V(6); PG8_BAR; PG8_MMA(1, 1, At, B1); PG8_BAR;
	ds_read_b128 v[168:171], v166 offset:49152
	ds_read_b128 v[172:175], v166 offset:50176
	ds_read_b128 v[176:179], v166 offset:51200
	ds_read_b128 v[180:183], v166 offset:52224
	ds_read_b128 v[184:187], v166 offset:53248
	ds_read_b128 v[188:191], v166 offset:54272
	ds_read_b128 v[192:195], v166 offset:55296
	ds_read_b128 v[198:201], v166 offset:56320
	global_load_lds_dwordx4 v[160:161], off
	v_lshl_add_u64 v[160:161], v[222:223], 0, s[46:47]
	s_mov_b32 m0, s31
	s_nop 0
	global_load_lds_dwordx4 v[160:161], off
	s_barrier
	s_setprio 1
	s_waitcnt lgkmcnt(7)
	v_mfma_f32_16x16x32_bf16 v[76:79], v[56:59], v[168:171], v[76:79]
	v_mfma_f32_16x16x32_bf16 v[72:75], v[64:67], v[168:171], v[72:75]
	s_waitcnt lgkmcnt(5)
	v_mfma_f32_16x16x32_bf16 v[52:55], v[56:59], v[176:179], v[52:55]
	v_mfma_f32_16x16x32_bf16 v[48:51], v[64:67], v[176:179], v[48:51]
	s_waitcnt lgkmcnt(3)
	v_mfma_f32_16x16x32_bf16 v[28:31], v[56:59], v[184:187], v[28:31]
	v_mfma_f32_16x16x32_bf16 v[24:27], v[64:67], v[184:187], v[24:27]
	s_waitcnt lgkmcnt(1)
	v_mfma_f32_16x16x32_bf16 v[12:15], v[56:59], v[192:195], v[12:15]
	v_mfma_f32_16x16x32_bf16 v[8:11], v[64:67], v[192:195], v[8:11]
	v_mfma_f32_16x16x32_bf16 v[76:79], v[60:63], v[172:175], v[76:79]
	v_mfma_f32_16x16x32_bf16 v[72:75], v[68:71], v[172:175], v[72:75]
	v_mfma_f32_16x16x32_bf16 v[52:55], v[60:63], v[180:183], v[52:55]
	v_mfma_f32_16x16x32_bf16 v[48:51], v[68:71], v[180:183], v[48:51]
	v_mfma_f32_16x16x32_bf16 v[28:31], v[60:63], v[188:191], v[28:31]
	v_mfma_f32_16x16x32_bf16 v[24:27], v[68:71], v[188:191], v[24:27]
	s_waitcnt lgkmcnt(0)
	v_mfma_f32_16x16x32_bf16 v[12:15], v[60:63], v[198:201], v[12:15]
	v_mfma_f32_16x16x32_bf16 v[8:11], v[68:71], v[198:201], v[8:11]
	s_setprio 0
	s_barrier
	s_add_u32 s12, s12, 0x20080
	s_addc_u32 s13, s13, 0
	s_add_i32 s14, s14, s22
	v_lshl_add_u64 v[56:57], s[12:13], 0, v[148:149]
	s_mov_b32 m0, s14
	s_nop 0
	global_load_lds_dwordx4 v[56:57], off
	v_lshl_add_u64 v[56:57], s[12:13], 0, v[144:145]
	s_add_i32 m0, s14, 0x2000
	s_nop 0
	global_load_lds_dwordx4 v[56:57], off
	s_waitcnt vmcnt(6)
	s_barrier
	s_setprio 1
	v_mfma_f32_16x16x32_bf16 v[40:43], v[202:205], v[168:171], v[40:43]
	v_mfma_f32_16x16x32_bf16 v[68:71], v[206:209], v[172:175], v[40:43]
	v_mfma_f32_16x16x32_bf16 v[40:43], v[210:213], v[168:171], v[44:47]
	v_mfma_f32_16x16x32_bf16 v[36:39], v[202:205], v[176:179], v[36:39]
	v_mfma_f32_16x16x32_bf16 v[32:35], v[210:213], v[176:179], v[32:35]
	v_mfma_f32_16x16x32_bf16 v[20:23], v[202:205], v[184:187], v[20:23]
	v_mfma_f32_16x16x32_bf16 v[16:19], v[210:213], v[184:187], v[16:19]
	v_mfma_f32_16x16x32_bf16 v[4:7], v[202:205], v[192:195], v[4:7]
	v_mfma_f32_16x16x32_bf16 v[0:3], v[210:213], v[192:195], v[0:3]
	v_mfma_f32_16x16x32_bf16 v[64:67], v[214:217], v[172:175], v[40:43]
	v_mfma_f32_16x16x32_bf16 v[36:39], v[206:209], v[180:183], v[36:39]
	v_mfma_f32_16x16x32_bf16 v[32:35], v[214:217], v[180:183], v[32:35]
	v_mfma_f32_16x16x32_bf16 v[20:23], v[206:209], v[188:191], v[20:23]
	v_mfma_f32_16x16x32_bf16 v[16:19], v[214:217], v[188:191], v[16:19]
	v_mfma_f32_16x16x32_bf16 v[4:7], v[206:209], v[198:201], v[4:7]
	v_mfma_f32_16x16x32_bf16 v[0:3], v[214:217], v[198:201], v[0:3]
	s_setprio 0
	s_add_i32 s3, s3, 2
	s_add_u32 s53, s53, 0x100
	s_addc_u32 s56, s56, 0
	s_add_u32 s10, s10, 0x100
	s_addc_u32 s11, s11, 0
	s_cmp_gt_u32 s3, 5
	s_barrier
	s_cbranch_scc0 .LBB1_2339
	s_lshl_b32 s2, s2, 8
	v_mov_b32_e32 v40, v163
	v_mov_b32_e32 v168, v162
	s_or_b32 s2, s2, s29
	s_and_b64 vcc, exec, s[40:41]
	v_lshl_add_u32 v160, v40, 3, s2
	s_lshl_b32 s2, s8, 8
	s_add_i32 s2, s2, s28
	v_add_u32_e32 v168, s2, v168
	v_ashrrev_i32_e32 v169, 31, v168
	v_ashrrev_i32_e32 v161, 31, v160
	v_lshlrev_b64 v[168:169], 11, v[168:169]
	v_lshl_add_u64 v[44:45], v[160:161], 2, s[44:45]
	v_lshl_add_u64 v[160:161], v[168:169], 0, v[160:161]
	v_lshlrev_b64 v[160:161], 1, v[160:161]
	v_lshl_add_u64 v[172:173], s[4:5], 0, v[160:161]
	global_load_dwordx4 v[56:59], v[44:45], off offset:16
	global_load_dwordx4 v[60:63], v[44:45], off
	global_load_dwordx4 v[40:43], v[44:45], off offset:528
	s_nop 0
	global_load_dwordx4 v[44:47], v[44:45], off offset:512
	s_mov_b64 s[2:3], 0x10000
	global_load_dwordx4 v[168:171], v[172:173], off
	s_mov_b32 s8, s52
	s_mov_b64 s[10:11], s[54:55]
	s_mov_b64 s[12:13], s[6:7]
	s_waitcnt vmcnt(0) lgkmcnt(0)
	v_lshlrev_b32_e32 v174, 16, v168
	v_and_b32_e32 v175, 0xffff0000, v168
	v_lshlrev_b32_e32 v168, 16, v169
	v_and_b32_e32 v169, 0xffff0000, v169
	v_lshlrev_b32_e32 v176, 16, v170
	v_and_b32_e32 v177, 0xffff0000, v170
	v_lshlrev_b32_e32 v170, 16, v171
	v_and_b32_e32 v171, 0xffff0000, v171
	v_pk_fma_f32 v[142:143], v[142:143], v[62:63], v[168:169]
	v_pk_fma_f32 v[140:141], v[140:141], v[60:61], v[174:175]
	v_pk_fma_f32 v[168:169], v[138:139], v[58:59], v[170:171]
	v_pk_fma_f32 v[138:139], v[136:137], v[56:57], v[176:177]
	v_cvt_pk_bf16_f32 v136, v140, v141
	v_cvt_pk_bf16_f32 v137, v142, v143
	v_cvt_pk_bf16_f32 v138, v138, v139
	v_cvt_pk_bf16_f32 v139, v168, v169
	v_lshl_add_u64 v[140:141], s[42:43], 0, v[160:161]
	global_store_dwordx4 v[140:141], v[136:139], off
	global_load_dwordx4 v[136:139], v[172:173], off offset:256
	s_waitcnt vmcnt(0) lgkmcnt(0)
; DI unsigned pack2(float a, float b) { f32x2 v = {a, b}; hwbf16x2 r = __builtin_convertvector(v, hwbf16x2); return __builtin_bit_cast(unsigned, r); }
; DI float bflo(unsigned w) { return __uint_as_float(w << 16); }
; DI float bfhi(unsigned w) { return __uint_as_float(w & 0xffff0000u); }
;     DI void operator()(const f32x4 (&acc)[2][2][4][2], const Unit& u, int wr, int wc, int fr, int fq) const {
;     ...
;         for (int ai = 0; ai < 2; ++ai)
; #pragma unroll
;             for (int m = 0; m < 4; ++m) { const size_t ro = (size_t)(row0 + ai * HALF + m * 16) * D + col0;
; #pragma unroll
;                 for (int bj = 0; bj < 2; ++bj) {
;                     f32x4 x0, x1;
;                     if constexpr (IB) { const u32x4 w = *(const u32x4*)((const bf16_t*)Xin + ro + bj * HALF);
;                         x0 = (f32x4){bflo(w[0]), bfhi(w[0]), bflo(w[1]), bfhi(w[1])}; x1 = (f32x4){bflo(w[2]), bfhi(w[2]), bflo(w[3]), bfhi(w[3])}; }
;                     else { x0 = *(const f32x4*)((const float*)Xin + ro + bj * HALF); x1 = *(const f32x4*)((const float*)Xin + ro + bj * HALF + 4); }
;                     x0 += acc[ai][bj][m][0] * sc[bj][0]; x1 += acc[ai][bj][m][1] * sc[bj][1];
;                     if constexpr (OB) { u32x4 o; o[0] = pack2(x0[0], x0[1]); o[1] = pack2(x0[2], x0[3]); o[2] = pack2(x1[0], x1[1]); o[3] = pack2(x1[2], x1[3]);
;                         *(u32x4*)((bf16_t*)Xout + ro + bj * HALF) = o; }
;                     else { *(f32x4*)((float*)Xout + ro + bj * HALF) = x0; *(f32x4*)((float*)Xout + ro + bj * HALF + 4) = x1; } } }
	v_lshlrev_b32_e32 v142, 16, v136
	v_and_b32_e32 v143, 0xffff0000, v136
	v_lshlrev_b32_e32 v136, 16, v137
	v_and_b32_e32 v137, 0xffff0000, v137
	v_lshlrev_b32_e32 v168, 16, v138
	v_and_b32_e32 v169, 0xffff0000, v138
	v_lshlrev_b32_e32 v138, 16, v139
	v_and_b32_e32 v139, 0xffff0000, v139
	v_pk_fma_f32 v[134:135], v[134:135], v[46:47], v[136:137]
	v_pk_fma_f32 v[132:133], v[132:133], v[44:45], v[142:143]
	v_pk_fma_f32 v[136:137], v[130:131], v[42:43], v[138:139]
	v_pk_fma_f32 v[130:131], v[128:129], v[40:41], v[168:169]
	v_cvt_pk_bf16_f32 v128, v132, v133
	v_cvt_pk_bf16_f32 v129, v134, v135
	v_cvt_pk_bf16_f32 v130, v130, v131
	v_cvt_pk_bf16_f32 v131, v136, v137
	v_lshl_add_u64 v[132:133], v[160:161], 0, s[2:3]
	global_store_dwordx4 v[140:141], v[128:131], off offset:256
	v_lshl_add_u64 v[134:135], s[4:5], 0, v[132:133]
	global_load_dwordx4 v[128:131], v[134:135], off
	s_mov_b64 s[2:3], 0x20000
	s_waitcnt vmcnt(0) lgkmcnt(0)
	v_lshlrev_b32_e32 v136, 16, v128
	v_and_b32_e32 v137, 0xffff0000, v128
	v_lshlrev_b32_e32 v128, 16, v129
	v_and_b32_e32 v129, 0xffff0000, v129
	v_lshlrev_b32_e32 v138, 16, v130
	v_and_b32_e32 v139, 0xffff0000, v130
	v_lshlrev_b32_e32 v130, 16, v131
	v_and_b32_e32 v131, 0xffff0000, v131
	v_pk_fma_f32 v[126:127], v[126:127], v[62:63], v[128:129]
	v_pk_fma_f32 v[124:125], v[124:125], v[60:61], v[136:137]
	v_pk_fma_f32 v[128:129], v[122:123], v[58:59], v[130:131]
	v_pk_fma_f32 v[122:123], v[120:121], v[56:57], v[138:139]
	v_cvt_pk_bf16_f32 v120, v124, v125
	v_cvt_pk_bf16_f32 v121, v126, v127
	v_cvt_pk_bf16_f32 v122, v122, v123
	v_cvt_pk_bf16_f32 v123, v128, v129
	v_lshl_add_u64 v[124:125], s[42:43], 0, v[132:133]
	global_store_dwordx4 v[124:125], v[120:123], off
	global_load_dwordx4 v[120:123], v[134:135], off offset:256
	s_waitcnt vmcnt(0) lgkmcnt(0)
	v_lshlrev_b32_e32 v126, 16, v120
	v_and_b32_e32 v127, 0xffff0000, v120
	v_lshlrev_b32_e32 v120, 16, v121
	v_and_b32_e32 v121, 0xffff0000, v121
	v_lshlrev_b32_e32 v128, 16, v122
	v_and_b32_e32 v129, 0xffff0000, v122
	v_lshlrev_b32_e32 v122, 16, v123
	v_and_b32_e32 v123, 0xffff0000, v123
	v_pk_fma_f32 v[118:119], v[118:119], v[46:47], v[120:121]
	v_pk_fma_f32 v[116:117], v[116:117], v[44:45], v[126:127]
	v_pk_fma_f32 v[120:121], v[114:115], v[42:43], v[122:123]
	v_pk_fma_f32 v[114:115], v[112:113], v[40:41], v[128:129]
	v_cvt_pk_bf16_f32 v112, v116, v117
	v_cvt_pk_bf16_f32 v113, v118, v119
	v_cvt_pk_bf16_f32 v114, v114, v115
	v_cvt_pk_bf16_f32 v115, v120, v121
	v_lshl_add_u64 v[116:117], v[160:161], 0, s[2:3]
	global_store_dwordx4 v[124:125], v[112:115], off offset:256
	v_lshl_add_u64 v[118:119], s[4:5], 0, v[116:117]
	global_load_dwordx4 v[112:115], v[118:119], off
	s_mov_b64 s[2:3], 0x30000
	s_waitcnt vmcnt(0) lgkmcnt(0)
	v_lshlrev_b32_e32 v120, 16, v112
	v_and_b32_e32 v121, 0xffff0000, v112
	v_lshlrev_b32_e32 v112, 16, v113
	v_and_b32_e32 v113, 0xffff0000, v113
	v_lshlrev_b32_e32 v122, 16, v114
	v_and_b32_e32 v123, 0xffff0000, v114
	v_lshlrev_b32_e32 v114, 16, v115
	v_and_b32_e32 v115, 0xffff0000, v115
	v_pk_fma_f32 v[110:111], v[110:111], v[62:63], v[112:113]
	v_pk_fma_f32 v[108:109], v[108:109], v[60:61], v[120:121]
	v_pk_fma_f32 v[112:113], v[106:107], v[58:59], v[114:115]
	v_pk_fma_f32 v[106:107], v[104:105], v[56:57], v[122:123]
	v_cvt_pk_bf16_f32 v104, v108, v109
	v_cvt_pk_bf16_f32 v105, v110, v111
	v_cvt_pk_bf16_f32 v106, v106, v107
	v_cvt_pk_bf16_f32 v107, v112, v113
	v_lshl_add_u64 v[108:109], s[42:43], 0, v[116:117]
	global_store_dwordx4 v[108:109], v[104:107], off
	global_load_dwordx4 v[104:107], v[118:119], off offset:256
	s_waitcnt vmcnt(0) lgkmcnt(0)
	v_lshlrev_b32_e32 v110, 16, v104
	v_and_b32_e32 v111, 0xffff0000, v104
	v_lshlrev_b32_e32 v104, 16, v105
	v_and_b32_e32 v105, 0xffff0000, v105
	v_lshlrev_b32_e32 v112, 16, v106
	v_and_b32_e32 v113, 0xffff0000, v106
	v_lshlrev_b32_e32 v106, 16, v107
	v_and_b32_e32 v107, 0xffff0000, v107
	v_pk_fma_f32 v[102:103], v[102:103], v[46:47], v[104:105]
	v_pk_fma_f32 v[100:101], v[100:101], v[44:45], v[110:111]
	v_pk_fma_f32 v[104:105], v[98:99], v[42:43], v[106:107]
	v_pk_fma_f32 v[98:99], v[96:97], v[40:41], v[112:113]
	v_cvt_pk_bf16_f32 v96, v100, v101
	v_cvt_pk_bf16_f32 v97, v102, v103
	v_cvt_pk_bf16_f32 v98, v98, v99
	v_cvt_pk_bf16_f32 v99, v104, v105
	v_lshl_add_u64 v[100:101], v[160:161], 0, s[2:3]
	global_store_dwordx4 v[108:109], v[96:99], off offset:256
	v_lshl_add_u64 v[102:103], s[4:5], 0, v[100:101]
	global_load_dwordx4 v[96:99], v[102:103], off
	s_mov_b64 s[2:3], 0x80000
	s_waitcnt vmcnt(0) lgkmcnt(0)
	v_lshlrev_b32_e32 v104, 16, v96
	v_and_b32_e32 v105, 0xffff0000, v96
	v_lshlrev_b32_e32 v96, 16, v97
	v_and_b32_e32 v97, 0xffff0000, v97
	v_lshlrev_b32_e32 v106, 16, v98
	v_and_b32_e32 v107, 0xffff0000, v98
	v_lshlrev_b32_e32 v98, 16, v99
	v_and_b32_e32 v99, 0xffff0000, v99
	v_pk_fma_f32 v[94:95], v[94:95], v[62:63], v[96:97]
	v_pk_fma_f32 v[92:93], v[92:93], v[60:61], v[104:105]
	v_pk_fma_f32 v[96:97], v[90:91], v[58:59], v[98:99]
	v_pk_fma_f32 v[90:91], v[88:89], v[56:57], v[106:107]
	v_cvt_pk_bf16_f32 v88, v92, v93
	v_cvt_pk_bf16_f32 v89, v94, v95
	v_cvt_pk_bf16_f32 v90, v90, v91
	v_cvt_pk_bf16_f32 v91, v96, v97
	v_lshl_add_u64 v[92:93], s[42:43], 0, v[100:101]
	global_store_dwordx4 v[92:93], v[88:91], off
	global_load_dwordx4 v[88:91], v[102:103], off offset:256
	s_waitcnt vmcnt(0) lgkmcnt(0)
; DI unsigned pack2(float a, float b) { f32x2 v = {a, b}; hwbf16x2 r = __builtin_convertvector(v, hwbf16x2); return __builtin_bit_cast(unsigned, r); }
; DI float bflo(unsigned w) { return __uint_as_float(w << 16); }
; DI float bfhi(unsigned w) { return __uint_as_float(w & 0xffff0000u); }
;     DI void operator()(const f32x4 (&acc)[2][2][4][2], const Unit& u, int wr, int wc, int fr, int fq) const {
;     ...
;         for (int ai = 0; ai < 2; ++ai)
; #pragma unroll
;             for (int m = 0; m < 4; ++m) { const size_t ro = (size_t)(row0 + ai * HALF + m * 16) * D + col0;
; #pragma unroll
;                 for (int bj = 0; bj < 2; ++bj) {
;                     f32x4 x0, x1;
;                     if constexpr (IB) { const u32x4 w = *(const u32x4*)((const bf16_t*)Xin + ro + bj * HALF);
;                         x0 = (f32x4){bflo(w[0]), bfhi(w[0]), bflo(w[1]), bfhi(w[1])}; x1 = (f32x4){bflo(w[2]), bfhi(w[2]), bflo(w[3]), bfhi(w[3])}; }
;                     else { x0 = *(const f32x4*)((const float*)Xin + ro + bj * HALF); x1 = *(const f32x4*)((const float*)Xin + ro + bj * HALF + 4); }
;                     x0 += acc[ai][bj][m][0] * sc[bj][0]; x1 += acc[ai][bj][m][1] * sc[bj][1];
;                     if constexpr (OB) { u32x4 o; o[0] = pack2(x0[0], x0[1]); o[1] = pack2(x0[2], x0[3]); o[2] = pack2(x1[0], x1[1]); o[3] = pack2(x1[2], x1[3]);
;                         *(u32x4*)((bf16_t*)Xout + ro + bj * HALF) = o; }
;                     else { *(f32x4*)((float*)Xout + ro + bj * HALF) = x0; *(f32x4*)((float*)Xout + ro + bj * HALF + 4) = x1; } } }
	v_lshlrev_b32_e32 v94, 16, v88
	v_and_b32_e32 v95, 0xffff0000, v88
	v_lshlrev_b32_e32 v88, 16, v89
	v_and_b32_e32 v89, 0xffff0000, v89
	v_lshlrev_b32_e32 v96, 16, v90
	v_and_b32_e32 v97, 0xffff0000, v90
	v_lshlrev_b32_e32 v90, 16, v91
	v_and_b32_e32 v91, 0xffff0000, v91
	v_pk_fma_f32 v[86:87], v[86:87], v[46:47], v[88:89]
	v_pk_fma_f32 v[84:85], v[84:85], v[44:45], v[94:95]
	v_pk_fma_f32 v[88:89], v[82:83], v[42:43], v[90:91]
	v_pk_fma_f32 v[82:83], v[80:81], v[40:41], v[96:97]
	v_cvt_pk_bf16_f32 v80, v84, v85
	v_cvt_pk_bf16_f32 v81, v86, v87
	v_cvt_pk_bf16_f32 v82, v82, v83
	v_cvt_pk_bf16_f32 v83, v88, v89
	v_lshl_add_u64 v[84:85], v[160:161], 0, s[2:3]
	global_store_dwordx4 v[92:93], v[80:83], off offset:256
	v_lshl_add_u64 v[86:87], s[4:5], 0, v[84:85]
	global_load_dwordx4 v[80:83], v[86:87], off
	s_mov_b64 s[2:3], 0x90000
	s_waitcnt vmcnt(0) lgkmcnt(0)
	v_lshlrev_b32_e32 v88, 16, v80
	v_and_b32_e32 v89, 0xffff0000, v80
	v_lshlrev_b32_e32 v80, 16, v81
	v_and_b32_e32 v81, 0xffff0000, v81
	v_lshlrev_b32_e32 v90, 16, v82
	v_and_b32_e32 v91, 0xffff0000, v82
	v_lshlrev_b32_e32 v82, 16, v83
	v_and_b32_e32 v83, 0xffff0000, v83
	v_pk_fma_f32 v[78:79], v[78:79], v[62:63], v[80:81]
	v_pk_fma_f32 v[76:77], v[76:77], v[60:61], v[88:89]
	v_pk_fma_f32 v[80:81], v[74:75], v[58:59], v[82:83]
	v_pk_fma_f32 v[74:75], v[72:73], v[56:57], v[90:91]
	v_cvt_pk_bf16_f32 v72, v76, v77
	v_cvt_pk_bf16_f32 v73, v78, v79
	v_cvt_pk_bf16_f32 v74, v74, v75
	v_cvt_pk_bf16_f32 v75, v80, v81
	v_lshl_add_u64 v[76:77], s[42:43], 0, v[84:85]
	global_store_dwordx4 v[76:77], v[72:75], off
	global_load_dwordx4 v[72:75], v[86:87], off offset:256
	s_waitcnt vmcnt(0) lgkmcnt(0)
	v_lshlrev_b32_e32 v78, 16, v72
	v_and_b32_e32 v79, 0xffff0000, v72
	v_lshlrev_b32_e32 v72, 16, v73
	v_and_b32_e32 v73, 0xffff0000, v73
	v_lshlrev_b32_e32 v80, 16, v74
	v_and_b32_e32 v81, 0xffff0000, v74
	v_lshlrev_b32_e32 v74, 16, v75
	v_and_b32_e32 v75, 0xffff0000, v75
	v_pk_fma_f32 v[70:71], v[70:71], v[46:47], v[72:73]
	v_pk_fma_f32 v[68:69], v[68:69], v[44:45], v[78:79]
	v_pk_fma_f32 v[72:73], v[66:67], v[42:43], v[74:75]
	v_pk_fma_f32 v[66:67], v[64:65], v[40:41], v[80:81]
	v_cvt_pk_bf16_f32 v64, v68, v69
	v_cvt_pk_bf16_f32 v65, v70, v71
	v_cvt_pk_bf16_f32 v66, v66, v67
	v_cvt_pk_bf16_f32 v67, v72, v73
	v_lshl_add_u64 v[68:69], v[160:161], 0, s[2:3]
	global_store_dwordx4 v[76:77], v[64:67], off offset:256
	v_lshl_add_u64 v[70:71], s[4:5], 0, v[68:69]
	global_load_dwordx4 v[64:67], v[70:71], off
	s_mov_b64 s[2:3], 0xa0000
	s_waitcnt vmcnt(0) lgkmcnt(0)
	v_lshlrev_b32_e32 v72, 16, v64
	v_and_b32_e32 v73, 0xffff0000, v64
	v_lshlrev_b32_e32 v64, 16, v65
	v_and_b32_e32 v65, 0xffff0000, v65
	v_lshlrev_b32_e32 v74, 16, v66
	v_and_b32_e32 v75, 0xffff0000, v66
	v_lshlrev_b32_e32 v66, 16, v67
	v_and_b32_e32 v67, 0xffff0000, v67
	v_pk_fma_f32 v[54:55], v[54:55], v[62:63], v[64:65]
	v_pk_fma_f32 v[52:53], v[52:53], v[60:61], v[72:73]
	v_pk_fma_f32 v[64:65], v[50:51], v[58:59], v[66:67]
	v_pk_fma_f32 v[50:51], v[48:49], v[56:57], v[74:75]
	v_cvt_pk_bf16_f32 v48, v52, v53
	v_cvt_pk_bf16_f32 v49, v54, v55
	v_cvt_pk_bf16_f32 v50, v50, v51
	v_cvt_pk_bf16_f32 v51, v64, v65
	v_lshl_add_u64 v[52:53], s[42:43], 0, v[68:69]
	global_store_dwordx4 v[52:53], v[48:51], off
	global_load_dwordx4 v[48:51], v[70:71], off offset:256
	s_waitcnt vmcnt(0) lgkmcnt(0)
; DI unsigned pack2(float a, float b) { f32x2 v = {a, b}; hwbf16x2 r = __builtin_convertvector(v, hwbf16x2); return __builtin_bit_cast(unsigned, r); }
; DI float bflo(unsigned w) { return __uint_as_float(w << 16); }
; DI float bfhi(unsigned w) { return __uint_as_float(w & 0xffff0000u); }
; #define PG8_WAIT_V(n) asm volatile("s_waitcnt vmcnt(" #n ")" ::: "memory")
; #define PG8_BAR __builtin_amdgcn_s_barrier()
;     DI void operator()(const f32x4 (&acc)[2][2][4][2], const Unit& u, int wr, int wc, int fr, int fq) const {
;     ...
;         for (int ai = 0; ai < 2; ++ai)
; #pragma unroll
;             for (int m = 0; m < 4; ++m) { const size_t ro = (size_t)(row0 + ai * HALF + m * 16) * D + col0;
; #pragma unroll
;                 for (int bj = 0; bj < 2; ++bj) {
;                     f32x4 x0, x1;
;                     if constexpr (IB) { const u32x4 w = *(const u32x4*)((const bf16_t*)Xin + ro + bj * HALF);
;                         x0 = (f32x4){bflo(w[0]), bfhi(w[0]), bflo(w[1]), bfhi(w[1])}; x1 = (f32x4){bflo(w[2]), bfhi(w[2]), bflo(w[3]), bfhi(w[3])}; }
;                     else { x0 = *(const f32x4*)((const float*)Xin + ro + bj * HALF); x1 = *(const f32x4*)((const float*)Xin + ro + bj * HALF + 4); }
;                     x0 += acc[ai][bj][m][0] * sc[bj][0]; x1 += acc[ai][bj][m][1] * sc[bj][1];
;                     if constexpr (OB) { u32x4 o; o[0] = pack2(x0[0], x0[1]); o[1] = pack2(x0[2], x0[3]); o[2] = pack2(x1[0], x1[1]); o[3] = pack2(x1[2], x1[3]);
;                         *(u32x4*)((bf16_t*)Xout + ro + bj * HALF) = o; }
;                     else { *(f32x4*)((float*)Xout + ro + bj * HALF) = x0; *(f32x4*)((float*)Xout + ro + bj * HALF + 4) = x1; } } }
; template <class Map, class Epi>
; DI void gemm_phase(LAS unsigned char* lds, const Map& MP, const Epi& E, const int nM, const int nN, const int K, const int lda, const int ldb) {
;     ...
;     PG8_WAIT_V(0);
;     if (wr == 0) PG8_BAR;
;     PG8_BAR;
	v_lshlrev_b32_e32 v54, 16, v48
	v_and_b32_e32 v55, 0xffff0000, v48
	v_lshlrev_b32_e32 v48, 16, v49
	v_and_b32_e32 v49, 0xffff0000, v49
	v_lshlrev_b32_e32 v64, 16, v50
	v_and_b32_e32 v65, 0xffff0000, v50
	v_lshlrev_b32_e32 v50, 16, v51
	v_and_b32_e32 v51, 0xffff0000, v51
	v_pk_fma_f32 v[38:39], v[38:39], v[46:47], v[48:49]
	v_pk_fma_f32 v[36:37], v[36:37], v[44:45], v[54:55]
	v_pk_fma_f32 v[48:49], v[34:35], v[42:43], v[50:51]
	v_pk_fma_f32 v[34:35], v[32:33], v[40:41], v[64:65]
	v_cvt_pk_bf16_f32 v32, v36, v37
	v_cvt_pk_bf16_f32 v33, v38, v39
	v_cvt_pk_bf16_f32 v34, v34, v35
	v_cvt_pk_bf16_f32 v35, v48, v49
	v_lshl_add_u64 v[36:37], v[160:161], 0, s[2:3]
	global_store_dwordx4 v[52:53], v[32:35], off offset:256
	v_lshl_add_u64 v[38:39], s[4:5], 0, v[36:37]
	global_load_dwordx4 v[32:35], v[38:39], off
	s_mov_b64 s[2:3], 0xb0000
	s_waitcnt vmcnt(0) lgkmcnt(0)
	v_lshlrev_b32_e32 v48, 16, v32
	v_and_b32_e32 v49, 0xffff0000, v32
	v_lshlrev_b32_e32 v32, 16, v33
	v_and_b32_e32 v33, 0xffff0000, v33
	v_lshlrev_b32_e32 v50, 16, v34
	v_and_b32_e32 v51, 0xffff0000, v34
	v_lshlrev_b32_e32 v34, 16, v35
	v_and_b32_e32 v35, 0xffff0000, v35
	v_pk_fma_f32 v[30:31], v[30:31], v[62:63], v[32:33]
	v_pk_fma_f32 v[28:29], v[28:29], v[60:61], v[48:49]
	v_pk_fma_f32 v[32:33], v[26:27], v[58:59], v[34:35]
	v_pk_fma_f32 v[26:27], v[24:25], v[56:57], v[50:51]
	v_cvt_pk_bf16_f32 v24, v28, v29
	v_cvt_pk_bf16_f32 v25, v30, v31
	v_cvt_pk_bf16_f32 v26, v26, v27
	v_cvt_pk_bf16_f32 v27, v32, v33
	v_lshl_add_u64 v[28:29], s[42:43], 0, v[36:37]
	global_store_dwordx4 v[28:29], v[24:27], off
	global_load_dwordx4 v[24:27], v[38:39], off offset:256
	s_waitcnt vmcnt(0) lgkmcnt(0)
	v_lshlrev_b32_e32 v30, 16, v24
	v_and_b32_e32 v31, 0xffff0000, v24
	v_lshlrev_b32_e32 v24, 16, v25
	v_and_b32_e32 v25, 0xffff0000, v25
	v_lshlrev_b32_e32 v32, 16, v26
	v_and_b32_e32 v33, 0xffff0000, v26
	v_lshlrev_b32_e32 v26, 16, v27
	v_and_b32_e32 v27, 0xffff0000, v27
	v_pk_fma_f32 v[22:23], v[22:23], v[46:47], v[24:25]
	v_pk_fma_f32 v[20:21], v[20:21], v[44:45], v[30:31]
	v_pk_fma_f32 v[24:25], v[18:19], v[42:43], v[26:27]
	v_pk_fma_f32 v[18:19], v[16:17], v[40:41], v[32:33]
	v_cvt_pk_bf16_f32 v16, v20, v21
	v_cvt_pk_bf16_f32 v17, v22, v23
	v_cvt_pk_bf16_f32 v18, v18, v19
	v_cvt_pk_bf16_f32 v19, v24, v25
	v_lshl_add_u64 v[20:21], v[160:161], 0, s[2:3]
	global_store_dwordx4 v[28:29], v[16:19], off offset:256
	v_lshl_add_u64 v[22:23], s[4:5], 0, v[20:21]
	global_load_dwordx4 v[16:19], v[22:23], off
	s_mov_b32 s2, s37
	s_waitcnt vmcnt(0) lgkmcnt(0)
	v_lshlrev_b32_e32 v24, 16, v16
	v_and_b32_e32 v25, 0xffff0000, v16
	v_lshlrev_b32_e32 v16, 16, v17
	v_and_b32_e32 v17, 0xffff0000, v17
	v_lshlrev_b32_e32 v26, 16, v18
	v_and_b32_e32 v27, 0xffff0000, v18
	v_lshlrev_b32_e32 v18, 16, v19
	v_and_b32_e32 v19, 0xffff0000, v19
	v_pk_fma_f32 v[14:15], v[14:15], v[62:63], v[16:17]
	v_pk_fma_f32 v[12:13], v[12:13], v[60:61], v[24:25]
	v_pk_fma_f32 v[16:17], v[10:11], v[58:59], v[18:19]
	v_pk_fma_f32 v[10:11], v[8:9], v[56:57], v[26:27]
	v_cvt_pk_bf16_f32 v8, v12, v13
	v_cvt_pk_bf16_f32 v9, v14, v15
	v_cvt_pk_bf16_f32 v10, v10, v11
	v_cvt_pk_bf16_f32 v11, v16, v17
	v_lshl_add_u64 v[12:13], s[42:43], 0, v[20:21]
	global_store_dwordx4 v[12:13], v[8:11], off
	global_load_dwordx4 v[8:11], v[22:23], off offset:256
	s_waitcnt vmcnt(0) lgkmcnt(0)
	v_lshlrev_b32_e32 v14, 16, v8
	v_and_b32_e32 v15, 0xffff0000, v8
	v_lshlrev_b32_e32 v8, 16, v9
	v_and_b32_e32 v9, 0xffff0000, v9
	v_lshlrev_b32_e32 v16, 16, v10
	v_and_b32_e32 v17, 0xffff0000, v10
	v_lshlrev_b32_e32 v10, 16, v11
	v_and_b32_e32 v11, 0xffff0000, v11
	v_pk_fma_f32 v[6:7], v[6:7], v[46:47], v[8:9]
	v_pk_fma_f32 v[4:5], v[4:5], v[44:45], v[14:15]
	v_pk_fma_f32 v[8:9], v[2:3], v[42:43], v[10:11]
	v_pk_fma_f32 v[2:3], v[0:1], v[40:41], v[16:17]
	v_cvt_pk_bf16_f32 v0, v4, v5
	v_cvt_pk_bf16_f32 v1, v6, v7
	v_cvt_pk_bf16_f32 v2, v2, v3
	v_cvt_pk_bf16_f32 v3, v8, v9
	global_store_dwordx4 v[12:13], v[0:3], off offset:256
	s_cbranch_vccz .LBB1_2336
	s_waitcnt vmcnt(0)
	s_cmpk_gt_u32 s17, 0xff
	s_cbranch_scc1 .LBB1_2343
	s_barrier

; #define PG8_STAGE(bufoff, gbase, voff) do { _Pragma("unroll") for (int _i = 0; _i < 2; ++_i) \
;         __builtin_amdgcn_global_load_lds((const unsigned*)((const char*)(gbase) + (voff)[_i]), (LAS unsigned*)(lds + (bufoff) + ldsw + _i * 8192), 16, 0, 0); } while (0)
; #define PG8_LDA(dst, b, h) do { _Pragma("unroll") for (int m = 0; m < 4; ++m) _Pragma("unroll") for (int k = 0; k < 2; ++k) dst[m][k] = *(const LAS bf16x8*)(lds + PG8_SA(b, h) + aoff + m * 2048 + k * 1024); } while (0)
; #define PG8_LDB(dst, b, h) do { _Pragma("unroll") for (int n = 0; n < 2; ++n) _Pragma("unroll") for (int k = 0; k < 2; ++k) dst[n][k] = *(const LAS bf16x8*)(lds + PG8_SB(b, h) + boff + n * 2048 + k * 1024); } while (0)
; #define PG8_MMA(ai, bj, At, Bt) do { __builtin_amdgcn_s_setprio(1); _Pragma("unroll") for (int m = 0; m < 4; ++m) _Pragma("unroll") for (int n = 0; n < 2; ++n) _Pragma("unroll") for (int k = 0; k < 2; ++k) \
;         acc[ai][bj][m][n] = __builtin_amdgcn_mfma_f32_16x16x32_bf16(Bt[n][k], At[m][k], acc[ai][bj][m][n], 0, 0, 0); __builtin_amdgcn_s_setprio(0); } while (0)
; #define PG8_WAIT_V(n) asm volatile("s_waitcnt vmcnt(" #n ")" ::: "memory")
; #define PG8_WAIT_L(n) asm volatile("s_waitcnt lgkmcnt(" #n ")" ::: "memory")
; #define PG8_BAR __builtin_amdgcn_s_barrier()
; #define PG8_SCHED __builtin_amdgcn_sched_barrier(0)
; template <class Map, class Epi>
; DI void gemm_phase(LAS unsigned char* lds, const Map& MP, const Epi& E, const int nM, const int nN, const int K, const int lda, const int ldb) {
;     ...
;             PG8_LDB(B0, 0, 0); PG8_SCHED; PG8_LDA(At, 0, 0); PG8_STAGE(PG8_SA(1, 1), a1 + hstepA, voffA);
;             PG8_WAIT_L(8); PG8_BAR; PG8_WAIT_L(0); PG8_MMA(0, 0, At, B0); PG8_BAR; PG8_SCHED;
;             PG8_LDB(B1, 0, 1); PG8_STAGE(PG8_SB(0, 0), b2, voffB);
;             PG8_BAR; PG8_WAIT_L(0); PG8_MMA(0, 1, At, B1); PG8_BAR;
;             PG8_LDA(At, 0, 1); PG8_STAGE(PG8_SA(0, 0), a2, voffA);
;             PG8_BAR; PG8_WAIT_L(0); PG8_MMA(1, 0, At, B0); PG8_BAR; PG8_SCHED;
;             PG8_STAGE(PG8_SB(0, 1), b2 + hstepB, voffB);
;             PG8_WAIT_V(6); PG8_BAR; PG8_MMA(1, 1, At, B1); PG8_BAR;
.LBB1_2483:
	ds_read_b128 v[80:83], v189
	ds_read_b128 v[84:87], v189 offset:1024
	ds_read_b128 v[88:91], v189 offset:2048
	ds_read_b128 v[92:95], v189 offset:3072
	s_add_u32 s28, s42, 0xfff80080
	s_addc_u32 s29, s43, -1
	s_cmp_eq_u32 s3, 28
	s_cselect_b32 s47, s23, s29
	s_cselect_b32 s46, s58, s28
	s_cselect_b32 s29, s21, vcc_hi
	s_cselect_b32 s28, s59, vcc_lo
	v_lshl_add_u64 v[184:185], s[42:43], 0, v[178:179]
	s_add_i32 m0, s38, 0xc000
	ds_read_b128 v[96:99], v190
	ds_read_b128 v[100:103], v190 offset:1024
	ds_read_b128 v[108:111], v190 offset:2048
	ds_read_b128 v[112:115], v190 offset:3072
	ds_read_b128 v[160:163], v190 offset:4096
	ds_read_b128 v[164:167], v190 offset:5120
	ds_read_b128 v[198:201], v190 offset:6144
	ds_read_b128 v[202:205], v190 offset:7168
	global_load_lds_dwordx4 v[184:185], off
	v_lshl_add_u64 v[184:185], s[42:43], 0, v[176:177]
	s_add_i32 m0, s38, 0xe000
	s_nop 0
	global_load_lds_dwordx4 v[184:185], off
	s_waitcnt lgkmcnt(8)
	s_barrier
	s_setprio 1
	s_waitcnt lgkmcnt(7)
	v_mfma_f32_16x16x32_bf16 v[148:151], v[80:83], v[96:99], v[148:151]
	v_mfma_f32_16x16x32_bf16 v[144:147], v[88:91], v[96:99], v[144:147]
	s_waitcnt lgkmcnt(5)
	v_mfma_f32_16x16x32_bf16 v[136:139], v[80:83], v[108:111], v[136:139]
	v_mfma_f32_16x16x32_bf16 v[128:131], v[88:91], v[108:111], v[128:131]
	s_waitcnt lgkmcnt(3)
	v_mfma_f32_16x16x32_bf16 v[120:123], v[80:83], v[160:163], v[120:123]
	v_mfma_f32_16x16x32_bf16 v[104:107], v[88:91], v[160:163], v[104:107]
	s_waitcnt lgkmcnt(1)
	v_mfma_f32_16x16x32_bf16 v[76:79], v[80:83], v[198:201], v[76:79]
	v_mfma_f32_16x16x32_bf16 v[72:75], v[88:91], v[198:201], v[72:75]
	v_mfma_f32_16x16x32_bf16 v[148:151], v[84:87], v[100:103], v[148:151]
	v_mfma_f32_16x16x32_bf16 v[144:147], v[92:95], v[100:103], v[144:147]
	v_mfma_f32_16x16x32_bf16 v[136:139], v[84:87], v[112:115], v[136:139]
	v_mfma_f32_16x16x32_bf16 v[128:131], v[92:95], v[112:115], v[128:131]
	v_mfma_f32_16x16x32_bf16 v[120:123], v[84:87], v[164:167], v[120:123]
	v_mfma_f32_16x16x32_bf16 v[104:107], v[92:95], v[164:167], v[104:107]
	s_waitcnt lgkmcnt(0)
	v_mfma_f32_16x16x32_bf16 v[76:79], v[84:87], v[202:205], v[76:79]
	v_mfma_f32_16x16x32_bf16 v[72:75], v[92:95], v[202:205], v[72:75]
	s_setprio 0
	s_barrier
	s_add_i32 s68, s2, s37
	v_lshl_add_u64 v[184:185], s[28:29], 0, v[172:173]
	s_mov_b32 m0, s68
	ds_read_b128 v[206:209], v191
	ds_read_b128 v[210:213], v191 offset:1024
	ds_read_b128 v[214:217], v191 offset:2048
	ds_read_b128 v[218:221], v191 offset:3072
	global_load_lds_dwordx4 v[184:185], off
	v_lshl_add_u64 v[194:195], s[28:29], 0, v[168:169]
	s_add_i32 m0, s68, 0x2000
	s_nop 0
	global_load_lds_dwordx4 v[194:195], off
	s_barrier
	s_setprio 1
	s_waitcnt lgkmcnt(3)
	v_mfma_f32_16x16x32_bf16 v[156:159], v[206:209], v[96:99], v[156:159]
	s_waitcnt lgkmcnt(1)
	v_mfma_f32_16x16x32_bf16 v[96:99], v[214:217], v[96:99], v[152:155]
	v_mfma_f32_16x16x32_bf16 v[156:159], v[210:213], v[100:103], v[156:159]
	s_waitcnt lgkmcnt(0)
	v_mfma_f32_16x16x32_bf16 v[96:99], v[218:221], v[100:103], v[96:99]
	v_mfma_f32_16x16x32_bf16 v[100:103], v[206:209], v[108:111], v[140:143]
	v_mfma_f32_16x16x32_bf16 v[108:111], v[214:217], v[108:111], v[132:135]
	v_mfma_f32_16x16x32_bf16 v[116:119], v[214:217], v[160:163], v[116:119]
	v_mfma_f32_16x16x32_bf16 v[68:71], v[206:209], v[198:201], v[68:71]
	v_mfma_f32_16x16x32_bf16 v[64:67], v[214:217], v[198:201], v[64:67]
	v_mfma_f32_16x16x32_bf16 v[100:103], v[210:213], v[112:115], v[100:103]
	v_mfma_f32_16x16x32_bf16 v[108:111], v[218:221], v[112:115], v[108:111]
	v_mfma_f32_16x16x32_bf16 v[112:115], v[206:209], v[160:163], v[124:127]
	v_mfma_f32_16x16x32_bf16 v[116:119], v[218:221], v[164:167], v[116:119]
	v_mfma_f32_16x16x32_bf16 v[68:71], v[210:213], v[202:205], v[68:71]
	v_mfma_f32_16x16x32_bf16 v[64:67], v[218:221], v[202:205], v[64:67]
	v_mfma_f32_16x16x32_bf16 v[112:115], v[210:213], v[164:167], v[112:115]
	s_setprio 0
	s_mov_b32 m0, s38
	v_lshl_add_u64 v[230:231], s[46:47], 0, v[174:175]
	s_barrier
	ds_read_b128 v[124:127], v190 offset:16384
	ds_read_b128 v[132:135], v190 offset:17408
	ds_read_b128 v[140:143], v190 offset:18432
	ds_read_b128 v[152:155], v190 offset:19456
	ds_read_b128 v[160:163], v190 offset:20480
	ds_read_b128 v[164:167], v190 offset:21504
	ds_read_b128 v[198:201], v190 offset:22528
	ds_read_b128 v[202:205], v190 offset:23552
	global_load_lds_dwordx4 v[230:231], off
	v_lshl_add_u64 v[232:233], s[46:47], 0, v[170:171]
	s_mov_b32 m0, s39
	s_nop 0
	global_load_lds_dwordx4 v[232:233], off
	s_barrier
	s_setprio 1
	s_waitcnt lgkmcnt(7)
	v_mfma_f32_16x16x32_bf16 v[60:63], v[80:83], v[124:127], v[60:63]
	v_mfma_f32_16x16x32_bf16 v[48:51], v[88:91], v[124:127], v[48:51]
	s_waitcnt lgkmcnt(5)
	v_mfma_f32_16x16x32_bf16 v[40:43], v[80:83], v[140:143], v[40:43]
	v_mfma_f32_16x16x32_bf16 v[32:35], v[88:91], v[140:143], v[32:35]
	s_waitcnt lgkmcnt(3)
	v_mfma_f32_16x16x32_bf16 v[24:27], v[80:83], v[160:163], v[24:27]
	v_mfma_f32_16x16x32_bf16 v[16:19], v[88:91], v[160:163], v[16:19]
	s_waitcnt lgkmcnt(1)
	v_mfma_f32_16x16x32_bf16 v[12:15], v[80:83], v[198:201], v[12:15]
	v_mfma_f32_16x16x32_bf16 v[8:11], v[88:91], v[198:201], v[8:11]
	v_mfma_f32_16x16x32_bf16 v[60:63], v[84:87], v[132:135], v[60:63]
	v_mfma_f32_16x16x32_bf16 v[48:51], v[92:95], v[132:135], v[48:51]
	v_mfma_f32_16x16x32_bf16 v[40:43], v[84:87], v[152:155], v[40:43]
	v_mfma_f32_16x16x32_bf16 v[32:35], v[92:95], v[152:155], v[32:35]
	v_mfma_f32_16x16x32_bf16 v[24:27], v[84:87], v[164:167], v[24:27]
	v_mfma_f32_16x16x32_bf16 v[16:19], v[92:95], v[164:167], v[16:19]
	s_waitcnt lgkmcnt(0)
	v_mfma_f32_16x16x32_bf16 v[12:15], v[84:87], v[202:205], v[12:15]
	v_mfma_f32_16x16x32_bf16 v[8:11], v[92:95], v[202:205], v[8:11]
	s_setprio 0
	s_barrier
; #define PG8_STAGE(bufoff, gbase, voff) do { _Pragma("unroll") for (int _i = 0; _i < 2; ++_i) \
;         __builtin_amdgcn_global_load_lds((const unsigned*)((const char*)(gbase) + (voff)[_i]), (LAS unsigned*)(lds + (bufoff) + ldsw + _i * 8192), 16, 0, 0); } while (0)
; #define PG8_LDA(dst, b, h) do { _Pragma("unroll") for (int m = 0; m < 4; ++m) _Pragma("unroll") for (int k = 0; k < 2; ++k) dst[m][k] = *(const LAS bf16x8*)(lds + PG8_SA(b, h) + aoff + m * 2048 + k * 1024); } while (0)
; #define PG8_LDB(dst, b, h) do { _Pragma("unroll") for (int n = 0; n < 2; ++n) _Pragma("unroll") for (int k = 0; k < 2; ++k) dst[n][k] = *(const LAS bf16x8*)(lds + PG8_SB(b, h) + boff + n * 2048 + k * 1024); } while (0)
; #define PG8_MMA(ai, bj, At, Bt) do { __builtin_amdgcn_s_setprio(1); _Pragma("unroll") for (int m = 0; m < 4; ++m) _Pragma("unroll") for (int n = 0; n < 2; ++n) _Pragma("unroll") for (int k = 0; k < 2; ++k) \
;         acc[ai][bj][m][n] = __builtin_amdgcn_mfma_f32_16x16x32_bf16(Bt[n][k], At[m][k], acc[ai][bj][m][n], 0, 0, 0); __builtin_amdgcn_s_setprio(0); } while (0)
; #define PG8_WAIT_V(n) asm volatile("s_waitcnt vmcnt(" #n ")" ::: "memory")
; #define PG8_WAIT_L(n) asm volatile("s_waitcnt lgkmcnt(" #n ")" ::: "memory")
; #define PG8_BAR __builtin_amdgcn_s_barrier()
; #define PG8_SCHED __builtin_amdgcn_sched_barrier(0)
; template <class Map, class Epi>
; DI void gemm_phase(LAS unsigned char* lds, const Map& MP, const Epi& E, const int nM, const int nN, const int K, const int lda, const int ldb) {
;     ...
;             PG8_BAR; PG8_WAIT_L(0); PG8_MMA(1, 0, At, B0); PG8_BAR; PG8_SCHED;
;             PG8_STAGE(PG8_SB(0, 1), b2 + hstepB, voffB);
;             PG8_WAIT_V(6); PG8_BAR; PG8_MMA(1, 1, At, B1); PG8_BAR;
;             PG8_LDB(B0, 1, 0); PG8_SCHED; PG8_LDA(At, 1, 0); PG8_STAGE(PG8_SA(0, 1), a2 + hstepA, voffA);
;             PG8_WAIT_L(8); PG8_BAR; PG8_WAIT_L(0); PG8_MMA(0, 0, At, B0); PG8_BAR; PG8_SCHED;
;             PG8_LDB(B1, 1, 1); PG8_STAGE(PG8_SB(1, 0), b3, voffB);
;             PG8_BAR; PG8_WAIT_L(0); PG8_MMA(0, 1, At, B1); PG8_BAR;
;             PG8_LDA(At, 1, 1); PG8_STAGE(PG8_SA(1, 0), a3, voffA);
;             PG8_BAR; PG8_WAIT_L(0); PG8_MMA(1, 0, At, B0); PG8_BAR; PG8_SCHED;
	s_add_u32 s68, s28, 0x80000
	s_addc_u32 s69, s29, 0
	s_add_i32 s70, s67, s37
	v_lshl_add_u64 v[80:81], s[68:69], 0, v[172:173]
	s_mov_b32 m0, s70
	s_nop 0
	global_load_lds_dwordx4 v[80:81], off
	v_lshl_add_u64 v[80:81], s[68:69], 0, v[168:169]
	s_add_i32 m0, s70, 0x2000
	s_nop 0
	global_load_lds_dwordx4 v[80:81], off
	s_waitcnt vmcnt(6)
	s_barrier
	s_setprio 1
	v_mfma_f32_16x16x32_bf16 v[56:59], v[206:209], v[124:127], v[56:59]
	v_mfma_f32_16x16x32_bf16 v[52:55], v[214:217], v[124:127], v[52:55]
	v_mfma_f32_16x16x32_bf16 v[44:47], v[206:209], v[140:143], v[44:47]
	v_mfma_f32_16x16x32_bf16 v[36:39], v[214:217], v[140:143], v[36:39]
	v_mfma_f32_16x16x32_bf16 v[28:31], v[206:209], v[160:163], v[28:31]
	v_mfma_f32_16x16x32_bf16 v[20:23], v[214:217], v[160:163], v[20:23]
	v_mfma_f32_16x16x32_bf16 v[4:7], v[206:209], v[198:201], v[4:7]
	v_mfma_f32_16x16x32_bf16 v[0:3], v[214:217], v[198:201], v[0:3]
	v_mfma_f32_16x16x32_bf16 v[56:59], v[210:213], v[132:135], v[56:59]
	v_mfma_f32_16x16x32_bf16 v[52:55], v[218:221], v[132:135], v[52:55]
	v_mfma_f32_16x16x32_bf16 v[44:47], v[210:213], v[152:155], v[44:47]
	v_mfma_f32_16x16x32_bf16 v[36:39], v[218:221], v[152:155], v[36:39]
	v_mfma_f32_16x16x32_bf16 v[28:31], v[210:213], v[164:167], v[28:31]
	v_mfma_f32_16x16x32_bf16 v[20:23], v[218:221], v[164:167], v[20:23]
	v_mfma_f32_16x16x32_bf16 v[4:7], v[210:213], v[202:205], v[4:7]
	v_mfma_f32_16x16x32_bf16 v[0:3], v[218:221], v[202:205], v[0:3]
	s_setprio 0
	s_add_i32 s68, 0, 0x18000
	v_add_u32_e32 v92, s68, v188
	s_barrier
	ds_read_b128 v[80:83], v92
	ds_read_b128 v[84:87], v92 offset:1024
	ds_read_b128 v[88:91], v92 offset:2048
	ds_read_b128 v[92:95], v92 offset:3072
	s_add_u32 s46, s46, 0x80000
	s_addc_u32 s47, s47, 0
	s_mov_b32 m0, s55
	v_lshl_add_u64 v[140:141], s[46:47], 0, v[174:175]
	ds_read_b128 v[124:127], v190 offset:32768
	ds_read_b128 v[132:135], v190 offset:33792
	ds_read_b128 v[160:163], v190 offset:34816
	ds_read_b128 v[164:167], v190 offset:35840
	ds_read_b128 v[198:201], v190 offset:36864
	ds_read_b128 v[202:205], v190 offset:37888
	ds_read_b128 v[206:209], v190 offset:38912
	ds_read_b128 v[210:213], v190 offset:39936
	global_load_lds_dwordx4 v[140:141], off
	v_lshl_add_u64 v[140:141], s[46:47], 0, v[170:171]
	s_mov_b32 m0, s56
	s_nop 0
	global_load_lds_dwordx4 v[140:141], off
	s_waitcnt lgkmcnt(8)
	s_barrier
	s_setprio 1
	s_waitcnt lgkmcnt(7)
	v_mfma_f32_16x16x32_bf16 v[140:143], v[80:83], v[124:127], v[148:151]
	s_waitcnt lgkmcnt(6)
	v_mfma_f32_16x16x32_bf16 v[148:151], v[84:87], v[132:135], v[140:143]
	v_mfma_f32_16x16x32_bf16 v[140:143], v[88:91], v[124:127], v[144:147]
	s_waitcnt lgkmcnt(5)
	v_mfma_f32_16x16x32_bf16 v[136:139], v[80:83], v[160:163], v[136:139]
	v_mfma_f32_16x16x32_bf16 v[128:131], v[88:91], v[160:163], v[128:131]
	s_waitcnt lgkmcnt(3)
	v_mfma_f32_16x16x32_bf16 v[120:123], v[80:83], v[198:201], v[120:123]
	v_mfma_f32_16x16x32_bf16 v[104:107], v[88:91], v[198:201], v[104:107]
	s_waitcnt lgkmcnt(1)
	v_mfma_f32_16x16x32_bf16 v[76:79], v[80:83], v[206:209], v[76:79]
	v_mfma_f32_16x16x32_bf16 v[72:75], v[88:91], v[206:209], v[72:75]
	v_mfma_f32_16x16x32_bf16 v[144:147], v[92:95], v[132:135], v[140:143]
	v_mfma_f32_16x16x32_bf16 v[136:139], v[84:87], v[164:167], v[136:139]
	v_mfma_f32_16x16x32_bf16 v[128:131], v[92:95], v[164:167], v[128:131]
	v_mfma_f32_16x16x32_bf16 v[120:123], v[84:87], v[202:205], v[120:123]
	v_mfma_f32_16x16x32_bf16 v[104:107], v[92:95], v[202:205], v[104:107]
	s_waitcnt lgkmcnt(0)
	v_mfma_f32_16x16x32_bf16 v[76:79], v[84:87], v[210:213], v[76:79]
	v_mfma_f32_16x16x32_bf16 v[72:75], v[92:95], v[210:213], v[72:75]
	s_setprio 0
	s_barrier
	s_add_i32 s46, 0, 0x1c000
	v_add_u32_e32 v140, s46, v188
	s_add_i32 s47, s68, s37
	ds_read_b128 v[214:217], v140
	ds_read_b128 v[218:221], v140 offset:1024
	ds_read_b128 v[222:225], v140 offset:2048
	ds_read_b128 v[226:229], v140 offset:3072
	v_lshl_add_u64 v[140:141], v[184:185], 0, s[14:15]
	s_mov_b32 m0, s47
	s_nop 0
	global_load_lds_dwordx4 v[140:141], off
	v_lshl_add_u64 v[140:141], v[194:195], 0, s[14:15]
	s_add_i32 m0, s47, 0x2000
	s_nop 0
	global_load_lds_dwordx4 v[140:141], off
	s_barrier
	s_setprio 1
	s_waitcnt lgkmcnt(1)
	v_mfma_f32_16x16x32_bf16 v[96:99], v[222:225], v[124:127], v[96:99]
	v_mfma_f32_16x16x32_bf16 v[140:143], v[214:217], v[124:127], v[156:159]
	s_waitcnt lgkmcnt(0)
	v_mfma_f32_16x16x32_bf16 v[152:155], v[226:229], v[132:135], v[96:99]
	v_mfma_f32_16x16x32_bf16 v[96:99], v[214:217], v[160:163], v[100:103]
	v_mfma_f32_16x16x32_bf16 v[156:159], v[218:221], v[132:135], v[140:143]
	v_mfma_f32_16x16x32_bf16 v[140:143], v[218:221], v[164:167], v[96:99]
	v_mfma_f32_16x16x32_bf16 v[96:99], v[222:225], v[160:163], v[108:111]
	v_mfma_f32_16x16x32_bf16 v[132:135], v[226:229], v[164:167], v[96:99]
	v_mfma_f32_16x16x32_bf16 v[96:99], v[214:217], v[198:201], v[112:115]
	v_mfma_f32_16x16x32_bf16 v[124:127], v[218:221], v[202:205], v[96:99]
	v_mfma_f32_16x16x32_bf16 v[96:99], v[222:225], v[198:201], v[116:119]
	v_mfma_f32_16x16x32_bf16 v[68:71], v[214:217], v[206:209], v[68:71]
	v_mfma_f32_16x16x32_bf16 v[64:67], v[222:225], v[206:209], v[64:67]
	v_mfma_f32_16x16x32_bf16 v[116:119], v[226:229], v[202:205], v[96:99]
	v_mfma_f32_16x16x32_bf16 v[68:71], v[218:221], v[210:213], v[68:71]
	v_mfma_f32_16x16x32_bf16 v[64:67], v[226:229], v[210:213], v[64:67]
	s_setprio 0
	s_mov_b32 m0, s62
	v_lshl_add_u64 v[184:185], v[230:231], 0, s[14:15]
	s_barrier
; #define PG8_STAGE(bufoff, gbase, voff) do { _Pragma("unroll") for (int _i = 0; _i < 2; ++_i) \
;         __builtin_amdgcn_global_load_lds((const unsigned*)((const char*)(gbase) + (voff)[_i]), (LAS unsigned*)(lds + (bufoff) + ldsw + _i * 8192), 16, 0, 0); } while (0)
; #define PG8_MMA(ai, bj, At, Bt) do { __builtin_amdgcn_s_setprio(1); _Pragma("unroll") for (int m = 0; m < 4; ++m) _Pragma("unroll") for (int n = 0; n < 2; ++n) _Pragma("unroll") for (int k = 0; k < 2; ++k) \
;         acc[ai][bj][m][n] = __builtin_amdgcn_mfma_f32_16x16x32_bf16(Bt[n][k], At[m][k], acc[ai][bj][m][n], 0, 0, 0); __builtin_amdgcn_s_setprio(0); } while (0)
; #define PG8_WAIT_V(n) asm volatile("s_waitcnt vmcnt(" #n ")" ::: "memory")
; #define PG8_WAIT_L(n) asm volatile("s_waitcnt lgkmcnt(" #n ")" ::: "memory")
; #define PG8_BAR __builtin_amdgcn_s_barrier()
; #define PG8_SCHED __builtin_amdgcn_sched_barrier(0)
; template <class Map, class Epi>
; DI void gemm_phase(LAS unsigned char* lds, const Map& MP, const Epi& E, const int nM, const int nN, const int K, const int lda, const int ldb) {
;     ...
;             PG8_BAR; PG8_WAIT_L(0); PG8_MMA(1, 0, At, B0); PG8_BAR; PG8_SCHED;
;             PG8_STAGE(PG8_SB(1, 1), b3 + hstepB, voffB);
;             PG8_WAIT_V(6); PG8_BAR; PG8_MMA(1, 1, At, B1); PG8_BAR;
	ds_read_b128 v[96:99], v190 offset:49152
	ds_read_b128 v[100:103], v190 offset:50176
	ds_read_b128 v[108:111], v190 offset:51200
	ds_read_b128 v[112:115], v190 offset:52224
	ds_read_b128 v[160:163], v190 offset:53248
	ds_read_b128 v[164:167], v190 offset:54272
	ds_read_b128 v[198:201], v190 offset:55296
	ds_read_b128 v[202:205], v190 offset:56320
	global_load_lds_dwordx4 v[184:185], off
	v_lshl_add_u64 v[184:185], v[232:233], 0, s[14:15]
	s_mov_b32 m0, s63
	s_nop 0
	global_load_lds_dwordx4 v[184:185], off
	s_barrier
	s_setprio 1
	s_waitcnt lgkmcnt(7)
	v_mfma_f32_16x16x32_bf16 v[60:63], v[80:83], v[96:99], v[60:63]
	v_mfma_f32_16x16x32_bf16 v[48:51], v[88:91], v[96:99], v[48:51]
	s_waitcnt lgkmcnt(5)
	v_mfma_f32_16x16x32_bf16 v[40:43], v[80:83], v[108:111], v[40:43]
	v_mfma_f32_16x16x32_bf16 v[32:35], v[88:91], v[108:111], v[32:35]
	s_waitcnt lgkmcnt(3)
	v_mfma_f32_16x16x32_bf16 v[24:27], v[80:83], v[160:163], v[24:27]
	v_mfma_f32_16x16x32_bf16 v[16:19], v[88:91], v[160:163], v[16:19]
	s_waitcnt lgkmcnt(1)
	v_mfma_f32_16x16x32_bf16 v[12:15], v[80:83], v[198:201], v[12:15]
	v_mfma_f32_16x16x32_bf16 v[8:11], v[88:91], v[198:201], v[8:11]
	v_mfma_f32_16x16x32_bf16 v[60:63], v[84:87], v[100:103], v[60:63]
	v_mfma_f32_16x16x32_bf16 v[48:51], v[92:95], v[100:103], v[48:51]
	v_mfma_f32_16x16x32_bf16 v[40:43], v[84:87], v[112:115], v[40:43]
	v_mfma_f32_16x16x32_bf16 v[32:35], v[92:95], v[112:115], v[32:35]
	v_mfma_f32_16x16x32_bf16 v[24:27], v[84:87], v[164:167], v[24:27]
	v_mfma_f32_16x16x32_bf16 v[16:19], v[92:95], v[164:167], v[16:19]
	s_waitcnt lgkmcnt(0)
	v_mfma_f32_16x16x32_bf16 v[12:15], v[84:87], v[202:205], v[12:15]
	v_mfma_f32_16x16x32_bf16 v[8:11], v[92:95], v[202:205], v[8:11]
	s_setprio 0
	s_barrier
	s_add_u32 s28, s28, 0x80080
	s_addc_u32 s29, s29, 0
	s_add_i32 s46, s46, s37
	v_lshl_add_u64 v[80:81], s[28:29], 0, v[172:173]
	s_mov_b32 m0, s46
	s_nop 0
	global_load_lds_dwordx4 v[80:81], off
	v_lshl_add_u64 v[80:81], s[28:29], 0, v[168:169]
	s_add_i32 m0, s46, 0x2000
	s_nop 0
	global_load_lds_dwordx4 v[80:81], off
	s_waitcnt vmcnt(6)
	s_barrier
	s_setprio 1
	v_mfma_f32_16x16x32_bf16 v[56:59], v[214:217], v[96:99], v[56:59]
	v_mfma_f32_16x16x32_bf16 v[52:55], v[222:225], v[96:99], v[52:55]
	v_mfma_f32_16x16x32_bf16 v[44:47], v[214:217], v[108:111], v[44:47]
	v_mfma_f32_16x16x32_bf16 v[36:39], v[222:225], v[108:111], v[36:39]
	v_mfma_f32_16x16x32_bf16 v[28:31], v[214:217], v[160:163], v[28:31]
	v_mfma_f32_16x16x32_bf16 v[20:23], v[222:225], v[160:163], v[20:23]
	v_mfma_f32_16x16x32_bf16 v[4:7], v[214:217], v[198:201], v[4:7]
	v_mfma_f32_16x16x32_bf16 v[0:3], v[222:225], v[198:201], v[0:3]
	v_mfma_f32_16x16x32_bf16 v[56:59], v[218:221], v[100:103], v[56:59]
	v_mfma_f32_16x16x32_bf16 v[52:55], v[226:229], v[100:103], v[52:55]
	v_mfma_f32_16x16x32_bf16 v[44:47], v[218:221], v[112:115], v[44:47]
	v_mfma_f32_16x16x32_bf16 v[36:39], v[226:229], v[112:115], v[36:39]
	v_mfma_f32_16x16x32_bf16 v[28:31], v[218:221], v[164:167], v[28:31]
	v_mfma_f32_16x16x32_bf16 v[20:23], v[226:229], v[164:167], v[20:23]
	v_mfma_f32_16x16x32_bf16 v[4:7], v[218:221], v[202:205], v[4:7]
	v_mfma_f32_16x16x32_bf16 v[0:3], v[226:229], v[202:205], v[0:3]
	s_setprio 0
	s_add_i32 s3, s3, 2
	s_add_u32 vcc_lo, vcc_lo, 0x100
	s_addc_u32 vcc_hi, vcc_hi, 0
	s_add_u32 s42, s42, 0x100
	s_addc_u32 s43, s43, 0
	s_cmp_gt_u32 s3, 29
	s_barrier
	s_cbranch_scc0 .LBB1_2483
; DI float silu_mul(float g, float v) { return g * v * __builtin_amdgcn_rcpf(1.0f + __builtin_amdgcn_exp2f(-LOG2E * g)); }
;     DI void operator()(const f32x4 (&acc)[2][2][4][2], const Unit& u, int wr, int wc, int fr, int fq) const {
;         const int row0 = u.pm * BM + wr * 64 + fr, ch0 = u.pn * 128 + wc * 32 + 8 * fq;
;         f32x4 w0[2], w1[2], w2[2], bb[2];
; #pragma unroll
;         for (int n = 0; n < 2; ++n) { w0[n] = *(const f32x4*)(cw + ch0 + 4 * n); w1[n] = *(const f32x4*)(cw + DFF + ch0 + 4 * n); w2[n] = *(const f32x4*)(cw + 2 * DFF + ch0 + 4 * n); bb[n] = *(const f32x4*)(cb + ch0 + 4 * n); }
; #pragma unroll
;         for (int ai = 0; ai < 2; ++ai)
; #pragma unroll
;             for (int m = 0; m < 4; ++m) {
;                 const bool efirst = (m == 0) && (fr == 0), elast = (m == 3) && (fr == 15);
;                 const int row = row0 + ai * HALF + m * 16;
;                 f32x4 gc[2];
; #pragma unroll
;                 for (int n = 0; n < 2; ++n) {
;                     const f32x4 g = acc[ai][0][m][n];
;                     const f32x4 gprev = acc[ai][0][m > 0 ? m - 1 : 0][n], gnext = acc[ai][0][m < 3 ? m + 1 : 3][n];
;                     f32x4 up, dn;
; #pragma unroll
;                     for (int e = 0; e < 4; ++e) {
;                         const float pu = (m > 0 && fr == 15) ? gprev[e] : g[e];
;                         const float pd = (m < 3 && fr == 0) ? gnext[e] : g[e];
;                         up[e] = dpp_ror1(pu); dn[e] = dpp_ror15(pd);
;                     }
;                     if (efirst) up = (f32x4){0.f, 0.f, 0.f, 0.f};
;                     if (elast) dn = (f32x4){0.f, 0.f, 0.f, 0.f};
;                     gc[n] = w0[n] * up + w1[n] * g + w2[n] * dn + bb[n];
;                 }
;                 if (efirst || elast) {
;                     const size_t eo = (size_t)((row >> 6) * 2 + (elast ? 1 : 0)) * DFF + ch0;
; #pragma unroll
;                     for (int n = 0; n < 2; ++n) { *(f32x4*)(EP + eo + 4 * n) = gc[n]; *(f32x4*)(ER + eo + 4 * n) = acc[ai][0][m][n]; *(f32x4*)(EV + eo + 4 * n) = acc[ai][1][m][n]; }
;                 } else {
;                     const f32x4 v0 = acc[ai][1][m][0], v1 = acc[ai][1][m][1];
;                     u32x4 o;
;                     o[0] = pack2(silu_mul(gc[0][0], v0[0]), silu_mul(gc[0][1], v0[1])); o[1] = pack2(silu_mul(gc[0][2], v0[2]), silu_mul(gc[0][3], v0[3]));
	s_lshl_b32 s21, s45, 7
	v_mov_b32_e32 v80, v187
	v_mov_b32_e32 v194, v186
	s_or_b32 s21, s21, s57
	v_mov_b32_e32 v160, 0
	v_lshl_add_u32 v184, v80, 3, s21
	v_ashrrev_i32_e32 v185, 31, v184
	v_lshlrev_b64 v[80:81], 2, v[184:185]
	v_lshl_add_u64 v[84:85], s[4:5], 0, v[80:81]
	v_lshl_add_u64 v[88:89], s[16:17], 0, v[80:81]
	v_lshl_add_u64 v[92:93], s[18:19], 0, v[80:81]
	v_lshl_add_u64 v[112:113], s[6:7], 0, v[80:81]
	global_load_dwordx4 v[80:83], v[84:85], off offset:16
	global_load_dwordx4 v[96:99], v[84:85], off
	s_nop 0
	global_load_dwordx4 v[84:87], v[88:89], off offset:16
	global_load_dwordx4 v[100:103], v[88:89], off
	s_nop 0
	global_load_dwordx4 v[88:91], v[92:93], off offset:16
	global_load_dwordx4 v[108:111], v[92:93], off
	s_nop 0
	global_load_dwordx4 v[92:95], v[112:113], off offset:16
	s_nop 0
	global_load_dwordx4 v[112:115], v[112:113], off
	v_cmp_eq_u32_e32 vcc, 0, v194
	v_mov_b32_e32 v164, 0
	v_mov_b32_e32 v195, 0
	v_cndmask_b32_e32 v161, v148, v136, vcc
	v_cndmask_b32_e32 v162, v149, v137, vcc
	v_cndmask_b32_e32 v163, v150, v138, vcc
	v_mov_b32_dpp v160, v161 row_ror:15 row_mask:0xf bank_mask:0xf
	v_mov_b32_e32 v161, 0
	v_mov_b32_e32 v166, 0
	v_mov_b32_e32 v167, 0
	v_mov_b32_dpp v161, v162 row_ror:15 row_mask:0xf bank_mask:0xf
	v_mov_b32_e32 v162, 0
	v_mov_b32_dpp v164, v150 row_ror:1 row_mask:0xf bank_mask:0xf
	v_cndmask_b32_e32 v165, v151, v139, vcc
	v_mov_b32_dpp v162, v163 row_ror:15 row_mask:0xf bank_mask:0xf
	v_mov_b32_dpp v195, v151 row_ror:1 row_mask:0xf bank_mask:0xf
	v_mov_b32_e32 v163, 0
	v_mov_b32_dpp v166, v148 row_ror:1 row_mask:0xf bank_mask:0xf
	v_mov_b32_dpp v167, v149 row_ror:1 row_mask:0xf bank_mask:0xf
	v_mov_b32_dpp v163, v165 row_ror:15 row_mask:0xf bank_mask:0xf
	v_cndmask_b32_e64 v165, v195, 0, vcc
	v_cndmask_b32_e64 v164, v164, 0, vcc
	v_cndmask_b32_e64 v167, v167, 0, vcc
	v_cndmask_b32_e64 v166, v166, 0, vcc
	v_mov_b32_e32 v195, 0
	v_mov_b32_e32 v196, 0
	v_mov_b32_e32 v198, 0
	v_mov_b32_e32 v200, 0
	v_mov_b32_dpp v195, v144 row_ror:1 row_mask:0xf bank_mask:0xf
	v_mov_b32_dpp v196, v145 row_ror:1 row_mask:0xf bank_mask:0xf
	v_mov_b32_dpp v198, v146 row_ror:1 row_mask:0xf bank_mask:0xf
	v_cndmask_b32_e32 v199, v147, v131, vcc
	v_mov_b32_dpp v200, v147 row_ror:1 row_mask:0xf bank_mask:0xf
	v_cndmask_b32_e64 v198, v198, 0, vcc
	v_cndmask_b32_e64 v201, v196, 0, vcc
	s_lshl_b32 s3, s44, 8
	s_add_i32 s3, s3, s49
	v_add_u32_e32 v193, s3, v194
	v_cmp_ne_u32_e64 s[46:47], 0, v194
	s_waitcnt vmcnt(0)
	v_pk_mul_f32 v[164:165], v[98:99], v[164:165]
	v_pk_mul_f32 v[166:167], v[96:97], v[166:167]
	v_pk_fma_f32 v[164:165], v[150:151], v[102:103], v[164:165]
	v_pk_fma_f32 v[166:167], v[148:149], v[100:101], v[166:167]
	v_pk_fma_f32 v[162:163], v[110:111], v[162:163], v[164:165]
	v_cndmask_b32_e32 v165, v144, v128, vcc
	v_mov_b32_e32 v164, 0
	v_pk_fma_f32 v[160:161], v[108:109], v[160:161], v[166:167]
	v_cndmask_b32_e32 v166, v145, v129, vcc
	v_mov_b32_dpp v164, v165 row_ror:15 row_mask:0xf bank_mask:0xf
	v_mov_b32_e32 v165, 0
	v_cndmask_b32_e32 v167, v146, v130, vcc
	v_pk_add_f32 v[162:163], v[114:115], v[162:163]
	v_mov_b32_dpp v165, v166 row_ror:15 row_mask:0xf bank_mask:0xf
	v_mov_b32_e32 v166, 0
	v_pk_add_f32 v[160:161], v[112:113], v[160:161]
	s_nop 0
	v_mov_b32_dpp v166, v167 row_ror:15 row_mask:0xf bank_mask:0xf
	v_mov_b32_e32 v167, 0
	s_nop 1
	v_mov_b32_dpp v167, v199 row_ror:15 row_mask:0xf bank_mask:0xf
	v_cndmask_b32_e64 v199, v200, 0, vcc
	v_cndmask_b32_e64 v200, v195, 0, vcc
	v_pk_mul_f32 v[200:201], v[80:81], v[200:201]
	v_pk_mul_f32 v[198:199], v[82:83], v[198:199]
	v_pk_fma_f32 v[200:201], v[144:145], v[84:85], v[200:201]
	v_pk_fma_f32 v[198:199], v[146:147], v[86:87], v[198:199]
	v_pk_fma_f32 v[164:165], v[88:89], v[164:165], v[200:201]
	v_pk_fma_f32 v[166:167], v[90:91], v[166:167], v[198:199]
	v_pk_add_f32 v[164:165], v[92:93], v[164:165]
	v_pk_add_f32 v[166:167], v[94:95], v[166:167]
	s_and_saveexec_b64 s[28:29], s[46:47]
	s_xor_b64 s[28:29], exec, s[28:29]
	s_cbranch_execz .LBB1_2486
	v_mul_f32_e32 v195, 0xbfb8aa3b, v160
	v_exp_f32_e32 v195, v195
	v_mul_f32_e32 v196, 0xbfb8aa3b, v161
	v_exp_f32_e32 v196, v196
	v_pk_mul_f32 v[160:161], v[156:157], v[160:161]
	v_add_f32_e32 v195, 1.0, v195
	v_rcp_f32_e32 v198, v195
	v_add_f32_e32 v196, 1.0, v196
	v_mul_f32_e32 v195, 0xbfb8aa3b, v162
	v_rcp_f32_e32 v199, v196
	v_exp_f32_e32 v195, v195
	v_mul_f32_e32 v196, 0xbfb8aa3b, v163
	v_exp_f32_e32 v196, v196
	v_pk_mul_f32 v[160:161], v[160:161], v[198:199]
	v_add_f32_e32 v195, 1.0, v195
	v_rcp_f32_e32 v200, v195
	v_add_f32_e32 v195, 1.0, v196
	v_rcp_f32_e32 v201, v195
	v_cvt_pk_bf16_f32 v160, v160, v161
	v_mul_f32_e32 v161, 0xbfb8aa3b, v164
	v_exp_f32_e32 v195, v161
	v_mul_f32_e32 v161, 0xbfb8aa3b, v165
	v_exp_f32_e32 v196, v161
	v_pk_mul_f32 v[162:163], v[158:159], v[162:163]
	v_pk_mul_f32 v[164:165], v[152:153], v[164:165]
	v_pk_mul_f32 v[162:163], v[162:163], v[200:201]
	s_nop 0
	v_cvt_pk_bf16_f32 v161, v162, v163
	v_add_f32_e32 v162, 1.0, v195
	v_mul_f32_e32 v195, 0xbfb8aa3b, v166
	v_add_f32_e32 v163, 1.0, v196
	v_exp_f32_e32 v195, v195
	v_mul_f32_e32 v196, 0xbfb8aa3b, v167
	v_exp_f32_e32 v196, v196
	v_rcp_f32_e32 v162, v162
	v_add_f32_e32 v195, 1.0, v195
	v_rcp_f32_e32 v198, v195
	v_add_f32_e32 v195, 1.0, v196
	v_rcp_f32_e32 v163, v163
	v_rcp_f32_e32 v199, v195
	v_pk_mul_f32 v[166:167], v[154:155], v[166:167]
	v_pk_mul_f32 v[162:163], v[164:165], v[162:163]
	v_pk_mul_f32 v[164:165], v[166:167], v[198:199]
	v_cvt_pk_bf16_f32 v162, v162, v163
	v_cvt_pk_bf16_f32 v163, v164, v165
	v_mov_b64_e32 v[164:165], s[52:53]
	v_mad_i64_i32 v[164:165], s[42:43], v193, s60, v[164:165]
	v_lshl_add_u64 v[164:165], v[184:185], 1, v[164:165]
	global_store_dwordx4 v[164:165], v[160:163], off

; #define PG8_STAGE(bufoff, gbase, voff) do { _Pragma("unroll") for (int _i = 0; _i < 2; ++_i) \
;         __builtin_amdgcn_global_load_lds((const unsigned*)((const char*)(gbase) + (voff)[_i]), (LAS unsigned*)(lds + (bufoff) + ldsw + _i * 8192), 16, 0, 0); } while (0)
; #define PG8_LDA(dst, b, h) do { _Pragma("unroll") for (int m = 0; m < 4; ++m) _Pragma("unroll") for (int k = 0; k < 2; ++k) dst[m][k] = *(const LAS bf16x8*)(lds + PG8_SA(b, h) + aoff + m * 2048 + k * 1024); } while (0)
; #define PG8_LDB(dst, b, h) do { _Pragma("unroll") for (int n = 0; n < 2; ++n) _Pragma("unroll") for (int k = 0; k < 2; ++k) dst[n][k] = *(const LAS bf16x8*)(lds + PG8_SB(b, h) + boff + n * 2048 + k * 1024); } while (0)
; #define PG8_MMA(ai, bj, At, Bt) do { __builtin_amdgcn_s_setprio(1); _Pragma("unroll") for (int m = 0; m < 4; ++m) _Pragma("unroll") for (int n = 0; n < 2; ++n) _Pragma("unroll") for (int k = 0; k < 2; ++k) \
;         acc[ai][bj][m][n] = __builtin_amdgcn_mfma_f32_16x16x32_bf16(Bt[n][k], At[m][k], acc[ai][bj][m][n], 0, 0, 0); __builtin_amdgcn_s_setprio(0); } while (0)
; #define PG8_WAIT_V(n) asm volatile("s_waitcnt vmcnt(" #n ")" ::: "memory")
; #define PG8_WAIT_L(n) asm volatile("s_waitcnt lgkmcnt(" #n ")" ::: "memory")
; #define PG8_BAR __builtin_amdgcn_s_barrier()
; #define PG8_SCHED __builtin_amdgcn_sched_barrier(0)
; template <class Map, class Epi>
; DI void gemm_phase(LAS unsigned char* lds, const Map& MP, const Epi& E, const int nM, const int nN, const int K, const int lda, const int ldb) {
;     ...
;             PG8_LDB(B0, 0, 0); PG8_SCHED; PG8_LDA(At, 0, 0); PG8_STAGE(PG8_SA(1, 1), a1 + hstepA, voffA);
;             PG8_WAIT_L(8); PG8_BAR; PG8_WAIT_L(0); PG8_MMA(0, 0, At, B0); PG8_BAR; PG8_SCHED;
;             PG8_LDB(B1, 0, 1); PG8_STAGE(PG8_SB(0, 0), b2, voffB);
;             PG8_BAR; PG8_WAIT_L(0); PG8_MMA(0, 1, At, B1); PG8_BAR;
;             PG8_LDA(At, 0, 1); PG8_STAGE(PG8_SA(0, 0), a2, voffA);
;             PG8_BAR; PG8_WAIT_L(0); PG8_MMA(1, 0, At, B0); PG8_BAR; PG8_SCHED;
;             PG8_STAGE(PG8_SB(0, 1), b2 + hstepB, voffB);
;             PG8_WAIT_V(6); PG8_BAR; PG8_MMA(1, 1, At, B1); PG8_BAR;
.LBB1_2653:
	ds_read_b128 v[152:155], v149
	ds_read_b128 v[156:159], v149 offset:1024
	ds_read_b128 v[160:163], v149 offset:2048
	ds_read_b128 v[164:167], v149 offset:3072
	s_add_u32 s10, s8, 0x100
	s_addc_u32 s11, s9, 0
	s_cmpk_eq_i32 s48, 0x54
	s_cselect_b32 s15, s43, s11
	s_cselect_b32 s14, s42, s10
	s_cselect_b32 s13, s45, s39
	s_cselect_b32 s12, s44, s38
	v_lshl_add_u64 v[144:145], s[8:9], 0, v[138:139]
	s_add_i32 m0, s22, 0xc000
	ds_read_b128 v[168:171], v150
	ds_read_b128 v[172:175], v150 offset:1024
	ds_read_b128 v[176:179], v150 offset:2048
	ds_read_b128 v[180:183], v150 offset:3072
	ds_read_b128 v[184:187], v150 offset:4096
	ds_read_b128 v[188:191], v150 offset:5120
	ds_read_b128 v[192:195], v150 offset:6144
	ds_read_b128 v[196:199], v150 offset:7168
	global_load_lds_dwordx4 v[144:145], off
	v_lshl_add_u64 v[144:145], s[8:9], 0, v[136:137]
	s_add_i32 m0, s22, 0xe000
	s_nop 0
	global_load_lds_dwordx4 v[144:145], off
	s_waitcnt lgkmcnt(8)
	s_barrier
	s_setprio 1
	s_waitcnt lgkmcnt(7)
	v_mfma_f32_16x16x32_bf16 v[124:127], v[152:155], v[168:171], v[124:127]
	v_mfma_f32_16x16x32_bf16 v[120:123], v[160:163], v[168:171], v[120:123]
	s_waitcnt lgkmcnt(5)
	v_mfma_f32_16x16x32_bf16 v[108:111], v[152:155], v[176:179], v[108:111]
	v_mfma_f32_16x16x32_bf16 v[104:107], v[160:163], v[176:179], v[104:107]
	s_waitcnt lgkmcnt(3)
	v_mfma_f32_16x16x32_bf16 v[92:95], v[152:155], v[184:187], v[92:95]
	v_mfma_f32_16x16x32_bf16 v[88:91], v[160:163], v[184:187], v[88:91]
	s_waitcnt lgkmcnt(1)
	v_mfma_f32_16x16x32_bf16 v[76:79], v[152:155], v[192:195], v[76:79]
	v_mfma_f32_16x16x32_bf16 v[72:75], v[160:163], v[192:195], v[72:75]
	v_mfma_f32_16x16x32_bf16 v[124:127], v[156:159], v[172:175], v[124:127]
	v_mfma_f32_16x16x32_bf16 v[120:123], v[164:167], v[172:175], v[120:123]
	v_mfma_f32_16x16x32_bf16 v[108:111], v[156:159], v[180:183], v[108:111]
	v_mfma_f32_16x16x32_bf16 v[104:107], v[164:167], v[180:183], v[104:107]
	v_mfma_f32_16x16x32_bf16 v[92:95], v[156:159], v[188:191], v[92:95]
	v_mfma_f32_16x16x32_bf16 v[88:91], v[164:167], v[188:191], v[88:91]
	s_waitcnt lgkmcnt(0)
	v_mfma_f32_16x16x32_bf16 v[76:79], v[156:159], v[196:199], v[76:79]
	v_mfma_f32_16x16x32_bf16 v[72:75], v[164:167], v[196:199], v[72:75]
	s_setprio 0
	s_barrier
	s_add_i32 s8, s33, s20
	v_lshl_add_u64 v[144:145], s[12:13], 0, v[132:133]
	s_mov_b32 m0, s8
	ds_read_b128 v[200:203], v151
	ds_read_b128 v[204:207], v151 offset:1024
	ds_read_b128 v[208:211], v151 offset:2048
	ds_read_b128 v[212:215], v151 offset:3072
	global_load_lds_dwordx4 v[144:145], off
	v_lshl_add_u64 v[216:217], s[12:13], 0, v[128:129]
	s_add_i32 m0, s8, 0x2000
	s_nop 0
	global_load_lds_dwordx4 v[216:217], off
	s_barrier
	s_setprio 1
	s_waitcnt lgkmcnt(3)
	v_mfma_f32_16x16x32_bf16 v[116:119], v[200:203], v[168:171], v[116:119]
	s_waitcnt lgkmcnt(1)
	v_mfma_f32_16x16x32_bf16 v[112:115], v[208:211], v[168:171], v[112:115]
	v_mfma_f32_16x16x32_bf16 v[100:103], v[200:203], v[176:179], v[100:103]
	v_mfma_f32_16x16x32_bf16 v[96:99], v[208:211], v[176:179], v[96:99]
	v_mfma_f32_16x16x32_bf16 v[84:87], v[200:203], v[184:187], v[84:87]
	v_mfma_f32_16x16x32_bf16 v[80:83], v[208:211], v[184:187], v[80:83]
	v_mfma_f32_16x16x32_bf16 v[68:71], v[200:203], v[192:195], v[68:71]
	v_mfma_f32_16x16x32_bf16 v[64:67], v[208:211], v[192:195], v[64:67]
	v_mfma_f32_16x16x32_bf16 v[116:119], v[204:207], v[172:175], v[116:119]
	s_waitcnt lgkmcnt(0)
	v_mfma_f32_16x16x32_bf16 v[112:115], v[212:215], v[172:175], v[112:115]
	v_mfma_f32_16x16x32_bf16 v[100:103], v[204:207], v[180:183], v[100:103]
	v_mfma_f32_16x16x32_bf16 v[96:99], v[212:215], v[180:183], v[96:99]
	v_mfma_f32_16x16x32_bf16 v[84:87], v[204:207], v[188:191], v[84:87]
	v_mfma_f32_16x16x32_bf16 v[80:83], v[212:215], v[188:191], v[80:83]
	v_mfma_f32_16x16x32_bf16 v[68:71], v[204:207], v[196:199], v[68:71]
	v_mfma_f32_16x16x32_bf16 v[64:67], v[212:215], v[196:199], v[64:67]
	s_setprio 0
	s_mov_b32 m0, s22
	v_lshl_add_u64 v[218:219], s[14:15], 0, v[134:135]
	s_barrier
	ds_read_b128 v[168:171], v150 offset:16384
	ds_read_b128 v[172:175], v150 offset:17408
	ds_read_b128 v[176:179], v150 offset:18432
	ds_read_b128 v[180:183], v150 offset:19456
	ds_read_b128 v[184:187], v150 offset:20480
	ds_read_b128 v[188:191], v150 offset:21504
	ds_read_b128 v[192:195], v150 offset:22528
	ds_read_b128 v[196:199], v150 offset:23552
	global_load_lds_dwordx4 v[218:219], off
	v_lshl_add_u64 v[220:221], s[14:15], 0, v[130:131]
	s_mov_b32 m0, s23
	s_nop 0
	global_load_lds_dwordx4 v[220:221], off
	s_barrier
	s_setprio 1
	s_waitcnt lgkmcnt(7)
	v_mfma_f32_16x16x32_bf16 v[60:63], v[152:155], v[168:171], v[60:63]
	v_mfma_f32_16x16x32_bf16 v[56:59], v[160:163], v[168:171], v[56:59]
	s_waitcnt lgkmcnt(5)
	v_mfma_f32_16x16x32_bf16 v[44:47], v[152:155], v[176:179], v[44:47]
	v_mfma_f32_16x16x32_bf16 v[40:43], v[160:163], v[176:179], v[40:43]
	s_waitcnt lgkmcnt(3)
	v_mfma_f32_16x16x32_bf16 v[28:31], v[152:155], v[184:187], v[28:31]
	v_mfma_f32_16x16x32_bf16 v[24:27], v[160:163], v[184:187], v[24:27]
	s_waitcnt lgkmcnt(1)
	v_mfma_f32_16x16x32_bf16 v[12:15], v[152:155], v[192:195], v[12:15]
	v_mfma_f32_16x16x32_bf16 v[8:11], v[160:163], v[192:195], v[8:11]
	v_mfma_f32_16x16x32_bf16 v[60:63], v[156:159], v[172:175], v[60:63]
	v_mfma_f32_16x16x32_bf16 v[56:59], v[164:167], v[172:175], v[56:59]
	v_mfma_f32_16x16x32_bf16 v[44:47], v[156:159], v[180:183], v[44:47]
	v_mfma_f32_16x16x32_bf16 v[40:43], v[164:167], v[180:183], v[40:43]
	v_mfma_f32_16x16x32_bf16 v[28:31], v[156:159], v[188:191], v[28:31]
	v_mfma_f32_16x16x32_bf16 v[24:27], v[164:167], v[188:191], v[24:27]
	s_waitcnt lgkmcnt(0)
	v_mfma_f32_16x16x32_bf16 v[12:15], v[156:159], v[196:199], v[12:15]
	v_mfma_f32_16x16x32_bf16 v[8:11], v[164:167], v[196:199], v[8:11]
	s_setprio 0
	s_barrier
; #define PG8_STAGE(bufoff, gbase, voff) do { _Pragma("unroll") for (int _i = 0; _i < 2; ++_i) \
;         __builtin_amdgcn_global_load_lds((const unsigned*)((const char*)(gbase) + (voff)[_i]), (LAS unsigned*)(lds + (bufoff) + ldsw + _i * 8192), 16, 0, 0); } while (0)
; #define PG8_LDA(dst, b, h) do { _Pragma("unroll") for (int m = 0; m < 4; ++m) _Pragma("unroll") for (int k = 0; k < 2; ++k) dst[m][k] = *(const LAS bf16x8*)(lds + PG8_SA(b, h) + aoff + m * 2048 + k * 1024); } while (0)
; #define PG8_LDB(dst, b, h) do { _Pragma("unroll") for (int n = 0; n < 2; ++n) _Pragma("unroll") for (int k = 0; k < 2; ++k) dst[n][k] = *(const LAS bf16x8*)(lds + PG8_SB(b, h) + boff + n * 2048 + k * 1024); } while (0)
; #define PG8_MMA(ai, bj, At, Bt) do { __builtin_amdgcn_s_setprio(1); _Pragma("unroll") for (int m = 0; m < 4; ++m) _Pragma("unroll") for (int n = 0; n < 2; ++n) _Pragma("unroll") for (int k = 0; k < 2; ++k) \
;         acc[ai][bj][m][n] = __builtin_amdgcn_mfma_f32_16x16x32_bf16(Bt[n][k], At[m][k], acc[ai][bj][m][n], 0, 0, 0); __builtin_amdgcn_s_setprio(0); } while (0)
; #define PG8_WAIT_V(n) asm volatile("s_waitcnt vmcnt(" #n ")" ::: "memory")
; #define PG8_WAIT_L(n) asm volatile("s_waitcnt lgkmcnt(" #n ")" ::: "memory")
; #define PG8_BAR __builtin_amdgcn_s_barrier()
; #define PG8_SCHED __builtin_amdgcn_sched_barrier(0)
; template <class Map, class Epi>
; DI void gemm_phase(LAS unsigned char* lds, const Map& MP, const Epi& E, const int nM, const int nN, const int K, const int lda, const int ldb) {
;     ...
;             PG8_BAR; PG8_WAIT_L(0); PG8_MMA(1, 0, At, B0); PG8_BAR; PG8_SCHED;
;             PG8_STAGE(PG8_SB(0, 1), b2 + hstepB, voffB);
;             PG8_WAIT_V(6); PG8_BAR; PG8_MMA(1, 1, At, B1); PG8_BAR;
;             PG8_LDB(B0, 1, 0); PG8_SCHED; PG8_LDA(At, 1, 0); PG8_STAGE(PG8_SA(0, 1), a2 + hstepA, voffA);
;             PG8_WAIT_L(8); PG8_BAR; PG8_WAIT_L(0); PG8_MMA(0, 0, At, B0); PG8_BAR; PG8_SCHED;
;             PG8_LDB(B1, 1, 1); PG8_STAGE(PG8_SB(1, 0), b3, voffB);
;             PG8_BAR; PG8_WAIT_L(0); PG8_MMA(0, 1, At, B1); PG8_BAR;
;             PG8_LDA(At, 1, 1); PG8_STAGE(PG8_SA(1, 0), a3, voffA);
;             PG8_BAR; PG8_WAIT_L(0); PG8_MMA(1, 0, At, B0); PG8_BAR; PG8_SCHED;
	s_add_u32 s8, s12, 0x160000
	s_addc_u32 s9, s13, 0
	s_add_i32 s49, s34, s20
	v_lshl_add_u64 v[152:153], s[8:9], 0, v[132:133]
	s_mov_b32 m0, s49
	s_nop 0
	global_load_lds_dwordx4 v[152:153], off
	v_lshl_add_u64 v[152:153], s[8:9], 0, v[128:129]
	s_add_i32 m0, s49, 0x2000
	s_nop 0
	global_load_lds_dwordx4 v[152:153], off
	s_waitcnt vmcnt(6)
	s_barrier
	s_setprio 1
	v_mfma_f32_16x16x32_bf16 v[52:55], v[200:203], v[168:171], v[52:55]
	v_mfma_f32_16x16x32_bf16 v[48:51], v[208:211], v[168:171], v[48:51]
	v_mfma_f32_16x16x32_bf16 v[36:39], v[200:203], v[176:179], v[36:39]
	v_mfma_f32_16x16x32_bf16 v[32:35], v[208:211], v[176:179], v[32:35]
	v_mfma_f32_16x16x32_bf16 v[20:23], v[200:203], v[184:187], v[20:23]
	v_mfma_f32_16x16x32_bf16 v[16:19], v[208:211], v[184:187], v[16:19]
	v_mfma_f32_16x16x32_bf16 v[4:7], v[200:203], v[192:195], v[4:7]
	v_mfma_f32_16x16x32_bf16 v[0:3], v[208:211], v[192:195], v[0:3]
	v_mfma_f32_16x16x32_bf16 v[52:55], v[204:207], v[172:175], v[52:55]
	v_mfma_f32_16x16x32_bf16 v[48:51], v[212:215], v[172:175], v[48:51]
	v_mfma_f32_16x16x32_bf16 v[36:39], v[204:207], v[180:183], v[36:39]
	v_mfma_f32_16x16x32_bf16 v[32:35], v[212:215], v[180:183], v[32:35]
	v_mfma_f32_16x16x32_bf16 v[20:23], v[204:207], v[188:191], v[20:23]
	v_mfma_f32_16x16x32_bf16 v[16:19], v[212:215], v[188:191], v[16:19]
	v_mfma_f32_16x16x32_bf16 v[4:7], v[204:207], v[196:199], v[4:7]
	v_mfma_f32_16x16x32_bf16 v[0:3], v[212:215], v[196:199], v[0:3]
	s_setprio 0
	s_add_i32 s49, 0, 0x18000
	v_add_u32_e32 v164, s49, v148
	s_barrier
	ds_read_b128 v[152:155], v164
	ds_read_b128 v[156:159], v164 offset:1024
	ds_read_b128 v[160:163], v164 offset:2048
	ds_read_b128 v[164:167], v164 offset:3072
	s_add_u32 s8, s14, 0x160000
	s_addc_u32 s9, s15, 0
	s_mov_b32 m0, s24
	v_lshl_add_u64 v[200:201], s[8:9], 0, v[134:135]
	ds_read_b128 v[168:171], v150 offset:32768
	ds_read_b128 v[172:175], v150 offset:33792
	ds_read_b128 v[176:179], v150 offset:34816
	ds_read_b128 v[180:183], v150 offset:35840
	ds_read_b128 v[184:187], v150 offset:36864
	ds_read_b128 v[188:191], v150 offset:37888
	ds_read_b128 v[192:195], v150 offset:38912
	ds_read_b128 v[196:199], v150 offset:39936
	global_load_lds_dwordx4 v[200:201], off
	v_lshl_add_u64 v[200:201], s[8:9], 0, v[130:131]
	s_mov_b32 m0, s25
	s_nop 0
	global_load_lds_dwordx4 v[200:201], off
	s_waitcnt lgkmcnt(8)
	s_barrier
	s_setprio 1
	s_waitcnt lgkmcnt(7)
	v_mfma_f32_16x16x32_bf16 v[124:127], v[152:155], v[168:171], v[124:127]
	v_mfma_f32_16x16x32_bf16 v[120:123], v[160:163], v[168:171], v[120:123]
	s_waitcnt lgkmcnt(5)
	v_mfma_f32_16x16x32_bf16 v[108:111], v[152:155], v[176:179], v[108:111]
	v_mfma_f32_16x16x32_bf16 v[104:107], v[160:163], v[176:179], v[104:107]
	s_waitcnt lgkmcnt(3)
	v_mfma_f32_16x16x32_bf16 v[92:95], v[152:155], v[184:187], v[92:95]
	v_mfma_f32_16x16x32_bf16 v[88:91], v[160:163], v[184:187], v[88:91]
	s_waitcnt lgkmcnt(1)
	v_mfma_f32_16x16x32_bf16 v[76:79], v[152:155], v[192:195], v[76:79]
	v_mfma_f32_16x16x32_bf16 v[72:75], v[160:163], v[192:195], v[72:75]
	v_mfma_f32_16x16x32_bf16 v[124:127], v[156:159], v[172:175], v[124:127]
	v_mfma_f32_16x16x32_bf16 v[120:123], v[164:167], v[172:175], v[120:123]
	v_mfma_f32_16x16x32_bf16 v[108:111], v[156:159], v[180:183], v[108:111]
	v_mfma_f32_16x16x32_bf16 v[104:107], v[164:167], v[180:183], v[104:107]
	v_mfma_f32_16x16x32_bf16 v[92:95], v[156:159], v[188:191], v[92:95]
	v_mfma_f32_16x16x32_bf16 v[88:91], v[164:167], v[188:191], v[88:91]
	s_waitcnt lgkmcnt(0)
	v_mfma_f32_16x16x32_bf16 v[76:79], v[156:159], v[196:199], v[76:79]
	v_mfma_f32_16x16x32_bf16 v[72:75], v[164:167], v[196:199], v[72:75]
	s_setprio 0
	s_barrier
	s_add_i32 s14, 0, 0x1c000
	s_add_i32 s8, s49, s20
	v_add_u32_e32 v212, s14, v148
	v_lshl_add_u64 v[144:145], v[144:145], 0, s[46:47]
	s_mov_b32 m0, s8
	ds_read_b128 v[200:203], v212
	ds_read_b128 v[204:207], v212 offset:1024
	ds_read_b128 v[208:211], v212 offset:2048
	ds_read_b128 v[212:215], v212 offset:3072
	global_load_lds_dwordx4 v[144:145], off
	v_lshl_add_u64 v[144:145], v[216:217], 0, s[46:47]
	s_add_i32 m0, s8, 0x2000
	s_nop 0
	global_load_lds_dwordx4 v[144:145], off
	s_barrier
	s_setprio 1
	s_waitcnt lgkmcnt(3)
	v_mfma_f32_16x16x32_bf16 v[116:119], v[200:203], v[168:171], v[116:119]
	s_waitcnt lgkmcnt(1)
	v_mfma_f32_16x16x32_bf16 v[112:115], v[208:211], v[168:171], v[112:115]
	v_mfma_f32_16x16x32_bf16 v[100:103], v[200:203], v[176:179], v[100:103]
	v_mfma_f32_16x16x32_bf16 v[96:99], v[208:211], v[176:179], v[96:99]
	v_mfma_f32_16x16x32_bf16 v[84:87], v[200:203], v[184:187], v[84:87]
	v_mfma_f32_16x16x32_bf16 v[80:83], v[208:211], v[184:187], v[80:83]
	v_mfma_f32_16x16x32_bf16 v[68:71], v[200:203], v[192:195], v[68:71]
	v_mfma_f32_16x16x32_bf16 v[64:67], v[208:211], v[192:195], v[64:67]
	v_mfma_f32_16x16x32_bf16 v[116:119], v[204:207], v[172:175], v[116:119]
	s_waitcnt lgkmcnt(0)
	v_mfma_f32_16x16x32_bf16 v[112:115], v[212:215], v[172:175], v[112:115]
	v_mfma_f32_16x16x32_bf16 v[100:103], v[204:207], v[180:183], v[100:103]
	v_mfma_f32_16x16x32_bf16 v[96:99], v[212:215], v[180:183], v[96:99]
	v_mfma_f32_16x16x32_bf16 v[84:87], v[204:207], v[188:191], v[84:87]
	v_mfma_f32_16x16x32_bf16 v[80:83], v[212:215], v[188:191], v[80:83]
	v_mfma_f32_16x16x32_bf16 v[68:71], v[204:207], v[196:199], v[68:71]
	v_mfma_f32_16x16x32_bf16 v[64:67], v[212:215], v[196:199], v[64:67]
	s_setprio 0
	s_mov_b32 m0, s29
	v_lshl_add_u64 v[144:145], v[218:219], 0, s[46:47]
	s_barrier
; DI unsigned pack2(float a, float b) { f32x2 v = {a, b}; hwbf16x2 r = __builtin_convertvector(v, hwbf16x2); return __builtin_bit_cast(unsigned, r); }
; DI float bflo(unsigned w) { return __uint_as_float(w << 16); }
; DI float bfhi(unsigned w) { return __uint_as_float(w & 0xffff0000u); }
; #define PG8_STAGE(bufoff, gbase, voff) do { _Pragma("unroll") for (int _i = 0; _i < 2; ++_i) \
;         __builtin_amdgcn_global_load_lds((const unsigned*)((const char*)(gbase) + (voff)[_i]), (LAS unsigned*)(lds + (bufoff) + ldsw + _i * 8192), 16, 0, 0); } while (0)
; #define PG8_WAIT_V(n) asm volatile("s_waitcnt vmcnt(" #n ")" ::: "memory")
; #define PG8_WAIT_L(n) asm volatile("s_waitcnt lgkmcnt(" #n ")" ::: "memory")
;     DI void operator()(const f32x4 (&acc)[2][2][4][2], const Unit& u, int wr, int wc, int fr, int fq) const {
;     ...
;         for (int ai = 0; ai < 2; ++ai)
; #pragma unroll
;             for (int m = 0; m < 4; ++m) { const size_t ro = (size_t)(row0 + ai * HALF + m * 16) * D + col0;
; #pragma unroll
;                 for (int bj = 0; bj < 2; ++bj) {
;                     f32x4 x0, x1;
;                     if constexpr (IB) { const u32x4 w = *(const u32x4*)((const bf16_t*)Xin + ro + bj * HALF);
;                         x0 = (f32x4){bflo(w[0]), bfhi(w[0]), bflo(w[1]), bfhi(w[1])}; x1 = (f32x4){bflo(w[2]), bfhi(w[2]), bflo(w[3]), bfhi(w[3])}; }
;                     else { x0 = *(const f32x4*)((const float*)Xin + ro + bj * HALF); x1 = *(const f32x4*)((const float*)Xin + ro + bj * HALF + 4); }
;                     x0 += acc[ai][bj][m][0] * sc[bj][0]; x1 += acc[ai][bj][m][1] * sc[bj][1];
;                     if constexpr (OB) { u32x4 o; o[0] = pack2(x0[0], x0[1]); o[1] = pack2(x0[2], x0[3]); o[2] = pack2(x1[0], x1[1]); o[3] = pack2(x1[2], x1[3]);
;                         *(u32x4*)((bf16_t*)Xout + ro + bj * HALF) = o; }
;                     else { *(f32x4*)((float*)Xout + ro + bj * HALF) = x0; *(f32x4*)((float*)Xout + ro + bj * HALF + 4) = x1; } } }
; template <class Map, class Epi>
; DI void gemm_phase(LAS unsigned char* lds, const Map& MP, const Epi& E, const int nM, const int nN, const int K, const int lda, const int ldb) {
;     ...
;             PG8_BAR; PG8_WAIT_L(0); PG8_MMA(1, 0, At, B0); PG8_BAR; PG8_SCHED;
;             PG8_STAGE(PG8_SB(1, 1), b3 + hstepB, voffB);
;             PG8_WAIT_V(6); PG8_BAR; PG8_MMA(1, 1, At, B1); PG8_BAR;
	ds_read_b128 v[168:171], v150 offset:49152
	ds_read_b128 v[172:175], v150 offset:50176
	ds_read_b128 v[176:179], v150 offset:51200
	ds_read_b128 v[180:183], v150 offset:52224
	ds_read_b128 v[184:187], v150 offset:53248
	ds_read_b128 v[188:191], v150 offset:54272
	ds_read_b128 v[192:195], v150 offset:55296
	ds_read_b128 v[196:199], v150 offset:56320
	global_load_lds_dwordx4 v[144:145], off
	v_lshl_add_u64 v[144:145], v[220:221], 0, s[46:47]
	s_mov_b32 m0, s30
	s_nop 0
	global_load_lds_dwordx4 v[144:145], off
	s_barrier
	s_setprio 1
	s_waitcnt lgkmcnt(7)
	v_mfma_f32_16x16x32_bf16 v[60:63], v[152:155], v[168:171], v[60:63]
	v_mfma_f32_16x16x32_bf16 v[56:59], v[160:163], v[168:171], v[56:59]
	s_waitcnt lgkmcnt(5)
	v_mfma_f32_16x16x32_bf16 v[44:47], v[152:155], v[176:179], v[44:47]
	v_mfma_f32_16x16x32_bf16 v[40:43], v[160:163], v[176:179], v[40:43]
	s_waitcnt lgkmcnt(3)
	v_mfma_f32_16x16x32_bf16 v[28:31], v[152:155], v[184:187], v[28:31]
	v_mfma_f32_16x16x32_bf16 v[24:27], v[160:163], v[184:187], v[24:27]
	s_waitcnt lgkmcnt(1)
	v_mfma_f32_16x16x32_bf16 v[12:15], v[152:155], v[192:195], v[12:15]
	v_mfma_f32_16x16x32_bf16 v[8:11], v[160:163], v[192:195], v[8:11]
	v_mfma_f32_16x16x32_bf16 v[60:63], v[156:159], v[172:175], v[60:63]
	v_mfma_f32_16x16x32_bf16 v[56:59], v[164:167], v[172:175], v[56:59]
	v_mfma_f32_16x16x32_bf16 v[44:47], v[156:159], v[180:183], v[44:47]
	v_mfma_f32_16x16x32_bf16 v[40:43], v[164:167], v[180:183], v[40:43]
	v_mfma_f32_16x16x32_bf16 v[28:31], v[156:159], v[188:191], v[28:31]
	v_mfma_f32_16x16x32_bf16 v[24:27], v[164:167], v[188:191], v[24:27]
	s_waitcnt lgkmcnt(0)
	v_mfma_f32_16x16x32_bf16 v[12:15], v[156:159], v[196:199], v[12:15]
	v_mfma_f32_16x16x32_bf16 v[8:11], v[164:167], v[196:199], v[8:11]
	s_setprio 0
	s_barrier
	s_add_u32 s8, s12, 0x160080
	s_addc_u32 s9, s13, 0
	s_add_i32 s12, s14, s20
	v_lshl_add_u64 v[144:145], s[8:9], 0, v[132:133]
	s_mov_b32 m0, s12
	s_nop 0
	global_load_lds_dwordx4 v[144:145], off
	v_lshl_add_u64 v[144:145], s[8:9], 0, v[128:129]
	s_add_i32 m0, s12, 0x2000
	s_nop 0
	global_load_lds_dwordx4 v[144:145], off
	s_waitcnt vmcnt(6)
	s_barrier
	s_setprio 1
	v_mfma_f32_16x16x32_bf16 v[52:55], v[200:203], v[168:171], v[52:55]
	v_mfma_f32_16x16x32_bf16 v[48:51], v[208:211], v[168:171], v[48:51]
	v_mfma_f32_16x16x32_bf16 v[36:39], v[200:203], v[176:179], v[36:39]
	v_mfma_f32_16x16x32_bf16 v[32:35], v[208:211], v[176:179], v[32:35]
	v_mfma_f32_16x16x32_bf16 v[20:23], v[200:203], v[184:187], v[20:23]
	v_mfma_f32_16x16x32_bf16 v[16:19], v[208:211], v[184:187], v[16:19]
	v_mfma_f32_16x16x32_bf16 v[4:7], v[200:203], v[192:195], v[4:7]
	v_mfma_f32_16x16x32_bf16 v[0:3], v[208:211], v[192:195], v[0:3]
	v_mfma_f32_16x16x32_bf16 v[52:55], v[204:207], v[172:175], v[52:55]
	v_mfma_f32_16x16x32_bf16 v[48:51], v[212:215], v[172:175], v[48:51]
	v_mfma_f32_16x16x32_bf16 v[36:39], v[204:207], v[180:183], v[36:39]
	v_mfma_f32_16x16x32_bf16 v[32:35], v[212:215], v[180:183], v[32:35]
	v_mfma_f32_16x16x32_bf16 v[20:23], v[204:207], v[188:191], v[20:23]
	v_mfma_f32_16x16x32_bf16 v[16:19], v[212:215], v[188:191], v[16:19]
	v_mfma_f32_16x16x32_bf16 v[4:7], v[204:207], v[196:199], v[4:7]
	v_mfma_f32_16x16x32_bf16 v[0:3], v[212:215], v[196:199], v[0:3]
	s_setprio 0
	s_add_i32 s48, s48, 2
	s_add_u32 s38, s38, 0x100
	s_addc_u32 s39, s39, 0
	s_cmpk_gt_u32 s48, 0x55
	s_mov_b64 s[8:9], s[10:11]
	s_barrier
	s_cbranch_scc0 .LBB1_2653
	v_mov_b32_e32 v144, v147
	v_mov_b32_e32 v152, v146
	s_lshl_b32 s2, s2, 8
	s_lshl_b32 s8, s37, 8
	s_add_i32 s2, s2, s27
	s_or_b32 s8, s8, s28
	v_add_u32_e32 v152, s2, v152
	v_lshl_add_u32 v144, v144, 3, s8
	v_ashrrev_i32_e32 v153, 31, v152
	v_ashrrev_i32_e32 v145, 31, v144
	v_lshlrev_b64 v[152:153], 11, v[152:153]
	v_lshl_add_u64 v[144:145], v[152:153], 0, v[144:145]
	v_lshl_add_u64 v[156:157], v[144:145], 1, s[6:7]
	global_load_dwordx4 v[152:155], v[156:157], off
	s_mov_b64 s[8:9], 0x8000
	s_and_b64 vcc, exec, s[40:41]
	s_mov_b32 s37, s35
	s_mov_b32 s2, s36
	s_mov_b64 s[10:11], s[44:45]
	s_waitcnt vmcnt(0) lgkmcnt(0)
	v_lshlrev_b32_e32 v158, 16, v152
	v_and_b32_e32 v159, 0xffff0000, v152
	v_lshlrev_b32_e32 v152, 16, v153
	v_and_b32_e32 v153, 0xffff0000, v153
	v_lshlrev_b32_e32 v160, 16, v154
	v_and_b32_e32 v161, 0xffff0000, v154
	v_lshlrev_b32_e32 v154, 16, v155
	v_and_b32_e32 v155, 0xffff0000, v155
	v_pk_add_f32 v[126:127], v[126:127], v[152:153]
	v_pk_add_f32 v[124:125], v[124:125], v[158:159]
	v_lshl_add_u64 v[152:153], v[144:145], 2, s[4:5]
	v_pk_add_f32 v[122:123], v[122:123], v[154:155]
	v_pk_add_f32 v[120:121], v[120:121], v[160:161]
	global_store_dwordx4 v[152:153], v[124:127], off
	global_store_dwordx4 v[152:153], v[120:123], off offset:16
	global_load_dwordx4 v[120:123], v[156:157], off offset:256
	s_waitcnt vmcnt(0) lgkmcnt(0)
	v_lshlrev_b32_e32 v124, 16, v120
	v_and_b32_e32 v125, 0xffff0000, v120
	v_lshlrev_b32_e32 v120, 16, v121
	v_and_b32_e32 v121, 0xffff0000, v121
	v_lshlrev_b32_e32 v126, 16, v122
	v_and_b32_e32 v127, 0xffff0000, v122
	v_lshlrev_b32_e32 v122, 16, v123
	v_and_b32_e32 v123, 0xffff0000, v123
	v_pk_add_f32 v[118:119], v[118:119], v[120:121]
	v_pk_add_f32 v[116:117], v[116:117], v[124:125]
	v_pk_add_f32 v[114:115], v[114:115], v[122:123]
	v_pk_add_f32 v[112:113], v[112:113], v[126:127]
	global_store_dwordx4 v[152:153], v[116:119], off offset:512
	global_store_dwordx4 v[152:153], v[112:115], off offset:528
	s_nop 0
	v_lshl_add_u64 v[116:117], v[144:145], 0, s[8:9]
	v_lshl_add_u64 v[118:119], v[116:117], 1, s[6:7]
	global_load_dwordx4 v[112:115], v[118:119], off
	s_mov_b64 s[8:9], 0x10000
	s_waitcnt vmcnt(0) lgkmcnt(0)
; DI unsigned pack2(float a, float b) { f32x2 v = {a, b}; hwbf16x2 r = __builtin_convertvector(v, hwbf16x2); return __builtin_bit_cast(unsigned, r); }
; DI float bflo(unsigned w) { return __uint_as_float(w << 16); }
; DI float bfhi(unsigned w) { return __uint_as_float(w & 0xffff0000u); }
;     DI void operator()(const f32x4 (&acc)[2][2][4][2], const Unit& u, int wr, int wc, int fr, int fq) const {
;     ...
;         for (int ai = 0; ai < 2; ++ai)
; #pragma unroll
;             for (int m = 0; m < 4; ++m) { const size_t ro = (size_t)(row0 + ai * HALF + m * 16) * D + col0;
; #pragma unroll
;                 for (int bj = 0; bj < 2; ++bj) {
;                     f32x4 x0, x1;
;                     if constexpr (IB) { const u32x4 w = *(const u32x4*)((const bf16_t*)Xin + ro + bj * HALF);
;                         x0 = (f32x4){bflo(w[0]), bfhi(w[0]), bflo(w[1]), bfhi(w[1])}; x1 = (f32x4){bflo(w[2]), bfhi(w[2]), bflo(w[3]), bfhi(w[3])}; }
;                     else { x0 = *(const f32x4*)((const float*)Xin + ro + bj * HALF); x1 = *(const f32x4*)((const float*)Xin + ro + bj * HALF + 4); }
;                     x0 += acc[ai][bj][m][0] * sc[bj][0]; x1 += acc[ai][bj][m][1] * sc[bj][1];
;                     if constexpr (OB) { u32x4 o; o[0] = pack2(x0[0], x0[1]); o[1] = pack2(x0[2], x0[3]); o[2] = pack2(x1[0], x1[1]); o[3] = pack2(x1[2], x1[3]);
;                         *(u32x4*)((bf16_t*)Xout + ro + bj * HALF) = o; }
;                     else { *(f32x4*)((float*)Xout + ro + bj * HALF) = x0; *(f32x4*)((float*)Xout + ro + bj * HALF + 4) = x1; } } }
	v_lshlrev_b32_e32 v120, 16, v112
	v_and_b32_e32 v121, 0xffff0000, v112
	v_lshlrev_b32_e32 v112, 16, v113
	v_and_b32_e32 v113, 0xffff0000, v113
	v_lshlrev_b32_e32 v122, 16, v114
	v_and_b32_e32 v123, 0xffff0000, v114
	v_lshlrev_b32_e32 v114, 16, v115
	v_and_b32_e32 v115, 0xffff0000, v115
	v_pk_add_f32 v[110:111], v[110:111], v[112:113]
	v_pk_add_f32 v[108:109], v[108:109], v[120:121]
	v_lshl_add_u64 v[112:113], v[116:117], 2, s[4:5]
	v_pk_add_f32 v[106:107], v[106:107], v[114:115]
	v_pk_add_f32 v[104:105], v[104:105], v[122:123]
	global_store_dwordx4 v[112:113], v[108:111], off
	global_store_dwordx4 v[112:113], v[104:107], off offset:16
	global_load_dwordx4 v[104:107], v[118:119], off offset:256
	s_waitcnt vmcnt(0) lgkmcnt(0)
	v_lshlrev_b32_e32 v108, 16, v104
	v_and_b32_e32 v109, 0xffff0000, v104
	v_lshlrev_b32_e32 v104, 16, v105
	v_and_b32_e32 v105, 0xffff0000, v105
	v_lshlrev_b32_e32 v110, 16, v106
	v_and_b32_e32 v111, 0xffff0000, v106
	v_lshlrev_b32_e32 v106, 16, v107
	v_and_b32_e32 v107, 0xffff0000, v107
	v_pk_add_f32 v[102:103], v[102:103], v[104:105]
	v_pk_add_f32 v[100:101], v[100:101], v[108:109]
	v_pk_add_f32 v[98:99], v[98:99], v[106:107]
	v_pk_add_f32 v[96:97], v[96:97], v[110:111]
	global_store_dwordx4 v[112:113], v[100:103], off offset:512
	global_store_dwordx4 v[112:113], v[96:99], off offset:528
	s_nop 0
	v_lshl_add_u64 v[100:101], v[144:145], 0, s[8:9]
	v_lshl_add_u64 v[102:103], v[100:101], 1, s[6:7]
	global_load_dwordx4 v[96:99], v[102:103], off
	s_mov_b64 s[8:9], 0x18000
	s_waitcnt vmcnt(0) lgkmcnt(0)
	v_lshlrev_b32_e32 v104, 16, v96
	v_and_b32_e32 v105, 0xffff0000, v96
	v_lshlrev_b32_e32 v96, 16, v97
	v_and_b32_e32 v97, 0xffff0000, v97
	v_lshlrev_b32_e32 v106, 16, v98
	v_and_b32_e32 v107, 0xffff0000, v98
	v_lshlrev_b32_e32 v98, 16, v99
	v_and_b32_e32 v99, 0xffff0000, v99
	v_pk_add_f32 v[94:95], v[94:95], v[96:97]
	v_pk_add_f32 v[92:93], v[92:93], v[104:105]
	v_lshl_add_u64 v[96:97], v[100:101], 2, s[4:5]
	v_pk_add_f32 v[90:91], v[90:91], v[98:99]
	v_pk_add_f32 v[88:89], v[88:89], v[106:107]
	global_store_dwordx4 v[96:97], v[92:95], off
	global_store_dwordx4 v[96:97], v[88:91], off offset:16
	global_load_dwordx4 v[88:91], v[102:103], off offset:256
	s_waitcnt vmcnt(0) lgkmcnt(0)
	v_lshlrev_b32_e32 v92, 16, v88
	v_and_b32_e32 v93, 0xffff0000, v88
	v_lshlrev_b32_e32 v88, 16, v89
	v_and_b32_e32 v89, 0xffff0000, v89
	v_lshlrev_b32_e32 v94, 16, v90
	v_and_b32_e32 v95, 0xffff0000, v90
	v_lshlrev_b32_e32 v90, 16, v91
	v_and_b32_e32 v91, 0xffff0000, v91
	v_pk_add_f32 v[86:87], v[86:87], v[88:89]
	v_pk_add_f32 v[84:85], v[84:85], v[92:93]
	v_pk_add_f32 v[82:83], v[82:83], v[90:91]
	v_pk_add_f32 v[80:81], v[80:81], v[94:95]
	global_store_dwordx4 v[96:97], v[84:87], off offset:512
	global_store_dwordx4 v[96:97], v[80:83], off offset:528
	s_nop 0
	v_lshl_add_u64 v[84:85], v[144:145], 0, s[8:9]
	v_lshl_add_u64 v[86:87], v[84:85], 1, s[6:7]
	global_load_dwordx4 v[80:83], v[86:87], off
	s_mov_b64 s[8:9], 0x40000
	s_waitcnt vmcnt(0) lgkmcnt(0)
	v_lshlrev_b32_e32 v88, 16, v80
	v_and_b32_e32 v89, 0xffff0000, v80
	v_lshlrev_b32_e32 v80, 16, v81
	v_and_b32_e32 v81, 0xffff0000, v81
	v_lshlrev_b32_e32 v90, 16, v82
	v_and_b32_e32 v91, 0xffff0000, v82
	v_lshlrev_b32_e32 v82, 16, v83
	v_and_b32_e32 v83, 0xffff0000, v83
	v_pk_add_f32 v[78:79], v[78:79], v[80:81]
	v_pk_add_f32 v[76:77], v[76:77], v[88:89]
	v_lshl_add_u64 v[80:81], v[84:85], 2, s[4:5]
	v_pk_add_f32 v[74:75], v[74:75], v[82:83]
	v_pk_add_f32 v[72:73], v[72:73], v[90:91]
	global_store_dwordx4 v[80:81], v[76:79], off
	global_store_dwordx4 v[80:81], v[72:75], off offset:16
	global_load_dwordx4 v[72:75], v[86:87], off offset:256
	s_waitcnt vmcnt(0) lgkmcnt(0)
	v_lshlrev_b32_e32 v76, 16, v72
	v_and_b32_e32 v77, 0xffff0000, v72
	v_lshlrev_b32_e32 v72, 16, v73
	v_and_b32_e32 v73, 0xffff0000, v73
	v_lshlrev_b32_e32 v78, 16, v74
	v_and_b32_e32 v79, 0xffff0000, v74
	v_lshlrev_b32_e32 v74, 16, v75
	v_and_b32_e32 v75, 0xffff0000, v75
	v_pk_add_f32 v[70:71], v[70:71], v[72:73]
	v_pk_add_f32 v[68:69], v[68:69], v[76:77]
	v_pk_add_f32 v[66:67], v[66:67], v[74:75]
	v_pk_add_f32 v[64:65], v[64:65], v[78:79]
	global_store_dwordx4 v[80:81], v[68:71], off offset:512
	global_store_dwordx4 v[80:81], v[64:67], off offset:528
	s_nop 0
	v_lshl_add_u64 v[68:69], v[144:145], 0, s[8:9]
	v_lshl_add_u64 v[70:71], v[68:69], 1, s[6:7]
	global_load_dwordx4 v[64:67], v[70:71], off
	s_mov_b64 s[8:9], 0x48000
	s_waitcnt vmcnt(0) lgkmcnt(0)
	v_lshlrev_b32_e32 v72, 16, v64
	v_and_b32_e32 v73, 0xffff0000, v64
	v_lshlrev_b32_e32 v64, 16, v65
	v_and_b32_e32 v65, 0xffff0000, v65
	v_lshlrev_b32_e32 v74, 16, v66
	v_and_b32_e32 v75, 0xffff0000, v66
	v_lshlrev_b32_e32 v66, 16, v67
	v_and_b32_e32 v67, 0xffff0000, v67
	v_pk_add_f32 v[62:63], v[62:63], v[64:65]
	v_pk_add_f32 v[60:61], v[60:61], v[72:73]
	v_lshl_add_u64 v[64:65], v[68:69], 2, s[4:5]
	v_pk_add_f32 v[58:59], v[58:59], v[66:67]
	v_pk_add_f32 v[56:57], v[56:57], v[74:75]
	global_store_dwordx4 v[64:65], v[60:63], off
	global_store_dwordx4 v[64:65], v[56:59], off offset:16
	global_load_dwordx4 v[56:59], v[70:71], off offset:256
	s_waitcnt vmcnt(0) lgkmcnt(0)
; DI unsigned pack2(float a, float b) { f32x2 v = {a, b}; hwbf16x2 r = __builtin_convertvector(v, hwbf16x2); return __builtin_bit_cast(unsigned, r); }
; DI float bflo(unsigned w) { return __uint_as_float(w << 16); }
; DI float bfhi(unsigned w) { return __uint_as_float(w & 0xffff0000u); }
;     DI void operator()(const f32x4 (&acc)[2][2][4][2], const Unit& u, int wr, int wc, int fr, int fq) const {
;     ...
;             for (int m = 0; m < 4; ++m) { const size_t ro = (size_t)(row0 + ai * HALF + m * 16) * D + col0;
; #pragma unroll
;                 for (int bj = 0; bj < 2; ++bj) {
;                     f32x4 x0, x1;
;                     if constexpr (IB) { const u32x4 w = *(const u32x4*)((const bf16_t*)Xin + ro + bj * HALF);
;                         x0 = (f32x4){bflo(w[0]), bfhi(w[0]), bflo(w[1]), bfhi(w[1])}; x1 = (f32x4){bflo(w[2]), bfhi(w[2]), bflo(w[3]), bfhi(w[3])}; }
;                     else { x0 = *(const f32x4*)((const float*)Xin + ro + bj * HALF); x1 = *(const f32x4*)((const float*)Xin + ro + bj * HALF + 4); }
;                     x0 += acc[ai][bj][m][0] * sc[bj][0]; x1 += acc[ai][bj][m][1] * sc[bj][1];
;                     if constexpr (OB) { u32x4 o; o[0] = pack2(x0[0], x0[1]); o[1] = pack2(x0[2], x0[3]); o[2] = pack2(x1[0], x1[1]); o[3] = pack2(x1[2], x1[3]);
;                         *(u32x4*)((bf16_t*)Xout + ro + bj * HALF) = o; }
;                     else { *(f32x4*)((float*)Xout + ro + bj * HALF) = x0; *(f32x4*)((float*)Xout + ro + bj * HALF + 4) = x1; } } }
	v_lshlrev_b32_e32 v60, 16, v56
	v_and_b32_e32 v61, 0xffff0000, v56
	v_lshlrev_b32_e32 v56, 16, v57
	v_and_b32_e32 v57, 0xffff0000, v57
	v_lshlrev_b32_e32 v62, 16, v58
	v_and_b32_e32 v63, 0xffff0000, v58
	v_lshlrev_b32_e32 v58, 16, v59
	v_and_b32_e32 v59, 0xffff0000, v59
	v_pk_add_f32 v[54:55], v[54:55], v[56:57]
	v_pk_add_f32 v[52:53], v[52:53], v[60:61]
	v_pk_add_f32 v[50:51], v[50:51], v[58:59]
	v_pk_add_f32 v[48:49], v[48:49], v[62:63]
	global_store_dwordx4 v[64:65], v[52:55], off offset:512
	global_store_dwordx4 v[64:65], v[48:51], off offset:528
	s_nop 0
	v_lshl_add_u64 v[52:53], v[144:145], 0, s[8:9]
	v_lshl_add_u64 v[54:55], v[52:53], 1, s[6:7]
	global_load_dwordx4 v[48:51], v[54:55], off
	s_mov_b64 s[8:9], 0x50000
	s_waitcnt vmcnt(0) lgkmcnt(0)
	v_lshlrev_b32_e32 v56, 16, v48
	v_and_b32_e32 v57, 0xffff0000, v48
	v_lshlrev_b32_e32 v48, 16, v49
	v_and_b32_e32 v49, 0xffff0000, v49
	v_lshlrev_b32_e32 v58, 16, v50
	v_and_b32_e32 v59, 0xffff0000, v50
	v_lshlrev_b32_e32 v50, 16, v51
	v_and_b32_e32 v51, 0xffff0000, v51
	v_pk_add_f32 v[46:47], v[46:47], v[48:49]
	v_pk_add_f32 v[44:45], v[44:45], v[56:57]
	v_lshl_add_u64 v[48:49], v[52:53], 2, s[4:5]
	v_pk_add_f32 v[42:43], v[42:43], v[50:51]
	v_pk_add_f32 v[40:41], v[40:41], v[58:59]
	global_store_dwordx4 v[48:49], v[44:47], off
	global_store_dwordx4 v[48:49], v[40:43], off offset:16
	global_load_dwordx4 v[40:43], v[54:55], off offset:256
	s_waitcnt vmcnt(0) lgkmcnt(0)
	v_lshlrev_b32_e32 v44, 16, v40
	v_and_b32_e32 v45, 0xffff0000, v40
	v_lshlrev_b32_e32 v40, 16, v41
	v_and_b32_e32 v41, 0xffff0000, v41
	v_lshlrev_b32_e32 v46, 16, v42
	v_and_b32_e32 v47, 0xffff0000, v42
	v_lshlrev_b32_e32 v42, 16, v43
	v_and_b32_e32 v43, 0xffff0000, v43
	v_pk_add_f32 v[38:39], v[38:39], v[40:41]
	v_pk_add_f32 v[36:37], v[36:37], v[44:45]
	v_pk_add_f32 v[34:35], v[34:35], v[42:43]
	v_pk_add_f32 v[32:33], v[32:33], v[46:47]
	global_store_dwordx4 v[48:49], v[36:39], off offset:512
	global_store_dwordx4 v[48:49], v[32:35], off offset:528
	s_nop 0
	v_lshl_add_u64 v[36:37], v[144:145], 0, s[8:9]
	v_lshl_add_u64 v[38:39], v[36:37], 1, s[6:7]
	global_load_dwordx4 v[32:35], v[38:39], off
	s_mov_b64 s[8:9], 0x58000
	s_waitcnt vmcnt(0) lgkmcnt(0)
	v_lshlrev_b32_e32 v40, 16, v32
	v_and_b32_e32 v41, 0xffff0000, v32
	v_lshlrev_b32_e32 v32, 16, v33
	v_and_b32_e32 v33, 0xffff0000, v33
	v_lshlrev_b32_e32 v42, 16, v34
	v_and_b32_e32 v43, 0xffff0000, v34
	v_lshlrev_b32_e32 v34, 16, v35
	v_and_b32_e32 v35, 0xffff0000, v35
	v_pk_add_f32 v[30:31], v[30:31], v[32:33]
	v_pk_add_f32 v[28:29], v[28:29], v[40:41]
	v_lshl_add_u64 v[32:33], v[36:37], 2, s[4:5]
	v_pk_add_f32 v[26:27], v[26:27], v[34:35]
	v_pk_add_f32 v[24:25], v[24:25], v[42:43]
	global_store_dwordx4 v[32:33], v[28:31], off
	global_store_dwordx4 v[32:33], v[24:27], off offset:16
	global_load_dwordx4 v[24:27], v[38:39], off offset:256
	s_waitcnt vmcnt(0) lgkmcnt(0)
	v_lshlrev_b32_e32 v28, 16, v24
	v_and_b32_e32 v29, 0xffff0000, v24
	v_lshlrev_b32_e32 v24, 16, v25
	v_and_b32_e32 v25, 0xffff0000, v25
	v_lshlrev_b32_e32 v30, 16, v26
	v_and_b32_e32 v31, 0xffff0000, v26
	v_lshlrev_b32_e32 v26, 16, v27
	v_and_b32_e32 v27, 0xffff0000, v27
	v_pk_add_f32 v[22:23], v[22:23], v[24:25]
	v_pk_add_f32 v[20:21], v[20:21], v[28:29]
	v_pk_add_f32 v[18:19], v[18:19], v[26:27]
	v_pk_add_f32 v[16:17], v[16:17], v[30:31]
	global_store_dwordx4 v[32:33], v[20:23], off offset:512
	global_store_dwordx4 v[32:33], v[16:19], off offset:528
	s_nop 0
	v_lshl_add_u64 v[20:21], v[144:145], 0, s[8:9]
	v_lshl_add_u64 v[22:23], v[20:21], 1, s[6:7]
	global_load_dwordx4 v[16:19], v[22:23], off
	s_mov_b64 s[8:9], s[42:43]
	s_waitcnt vmcnt(0) lgkmcnt(0)
	v_lshlrev_b32_e32 v24, 16, v16
	v_and_b32_e32 v25, 0xffff0000, v16
	v_lshlrev_b32_e32 v16, 16, v17
	v_and_b32_e32 v17, 0xffff0000, v17
	v_lshlrev_b32_e32 v26, 16, v18
	v_and_b32_e32 v27, 0xffff0000, v18
	v_lshlrev_b32_e32 v18, 16, v19
	v_and_b32_e32 v19, 0xffff0000, v19
	v_pk_add_f32 v[14:15], v[14:15], v[16:17]
	v_pk_add_f32 v[12:13], v[12:13], v[24:25]
	v_lshl_add_u64 v[16:17], v[20:21], 2, s[4:5]
	v_pk_add_f32 v[10:11], v[10:11], v[18:19]
	v_pk_add_f32 v[8:9], v[8:9], v[26:27]
	global_store_dwordx4 v[16:17], v[12:15], off
	global_store_dwordx4 v[16:17], v[8:11], off offset:16
	global_load_dwordx4 v[8:11], v[22:23], off offset:256
	s_waitcnt vmcnt(0) lgkmcnt(0)
	v_lshlrev_b32_e32 v12, 16, v8
	v_and_b32_e32 v13, 0xffff0000, v8
	v_lshlrev_b32_e32 v8, 16, v9
	v_and_b32_e32 v9, 0xffff0000, v9
	v_lshlrev_b32_e32 v14, 16, v10
	v_and_b32_e32 v15, 0xffff0000, v10
	v_lshlrev_b32_e32 v10, 16, v11
	v_and_b32_e32 v11, 0xffff0000, v11
	v_pk_add_f32 v[6:7], v[6:7], v[8:9]
	v_pk_add_f32 v[4:5], v[4:5], v[12:13]
	v_pk_add_f32 v[2:3], v[2:3], v[10:11]
	v_pk_add_f32 v[0:1], v[0:1], v[14:15]
	global_store_dwordx4 v[16:17], v[4:7], off offset:512
	global_store_dwordx4 v[16:17], v[0:3], off offset:528
	s_cbranch_vccz .LBB1_2646
	s_waitcnt vmcnt(0)
	s_cmpk_gt_u32 s3, 0xff
	s_cbranch_scc1 .LBB1_2657
	s_barrier
